# packed f32 mul/add outside the attention loops written as two plain f32 ops each
# speedup vs baseline: 1.0079x; 1.0079x over previous
; DI void prep_wt(const float* __restrict__ src, u16* __restrict__ dst, int K, int N, int Npad,
;                 const float* __restrict__ gain, float* tile) {
;     ...
;     for (int j = 0; j < 4; ++j) {
;       const int t = t0 + j * gridDim.x;
;       const int kt = t % tk, nt = t / tk;
; #pragma unroll
;       for (int i = 0; i < 2; ++i) {
;         const int e = tid + NTHR * i; const int kk = e >> 4, n4 = (e & 15) * 4; const int n = nt * 64 + n4;
;         v[j][i] = (f32x4){0.f, 0.f, 0.f, 0.f};
;         if (t < nt4 && n < N) {
;           v[j][i] = *(const f32x4*)(src + (size_t)(kt * 64 + kk) * N + n);
;           if (gain) v[j][i] *= gain[kt * 64 + kk];
;         }
;       }
.LBB0_23:
	s_ashr_i32 s0, s65, 31
	s_lshr_b32 s0, s0, 28
	s_add_i32 s0, s65, s0
	s_ashr_i32 s2, s0, 4
	s_lshl_b32 s83, s2, 6
	v_or_b32_e32 v0, s83, v39
	s_lshl_b32 s2, s2, 10
	v_ashrrev_i32_e32 v1, 31, v0
	v_cmp_gt_i32_e64 s[0:1], s78, v0
	s_sub_i32 s84, 0, s2
	v_lshl_add_u64 v[8:9], v[0:1], 2, s[42:43]
	v_mov_b32_e32 v0, 0
	v_cmp_ne_u32_e64 s[2:3], 1, v38
	v_mov_b32_e32 v4, 0
	v_mov_b32_e32 v5, 0
	v_mov_b32_e32 v6, 0
	v_mov_b32_e32 v7, 0
	s_and_saveexec_b64 s[46:47], s[0:1]
	s_cbranch_execz .LBB0_26
	s_add_i32 s48, s84, s64
	v_add_u32_e32 v2, s48, v42
	v_mad_i64_i32 v[4:5], s[48:49], v2, s79, v[8:9]
	global_load_dwordx4 v[4:7], v[4:5], off
	s_and_b64 vcc, exec, s[2:3]
	s_cbranch_vccnz .LBB0_26
	v_ashrrev_i32_e32 v3, 31, v2
	v_lshl_add_u64 v[2:3], v[2:3], 2, s[40:41]
	global_load_dword v2, v[2:3], off
	s_waitcnt vmcnt(0)
	v_mul_f32_e32 v6, v6, v2
	v_mul_f32_e32 v7, v7, v2
	v_mul_f32_e32 v4, v4, v2
	v_mul_f32_e32 v5, v5, v2
.LBB0_26:
	s_or_b64 exec, exec, s[46:47]
	v_mov_b32_e32 v1, 0
	v_mov_b32_e32 v2, 0
	v_mov_b32_e32 v3, 0
	s_and_saveexec_b64 s[46:47], s[0:1]
	s_cbranch_execz .LBB0_29
	s_add_i32 s0, s84, s64
	v_add_u32_e32 v10, s0, v43
	v_mad_i64_i32 v[0:1], s[0:1], v10, s79, v[8:9]
	global_load_dwordx4 v[0:3], v[0:1], off
	s_and_b64 vcc, exec, s[2:3]
	s_cbranch_vccnz .LBB0_29
	v_ashrrev_i32_e32 v11, 31, v10
	v_lshl_add_u64 v[8:9], v[10:11], 2, s[40:41]
	global_load_dword v8, v[8:9], off
	s_waitcnt vmcnt(0)
	v_mul_f32_e32 v2, v2, v8
	v_mul_f32_e32 v3, v3, v8
	v_mul_f32_e32 v0, v0, v8
	v_mul_f32_e32 v1, v1, v8
.LBB0_29:
	s_or_b64 exec, exec, s[46:47]
	s_add_i32 s0, s60, s65
	s_ashr_i32 s1, s0, 31
	s_lshr_b32 s1, s1, 28
	s_add_i32 s1, s0, s1
	s_and_b32 s46, s1, 0x3fffff0
	s_lshl_b32 s1, s1, 2
	s_sub_i32 s50, s0, s46
	s_andn2_b32 s1, s1, 63
	v_or_b32_e32 v8, s1, v39
	s_cmpk_lt_i32 s0, 0x240
	s_cselect_b64 s[46:47], -1, 0
	v_cmp_gt_i32_e32 vcc, s78, v8
	v_ashrrev_i32_e32 v9, 31, v8
	s_and_b64 s[48:49], s[46:47], vcc
	s_lshl_b32 s0, s50, 6
	v_lshl_add_u64 v[16:17], v[8:9], 2, s[42:43]
	v_mov_b32_e32 v8, 0
	v_mov_b32_e32 v12, 0
	v_mov_b32_e32 v13, 0
	v_mov_b32_e32 v14, 0
	v_mov_b32_e32 v15, 0
	s_and_saveexec_b64 s[50:51], s[48:49]
	s_cbranch_execz .LBB0_32
	v_add_u32_e32 v10, s0, v42
	v_mad_i64_i32 v[12:13], s[52:53], v10, s79, v[16:17]
	global_load_dwordx4 v[12:15], v[12:13], off
	s_and_b64 vcc, exec, s[2:3]
	s_cbranch_vccnz .LBB0_32
	v_ashrrev_i32_e32 v11, 31, v10
	v_lshl_add_u64 v[10:11], v[10:11], 2, s[40:41]
	global_load_dword v10, v[10:11], off
	s_waitcnt vmcnt(0)
	v_mul_f32_e32 v14, v14, v10
	v_mul_f32_e32 v15, v15, v10
	v_mul_f32_e32 v12, v12, v10
	v_mul_f32_e32 v13, v13, v10
.LBB0_32:
	s_or_b64 exec, exec, s[50:51]
	v_mov_b32_e32 v9, 0
	v_mov_b32_e32 v10, 0
	v_mov_b32_e32 v11, 0
	s_and_saveexec_b64 s[50:51], s[48:49]
	s_cbranch_execz .LBB0_35
	v_add_u32_e32 v18, s0, v43
	v_mad_i64_i32 v[8:9], s[48:49], v18, s79, v[16:17]
	global_load_dwordx4 v[8:11], v[8:9], off
	s_and_b64 vcc, exec, s[2:3]
	s_cbranch_vccnz .LBB0_35
	v_ashrrev_i32_e32 v19, 31, v18
	v_lshl_add_u64 v[16:17], v[18:19], 2, s[40:41]
	global_load_dword v16, v[16:17], off
	s_waitcnt vmcnt(0)
	v_mul_f32_e32 v10, v10, v16
	v_mul_f32_e32 v11, v11, v16
	v_mul_f32_e32 v8, v8, v16
	v_mul_f32_e32 v9, v9, v16
.LBB0_35:
	s_or_b64 exec, exec, s[50:51]
	s_add_i32 s48, s63, s65
	s_ashr_i32 s49, s48, 31
	s_lshr_b32 s49, s49, 28
	s_add_i32 s49, s48, s49
	s_and_b32 s50, s49, 0x3fffff0
	s_lshl_b32 s49, s49, 2
	s_sub_i32 s54, s48, s50
	s_andn2_b32 s49, s49, 63
	v_or_b32_e32 v16, s49, v39
	s_cmpk_lt_i32 s48, 0x240
	s_cselect_b64 s[50:51], -1, 0
	v_cmp_gt_i32_e32 vcc, s78, v16
	v_ashrrev_i32_e32 v17, 31, v16
	s_and_b64 s[52:53], s[50:51], vcc
	s_lshl_b32 s48, s54, 6
	v_lshl_add_u64 v[24:25], v[16:17], 2, s[42:43]
	v_mov_b32_e32 v16, 0
	v_mov_b32_e32 v20, 0
	v_mov_b32_e32 v21, 0
	v_mov_b32_e32 v22, 0
	v_mov_b32_e32 v23, 0
	s_and_saveexec_b64 s[54:55], s[52:53]
	s_cbranch_execz .LBB0_38
	v_add_u32_e32 v18, s48, v42
	v_mad_i64_i32 v[20:21], s[56:57], v18, s79, v[24:25]
	global_load_dwordx4 v[20:23], v[20:21], off
	s_and_b64 vcc, exec, s[2:3]
	s_cbranch_vccnz .LBB0_38
	v_ashrrev_i32_e32 v19, 31, v18
	v_lshl_add_u64 v[18:19], v[18:19], 2, s[40:41]
	global_load_dword v18, v[18:19], off
	s_waitcnt vmcnt(0)
	v_mul_f32_e32 v22, v22, v18
	v_mul_f32_e32 v23, v23, v18
	v_mul_f32_e32 v20, v20, v18
	v_mul_f32_e32 v21, v21, v18
.LBB0_38:
	s_or_b64 exec, exec, s[54:55]
	v_mov_b32_e32 v17, 0
	v_mov_b32_e32 v18, 0
	v_mov_b32_e32 v19, 0
	s_and_saveexec_b64 s[54:55], s[52:53]
	s_cbranch_execz .LBB0_41
	v_add_u32_e32 v26, s48, v43
	v_mad_i64_i32 v[16:17], s[52:53], v26, s79, v[24:25]
	global_load_dwordx4 v[16:19], v[16:17], off
	s_and_b64 vcc, exec, s[2:3]
	s_cbranch_vccnz .LBB0_41
	v_ashrrev_i32_e32 v27, 31, v26
	v_lshl_add_u64 v[24:25], v[26:27], 2, s[40:41]
	global_load_dword v24, v[24:25], off
	s_waitcnt vmcnt(0)
	v_mul_f32_e32 v18, v18, v24
	v_mul_f32_e32 v19, v19, v24
	v_mul_f32_e32 v16, v16, v24
	v_mul_f32_e32 v17, v17, v24
.LBB0_41:
	s_or_b64 exec, exec, s[54:55]
	s_mul_i32 s52, s60, 3
	s_add_i32 s52, s52, s65
	s_ashr_i32 s53, s52, 31
	s_lshr_b32 s53, s53, 28
	s_add_i32 s53, s52, s53
	s_and_b32 s54, s53, 0x3fffff0
	s_lshl_b32 s53, s53, 2
	s_sub_i32 s58, s52, s54
	s_andn2_b32 s53, s53, 63
	v_or_b32_e32 v24, s53, v39
	s_cmpk_lt_i32 s52, 0x240
	s_cselect_b64 s[54:55], -1, 0
	v_cmp_gt_i32_e32 vcc, s78, v24
	v_ashrrev_i32_e32 v25, 31, v24
	s_and_b64 s[56:57], s[54:55], vcc
	s_lshl_b32 s52, s58, 6
	v_lshl_add_u64 v[34:35], v[24:25], 2, s[42:43]
	v_mov_b32_e32 v24, 0
	v_mov_b32_e32 v28, 0
	v_mov_b32_e32 v29, 0
	v_mov_b32_e32 v30, 0
	v_mov_b32_e32 v31, 0
	s_and_saveexec_b64 s[58:59], s[56:57]
	s_cbranch_execz .LBB0_44
	v_add_u32_e32 v26, s52, v42
	v_mad_i64_i32 v[28:29], s[86:87], v26, s79, v[34:35]
	global_load_dwordx4 v[28:31], v[28:29], off
	s_and_b64 vcc, exec, s[2:3]
	s_cbranch_vccnz .LBB0_44
	v_ashrrev_i32_e32 v27, 31, v26
	v_lshl_add_u64 v[26:27], v[26:27], 2, s[40:41]
	global_load_dword v26, v[26:27], off
	s_waitcnt vmcnt(0)
	v_mul_f32_e32 v30, v30, v26
	v_mul_f32_e32 v31, v31, v26
	v_mul_f32_e32 v28, v28, v26
	v_mul_f32_e32 v29, v29, v26
.LBB0_44:
	s_or_b64 exec, exec, s[58:59]
	v_mov_b32_e32 v25, 0
	v_mov_b32_e32 v26, 0
	v_mov_b32_e32 v27, 0
	s_and_saveexec_b64 s[58:59], s[56:57]
	s_cbranch_execz .LBB0_47
	v_add_u32_e32 v36, s52, v43
	v_mad_i64_i32 v[24:25], s[56:57], v36, s79, v[34:35]
	global_load_dwordx4 v[24:27], v[24:25], off
	s_and_b64 vcc, exec, s[2:3]
	s_cbranch_vccnz .LBB0_47
	v_ashrrev_i32_e32 v37, 31, v36
	v_lshl_add_u64 v[34:35], v[36:37], 2, s[40:41]
	global_load_dword v34, v[34:35], off
	s_waitcnt vmcnt(0)
	v_mul_f32_e32 v26, v26, v34
	v_mul_f32_e32 v27, v27, v34
	v_mul_f32_e32 v24, v24, v34
	v_mul_f32_e32 v25, v25, v34

; DI void prep_wt(const float* __restrict__ src, u16* __restrict__ dst, int K, int N, int Npad,
;                 const float* __restrict__ gain, float* tile) {
;     ...
;     for (int j = 0; j < 4; ++j) {
;       const int t = t0 + j * gridDim.x;
;       const int kt = t % tk, nt = t / tk;
; #pragma unroll
;       for (int i = 0; i < 2; ++i) {
;         const int e = tid + NTHR * i; const int kk = e >> 4, n4 = (e & 15) * 4; const int n = nt * 64 + n4;
;         v[j][i] = (f32x4){0.f, 0.f, 0.f, 0.f};
;         if (t < nt4 && n < N) {
;           v[j][i] = *(const f32x4*)(src + (size_t)(kt * 64 + kk) * N + n);
;           if (gain) v[j][i] *= gain[kt * 64 + kk];
;         }
;       }
.LBB0_56:
	s_mul_hi_i32 s0, s84, 0x2aaaaaab
	s_lshr_b32 s1, s0, 31
	s_add_i32 s86, s0, s1
	s_lshl_b32 s85, s86, 6
	v_or_b32_e32 v0, s85, v39
	v_ashrrev_i32_e32 v1, 31, v0
	v_lshl_add_u64 v[8:9], v[0:1], 2, s[42:43]
	v_cndmask_b32_e64 v1, 0, 1, s[30:31]
	v_cmp_gt_i32_e64 s[0:1], s72, v0
	s_mulk_i32 s86, 0xfe80
	v_mov_b32_e32 v0, 0
	v_cmp_ne_u32_e64 s[2:3], 1, v1
	v_mov_b32_e32 v4, 0
	v_mov_b32_e32 v5, 0
	v_mov_b32_e32 v6, 0
	v_mov_b32_e32 v7, 0
	s_and_saveexec_b64 s[48:49], s[0:1]
	s_cbranch_execz .LBB0_59
	s_add_i32 s50, s86, s83
	v_add_u32_e32 v2, s50, v42
	v_mad_i64_i32 v[4:5], s[50:51], v2, s80, v[8:9]
	global_load_dwordx4 v[4:7], v[4:5], off
	s_and_b64 vcc, exec, s[2:3]
	s_cbranch_vccnz .LBB0_59
	v_ashrrev_i32_e32 v3, 31, v2
	v_lshl_add_u64 v[2:3], v[2:3], 2, s[46:47]
	global_load_dword v2, v[2:3], off
	s_waitcnt vmcnt(0)
	v_mul_f32_e32 v6, v6, v2
	v_mul_f32_e32 v7, v7, v2
	v_mul_f32_e32 v4, v4, v2
	v_mul_f32_e32 v5, v5, v2
.LBB0_59:
	s_or_b64 exec, exec, s[48:49]
	v_mov_b32_e32 v1, 0
	v_mov_b32_e32 v2, 0
	v_mov_b32_e32 v3, 0
	s_and_saveexec_b64 s[48:49], s[0:1]
	s_cbranch_execz .LBB0_62
	s_add_i32 s0, s86, s83
	v_add_u32_e32 v10, s0, v43
	v_mad_i64_i32 v[0:1], s[0:1], v10, s80, v[8:9]
	global_load_dwordx4 v[0:3], v[0:1], off
	s_and_b64 vcc, exec, s[2:3]
	s_cbranch_vccnz .LBB0_62
	v_ashrrev_i32_e32 v11, 31, v10
	v_lshl_add_u64 v[8:9], v[10:11], 2, s[46:47]
	global_load_dword v8, v[8:9], off
	s_waitcnt vmcnt(0)
	v_mul_f32_e32 v2, v2, v8
	v_mul_f32_e32 v3, v3, v8
	v_mul_f32_e32 v0, v0, v8
	v_mul_f32_e32 v1, v1, v8
.LBB0_62:
	s_or_b64 exec, exec, s[48:49]
	s_add_i32 s0, s62, s84
	s_mul_hi_i32 s1, s0, 0x2aaaaaab
	s_lshr_b32 s48, s1, 31
	s_add_i32 s1, s1, s48
	s_mul_i32 s48, s1, 6
	s_sub_i32 s52, s0, s48
	s_lshl_b32 s1, s1, 6
	v_or_b32_e32 v8, s1, v39
	s_cmpk_lt_i32 s0, 0x48
	s_cselect_b64 s[48:49], -1, 0
	v_cmp_gt_i32_e32 vcc, s72, v8
	v_ashrrev_i32_e32 v9, 31, v8
	s_and_b64 s[50:51], s[48:49], vcc
	s_lshl_b32 s0, s52, 6
	v_lshl_add_u64 v[16:17], v[8:9], 2, s[42:43]
	v_mov_b32_e32 v8, 0
	v_mov_b32_e32 v12, 0
	v_mov_b32_e32 v13, 0
	v_mov_b32_e32 v14, 0
	v_mov_b32_e32 v15, 0
	s_and_saveexec_b64 s[52:53], s[50:51]
	s_cbranch_execz .LBB0_65
	v_add_u32_e32 v10, s0, v42
	v_mad_i64_i32 v[12:13], s[54:55], v10, s80, v[16:17]
	global_load_dwordx4 v[12:15], v[12:13], off
	s_and_b64 vcc, exec, s[2:3]
	s_cbranch_vccnz .LBB0_65
	v_ashrrev_i32_e32 v11, 31, v10
	v_lshl_add_u64 v[10:11], v[10:11], 2, s[46:47]
	global_load_dword v10, v[10:11], off
	s_waitcnt vmcnt(0)
	v_mul_f32_e32 v14, v14, v10
	v_mul_f32_e32 v15, v15, v10
	v_mul_f32_e32 v12, v12, v10
	v_mul_f32_e32 v13, v13, v10
.LBB0_65:
	s_or_b64 exec, exec, s[52:53]
	v_mov_b32_e32 v9, 0
	v_mov_b32_e32 v10, 0
	v_mov_b32_e32 v11, 0
	s_and_saveexec_b64 s[52:53], s[50:51]
	s_cbranch_execz .LBB0_68
	v_add_u32_e32 v18, s0, v43
	v_mad_i64_i32 v[8:9], s[50:51], v18, s80, v[16:17]
	global_load_dwordx4 v[8:11], v[8:9], off
	s_and_b64 vcc, exec, s[2:3]
	s_cbranch_vccnz .LBB0_68
	v_ashrrev_i32_e32 v19, 31, v18
	v_lshl_add_u64 v[16:17], v[18:19], 2, s[46:47]
	global_load_dword v16, v[16:17], off
	s_waitcnt vmcnt(0)
	v_mul_f32_e32 v10, v10, v16
	v_mul_f32_e32 v11, v11, v16
	v_mul_f32_e32 v8, v8, v16
	v_mul_f32_e32 v9, v9, v16
.LBB0_68:
	s_or_b64 exec, exec, s[52:53]
	s_add_i32 s50, s65, s84
	s_mul_hi_i32 s51, s50, 0x2aaaaaab
	s_lshr_b32 s52, s51, 31
	s_add_i32 s51, s51, s52
	s_mul_i32 s52, s51, 6
	s_sub_i32 s56, s50, s52
	s_lshl_b32 s51, s51, 6
	v_or_b32_e32 v16, s51, v39
	s_cmpk_lt_i32 s50, 0x48
	s_cselect_b64 s[52:53], -1, 0
	v_cmp_gt_i32_e32 vcc, s72, v16
	v_ashrrev_i32_e32 v17, 31, v16
	s_and_b64 s[54:55], s[52:53], vcc
	s_lshl_b32 s50, s56, 6
	v_lshl_add_u64 v[24:25], v[16:17], 2, s[42:43]
	v_mov_b32_e32 v16, 0
	v_mov_b32_e32 v20, 0
	v_mov_b32_e32 v21, 0
	v_mov_b32_e32 v22, 0
	v_mov_b32_e32 v23, 0
	s_and_saveexec_b64 s[56:57], s[54:55]
	s_cbranch_execz .LBB0_71
	v_add_u32_e32 v18, s50, v42
	v_mad_i64_i32 v[20:21], s[58:59], v18, s80, v[24:25]
	global_load_dwordx4 v[20:23], v[20:21], off
	s_and_b64 vcc, exec, s[2:3]
	s_cbranch_vccnz .LBB0_71
	v_ashrrev_i32_e32 v19, 31, v18
	v_lshl_add_u64 v[18:19], v[18:19], 2, s[46:47]
	global_load_dword v18, v[18:19], off
	s_waitcnt vmcnt(0)
	v_mul_f32_e32 v22, v22, v18
	v_mul_f32_e32 v23, v23, v18
	v_mul_f32_e32 v20, v20, v18
	v_mul_f32_e32 v21, v21, v18
.LBB0_71:
	s_or_b64 exec, exec, s[56:57]
	v_mov_b32_e32 v17, 0
	v_mov_b32_e32 v18, 0
	v_mov_b32_e32 v19, 0
	s_and_saveexec_b64 s[56:57], s[54:55]
	s_cbranch_execz .LBB0_74
	v_add_u32_e32 v26, s50, v43
	v_mad_i64_i32 v[16:17], s[54:55], v26, s80, v[24:25]
	global_load_dwordx4 v[16:19], v[16:17], off
	s_and_b64 vcc, exec, s[2:3]
	s_cbranch_vccnz .LBB0_74
	v_ashrrev_i32_e32 v27, 31, v26
	v_lshl_add_u64 v[24:25], v[26:27], 2, s[46:47]
	global_load_dword v24, v[24:25], off
	s_waitcnt vmcnt(0)
	v_mul_f32_e32 v18, v18, v24
	v_mul_f32_e32 v19, v19, v24
	v_mul_f32_e32 v16, v16, v24
	v_mul_f32_e32 v17, v17, v24
.LBB0_74:
	s_or_b64 exec, exec, s[56:57]
	s_mul_i32 s54, s62, 3
	s_add_i32 s54, s54, s84
	s_mul_hi_i32 s55, s54, 0x2aaaaaab
	s_lshr_b32 s56, s55, 31
	s_add_i32 s55, s55, s56
	s_mul_i32 s56, s55, 6
	s_sub_i32 s60, s54, s56
	s_lshl_b32 s55, s55, 6
	v_or_b32_e32 v24, s55, v39
	s_cmpk_lt_i32 s54, 0x48
	s_cselect_b64 s[56:57], -1, 0
	v_cmp_gt_i32_e32 vcc, s72, v24
	v_ashrrev_i32_e32 v25, 31, v24
	s_and_b64 s[58:59], s[56:57], vcc
	s_lshl_b32 s54, s60, 6
	v_lshl_add_u64 v[34:35], v[24:25], 2, s[42:43]
	v_mov_b32_e32 v24, 0
	v_mov_b32_e32 v28, 0
	v_mov_b32_e32 v29, 0
	v_mov_b32_e32 v30, 0
	v_mov_b32_e32 v31, 0
	s_and_saveexec_b64 s[60:61], s[58:59]
	s_cbranch_execz .LBB0_77
	v_add_u32_e32 v26, s54, v42
	v_mad_i64_i32 v[28:29], s[88:89], v26, s80, v[34:35]
	global_load_dwordx4 v[28:31], v[28:29], off
	s_and_b64 vcc, exec, s[2:3]
	s_cbranch_vccnz .LBB0_77
	v_ashrrev_i32_e32 v27, 31, v26
	v_lshl_add_u64 v[26:27], v[26:27], 2, s[46:47]
	global_load_dword v26, v[26:27], off
	s_waitcnt vmcnt(0)
	v_mul_f32_e32 v30, v30, v26
	v_mul_f32_e32 v31, v31, v26
	v_mul_f32_e32 v28, v28, v26
	v_mul_f32_e32 v29, v29, v26
.LBB0_77:
	s_or_b64 exec, exec, s[60:61]
	v_mov_b32_e32 v25, 0
	v_mov_b32_e32 v26, 0
	v_mov_b32_e32 v27, 0
	s_and_saveexec_b64 s[60:61], s[58:59]
	s_cbranch_execz .LBB0_80
	v_add_u32_e32 v36, s54, v43
	v_mad_i64_i32 v[24:25], s[58:59], v36, s80, v[34:35]
	global_load_dwordx4 v[24:27], v[24:25], off
	s_and_b64 vcc, exec, s[2:3]
	s_cbranch_vccnz .LBB0_80
	v_ashrrev_i32_e32 v37, 31, v36
	v_lshl_add_u64 v[34:35], v[36:37], 2, s[46:47]
	global_load_dword v34, v[34:35], off
	s_waitcnt vmcnt(0)
	v_mul_f32_e32 v26, v26, v34
	v_mul_f32_e32 v27, v27, v34
	v_mul_f32_e32 v24, v24, v34
	v_mul_f32_e32 v25, v25, v34

; DI void prep_wt(const float* __restrict__ src, u16* __restrict__ dst, int K, int N, int Npad,
;                 const float* __restrict__ gain, float* tile) {
;     ...
;     for (int j = 0; j < 4; ++j) {
;       const int t = t0 + j * gridDim.x;
;       const int kt = t % tk, nt = t / tk;
; #pragma unroll
;       for (int i = 0; i < 2; ++i) {
;         const int e = tid + NTHR * i; const int kk = e >> 4, n4 = (e & 15) * 4; const int n = nt * 64 + n4;
;         v[j][i] = (f32x4){0.f, 0.f, 0.f, 0.f};
;         if (t < nt4 && n < N) {
;           v[j][i] = *(const f32x4*)(src + (size_t)(kt * 64 + kk) * N + n);
;           if (gain) v[j][i] *= gain[kt * 64 + kk];
;         }
;       }
.LBB0_89:
	s_ashr_i32 s0, s54, 31
	s_lshr_b32 s0, s0, 30
	s_add_i32 s0, s54, s0
	s_lshl_b32 s51, s0, 4
	s_andn2_b32 s51, s51, 63
	v_or_b32_e32 v0, s51, v39
	s_and_b32 s1, s0, 0x3fffffc
	v_ashrrev_i32_e32 v1, 31, v0
	s_sub_i32 s2, s54, s1
	v_lshl_add_u64 v[8:9], v[0:1], 2, s[44:45]
	v_cndmask_b32_e64 v1, 0, 1, s[34:35]
	v_cmp_gt_i32_e64 s[0:1], s81, v0
	s_lshl_b32 s50, s2, 6
	v_mov_b32_e32 v0, 0
	v_cmp_ne_u32_e64 s[2:3], 1, v1
	v_mov_b32_e32 v4, 0
	v_mov_b32_e32 v5, 0
	v_mov_b32_e32 v6, 0
	v_mov_b32_e32 v7, 0
	s_and_saveexec_b64 s[52:53], s[0:1]
	s_cbranch_execz .LBB0_92
	v_add_u32_e32 v2, s50, v42
	v_ashrrev_i32_e32 v3, 31, v2
	v_lshlrev_b64 v[4:5], 12, v[2:3]
	v_lshl_add_u64 v[4:5], v[8:9], 0, v[4:5]
	global_load_dwordx4 v[4:7], v[4:5], off
	s_and_b64 vcc, exec, s[2:3]
	s_cbranch_vccnz .LBB0_92
	v_lshl_add_u64 v[2:3], v[2:3], 2, s[48:49]
	global_load_dword v2, v[2:3], off
	s_waitcnt vmcnt(0)
	v_mul_f32_e32 v6, v6, v2
	v_mul_f32_e32 v7, v7, v2
	v_mul_f32_e32 v4, v4, v2
	v_mul_f32_e32 v5, v5, v2
.LBB0_92:
	s_or_b64 exec, exec, s[52:53]
	v_mov_b32_e32 v1, 0
	v_mov_b32_e32 v2, 0
	v_mov_b32_e32 v3, 0
	s_and_saveexec_b64 s[52:53], s[0:1]
	s_cbranch_execz .LBB0_95
	v_add_u32_e32 v10, s50, v43
	v_ashrrev_i32_e32 v11, 31, v10
	v_lshlrev_b64 v[0:1], 12, v[10:11]
	v_lshl_add_u64 v[0:1], v[8:9], 0, v[0:1]
	global_load_dwordx4 v[0:3], v[0:1], off
	s_and_b64 vcc, exec, s[2:3]
	s_cbranch_vccnz .LBB0_95
	v_lshl_add_u64 v[8:9], v[10:11], 2, s[48:49]
	global_load_dword v8, v[8:9], off
	s_waitcnt vmcnt(0)
	v_mul_f32_e32 v2, v2, v8
	v_mul_f32_e32 v3, v3, v8
	v_mul_f32_e32 v0, v0, v8
	v_mul_f32_e32 v1, v1, v8
.LBB0_95:
	s_or_b64 exec, exec, s[52:53]
	s_add_i32 s58, s83, s54
	s_ashr_i32 s0, s58, 31
	s_lshr_b32 s0, s0, 30
	s_add_i32 s0, s58, s0
	s_and_b32 s1, s0, 0x3fffffc
	s_sub_i32 s56, s58, s1
	s_lshl_b32 s1, s0, 4
	s_andn2_b32 s1, s1, 63
	v_or_b32_e32 v8, s1, v39
	s_cmp_lt_i32 s58, 64
	s_cselect_b64 s[52:53], -1, 0
	v_cmp_gt_i32_e32 vcc, s81, v8
	v_ashrrev_i32_e32 v9, 31, v8
	s_and_b64 s[54:55], s[52:53], vcc
	s_lshl_b32 s0, s56, 6
	v_lshl_add_u64 v[16:17], v[8:9], 2, s[44:45]
	v_mov_b32_e32 v8, 0
	v_mov_b32_e32 v12, 0
	v_mov_b32_e32 v13, 0
	v_mov_b32_e32 v14, 0
	v_mov_b32_e32 v15, 0
	s_and_saveexec_b64 s[56:57], s[54:55]
	s_cbranch_execz .LBB0_98
	v_add_u32_e32 v10, s0, v42
	v_ashrrev_i32_e32 v11, 31, v10
	v_lshlrev_b64 v[12:13], 12, v[10:11]
	v_lshl_add_u64 v[12:13], v[16:17], 0, v[12:13]
	global_load_dwordx4 v[12:15], v[12:13], off
	s_and_b64 vcc, exec, s[2:3]
	s_cbranch_vccnz .LBB0_98
	v_lshl_add_u64 v[10:11], v[10:11], 2, s[48:49]
	global_load_dword v10, v[10:11], off
	s_waitcnt vmcnt(0)
	v_mul_f32_e32 v14, v14, v10
	v_mul_f32_e32 v15, v15, v10
	v_mul_f32_e32 v12, v12, v10
	v_mul_f32_e32 v13, v13, v10
.LBB0_98:
	s_or_b64 exec, exec, s[56:57]
	v_mov_b32_e32 v9, 0
	v_mov_b32_e32 v10, 0
	v_mov_b32_e32 v11, 0
	s_and_saveexec_b64 s[56:57], s[54:55]
	s_cbranch_execz .LBB0_101
	v_add_u32_e32 v18, s0, v43
	v_ashrrev_i32_e32 v19, 31, v18
	v_lshlrev_b64 v[8:9], 12, v[18:19]
	v_lshl_add_u64 v[8:9], v[16:17], 0, v[8:9]
	global_load_dwordx4 v[8:11], v[8:9], off
	s_and_b64 vcc, exec, s[2:3]
	s_cbranch_vccnz .LBB0_101
	v_lshl_add_u64 v[16:17], v[18:19], 2, s[48:49]
	global_load_dword v16, v[16:17], off
	s_waitcnt vmcnt(0)
	v_mul_f32_e32 v10, v10, v16
	v_mul_f32_e32 v11, v11, v16
	v_mul_f32_e32 v8, v8, v16
	v_mul_f32_e32 v9, v9, v16
.LBB0_101:
	s_or_b64 exec, exec, s[56:57]
	s_add_i32 s62, s83, s58
	s_ashr_i32 s54, s62, 31
	s_lshr_b32 s54, s54, 30
	s_add_i32 s54, s62, s54
	s_and_b32 s55, s54, 0x3fffffc
	s_sub_i32 s60, s62, s55
	s_lshl_b32 s55, s54, 4
	s_andn2_b32 s55, s55, 63
	v_or_b32_e32 v16, s55, v39
	s_cmp_lt_i32 s62, 64
	s_cselect_b64 s[56:57], -1, 0
	v_cmp_gt_i32_e32 vcc, s81, v16
	v_ashrrev_i32_e32 v17, 31, v16
	s_and_b64 s[58:59], s[56:57], vcc
	s_lshl_b32 s54, s60, 6
	v_lshl_add_u64 v[24:25], v[16:17], 2, s[44:45]
	v_mov_b32_e32 v16, 0
	v_mov_b32_e32 v20, 0
	v_mov_b32_e32 v21, 0
	v_mov_b32_e32 v22, 0
	v_mov_b32_e32 v23, 0
	s_and_saveexec_b64 s[60:61], s[58:59]
	s_cbranch_execz .LBB0_104
	v_add_u32_e32 v18, s54, v42
	v_ashrrev_i32_e32 v19, 31, v18
	v_lshlrev_b64 v[20:21], 12, v[18:19]
	v_lshl_add_u64 v[20:21], v[24:25], 0, v[20:21]
	global_load_dwordx4 v[20:23], v[20:21], off
	s_and_b64 vcc, exec, s[2:3]
	s_cbranch_vccnz .LBB0_104
	v_lshl_add_u64 v[18:19], v[18:19], 2, s[48:49]
	global_load_dword v18, v[18:19], off
	s_waitcnt vmcnt(0)
	v_mul_f32_e32 v22, v22, v18
	v_mul_f32_e32 v23, v23, v18
	v_mul_f32_e32 v20, v20, v18
	v_mul_f32_e32 v21, v21, v18
.LBB0_104:
	s_or_b64 exec, exec, s[60:61]
	v_mov_b32_e32 v17, 0
	v_mov_b32_e32 v18, 0
	v_mov_b32_e32 v19, 0
	s_and_saveexec_b64 s[60:61], s[58:59]
	s_cbranch_execz .LBB0_107
	v_add_u32_e32 v26, s54, v43
	v_ashrrev_i32_e32 v27, 31, v26
	v_lshlrev_b64 v[16:17], 12, v[26:27]
	v_lshl_add_u64 v[16:17], v[24:25], 0, v[16:17]
	global_load_dwordx4 v[16:19], v[16:17], off
	s_and_b64 vcc, exec, s[2:3]
	s_cbranch_vccnz .LBB0_107
	v_lshl_add_u64 v[24:25], v[26:27], 2, s[48:49]
	global_load_dword v24, v[24:25], off
	s_waitcnt vmcnt(0)
	v_mul_f32_e32 v18, v18, v24
	v_mul_f32_e32 v19, v19, v24
	v_mul_f32_e32 v16, v16, v24
	v_mul_f32_e32 v17, v17, v24
.LBB0_107:
	s_or_b64 exec, exec, s[60:61]
	s_add_i32 s84, s83, s62
	s_ashr_i32 s58, s84, 31
	s_lshr_b32 s58, s58, 30
	s_add_i32 s58, s84, s58
	s_and_b32 s59, s58, 0x3fffffc
	s_sub_i32 s64, s84, s59
	s_lshl_b32 s59, s58, 4
	s_andn2_b32 s59, s59, 63
	v_or_b32_e32 v24, s59, v39
	s_cmp_lt_i32 s84, 64
	s_cselect_b64 s[60:61], -1, 0
	v_cmp_gt_i32_e32 vcc, s81, v24
	v_ashrrev_i32_e32 v25, 31, v24
	s_and_b64 s[62:63], s[60:61], vcc
	s_lshl_b32 s58, s64, 6
	v_lshl_add_u64 v[34:35], v[24:25], 2, s[44:45]
	v_mov_b32_e32 v24, 0
	v_mov_b32_e32 v28, 0
	v_mov_b32_e32 v29, 0
	v_mov_b32_e32 v30, 0
	v_mov_b32_e32 v31, 0
	s_and_saveexec_b64 s[64:65], s[62:63]
	s_cbranch_execz .LBB0_110
	v_add_u32_e32 v26, s58, v42
	v_ashrrev_i32_e32 v27, 31, v26
	v_lshlrev_b64 v[28:29], 12, v[26:27]
	v_lshl_add_u64 v[28:29], v[34:35], 0, v[28:29]
	global_load_dwordx4 v[28:31], v[28:29], off
	s_and_b64 vcc, exec, s[2:3]
	s_cbranch_vccnz .LBB0_110
	v_lshl_add_u64 v[26:27], v[26:27], 2, s[48:49]
	global_load_dword v26, v[26:27], off
	s_waitcnt vmcnt(0)
	v_mul_f32_e32 v30, v30, v26
	v_mul_f32_e32 v31, v31, v26
	v_mul_f32_e32 v28, v28, v26
	v_mul_f32_e32 v29, v29, v26
.LBB0_110:
	s_or_b64 exec, exec, s[64:65]
	v_mov_b32_e32 v25, 0
	v_mov_b32_e32 v26, 0
	v_mov_b32_e32 v27, 0
	s_and_saveexec_b64 s[64:65], s[62:63]
	s_cbranch_execz .LBB0_113
	v_add_u32_e32 v36, s58, v43
	v_ashrrev_i32_e32 v37, 31, v36
	v_lshlrev_b64 v[24:25], 12, v[36:37]
	v_lshl_add_u64 v[24:25], v[34:35], 0, v[24:25]
	global_load_dwordx4 v[24:27], v[24:25], off
	s_and_b64 vcc, exec, s[2:3]
	s_cbranch_vccnz .LBB0_113
	v_lshl_add_u64 v[34:35], v[36:37], 2, s[48:49]
	global_load_dword v34, v[34:35], off
	s_waitcnt vmcnt(0)
	v_mul_f32_e32 v26, v26, v34
	v_mul_f32_e32 v27, v27, v34
	v_mul_f32_e32 v24, v24, v34
	v_mul_f32_e32 v25, v25, v34

; DI void prep_wt(const float* __restrict__ src, u16* __restrict__ dst, int K, int N, int Npad,
;                 const float* __restrict__ gain, float* tile) {
;     ...
;     for (int j = 0; j < 4; ++j) {
;       const int t = t0 + j * gridDim.x;
;       const int kt = t % tk, nt = t / tk;
; #pragma unroll
;       for (int i = 0; i < 2; ++i) {
;         const int e = tid + NTHR * i; const int kk = e >> 4, n4 = (e & 15) * 4; const int n = nt * 64 + n4;
;         v[j][i] = (f32x4){0.f, 0.f, 0.f, 0.f};
;         if (t < nt4 && n < N) {
;           v[j][i] = *(const f32x4*)(src + (size_t)(kt * 64 + kk) * N + n);
;           if (gain) v[j][i] *= gain[kt * 64 + kk];
;         }
;       }
.LBB0_147:
	s_ashr_i32 s46, s83, 31
	s_lshr_b32 s46, s46, 28
	s_add_i32 s46, s83, s46
	s_ashr_i32 s46, s46, 4
	s_lshl_b32 s84, s46, 6
	v_or_b32_e32 v0, s84, v36
	s_lshl_b32 s46, s46, 10
	v_ashrrev_i32_e32 v1, 31, v0
	v_cmp_gt_i32_e32 vcc, s80, v0
	s_sub_i32 s85, 0, s46
	v_lshl_add_u64 v[8:9], v[0:1], 2, s[0:1]
	v_mov_b32_e32 v0, 0
	v_mov_b32_e32 v4, 0
	v_mov_b32_e32 v5, 0
	v_mov_b32_e32 v2, 0
	v_mov_b32_e32 v3, 0
	s_and_saveexec_b64 s[46:47], vcc
	s_cbranch_execz .LBB0_149
	s_add_i32 s48, s85, s65
	v_add_u32_e32 v2, s48, v40
	v_ashrrev_i32_e32 v3, 31, v2
	v_mad_i64_i32 v[4:5], s[48:49], v2, s82, v[8:9]
	v_lshl_add_u64 v[2:3], v[2:3], 2, s[40:41]
	global_load_dwordx4 v[4:7], v[4:5], off
	s_nop 0
	global_load_dword v10, v[2:3], off
	s_waitcnt vmcnt(0)
	v_mul_f32_e32 v2, v6, v10
	v_mul_f32_e32 v3, v7, v10
	v_mul_f32_e32 v4, v4, v10
	v_mul_f32_e32 v5, v5, v10
.LBB0_149:
	s_or_b64 exec, exec, s[46:47]
	v_mov_b32_e32 v1, 0
	v_mov_b32_e32 v6, 0
	v_mov_b32_e32 v7, 0
	s_and_saveexec_b64 s[46:47], vcc
	s_cbranch_execz .LBB0_151
	s_add_i32 s48, s85, s65
	v_add_u32_e32 v0, s48, v41
	v_ashrrev_i32_e32 v1, 31, v0
	v_mad_i64_i32 v[6:7], s[48:49], v0, s82, v[8:9]
	v_lshl_add_u64 v[0:1], v[0:1], 2, s[40:41]
	global_load_dwordx4 v[8:11], v[6:7], off
	s_nop 0
	global_load_dword v0, v[0:1], off
	s_waitcnt vmcnt(0)
	v_mul_f32_e32 v6, v10, v0
	v_mul_f32_e32 v7, v11, v0
	v_mul_f32_e32 v1, v9, v0
	v_mul_f32_e32 v0, v8, v0
.LBB0_151:
	s_or_b64 exec, exec, s[46:47]
	s_add_i32 s46, s36, s83
	s_ashr_i32 s47, s46, 31
	s_lshr_b32 s47, s47, 28
	s_add_i32 s47, s46, s47
	s_and_b32 s48, s47, 0x3fffff0
	s_lshl_b32 s47, s47, 2
	s_sub_i32 s52, s46, s48
	s_andn2_b32 s47, s47, 63
	v_or_b32_e32 v8, s47, v36
	s_cmpk_lt_i32 s46, 0x300
	s_cselect_b64 s[48:49], -1, 0
	v_cmp_gt_i32_e32 vcc, s80, v8
	v_ashrrev_i32_e32 v9, 31, v8
	s_and_b64 s[50:51], s[48:49], vcc
	s_lshl_b32 s46, s52, 6
	v_lshl_add_u64 v[16:17], v[8:9], 2, s[0:1]
	v_mov_b32_e32 v8, 0
	v_mov_b32_e32 v12, 0
	v_mov_b32_e32 v13, 0
	v_mov_b32_e32 v10, 0
	v_mov_b32_e32 v11, 0
	s_and_saveexec_b64 s[52:53], s[50:51]
	s_cbranch_execz .LBB0_153
	v_add_u32_e32 v10, s46, v40
	v_ashrrev_i32_e32 v11, 31, v10
	v_mad_i64_i32 v[12:13], s[54:55], v10, s82, v[16:17]
	v_lshl_add_u64 v[10:11], v[10:11], 2, s[40:41]
	global_load_dwordx4 v[12:15], v[12:13], off
	s_nop 0
	global_load_dword v18, v[10:11], off
	s_waitcnt vmcnt(0)
	v_mul_f32_e32 v10, v14, v18
	v_mul_f32_e32 v11, v15, v18
	v_mul_f32_e32 v12, v12, v18
	v_mul_f32_e32 v13, v13, v18
.LBB0_153:
	s_or_b64 exec, exec, s[52:53]
	v_mov_b32_e32 v9, 0
	v_mov_b32_e32 v14, 0
	v_mov_b32_e32 v15, 0
	s_and_saveexec_b64 s[52:53], s[50:51]
	s_cbranch_execz .LBB0_155
	v_add_u32_e32 v8, s46, v41
	v_ashrrev_i32_e32 v9, 31, v8
	v_mad_i64_i32 v[14:15], s[50:51], v8, s82, v[16:17]
	v_lshl_add_u64 v[8:9], v[8:9], 2, s[40:41]
	global_load_dwordx4 v[16:19], v[14:15], off
	s_nop 0
	global_load_dword v8, v[8:9], off
	s_waitcnt vmcnt(0)
	v_mul_f32_e32 v14, v18, v8
	v_mul_f32_e32 v15, v19, v8
	v_mul_f32_e32 v9, v17, v8
	v_mul_f32_e32 v8, v16, v8
.LBB0_155:
	s_or_b64 exec, exec, s[52:53]
	s_add_i32 s50, s64, s83
	s_ashr_i32 s51, s50, 31
	s_lshr_b32 s51, s51, 28
	s_add_i32 s51, s50, s51
	s_and_b32 s52, s51, 0x3fffff0
	s_lshl_b32 s51, s51, 2
	s_sub_i32 s56, s50, s52
	s_andn2_b32 s51, s51, 63
	v_or_b32_e32 v16, s51, v36
	s_cmpk_lt_i32 s50, 0x300
	s_cselect_b64 s[52:53], -1, 0
	v_cmp_gt_i32_e32 vcc, s80, v16
	v_ashrrev_i32_e32 v17, 31, v16
	s_and_b64 s[54:55], s[52:53], vcc
	s_lshl_b32 s50, s56, 6
	v_lshl_add_u64 v[24:25], v[16:17], 2, s[0:1]
	v_mov_b32_e32 v16, 0
	v_mov_b32_e32 v20, 0
	v_mov_b32_e32 v21, 0
	v_mov_b32_e32 v18, 0
	v_mov_b32_e32 v19, 0
	s_and_saveexec_b64 s[56:57], s[54:55]
	s_cbranch_execz .LBB0_157
	v_add_u32_e32 v18, s50, v40
	v_ashrrev_i32_e32 v19, 31, v18
	v_mad_i64_i32 v[20:21], s[58:59], v18, s82, v[24:25]
	v_lshl_add_u64 v[18:19], v[18:19], 2, s[40:41]
	global_load_dwordx4 v[20:23], v[20:21], off
	s_nop 0
	global_load_dword v26, v[18:19], off
	s_waitcnt vmcnt(0)
	v_mul_f32_e32 v18, v22, v26
	v_mul_f32_e32 v19, v23, v26
	v_mul_f32_e32 v20, v20, v26
	v_mul_f32_e32 v21, v21, v26
.LBB0_157:
	s_or_b64 exec, exec, s[56:57]
	v_mov_b32_e32 v17, 0
	v_mov_b32_e32 v22, 0
	v_mov_b32_e32 v23, 0
	s_and_saveexec_b64 s[56:57], s[54:55]
	s_cbranch_execz .LBB0_159
	v_add_u32_e32 v16, s50, v41
	v_ashrrev_i32_e32 v17, 31, v16
	v_mad_i64_i32 v[22:23], s[54:55], v16, s82, v[24:25]
	v_lshl_add_u64 v[16:17], v[16:17], 2, s[40:41]
	global_load_dwordx4 v[24:27], v[22:23], off
	s_nop 0
	global_load_dword v16, v[16:17], off
	s_waitcnt vmcnt(0)
	v_mul_f32_e32 v22, v26, v16
	v_mul_f32_e32 v23, v27, v16
	v_mul_f32_e32 v17, v25, v16
	v_mul_f32_e32 v16, v24, v16
.LBB0_159:
	s_or_b64 exec, exec, s[56:57]
	s_mul_i32 s54, s36, 3
	s_add_i32 s54, s54, s83
	s_ashr_i32 s55, s54, 31
	s_lshr_b32 s55, s55, 28
	s_add_i32 s55, s54, s55
	s_and_b32 s56, s55, 0x3fffff0
	s_lshl_b32 s55, s55, 2
	s_sub_i32 s60, s54, s56
	s_andn2_b32 s55, s55, 63
	v_or_b32_e32 v24, s55, v36
	s_cmpk_lt_i32 s54, 0x300
	s_cselect_b64 s[56:57], -1, 0
	v_cmp_gt_i32_e32 vcc, s80, v24
	v_ashrrev_i32_e32 v25, 31, v24
	s_and_b64 s[58:59], s[56:57], vcc
	s_lshl_b32 s54, s60, 6
	v_lshl_add_u64 v[34:35], v[24:25], 2, s[0:1]
	v_mov_b32_e32 v24, 0
	v_mov_b32_e32 v28, 0
	v_mov_b32_e32 v29, 0
	v_mov_b32_e32 v26, 0
	v_mov_b32_e32 v27, 0
	s_and_saveexec_b64 s[60:61], s[58:59]
	s_cbranch_execz .LBB0_161
	v_add_u32_e32 v26, s54, v40
	v_ashrrev_i32_e32 v27, 31, v26
	v_mad_i64_i32 v[28:29], s[86:87], v26, s82, v[34:35]
	v_lshl_add_u64 v[26:27], v[26:27], 2, s[40:41]
	global_load_dwordx4 v[28:31], v[28:29], off
	s_nop 0
	global_load_dword v44, v[26:27], off
	s_waitcnt vmcnt(0)
	v_mul_f32_e32 v26, v30, v44
	v_mul_f32_e32 v27, v31, v44
	v_mul_f32_e32 v28, v28, v44
	v_mul_f32_e32 v29, v29, v44
.LBB0_161:
	s_or_b64 exec, exec, s[60:61]
	v_mov_b32_e32 v25, 0
	v_mov_b32_e32 v30, 0
	v_mov_b32_e32 v31, 0
	s_and_saveexec_b64 s[60:61], s[58:59]
	s_cbranch_execz .LBB0_163
	v_add_u32_e32 v24, s54, v41
	v_ashrrev_i32_e32 v25, 31, v24
	v_mad_i64_i32 v[30:31], s[58:59], v24, s82, v[34:35]
	v_lshl_add_u64 v[24:25], v[24:25], 2, s[40:41]
	global_load_dwordx4 v[44:47], v[30:31], off
	s_nop 0
	global_load_dword v24, v[24:25], off
	s_waitcnt vmcnt(0)
	v_mul_f32_e32 v30, v46, v24
	v_mul_f32_e32 v31, v47, v24
	v_mul_f32_e32 v25, v45, v24
	v_mul_f32_e32 v24, v44, v24

; DI void prep_wt(const float* __restrict__ src, u16* __restrict__ dst, int K, int N, int Npad,
;                 const float* __restrict__ gain, float* tile) {
;     ...
;     for (int j = 0; j < 4; ++j) {
;       const int t = t0 + j * gridDim.x;
;       const int kt = t % tk, nt = t / tk;
; #pragma unroll
;       for (int i = 0; i < 2; ++i) {
;         const int e = tid + NTHR * i; const int kk = e >> 4, n4 = (e & 15) * 4; const int n = nt * 64 + n4;
;         v[j][i] = (f32x4){0.f, 0.f, 0.f, 0.f};
;         if (t < nt4 && n < N) {
;           v[j][i] = *(const f32x4*)(src + (size_t)(kt * 64 + kk) * N + n);
;           if (gain) v[j][i] *= gain[kt * 64 + kk];
;         }
;       }
.LBB0_199:
	s_ashr_i32 s0, s34, 31
	s_lshr_b32 s0, s0, 28
	s_add_i32 s0, s34, s0
	s_lshl_b32 s29, s0, 2
	s_andn2_b32 s29, s29, 63
	s_and_b32 s1, s0, 0x3fffff0
	v_or_b32_e32 v0, s29, v38
	s_sub_i32 s28, s34, s1
	v_ashrrev_i32_e32 v1, 31, v0
	v_cmp_gt_i32_e64 s[0:1], s50, v0
	s_lshl_b32 s28, s28, 6
	v_lshl_add_u64 v[8:9], v[0:1], 2, s[8:9]
	v_mov_b32_e32 v0, 0
	v_mov_b32_e32 v4, 0
	v_mov_b32_e32 v5, 0
	v_mov_b32_e32 v6, 0
	v_mov_b32_e32 v7, 0
	s_and_saveexec_b64 s[30:31], s[0:1]
	s_cbranch_execz .LBB0_202
	v_add_u32_e32 v2, s28, v41
	v_ashrrev_i32_e32 v3, 31, v2
	v_lshlrev_b64 v[4:5], 14, v[2:3]
	v_lshl_add_u64 v[4:5], v[8:9], 0, v[4:5]
	global_load_dwordx4 v[4:7], v[4:5], off
	s_and_b64 vcc, exec, s[4:5]
	s_cbranch_vccnz .LBB0_202
	v_lshl_add_u64 v[2:3], v[2:3], 2, s[22:23]
	global_load_dword v2, v[2:3], off
	s_waitcnt vmcnt(0)
	v_mul_f32_e32 v6, v6, v2
	v_mul_f32_e32 v7, v7, v2
	v_mul_f32_e32 v4, v4, v2
	v_mul_f32_e32 v5, v5, v2
.LBB0_202:
	s_or_b64 exec, exec, s[30:31]
	v_mov_b32_e32 v1, 0
	v_mov_b32_e32 v2, 0
	v_mov_b32_e32 v3, 0
	s_and_saveexec_b64 s[30:31], s[0:1]
	s_cbranch_execz .LBB0_205
	v_add_u32_e32 v10, s28, v42
	v_ashrrev_i32_e32 v11, 31, v10
	v_lshlrev_b64 v[0:1], 14, v[10:11]
	v_lshl_add_u64 v[0:1], v[8:9], 0, v[0:1]
	global_load_dwordx4 v[0:3], v[0:1], off
	s_and_b64 vcc, exec, s[4:5]
	s_cbranch_vccnz .LBB0_205
	v_lshl_add_u64 v[8:9], v[10:11], 2, s[22:23]
	global_load_dword v8, v[8:9], off
	s_waitcnt vmcnt(0)
	v_mul_f32_e32 v2, v2, v8
	v_mul_f32_e32 v3, v3, v8
	v_mul_f32_e32 v0, v0, v8
	v_mul_f32_e32 v1, v1, v8
.LBB0_205:
	s_or_b64 exec, exec, s[30:31]
	s_add_i32 s38, s52, s34
	s_ashr_i32 s0, s38, 31
	s_lshr_b32 s0, s0, 28
	s_add_i32 s0, s38, s0
	s_and_b32 s1, s0, 0x3fffff0
	s_sub_i32 s36, s38, s1
	s_lshl_b32 s1, s0, 2
	s_andn2_b32 s1, s1, 63
	v_or_b32_e32 v8, s1, v38
	s_cmpk_lt_i32 s38, 0x400
	s_cselect_b64 s[30:31], -1, 0
	v_cmp_gt_i32_e32 vcc, s50, v8
	v_ashrrev_i32_e32 v9, 31, v8
	s_and_b64 s[34:35], s[30:31], vcc
	s_lshl_b32 s0, s36, 6
	v_lshl_add_u64 v[16:17], v[8:9], 2, s[8:9]
	v_mov_b32_e32 v8, 0
	v_mov_b32_e32 v12, 0
	v_mov_b32_e32 v13, 0
	v_mov_b32_e32 v14, 0
	v_mov_b32_e32 v15, 0
	s_and_saveexec_b64 s[36:37], s[34:35]
	s_cbranch_execz .LBB0_208
	v_add_u32_e32 v10, s0, v41
	v_ashrrev_i32_e32 v11, 31, v10
	v_lshlrev_b64 v[12:13], 14, v[10:11]
	v_lshl_add_u64 v[12:13], v[16:17], 0, v[12:13]
	global_load_dwordx4 v[12:15], v[12:13], off
	s_and_b64 vcc, exec, s[4:5]
	s_cbranch_vccnz .LBB0_208
	v_lshl_add_u64 v[10:11], v[10:11], 2, s[22:23]
	global_load_dword v10, v[10:11], off
	s_waitcnt vmcnt(0)
	v_mul_f32_e32 v14, v14, v10
	v_mul_f32_e32 v15, v15, v10
	v_mul_f32_e32 v12, v12, v10
	v_mul_f32_e32 v13, v13, v10
.LBB0_208:
	s_or_b64 exec, exec, s[36:37]
	v_mov_b32_e32 v9, 0
	v_mov_b32_e32 v10, 0
	v_mov_b32_e32 v11, 0
	s_and_saveexec_b64 s[36:37], s[34:35]
	s_cbranch_execz .LBB0_211
	v_add_u32_e32 v18, s0, v42
	v_ashrrev_i32_e32 v19, 31, v18
	v_lshlrev_b64 v[8:9], 14, v[18:19]
	v_lshl_add_u64 v[8:9], v[16:17], 0, v[8:9]
	global_load_dwordx4 v[8:11], v[8:9], off
	s_and_b64 vcc, exec, s[4:5]
	s_cbranch_vccnz .LBB0_211
	v_lshl_add_u64 v[16:17], v[18:19], 2, s[22:23]
	global_load_dword v16, v[16:17], off
	s_waitcnt vmcnt(0)
	v_mul_f32_e32 v10, v10, v16
	v_mul_f32_e32 v11, v11, v16
	v_mul_f32_e32 v8, v8, v16
	v_mul_f32_e32 v9, v9, v16
.LBB0_211:
	s_or_b64 exec, exec, s[36:37]
	s_add_i32 s42, s52, s38
	s_ashr_i32 s34, s42, 31
	s_lshr_b32 s34, s34, 28
	s_add_i32 s34, s42, s34
	s_and_b32 s35, s34, 0x3fffff0
	s_sub_i32 s40, s42, s35
	s_lshl_b32 s35, s34, 2
	s_andn2_b32 s35, s35, 63
	v_or_b32_e32 v16, s35, v38
	s_cmpk_lt_i32 s42, 0x400
	s_cselect_b64 s[36:37], -1, 0
	v_cmp_gt_i32_e32 vcc, s50, v16
	v_ashrrev_i32_e32 v17, 31, v16
	s_and_b64 s[38:39], s[36:37], vcc
	s_lshl_b32 s34, s40, 6
	v_lshl_add_u64 v[24:25], v[16:17], 2, s[8:9]
	v_mov_b32_e32 v16, 0
	v_mov_b32_e32 v20, 0
	v_mov_b32_e32 v21, 0
	v_mov_b32_e32 v22, 0
	v_mov_b32_e32 v23, 0
	s_and_saveexec_b64 s[40:41], s[38:39]
	s_cbranch_execz .LBB0_214
	v_add_u32_e32 v18, s34, v41
	v_ashrrev_i32_e32 v19, 31, v18
	v_lshlrev_b64 v[20:21], 14, v[18:19]
	v_lshl_add_u64 v[20:21], v[24:25], 0, v[20:21]
	global_load_dwordx4 v[20:23], v[20:21], off
	s_and_b64 vcc, exec, s[4:5]
	s_cbranch_vccnz .LBB0_214
	v_lshl_add_u64 v[18:19], v[18:19], 2, s[22:23]
	global_load_dword v18, v[18:19], off
	s_waitcnt vmcnt(0)
	v_mul_f32_e32 v22, v22, v18
	v_mul_f32_e32 v23, v23, v18
	v_mul_f32_e32 v20, v20, v18
	v_mul_f32_e32 v21, v21, v18
.LBB0_214:
	s_or_b64 exec, exec, s[40:41]
	v_mov_b32_e32 v17, 0
	v_mov_b32_e32 v18, 0
	v_mov_b32_e32 v19, 0
	s_and_saveexec_b64 s[40:41], s[38:39]
	s_cbranch_execz .LBB0_217
	v_add_u32_e32 v26, s34, v42
	v_ashrrev_i32_e32 v27, 31, v26
	v_lshlrev_b64 v[16:17], 14, v[26:27]
	v_lshl_add_u64 v[16:17], v[24:25], 0, v[16:17]
	global_load_dwordx4 v[16:19], v[16:17], off
	s_and_b64 vcc, exec, s[4:5]
	s_cbranch_vccnz .LBB0_217
	v_lshl_add_u64 v[24:25], v[26:27], 2, s[22:23]
	global_load_dword v24, v[24:25], off
	s_waitcnt vmcnt(0)
	v_mul_f32_e32 v18, v18, v24
	v_mul_f32_e32 v19, v19, v24
	v_mul_f32_e32 v16, v16, v24
	v_mul_f32_e32 v17, v17, v24
.LBB0_217:
	s_or_b64 exec, exec, s[40:41]
	s_add_i32 s53, s52, s42
	s_ashr_i32 s38, s53, 31
	s_lshr_b32 s38, s38, 28
	s_add_i32 s38, s53, s38
	s_and_b32 s39, s38, 0x3fffff0
	s_sub_i32 s44, s53, s39
	s_lshl_b32 s39, s38, 2
	s_andn2_b32 s39, s39, 63
	v_or_b32_e32 v24, s39, v38
	s_cmpk_lt_i32 s53, 0x400
	s_cselect_b64 s[40:41], -1, 0
	v_cmp_gt_i32_e32 vcc, s50, v24
	v_ashrrev_i32_e32 v25, 31, v24
	s_and_b64 s[42:43], s[40:41], vcc
	s_lshl_b32 s38, s44, 6
	v_lshl_add_u64 v[34:35], v[24:25], 2, s[8:9]
	v_mov_b32_e32 v24, 0
	v_mov_b32_e32 v28, 0
	v_mov_b32_e32 v29, 0
	v_mov_b32_e32 v30, 0
	v_mov_b32_e32 v31, 0
	s_and_saveexec_b64 s[44:45], s[42:43]
	s_cbranch_execz .LBB0_220
	v_add_u32_e32 v26, s38, v41
	v_ashrrev_i32_e32 v27, 31, v26
	v_lshlrev_b64 v[28:29], 14, v[26:27]
	v_lshl_add_u64 v[28:29], v[34:35], 0, v[28:29]
	global_load_dwordx4 v[28:31], v[28:29], off
	s_and_b64 vcc, exec, s[4:5]
	s_cbranch_vccnz .LBB0_220
	v_lshl_add_u64 v[26:27], v[26:27], 2, s[22:23]
	global_load_dword v26, v[26:27], off
	s_waitcnt vmcnt(0)
	v_mul_f32_e32 v30, v30, v26
	v_mul_f32_e32 v31, v31, v26
	v_mul_f32_e32 v28, v28, v26
	v_mul_f32_e32 v29, v29, v26
.LBB0_220:
	s_or_b64 exec, exec, s[44:45]
	v_mov_b32_e32 v25, 0
	v_mov_b32_e32 v26, 0
	v_mov_b32_e32 v27, 0
	s_and_saveexec_b64 s[44:45], s[42:43]
	s_cbranch_execz .LBB0_223
	v_add_u32_e32 v36, s38, v42
	v_ashrrev_i32_e32 v37, 31, v36
	v_lshlrev_b64 v[24:25], 14, v[36:37]
	v_lshl_add_u64 v[24:25], v[34:35], 0, v[24:25]
	global_load_dwordx4 v[24:27], v[24:25], off
	s_and_b64 vcc, exec, s[4:5]
	s_cbranch_vccnz .LBB0_223
	v_lshl_add_u64 v[34:35], v[36:37], 2, s[22:23]
	global_load_dword v34, v[34:35], off
	s_waitcnt vmcnt(0)
	v_mul_f32_e32 v26, v26, v34
	v_mul_f32_e32 v27, v27, v34
	v_mul_f32_e32 v24, v24, v34
	v_mul_f32_e32 v25, v25, v34

; #define PG8_STAGE(bufoff, gbase, voff) do { _Pragma("unroll") for (int _i = 0; _i < 2; ++_i) \
;     __builtin_amdgcn_global_load_lds((const unsigned*)((const char*)(gbase) + (voff)[_i]), (LAS unsigned*)(lds + (bufoff) + ldsw + _i * 8192), 16, 0, 0); } while (0)
; #define PG8_LDA(dst, b, h) do { _Pragma("unroll") for (int m = 0; m < 4; ++m) _Pragma("unroll") for (int k = 0; k < 2; ++k) dst[m][k] = *(const LAS bf16x8*)(lds + PG8_SA(b, h) + aoff + m * 2048 + k * 1024); } while (0)
; #define PG8_LDB(dst, b, h) do { _Pragma("unroll") for (int n = 0; n < 2; ++n) _Pragma("unroll") for (int k = 0; k < 2; ++k) dst[n][k] = *(const LAS bf16x8*)(lds + PG8_SB(b, h) + boff + n * 2048 + k * 1024); } while (0)
; #define PG8_MMA(ai, bj, At, Bt) do { __builtin_amdgcn_s_setprio(1); _Pragma("unroll") for (int m = 0; m < 4; ++m) _Pragma("unroll") for (int n = 0; n < 2; ++n) _Pragma("unroll") for (int k = 0; k < 2; ++k) \
;     acc[ai][bj][m][n] = __builtin_amdgcn_mfma_f32_16x16x32_bf16(Bt[n][k], At[m][k], acc[ai][bj][m][n], 0, 0, 0); __builtin_amdgcn_s_setprio(0); } while (0)
; #define PG8_WAIT_V(n) asm volatile("s_waitcnt vmcnt(" #n ")" ::: "memory")
; #define PG8_WAIT_L(n) asm volatile("s_waitcnt lgkmcnt(" #n ")" ::: "memory")
; #define PG8_BAR __builtin_amdgcn_s_barrier()
; #define PG8_SCHED __builtin_amdgcn_sched_barrier(0)
; template <class Epi, class Sched>
; DI void gemm_phase(LAS unsigned char* lds, const Gemm g, const Sched& S, const Epi& E) {
;     ...
;       PG8_LDB(B0, 0, 0); PG8_SCHED; PG8_LDA(At, 0, 0); PG8_STAGE(PG8_SA(1, 1), a1 + hstep, voffA);
;       PG8_WAIT_L(8); PG8_BAR; PG8_WAIT_L(0); PG8_MMA(0, 0, At, B0); PG8_BAR; PG8_SCHED;
;       PG8_LDB(B1, 0, 1); PG8_STAGE(PG8_SB(0, 0), b2, voffB);
;       PG8_BAR; PG8_WAIT_L(0); PG8_MMA(0, 1, At, B1); PG8_BAR;
;       PG8_LDA(At, 0, 1); PG8_STAGE(PG8_SA(0, 0), a2, voffA);
;       PG8_BAR; PG8_WAIT_L(0); PG8_MMA(1, 0, At, B0); PG8_BAR; PG8_SCHED;
;       PG8_STAGE(PG8_SB(0, 1), b2 + hstep, voffB);
;       PG8_WAIT_V(6); PG8_BAR; PG8_MMA(1, 1, At, B1); PG8_BAR;
.LBB0_370:
	s_add_u32 s4, s2, 0xfffc0080
	s_addc_u32 s5, s3, -1
	s_add_i32 s51, 0, 0x10000
	ds_read_b128 v[128:131], v228
	ds_read_b128 v[146:149], v228 offset:1024
	ds_read_b128 v[150:153], v228 offset:2048
	ds_read_b128 v[160:163], v228 offset:3072
	s_cmp_eq_u32 s50, 12
	s_cselect_b32 s21, s15, s5
	s_cselect_b32 s20, s29, s4
	s_cselect_b32 s5, s13, s49
	s_cselect_b32 s4, s36, s37
	s_add_i32 m0, s40, 0xc000
	ds_read_b128 v[164:167], v158
	ds_read_b128 v[168:171], v158 offset:1024
	ds_read_b128 v[172:175], v158 offset:2048
	ds_read_b128 v[176:179], v158 offset:3072
	ds_read_b128 v[196:199], v158 offset:4096
	ds_read_b128 v[200:203], v158 offset:5120
	ds_read_b128 v[204:207], v158 offset:6144
	ds_read_b128 v[208:211], v158 offset:7168
	global_load_lds_dwordx4 v140, s[2:3]
	s_add_i32 m0, s40, 0xe000
	s_nop 0
	global_load_lds_dwordx4 v142, s[2:3]
	s_waitcnt lgkmcnt(8)
	s_barrier
	s_waitcnt lgkmcnt(0)
	v_mfma_f32_16x16x32_bf16 v[124:127], v[128:131], v[164:167], v[124:127]
	v_mfma_f32_16x16x32_bf16 v[120:123], v[150:153], v[164:167], v[120:123]
	v_mfma_f32_16x16x32_bf16 v[108:111], v[128:131], v[172:175], v[108:111]
	v_mfma_f32_16x16x32_bf16 v[104:107], v[150:153], v[172:175], v[104:107]
	v_mfma_f32_16x16x32_bf16 v[92:95], v[128:131], v[196:199], v[92:95]
	v_mfma_f32_16x16x32_bf16 v[88:91], v[150:153], v[196:199], v[88:91]
	v_mfma_f32_16x16x32_bf16 v[76:79], v[128:131], v[204:207], v[76:79]
	v_mfma_f32_16x16x32_bf16 v[72:75], v[150:153], v[204:207], v[72:75]
	v_mfma_f32_16x16x32_bf16 v[124:127], v[146:149], v[168:171], v[124:127]
	v_mfma_f32_16x16x32_bf16 v[120:123], v[160:163], v[168:171], v[120:123]
	v_mfma_f32_16x16x32_bf16 v[108:111], v[146:149], v[176:179], v[108:111]
	v_mfma_f32_16x16x32_bf16 v[104:107], v[160:163], v[176:179], v[104:107]
	v_mfma_f32_16x16x32_bf16 v[92:95], v[146:149], v[200:203], v[92:95]
	v_mfma_f32_16x16x32_bf16 v[88:91], v[160:163], v[200:203], v[88:91]
	v_mfma_f32_16x16x32_bf16 v[76:79], v[146:149], v[208:211], v[76:79]
	v_mfma_f32_16x16x32_bf16 v[72:75], v[160:163], v[208:211], v[72:75]
	s_barrier
	s_add_i32 s54, 0, 0x14000
	s_add_i32 s51, s51, s34
	s_add_u32 vcc_lo, s4, s0
	s_addc_u32 vcc_hi, s5, s1
	s_mov_b32 m0, s51
	ds_read_b128 v[212:215], v229
	ds_read_b128 v[216:219], v229 offset:1024
	ds_read_b128 v[220:223], v229 offset:2048
	ds_read_b128 v[224:227], v229 offset:3072
	global_load_lds_dwordx4 v136, s[4:5]
	s_add_i32 m0, s51, 0x2000
	s_nop 0
	global_load_lds_dwordx4 v132, s[4:5]
	s_barrier
	s_waitcnt lgkmcnt(0)
	v_mfma_f32_16x16x32_bf16 v[116:119], v[212:215], v[164:167], v[116:119]
	v_mfma_f32_16x16x32_bf16 v[112:115], v[220:223], v[164:167], v[112:115]
	v_mfma_f32_16x16x32_bf16 v[100:103], v[212:215], v[172:175], v[100:103]
	v_mfma_f32_16x16x32_bf16 v[96:99], v[220:223], v[172:175], v[96:99]
	v_mfma_f32_16x16x32_bf16 v[84:87], v[212:215], v[196:199], v[84:87]
	v_mfma_f32_16x16x32_bf16 v[80:83], v[220:223], v[196:199], v[80:83]
	v_mfma_f32_16x16x32_bf16 v[68:71], v[212:215], v[204:207], v[68:71]
	v_mfma_f32_16x16x32_bf16 v[64:67], v[220:223], v[204:207], v[64:67]
	v_mfma_f32_16x16x32_bf16 v[116:119], v[216:219], v[168:171], v[116:119]
	v_mfma_f32_16x16x32_bf16 v[112:115], v[224:227], v[168:171], v[112:115]
	v_mfma_f32_16x16x32_bf16 v[100:103], v[216:219], v[176:179], v[100:103]
	v_mfma_f32_16x16x32_bf16 v[96:99], v[224:227], v[176:179], v[96:99]
	v_mfma_f32_16x16x32_bf16 v[84:87], v[216:219], v[200:203], v[84:87]
	v_mfma_f32_16x16x32_bf16 v[80:83], v[224:227], v[200:203], v[80:83]
	v_mfma_f32_16x16x32_bf16 v[68:71], v[216:219], v[208:211], v[68:71]
	v_mfma_f32_16x16x32_bf16 v[64:67], v[224:227], v[208:211], v[64:67]
	s_mov_b32 m0, s40
	s_add_u32 s100, s20, s0
	s_addc_u32 s101, s21, s1
	s_barrier
	ds_read_b128 v[164:167], v158 offset:16384
	ds_read_b128 v[168:171], v158 offset:17408
	ds_read_b128 v[172:175], v158 offset:18432
	ds_read_b128 v[176:179], v158 offset:19456
	ds_read_b128 v[196:199], v158 offset:20480
	ds_read_b128 v[200:203], v158 offset:21504
	ds_read_b128 v[204:207], v158 offset:22528
	ds_read_b128 v[208:211], v158 offset:23552
	global_load_lds_dwordx4 v138, s[20:21]
	s_mov_b32 m0, s41
	s_nop 0
	global_load_lds_dwordx4 v134, s[20:21]
	s_barrier
	s_waitcnt lgkmcnt(0)
	v_mfma_f32_16x16x32_bf16 v[60:63], v[128:131], v[164:167], v[60:63]
	v_mfma_f32_16x16x32_bf16 v[56:59], v[150:153], v[164:167], v[56:59]
	v_mfma_f32_16x16x32_bf16 v[44:47], v[128:131], v[172:175], v[44:47]
	v_mfma_f32_16x16x32_bf16 v[40:43], v[150:153], v[172:175], v[40:43]
	v_mfma_f32_16x16x32_bf16 v[28:31], v[128:131], v[196:199], v[28:31]
	v_mfma_f32_16x16x32_bf16 v[24:27], v[150:153], v[196:199], v[24:27]
	v_mfma_f32_16x16x32_bf16 v[12:15], v[128:131], v[204:207], v[12:15]
	v_mfma_f32_16x16x32_bf16 v[8:11], v[150:153], v[204:207], v[8:11]
	v_mfma_f32_16x16x32_bf16 v[60:63], v[146:149], v[168:171], v[60:63]
	v_mfma_f32_16x16x32_bf16 v[56:59], v[160:163], v[168:171], v[56:59]
	v_mfma_f32_16x16x32_bf16 v[44:47], v[146:149], v[176:179], v[44:47]
	v_mfma_f32_16x16x32_bf16 v[40:43], v[160:163], v[176:179], v[40:43]
	v_mfma_f32_16x16x32_bf16 v[28:31], v[146:149], v[200:203], v[28:31]
	v_mfma_f32_16x16x32_bf16 v[24:27], v[160:163], v[200:203], v[24:27]
	v_mfma_f32_16x16x32_bf16 v[12:15], v[146:149], v[208:211], v[12:15]
	v_mfma_f32_16x16x32_bf16 v[8:11], v[160:163], v[208:211], v[8:11]
	s_barrier
	s_add_u32 s52, s4, 0x40000
	s_addc_u32 s53, s5, 0
	s_add_i32 s51, s54, s34
	s_mov_b32 m0, s51
	s_nop 0
	global_load_lds_dwordx4 v136, s[52:53]
	s_add_i32 m0, s51, 0x2000
	s_nop 0
	global_load_lds_dwordx4 v132, s[52:53]
	s_waitcnt vmcnt(6)
	s_barrier
; #define PG8_STAGE(bufoff, gbase, voff) do { _Pragma("unroll") for (int _i = 0; _i < 2; ++_i) \
;     __builtin_amdgcn_global_load_lds((const unsigned*)((const char*)(gbase) + (voff)[_i]), (LAS unsigned*)(lds + (bufoff) + ldsw + _i * 8192), 16, 0, 0); } while (0)
; #define PG8_LDA(dst, b, h) do { _Pragma("unroll") for (int m = 0; m < 4; ++m) _Pragma("unroll") for (int k = 0; k < 2; ++k) dst[m][k] = *(const LAS bf16x8*)(lds + PG8_SA(b, h) + aoff + m * 2048 + k * 1024); } while (0)
; #define PG8_LDB(dst, b, h) do { _Pragma("unroll") for (int n = 0; n < 2; ++n) _Pragma("unroll") for (int k = 0; k < 2; ++k) dst[n][k] = *(const LAS bf16x8*)(lds + PG8_SB(b, h) + boff + n * 2048 + k * 1024); } while (0)
; #define PG8_MMA(ai, bj, At, Bt) do { __builtin_amdgcn_s_setprio(1); _Pragma("unroll") for (int m = 0; m < 4; ++m) _Pragma("unroll") for (int n = 0; n < 2; ++n) _Pragma("unroll") for (int k = 0; k < 2; ++k) \
;     acc[ai][bj][m][n] = __builtin_amdgcn_mfma_f32_16x16x32_bf16(Bt[n][k], At[m][k], acc[ai][bj][m][n], 0, 0, 0); __builtin_amdgcn_s_setprio(0); } while (0)
; #define PG8_WAIT_V(n) asm volatile("s_waitcnt vmcnt(" #n ")" ::: "memory")
; #define PG8_WAIT_L(n) asm volatile("s_waitcnt lgkmcnt(" #n ")" ::: "memory")
; #define PG8_BAR __builtin_amdgcn_s_barrier()
; #define PG8_SCHED __builtin_amdgcn_sched_barrier(0)
; template <class Epi, class Sched>
; DI void gemm_phase(LAS unsigned char* lds, const Gemm g, const Sched& S, const Epi& E) {
;     ...
;       PG8_WAIT_V(6); PG8_BAR; PG8_MMA(1, 1, At, B1); PG8_BAR;
;       PG8_LDB(B0, 1, 0); PG8_SCHED; PG8_LDA(At, 1, 0); PG8_STAGE(PG8_SA(0, 1), a2 + hstep, voffA);
;       PG8_WAIT_L(8); PG8_BAR; PG8_WAIT_L(0); PG8_MMA(0, 0, At, B0); PG8_BAR; PG8_SCHED;
;       PG8_LDB(B1, 1, 1); PG8_STAGE(PG8_SB(1, 0), b3, voffB);
;       PG8_BAR; PG8_WAIT_L(0); PG8_MMA(0, 1, At, B1); PG8_BAR;
;       PG8_LDA(At, 1, 1); PG8_STAGE(PG8_SA(1, 0), a3, voffA);
;       PG8_BAR; PG8_WAIT_L(0); PG8_MMA(1, 0, At, B0); PG8_BAR; PG8_SCHED;
	v_mfma_f32_16x16x32_bf16 v[52:55], v[212:215], v[164:167], v[52:55]
	v_mfma_f32_16x16x32_bf16 v[48:51], v[220:223], v[164:167], v[48:51]
	v_mfma_f32_16x16x32_bf16 v[36:39], v[212:215], v[172:175], v[36:39]
	v_mfma_f32_16x16x32_bf16 v[32:35], v[220:223], v[172:175], v[32:35]
	v_mfma_f32_16x16x32_bf16 v[20:23], v[212:215], v[196:199], v[20:23]
	v_mfma_f32_16x16x32_bf16 v[16:19], v[220:223], v[196:199], v[16:19]
	v_mfma_f32_16x16x32_bf16 v[4:7], v[212:215], v[204:207], v[4:7]
	v_mfma_f32_16x16x32_bf16 v[0:3], v[220:223], v[204:207], v[0:3]
	v_mfma_f32_16x16x32_bf16 v[52:55], v[216:219], v[168:171], v[52:55]
	v_mfma_f32_16x16x32_bf16 v[48:51], v[224:227], v[168:171], v[48:51]
	v_mfma_f32_16x16x32_bf16 v[36:39], v[216:219], v[176:179], v[36:39]
	v_mfma_f32_16x16x32_bf16 v[32:35], v[224:227], v[176:179], v[32:35]
	v_mfma_f32_16x16x32_bf16 v[20:23], v[216:219], v[200:203], v[20:23]
	v_mfma_f32_16x16x32_bf16 v[16:19], v[224:227], v[200:203], v[16:19]
	v_mfma_f32_16x16x32_bf16 v[4:7], v[216:219], v[208:211], v[4:7]
	v_mfma_f32_16x16x32_bf16 v[0:3], v[224:227], v[208:211], v[0:3]
	s_add_i32 s51, 0, 0x18000
	s_barrier
	ds_read_b128 v[128:131], v230
	ds_read_b128 v[146:149], v230 offset:1024
	ds_read_b128 v[150:153], v230 offset:2048
	ds_read_b128 v[160:163], v230 offset:3072
	s_add_u32 s20, s20, 0x40000
	s_addc_u32 s21, s21, 0
	s_mov_b32 m0, s42
	ds_read_b128 v[164:167], v158 offset:32768
	ds_read_b128 v[168:171], v158 offset:33792
	ds_read_b128 v[172:175], v158 offset:34816
	ds_read_b128 v[176:179], v158 offset:35840
	ds_read_b128 v[196:199], v158 offset:36864
	ds_read_b128 v[200:203], v158 offset:37888
	ds_read_b128 v[204:207], v158 offset:38912
	ds_read_b128 v[208:211], v158 offset:39936
	global_load_lds_dwordx4 v138, s[20:21]
	s_mov_b32 m0, s43
	s_nop 0
	global_load_lds_dwordx4 v134, s[20:21]
	s_waitcnt lgkmcnt(8)
	s_barrier
	s_waitcnt lgkmcnt(0)
	v_mfma_f32_16x16x32_bf16 v[124:127], v[128:131], v[164:167], v[124:127]
	v_mfma_f32_16x16x32_bf16 v[120:123], v[150:153], v[164:167], v[120:123]
	v_mfma_f32_16x16x32_bf16 v[108:111], v[128:131], v[172:175], v[108:111]
	v_mfma_f32_16x16x32_bf16 v[104:107], v[150:153], v[172:175], v[104:107]
	v_mfma_f32_16x16x32_bf16 v[92:95], v[128:131], v[196:199], v[92:95]
	v_mfma_f32_16x16x32_bf16 v[88:91], v[150:153], v[196:199], v[88:91]
	v_mfma_f32_16x16x32_bf16 v[76:79], v[128:131], v[204:207], v[76:79]
	v_mfma_f32_16x16x32_bf16 v[72:75], v[150:153], v[204:207], v[72:75]
	v_mfma_f32_16x16x32_bf16 v[124:127], v[146:149], v[168:171], v[124:127]
	v_mfma_f32_16x16x32_bf16 v[120:123], v[160:163], v[168:171], v[120:123]
	v_mfma_f32_16x16x32_bf16 v[108:111], v[146:149], v[176:179], v[108:111]
	v_mfma_f32_16x16x32_bf16 v[104:107], v[160:163], v[176:179], v[104:107]
	v_mfma_f32_16x16x32_bf16 v[92:95], v[146:149], v[200:203], v[92:95]
	v_mfma_f32_16x16x32_bf16 v[88:91], v[160:163], v[200:203], v[88:91]
	v_mfma_f32_16x16x32_bf16 v[76:79], v[146:149], v[208:211], v[76:79]
	v_mfma_f32_16x16x32_bf16 v[72:75], v[160:163], v[208:211], v[72:75]
	s_barrier
	s_add_i32 s20, 0, 0x1c000
	s_add_i32 s21, s51, s34
	s_mov_b32 m0, s21
	ds_read_b128 v[212:215], v231
	ds_read_b128 v[216:219], v231 offset:1024
	ds_read_b128 v[220:223], v231 offset:2048
	ds_read_b128 v[224:227], v231 offset:3072
	global_load_lds_dwordx4 v136, vcc
	s_add_i32 m0, s21, 0x2000
	s_nop 0
	global_load_lds_dwordx4 v132, vcc
	s_barrier
	s_waitcnt lgkmcnt(0)
	v_mfma_f32_16x16x32_bf16 v[116:119], v[212:215], v[164:167], v[116:119]
	v_mfma_f32_16x16x32_bf16 v[112:115], v[220:223], v[164:167], v[112:115]
	v_mfma_f32_16x16x32_bf16 v[100:103], v[212:215], v[172:175], v[100:103]
	v_mfma_f32_16x16x32_bf16 v[96:99], v[220:223], v[172:175], v[96:99]
	v_mfma_f32_16x16x32_bf16 v[84:87], v[212:215], v[196:199], v[84:87]
	v_mfma_f32_16x16x32_bf16 v[80:83], v[220:223], v[196:199], v[80:83]
	v_mfma_f32_16x16x32_bf16 v[68:71], v[212:215], v[204:207], v[68:71]
	v_mfma_f32_16x16x32_bf16 v[64:67], v[220:223], v[204:207], v[64:67]
	v_mfma_f32_16x16x32_bf16 v[116:119], v[216:219], v[168:171], v[116:119]
	v_mfma_f32_16x16x32_bf16 v[112:115], v[224:227], v[168:171], v[112:115]
	v_mfma_f32_16x16x32_bf16 v[100:103], v[216:219], v[176:179], v[100:103]
	v_mfma_f32_16x16x32_bf16 v[96:99], v[224:227], v[176:179], v[96:99]
	v_mfma_f32_16x16x32_bf16 v[84:87], v[216:219], v[200:203], v[84:87]
	v_mfma_f32_16x16x32_bf16 v[80:83], v[224:227], v[200:203], v[80:83]
	v_mfma_f32_16x16x32_bf16 v[68:71], v[216:219], v[208:211], v[68:71]
	v_mfma_f32_16x16x32_bf16 v[64:67], v[224:227], v[208:211], v[64:67]
	s_mov_b32 m0, s46
	s_barrier
; #define PG8_STAGE(bufoff, gbase, voff) do { _Pragma("unroll") for (int _i = 0; _i < 2; ++_i) \
;     __builtin_amdgcn_global_load_lds((const unsigned*)((const char*)(gbase) + (voff)[_i]), (LAS unsigned*)(lds + (bufoff) + ldsw + _i * 8192), 16, 0, 0); } while (0)
; #define PG8_LDA(dst, b, h) do { _Pragma("unroll") for (int m = 0; m < 4; ++m) _Pragma("unroll") for (int k = 0; k < 2; ++k) dst[m][k] = *(const LAS bf16x8*)(lds + PG8_SA(b, h) + aoff + m * 2048 + k * 1024); } while (0)
; #define PG8_MMA(ai, bj, At, Bt) do { __builtin_amdgcn_s_setprio(1); _Pragma("unroll") for (int m = 0; m < 4; ++m) _Pragma("unroll") for (int n = 0; n < 2; ++n) _Pragma("unroll") for (int k = 0; k < 2; ++k) \
;     acc[ai][bj][m][n] = __builtin_amdgcn_mfma_f32_16x16x32_bf16(Bt[n][k], At[m][k], acc[ai][bj][m][n], 0, 0, 0); __builtin_amdgcn_s_setprio(0); } while (0)
; #define PG8_WAIT_V(n) asm volatile("s_waitcnt vmcnt(" #n ")" ::: "memory")
; #define PG8_WAIT_L(n) asm volatile("s_waitcnt lgkmcnt(" #n ")" ::: "memory")
; #define PG8_BAR __builtin_amdgcn_s_barrier()
; #define PG8_SCHED __builtin_amdgcn_sched_barrier(0)
; template <class Epi, class Sched>
; DI void gemm_phase(LAS unsigned char* lds, const Gemm g, const Sched& S, const Epi& E) {
;     ...
;       PG8_LDA(At, 1, 1); PG8_STAGE(PG8_SA(1, 0), a3, voffA);
;       PG8_BAR; PG8_WAIT_L(0); PG8_MMA(1, 0, At, B0); PG8_BAR; PG8_SCHED;
;       PG8_STAGE(PG8_SB(1, 1), b3 + hstep, voffB);
;       PG8_WAIT_V(6); PG8_BAR; PG8_MMA(1, 1, At, B1); PG8_BAR;
;   DI void operator()(const f32x4 (&acc)[2][2][4][2], const pg8::Unit& u, int wr, int wc, int fr_, int fq_) const {
;     ...
;             } else if (EPI == EPI_CIN) {
;               if (n == 0) {
;                 const int gb = u.pn * 256 + bj * 128 + wc * 32;
;                 const int f8 = gb + 8 * fq;
;                 const f32x4 v1 = acc[ai][bj][m][1];
;                 if (gb < 1024) st_bf8((u16*)(big + O_QD) + (size_t)token * 1024 + f8, v, v1, rinv * (0.125f * LOG2E));
;                 else if (gb < 2048) st_bf8((u16*)(big + O_KD) + (size_t)token * 1024 + (f8 - 1024), v, v1, rinv);
;                 else st_bf8((u16*)(big + O_VDT) + (size_t)token * 1024 + (f8 - 2048), v, v1, rinv);
	ds_read_b128 v[164:167], v158 offset:49152
	ds_read_b128 v[168:171], v158 offset:50176
	ds_read_b128 v[172:175], v158 offset:51200
	ds_read_b128 v[176:179], v158 offset:52224
	ds_read_b128 v[196:199], v158 offset:53248
	ds_read_b128 v[200:203], v158 offset:54272
	ds_read_b128 v[204:207], v158 offset:55296
	ds_read_b128 v[208:211], v158 offset:56320
	global_load_lds_dwordx4 v138, s[100:101]
	s_mov_b32 m0, s47
	s_nop 0
	global_load_lds_dwordx4 v134, s[100:101]
	s_barrier
	s_waitcnt lgkmcnt(0)
	v_mfma_f32_16x16x32_bf16 v[60:63], v[128:131], v[164:167], v[60:63]
	v_mfma_f32_16x16x32_bf16 v[56:59], v[150:153], v[164:167], v[56:59]
	v_mfma_f32_16x16x32_bf16 v[44:47], v[128:131], v[172:175], v[44:47]
	v_mfma_f32_16x16x32_bf16 v[40:43], v[150:153], v[172:175], v[40:43]
	v_mfma_f32_16x16x32_bf16 v[28:31], v[128:131], v[196:199], v[28:31]
	v_mfma_f32_16x16x32_bf16 v[24:27], v[150:153], v[196:199], v[24:27]
	v_mfma_f32_16x16x32_bf16 v[12:15], v[128:131], v[204:207], v[12:15]
	v_mfma_f32_16x16x32_bf16 v[8:11], v[150:153], v[204:207], v[8:11]
	v_mfma_f32_16x16x32_bf16 v[60:63], v[146:149], v[168:171], v[60:63]
	v_mfma_f32_16x16x32_bf16 v[56:59], v[160:163], v[168:171], v[56:59]
	v_mfma_f32_16x16x32_bf16 v[44:47], v[146:149], v[176:179], v[44:47]
	v_mfma_f32_16x16x32_bf16 v[40:43], v[160:163], v[176:179], v[40:43]
	v_mfma_f32_16x16x32_bf16 v[28:31], v[146:149], v[200:203], v[28:31]
	v_mfma_f32_16x16x32_bf16 v[24:27], v[160:163], v[200:203], v[24:27]
	v_mfma_f32_16x16x32_bf16 v[12:15], v[146:149], v[208:211], v[12:15]
	v_mfma_f32_16x16x32_bf16 v[8:11], v[160:163], v[208:211], v[8:11]
	s_barrier
	s_add_u32 s4, s4, 0x40080
	s_addc_u32 s5, s5, 0
	s_add_i32 s20, s20, s34
	s_mov_b32 m0, s20
	s_nop 0
	global_load_lds_dwordx4 v136, s[4:5]
	s_add_i32 m0, s20, 0x2000
	s_nop 0
	global_load_lds_dwordx4 v132, s[4:5]
	s_waitcnt vmcnt(6)
	s_barrier
	v_mfma_f32_16x16x32_bf16 v[52:55], v[212:215], v[164:167], v[52:55]
	v_mfma_f32_16x16x32_bf16 v[48:51], v[220:223], v[164:167], v[48:51]
	v_mfma_f32_16x16x32_bf16 v[36:39], v[212:215], v[172:175], v[36:39]
	v_mfma_f32_16x16x32_bf16 v[32:35], v[220:223], v[172:175], v[32:35]
	v_mfma_f32_16x16x32_bf16 v[20:23], v[212:215], v[196:199], v[20:23]
	v_mfma_f32_16x16x32_bf16 v[16:19], v[220:223], v[196:199], v[16:19]
	v_mfma_f32_16x16x32_bf16 v[4:7], v[212:215], v[204:207], v[4:7]
	v_mfma_f32_16x16x32_bf16 v[0:3], v[220:223], v[204:207], v[0:3]
	v_mfma_f32_16x16x32_bf16 v[52:55], v[216:219], v[168:171], v[52:55]
	v_mfma_f32_16x16x32_bf16 v[48:51], v[224:227], v[168:171], v[48:51]
	v_mfma_f32_16x16x32_bf16 v[36:39], v[216:219], v[176:179], v[36:39]
	v_mfma_f32_16x16x32_bf16 v[32:35], v[224:227], v[176:179], v[32:35]
	v_mfma_f32_16x16x32_bf16 v[20:23], v[216:219], v[200:203], v[20:23]
	v_mfma_f32_16x16x32_bf16 v[16:19], v[224:227], v[200:203], v[16:19]
	v_mfma_f32_16x16x32_bf16 v[4:7], v[216:219], v[208:211], v[4:7]
	v_mfma_f32_16x16x32_bf16 v[0:3], v[224:227], v[208:211], v[0:3]
	s_add_i32 s50, s50, 2
	s_add_u32 s2, s2, 0x100
	s_addc_u32 s3, s3, 0
	s_add_u32 s37, s37, 0x100
	s_addc_u32 s49, s49, 0
	s_cmp_gt_u32 s50, 13
	s_barrier
	s_cbranch_scc0 .LBB0_370
	v_mov_b32_e32 v128, v182
	s_lshl_b32 s2, s22, 10
	v_and_or_b32 v160, v128, 15, s44
	v_lshrrev_b32_e32 v128, 1, v128
	s_add_i32 s2, s2, 0
	v_and_b32_e32 v146, 24, v128
	v_lshl_add_u32 v128, v160, 2, s2
	v_add_u32_e32 v159, 0x20000, v128
	s_lshl_b32 s13, s28, 8
	s_lshl_b32 s3, s23, 8
	ds_read_b32 v154, v159
	v_add_u32_e32 v150, s13, v160
	s_or_b32 s20, s3, s45
	v_ashrrev_i32_e32 v151, 31, v150
	s_cmpk_gt_i32 s20, 0x3ff
	v_lshlrev_b64 v[128:129], 11, v[150:151]
	v_or_b32_e32 v148, s20, v146
	s_cselect_b64 s[4:5], -1, 0
	s_cmpk_gt_u32 s3, 0x7ff
	s_cselect_b64 s[2:3], -1, 0
	v_mov_b32_e32 v144, v148
	v_lshl_add_u64 v[152:153], s[10:11], 0, v[128:129]
	s_mov_b64 s[22:23], -1
	s_and_b64 vcc, exec, s[4:5]
	s_cbranch_vccz .LBB0_377
	s_waitcnt lgkmcnt(0)
	v_mul_f32_e32 v128, v124, v154
	v_mul_f32_e32 v129, v125, v154
	v_mul_f32_e32 v130, v126, v154
	v_mul_f32_e32 v131, v127, v154
	v_cvt_pk_bf16_f32 v128, v128, v129
	v_cvt_pk_bf16_f32 v129, v130, v131
	v_mul_f32_e32 v130, v120, v154
	v_mul_f32_e32 v131, v121, v154
	v_mul_f32_e32 v162, v122, v154
	v_mul_f32_e32 v163, v123, v154
	v_lshl_add_u64 v[156:157], v[144:145], 1, v[152:153]
	v_cvt_pk_bf16_f32 v130, v130, v131
	v_cvt_pk_bf16_f32 v131, v162, v163
	s_and_b64 vcc, exec, s[2:3]
	s_cbranch_vccz .LBB0_374
	v_add_co_u32_e32 v162, vcc, 0x7fff000, v156
	s_mov_b64 s[22:23], 0
	s_nop 0
	v_addc_co_u32_e32 v163, vcc, 0, v157, vcc
	global_store_dwordx4 v[162:163], v[128:131], off

; DI void st_bf8(u16* p, f32x4 a, f32x4 b, float sc) {
;   u32x4 u; u.x = pack2(a[0] * sc, a[1] * sc); u.y = pack2(a[2] * sc, a[3] * sc); u.z = pack2(b[0] * sc, b[1] * sc); u.w = pack2(b[2] * sc, b[3] * sc);
;   *(u32x4*)p = u;
;   DI void operator()(const f32x4 (&acc)[2][2][4][2], const pg8::Unit& u, int wr, int wc, int fr_, int fq_) const {
;     ...
;             } else if (EPI == EPI_CIN) {
;               if (n == 0) {
;                 const int gb = u.pn * 256 + bj * 128 + wc * 32;
;                 const int f8 = gb + 8 * fq;
;                 const f32x4 v1 = acc[ai][bj][m][1];
;                 if (gb < 1024) st_bf8((u16*)(big + O_QD) + (size_t)token * 1024 + f8, v, v1, rinv * (0.125f * LOG2E));
;                 else if (gb < 2048) st_bf8((u16*)(big + O_KD) + (size_t)token * 1024 + (f8 - 1024), v, v1, rinv);
;                 else st_bf8((u16*)(big + O_VDT) + (size_t)token * 1024 + (f8 - 2048), v, v1, rinv);
.LBB0_377:
	s_waitcnt lgkmcnt(0)
	v_mul_f32_e32 v128, 0x3e38aa3b, v154
	s_andn2_b64 vcc, exec, s[22:23]
	v_ashrrev_i32_e32 v149, 31, v148
	s_cbranch_vccnz .LBB0_379
	v_mul_f32_e32 v124, v124, v128
	v_mul_f32_e32 v125, v125, v128
	v_mul_f32_e32 v126, v126, v128
	v_mul_f32_e32 v127, v127, v128
	v_mul_f32_e32 v120, v120, v128
	v_mul_f32_e32 v121, v121, v128
	v_cvt_pk_bf16_f32 v124, v124, v125
	v_cvt_pk_bf16_f32 v125, v126, v127
	v_cvt_pk_bf16_f32 v126, v120, v121
	v_mul_f32_e32 v120, v122, v128
	v_mul_f32_e32 v121, v123, v128
	v_lshl_add_u64 v[130:131], v[148:149], 1, v[152:153]
	v_cvt_pk_bf16_f32 v127, v120, v121
	global_store_dwordx4 v[130:131], v[124:127], off
.LBB0_379:
	s_or_b32 s15, s20, 0x80
	s_cmpk_gt_i32 s15, 0x3ff
	v_cndmask_b32_e64 v120, 0, 1, s[2:3]
	s_mov_b64 s[28:29], -1
	s_cselect_b64 s[22:23], -1, 0
	s_cmpk_lt_i32 s15, 0x400
	v_add_u32_e32 v124, s20, v146
	v_cmp_ne_u32_e64 s[2:3], 1, v120
	v_readlane_b32 s51, v237, 11
	s_cbranch_scc1 .LBB0_385
	v_mov_b32_e32 v125, v145
	v_lshl_add_u64 v[120:121], v[124:125], 1, v[152:153]
	s_mov_b64 s[28:29], 0x100
	v_lshl_add_u64 v[126:127], v[120:121], 0, s[28:29]
	v_mul_f32_e32 v120, v116, v154
	v_mul_f32_e32 v121, v117, v154
	v_mul_f32_e32 v122, v118, v154
	v_mul_f32_e32 v123, v119, v154
	v_cvt_pk_bf16_f32 v120, v120, v121
	v_cvt_pk_bf16_f32 v121, v122, v123
	v_mul_f32_e32 v122, v112, v154
	v_mul_f32_e32 v123, v113, v154
	v_mul_f32_e32 v130, v114, v154
	v_mul_f32_e32 v131, v115, v154
	v_cvt_pk_bf16_f32 v122, v122, v123
	v_cvt_pk_bf16_f32 v123, v130, v131
	s_and_b64 vcc, exec, s[2:3]
	s_mov_b64 s[28:29], -1
	s_cbranch_vccnz .LBB0_382
	v_add_co_u32_e32 v130, vcc, 0x7fff000, v126
	s_mov_b64 s[28:29], 0
	s_nop 0
	v_addc_co_u32_e32 v131, vcc, 0, v127, vcc
	global_store_dwordx4 v[130:131], v[120:123], off

; DI void st_bf8(u16* p, f32x4 a, f32x4 b, float sc) {
;   u32x4 u; u.x = pack2(a[0] * sc, a[1] * sc); u.y = pack2(a[2] * sc, a[3] * sc); u.z = pack2(b[0] * sc, b[1] * sc); u.w = pack2(b[2] * sc, b[3] * sc);
;   *(u32x4*)p = u;
;   DI void operator()(const f32x4 (&acc)[2][2][4][2], const pg8::Unit& u, int wr, int wc, int fr_, int fq_) const {
;     ...
;             } else if (EPI == EPI_CIN) {
;               if (n == 0) {
;                 const int gb = u.pn * 256 + bj * 128 + wc * 32;
;                 const int f8 = gb + 8 * fq;
;                 const f32x4 v1 = acc[ai][bj][m][1];
;                 if (gb < 1024) st_bf8((u16*)(big + O_QD) + (size_t)token * 1024 + f8, v, v1, rinv * (0.125f * LOG2E));
;                 else if (gb < 2048) st_bf8((u16*)(big + O_KD) + (size_t)token * 1024 + (f8 - 1024), v, v1, rinv);
;                 else st_bf8((u16*)(big + O_VDT) + (size_t)token * 1024 + (f8 - 2048), v, v1, rinv);
.LBB0_385:
	s_andn2_b64 vcc, exec, s[28:29]
	s_cbranch_vccnz .LBB0_387
	v_mov_b32_e32 v147, v145
	s_ashr_i32 s21, s20, 31
	v_mul_f32_e32 v116, v116, v128
	v_mul_f32_e32 v117, v117, v128
	v_mul_f32_e32 v118, v118, v128
	v_mul_f32_e32 v119, v119, v128
	v_mul_f32_e32 v112, v112, v128
	v_mul_f32_e32 v113, v113, v128
	v_lshl_add_u64 v[120:121], v[146:147], 0, s[20:21]
	v_cvt_pk_bf16_f32 v116, v116, v117
	v_cvt_pk_bf16_f32 v117, v118, v119
	v_cvt_pk_bf16_f32 v118, v112, v113
	v_mul_f32_e32 v112, v114, v128
	v_mul_f32_e32 v113, v115, v128
	v_lshl_add_u64 v[120:121], v[120:121], 1, v[152:153]
	v_cvt_pk_bf16_f32 v119, v112, v113
	global_store_dwordx4 v[120:121], v[116:119], off offset:256
.LBB0_387:
	v_add3_u32 v112, s13, v160, 16
	ds_read_b32 v118, v159 offset:64
	v_ashrrev_i32_e32 v113, 31, v112
	v_lshlrev_b64 v[112:113], 11, v[112:113]
	v_lshl_add_u64 v[116:117], s[10:11], 0, v[112:113]
	v_cndmask_b32_e64 v112, 0, 1, s[4:5]
	v_cmp_ne_u32_e64 s[36:37], 1, v112
	s_andn2_b64 vcc, exec, s[4:5]
	s_mov_b64 s[4:5], -1
	s_cbranch_vccnz .LBB0_393
	s_waitcnt lgkmcnt(0)
	v_mul_f32_e32 v112, v108, v118
	v_mul_f32_e32 v113, v109, v118
	v_mul_f32_e32 v114, v110, v118
	v_mul_f32_e32 v115, v111, v118
	v_cvt_pk_bf16_f32 v112, v112, v113
	v_cvt_pk_bf16_f32 v113, v114, v115
	v_mul_f32_e32 v114, v104, v118
	v_mul_f32_e32 v115, v105, v118
	v_mul_f32_e32 v122, v106, v118
	v_mul_f32_e32 v123, v107, v118
	v_lshl_add_u64 v[120:121], v[144:145], 1, v[116:117]
	v_cvt_pk_bf16_f32 v114, v114, v115
	v_cvt_pk_bf16_f32 v115, v122, v123
	s_and_b64 vcc, exec, s[2:3]
	s_cbranch_vccnz .LBB0_390
	v_add_co_u32_e32 v122, vcc, 0x7fff000, v120
	s_mov_b64 s[4:5], 0
	s_nop 0
	v_addc_co_u32_e32 v123, vcc, 0, v121, vcc
	global_store_dwordx4 v[122:123], v[112:115], off

; DI void st_bf8(u16* p, f32x4 a, f32x4 b, float sc) {
;   u32x4 u; u.x = pack2(a[0] * sc, a[1] * sc); u.y = pack2(a[2] * sc, a[3] * sc); u.z = pack2(b[0] * sc, b[1] * sc); u.w = pack2(b[2] * sc, b[3] * sc);
;   *(u32x4*)p = u;
;   DI void operator()(const f32x4 (&acc)[2][2][4][2], const pg8::Unit& u, int wr, int wc, int fr_, int fq_) const {
;     ...
;             } else if (EPI == EPI_CIN) {
;               if (n == 0) {
;                 const int gb = u.pn * 256 + bj * 128 + wc * 32;
;                 const int f8 = gb + 8 * fq;
;                 const f32x4 v1 = acc[ai][bj][m][1];
;                 if (gb < 1024) st_bf8((u16*)(big + O_QD) + (size_t)token * 1024 + f8, v, v1, rinv * (0.125f * LOG2E));
;                 else if (gb < 2048) st_bf8((u16*)(big + O_KD) + (size_t)token * 1024 + (f8 - 1024), v, v1, rinv);
;                 else st_bf8((u16*)(big + O_VDT) + (size_t)token * 1024 + (f8 - 2048), v, v1, rinv);
.LBB0_393:
	s_andn2_b64 vcc, exec, s[4:5]
	s_waitcnt lgkmcnt(0)
	v_mul_f32_e32 v112, 0x3e38aa3b, v118
	s_cbranch_vccnz .LBB0_395
	v_mul_f32_e32 v108, v108, v112
	v_mul_f32_e32 v109, v109, v112
	v_mul_f32_e32 v110, v110, v112
	v_mul_f32_e32 v111, v111, v112
	v_mul_f32_e32 v104, v104, v112
	v_mul_f32_e32 v105, v105, v112
	v_cvt_pk_bf16_f32 v108, v108, v109
	v_cvt_pk_bf16_f32 v109, v110, v111
	v_cvt_pk_bf16_f32 v110, v104, v105
	v_mul_f32_e32 v104, v106, v112
	v_mul_f32_e32 v105, v107, v112
	v_lshl_add_u64 v[114:115], v[148:149], 1, v[116:117]
	v_cvt_pk_bf16_f32 v111, v104, v105
	global_store_dwordx4 v[114:115], v[108:111], off
.LBB0_395:
	v_cndmask_b32_e64 v104, 0, 1, s[22:23]
	v_cmp_ne_u32_e64 s[4:5], 1, v104
	s_andn2_b64 vcc, exec, s[22:23]
	s_mov_b64 s[22:23], -1
	s_cbranch_vccnz .LBB0_401
	v_mov_b32_e32 v125, v145
	v_lshl_add_u64 v[104:105], v[124:125], 1, v[116:117]
	s_mov_b64 s[22:23], 0x100
	v_lshl_add_u64 v[108:109], v[104:105], 0, s[22:23]
	v_mul_f32_e32 v104, v100, v118
	v_mul_f32_e32 v105, v101, v118
	v_mul_f32_e32 v106, v102, v118
	v_mul_f32_e32 v107, v103, v118
	v_cvt_pk_bf16_f32 v104, v104, v105
	v_cvt_pk_bf16_f32 v105, v106, v107
	v_mul_f32_e32 v106, v96, v118
	v_mul_f32_e32 v107, v97, v118
	v_mul_f32_e32 v110, v98, v118
	v_mul_f32_e32 v111, v99, v118
	v_cvt_pk_bf16_f32 v106, v106, v107
	v_cvt_pk_bf16_f32 v107, v110, v111
	s_and_b64 vcc, exec, s[2:3]
	s_mov_b64 s[22:23], -1
	s_cbranch_vccnz .LBB0_398
	v_add_co_u32_e32 v110, vcc, 0x7fff000, v108
	s_mov_b64 s[22:23], 0
	s_nop 0
	v_addc_co_u32_e32 v111, vcc, 0, v109, vcc
	global_store_dwordx4 v[110:111], v[104:107], off

; DI void st_bf8(u16* p, f32x4 a, f32x4 b, float sc) {
;   u32x4 u; u.x = pack2(a[0] * sc, a[1] * sc); u.y = pack2(a[2] * sc, a[3] * sc); u.z = pack2(b[0] * sc, b[1] * sc); u.w = pack2(b[2] * sc, b[3] * sc);
;   *(u32x4*)p = u;
;   DI void operator()(const f32x4 (&acc)[2][2][4][2], const pg8::Unit& u, int wr, int wc, int fr_, int fq_) const {
;     ...
;             } else if (EPI == EPI_CIN) {
;               if (n == 0) {
;                 const int gb = u.pn * 256 + bj * 128 + wc * 32;
;                 const int f8 = gb + 8 * fq;
;                 const f32x4 v1 = acc[ai][bj][m][1];
;                 if (gb < 1024) st_bf8((u16*)(big + O_QD) + (size_t)token * 1024 + f8, v, v1, rinv * (0.125f * LOG2E));
;                 else if (gb < 2048) st_bf8((u16*)(big + O_KD) + (size_t)token * 1024 + (f8 - 1024), v, v1, rinv);
;                 else st_bf8((u16*)(big + O_VDT) + (size_t)token * 1024 + (f8 - 2048), v, v1, rinv);
.LBB0_401:
	s_andn2_b64 vcc, exec, s[22:23]
	s_cbranch_vccnz .LBB0_403
	v_mov_b32_e32 v147, v145
	s_ashr_i32 s21, s20, 31
	v_mul_f32_e32 v100, v100, v112
	v_mul_f32_e32 v101, v101, v112
	v_mul_f32_e32 v102, v102, v112
	v_mul_f32_e32 v103, v103, v112
	v_mul_f32_e32 v96, v96, v112
	v_mul_f32_e32 v97, v97, v112
	v_lshl_add_u64 v[104:105], v[146:147], 0, s[20:21]
	v_cvt_pk_bf16_f32 v100, v100, v101
	v_cvt_pk_bf16_f32 v101, v102, v103
	v_cvt_pk_bf16_f32 v102, v96, v97
	v_mul_f32_e32 v96, v98, v112
	v_mul_f32_e32 v97, v99, v112
	v_lshl_add_u64 v[104:105], v[104:105], 1, v[116:117]
	v_cvt_pk_bf16_f32 v103, v96, v97
	global_store_dwordx4 v[104:105], v[100:103], off offset:256

; DI void st_bf8(u16* p, f32x4 a, f32x4 b, float sc) {
;   u32x4 u; u.x = pack2(a[0] * sc, a[1] * sc); u.y = pack2(a[2] * sc, a[3] * sc); u.z = pack2(b[0] * sc, b[1] * sc); u.w = pack2(b[2] * sc, b[3] * sc);
;   *(u32x4*)p = u;
;   DI void operator()(const f32x4 (&acc)[2][2][4][2], const pg8::Unit& u, int wr, int wc, int fr_, int fq_) const {
;     ...
;             } else if (EPI == EPI_CIN) {
;               if (n == 0) {
;                 const int gb = u.pn * 256 + bj * 128 + wc * 32;
;                 const int f8 = gb + 8 * fq;
;                 const f32x4 v1 = acc[ai][bj][m][1];
;                 if (gb < 1024) st_bf8((u16*)(big + O_QD) + (size_t)token * 1024 + f8, v, v1, rinv * (0.125f * LOG2E));
;                 else if (gb < 2048) st_bf8((u16*)(big + O_KD) + (size_t)token * 1024 + (f8 - 1024), v, v1, rinv);
;                 else st_bf8((u16*)(big + O_VDT) + (size_t)token * 1024 + (f8 - 2048), v, v1, rinv);
.LBB0_407:
	v_mov_b32_e32 v147, v145
	s_ashr_i32 s21, s20, 31
	v_mul_f32_e32 v84, v84, v96
	v_mul_f32_e32 v85, v85, v96
	v_mul_f32_e32 v86, v86, v96
	v_mul_f32_e32 v87, v87, v96
	v_mul_f32_e32 v80, v80, v96
	v_mul_f32_e32 v81, v81, v96
	v_lshl_add_u64 v[88:89], v[146:147], 0, s[20:21]
	v_cvt_pk_bf16_f32 v84, v84, v85
	v_cvt_pk_bf16_f32 v85, v86, v87
	v_cvt_pk_bf16_f32 v86, v80, v81
	v_mul_f32_e32 v80, v82, v96
	v_mul_f32_e32 v81, v83, v96
	v_lshl_add_u64 v[88:89], v[88:89], 1, v[100:101]
	v_cvt_pk_bf16_f32 v87, v80, v81
	global_store_dwordx4 v[88:89], v[84:87], off offset:256

; DI void st_bf8(u16* p, f32x4 a, f32x4 b, float sc) {
;   u32x4 u; u.x = pack2(a[0] * sc, a[1] * sc); u.y = pack2(a[2] * sc, a[3] * sc); u.z = pack2(b[0] * sc, b[1] * sc); u.w = pack2(b[2] * sc, b[3] * sc);
;   *(u32x4*)p = u;
;   DI void operator()(const f32x4 (&acc)[2][2][4][2], const pg8::Unit& u, int wr, int wc, int fr_, int fq_) const {
;     ...
;             } else if (EPI == EPI_CIN) {
;               if (n == 0) {
;                 const int gb = u.pn * 256 + bj * 128 + wc * 32;
;                 const int f8 = gb + 8 * fq;
;                 const f32x4 v1 = acc[ai][bj][m][1];
;                 if (gb < 1024) st_bf8((u16*)(big + O_QD) + (size_t)token * 1024 + f8, v, v1, rinv * (0.125f * LOG2E));
;                 else if (gb < 2048) st_bf8((u16*)(big + O_KD) + (size_t)token * 1024 + (f8 - 1024), v, v1, rinv);
;                 else st_bf8((u16*)(big + O_VDT) + (size_t)token * 1024 + (f8 - 2048), v, v1, rinv);
.LBB0_412:
	v_mov_b32_e32 v147, v145
	s_ashr_i32 s21, s20, 31
	v_mul_f32_e32 v68, v68, v80
	v_mul_f32_e32 v69, v69, v80
	v_mul_f32_e32 v70, v70, v80
	v_mul_f32_e32 v71, v71, v80
	v_mul_f32_e32 v64, v64, v80
	v_mul_f32_e32 v65, v65, v80
	v_lshl_add_u64 v[72:73], v[146:147], 0, s[20:21]
	v_cvt_pk_bf16_f32 v68, v68, v69
	v_cvt_pk_bf16_f32 v69, v70, v71
	v_cvt_pk_bf16_f32 v70, v64, v65
	v_mul_f32_e32 v64, v66, v80
	v_mul_f32_e32 v65, v67, v80
	v_lshl_add_u64 v[72:73], v[72:73], 1, v[84:85]
	v_cvt_pk_bf16_f32 v71, v64, v65
	global_store_dwordx4 v[72:73], v[68:71], off offset:256

; DI void st_bf8(u16* p, f32x4 a, f32x4 b, float sc) {
;   u32x4 u; u.x = pack2(a[0] * sc, a[1] * sc); u.y = pack2(a[2] * sc, a[3] * sc); u.z = pack2(b[0] * sc, b[1] * sc); u.w = pack2(b[2] * sc, b[3] * sc);
;   *(u32x4*)p = u;
;   DI void operator()(const f32x4 (&acc)[2][2][4][2], const pg8::Unit& u, int wr, int wc, int fr_, int fq_) const {
;     ...
;             } else if (EPI == EPI_CIN) {
;               if (n == 0) {
;                 const int gb = u.pn * 256 + bj * 128 + wc * 32;
;                 const int f8 = gb + 8 * fq;
;                 const f32x4 v1 = acc[ai][bj][m][1];
;                 if (gb < 1024) st_bf8((u16*)(big + O_QD) + (size_t)token * 1024 + f8, v, v1, rinv * (0.125f * LOG2E));
;                 else if (gb < 2048) st_bf8((u16*)(big + O_KD) + (size_t)token * 1024 + (f8 - 1024), v, v1, rinv);
;                 else st_bf8((u16*)(big + O_VDT) + (size_t)token * 1024 + (f8 - 2048), v, v1, rinv);
.LBB0_417:
	v_mov_b32_e32 v147, v145
	s_ashr_i32 s21, s20, 31
	v_mul_f32_e32 v52, v52, v64
	v_mul_f32_e32 v53, v53, v64
	v_mul_f32_e32 v54, v54, v64
	v_mul_f32_e32 v55, v55, v64
	v_mul_f32_e32 v48, v48, v64
	v_mul_f32_e32 v49, v49, v64
	v_lshl_add_u64 v[56:57], v[146:147], 0, s[20:21]
	v_cvt_pk_bf16_f32 v52, v52, v53
	v_cvt_pk_bf16_f32 v53, v54, v55
	v_cvt_pk_bf16_f32 v54, v48, v49
	v_mul_f32_e32 v48, v50, v64
	v_mul_f32_e32 v49, v51, v64
	v_lshl_add_u64 v[56:57], v[56:57], 1, v[68:69]
	v_cvt_pk_bf16_f32 v55, v48, v49
	global_store_dwordx4 v[56:57], v[52:55], off offset:256

; DI void st_bf8(u16* p, f32x4 a, f32x4 b, float sc) {
;   u32x4 u; u.x = pack2(a[0] * sc, a[1] * sc); u.y = pack2(a[2] * sc, a[3] * sc); u.z = pack2(b[0] * sc, b[1] * sc); u.w = pack2(b[2] * sc, b[3] * sc);
;   *(u32x4*)p = u;
;   DI void operator()(const f32x4 (&acc)[2][2][4][2], const pg8::Unit& u, int wr, int wc, int fr_, int fq_) const {
;     ...
;             } else if (EPI == EPI_CIN) {
;               if (n == 0) {
;                 const int gb = u.pn * 256 + bj * 128 + wc * 32;
;                 const int f8 = gb + 8 * fq;
;                 const f32x4 v1 = acc[ai][bj][m][1];
;                 if (gb < 1024) st_bf8((u16*)(big + O_QD) + (size_t)token * 1024 + f8, v, v1, rinv * (0.125f * LOG2E));
;                 else if (gb < 2048) st_bf8((u16*)(big + O_KD) + (size_t)token * 1024 + (f8 - 1024), v, v1, rinv);
;                 else st_bf8((u16*)(big + O_VDT) + (size_t)token * 1024 + (f8 - 2048), v, v1, rinv);
.LBB0_422:
	v_mov_b32_e32 v147, v145
	s_ashr_i32 s21, s20, 31
	v_mul_f32_e32 v36, v36, v48
	v_mul_f32_e32 v37, v37, v48
	v_mul_f32_e32 v38, v38, v48
	v_mul_f32_e32 v39, v39, v48
	v_mul_f32_e32 v32, v32, v48
	v_mul_f32_e32 v33, v33, v48
	v_lshl_add_u64 v[40:41], v[146:147], 0, s[20:21]
	v_cvt_pk_bf16_f32 v36, v36, v37
	v_cvt_pk_bf16_f32 v37, v38, v39
	v_cvt_pk_bf16_f32 v38, v32, v33
	v_mul_f32_e32 v32, v34, v48
	v_mul_f32_e32 v33, v35, v48
	v_lshl_add_u64 v[40:41], v[40:41], 1, v[52:53]
	v_cvt_pk_bf16_f32 v39, v32, v33
	global_store_dwordx4 v[40:41], v[36:39], off offset:256

; DI void st_bf8(u16* p, f32x4 a, f32x4 b, float sc) {
;   u32x4 u; u.x = pack2(a[0] * sc, a[1] * sc); u.y = pack2(a[2] * sc, a[3] * sc); u.z = pack2(b[0] * sc, b[1] * sc); u.w = pack2(b[2] * sc, b[3] * sc);
;   *(u32x4*)p = u;
;   DI void operator()(const f32x4 (&acc)[2][2][4][2], const pg8::Unit& u, int wr, int wc, int fr_, int fq_) const {
;     ...
;             } else if (EPI == EPI_CIN) {
;               if (n == 0) {
;                 const int gb = u.pn * 256 + bj * 128 + wc * 32;
;                 const int f8 = gb + 8 * fq;
;                 const f32x4 v1 = acc[ai][bj][m][1];
;                 if (gb < 1024) st_bf8((u16*)(big + O_QD) + (size_t)token * 1024 + f8, v, v1, rinv * (0.125f * LOG2E));
;                 else if (gb < 2048) st_bf8((u16*)(big + O_KD) + (size_t)token * 1024 + (f8 - 1024), v, v1, rinv);
;                 else st_bf8((u16*)(big + O_VDT) + (size_t)token * 1024 + (f8 - 2048), v, v1, rinv);
.LBB0_427:
	v_mov_b32_e32 v147, v145
	s_ashr_i32 s21, s20, 31
	v_mul_f32_e32 v20, v20, v32
	v_mul_f32_e32 v21, v21, v32
	v_mul_f32_e32 v22, v22, v32
	v_mul_f32_e32 v23, v23, v32
	v_mul_f32_e32 v16, v16, v32
	v_mul_f32_e32 v17, v17, v32
	v_lshl_add_u64 v[24:25], v[146:147], 0, s[20:21]
	v_cvt_pk_bf16_f32 v20, v20, v21
	v_cvt_pk_bf16_f32 v21, v22, v23
	v_cvt_pk_bf16_f32 v22, v16, v17
	v_mul_f32_e32 v16, v18, v32
	v_mul_f32_e32 v17, v19, v32
	v_lshl_add_u64 v[24:25], v[24:25], 1, v[36:37]
	v_cvt_pk_bf16_f32 v23, v16, v17
	global_store_dwordx4 v[24:25], v[20:23], off offset:256

; DI void st_bf8(u16* p, f32x4 a, f32x4 b, float sc) {
;   u32x4 u; u.x = pack2(a[0] * sc, a[1] * sc); u.y = pack2(a[2] * sc, a[3] * sc); u.z = pack2(b[0] * sc, b[1] * sc); u.w = pack2(b[2] * sc, b[3] * sc);
;   *(u32x4*)p = u;
;   DI void operator()(const f32x4 (&acc)[2][2][4][2], const pg8::Unit& u, int wr, int wc, int fr_, int fq_) const {
;     ...
;             } else if (EPI == EPI_CIN) {
;               if (n == 0) {
;                 const int gb = u.pn * 256 + bj * 128 + wc * 32;
;                 const int f8 = gb + 8 * fq;
;                 const f32x4 v1 = acc[ai][bj][m][1];
;                 if (gb < 1024) st_bf8((u16*)(big + O_QD) + (size_t)token * 1024 + f8, v, v1, rinv * (0.125f * LOG2E));
;                 else if (gb < 2048) st_bf8((u16*)(big + O_KD) + (size_t)token * 1024 + (f8 - 1024), v, v1, rinv);
;                 else st_bf8((u16*)(big + O_VDT) + (size_t)token * 1024 + (f8 - 2048), v, v1, rinv);
.LBB0_432:
	s_waitcnt lgkmcnt(0)
	v_mul_f32_e32 v96, v92, v102
	v_mul_f32_e32 v97, v93, v102
	v_mul_f32_e32 v98, v94, v102
	v_mul_f32_e32 v99, v95, v102
	v_cvt_pk_bf16_f32 v96, v96, v97
	v_cvt_pk_bf16_f32 v97, v98, v99
	v_mul_f32_e32 v98, v88, v102
	v_mul_f32_e32 v99, v89, v102
	v_mul_f32_e32 v106, v90, v102
	v_mul_f32_e32 v107, v91, v102
	v_lshl_add_u64 v[104:105], v[144:145], 1, v[100:101]
	v_cvt_pk_bf16_f32 v98, v98, v99
	v_cvt_pk_bf16_f32 v99, v106, v107
	s_and_b64 vcc, exec, s[2:3]
	s_cbranch_vccnz .LBB0_434
	v_add_co_u32_e32 v106, vcc, 0x7fff000, v104
	s_mov_b64 s[22:23], 0
	s_nop 0
	v_addc_co_u32_e32 v107, vcc, 0, v105, vcc
	global_store_dwordx4 v[106:107], v[96:99], off

; DI void st_bf8(u16* p, f32x4 a, f32x4 b, float sc) {
;   u32x4 u; u.x = pack2(a[0] * sc, a[1] * sc); u.y = pack2(a[2] * sc, a[3] * sc); u.z = pack2(b[0] * sc, b[1] * sc); u.w = pack2(b[2] * sc, b[3] * sc);
;   *(u32x4*)p = u;
;   DI void operator()(const f32x4 (&acc)[2][2][4][2], const pg8::Unit& u, int wr, int wc, int fr_, int fq_) const {
;     ...
;             } else if (EPI == EPI_CIN) {
;               if (n == 0) {
;                 const int gb = u.pn * 256 + bj * 128 + wc * 32;
;                 const int f8 = gb + 8 * fq;
;                 const f32x4 v1 = acc[ai][bj][m][1];
;                 if (gb < 1024) st_bf8((u16*)(big + O_QD) + (size_t)token * 1024 + f8, v, v1, rinv * (0.125f * LOG2E));
;                 else if (gb < 2048) st_bf8((u16*)(big + O_KD) + (size_t)token * 1024 + (f8 - 1024), v, v1, rinv);
;                 else st_bf8((u16*)(big + O_VDT) + (size_t)token * 1024 + (f8 - 2048), v, v1, rinv);
.LBB0_437:
	v_mul_f32_e32 v92, v92, v96
	v_mul_f32_e32 v93, v93, v96
	v_mul_f32_e32 v94, v94, v96
	v_mul_f32_e32 v95, v95, v96
	v_mul_f32_e32 v88, v88, v96
	v_mul_f32_e32 v89, v89, v96
	v_cvt_pk_bf16_f32 v92, v92, v93
	v_cvt_pk_bf16_f32 v93, v94, v95
	v_cvt_pk_bf16_f32 v94, v88, v89
	v_mul_f32_e32 v88, v90, v96
	v_mul_f32_e32 v89, v91, v96
	v_lshl_add_u64 v[98:99], v[148:149], 1, v[100:101]
	v_cvt_pk_bf16_f32 v95, v88, v89
	global_store_dwordx4 v[98:99], v[92:95], off
	s_and_b64 vcc, exec, s[4:5]
	s_mov_b64 s[22:23], -1
	s_cbranch_vccnz .LBB0_406
.LBB0_438:
	v_mov_b32_e32 v125, v145
	v_lshl_add_u64 v[88:89], v[124:125], 1, v[100:101]
	s_mov_b64 s[22:23], 0x100
	v_lshl_add_u64 v[92:93], v[88:89], 0, s[22:23]
	v_mul_f32_e32 v88, v84, v102
	v_mul_f32_e32 v89, v85, v102
	v_mul_f32_e32 v90, v86, v102
	v_mul_f32_e32 v91, v87, v102
	v_cvt_pk_bf16_f32 v88, v88, v89
	v_cvt_pk_bf16_f32 v89, v90, v91
	v_mul_f32_e32 v90, v80, v102
	v_mul_f32_e32 v91, v81, v102
	v_mul_f32_e32 v94, v82, v102
	v_mul_f32_e32 v95, v83, v102
	v_cvt_pk_bf16_f32 v90, v90, v91
	v_cvt_pk_bf16_f32 v91, v94, v95
	s_and_b64 vcc, exec, s[2:3]
	s_mov_b64 s[22:23], -1
	s_cbranch_vccnz .LBB0_440
	v_add_co_u32_e32 v94, vcc, 0x7fff000, v92
	s_mov_b64 s[22:23], 0
	s_nop 0
	v_addc_co_u32_e32 v95, vcc, 0, v93, vcc
	global_store_dwordx4 v[94:95], v[88:91], off

; DI void st_bf8(u16* p, f32x4 a, f32x4 b, float sc) {
;   u32x4 u; u.x = pack2(a[0] * sc, a[1] * sc); u.y = pack2(a[2] * sc, a[3] * sc); u.z = pack2(b[0] * sc, b[1] * sc); u.w = pack2(b[2] * sc, b[3] * sc);
;   *(u32x4*)p = u;
;   DI void operator()(const f32x4 (&acc)[2][2][4][2], const pg8::Unit& u, int wr, int wc, int fr_, int fq_) const {
;     ...
;             } else if (EPI == EPI_CIN) {
;               if (n == 0) {
;                 const int gb = u.pn * 256 + bj * 128 + wc * 32;
;                 const int f8 = gb + 8 * fq;
;                 const f32x4 v1 = acc[ai][bj][m][1];
;                 if (gb < 1024) st_bf8((u16*)(big + O_QD) + (size_t)token * 1024 + f8, v, v1, rinv * (0.125f * LOG2E));
;                 else if (gb < 2048) st_bf8((u16*)(big + O_KD) + (size_t)token * 1024 + (f8 - 1024), v, v1, rinv);
;                 else st_bf8((u16*)(big + O_VDT) + (size_t)token * 1024 + (f8 - 2048), v, v1, rinv);
.LBB0_443:
	s_waitcnt lgkmcnt(0)
	v_mul_f32_e32 v80, v76, v86
	v_mul_f32_e32 v81, v77, v86
	v_mul_f32_e32 v82, v78, v86
	v_mul_f32_e32 v83, v79, v86
	v_cvt_pk_bf16_f32 v80, v80, v81
	v_cvt_pk_bf16_f32 v81, v82, v83
	v_mul_f32_e32 v82, v72, v86
	v_mul_f32_e32 v83, v73, v86
	v_mul_f32_e32 v90, v74, v86
	v_mul_f32_e32 v91, v75, v86
	v_lshl_add_u64 v[88:89], v[144:145], 1, v[84:85]
	v_cvt_pk_bf16_f32 v82, v82, v83
	v_cvt_pk_bf16_f32 v83, v90, v91
	s_and_b64 vcc, exec, s[2:3]
	s_cbranch_vccnz .LBB0_445
	v_add_co_u32_e32 v90, vcc, 0x7fff000, v88
	s_mov_b64 s[22:23], 0
	s_nop 0
	v_addc_co_u32_e32 v91, vcc, 0, v89, vcc
	global_store_dwordx4 v[90:91], v[80:83], off

; DI void st_bf8(u16* p, f32x4 a, f32x4 b, float sc) {
;   u32x4 u; u.x = pack2(a[0] * sc, a[1] * sc); u.y = pack2(a[2] * sc, a[3] * sc); u.z = pack2(b[0] * sc, b[1] * sc); u.w = pack2(b[2] * sc, b[3] * sc);
;   *(u32x4*)p = u;
;   DI void operator()(const f32x4 (&acc)[2][2][4][2], const pg8::Unit& u, int wr, int wc, int fr_, int fq_) const {
;     ...
;             } else if (EPI == EPI_CIN) {
;               if (n == 0) {
;                 const int gb = u.pn * 256 + bj * 128 + wc * 32;
;                 const int f8 = gb + 8 * fq;
;                 const f32x4 v1 = acc[ai][bj][m][1];
;                 if (gb < 1024) st_bf8((u16*)(big + O_QD) + (size_t)token * 1024 + f8, v, v1, rinv * (0.125f * LOG2E));
;                 else if (gb < 2048) st_bf8((u16*)(big + O_KD) + (size_t)token * 1024 + (f8 - 1024), v, v1, rinv);
;                 else st_bf8((u16*)(big + O_VDT) + (size_t)token * 1024 + (f8 - 2048), v, v1, rinv);
.LBB0_448:
	v_mul_f32_e32 v76, v76, v80
	v_mul_f32_e32 v77, v77, v80
	v_mul_f32_e32 v78, v78, v80
	v_mul_f32_e32 v79, v79, v80
	v_mul_f32_e32 v72, v72, v80
	v_mul_f32_e32 v73, v73, v80
	v_cvt_pk_bf16_f32 v76, v76, v77
	v_cvt_pk_bf16_f32 v77, v78, v79
	v_cvt_pk_bf16_f32 v78, v72, v73
	v_mul_f32_e32 v72, v74, v80
	v_mul_f32_e32 v73, v75, v80
	v_lshl_add_u64 v[82:83], v[148:149], 1, v[84:85]
	v_cvt_pk_bf16_f32 v79, v72, v73
	global_store_dwordx4 v[82:83], v[76:79], off
	s_and_b64 vcc, exec, s[4:5]
	s_mov_b64 s[22:23], -1
	s_cbranch_vccnz .LBB0_411
.LBB0_449:
	v_mov_b32_e32 v125, v145
	v_lshl_add_u64 v[72:73], v[124:125], 1, v[84:85]
	s_mov_b64 s[22:23], 0x100
	v_lshl_add_u64 v[76:77], v[72:73], 0, s[22:23]
	v_mul_f32_e32 v72, v68, v86
	v_mul_f32_e32 v73, v69, v86
	v_mul_f32_e32 v74, v70, v86
	v_mul_f32_e32 v75, v71, v86
	v_cvt_pk_bf16_f32 v72, v72, v73
	v_cvt_pk_bf16_f32 v73, v74, v75
	v_mul_f32_e32 v74, v64, v86
	v_mul_f32_e32 v75, v65, v86
	v_mul_f32_e32 v78, v66, v86
	v_mul_f32_e32 v79, v67, v86
	v_cvt_pk_bf16_f32 v74, v74, v75
	v_cvt_pk_bf16_f32 v75, v78, v79
	s_and_b64 vcc, exec, s[2:3]
	s_mov_b64 s[22:23], -1
	s_cbranch_vccnz .LBB0_451
	v_add_co_u32_e32 v78, vcc, 0x7fff000, v76
	s_mov_b64 s[22:23], 0
	s_nop 0
	v_addc_co_u32_e32 v79, vcc, 0, v77, vcc
	global_store_dwordx4 v[78:79], v[72:75], off

; DI void st_bf8(u16* p, f32x4 a, f32x4 b, float sc) {
;   u32x4 u; u.x = pack2(a[0] * sc, a[1] * sc); u.y = pack2(a[2] * sc, a[3] * sc); u.z = pack2(b[0] * sc, b[1] * sc); u.w = pack2(b[2] * sc, b[3] * sc);
;   *(u32x4*)p = u;
;   DI void operator()(const f32x4 (&acc)[2][2][4][2], const pg8::Unit& u, int wr, int wc, int fr_, int fq_) const {
;     ...
;             } else if (EPI == EPI_CIN) {
;               if (n == 0) {
;                 const int gb = u.pn * 256 + bj * 128 + wc * 32;
;                 const int f8 = gb + 8 * fq;
;                 const f32x4 v1 = acc[ai][bj][m][1];
;                 if (gb < 1024) st_bf8((u16*)(big + O_QD) + (size_t)token * 1024 + f8, v, v1, rinv * (0.125f * LOG2E));
;                 else if (gb < 2048) st_bf8((u16*)(big + O_KD) + (size_t)token * 1024 + (f8 - 1024), v, v1, rinv);
;                 else st_bf8((u16*)(big + O_VDT) + (size_t)token * 1024 + (f8 - 2048), v, v1, rinv);
.LBB0_454:
	s_waitcnt lgkmcnt(0)
	v_mul_f32_e32 v64, v60, v70
	v_mul_f32_e32 v65, v61, v70
	v_mul_f32_e32 v66, v62, v70
	v_mul_f32_e32 v67, v63, v70
	v_cvt_pk_bf16_f32 v64, v64, v65
	v_cvt_pk_bf16_f32 v65, v66, v67
	v_mul_f32_e32 v66, v56, v70
	v_mul_f32_e32 v67, v57, v70
	v_mul_f32_e32 v74, v58, v70
	v_mul_f32_e32 v75, v59, v70
	v_lshl_add_u64 v[72:73], v[144:145], 1, v[68:69]
	v_cvt_pk_bf16_f32 v66, v66, v67
	v_cvt_pk_bf16_f32 v67, v74, v75
	s_and_b64 vcc, exec, s[2:3]
	s_cbranch_vccnz .LBB0_456
	v_add_co_u32_e32 v74, vcc, 0x7fff000, v72
	s_mov_b64 s[22:23], 0
	s_nop 0
	v_addc_co_u32_e32 v75, vcc, 0, v73, vcc
	global_store_dwordx4 v[74:75], v[64:67], off

; DI void st_bf8(u16* p, f32x4 a, f32x4 b, float sc) {
;   u32x4 u; u.x = pack2(a[0] * sc, a[1] * sc); u.y = pack2(a[2] * sc, a[3] * sc); u.z = pack2(b[0] * sc, b[1] * sc); u.w = pack2(b[2] * sc, b[3] * sc);
;   *(u32x4*)p = u;
;   DI void operator()(const f32x4 (&acc)[2][2][4][2], const pg8::Unit& u, int wr, int wc, int fr_, int fq_) const {
;     ...
;             } else if (EPI == EPI_CIN) {
;               if (n == 0) {
;                 const int gb = u.pn * 256 + bj * 128 + wc * 32;
;                 const int f8 = gb + 8 * fq;
;                 const f32x4 v1 = acc[ai][bj][m][1];
;                 if (gb < 1024) st_bf8((u16*)(big + O_QD) + (size_t)token * 1024 + f8, v, v1, rinv * (0.125f * LOG2E));
;                 else if (gb < 2048) st_bf8((u16*)(big + O_KD) + (size_t)token * 1024 + (f8 - 1024), v, v1, rinv);
;                 else st_bf8((u16*)(big + O_VDT) + (size_t)token * 1024 + (f8 - 2048), v, v1, rinv);
.LBB0_459:
	v_mul_f32_e32 v60, v60, v64
	v_mul_f32_e32 v61, v61, v64
	v_mul_f32_e32 v62, v62, v64
	v_mul_f32_e32 v63, v63, v64
	v_mul_f32_e32 v56, v56, v64
	v_mul_f32_e32 v57, v57, v64
	v_cvt_pk_bf16_f32 v60, v60, v61
	v_cvt_pk_bf16_f32 v61, v62, v63
	v_cvt_pk_bf16_f32 v62, v56, v57
	v_mul_f32_e32 v56, v58, v64
	v_mul_f32_e32 v57, v59, v64
	v_lshl_add_u64 v[66:67], v[148:149], 1, v[68:69]
	v_cvt_pk_bf16_f32 v63, v56, v57
	global_store_dwordx4 v[66:67], v[60:63], off
	s_and_b64 vcc, exec, s[4:5]
	s_mov_b64 s[22:23], -1
	s_cbranch_vccnz .LBB0_416
.LBB0_460:
	v_mov_b32_e32 v125, v145
	v_lshl_add_u64 v[56:57], v[124:125], 1, v[68:69]
	s_mov_b64 s[22:23], 0x100
	v_lshl_add_u64 v[60:61], v[56:57], 0, s[22:23]
	v_mul_f32_e32 v56, v52, v70
	v_mul_f32_e32 v57, v53, v70
	v_mul_f32_e32 v58, v54, v70
	v_mul_f32_e32 v59, v55, v70
	v_cvt_pk_bf16_f32 v56, v56, v57
	v_cvt_pk_bf16_f32 v57, v58, v59
	v_mul_f32_e32 v58, v48, v70
	v_mul_f32_e32 v59, v49, v70
	v_mul_f32_e32 v62, v50, v70
	v_mul_f32_e32 v63, v51, v70
	v_cvt_pk_bf16_f32 v58, v58, v59
	v_cvt_pk_bf16_f32 v59, v62, v63
	s_and_b64 vcc, exec, s[2:3]
	s_mov_b64 s[22:23], -1
	s_cbranch_vccnz .LBB0_462
	v_add_co_u32_e32 v62, vcc, 0x7fff000, v60
	s_mov_b64 s[22:23], 0
	s_nop 0
	v_addc_co_u32_e32 v63, vcc, 0, v61, vcc
	global_store_dwordx4 v[62:63], v[56:59], off

; DI void st_bf8(u16* p, f32x4 a, f32x4 b, float sc) {
;   u32x4 u; u.x = pack2(a[0] * sc, a[1] * sc); u.y = pack2(a[2] * sc, a[3] * sc); u.z = pack2(b[0] * sc, b[1] * sc); u.w = pack2(b[2] * sc, b[3] * sc);
;   *(u32x4*)p = u;
;   DI void operator()(const f32x4 (&acc)[2][2][4][2], const pg8::Unit& u, int wr, int wc, int fr_, int fq_) const {
;     ...
;             } else if (EPI == EPI_CIN) {
;               if (n == 0) {
;                 const int gb = u.pn * 256 + bj * 128 + wc * 32;
;                 const int f8 = gb + 8 * fq;
;                 const f32x4 v1 = acc[ai][bj][m][1];
;                 if (gb < 1024) st_bf8((u16*)(big + O_QD) + (size_t)token * 1024 + f8, v, v1, rinv * (0.125f * LOG2E));
;                 else if (gb < 2048) st_bf8((u16*)(big + O_KD) + (size_t)token * 1024 + (f8 - 1024), v, v1, rinv);
;                 else st_bf8((u16*)(big + O_VDT) + (size_t)token * 1024 + (f8 - 2048), v, v1, rinv);
.LBB0_465:
	s_waitcnt lgkmcnt(0)
	v_mul_f32_e32 v48, v44, v54
	v_mul_f32_e32 v49, v45, v54
	v_mul_f32_e32 v50, v46, v54
	v_mul_f32_e32 v51, v47, v54
	v_cvt_pk_bf16_f32 v48, v48, v49
	v_cvt_pk_bf16_f32 v49, v50, v51
	v_mul_f32_e32 v50, v40, v54
	v_mul_f32_e32 v51, v41, v54
	v_mul_f32_e32 v58, v42, v54
	v_mul_f32_e32 v59, v43, v54
	v_lshl_add_u64 v[56:57], v[144:145], 1, v[52:53]
	v_cvt_pk_bf16_f32 v50, v50, v51
	v_cvt_pk_bf16_f32 v51, v58, v59
	s_and_b64 vcc, exec, s[2:3]
	s_cbranch_vccnz .LBB0_467
	v_add_co_u32_e32 v58, vcc, 0x7fff000, v56
	s_mov_b64 s[22:23], 0
	s_nop 0
	v_addc_co_u32_e32 v59, vcc, 0, v57, vcc
	global_store_dwordx4 v[58:59], v[48:51], off

; DI void st_bf8(u16* p, f32x4 a, f32x4 b, float sc) {
;   u32x4 u; u.x = pack2(a[0] * sc, a[1] * sc); u.y = pack2(a[2] * sc, a[3] * sc); u.z = pack2(b[0] * sc, b[1] * sc); u.w = pack2(b[2] * sc, b[3] * sc);
;   *(u32x4*)p = u;
;   DI void operator()(const f32x4 (&acc)[2][2][4][2], const pg8::Unit& u, int wr, int wc, int fr_, int fq_) const {
;     ...
;             } else if (EPI == EPI_CIN) {
;               if (n == 0) {
;                 const int gb = u.pn * 256 + bj * 128 + wc * 32;
;                 const int f8 = gb + 8 * fq;
;                 const f32x4 v1 = acc[ai][bj][m][1];
;                 if (gb < 1024) st_bf8((u16*)(big + O_QD) + (size_t)token * 1024 + f8, v, v1, rinv * (0.125f * LOG2E));
;                 else if (gb < 2048) st_bf8((u16*)(big + O_KD) + (size_t)token * 1024 + (f8 - 1024), v, v1, rinv);
;                 else st_bf8((u16*)(big + O_VDT) + (size_t)token * 1024 + (f8 - 2048), v, v1, rinv);
.LBB0_470:
	v_mul_f32_e32 v44, v44, v48
	v_mul_f32_e32 v45, v45, v48
	v_mul_f32_e32 v46, v46, v48
	v_mul_f32_e32 v47, v47, v48
	v_mul_f32_e32 v40, v40, v48
	v_mul_f32_e32 v41, v41, v48
	v_cvt_pk_bf16_f32 v44, v44, v45
	v_cvt_pk_bf16_f32 v45, v46, v47
	v_cvt_pk_bf16_f32 v46, v40, v41
	v_mul_f32_e32 v40, v42, v48
	v_mul_f32_e32 v41, v43, v48
	v_lshl_add_u64 v[50:51], v[148:149], 1, v[52:53]
	v_cvt_pk_bf16_f32 v47, v40, v41
	global_store_dwordx4 v[50:51], v[44:47], off
	s_and_b64 vcc, exec, s[4:5]
	s_mov_b64 s[22:23], -1
	s_cbranch_vccnz .LBB0_421
.LBB0_471:
	v_mov_b32_e32 v125, v145
	v_lshl_add_u64 v[40:41], v[124:125], 1, v[52:53]
	s_mov_b64 s[22:23], 0x100
	v_lshl_add_u64 v[44:45], v[40:41], 0, s[22:23]
	v_mul_f32_e32 v40, v36, v54
	v_mul_f32_e32 v41, v37, v54
	v_mul_f32_e32 v42, v38, v54
	v_mul_f32_e32 v43, v39, v54
	v_cvt_pk_bf16_f32 v40, v40, v41
	v_cvt_pk_bf16_f32 v41, v42, v43
	v_mul_f32_e32 v42, v32, v54
	v_mul_f32_e32 v43, v33, v54
	v_mul_f32_e32 v46, v34, v54
	v_mul_f32_e32 v47, v35, v54
	v_cvt_pk_bf16_f32 v42, v42, v43
	v_cvt_pk_bf16_f32 v43, v46, v47
	s_and_b64 vcc, exec, s[2:3]
	s_mov_b64 s[22:23], -1
	s_cbranch_vccnz .LBB0_473
	v_add_co_u32_e32 v46, vcc, 0x7fff000, v44
	s_mov_b64 s[22:23], 0
	s_nop 0
	v_addc_co_u32_e32 v47, vcc, 0, v45, vcc
	global_store_dwordx4 v[46:47], v[40:43], off

; DI void st_bf8(u16* p, f32x4 a, f32x4 b, float sc) {
;   u32x4 u; u.x = pack2(a[0] * sc, a[1] * sc); u.y = pack2(a[2] * sc, a[3] * sc); u.z = pack2(b[0] * sc, b[1] * sc); u.w = pack2(b[2] * sc, b[3] * sc);
;   *(u32x4*)p = u;
;   DI void operator()(const f32x4 (&acc)[2][2][4][2], const pg8::Unit& u, int wr, int wc, int fr_, int fq_) const {
;     ...
;             } else if (EPI == EPI_CIN) {
;               if (n == 0) {
;                 const int gb = u.pn * 256 + bj * 128 + wc * 32;
;                 const int f8 = gb + 8 * fq;
;                 const f32x4 v1 = acc[ai][bj][m][1];
;                 if (gb < 1024) st_bf8((u16*)(big + O_QD) + (size_t)token * 1024 + f8, v, v1, rinv * (0.125f * LOG2E));
;                 else if (gb < 2048) st_bf8((u16*)(big + O_KD) + (size_t)token * 1024 + (f8 - 1024), v, v1, rinv);
;                 else st_bf8((u16*)(big + O_VDT) + (size_t)token * 1024 + (f8 - 2048), v, v1, rinv);
.LBB0_476:
	s_waitcnt lgkmcnt(0)
	v_mul_f32_e32 v32, v28, v38
	v_mul_f32_e32 v33, v29, v38
	v_mul_f32_e32 v34, v30, v38
	v_mul_f32_e32 v35, v31, v38
	v_cvt_pk_bf16_f32 v32, v32, v33
	v_cvt_pk_bf16_f32 v33, v34, v35
	v_mul_f32_e32 v34, v24, v38
	v_mul_f32_e32 v35, v25, v38
	v_mul_f32_e32 v42, v26, v38
	v_mul_f32_e32 v43, v27, v38
	v_lshl_add_u64 v[40:41], v[144:145], 1, v[36:37]
	v_cvt_pk_bf16_f32 v34, v34, v35
	v_cvt_pk_bf16_f32 v35, v42, v43
	s_and_b64 vcc, exec, s[2:3]
	s_cbranch_vccnz .LBB0_478
	v_add_co_u32_e32 v42, vcc, 0x7fff000, v40
	s_mov_b64 s[22:23], 0
	s_nop 0
	v_addc_co_u32_e32 v43, vcc, 0, v41, vcc
	global_store_dwordx4 v[42:43], v[32:35], off

; DI void st_bf8(u16* p, f32x4 a, f32x4 b, float sc) {
;   u32x4 u; u.x = pack2(a[0] * sc, a[1] * sc); u.y = pack2(a[2] * sc, a[3] * sc); u.z = pack2(b[0] * sc, b[1] * sc); u.w = pack2(b[2] * sc, b[3] * sc);
;   *(u32x4*)p = u;
;   DI void operator()(const f32x4 (&acc)[2][2][4][2], const pg8::Unit& u, int wr, int wc, int fr_, int fq_) const {
;     ...
;             } else if (EPI == EPI_CIN) {
;               if (n == 0) {
;                 const int gb = u.pn * 256 + bj * 128 + wc * 32;
;                 const int f8 = gb + 8 * fq;
;                 const f32x4 v1 = acc[ai][bj][m][1];
;                 if (gb < 1024) st_bf8((u16*)(big + O_QD) + (size_t)token * 1024 + f8, v, v1, rinv * (0.125f * LOG2E));
;                 else if (gb < 2048) st_bf8((u16*)(big + O_KD) + (size_t)token * 1024 + (f8 - 1024), v, v1, rinv);
;                 else st_bf8((u16*)(big + O_VDT) + (size_t)token * 1024 + (f8 - 2048), v, v1, rinv);
.LBB0_481:
	v_mul_f32_e32 v28, v28, v32
	v_mul_f32_e32 v29, v29, v32
	v_mul_f32_e32 v30, v30, v32
	v_mul_f32_e32 v31, v31, v32
	v_mul_f32_e32 v24, v24, v32
	v_mul_f32_e32 v25, v25, v32
	v_cvt_pk_bf16_f32 v28, v28, v29
	v_cvt_pk_bf16_f32 v29, v30, v31
	v_cvt_pk_bf16_f32 v30, v24, v25
	v_mul_f32_e32 v24, v26, v32
	v_mul_f32_e32 v25, v27, v32
	v_lshl_add_u64 v[34:35], v[148:149], 1, v[36:37]
	v_cvt_pk_bf16_f32 v31, v24, v25
	global_store_dwordx4 v[34:35], v[28:31], off
	s_and_b64 vcc, exec, s[4:5]
	s_mov_b64 s[22:23], -1
	s_cbranch_vccnz .LBB0_426
.LBB0_482:
	v_mov_b32_e32 v125, v145
	v_lshl_add_u64 v[24:25], v[124:125], 1, v[36:37]
	s_mov_b64 s[22:23], 0x100
	v_lshl_add_u64 v[28:29], v[24:25], 0, s[22:23]
	v_mul_f32_e32 v24, v20, v38
	v_mul_f32_e32 v25, v21, v38
	v_mul_f32_e32 v26, v22, v38
	v_mul_f32_e32 v27, v23, v38
	v_cvt_pk_bf16_f32 v24, v24, v25
	v_cvt_pk_bf16_f32 v25, v26, v27
	v_mul_f32_e32 v26, v16, v38
	v_mul_f32_e32 v27, v17, v38
	v_mul_f32_e32 v30, v18, v38
	v_mul_f32_e32 v31, v19, v38
	v_cvt_pk_bf16_f32 v26, v26, v27
	v_cvt_pk_bf16_f32 v27, v30, v31
	s_and_b64 vcc, exec, s[2:3]
	s_mov_b64 s[22:23], -1
	s_cbranch_vccnz .LBB0_484
	v_add_co_u32_e32 v30, vcc, 0x7fff000, v28
	s_mov_b64 s[22:23], 0
	s_nop 0
	v_addc_co_u32_e32 v31, vcc, 0, v29, vcc
	global_store_dwordx4 v[30:31], v[24:27], off

; DI void st_bf8(u16* p, f32x4 a, f32x4 b, float sc) {
;   u32x4 u; u.x = pack2(a[0] * sc, a[1] * sc); u.y = pack2(a[2] * sc, a[3] * sc); u.z = pack2(b[0] * sc, b[1] * sc); u.w = pack2(b[2] * sc, b[3] * sc);
;   *(u32x4*)p = u;
;   DI void operator()(const f32x4 (&acc)[2][2][4][2], const pg8::Unit& u, int wr, int wc, int fr_, int fq_) const {
;     ...
;             } else if (EPI == EPI_CIN) {
;               if (n == 0) {
;                 const int gb = u.pn * 256 + bj * 128 + wc * 32;
;                 const int f8 = gb + 8 * fq;
;                 const f32x4 v1 = acc[ai][bj][m][1];
;                 if (gb < 1024) st_bf8((u16*)(big + O_QD) + (size_t)token * 1024 + f8, v, v1, rinv * (0.125f * LOG2E));
;                 else if (gb < 2048) st_bf8((u16*)(big + O_KD) + (size_t)token * 1024 + (f8 - 1024), v, v1, rinv);
;                 else st_bf8((u16*)(big + O_VDT) + (size_t)token * 1024 + (f8 - 2048), v, v1, rinv);
.LBB0_487:
	s_waitcnt lgkmcnt(0)
	v_mul_f32_e32 v16, v12, v22
	v_mul_f32_e32 v17, v13, v22
	v_mul_f32_e32 v18, v14, v22
	v_mul_f32_e32 v19, v15, v22
	v_cvt_pk_bf16_f32 v16, v16, v17
	v_cvt_pk_bf16_f32 v17, v18, v19
	v_mul_f32_e32 v18, v8, v22
	v_mul_f32_e32 v19, v9, v22
	v_mul_f32_e32 v26, v10, v22
	v_mul_f32_e32 v27, v11, v22
	v_lshl_add_u64 v[24:25], v[144:145], 1, v[20:21]
	v_cvt_pk_bf16_f32 v18, v18, v19
	v_cvt_pk_bf16_f32 v19, v26, v27
	s_and_b64 vcc, exec, s[2:3]
	s_cbranch_vccnz .LBB0_489
	v_add_co_u32_e32 v26, vcc, 0x7fff000, v24
	s_mov_b64 s[22:23], 0
	s_nop 0
	v_addc_co_u32_e32 v27, vcc, 0, v25, vcc
	global_store_dwordx4 v[26:27], v[16:19], off

; DI void st_bf8(u16* p, f32x4 a, f32x4 b, float sc) {
;   u32x4 u; u.x = pack2(a[0] * sc, a[1] * sc); u.y = pack2(a[2] * sc, a[3] * sc); u.z = pack2(b[0] * sc, b[1] * sc); u.w = pack2(b[2] * sc, b[3] * sc);
;   *(u32x4*)p = u;
;   DI void operator()(const f32x4 (&acc)[2][2][4][2], const pg8::Unit& u, int wr, int wc, int fr_, int fq_) const {
;     ...
;             } else if (EPI == EPI_CIN) {
;               if (n == 0) {
;                 const int gb = u.pn * 256 + bj * 128 + wc * 32;
;                 const int f8 = gb + 8 * fq;
;                 const f32x4 v1 = acc[ai][bj][m][1];
;                 if (gb < 1024) st_bf8((u16*)(big + O_QD) + (size_t)token * 1024 + f8, v, v1, rinv * (0.125f * LOG2E));
;                 else if (gb < 2048) st_bf8((u16*)(big + O_KD) + (size_t)token * 1024 + (f8 - 1024), v, v1, rinv);
;                 else st_bf8((u16*)(big + O_VDT) + (size_t)token * 1024 + (f8 - 2048), v, v1, rinv);
.LBB0_492:
	v_mul_f32_e32 v12, v12, v16
	v_mul_f32_e32 v13, v13, v16
	v_mul_f32_e32 v14, v14, v16
	v_mul_f32_e32 v15, v15, v16
	v_mul_f32_e32 v8, v8, v16
	v_mul_f32_e32 v9, v9, v16
	v_cvt_pk_bf16_f32 v12, v12, v13
	v_cvt_pk_bf16_f32 v13, v14, v15
	v_cvt_pk_bf16_f32 v14, v8, v9
	v_mul_f32_e32 v8, v10, v16
	v_mul_f32_e32 v9, v11, v16
	v_lshl_add_u64 v[18:19], v[148:149], 1, v[20:21]
	v_cvt_pk_bf16_f32 v15, v8, v9
	global_store_dwordx4 v[18:19], v[12:15], off
	s_and_b64 vcc, exec, s[4:5]
	s_mov_b64 s[4:5], -1
	s_cbranch_vccnz .LBB0_431
.LBB0_493:
	v_mov_b32_e32 v125, v145
	v_lshl_add_u64 v[8:9], v[124:125], 1, v[20:21]
	s_mov_b64 s[4:5], 0x100
	v_lshl_add_u64 v[12:13], v[8:9], 0, s[4:5]
	v_mul_f32_e32 v8, v4, v22
	v_mul_f32_e32 v9, v5, v22
	v_mul_f32_e32 v10, v6, v22
	v_mul_f32_e32 v11, v7, v22
	v_cvt_pk_bf16_f32 v8, v8, v9
	v_cvt_pk_bf16_f32 v9, v10, v11
	v_mul_f32_e32 v10, v0, v22
	v_mul_f32_e32 v11, v1, v22
	v_mul_f32_e32 v14, v2, v22
	v_mul_f32_e32 v15, v3, v22
	v_cvt_pk_bf16_f32 v10, v10, v11
	v_cvt_pk_bf16_f32 v11, v14, v15
	s_and_b64 vcc, exec, s[2:3]
	s_mov_b64 s[2:3], -1
	s_cbranch_vccnz .LBB0_495
	v_add_co_u32_e32 v14, vcc, 0x7fff000, v12
	s_mov_b64 s[2:3], 0
	s_nop 0
	v_addc_co_u32_e32 v15, vcc, 0, v13, vcc
	global_store_dwordx4 v[14:15], v[8:11], off

; DI void st_bf8(u16* p, f32x4 a, f32x4 b, float sc) {
;   u32x4 u; u.x = pack2(a[0] * sc, a[1] * sc); u.y = pack2(a[2] * sc, a[3] * sc); u.z = pack2(b[0] * sc, b[1] * sc); u.w = pack2(b[2] * sc, b[3] * sc);
;   *(u32x4*)p = u;
;   DI void operator()(const f32x4 (&acc)[2][2][4][2], const pg8::Unit& u, int wr, int wc, int fr_, int fq_) const {
;     ...
;             } else if (EPI == EPI_CIN) {
;               if (n == 0) {
;                 const int gb = u.pn * 256 + bj * 128 + wc * 32;
;                 const int f8 = gb + 8 * fq;
;                 const f32x4 v1 = acc[ai][bj][m][1];
;                 if (gb < 1024) st_bf8((u16*)(big + O_QD) + (size_t)token * 1024 + f8, v, v1, rinv * (0.125f * LOG2E));
;                 else if (gb < 2048) st_bf8((u16*)(big + O_KD) + (size_t)token * 1024 + (f8 - 1024), v, v1, rinv);
;                 else st_bf8((u16*)(big + O_VDT) + (size_t)token * 1024 + (f8 - 2048), v, v1, rinv);
.LBB0_498:
	v_mov_b32_e32 v147, v145
	s_ashr_i32 s21, s20, 31
	v_mul_f32_e32 v4, v4, v16
	v_mul_f32_e32 v5, v5, v16
	v_mul_f32_e32 v6, v6, v16
	v_mul_f32_e32 v7, v7, v16
	v_mul_f32_e32 v0, v0, v16
	v_mul_f32_e32 v1, v1, v16
	v_lshl_add_u64 v[8:9], v[146:147], 0, s[20:21]
	v_cvt_pk_bf16_f32 v4, v4, v5
	v_cvt_pk_bf16_f32 v5, v6, v7
	v_cvt_pk_bf16_f32 v6, v0, v1
	v_mul_f32_e32 v0, v2, v16
	v_mul_f32_e32 v1, v3, v16
	v_lshl_add_u64 v[8:9], v[8:9], 1, v[20:21]
	v_cvt_pk_bf16_f32 v7, v0, v1
	global_store_dwordx4 v[8:9], v[4:7], off offset:256
	s_branch .LBB0_366

; DI void attn_diff_unit(const Params& p, int li, int b, int h, int qb, char* smem, bool pre, int nh, bool has_next) {
;     ...
;   __syncthreads();
;   if (map == 0) {
;     const float lam = ((const float*)(p.ws + TB_LAM))[li];
;     const int layer = 2 * li + 1;
;     const float linit = 0.8f - 0.6f * expf(-0.3f * (float)layer);
;     float ss = 0.f;
; #pragma unroll
;     for (int j = 0; j < 4; ++j)
; #pragma unroll
;       for (int i = 0; i < 16; ++i) {
;         float v = O[j][i] * inv - lam * xch[(rg * 64 + j * 16 + i) * 64 + lane];
;         O[j][i] = v; ss += v * v;
;       }
.LBB0_596:
	s_or_b64 exec, exec, s[2:3]
	s_movk_i32 s2, 0x100
	v_cmp_gt_u32_e32 vcc, s2, v146
	s_waitcnt lgkmcnt(0)
	s_barrier
	s_and_saveexec_b64 s[2:3], vcc
	s_cbranch_execz .LBB0_560
	global_load_dword v72, v145, s[18:19]
	s_add_i32 s24, 0, 0x12800
	v_lshlrev_b32_e32 v70, 8, v146
	v_lshl_add_u32 v67, v158, 2, s24
	v_and_b32_e32 v64, 0xc000, v70
	v_add_u32_e32 v71, v67, v64
	s_waitcnt vmcnt(2)
	ds_read2st64_b32 v[130:131], v71 offset1:1
	ds_read2st64_b32 v[132:133], v71 offset0:2 offset1:3
	ds_read2st64_b32 v[126:127], v71 offset0:4 offset1:5
	ds_read2st64_b32 v[128:129], v71 offset0:6 offset1:7
	ds_read2st64_b32 v[122:123], v71 offset0:8 offset1:9
	ds_read2st64_b32 v[124:125], v71 offset0:10 offset1:11
	ds_read2st64_b32 v[118:119], v71 offset0:12 offset1:13
	ds_read2st64_b32 v[120:121], v71 offset0:14 offset1:15
	ds_read2st64_b32 v[114:115], v71 offset0:16 offset1:17
	ds_read2st64_b32 v[116:117], v71 offset0:18 offset1:19
	ds_read2st64_b32 v[110:111], v71 offset0:20 offset1:21
	ds_read2st64_b32 v[112:113], v71 offset0:22 offset1:23
	ds_read2st64_b32 v[106:107], v71 offset0:24 offset1:25
	ds_read2st64_b32 v[108:109], v71 offset0:26 offset1:27
	ds_read2st64_b32 v[102:103], v71 offset0:28 offset1:29
	ds_read2st64_b32 v[104:105], v71 offset0:30 offset1:31
	ds_read2st64_b32 v[98:99], v71 offset0:32 offset1:33
	ds_read2st64_b32 v[100:101], v71 offset0:34 offset1:35
	ds_read2st64_b32 v[94:95], v71 offset0:36 offset1:37
	ds_read2st64_b32 v[96:97], v71 offset0:38 offset1:39
	ds_read2st64_b32 v[90:91], v71 offset0:40 offset1:41
	ds_read2st64_b32 v[92:93], v71 offset0:42 offset1:43
	ds_read2st64_b32 v[86:87], v71 offset0:44 offset1:45
	ds_read2st64_b32 v[88:89], v71 offset0:46 offset1:47
	ds_read2st64_b32 v[82:83], v71 offset0:48 offset1:49
	ds_read2st64_b32 v[84:85], v71 offset0:50 offset1:51
	ds_read2st64_b32 v[78:79], v71 offset0:52 offset1:53
	ds_read2st64_b32 v[80:81], v71 offset0:54 offset1:55
	ds_read2st64_b32 v[74:75], v71 offset0:56 offset1:57
	ds_read2st64_b32 v[76:77], v71 offset0:58 offset1:59
	ds_read2st64_b32 v[64:65], v71 offset0:60 offset1:61
	v_lshlrev_b32_e32 v144, 1, v144
	s_lshl_b32 s24, s41, 1
	s_waitcnt vmcnt(0) lgkmcnt(0)
	v_mul_f32_e32 v64, v72, v64
	v_mul_f32_e32 v65, v72, v65
	v_pk_fma_f32 v[64:65], v[12:13], v[66:67], v[64:65] op_sel_hi:[1,0,1] neg_lo:[0,0,1] neg_hi:[0,0,1]
	v_or_b32_e32 v13, 0x3f00, v70
	v_add_u32_e32 v13, v67, v13
	ds_read_b32 v12, v71 offset:15872
	ds_read_b32 v13, v13
	v_mul_f32_e32 v126, v72, v126
	v_mul_f32_e32 v127, v72, v127
	v_mul_f32_e32 v130, v72, v130
	v_mul_f32_e32 v131, v72, v131
	v_mul_f32_e32 v132, v72, v132
	v_mul_f32_e32 v133, v72, v133
	v_mul_f32_e32 v128, v72, v128
	v_mul_f32_e32 v129, v72, v129
	s_waitcnt lgkmcnt(0)
	v_mul_f32_e32 v12, v72, v12
	v_mul_f32_e32 v13, v72, v13
	v_pk_fma_f32 v[12:13], v[14:15], v[66:67], v[12:13] op_sel_hi:[1,0,1] neg_lo:[0,0,1] neg_hi:[0,0,1]
	v_lshlrev_b32_e32 v67, 2, v153
	global_load_dwordx4 v[134:137], v67, s[20:21]
	v_pk_fma_f32 v[126:127], v[52:53], v[66:67], v[126:127] op_sel_hi:[1,0,1] neg_lo:[0,0,1] neg_hi:[0,0,1]
	v_mul_f32_e32 v52, v72, v124
	v_mul_f32_e32 v53, v72, v125
	v_pk_fma_f32 v[52:53], v[58:59], v[66:67], v[52:53] op_sel_hi:[1,0,1] neg_lo:[0,0,1] neg_hi:[0,0,1]
	v_mul_f32_e32 v58, v72, v122
	v_mul_f32_e32 v59, v72, v123
	v_pk_fma_f32 v[58:59], v[56:57], v[66:67], v[58:59] op_sel_hi:[1,0,1] neg_lo:[0,0,1] neg_hi:[0,0,1]
	v_mul_f32_e32 v56, v72, v120
	v_mul_f32_e32 v57, v72, v121
	v_pk_fma_f32 v[56:57], v[62:63], v[66:67], v[56:57] op_sel_hi:[1,0,1] neg_lo:[0,0,1] neg_hi:[0,0,1]
	v_mul_f32_e32 v62, v72, v118
	v_mul_f32_e32 v63, v72, v119
	v_pk_fma_f32 v[60:61], v[60:61], v[66:67], v[62:63] op_sel_hi:[1,0,1] neg_lo:[0,0,1] neg_hi:[0,0,1]
	v_mul_f32_e32 v62, v72, v116
	v_mul_f32_e32 v63, v72, v117
	v_pk_fma_f32 v[34:35], v[34:35], v[66:67], v[62:63] op_sel_hi:[1,0,1] neg_lo:[0,0,1] neg_hi:[0,0,1]
	v_mul_f32_e32 v62, v72, v114
	v_mul_f32_e32 v63, v72, v115
	v_pk_fma_f32 v[32:33], v[32:33], v[66:67], v[62:63] op_sel_hi:[1,0,1] neg_lo:[0,0,1] neg_hi:[0,0,1]
	v_mul_f32_e32 v62, v72, v112
	v_mul_f32_e32 v63, v72, v113
	v_pk_fma_f32 v[38:39], v[38:39], v[66:67], v[62:63] op_sel_hi:[1,0,1] neg_lo:[0,0,1] neg_hi:[0,0,1]
	v_mul_f32_e32 v62, v72, v110
	v_mul_f32_e32 v63, v72, v111
	v_pk_fma_f32 v[110:111], v[36:37], v[66:67], v[62:63] op_sel_hi:[1,0,1] neg_lo:[0,0,1] neg_hi:[0,0,1]
	v_mul_f32_e32 v36, v72, v108
	v_mul_f32_e32 v37, v72, v109
	v_pk_fma_f32 v[62:63], v[42:43], v[66:67], v[36:37] op_sel_hi:[1,0,1] neg_lo:[0,0,1] neg_hi:[0,0,1]
	v_mul_f32_e32 v36, v72, v106
	v_mul_f32_e32 v37, v72, v107
	v_pk_fma_f32 v[106:107], v[40:41], v[66:67], v[36:37] op_sel_hi:[1,0,1] neg_lo:[0,0,1] neg_hi:[0,0,1]
	v_mul_f32_e32 v36, v72, v104
	v_mul_f32_e32 v37, v72, v105
	v_pk_fma_f32 v[46:47], v[46:47], v[66:67], v[36:37] op_sel_hi:[1,0,1] neg_lo:[0,0,1] neg_hi:[0,0,1]
	v_mul_f32_e32 v36, v72, v102
	v_mul_f32_e32 v37, v72, v103
	v_pk_fma_f32 v[102:103], v[44:45], v[66:67], v[36:37] op_sel_hi:[1,0,1] neg_lo:[0,0,1] neg_hi:[0,0,1]
	v_mul_f32_e32 v36, v72, v100
	v_mul_f32_e32 v37, v72, v101
	v_pk_fma_f32 v[40:41], v[18:19], v[66:67], v[36:37] op_sel_hi:[1,0,1] neg_lo:[0,0,1] neg_hi:[0,0,1]
	v_mul_f32_e32 v18, v72, v98
	v_mul_f32_e32 v19, v72, v99
	v_pk_fma_f32 v[44:45], v[16:17], v[66:67], v[18:19] op_sel_hi:[1,0,1] neg_lo:[0,0,1] neg_hi:[0,0,1]
	v_mul_f32_e32 v16, v72, v96
	v_mul_f32_e32 v17, v72, v97
	v_pk_fma_f32 v[36:37], v[22:23], v[66:67], v[16:17] op_sel_hi:[1,0,1] neg_lo:[0,0,1] neg_hi:[0,0,1]
	v_mul_f32_e32 v16, v72, v94
	v_mul_f32_e32 v17, v72, v95
	v_pk_fma_f32 v[42:43], v[20:21], v[66:67], v[16:17] op_sel_hi:[1,0,1] neg_lo:[0,0,1] neg_hi:[0,0,1]
; DI void attn_diff_unit(const Params& p, int li, int b, int h, int qb, char* smem, bool pre, int nh, bool has_next) {
;     ...
; #pragma unroll
;     for (int j = 0; j < 4; ++j)
; #pragma unroll
;       for (int i = 0; i < 16; ++i) {
;         float v = O[j][i] * inv - lam * xch[(rg * 64 + j * 16 + i) * 64 + lane];
;         O[j][i] = v; ss += v * v;
;       }
;     ss += shx(ss, 32, lane);
;     const float rinv = rsqrtf(ss * (1.f / 128.f) + EPS) * (1.f - linit);
	v_mul_f32_e32 v16, v72, v92
	v_mul_f32_e32 v17, v72, v93
	v_pk_fma_f32 v[22:23], v[26:27], v[66:67], v[16:17] op_sel_hi:[1,0,1] neg_lo:[0,0,1] neg_hi:[0,0,1]
	v_mul_f32_e32 v16, v72, v90
	v_mul_f32_e32 v17, v72, v91
	v_pk_fma_f32 v[26:27], v[24:25], v[66:67], v[16:17] op_sel_hi:[1,0,1] neg_lo:[0,0,1] neg_hi:[0,0,1]
	v_mul_f32_e32 v16, v72, v88
	v_mul_f32_e32 v17, v72, v89
	v_pk_fma_f32 v[18:19], v[30:31], v[66:67], v[16:17] op_sel_hi:[1,0,1] neg_lo:[0,0,1] neg_hi:[0,0,1]
	v_mul_f32_e32 v16, v72, v86
	v_mul_f32_e32 v17, v72, v87
	v_pk_fma_f32 v[24:25], v[28:29], v[66:67], v[16:17] op_sel_hi:[1,0,1] neg_lo:[0,0,1] neg_hi:[0,0,1]
	v_mul_f32_e32 v16, v72, v84
	v_mul_f32_e32 v17, v72, v85
	v_pk_fma_f32 v[16:17], v[2:3], v[66:67], v[16:17] op_sel_hi:[1,0,1] neg_lo:[0,0,1] neg_hi:[0,0,1]
	v_mul_f32_e32 v2, v72, v82
	v_mul_f32_e32 v3, v72, v83
	v_pk_fma_f32 v[20:21], v[0:1], v[66:67], v[2:3] op_sel_hi:[1,0,1] neg_lo:[0,0,1] neg_hi:[0,0,1]
	v_mul_f32_e32 v0, v72, v80
	v_mul_f32_e32 v1, v72, v81
	v_pk_fma_f32 v[48:49], v[48:49], v[66:67], v[130:131] op_sel_hi:[1,0,1] neg_lo:[0,0,1] neg_hi:[0,0,1]
	v_pk_fma_f32 v[2:3], v[6:7], v[66:67], v[0:1] op_sel_hi:[1,0,1] neg_lo:[0,0,1] neg_hi:[0,0,1]
	v_mul_f32_e32 v0, v72, v78
	v_mul_f32_e32 v1, v72, v79
	v_pk_fma_f32 v[50:51], v[50:51], v[66:67], v[132:133] op_sel_hi:[1,0,1] neg_lo:[0,0,1] neg_hi:[0,0,1]
	v_mul_f32_e32 v130, v48, v48
	v_mul_f32_e32 v131, v49, v49
	v_pk_fma_f32 v[6:7], v[4:5], v[66:67], v[0:1] op_sel_hi:[1,0,1] neg_lo:[0,0,1] neg_hi:[0,0,1]
	v_mul_f32_e32 v0, v72, v76
	v_mul_f32_e32 v1, v72, v77
	v_mul_f32_e32 v4, v72, v74
	v_mul_f32_e32 v5, v72, v75
	v_mul_f32_e32 v132, v50, v50
	v_mul_f32_e32 v133, v51, v51
	v_pk_fma_f32 v[54:55], v[54:55], v[66:67], v[128:129] op_sel_hi:[1,0,1] neg_lo:[0,0,1] neg_hi:[0,0,1]
	v_pk_fma_f32 v[0:1], v[10:11], v[66:67], v[0:1] op_sel_hi:[1,0,1] neg_lo:[0,0,1] neg_hi:[0,0,1]
	v_pk_fma_f32 v[4:5], v[8:9], v[66:67], v[4:5] op_sel_hi:[1,0,1] neg_lo:[0,0,1] neg_hi:[0,0,1]
	v_add_f32_e32 v66, v130, v131
	v_add_f32_e32 v66, v66, v132
	v_add_f32_e32 v66, v66, v133
	v_mul_f32_e32 v128, v54, v54
	v_mul_f32_e32 v129, v55, v55
	v_mul_f32_e32 v122, v58, v58
	v_mul_f32_e32 v123, v59, v59
	v_mul_f32_e32 v124, v52, v52
	v_mul_f32_e32 v125, v53, v53
	v_mul_f32_e32 v118, v60, v60
	v_mul_f32_e32 v119, v61, v61
	v_mul_f32_e32 v120, v56, v56
	v_mul_f32_e32 v121, v57, v57
	v_mul_f32_e32 v114, v32, v32
	v_mul_f32_e32 v115, v33, v33
	v_mul_f32_e32 v116, v34, v34
	v_mul_f32_e32 v117, v35, v35
	v_mul_f32_e32 v112, v38, v38
	v_mul_f32_e32 v113, v39, v39
	v_mul_f32_e32 v138, v106, v106
	v_mul_f32_e32 v139, v107, v107
	v_mul_f32_e32 v108, v62, v62
	v_mul_f32_e32 v109, v63, v63
	v_mul_f32_e32 v140, v102, v102
	v_mul_f32_e32 v141, v103, v103
	v_mul_f32_e32 v104, v46, v46
	v_mul_f32_e32 v105, v47, v47
	v_mul_f32_e32 v98, v44, v44
	v_mul_f32_e32 v99, v45, v45
	v_mul_f32_e32 v100, v40, v40
	v_mul_f32_e32 v101, v41, v41
	v_mul_f32_e32 v94, v42, v42
	v_mul_f32_e32 v95, v43, v43
	v_mul_f32_e32 v96, v36, v36
	v_mul_f32_e32 v97, v37, v37
	v_mul_f32_e32 v90, v26, v26
	v_mul_f32_e32 v91, v27, v27
	v_mul_f32_e32 v92, v22, v22
	v_mul_f32_e32 v93, v23, v23
	s_waitcnt vmcnt(0)
	v_mul_f32_e32 v48, v48, v134
	v_mul_f32_e32 v49, v49, v135
	v_mul_f32_e32 v134, v126, v126
	v_mul_f32_e32 v135, v127, v127
	v_mul_f32_e32 v50, v50, v136
	v_mul_f32_e32 v51, v51, v137
	v_add_f32_e32 v66, v66, v134
	v_add_f32_e32 v66, v66, v135
	v_add_f32_e32 v66, v66, v128
	v_add_f32_e32 v66, v66, v129
	v_add_f32_e32 v66, v66, v122
	v_add_f32_e32 v66, v66, v123
	v_add_f32_e32 v66, v66, v124
	v_add_f32_e32 v66, v66, v125
	v_add_f32_e32 v66, v66, v118
	v_add_f32_e32 v66, v66, v119
	v_add_f32_e32 v66, v66, v120
	v_add_f32_e32 v66, v66, v121
	v_add_f32_e32 v66, v66, v114
	v_add_f32_e32 v66, v66, v115
	v_add_f32_e32 v66, v66, v116
	v_mul_f32_e32 v136, v110, v110
	v_mul_f32_e32 v137, v111, v111
	v_add_f32_e32 v66, v66, v117
	v_add_f32_e32 v66, v66, v136
	v_add_f32_e32 v66, v66, v137
	v_add_f32_e32 v66, v66, v112
	v_add_f32_e32 v66, v66, v113
	v_add_f32_e32 v66, v66, v138
	v_add_f32_e32 v66, v66, v139
	v_add_f32_e32 v66, v66, v108
	v_add_f32_e32 v66, v66, v109
	v_add_f32_e32 v66, v66, v140
	v_add_f32_e32 v66, v66, v141
	v_add_f32_e32 v66, v66, v104
	v_add_f32_e32 v66, v66, v105
	v_add_f32_e32 v66, v66, v98
	v_add_f32_e32 v66, v66, v99
	v_add_f32_e32 v66, v66, v100
	v_add_f32_e32 v66, v66, v101
	v_add_f32_e32 v66, v66, v94
	v_add_f32_e32 v66, v66, v95
	v_add_f32_e32 v66, v66, v96
	v_add_f32_e32 v66, v66, v97
	v_add_f32_e32 v66, v66, v90
	v_add_f32_e32 v66, v66, v91
	v_add_f32_e32 v66, v66, v92
	v_mul_f32_e32 v28, v24, v24
	v_mul_f32_e32 v29, v25, v25
	v_add_f32_e32 v66, v66, v93
	v_add_f32_e32 v28, v66, v28
	v_mul_f32_e32 v30, v18, v18
	v_mul_f32_e32 v31, v19, v19
	v_add_f32_e32 v28, v28, v29
	v_add_f32_e32 v28, v28, v30
	v_mul_f32_e32 v82, v20, v20
	v_mul_f32_e32 v83, v21, v21
	v_add_f32_e32 v28, v28, v31
	v_add_f32_e32 v28, v28, v82
	v_mul_f32_e32 v84, v16, v16
	v_mul_f32_e32 v85, v17, v17
	v_add_f32_e32 v28, v28, v83
	v_add_f32_e32 v28, v28, v84
	v_mul_f32_e32 v78, v6, v6
	v_mul_f32_e32 v79, v7, v7
	v_add_f32_e32 v28, v28, v85
	v_add_f32_e32 v28, v28, v78
	v_mul_f32_e32 v80, v2, v2
	v_mul_f32_e32 v81, v3, v3
	v_add_f32_e32 v28, v28, v79
	v_add_f32_e32 v28, v28, v80
	v_mul_f32_e32 v8, v4, v4
	v_mul_f32_e32 v9, v5, v5
	v_add_f32_e32 v28, v28, v81
	v_add_f32_e32 v8, v28, v8
	v_mul_f32_e32 v10, v0, v0
	v_mul_f32_e32 v11, v1, v1
	v_add_f32_e32 v8, v8, v9
	v_add_f32_e32 v8, v8, v10
	v_mul_f32_e32 v68, v64, v64
	v_mul_f32_e32 v69, v65, v65
	v_add_f32_e32 v8, v8, v11
	v_add_f32_e32 v8, v8, v68
	v_mul_f32_e32 v70, v12, v12
	v_mul_f32_e32 v71, v13, v13
	v_add_f32_e32 v8, v8, v69
	v_add_f32_e32 v8, v8, v70
	v_add_f32_e32 v8, v8, v71
	ds_bpermute_b32 v9, v147, v8
	v_lshl_add_u64 v[14:15], s[16:17], 0, v[144:145]
	v_lshl_add_u64 v[14:15], v[14:15], 0, s[24:25]
	s_mov_b32 s24, 0x800000
	v_lshlrev_b32_e32 v144, 1, v153
	s_waitcnt lgkmcnt(0)
; DI void attn_diff_unit(const Params& p, int li, int b, int h, int qb, char* smem, bool pre, int nh, bool has_next) {
;     ...
;     ss += shx(ss, 32, lane);
;     const float rinv = rsqrtf(ss * (1.f / 128.f) + EPS) * (1.f - linit);
;     const float* sub = p.c_subln + li * 128;
;     u16* op = o + (size_t)qrow * 1024 + h * 128 + 4 * hh;
; #pragma unroll
;     for (int j = 0; j < 4; ++j)
; #pragma unroll
;       for (int i4 = 0; i4 < 4; ++i4) {
;         const int dv = j * 32 + 8 * i4 + 4 * hh;
;         const f32x4 g4 = *(const f32x4*)(sub + dv);
;         f32x4 v = {O[j][4 * i4] * g4[0], O[j][4 * i4 + 1] * g4[1], O[j][4 * i4 + 2] * g4[2], O[j][4 * i4 + 3] * g4[3]};
;         st_bf4(op + j * 32 + 8 * i4, v, rinv);
	v_add_f32_e32 v8, v8, v9
	v_fmamk_f32 v8, v8, 0x3c000000, v184
	v_cmp_gt_f32_e32 vcc, s24, v8
	v_mul_f32_e32 v9, 0x4b800000, v8
	v_lshl_add_u64 v[14:15], v[14:15], 0, v[144:145]
	v_cndmask_b32_e32 v8, v8, v9, vcc
	v_rsq_f32_e32 v8, v8
	s_nop 0
	v_mul_f32_e32 v9, 0x45800000, v8
	v_cndmask_b32_e32 v8, v8, v9, vcc
	v_mul_f32_e32 v8, v152, v8
	v_mul_f32_e32 v10, v48, v8
	v_mul_f32_e32 v11, v49, v8
	v_mul_f32_e32 v28, v50, v8
	v_mul_f32_e32 v29, v51, v8
	v_cvt_pk_bf16_f32 v10, v10, v11
	v_cvt_pk_bf16_f32 v11, v28, v29
	global_store_dwordx2 v[14:15], v[10:11], off
	global_load_dwordx4 v[28:31], v67, s[20:21] offset:32
	s_waitcnt vmcnt(0)
	v_mul_f32_e32 v10, v126, v28
	v_mul_f32_e32 v11, v127, v29
	v_mul_f32_e32 v28, v54, v30
	v_mul_f32_e32 v29, v55, v31
	v_mul_f32_e32 v10, v10, v8
	v_mul_f32_e32 v11, v11, v8
	v_mul_f32_e32 v28, v28, v8
	v_mul_f32_e32 v29, v29, v8
	v_cvt_pk_bf16_f32 v10, v10, v11
	v_cvt_pk_bf16_f32 v11, v28, v29
	global_store_dwordx2 v[14:15], v[10:11], off offset:16
	global_load_dwordx4 v[28:31], v67, s[20:21] offset:64
	s_waitcnt vmcnt(0)
	v_mul_f32_e32 v10, v58, v28
	v_mul_f32_e32 v11, v59, v29
	v_mul_f32_e32 v28, v52, v30
	v_mul_f32_e32 v29, v53, v31
	v_mul_f32_e32 v10, v10, v8
	v_mul_f32_e32 v11, v11, v8
	v_mul_f32_e32 v28, v28, v8
	v_mul_f32_e32 v29, v29, v8
	v_cvt_pk_bf16_f32 v10, v10, v11
	v_cvt_pk_bf16_f32 v11, v28, v29
	global_store_dwordx2 v[14:15], v[10:11], off offset:32
	global_load_dwordx4 v[28:31], v67, s[20:21] offset:96
	s_waitcnt vmcnt(0)
	v_mul_f32_e32 v10, v60, v28
	v_mul_f32_e32 v11, v61, v29
	v_mul_f32_e32 v28, v56, v30
	v_mul_f32_e32 v29, v57, v31
	v_mul_f32_e32 v10, v10, v8
	v_mul_f32_e32 v11, v11, v8
	v_mul_f32_e32 v28, v28, v8
	v_mul_f32_e32 v29, v29, v8
	v_cvt_pk_bf16_f32 v10, v10, v11
	v_cvt_pk_bf16_f32 v11, v28, v29
	global_store_dwordx2 v[14:15], v[10:11], off offset:48
	global_load_dwordx4 v[28:31], v67, s[20:21] offset:128
	s_waitcnt vmcnt(0)
	v_mul_f32_e32 v10, v32, v28
	v_mul_f32_e32 v11, v33, v29
	v_mul_f32_e32 v28, v34, v30
	v_mul_f32_e32 v29, v35, v31
	v_mul_f32_e32 v10, v10, v8
	v_mul_f32_e32 v11, v11, v8
	v_mul_f32_e32 v28, v28, v8
	v_mul_f32_e32 v29, v29, v8
	v_cvt_pk_bf16_f32 v10, v10, v11
	v_cvt_pk_bf16_f32 v11, v28, v29
	global_store_dwordx2 v[14:15], v[10:11], off offset:64
	global_load_dwordx4 v[28:31], v67, s[20:21] offset:160
	s_waitcnt vmcnt(0)
	v_mul_f32_e32 v10, v110, v28
	v_mul_f32_e32 v11, v111, v29
	v_mul_f32_e32 v28, v38, v30
	v_mul_f32_e32 v29, v39, v31
	v_mul_f32_e32 v10, v8, v10
	v_mul_f32_e32 v11, v8, v11
	v_mul_f32_e32 v28, v8, v28
	v_mul_f32_e32 v29, v8, v29
	v_cvt_pk_bf16_f32 v10, v10, v11
	v_cvt_pk_bf16_f32 v11, v28, v29
	global_store_dwordx2 v[14:15], v[10:11], off offset:80
	global_load_dwordx4 v[28:31], v67, s[20:21] offset:192
	s_waitcnt vmcnt(0)
	v_mul_f32_e32 v10, v106, v28
	v_mul_f32_e32 v11, v107, v29
	v_mul_f32_e32 v28, v62, v30
	v_mul_f32_e32 v29, v63, v31
	v_mul_f32_e32 v10, v8, v10
	v_mul_f32_e32 v11, v8, v11
	v_mul_f32_e32 v28, v8, v28
	v_mul_f32_e32 v29, v8, v29
	v_cvt_pk_bf16_f32 v10, v10, v11
	v_cvt_pk_bf16_f32 v11, v28, v29
	global_store_dwordx2 v[14:15], v[10:11], off offset:96
	global_load_dwordx4 v[28:31], v67, s[20:21] offset:224
	s_waitcnt vmcnt(0)
	v_mul_f32_e32 v10, v102, v28
	v_mul_f32_e32 v11, v103, v29
	v_mul_f32_e32 v28, v46, v30
	v_mul_f32_e32 v29, v47, v31
	v_mul_f32_e32 v10, v8, v10
	v_mul_f32_e32 v11, v8, v11
	v_mul_f32_e32 v28, v8, v28
	v_mul_f32_e32 v29, v8, v29
	v_cvt_pk_bf16_f32 v10, v10, v11
	v_cvt_pk_bf16_f32 v11, v28, v29
	global_store_dwordx2 v[14:15], v[10:11], off offset:112
	global_load_dwordx4 v[28:31], v67, s[20:21] offset:256
	s_waitcnt vmcnt(0)
	v_mul_f32_e32 v10, v44, v28
	v_mul_f32_e32 v11, v45, v29
	v_mul_f32_e32 v28, v40, v30
	v_mul_f32_e32 v29, v41, v31
	v_mul_f32_e32 v10, v8, v10
	v_mul_f32_e32 v11, v8, v11
	v_mul_f32_e32 v28, v8, v28
	v_mul_f32_e32 v29, v8, v29
	v_cvt_pk_bf16_f32 v10, v10, v11
	v_cvt_pk_bf16_f32 v11, v28, v29
	global_store_dwordx2 v[14:15], v[10:11], off offset:128
	global_load_dwordx4 v[28:31], v67, s[20:21] offset:288
	s_waitcnt vmcnt(0)
	v_mul_f32_e32 v10, v42, v28
	v_mul_f32_e32 v11, v43, v29
	v_mul_f32_e32 v28, v36, v30
	v_mul_f32_e32 v29, v37, v31
	v_mul_f32_e32 v10, v8, v10
	v_mul_f32_e32 v11, v8, v11
	v_mul_f32_e32 v28, v8, v28
	v_mul_f32_e32 v29, v8, v29
	v_cvt_pk_bf16_f32 v10, v10, v11
	v_cvt_pk_bf16_f32 v11, v28, v29
	global_store_dwordx2 v[14:15], v[10:11], off offset:144
	global_load_dwordx4 v[28:31], v67, s[20:21] offset:320
	s_waitcnt vmcnt(0)
	v_mul_f32_e32 v10, v26, v28
	v_mul_f32_e32 v11, v27, v29
	v_mul_f32_e32 v22, v22, v30
	v_mul_f32_e32 v23, v23, v31
	v_mul_f32_e32 v10, v8, v10
	v_mul_f32_e32 v11, v8, v11
	v_mul_f32_e32 v22, v8, v22
	v_mul_f32_e32 v23, v8, v23
	v_cvt_pk_bf16_f32 v10, v10, v11
	v_cvt_pk_bf16_f32 v11, v22, v23
	global_store_dwordx2 v[14:15], v[10:11], off offset:160
	global_load_dwordx4 v[26:29], v67, s[20:21] offset:352
	s_waitcnt vmcnt(0)
	v_mul_f32_e32 v10, v24, v26
	v_mul_f32_e32 v11, v25, v27
	v_mul_f32_e32 v18, v18, v28
	v_mul_f32_e32 v19, v19, v29
	v_mul_f32_e32 v10, v8, v10
	v_mul_f32_e32 v11, v8, v11
	v_mul_f32_e32 v18, v8, v18
	v_mul_f32_e32 v19, v8, v19
	v_cvt_pk_bf16_f32 v10, v10, v11
	v_cvt_pk_bf16_f32 v11, v18, v19
	global_store_dwordx2 v[14:15], v[10:11], off offset:176
	global_load_dwordx4 v[22:25], v67, s[20:21] offset:384
	s_waitcnt vmcnt(0)
	v_mul_f32_e32 v10, v20, v22
	v_mul_f32_e32 v11, v21, v23
	v_mul_f32_e32 v16, v16, v24
	v_mul_f32_e32 v17, v17, v25
	v_mul_f32_e32 v10, v8, v10
	v_mul_f32_e32 v11, v8, v11
	v_mul_f32_e32 v16, v8, v16
	v_mul_f32_e32 v17, v8, v17
	v_cvt_pk_bf16_f32 v10, v10, v11
	v_cvt_pk_bf16_f32 v11, v16, v17
	global_store_dwordx2 v[14:15], v[10:11], off offset:192
	global_load_dwordx4 v[16:19], v67, s[20:21] offset:416
	s_waitcnt vmcnt(0)
	v_mul_f32_e32 v6, v6, v16
	v_mul_f32_e32 v7, v7, v17
	v_mul_f32_e32 v2, v2, v18
	v_mul_f32_e32 v3, v3, v19
	v_mul_f32_e32 v6, v8, v6
	v_mul_f32_e32 v7, v8, v7
	v_mul_f32_e32 v2, v8, v2
	v_mul_f32_e32 v3, v8, v3
	v_cvt_pk_bf16_f32 v6, v6, v7
	v_cvt_pk_bf16_f32 v7, v2, v3
	global_store_dwordx2 v[14:15], v[6:7], off offset:208
	global_load_dwordx4 v[16:19], v67, s[20:21] offset:448
	s_waitcnt vmcnt(0)
	v_mul_f32_e32 v2, v4, v16
	v_mul_f32_e32 v3, v5, v17
	v_mul_f32_e32 v0, v0, v18
	v_mul_f32_e32 v1, v1, v19
	v_mul_f32_e32 v2, v8, v2
	v_mul_f32_e32 v3, v8, v3
	v_mul_f32_e32 v0, v8, v0
	v_mul_f32_e32 v1, v8, v1
	v_cvt_pk_bf16_f32 v2, v2, v3
	v_cvt_pk_bf16_f32 v3, v0, v1
	global_store_dwordx2 v[14:15], v[2:3], off offset:224
	global_load_dwordx4 v[0:3], v67, s[20:21] offset:480
	s_waitcnt vmcnt(0)
	v_mul_f32_e32 v0, v64, v0
	v_mul_f32_e32 v1, v65, v1
	v_mul_f32_e32 v2, v12, v2
	v_mul_f32_e32 v3, v13, v3
	v_mul_f32_e32 v0, v8, v0
	v_mul_f32_e32 v1, v8, v1
	v_mul_f32_e32 v2, v8, v2
	v_mul_f32_e32 v3, v8, v3
	v_cvt_pk_bf16_f32 v0, v0, v1
	v_cvt_pk_bf16_f32 v1, v2, v3
	global_store_dwordx2 v[14:15], v[0:1], off offset:240
	s_branch .LBB0_560

; #define PG8_STAGE(bufoff, gbase, voff) do { _Pragma("unroll") for (int _i = 0; _i < 2; ++_i) \
;     __builtin_amdgcn_global_load_lds((const unsigned*)((const char*)(gbase) + (voff)[_i]), (LAS unsigned*)(lds + (bufoff) + ldsw + _i * 8192), 16, 0, 0); } while (0)
; #define PG8_LDA(dst, b, h) do { _Pragma("unroll") for (int m = 0; m < 4; ++m) _Pragma("unroll") for (int k = 0; k < 2; ++k) dst[m][k] = *(const LAS bf16x8*)(lds + PG8_SA(b, h) + aoff + m * 2048 + k * 1024); } while (0)
; #define PG8_LDB(dst, b, h) do { _Pragma("unroll") for (int n = 0; n < 2; ++n) _Pragma("unroll") for (int k = 0; k < 2; ++k) dst[n][k] = *(const LAS bf16x8*)(lds + PG8_SB(b, h) + boff + n * 2048 + k * 1024); } while (0)
; #define PG8_MMA(ai, bj, At, Bt) do { __builtin_amdgcn_s_setprio(1); _Pragma("unroll") for (int m = 0; m < 4; ++m) _Pragma("unroll") for (int n = 0; n < 2; ++n) _Pragma("unroll") for (int k = 0; k < 2; ++k) \
;     acc[ai][bj][m][n] = __builtin_amdgcn_mfma_f32_16x16x32_bf16(Bt[n][k], At[m][k], acc[ai][bj][m][n], 0, 0, 0); __builtin_amdgcn_s_setprio(0); } while (0)
; #define PG8_WAIT_V(n) asm volatile("s_waitcnt vmcnt(" #n ")" ::: "memory")
; #define PG8_WAIT_L(n) asm volatile("s_waitcnt lgkmcnt(" #n ")" ::: "memory")
; #define PG8_BAR __builtin_amdgcn_s_barrier()
; #define PG8_SCHED __builtin_amdgcn_sched_barrier(0)
; template <class Epi, class Sched>
; DI void gemm_phase(LAS unsigned char* lds, const Gemm g, const Sched& S, const Epi& E) {
;     ...
;       PG8_LDB(B0, 0, 0); PG8_SCHED; PG8_LDA(At, 0, 0); PG8_STAGE(PG8_SA(1, 1), a1 + hstep, voffA);
;       PG8_WAIT_L(8); PG8_BAR; PG8_WAIT_L(0); PG8_MMA(0, 0, At, B0); PG8_BAR; PG8_SCHED;
;       PG8_LDB(B1, 0, 1); PG8_STAGE(PG8_SB(0, 0), b2, voffB);
;       PG8_BAR; PG8_WAIT_L(0); PG8_MMA(0, 1, At, B1); PG8_BAR;
;       PG8_LDA(At, 0, 1); PG8_STAGE(PG8_SA(0, 0), a2, voffA);
;       PG8_BAR; PG8_WAIT_L(0); PG8_MMA(1, 0, At, B0); PG8_BAR; PG8_SCHED;
;       PG8_STAGE(PG8_SB(0, 1), b2 + hstep, voffB);
;       PG8_WAIT_V(6); PG8_BAR; PG8_MMA(1, 1, At, B1); PG8_BAR;
.LBB0_689:
	s_add_u32 s22, s20, 0xfffc0080
	s_addc_u32 s23, s21, -1
	s_add_i32 s42, 0, 0x10000
	ds_read_b128 v[128:131], v222
	ds_read_b128 v[132:135], v222 offset:1024
	ds_read_b128 v[150:153], v222 offset:2048
	ds_read_b128 v[154:157], v222 offset:3072
	s_cmp_eq_u32 s41, 12
	s_cselect_b32 s29, s13, s23
	s_cselect_b32 s28, s37, s22
	s_cselect_b32 s23, s15, s40
	s_cselect_b32 s22, s38, s39
	s_add_i32 m0, s56, 0xc000
	ds_read_b128 v[158:161], v197
	ds_read_b128 v[162:165], v197 offset:1024
	ds_read_b128 v[166:169], v197 offset:2048
	ds_read_b128 v[170:173], v197 offset:3072
	ds_read_b128 v[174:177], v197 offset:4096
	ds_read_b128 v[178:181], v197 offset:5120
	ds_read_b128 v[198:201], v197 offset:6144
	ds_read_b128 v[202:205], v197 offset:7168
	global_load_lds_dwordx4 v146, s[20:21]
	s_add_i32 m0, s56, 0xe000
	s_nop 0
	global_load_lds_dwordx4 v148, s[20:21]
	s_waitcnt lgkmcnt(8)
	s_barrier
	s_waitcnt lgkmcnt(0)
	v_mfma_f32_16x16x32_bf16 v[124:127], v[128:131], v[158:161], v[124:127]
	v_mfma_f32_16x16x32_bf16 v[120:123], v[150:153], v[158:161], v[120:123]
	v_mfma_f32_16x16x32_bf16 v[108:111], v[128:131], v[166:169], v[108:111]
	v_mfma_f32_16x16x32_bf16 v[104:107], v[150:153], v[166:169], v[104:107]
	v_mfma_f32_16x16x32_bf16 v[92:95], v[128:131], v[174:177], v[92:95]
	v_mfma_f32_16x16x32_bf16 v[88:91], v[150:153], v[174:177], v[88:91]
	v_mfma_f32_16x16x32_bf16 v[76:79], v[128:131], v[198:201], v[76:79]
	v_mfma_f32_16x16x32_bf16 v[72:75], v[150:153], v[198:201], v[72:75]
	v_mfma_f32_16x16x32_bf16 v[124:127], v[132:135], v[162:165], v[124:127]
	v_mfma_f32_16x16x32_bf16 v[120:123], v[154:157], v[162:165], v[120:123]
	v_mfma_f32_16x16x32_bf16 v[108:111], v[132:135], v[170:173], v[108:111]
	v_mfma_f32_16x16x32_bf16 v[104:107], v[154:157], v[170:173], v[104:107]
	v_mfma_f32_16x16x32_bf16 v[92:95], v[132:135], v[178:181], v[92:95]
	v_mfma_f32_16x16x32_bf16 v[88:91], v[154:157], v[178:181], v[88:91]
	v_mfma_f32_16x16x32_bf16 v[76:79], v[132:135], v[202:205], v[76:79]
	v_mfma_f32_16x16x32_bf16 v[72:75], v[154:157], v[202:205], v[72:75]
	s_barrier
	s_add_i32 s44, 0, 0x14000
	s_add_i32 s42, s42, s52
	s_add_u32 vcc_lo, s22, s0
	s_addc_u32 vcc_hi, s23, s1
	s_mov_b32 m0, s42
	ds_read_b128 v[206:209], v223
	ds_read_b128 v[210:213], v223 offset:1024
	ds_read_b128 v[214:217], v223 offset:2048
	ds_read_b128 v[218:221], v223 offset:3072
	global_load_lds_dwordx4 v140, s[22:23]
	s_add_i32 m0, s42, 0x2000
	s_nop 0
	global_load_lds_dwordx4 v136, s[22:23]
	s_barrier
	s_waitcnt lgkmcnt(0)
	v_mfma_f32_16x16x32_bf16 v[116:119], v[206:209], v[158:161], v[116:119]
	v_mfma_f32_16x16x32_bf16 v[112:115], v[214:217], v[158:161], v[112:115]
	v_mfma_f32_16x16x32_bf16 v[100:103], v[206:209], v[166:169], v[100:103]
	v_mfma_f32_16x16x32_bf16 v[96:99], v[214:217], v[166:169], v[96:99]
	v_mfma_f32_16x16x32_bf16 v[84:87], v[206:209], v[174:177], v[84:87]
	v_mfma_f32_16x16x32_bf16 v[80:83], v[214:217], v[174:177], v[80:83]
	v_mfma_f32_16x16x32_bf16 v[68:71], v[206:209], v[198:201], v[68:71]
	v_mfma_f32_16x16x32_bf16 v[64:67], v[214:217], v[198:201], v[64:67]
	v_mfma_f32_16x16x32_bf16 v[116:119], v[210:213], v[162:165], v[116:119]
	v_mfma_f32_16x16x32_bf16 v[112:115], v[218:221], v[162:165], v[112:115]
	v_mfma_f32_16x16x32_bf16 v[100:103], v[210:213], v[170:173], v[100:103]
	v_mfma_f32_16x16x32_bf16 v[96:99], v[218:221], v[170:173], v[96:99]
	v_mfma_f32_16x16x32_bf16 v[84:87], v[210:213], v[178:181], v[84:87]
	v_mfma_f32_16x16x32_bf16 v[80:83], v[218:221], v[178:181], v[80:83]
	v_mfma_f32_16x16x32_bf16 v[68:71], v[210:213], v[202:205], v[68:71]
	v_mfma_f32_16x16x32_bf16 v[64:67], v[218:221], v[202:205], v[64:67]
	s_mov_b32 m0, s56
	s_add_u32 s100, s28, s0
	s_addc_u32 s101, s29, s1
	s_barrier
	ds_read_b128 v[158:161], v197 offset:16384
	ds_read_b128 v[162:165], v197 offset:17408
	ds_read_b128 v[166:169], v197 offset:18432
	ds_read_b128 v[170:173], v197 offset:19456
	ds_read_b128 v[174:177], v197 offset:20480
	ds_read_b128 v[178:181], v197 offset:21504
	ds_read_b128 v[198:201], v197 offset:22528
	ds_read_b128 v[202:205], v197 offset:23552
	global_load_lds_dwordx4 v142, s[28:29]
	s_mov_b32 m0, s57
	s_nop 0
	global_load_lds_dwordx4 v138, s[28:29]
	s_barrier
	s_waitcnt lgkmcnt(0)
	v_mfma_f32_16x16x32_bf16 v[60:63], v[128:131], v[158:161], v[60:63]
	v_mfma_f32_16x16x32_bf16 v[56:59], v[150:153], v[158:161], v[56:59]
	v_mfma_f32_16x16x32_bf16 v[44:47], v[128:131], v[166:169], v[44:47]
	v_mfma_f32_16x16x32_bf16 v[40:43], v[150:153], v[166:169], v[40:43]
	v_mfma_f32_16x16x32_bf16 v[28:31], v[128:131], v[174:177], v[28:31]
	v_mfma_f32_16x16x32_bf16 v[24:27], v[150:153], v[174:177], v[24:27]
	v_mfma_f32_16x16x32_bf16 v[12:15], v[128:131], v[198:201], v[12:15]
	v_mfma_f32_16x16x32_bf16 v[8:11], v[150:153], v[198:201], v[8:11]
	v_mfma_f32_16x16x32_bf16 v[60:63], v[132:135], v[162:165], v[60:63]
	v_mfma_f32_16x16x32_bf16 v[56:59], v[154:157], v[162:165], v[56:59]
	v_mfma_f32_16x16x32_bf16 v[44:47], v[132:135], v[170:173], v[44:47]
	v_mfma_f32_16x16x32_bf16 v[40:43], v[154:157], v[170:173], v[40:43]
	v_mfma_f32_16x16x32_bf16 v[28:31], v[132:135], v[178:181], v[28:31]
	v_mfma_f32_16x16x32_bf16 v[24:27], v[154:157], v[178:181], v[24:27]
	v_mfma_f32_16x16x32_bf16 v[12:15], v[132:135], v[202:205], v[12:15]
	v_mfma_f32_16x16x32_bf16 v[8:11], v[154:157], v[202:205], v[8:11]
	s_barrier
	s_add_u32 s42, s22, 0x40000
	s_addc_u32 s43, s23, 0
	s_add_i32 s44, s44, s52
	s_mov_b32 m0, s44
	s_nop 0
	global_load_lds_dwordx4 v140, s[42:43]
	s_add_i32 m0, s44, 0x2000
	s_nop 0
	global_load_lds_dwordx4 v136, s[42:43]
	s_waitcnt vmcnt(6)
	s_barrier
; #define PG8_STAGE(bufoff, gbase, voff) do { _Pragma("unroll") for (int _i = 0; _i < 2; ++_i) \
;     __builtin_amdgcn_global_load_lds((const unsigned*)((const char*)(gbase) + (voff)[_i]), (LAS unsigned*)(lds + (bufoff) + ldsw + _i * 8192), 16, 0, 0); } while (0)
; #define PG8_LDA(dst, b, h) do { _Pragma("unroll") for (int m = 0; m < 4; ++m) _Pragma("unroll") for (int k = 0; k < 2; ++k) dst[m][k] = *(const LAS bf16x8*)(lds + PG8_SA(b, h) + aoff + m * 2048 + k * 1024); } while (0)
; #define PG8_LDB(dst, b, h) do { _Pragma("unroll") for (int n = 0; n < 2; ++n) _Pragma("unroll") for (int k = 0; k < 2; ++k) dst[n][k] = *(const LAS bf16x8*)(lds + PG8_SB(b, h) + boff + n * 2048 + k * 1024); } while (0)
; #define PG8_MMA(ai, bj, At, Bt) do { __builtin_amdgcn_s_setprio(1); _Pragma("unroll") for (int m = 0; m < 4; ++m) _Pragma("unroll") for (int n = 0; n < 2; ++n) _Pragma("unroll") for (int k = 0; k < 2; ++k) \
;     acc[ai][bj][m][n] = __builtin_amdgcn_mfma_f32_16x16x32_bf16(Bt[n][k], At[m][k], acc[ai][bj][m][n], 0, 0, 0); __builtin_amdgcn_s_setprio(0); } while (0)
; #define PG8_WAIT_V(n) asm volatile("s_waitcnt vmcnt(" #n ")" ::: "memory")
; #define PG8_WAIT_L(n) asm volatile("s_waitcnt lgkmcnt(" #n ")" ::: "memory")
; #define PG8_BAR __builtin_amdgcn_s_barrier()
; #define PG8_SCHED __builtin_amdgcn_sched_barrier(0)
; template <class Epi, class Sched>
; DI void gemm_phase(LAS unsigned char* lds, const Gemm g, const Sched& S, const Epi& E) {
;     ...
;       PG8_WAIT_V(6); PG8_BAR; PG8_MMA(1, 1, At, B1); PG8_BAR;
;       PG8_LDB(B0, 1, 0); PG8_SCHED; PG8_LDA(At, 1, 0); PG8_STAGE(PG8_SA(0, 1), a2 + hstep, voffA);
;       PG8_WAIT_L(8); PG8_BAR; PG8_WAIT_L(0); PG8_MMA(0, 0, At, B0); PG8_BAR; PG8_SCHED;
;       PG8_LDB(B1, 1, 1); PG8_STAGE(PG8_SB(1, 0), b3, voffB);
;       PG8_BAR; PG8_WAIT_L(0); PG8_MMA(0, 1, At, B1); PG8_BAR;
;       PG8_LDA(At, 1, 1); PG8_STAGE(PG8_SA(1, 0), a3, voffA);
;       PG8_BAR; PG8_WAIT_L(0); PG8_MMA(1, 0, At, B0); PG8_BAR; PG8_SCHED;
	v_mfma_f32_16x16x32_bf16 v[52:55], v[206:209], v[158:161], v[52:55]
	v_mfma_f32_16x16x32_bf16 v[48:51], v[214:217], v[158:161], v[48:51]
	v_mfma_f32_16x16x32_bf16 v[36:39], v[206:209], v[166:169], v[36:39]
	v_mfma_f32_16x16x32_bf16 v[32:35], v[214:217], v[166:169], v[32:35]
	v_mfma_f32_16x16x32_bf16 v[20:23], v[206:209], v[174:177], v[20:23]
	v_mfma_f32_16x16x32_bf16 v[16:19], v[214:217], v[174:177], v[16:19]
	v_mfma_f32_16x16x32_bf16 v[4:7], v[206:209], v[198:201], v[4:7]
	v_mfma_f32_16x16x32_bf16 v[0:3], v[214:217], v[198:201], v[0:3]
	v_mfma_f32_16x16x32_bf16 v[52:55], v[210:213], v[162:165], v[52:55]
	v_mfma_f32_16x16x32_bf16 v[48:51], v[218:221], v[162:165], v[48:51]
	v_mfma_f32_16x16x32_bf16 v[36:39], v[210:213], v[170:173], v[36:39]
	v_mfma_f32_16x16x32_bf16 v[32:35], v[218:221], v[170:173], v[32:35]
	v_mfma_f32_16x16x32_bf16 v[20:23], v[210:213], v[178:181], v[20:23]
	v_mfma_f32_16x16x32_bf16 v[16:19], v[218:221], v[178:181], v[16:19]
	v_mfma_f32_16x16x32_bf16 v[4:7], v[210:213], v[202:205], v[4:7]
	v_mfma_f32_16x16x32_bf16 v[0:3], v[218:221], v[202:205], v[0:3]
	s_add_i32 s42, 0, 0x18000
	s_barrier
	ds_read_b128 v[128:131], v224
	ds_read_b128 v[132:135], v224 offset:1024
	ds_read_b128 v[150:153], v224 offset:2048
	ds_read_b128 v[154:157], v224 offset:3072
	s_add_u32 s28, s28, 0x40000
	s_addc_u32 s29, s29, 0
	s_mov_b32 m0, s58
	ds_read_b128 v[158:161], v197 offset:32768
	ds_read_b128 v[162:165], v197 offset:33792
	ds_read_b128 v[166:169], v197 offset:34816
	ds_read_b128 v[170:173], v197 offset:35840
	ds_read_b128 v[174:177], v197 offset:36864
	ds_read_b128 v[178:181], v197 offset:37888
	ds_read_b128 v[198:201], v197 offset:38912
	ds_read_b128 v[202:205], v197 offset:39936
	global_load_lds_dwordx4 v142, s[28:29]
	s_mov_b32 m0, s59
	s_nop 0
	global_load_lds_dwordx4 v138, s[28:29]
	s_waitcnt lgkmcnt(8)
	s_barrier
	s_waitcnt lgkmcnt(0)
	v_mfma_f32_16x16x32_bf16 v[124:127], v[128:131], v[158:161], v[124:127]
	v_mfma_f32_16x16x32_bf16 v[120:123], v[150:153], v[158:161], v[120:123]
	v_mfma_f32_16x16x32_bf16 v[108:111], v[128:131], v[166:169], v[108:111]
	v_mfma_f32_16x16x32_bf16 v[104:107], v[150:153], v[166:169], v[104:107]
	v_mfma_f32_16x16x32_bf16 v[92:95], v[128:131], v[174:177], v[92:95]
	v_mfma_f32_16x16x32_bf16 v[88:91], v[150:153], v[174:177], v[88:91]
	v_mfma_f32_16x16x32_bf16 v[76:79], v[128:131], v[198:201], v[76:79]
	v_mfma_f32_16x16x32_bf16 v[72:75], v[150:153], v[198:201], v[72:75]
	v_mfma_f32_16x16x32_bf16 v[124:127], v[132:135], v[162:165], v[124:127]
	v_mfma_f32_16x16x32_bf16 v[120:123], v[154:157], v[162:165], v[120:123]
	v_mfma_f32_16x16x32_bf16 v[108:111], v[132:135], v[170:173], v[108:111]
	v_mfma_f32_16x16x32_bf16 v[104:107], v[154:157], v[170:173], v[104:107]
	v_mfma_f32_16x16x32_bf16 v[92:95], v[132:135], v[178:181], v[92:95]
	v_mfma_f32_16x16x32_bf16 v[88:91], v[154:157], v[178:181], v[88:91]
	v_mfma_f32_16x16x32_bf16 v[76:79], v[132:135], v[202:205], v[76:79]
	v_mfma_f32_16x16x32_bf16 v[72:75], v[154:157], v[202:205], v[72:75]
	s_barrier
	s_add_i32 s28, 0, 0x1c000
	s_add_i32 s29, s42, s52
	s_mov_b32 m0, s29
	ds_read_b128 v[206:209], v225
	ds_read_b128 v[210:213], v225 offset:1024
	ds_read_b128 v[214:217], v225 offset:2048
	ds_read_b128 v[218:221], v225 offset:3072
	global_load_lds_dwordx4 v140, vcc
	s_add_i32 m0, s29, 0x2000
	s_nop 0
	global_load_lds_dwordx4 v136, vcc
	s_barrier
	s_waitcnt lgkmcnt(0)
	v_mfma_f32_16x16x32_bf16 v[116:119], v[206:209], v[158:161], v[116:119]
	v_mfma_f32_16x16x32_bf16 v[112:115], v[214:217], v[158:161], v[112:115]
	v_mfma_f32_16x16x32_bf16 v[100:103], v[206:209], v[166:169], v[100:103]
	v_mfma_f32_16x16x32_bf16 v[96:99], v[214:217], v[166:169], v[96:99]
	v_mfma_f32_16x16x32_bf16 v[84:87], v[206:209], v[174:177], v[84:87]
	v_mfma_f32_16x16x32_bf16 v[80:83], v[214:217], v[174:177], v[80:83]
	v_mfma_f32_16x16x32_bf16 v[68:71], v[206:209], v[198:201], v[68:71]
	v_mfma_f32_16x16x32_bf16 v[64:67], v[214:217], v[198:201], v[64:67]
	v_mfma_f32_16x16x32_bf16 v[116:119], v[210:213], v[162:165], v[116:119]
	v_mfma_f32_16x16x32_bf16 v[112:115], v[218:221], v[162:165], v[112:115]
	v_mfma_f32_16x16x32_bf16 v[100:103], v[210:213], v[170:173], v[100:103]
	v_mfma_f32_16x16x32_bf16 v[96:99], v[218:221], v[170:173], v[96:99]
	v_mfma_f32_16x16x32_bf16 v[84:87], v[210:213], v[178:181], v[84:87]
	v_mfma_f32_16x16x32_bf16 v[80:83], v[218:221], v[178:181], v[80:83]
	v_mfma_f32_16x16x32_bf16 v[68:71], v[210:213], v[202:205], v[68:71]
	v_mfma_f32_16x16x32_bf16 v[64:67], v[218:221], v[202:205], v[64:67]
	s_mov_b32 m0, s62
	s_barrier
	ds_read_b128 v[158:161], v197 offset:49152
	ds_read_b128 v[162:165], v197 offset:50176
	ds_read_b128 v[166:169], v197 offset:51200
	ds_read_b128 v[170:173], v197 offset:52224
	ds_read_b128 v[174:177], v197 offset:53248
	ds_read_b128 v[178:181], v197 offset:54272
	ds_read_b128 v[198:201], v197 offset:55296
	ds_read_b128 v[202:205], v197 offset:56320
	global_load_lds_dwordx4 v142, s[100:101]
	s_mov_b32 m0, s63
	s_nop 0
	global_load_lds_dwordx4 v138, s[100:101]
	s_barrier
; #define PG8_STAGE(bufoff, gbase, voff) do { _Pragma("unroll") for (int _i = 0; _i < 2; ++_i) \
;     __builtin_amdgcn_global_load_lds((const unsigned*)((const char*)(gbase) + (voff)[_i]), (LAS unsigned*)(lds + (bufoff) + ldsw + _i * 8192), 16, 0, 0); } while (0)
; #define PG8_LDA(dst, b, h) do { _Pragma("unroll") for (int m = 0; m < 4; ++m) _Pragma("unroll") for (int k = 0; k < 2; ++k) dst[m][k] = *(const LAS bf16x8*)(lds + PG8_SA(b, h) + aoff + m * 2048 + k * 1024); } while (0)
; #define PG8_WAIT_V(n) asm volatile("s_waitcnt vmcnt(" #n ")" ::: "memory")
; #define PG8_WAIT_L(n) asm volatile("s_waitcnt lgkmcnt(" #n ")" ::: "memory")
; #define PG8_BAR __builtin_amdgcn_s_barrier()
; #define PG8_SCHED __builtin_amdgcn_sched_barrier(0)
; template <class Epi, class Sched>
; DI void gemm_phase(LAS unsigned char* lds, const Gemm g, const Sched& S, const Epi& E) {
;     ...
;       PG8_LDA(At, 1, 1); PG8_STAGE(PG8_SA(1, 0), a3, voffA);
;       PG8_BAR; PG8_WAIT_L(0); PG8_MMA(1, 0, At, B0); PG8_BAR; PG8_SCHED;
;       PG8_STAGE(PG8_SB(1, 1), b3 + hstep, voffB);
;       PG8_WAIT_V(6); PG8_BAR; PG8_MMA(1, 1, At, B1); PG8_BAR;
;   DI void operator()(const f32x4 (&acc)[2][2][4][2], const pg8::Unit& u, int wr, int wc, int fr_, int fq_) const {
;     ...
;             if (EPI == EPI_ABIN) {
;               if (n == 0) {
;                 const int gb = u.pn * 256 + bj * 128 + wc * 32; const int f8 = gb + 8 * fq;
;                 const f32x4 v1 = acc[ai][bj][m][1];
;                 if (gb < 384) st_bf8((u16*)(big + E_CQ) + (size_t)token * 384 + f8, v, v1, rinv);
;                 else if (gb < 640) st_bf8((u16*)(big + E_CKV) + (size_t)token * 256 + (f8 - 384), v, v1, rinv);
;                 else if (gb < 672) {
;                   f32x4 a0 = v, a1 = v1;
;                   rope_perm(a0, a1, fq, t_ & 63, tcos, tsin, token & (S_ - 1));
;                   st_bf8((u16*)(big + E_KPE) + (size_t)token * 32 + 8 * fq, a0, a1, rinv);
;                 }
;                 else if (gb < 1184) st_bf8((u16*)(big + E_QNA) + (size_t)token * 512 + (f8 - 672), v, v1, rinv * (0.125f * LOG2E));
;                 else if (gb < 1696) st_bf8((u16*)(big + E_KNA) + (size_t)token * 512 + (f8 - 1184), v, v1, rinv);
;                 else if (gb < 2208) st_bf8((u16*)(big + E_VNAT) + (size_t)token * 512 + (f8 - 1696), v, v1, rinv);
	s_waitcnt lgkmcnt(0)
	v_mfma_f32_16x16x32_bf16 v[60:63], v[128:131], v[158:161], v[60:63]
	v_mfma_f32_16x16x32_bf16 v[56:59], v[150:153], v[158:161], v[56:59]
	v_mfma_f32_16x16x32_bf16 v[44:47], v[128:131], v[166:169], v[44:47]
	v_mfma_f32_16x16x32_bf16 v[40:43], v[150:153], v[166:169], v[40:43]
	v_mfma_f32_16x16x32_bf16 v[28:31], v[128:131], v[174:177], v[28:31]
	v_mfma_f32_16x16x32_bf16 v[24:27], v[150:153], v[174:177], v[24:27]
	v_mfma_f32_16x16x32_bf16 v[12:15], v[128:131], v[198:201], v[12:15]
	v_mfma_f32_16x16x32_bf16 v[8:11], v[150:153], v[198:201], v[8:11]
	v_mfma_f32_16x16x32_bf16 v[60:63], v[132:135], v[162:165], v[60:63]
	v_mfma_f32_16x16x32_bf16 v[56:59], v[154:157], v[162:165], v[56:59]
	v_mfma_f32_16x16x32_bf16 v[44:47], v[132:135], v[170:173], v[44:47]
	v_mfma_f32_16x16x32_bf16 v[40:43], v[154:157], v[170:173], v[40:43]
	v_mfma_f32_16x16x32_bf16 v[28:31], v[132:135], v[178:181], v[28:31]
	v_mfma_f32_16x16x32_bf16 v[24:27], v[154:157], v[178:181], v[24:27]
	v_mfma_f32_16x16x32_bf16 v[12:15], v[132:135], v[202:205], v[12:15]
	v_mfma_f32_16x16x32_bf16 v[8:11], v[154:157], v[202:205], v[8:11]
	s_barrier
	s_add_u32 s22, s22, 0x40080
	s_addc_u32 s23, s23, 0
	s_add_i32 s28, s28, s52
	s_mov_b32 m0, s28
	s_nop 0
	global_load_lds_dwordx4 v140, s[22:23]
	s_add_i32 m0, s28, 0x2000
	s_nop 0
	global_load_lds_dwordx4 v136, s[22:23]
	s_waitcnt vmcnt(6)
	s_barrier
	v_mfma_f32_16x16x32_bf16 v[52:55], v[206:209], v[158:161], v[52:55]
	v_mfma_f32_16x16x32_bf16 v[48:51], v[214:217], v[158:161], v[48:51]
	v_mfma_f32_16x16x32_bf16 v[36:39], v[206:209], v[166:169], v[36:39]
	v_mfma_f32_16x16x32_bf16 v[32:35], v[214:217], v[166:169], v[32:35]
	v_mfma_f32_16x16x32_bf16 v[20:23], v[206:209], v[174:177], v[20:23]
	v_mfma_f32_16x16x32_bf16 v[16:19], v[214:217], v[174:177], v[16:19]
	v_mfma_f32_16x16x32_bf16 v[4:7], v[206:209], v[198:201], v[4:7]
	v_mfma_f32_16x16x32_bf16 v[0:3], v[214:217], v[198:201], v[0:3]
	v_mfma_f32_16x16x32_bf16 v[52:55], v[210:213], v[162:165], v[52:55]
	v_mfma_f32_16x16x32_bf16 v[48:51], v[218:221], v[162:165], v[48:51]
	v_mfma_f32_16x16x32_bf16 v[36:39], v[210:213], v[170:173], v[36:39]
	v_mfma_f32_16x16x32_bf16 v[32:35], v[218:221], v[170:173], v[32:35]
	v_mfma_f32_16x16x32_bf16 v[20:23], v[210:213], v[178:181], v[20:23]
	v_mfma_f32_16x16x32_bf16 v[16:19], v[218:221], v[178:181], v[16:19]
	v_mfma_f32_16x16x32_bf16 v[4:7], v[210:213], v[202:205], v[4:7]
	v_mfma_f32_16x16x32_bf16 v[0:3], v[218:221], v[202:205], v[0:3]
	s_add_i32 s41, s41, 2
	s_add_u32 s20, s20, 0x100
	s_addc_u32 s21, s21, 0
	s_add_u32 s39, s39, 0x100
	s_addc_u32 s40, s40, 0
	s_cmp_gt_u32 s41, 13
	s_barrier
	s_cbranch_scc0 .LBB0_689
	v_mov_b32_e32 v128, v182
	s_lshl_b32 s20, s34, 10
	v_bfe_u32 v129, v128, 4, 2
	v_and_or_b32 v201, v128, 15, s60
	s_lshl_b32 s13, s35, 8
	v_lshlrev_b32_e32 v128, 2, v128
	s_movk_i32 s21, 0x80
	s_add_i32 s20, s20, 0
	s_lshl_b32 s15, s36, 8
	v_bitop3_b32 v198, v128, s21, v190 bitop3:0x6c
	v_lshl_add_u32 v128, v201, 2, s20
	s_or_b32 s20, s13, s61
	v_add_u32_e32 v200, 0x20000, v128
	s_cmpk_gt_i32 s20, 0x17f
	ds_read_b32 v156, v200
	s_cselect_b64 s[28:29], -1, 0
	s_cmpk_gt_u32 s13, 0x27f
	s_cselect_b64 s[46:47], -1, 0
	s_cmpk_gt_u32 s20, 0x29f
	s_cselect_b64 s[40:41], -1, 0
	s_cmpk_gt_u32 s20, 0x49f
	v_lshlrev_b32_e32 v144, 3, v129
	v_add_u32_e32 v154, s15, v201
	s_cselect_b64 s[34:35], -1, 0
	s_cmpk_gt_u32 s20, 0x69f
	v_ashrrev_i32_e32 v155, 31, v154
	v_lshlrev_b32_e32 v128, 4, v154
	v_or_b32_e32 v150, s20, v144
	s_cselect_b64 s[22:23], -1, 0
	s_cmpk_lt_u32 s20, 0x8a0
	v_and_b32_e32 v199, 8, v144
	v_cmp_lt_u32_e64 s[92:93], 1, v129
	v_lshlrev_b64 v[164:165], 10, v[154:155]
	s_waitcnt lgkmcnt(0)
	v_mul_f32_e32 v162, 0x3e38aa3b, v156
	v_and_b32_e32 v157, 0xfcf0, v128
	v_lshlrev_b64 v[160:161], 6, v[154:155]
	v_lshlrev_b64 v[158:159], 9, v[154:155]
	s_cselect_b64 s[20:21], -1, 0
	v_mov_b32_e32 v152, v150
	v_mov_b32_e32 v153, v145
	s_mov_b64 s[36:37], -1
	s_and_b64 vcc, exec, s[28:29]
	s_cbranch_vccz .LBB0_714
	s_and_b64 vcc, exec, s[46:47]
	s_cbranch_vccz .LBB0_711
	s_and_b64 vcc, exec, s[40:41]
	s_cbranch_vccz .LBB0_704
	s_and_b64 vcc, exec, s[34:35]
	s_cbranch_vccz .LBB0_701
	s_and_b64 vcc, exec, s[22:23]
	s_cbranch_vccz .LBB0_698
	s_andn2_b64 vcc, exec, s[20:21]
	s_cbranch_vccnz .LBB0_697
	v_lshl_add_u64 v[128:129], s[2:3], 0, v[164:165]
	v_lshl_add_u64 v[132:133], v[152:153], 1, v[128:129]
	v_mul_f32_e32 v128, v124, v156
	v_mul_f32_e32 v129, v125, v156
	v_mul_f32_e32 v130, v126, v156
	v_mul_f32_e32 v131, v127, v156
	v_cvt_pk_bf16_f32 v128, v128, v129
	v_cvt_pk_bf16_f32 v129, v130, v131
	v_mul_f32_e32 v130, v120, v156
	v_mul_f32_e32 v131, v121, v156
	v_mul_f32_e32 v134, v122, v156
	v_mul_f32_e32 v135, v123, v156
	v_add_co_u32_e32 v132, vcc, 0x69ff000, v132
	v_cvt_pk_bf16_f32 v130, v130, v131
	v_cvt_pk_bf16_f32 v131, v134, v135
	v_addc_co_u32_e32 v133, vcc, 0, v133, vcc
	global_store_dwordx4 v[132:133], v[128:131], off offset:704

;   DI void operator()(const f32x4 (&acc)[2][2][4][2], const pg8::Unit& u, int wr, int wc, int fr_, int fq_) const {
;     ...
;                 else if (gb < 1696) st_bf8((u16*)(big + E_KNA) + (size_t)token * 512 + (f8 - 1184), v, v1, rinv);
.LBB0_698:
	s_andn2_b64 vcc, exec, s[36:37]
	s_cbranch_vccnz .LBB0_700
	v_lshl_add_u64 v[128:129], s[2:3], 0, v[164:165]
	v_lshl_add_u64 v[132:133], v[152:153], 1, v[128:129]
	v_mul_f32_e32 v128, v124, v156
	v_mul_f32_e32 v129, v125, v156
	v_mul_f32_e32 v130, v126, v156
	v_mul_f32_e32 v131, v127, v156
	v_cvt_pk_bf16_f32 v128, v128, v129
	v_cvt_pk_bf16_f32 v129, v130, v131
	v_mul_f32_e32 v130, v120, v156
	v_mul_f32_e32 v131, v121, v156
	v_mul_f32_e32 v134, v122, v156
	v_mul_f32_e32 v135, v123, v156
	v_add_co_u32_e32 v132, vcc, 0x49ff000, v132
	v_cvt_pk_bf16_f32 v130, v130, v131
	v_cvt_pk_bf16_f32 v131, v134, v135
	v_addc_co_u32_e32 v133, vcc, 0, v133, vcc
	global_store_dwordx4 v[132:133], v[128:131], off offset:1728

;   DI void operator()(const f32x4 (&acc)[2][2][4][2], const pg8::Unit& u, int wr, int wc, int fr_, int fq_) const {
;     ...
;                 else if (gb < 1184) st_bf8((u16*)(big + E_QNA) + (size_t)token * 512 + (f8 - 672), v, v1, rinv * (0.125f * LOG2E));
.LBB0_701:
	s_andn2_b64 vcc, exec, s[36:37]
	s_cbranch_vccnz .LBB0_703
	v_lshl_add_u64 v[128:129], s[2:3], 0, v[164:165]
	v_lshl_add_u64 v[132:133], v[152:153], 1, v[128:129]
	v_mul_f32_e32 v128, v124, v162
	v_mul_f32_e32 v129, v125, v162
	v_mul_f32_e32 v130, v126, v162
	v_mul_f32_e32 v131, v127, v162
	v_cvt_pk_bf16_f32 v128, v128, v129
	v_cvt_pk_bf16_f32 v129, v130, v131
	v_mul_f32_e32 v130, v120, v162
	v_mul_f32_e32 v131, v121, v162
	v_mul_f32_e32 v134, v122, v162
	v_mul_f32_e32 v135, v123, v162
	v_add_co_u32_e32 v132, vcc, 0x29ff000, v132
	v_cvt_pk_bf16_f32 v130, v130, v131
	v_cvt_pk_bf16_f32 v131, v134, v135
	v_addc_co_u32_e32 v133, vcc, 0, v133, vcc
	global_store_dwordx4 v[132:133], v[128:131], off offset:2752

; DI void rope_perm(f32x4& a0, f32x4& a1, int fq, int lane, const float* tcos, const float* tsin, int pos) {
;   f32x4 p0, p1;
; #pragma unroll
;   for (int e = 0; e < 4; ++e) { p0[e] = shx(a0[e], 32, lane); p1[e] = shx(a1[e], 32, lane); }
;   const int jb = 8 * (fq & 1);
;   const f32x4 c0 = *(const f32x4*)(tcos + pos * 16 + jb), c1 = *(const f32x4*)(tcos + pos * 16 + jb + 4);
;   const f32x4 s0 = *(const f32x4*)(tsin + pos * 16 + jb), s1 = *(const f32x4*)(tsin + pos * 16 + jb + 4);
;   if (fq < 2) { a0 = a0 * c0 - p0 * s0; a1 = a1 * c1 - p1 * s1; }
;   else        { a0 = a0 * c0 + p0 * s0; a1 = a1 * c1 + p1 * s1; }
; }
;   DI void operator()(const f32x4 (&acc)[2][2][4][2], const pg8::Unit& u, int wr, int wc, int fr_, int fq_) const {
;     ...
;                 else if (gb < 672) {
;                   f32x4 a0 = v, a1 = v1;
;                   rope_perm(a0, a1, fq, t_ & 63, tcos, tsin, token & (S_ - 1));
;                   st_bf8((u16*)(big + E_KPE) + (size_t)token * 32 + 8 * fq, a0, a1, rinv);
.LBB0_704:
	s_andn2_b64 vcc, exec, s[36:37]
	s_cbranch_vccnz .LBB0_710
	v_lshlrev_b32_e32 v132, 2, v157
	v_mov_b32_e32 v133, v145
	v_lshl_add_u64 v[128:129], s[4:5], 0, v[132:133]
	v_lshlrev_b32_e32 v134, 2, v199
	v_mov_b32_e32 v135, v145
	v_lshl_add_u64 v[132:133], s[6:7], 0, v[132:133]
	v_lshl_add_u64 v[166:167], v[128:129], 0, v[134:135]
	v_lshl_add_u64 v[168:169], v[132:133], 0, v[134:135]
	global_load_dwordx4 v[128:131], v[166:167], off
	global_load_dwordx4 v[132:135], v[168:169], off
	global_load_dwordx4 v[202:205], v[168:169], off offset:16
	global_load_dwordx4 v[206:209], v[166:167], off offset:16
	ds_bpermute_b32 v168, v198, v124
	ds_bpermute_b32 v172, v198, v120
	ds_bpermute_b32 v169, v198, v125
	ds_bpermute_b32 v173, v198, v121
	ds_bpermute_b32 v176, v198, v126
	ds_bpermute_b32 v180, v198, v122
	ds_bpermute_b32 v177, v198, v127
	ds_bpermute_b32 v181, v198, v123
	s_waitcnt vmcnt(0) lgkmcnt(0)
	v_mul_f32_e32 v174, v132, v168
	v_mul_f32_e32 v175, v133, v169
	v_mul_f32_e32 v166, v126, v130
	v_mul_f32_e32 v167, v127, v131
	v_mul_f32_e32 v170, v124, v128
	v_mul_f32_e32 v171, v125, v129
	v_mul_f32_e32 v178, v134, v176
	v_mul_f32_e32 v179, v135, v177
	v_mul_f32_e32 v168, v202, v172
	v_mul_f32_e32 v169, v203, v173
	v_mul_f32_e32 v172, v204, v180
	v_mul_f32_e32 v173, v205, v181
	v_mul_f32_e32 v176, v122, v208
	v_mul_f32_e32 v177, v123, v209
	v_mul_f32_e32 v180, v120, v206
	v_mul_f32_e32 v181, v121, v207
	s_and_saveexec_b64 s[36:37], s[92:93]
	s_xor_b64 s[36:37], exec, s[36:37]
	v_add_f32_e32 v130, v166, v178
	v_add_f32_e32 v131, v167, v179
	v_add_f32_e32 v128, v170, v174
	v_add_f32_e32 v129, v171, v175
	v_add_f32_e32 v134, v176, v172
	v_add_f32_e32 v135, v177, v173
	v_add_f32_e32 v132, v180, v168
	v_add_f32_e32 v133, v181, v169
	s_andn2_saveexec_b64 s[36:37], s[36:37]
	v_sub_f32_e32 v131, v167, v179
	v_sub_f32_e32 v130, v166, v178
	v_sub_f32_e32 v129, v171, v175
	v_sub_f32_e32 v128, v170, v174
	v_sub_f32_e32 v135, v177, v173
	v_sub_f32_e32 v134, v176, v172
	v_sub_f32_e32 v133, v181, v169
	v_sub_f32_e32 v132, v180, v168
	s_or_b64 exec, exec, s[36:37]
	v_mul_f32_e32 v128, v156, v128
	v_mul_f32_e32 v129, v156, v129
	v_mul_f32_e32 v130, v156, v130
	v_mul_f32_e32 v131, v156, v131
	v_lshl_add_u64 v[166:167], s[10:11], 0, v[160:161]
	v_lshlrev_b32_e32 v168, 1, v144
	v_mov_b32_e32 v169, v145
	v_cvt_pk_bf16_f32 v128, v128, v129
	v_cvt_pk_bf16_f32 v129, v130, v131
	v_mul_f32_e32 v130, v156, v132
	v_mul_f32_e32 v131, v156, v133
	v_mul_f32_e32 v132, v156, v134
	v_mul_f32_e32 v133, v156, v135
	v_lshl_add_u64 v[166:167], v[166:167], 0, v[168:169]
	v_cvt_pk_bf16_f32 v130, v130, v131
	v_cvt_pk_bf16_f32 v131, v132, v133
	global_store_dwordx4 v[166:167], v[128:131], off

;   DI void operator()(const f32x4 (&acc)[2][2][4][2], const pg8::Unit& u, int wr, int wc, int fr_, int fq_) const {
;     ...
;                 else if (gb < 640) st_bf8((u16*)(big + E_CKV) + (size_t)token * 256 + (f8 - 384), v, v1, rinv);
.LBB0_711:
	s_andn2_b64 vcc, exec, s[36:37]
	s_cbranch_vccnz .LBB0_713
	v_lshl_add_u64 v[128:129], s[2:3], 0, v[158:159]
	v_lshl_add_u64 v[132:133], v[152:153], 1, v[128:129]
	v_mul_f32_e32 v128, v124, v156
	v_mul_f32_e32 v129, v125, v156
	v_mul_f32_e32 v130, v126, v156
	v_mul_f32_e32 v131, v127, v156
	v_cvt_pk_bf16_f32 v128, v128, v129
	v_cvt_pk_bf16_f32 v129, v130, v131
	v_mul_f32_e32 v130, v120, v156
	v_mul_f32_e32 v131, v121, v156
	v_mul_f32_e32 v134, v122, v156
	v_mul_f32_e32 v135, v123, v156
	v_add_co_u32_e32 v132, vcc, 0x17ff000, v132
	v_cvt_pk_bf16_f32 v130, v130, v131
	v_cvt_pk_bf16_f32 v131, v134, v135
	v_addc_co_u32_e32 v133, vcc, 0, v133, vcc
	global_store_dwordx4 v[132:133], v[128:131], off offset:3328

;   DI void operator()(const f32x4 (&acc)[2][2][4][2], const pg8::Unit& u, int wr, int wc, int fr_, int fq_) const {
;     ...
;               if (n == 0) {
;                 const int gb = u.pn * 256 + bj * 128 + wc * 32; const int f8 = gb + 8 * fq;
;                 const f32x4 v1 = acc[ai][bj][m][1];
;                 if (gb < 384) st_bf8((u16*)(big + E_CQ) + (size_t)token * 384 + f8, v, v1, rinv);
;                 else if (gb < 640) st_bf8((u16*)(big + E_CKV) + (size_t)token * 256 + (f8 - 384), v, v1, rinv);
;                 else if (gb < 672) {
;                   f32x4 a0 = v, a1 = v1;
;                   rope_perm(a0, a1, fq, t_ & 63, tcos, tsin, token & (S_ - 1));
;                   st_bf8((u16*)(big + E_KPE) + (size_t)token * 32 + 8 * fq, a0, a1, rinv);
;                 }
;                 else if (gb < 1184) st_bf8((u16*)(big + E_QNA) + (size_t)token * 512 + (f8 - 672), v, v1, rinv * (0.125f * LOG2E));
;                 else if (gb < 1696) st_bf8((u16*)(big + E_KNA) + (size_t)token * 512 + (f8 - 1184), v, v1, rinv);
;                 else if (gb < 2208) st_bf8((u16*)(big + E_VNAT) + (size_t)token * 512 + (f8 - 1696), v, v1, rinv);
.LBB0_714:
	s_movk_i32 s38, 0x300
	v_mad_i64_i32 v[128:129], s[38:39], v154, s38, 0
	v_ashrrev_i32_e32 v151, 31, v150
	s_andn2_b64 vcc, exec, s[36:37]
	v_lshl_add_u64 v[128:129], s[2:3], 0, v[128:129]
	s_cbranch_vccnz .LBB0_716
	v_mul_f32_e32 v124, v124, v156
	v_mul_f32_e32 v125, v125, v156
	v_mul_f32_e32 v126, v126, v156
	v_mul_f32_e32 v127, v127, v156
	v_mul_f32_e32 v120, v120, v156
	v_mul_f32_e32 v121, v121, v156
	v_cvt_pk_bf16_f32 v124, v124, v125
	v_cvt_pk_bf16_f32 v125, v126, v127
	v_cvt_pk_bf16_f32 v126, v120, v121
	v_mul_f32_e32 v120, v122, v156
	v_mul_f32_e32 v121, v123, v156
	v_lshl_add_u64 v[130:131], v[150:151], 1, v[128:129]
	v_cvt_pk_bf16_f32 v127, v120, v121
	global_store_dwordx4 v[130:131], v[124:127], off
.LBB0_716:
	s_or_b32 s36, s13, 0x80
	s_or_b32 s50, s36, s61
	s_cmpk_gt_i32 s50, 0x17f
	s_cselect_b64 s[48:49], -1, 0
	s_cmpk_gt_u32 s36, 0x27f
	s_cselect_b64 s[66:67], -1, 0
	s_cmpk_gt_u32 s50, 0x29f
	s_cselect_b64 s[44:45], -1, 0
	s_cmpk_gt_u32 s50, 0x49f
	s_cselect_b64 s[42:43], -1, 0
	s_cmpk_gt_u32 s50, 0x69f
	s_cselect_b64 s[38:39], -1, 0
	s_cmpk_lt_u32 s50, 0x8a0
	v_cndmask_b32_e64 v120, 0, 1, s[66:67]
	s_cselect_b64 s[36:37], -1, 0
	s_cmpk_lt_i32 s50, 0x180
	s_mov_b64 s[50:51], -1
	v_cmp_ne_u32_e64 s[94:95], 1, v120
	s_cbranch_scc1 .LBB0_740
	s_and_b64 vcc, exec, s[94:95]
	s_cbranch_vccnz .LBB0_737
	s_andn2_b64 vcc, exec, s[44:45]
	s_cbranch_vccnz .LBB0_730
	s_andn2_b64 vcc, exec, s[42:43]
	s_cbranch_vccnz .LBB0_727
	s_andn2_b64 vcc, exec, s[38:39]
	s_cbranch_vccnz .LBB0_724
	s_andn2_b64 vcc, exec, s[36:37]
	s_cbranch_vccnz .LBB0_723
	s_add_i32 s50, s13, s61
	v_lshl_add_u64 v[120:121], s[2:3], 0, v[164:165]
	v_add_u32_e32 v122, s50, v144
	v_mov_b32_e32 v123, v145
	v_lshl_add_u64 v[124:125], v[122:123], 1, v[120:121]
	v_mul_f32_e32 v120, v116, v156
	v_mul_f32_e32 v121, v117, v156
	v_mul_f32_e32 v122, v118, v156
	v_mul_f32_e32 v123, v119, v156
	v_cvt_pk_bf16_f32 v120, v120, v121
	v_cvt_pk_bf16_f32 v121, v122, v123
	v_mul_f32_e32 v122, v112, v156
	v_mul_f32_e32 v123, v113, v156
	v_mul_f32_e32 v126, v114, v156
	v_mul_f32_e32 v127, v115, v156
	v_add_co_u32_e32 v124, vcc, 0x69ff000, v124
	v_cvt_pk_bf16_f32 v122, v122, v123
	v_cvt_pk_bf16_f32 v123, v126, v127
	v_addc_co_u32_e32 v125, vcc, 0, v125, vcc
	global_store_dwordx4 v[124:125], v[120:123], off offset:960

;   DI void operator()(const f32x4 (&acc)[2][2][4][2], const pg8::Unit& u, int wr, int wc, int fr_, int fq_) const {
;     ...
;                 else if (gb < 1696) st_bf8((u16*)(big + E_KNA) + (size_t)token * 512 + (f8 - 1184), v, v1, rinv);
.LBB0_724:
	s_andn2_b64 vcc, exec, s[50:51]
	s_cbranch_vccnz .LBB0_726
	s_add_i32 s50, s13, s61
	v_lshl_add_u64 v[120:121], s[2:3], 0, v[164:165]
	v_add_u32_e32 v122, s50, v144
	v_mov_b32_e32 v123, v145
	v_lshl_add_u64 v[124:125], v[122:123], 1, v[120:121]
	v_mul_f32_e32 v120, v116, v156
	v_mul_f32_e32 v121, v117, v156
	v_mul_f32_e32 v122, v118, v156
	v_mul_f32_e32 v123, v119, v156
	v_cvt_pk_bf16_f32 v120, v120, v121
	v_cvt_pk_bf16_f32 v121, v122, v123
	v_mul_f32_e32 v122, v112, v156
	v_mul_f32_e32 v123, v113, v156
	v_mul_f32_e32 v126, v114, v156
	v_mul_f32_e32 v127, v115, v156
	v_add_co_u32_e32 v124, vcc, 0x49ff000, v124
	v_cvt_pk_bf16_f32 v122, v122, v123
	v_cvt_pk_bf16_f32 v123, v126, v127
	v_addc_co_u32_e32 v125, vcc, 0, v125, vcc
	global_store_dwordx4 v[124:125], v[120:123], off offset:1984

;   DI void operator()(const f32x4 (&acc)[2][2][4][2], const pg8::Unit& u, int wr, int wc, int fr_, int fq_) const {
;     ...
;                 else if (gb < 1184) st_bf8((u16*)(big + E_QNA) + (size_t)token * 512 + (f8 - 672), v, v1, rinv * (0.125f * LOG2E));
.LBB0_727:
	s_andn2_b64 vcc, exec, s[50:51]
	s_cbranch_vccnz .LBB0_729
	s_add_i32 s50, s13, s61
	v_lshl_add_u64 v[120:121], s[2:3], 0, v[164:165]
	v_add_u32_e32 v122, s50, v144
	v_mov_b32_e32 v123, v145
	v_lshl_add_u64 v[124:125], v[122:123], 1, v[120:121]
	v_mul_f32_e32 v120, v116, v162
	v_mul_f32_e32 v121, v117, v162
	v_mul_f32_e32 v122, v118, v162
	v_mul_f32_e32 v123, v119, v162
	v_cvt_pk_bf16_f32 v120, v120, v121
	v_cvt_pk_bf16_f32 v121, v122, v123
	v_mul_f32_e32 v122, v112, v162
	v_mul_f32_e32 v123, v113, v162
	v_mul_f32_e32 v126, v114, v162
	v_mul_f32_e32 v127, v115, v162
	v_add_co_u32_e32 v124, vcc, 0x29ff000, v124
	v_cvt_pk_bf16_f32 v122, v122, v123
	v_cvt_pk_bf16_f32 v123, v126, v127
	v_addc_co_u32_e32 v125, vcc, 0, v125, vcc
	global_store_dwordx4 v[124:125], v[120:123], off offset:3008

; DI void rope_perm(f32x4& a0, f32x4& a1, int fq, int lane, const float* tcos, const float* tsin, int pos) {
;   f32x4 p0, p1;
; #pragma unroll
;   for (int e = 0; e < 4; ++e) { p0[e] = shx(a0[e], 32, lane); p1[e] = shx(a1[e], 32, lane); }
;   const int jb = 8 * (fq & 1);
;   const f32x4 c0 = *(const f32x4*)(tcos + pos * 16 + jb), c1 = *(const f32x4*)(tcos + pos * 16 + jb + 4);
;   const f32x4 s0 = *(const f32x4*)(tsin + pos * 16 + jb), s1 = *(const f32x4*)(tsin + pos * 16 + jb + 4);
;   if (fq < 2) { a0 = a0 * c0 - p0 * s0; a1 = a1 * c1 - p1 * s1; }
;   else        { a0 = a0 * c0 + p0 * s0; a1 = a1 * c1 + p1 * s1; }
; }
;   DI void operator()(const f32x4 (&acc)[2][2][4][2], const pg8::Unit& u, int wr, int wc, int fr_, int fq_) const {
;     ...
;                 else if (gb < 672) {
;                   f32x4 a0 = v, a1 = v1;
;                   rope_perm(a0, a1, fq, t_ & 63, tcos, tsin, token & (S_ - 1));
;                   st_bf8((u16*)(big + E_KPE) + (size_t)token * 32 + 8 * fq, a0, a1, rinv);
.LBB0_730:
	s_andn2_b64 vcc, exec, s[50:51]
	s_cbranch_vccnz .LBB0_736
	v_lshlrev_b32_e32 v124, 2, v157
	v_mov_b32_e32 v125, v145
	v_lshl_add_u64 v[120:121], s[4:5], 0, v[124:125]
	v_lshlrev_b32_e32 v126, 2, v199
	v_mov_b32_e32 v127, v145
	v_lshl_add_u64 v[124:125], s[6:7], 0, v[124:125]
	v_lshl_add_u64 v[130:131], v[120:121], 0, v[126:127]
	v_lshl_add_u64 v[132:133], v[124:125], 0, v[126:127]
	global_load_dwordx4 v[120:123], v[130:131], off
	global_load_dwordx4 v[124:127], v[132:133], off
	global_load_dwordx4 v[170:173], v[132:133], off offset:16
	global_load_dwordx4 v[174:177], v[130:131], off offset:16
	ds_bpermute_b32 v132, v198, v116
	ds_bpermute_b32 v162, v198, v112
	ds_bpermute_b32 v133, v198, v117
	ds_bpermute_b32 v163, v198, v113
	ds_bpermute_b32 v166, v198, v118
	ds_bpermute_b32 v178, v198, v114
	ds_bpermute_b32 v167, v198, v119
	ds_bpermute_b32 v179, v198, v115
	s_waitcnt vmcnt(0) lgkmcnt(0)
	v_mul_f32_e32 v164, v124, v132
	v_mul_f32_e32 v165, v125, v133
	v_mul_f32_e32 v130, v118, v122
	v_mul_f32_e32 v131, v119, v123
	v_mul_f32_e32 v134, v116, v120
	v_mul_f32_e32 v135, v117, v121
	v_mul_f32_e32 v168, v126, v166
	v_mul_f32_e32 v169, v127, v167
	v_mul_f32_e32 v132, v170, v162
	v_mul_f32_e32 v133, v171, v163
	v_mul_f32_e32 v162, v172, v178
	v_mul_f32_e32 v163, v173, v179
	v_mul_f32_e32 v166, v114, v176
	v_mul_f32_e32 v167, v115, v177
	v_mul_f32_e32 v170, v112, v174
	v_mul_f32_e32 v171, v113, v175
	s_and_saveexec_b64 s[50:51], s[92:93]
	s_xor_b64 s[50:51], exec, s[50:51]
	v_add_f32_e32 v122, v130, v168
	v_add_f32_e32 v123, v131, v169
	v_add_f32_e32 v120, v134, v164
	v_add_f32_e32 v121, v135, v165
	v_add_f32_e32 v126, v166, v162
	v_add_f32_e32 v127, v167, v163
	v_add_f32_e32 v124, v170, v132
	v_add_f32_e32 v125, v171, v133
	s_andn2_saveexec_b64 s[50:51], s[50:51]
	v_sub_f32_e32 v123, v131, v169
	v_sub_f32_e32 v122, v130, v168
	v_sub_f32_e32 v121, v135, v165
	v_sub_f32_e32 v120, v134, v164
	v_sub_f32_e32 v127, v167, v163
	v_sub_f32_e32 v126, v166, v162
	v_sub_f32_e32 v125, v171, v133
	v_sub_f32_e32 v124, v170, v132
	s_or_b64 exec, exec, s[50:51]
	v_mul_f32_e32 v120, v156, v120
	v_mul_f32_e32 v121, v156, v121
	v_mul_f32_e32 v122, v156, v122
	v_mul_f32_e32 v123, v156, v123
	v_lshl_add_u64 v[130:131], s[10:11], 0, v[160:161]
	v_lshlrev_b32_e32 v132, 1, v144
	v_mov_b32_e32 v133, v145
	v_cvt_pk_bf16_f32 v120, v120, v121
	v_cvt_pk_bf16_f32 v121, v122, v123
	v_mul_f32_e32 v122, v156, v124
	v_mul_f32_e32 v123, v156, v125
	v_mul_f32_e32 v124, v156, v126
	v_mul_f32_e32 v125, v156, v127
	v_lshl_add_u64 v[130:131], v[130:131], 0, v[132:133]
	v_cvt_pk_bf16_f32 v122, v122, v123
	v_cvt_pk_bf16_f32 v123, v124, v125
	global_store_dwordx4 v[130:131], v[120:123], off

;   DI void operator()(const f32x4 (&acc)[2][2][4][2], const pg8::Unit& u, int wr, int wc, int fr_, int fq_) const {
;     ...
;                 else if (gb < 640) st_bf8((u16*)(big + E_CKV) + (size_t)token * 256 + (f8 - 384), v, v1, rinv);
.LBB0_737:
	s_andn2_b64 vcc, exec, s[50:51]
	s_cbranch_vccnz .LBB0_739
	s_add_i32 s50, s13, s61
	v_lshl_add_u64 v[120:121], s[2:3], 0, v[158:159]
	v_add_u32_e32 v122, s50, v144
	v_mov_b32_e32 v123, v145
	v_lshl_add_u64 v[124:125], v[122:123], 1, v[120:121]
	v_mul_f32_e32 v120, v116, v156
	v_mul_f32_e32 v121, v117, v156
	v_mul_f32_e32 v122, v118, v156
	v_mul_f32_e32 v123, v119, v156
	v_cvt_pk_bf16_f32 v120, v120, v121
	v_cvt_pk_bf16_f32 v121, v122, v123
	v_mul_f32_e32 v122, v112, v156
	v_mul_f32_e32 v123, v113, v156
	v_mul_f32_e32 v126, v114, v156
	v_mul_f32_e32 v127, v115, v156
	v_add_co_u32_e32 v124, vcc, 0x17ff000, v124
	v_cvt_pk_bf16_f32 v122, v122, v123
	v_cvt_pk_bf16_f32 v123, v126, v127
	v_addc_co_u32_e32 v125, vcc, 0, v125, vcc
	global_store_dwordx4 v[124:125], v[120:123], off offset:3584

;   DI void operator()(const f32x4 (&acc)[2][2][4][2], const pg8::Unit& u, int wr, int wc, int fr_, int fq_) const {
;     ...
;               if (n == 0) {
;                 const int gb = u.pn * 256 + bj * 128 + wc * 32; const int f8 = gb + 8 * fq;
;                 const f32x4 v1 = acc[ai][bj][m][1];
;                 if (gb < 384) st_bf8((u16*)(big + E_CQ) + (size_t)token * 384 + f8, v, v1, rinv);
;                 else if (gb < 640) st_bf8((u16*)(big + E_CKV) + (size_t)token * 256 + (f8 - 384), v, v1, rinv);
;                 else if (gb < 672) {
;                   f32x4 a0 = v, a1 = v1;
;                   rope_perm(a0, a1, fq, t_ & 63, tcos, tsin, token & (S_ - 1));
;                   st_bf8((u16*)(big + E_KPE) + (size_t)token * 32 + 8 * fq, a0, a1, rinv);
;                 }
;                 else if (gb < 1184) st_bf8((u16*)(big + E_QNA) + (size_t)token * 512 + (f8 - 672), v, v1, rinv * (0.125f * LOG2E));
;                 else if (gb < 1696) st_bf8((u16*)(big + E_KNA) + (size_t)token * 512 + (f8 - 1184), v, v1, rinv);
;                 else if (gb < 2208) st_bf8((u16*)(big + E_VNAT) + (size_t)token * 512 + (f8 - 1696), v, v1, rinv);
.LBB0_740:
	s_andn2_b64 vcc, exec, s[50:51]
	s_cbranch_vccnz .LBB0_742
	s_ashr_i32 s51, s13, 31
	s_add_u32 s50, s13, s61
	s_addc_u32 s51, s51, 0
	v_mul_f32_e32 v116, v116, v156
	v_mul_f32_e32 v117, v117, v156
	v_mul_f32_e32 v118, v118, v156
	v_mul_f32_e32 v119, v119, v156
	v_mul_f32_e32 v112, v112, v156
	v_mul_f32_e32 v113, v113, v156
	v_lshl_add_u64 v[120:121], v[144:145], 0, s[50:51]
	v_cvt_pk_bf16_f32 v116, v116, v117
	v_cvt_pk_bf16_f32 v117, v118, v119
	v_cvt_pk_bf16_f32 v118, v112, v113
	v_mul_f32_e32 v112, v114, v156
	v_mul_f32_e32 v113, v115, v156
	v_lshl_add_u64 v[120:121], v[120:121], 1, v[128:129]
	v_cvt_pk_bf16_f32 v119, v112, v113
	global_store_dwordx4 v[120:121], v[116:119], off offset:256
.LBB0_742:
	ds_read_b32 v120, v200 offset:64
	v_add3_u32 v130, s15, v201, 16
	v_lshlrev_b32_e32 v112, 4, v130
	v_and_b32_e32 v121, 0xfdf0, v112
	v_cndmask_b32_e64 v112, 0, 1, s[28:29]
	v_ashrrev_i32_e32 v131, 31, v130
	v_cmp_ne_u32_e64 s[76:77], 1, v112
	v_cndmask_b32_e64 v112, 0, 1, s[46:47]
	v_lshlrev_b64 v[128:129], 10, v[130:131]
	s_waitcnt lgkmcnt(0)
	v_mul_f32_e32 v126, 0x3e38aa3b, v120
	v_lshlrev_b64 v[124:125], 6, v[130:131]
	v_lshlrev_b64 v[122:123], 9, v[130:131]
	s_mov_b64 s[50:51], -1
	s_andn2_b64 vcc, exec, s[28:29]
	v_cmp_ne_u32_e64 s[96:97], 1, v112
	s_cbranch_vccnz .LBB0_766
	s_and_b64 vcc, exec, s[96:97]
	s_mov_b64 s[28:29], -1
	s_cbranch_vccnz .LBB0_763
	s_andn2_b64 vcc, exec, s[40:41]
	s_cbranch_vccnz .LBB0_756
	s_andn2_b64 vcc, exec, s[34:35]
	s_cbranch_vccnz .LBB0_753
	s_andn2_b64 vcc, exec, s[22:23]
	s_cbranch_vccnz .LBB0_750
	s_andn2_b64 vcc, exec, s[20:21]
	s_cbranch_vccnz .LBB0_749
	v_lshl_add_u64 v[112:113], s[2:3], 0, v[128:129]
	v_lshl_add_u64 v[116:117], v[152:153], 1, v[112:113]
	v_mul_f32_e32 v112, v108, v120
	v_mul_f32_e32 v113, v109, v120
	v_mul_f32_e32 v114, v110, v120
	v_mul_f32_e32 v115, v111, v120
	v_cvt_pk_bf16_f32 v112, v112, v113
	v_cvt_pk_bf16_f32 v113, v114, v115
	v_mul_f32_e32 v114, v104, v120
	v_mul_f32_e32 v115, v105, v120
	v_mul_f32_e32 v118, v106, v120
	v_mul_f32_e32 v119, v107, v120
	v_add_co_u32_e32 v116, vcc, 0x69ff000, v116
	v_cvt_pk_bf16_f32 v114, v114, v115
	v_cvt_pk_bf16_f32 v115, v118, v119
	v_addc_co_u32_e32 v117, vcc, 0, v117, vcc
	global_store_dwordx4 v[116:117], v[112:115], off offset:704

;   DI void operator()(const f32x4 (&acc)[2][2][4][2], const pg8::Unit& u, int wr, int wc, int fr_, int fq_) const {
;     ...
;                 else if (gb < 1696) st_bf8((u16*)(big + E_KNA) + (size_t)token * 512 + (f8 - 1184), v, v1, rinv);
.LBB0_750:
	s_andn2_b64 vcc, exec, s[28:29]
	s_cbranch_vccnz .LBB0_752
	v_lshl_add_u64 v[112:113], s[2:3], 0, v[128:129]
	v_lshl_add_u64 v[116:117], v[152:153], 1, v[112:113]
	v_mul_f32_e32 v112, v108, v120
	v_mul_f32_e32 v113, v109, v120
	v_mul_f32_e32 v114, v110, v120
	v_mul_f32_e32 v115, v111, v120
	v_cvt_pk_bf16_f32 v112, v112, v113
	v_cvt_pk_bf16_f32 v113, v114, v115
	v_mul_f32_e32 v114, v104, v120
	v_mul_f32_e32 v115, v105, v120
	v_mul_f32_e32 v118, v106, v120
	v_mul_f32_e32 v119, v107, v120
	v_add_co_u32_e32 v116, vcc, 0x49ff000, v116
	v_cvt_pk_bf16_f32 v114, v114, v115
	v_cvt_pk_bf16_f32 v115, v118, v119
	v_addc_co_u32_e32 v117, vcc, 0, v117, vcc
	global_store_dwordx4 v[116:117], v[112:115], off offset:1728

;   DI void operator()(const f32x4 (&acc)[2][2][4][2], const pg8::Unit& u, int wr, int wc, int fr_, int fq_) const {
;     ...
;                 else if (gb < 1184) st_bf8((u16*)(big + E_QNA) + (size_t)token * 512 + (f8 - 672), v, v1, rinv * (0.125f * LOG2E));
.LBB0_753:
	s_andn2_b64 vcc, exec, s[28:29]
	s_cbranch_vccnz .LBB0_755
	v_lshl_add_u64 v[112:113], s[2:3], 0, v[128:129]
	v_lshl_add_u64 v[116:117], v[152:153], 1, v[112:113]
	v_mul_f32_e32 v112, v108, v126
	v_mul_f32_e32 v113, v109, v126
	v_mul_f32_e32 v114, v110, v126
	v_mul_f32_e32 v115, v111, v126
	v_cvt_pk_bf16_f32 v112, v112, v113
	v_cvt_pk_bf16_f32 v113, v114, v115
	v_mul_f32_e32 v114, v104, v126
	v_mul_f32_e32 v115, v105, v126
	v_mul_f32_e32 v118, v106, v126
	v_mul_f32_e32 v119, v107, v126
	v_add_co_u32_e32 v116, vcc, 0x29ff000, v116
	v_cvt_pk_bf16_f32 v114, v114, v115
	v_cvt_pk_bf16_f32 v115, v118, v119
	v_addc_co_u32_e32 v117, vcc, 0, v117, vcc
	global_store_dwordx4 v[116:117], v[112:115], off offset:2752

; DI void rope_perm(f32x4& a0, f32x4& a1, int fq, int lane, const float* tcos, const float* tsin, int pos) {
;   f32x4 p0, p1;
; #pragma unroll
;   for (int e = 0; e < 4; ++e) { p0[e] = shx(a0[e], 32, lane); p1[e] = shx(a1[e], 32, lane); }
;   const int jb = 8 * (fq & 1);
;   const f32x4 c0 = *(const f32x4*)(tcos + pos * 16 + jb), c1 = *(const f32x4*)(tcos + pos * 16 + jb + 4);
;   const f32x4 s0 = *(const f32x4*)(tsin + pos * 16 + jb), s1 = *(const f32x4*)(tsin + pos * 16 + jb + 4);
;   if (fq < 2) { a0 = a0 * c0 - p0 * s0; a1 = a1 * c1 - p1 * s1; }
;   else        { a0 = a0 * c0 + p0 * s0; a1 = a1 * c1 + p1 * s1; }
; }
;   DI void operator()(const f32x4 (&acc)[2][2][4][2], const pg8::Unit& u, int wr, int wc, int fr_, int fq_) const {
;     ...
;                 else if (gb < 672) {
;                   f32x4 a0 = v, a1 = v1;
;                   rope_perm(a0, a1, fq, t_ & 63, tcos, tsin, token & (S_ - 1));
;                   st_bf8((u16*)(big + E_KPE) + (size_t)token * 32 + 8 * fq, a0, a1, rinv);
;                 }
.LBB0_756:
	s_andn2_b64 vcc, exec, s[28:29]
	s_cbranch_vccnz .LBB0_762
	v_lshlrev_b32_e32 v116, 2, v121
	v_mov_b32_e32 v117, v145
	v_lshl_add_u64 v[112:113], s[4:5], 0, v[116:117]
	v_lshlrev_b32_e32 v118, 2, v199
	v_mov_b32_e32 v119, v145
	v_lshl_add_u64 v[116:117], s[6:7], 0, v[116:117]
	v_lshl_add_u64 v[132:133], v[112:113], 0, v[118:119]
	v_lshl_add_u64 v[134:135], v[116:117], 0, v[118:119]
	global_load_dwordx4 v[112:115], v[132:133], off
	global_load_dwordx4 v[116:119], v[134:135], off
	global_load_dwordx4 v[166:169], v[134:135], off offset:16
	global_load_dwordx4 v[170:173], v[132:133], off offset:16
	ds_bpermute_b32 v134, v198, v108
	ds_bpermute_b32 v158, v198, v104
	ds_bpermute_b32 v135, v198, v109
	ds_bpermute_b32 v159, v198, v105
	ds_bpermute_b32 v162, v198, v110
	ds_bpermute_b32 v174, v198, v106
	ds_bpermute_b32 v163, v198, v111
	ds_bpermute_b32 v175, v198, v107
	s_waitcnt vmcnt(0) lgkmcnt(0)
	v_mul_f32_e32 v160, v116, v134
	v_mul_f32_e32 v161, v117, v135
	v_mul_f32_e32 v132, v110, v114
	v_mul_f32_e32 v133, v111, v115
	v_mul_f32_e32 v156, v108, v112
	v_mul_f32_e32 v157, v109, v113
	v_mul_f32_e32 v164, v118, v162
	v_mul_f32_e32 v165, v119, v163
	v_mul_f32_e32 v134, v166, v158
	v_mul_f32_e32 v135, v167, v159
	v_mul_f32_e32 v158, v168, v174
	v_mul_f32_e32 v159, v169, v175
	v_mul_f32_e32 v162, v106, v172
	v_mul_f32_e32 v163, v107, v173
	v_mul_f32_e32 v166, v104, v170
	v_mul_f32_e32 v167, v105, v171
	s_and_saveexec_b64 s[28:29], s[92:93]
	s_xor_b64 s[28:29], exec, s[28:29]
	v_add_f32_e32 v114, v132, v164
	v_add_f32_e32 v115, v133, v165
	v_add_f32_e32 v112, v156, v160
	v_add_f32_e32 v113, v157, v161
	v_add_f32_e32 v118, v162, v158
	v_add_f32_e32 v119, v163, v159
	v_add_f32_e32 v116, v166, v134
	v_add_f32_e32 v117, v167, v135
	s_andn2_saveexec_b64 s[28:29], s[28:29]
	v_sub_f32_e32 v115, v133, v165
	v_sub_f32_e32 v114, v132, v164
	v_sub_f32_e32 v113, v157, v161
	v_sub_f32_e32 v112, v156, v160
	v_sub_f32_e32 v119, v163, v159
	v_sub_f32_e32 v118, v162, v158
	v_sub_f32_e32 v117, v167, v135
	v_sub_f32_e32 v116, v166, v134
	s_or_b64 exec, exec, s[28:29]
	v_mul_f32_e32 v112, v120, v112
	v_mul_f32_e32 v113, v120, v113
	v_mul_f32_e32 v114, v120, v114
	v_mul_f32_e32 v115, v120, v115
	v_lshl_add_u64 v[132:133], s[10:11], 0, v[124:125]
	v_lshlrev_b32_e32 v134, 1, v144
	v_mov_b32_e32 v135, v145
	v_cvt_pk_bf16_f32 v112, v112, v113
	v_cvt_pk_bf16_f32 v113, v114, v115
	v_mul_f32_e32 v114, v120, v116
	v_mul_f32_e32 v115, v120, v117
	v_mul_f32_e32 v116, v120, v118
	v_mul_f32_e32 v117, v120, v119
	v_lshl_add_u64 v[132:133], v[132:133], 0, v[134:135]
	v_cvt_pk_bf16_f32 v114, v114, v115
	v_cvt_pk_bf16_f32 v115, v116, v117
	global_store_dwordx4 v[132:133], v[112:115], off

; DI void st_bf8(u16* p, f32x4 a, f32x4 b, float sc) {
;   u32x4 u; u.x = pack2(a[0] * sc, a[1] * sc); u.y = pack2(a[2] * sc, a[3] * sc); u.z = pack2(b[0] * sc, b[1] * sc); u.w = pack2(b[2] * sc, b[3] * sc);
;   *(u32x4*)p = u;
;   DI void operator()(const f32x4 (&acc)[2][2][4][2], const pg8::Unit& u, int wr, int wc, int fr_, int fq_) const {
;     ...
;                 else if (gb < 640) st_bf8((u16*)(big + E_CKV) + (size_t)token * 256 + (f8 - 384), v, v1, rinv);
.LBB0_763:
	s_andn2_b64 vcc, exec, s[28:29]
	s_cbranch_vccnz .LBB0_765
	v_lshl_add_u64 v[112:113], s[2:3], 0, v[122:123]
	v_lshl_add_u64 v[116:117], v[152:153], 1, v[112:113]
	v_mul_f32_e32 v112, v108, v120
	v_mul_f32_e32 v113, v109, v120
	v_mul_f32_e32 v114, v110, v120
	v_mul_f32_e32 v115, v111, v120
	v_cvt_pk_bf16_f32 v112, v112, v113
	v_cvt_pk_bf16_f32 v113, v114, v115
	v_mul_f32_e32 v114, v104, v120
	v_mul_f32_e32 v115, v105, v120
	v_mul_f32_e32 v118, v106, v120
	v_mul_f32_e32 v119, v107, v120
	v_add_co_u32_e32 v116, vcc, 0x17ff000, v116
	v_cvt_pk_bf16_f32 v114, v114, v115
	v_cvt_pk_bf16_f32 v115, v118, v119
	v_addc_co_u32_e32 v117, vcc, 0, v117, vcc
	global_store_dwordx4 v[116:117], v[112:115], off offset:3328

; DI void st_bf8(u16* p, f32x4 a, f32x4 b, float sc) {
;   u32x4 u; u.x = pack2(a[0] * sc, a[1] * sc); u.y = pack2(a[2] * sc, a[3] * sc); u.z = pack2(b[0] * sc, b[1] * sc); u.w = pack2(b[2] * sc, b[3] * sc);
;   *(u32x4*)p = u;
;   DI void operator()(const f32x4 (&acc)[2][2][4][2], const pg8::Unit& u, int wr, int wc, int fr_, int fq_) const {
;     ...
;             if (EPI == EPI_ABIN) {
;               if (n == 0) {
;                 const int gb = u.pn * 256 + bj * 128 + wc * 32; const int f8 = gb + 8 * fq;
;                 const f32x4 v1 = acc[ai][bj][m][1];
;                 if (gb < 384) st_bf8((u16*)(big + E_CQ) + (size_t)token * 384 + f8, v, v1, rinv);
;                 else if (gb < 640) st_bf8((u16*)(big + E_CKV) + (size_t)token * 256 + (f8 - 384), v, v1, rinv);
;                 else if (gb < 672) {
;                   f32x4 a0 = v, a1 = v1;
;                   rope_perm(a0, a1, fq, t_ & 63, tcos, tsin, token & (S_ - 1));
;                   st_bf8((u16*)(big + E_KPE) + (size_t)token * 32 + 8 * fq, a0, a1, rinv);
;                 }
;                 else if (gb < 1184) st_bf8((u16*)(big + E_QNA) + (size_t)token * 512 + (f8 - 672), v, v1, rinv * (0.125f * LOG2E));
;                 else if (gb < 1696) st_bf8((u16*)(big + E_KNA) + (size_t)token * 512 + (f8 - 1184), v, v1, rinv);
;                 else if (gb < 2208) st_bf8((u16*)(big + E_VNAT) + (size_t)token * 512 + (f8 - 1696), v, v1, rinv);
.LBB0_766:
	s_movk_i32 s28, 0x300
	v_mad_i64_i32 v[112:113], s[28:29], v130, s28, 0
	s_andn2_b64 vcc, exec, s[50:51]
	v_lshl_add_u64 v[112:113], s[2:3], 0, v[112:113]
	s_cbranch_vccnz .LBB0_768
	v_mul_f32_e32 v108, v108, v120
	v_mul_f32_e32 v109, v109, v120
	v_mul_f32_e32 v110, v110, v120
	v_mul_f32_e32 v111, v111, v120
	v_mul_f32_e32 v104, v104, v120
	v_mul_f32_e32 v105, v105, v120
	v_cvt_pk_bf16_f32 v108, v108, v109
	v_cvt_pk_bf16_f32 v109, v110, v111
	v_cvt_pk_bf16_f32 v110, v104, v105
	v_mul_f32_e32 v104, v106, v120
	v_mul_f32_e32 v105, v107, v120
	v_lshl_add_u64 v[114:115], v[150:151], 1, v[112:113]
	v_cvt_pk_bf16_f32 v111, v104, v105
	global_store_dwordx4 v[114:115], v[108:111], off
.LBB0_768:
	v_cndmask_b32_e64 v104, 0, 1, s[48:49]
	v_cmp_ne_u32_e64 s[78:79], 1, v104
	s_andn2_b64 vcc, exec, s[48:49]
	s_mov_b64 s[28:29], -1
	v_readlane_b32 s51, v237, 11
	s_cbranch_vccnz .LBB0_792
	s_and_b64 vcc, exec, s[94:95]
	s_cbranch_vccnz .LBB0_789
	s_andn2_b64 vcc, exec, s[44:45]
	s_cbranch_vccnz .LBB0_782
	s_andn2_b64 vcc, exec, s[42:43]
	s_cbranch_vccnz .LBB0_779
	s_andn2_b64 vcc, exec, s[38:39]
	s_cbranch_vccnz .LBB0_776
	s_andn2_b64 vcc, exec, s[36:37]
	s_cbranch_vccnz .LBB0_775
	s_add_i32 s28, s13, s61
	v_lshl_add_u64 v[104:105], s[2:3], 0, v[128:129]
	v_add_u32_e32 v106, s28, v144
	v_mov_b32_e32 v107, v145
	v_lshl_add_u64 v[108:109], v[106:107], 1, v[104:105]
	v_mul_f32_e32 v104, v100, v120
	v_mul_f32_e32 v105, v101, v120
	v_mul_f32_e32 v106, v102, v120
	v_mul_f32_e32 v107, v103, v120
	v_cvt_pk_bf16_f32 v104, v104, v105
	v_cvt_pk_bf16_f32 v105, v106, v107
	v_mul_f32_e32 v106, v96, v120
	v_mul_f32_e32 v107, v97, v120
	v_mul_f32_e32 v110, v98, v120
	v_mul_f32_e32 v111, v99, v120
	v_add_co_u32_e32 v108, vcc, 0x69ff000, v108
	v_cvt_pk_bf16_f32 v106, v106, v107
	v_cvt_pk_bf16_f32 v107, v110, v111
	v_addc_co_u32_e32 v109, vcc, 0, v109, vcc
	global_store_dwordx4 v[108:109], v[104:107], off offset:960

; DI void st_bf8(u16* p, f32x4 a, f32x4 b, float sc) {
;   u32x4 u; u.x = pack2(a[0] * sc, a[1] * sc); u.y = pack2(a[2] * sc, a[3] * sc); u.z = pack2(b[0] * sc, b[1] * sc); u.w = pack2(b[2] * sc, b[3] * sc);
;   *(u32x4*)p = u;
;   DI void operator()(const f32x4 (&acc)[2][2][4][2], const pg8::Unit& u, int wr, int wc, int fr_, int fq_) const {
;     ...
;                 else if (gb < 1696) st_bf8((u16*)(big + E_KNA) + (size_t)token * 512 + (f8 - 1184), v, v1, rinv);
.LBB0_776:
	s_andn2_b64 vcc, exec, s[28:29]
	s_cbranch_vccnz .LBB0_778
	s_add_i32 s28, s13, s61
	v_lshl_add_u64 v[104:105], s[2:3], 0, v[128:129]
	v_add_u32_e32 v106, s28, v144
	v_mov_b32_e32 v107, v145
	v_lshl_add_u64 v[108:109], v[106:107], 1, v[104:105]
	v_mul_f32_e32 v104, v100, v120
	v_mul_f32_e32 v105, v101, v120
	v_mul_f32_e32 v106, v102, v120
	v_mul_f32_e32 v107, v103, v120
	v_cvt_pk_bf16_f32 v104, v104, v105
	v_cvt_pk_bf16_f32 v105, v106, v107
	v_mul_f32_e32 v106, v96, v120
	v_mul_f32_e32 v107, v97, v120
	v_mul_f32_e32 v110, v98, v120
	v_mul_f32_e32 v111, v99, v120
	v_add_co_u32_e32 v108, vcc, 0x49ff000, v108
	v_cvt_pk_bf16_f32 v106, v106, v107
	v_cvt_pk_bf16_f32 v107, v110, v111
	v_addc_co_u32_e32 v109, vcc, 0, v109, vcc
	global_store_dwordx4 v[108:109], v[104:107], off offset:1984

; DI void st_bf8(u16* p, f32x4 a, f32x4 b, float sc) {
;   u32x4 u; u.x = pack2(a[0] * sc, a[1] * sc); u.y = pack2(a[2] * sc, a[3] * sc); u.z = pack2(b[0] * sc, b[1] * sc); u.w = pack2(b[2] * sc, b[3] * sc);
;   *(u32x4*)p = u;
;   DI void operator()(const f32x4 (&acc)[2][2][4][2], const pg8::Unit& u, int wr, int wc, int fr_, int fq_) const {
;     ...
;                 else if (gb < 1184) st_bf8((u16*)(big + E_QNA) + (size_t)token * 512 + (f8 - 672), v, v1, rinv * (0.125f * LOG2E));
.LBB0_779:
	s_andn2_b64 vcc, exec, s[28:29]
	s_cbranch_vccnz .LBB0_781
	s_add_i32 s28, s13, s61
	v_lshl_add_u64 v[104:105], s[2:3], 0, v[128:129]
	v_add_u32_e32 v106, s28, v144
	v_mov_b32_e32 v107, v145
	v_lshl_add_u64 v[108:109], v[106:107], 1, v[104:105]
	v_mul_f32_e32 v104, v100, v126
	v_mul_f32_e32 v105, v101, v126
	v_mul_f32_e32 v106, v102, v126
	v_mul_f32_e32 v107, v103, v126
	v_cvt_pk_bf16_f32 v104, v104, v105
	v_cvt_pk_bf16_f32 v105, v106, v107
	v_mul_f32_e32 v106, v96, v126
	v_mul_f32_e32 v107, v97, v126
	v_mul_f32_e32 v110, v98, v126
	v_mul_f32_e32 v111, v99, v126
	v_add_co_u32_e32 v108, vcc, 0x29ff000, v108
	v_cvt_pk_bf16_f32 v106, v106, v107
	v_cvt_pk_bf16_f32 v107, v110, v111
	v_addc_co_u32_e32 v109, vcc, 0, v109, vcc
	global_store_dwordx4 v[108:109], v[104:107], off offset:3008

; DI void rope_perm(f32x4& a0, f32x4& a1, int fq, int lane, const float* tcos, const float* tsin, int pos) {
;   f32x4 p0, p1;
; #pragma unroll
;   for (int e = 0; e < 4; ++e) { p0[e] = shx(a0[e], 32, lane); p1[e] = shx(a1[e], 32, lane); }
;   const int jb = 8 * (fq & 1);
;   const f32x4 c0 = *(const f32x4*)(tcos + pos * 16 + jb), c1 = *(const f32x4*)(tcos + pos * 16 + jb + 4);
;   const f32x4 s0 = *(const f32x4*)(tsin + pos * 16 + jb), s1 = *(const f32x4*)(tsin + pos * 16 + jb + 4);
;   if (fq < 2) { a0 = a0 * c0 - p0 * s0; a1 = a1 * c1 - p1 * s1; }
;   else        { a0 = a0 * c0 + p0 * s0; a1 = a1 * c1 + p1 * s1; }
; }
;   DI void operator()(const f32x4 (&acc)[2][2][4][2], const pg8::Unit& u, int wr, int wc, int fr_, int fq_) const {
;     ...
;                 else if (gb < 672) {
;                   f32x4 a0 = v, a1 = v1;
;                   rope_perm(a0, a1, fq, t_ & 63, tcos, tsin, token & (S_ - 1));
;                   st_bf8((u16*)(big + E_KPE) + (size_t)token * 32 + 8 * fq, a0, a1, rinv);
;                 }
.LBB0_782:
	s_andn2_b64 vcc, exec, s[28:29]
	s_cbranch_vccnz .LBB0_788
	v_lshlrev_b32_e32 v108, 2, v121
	v_mov_b32_e32 v109, v145
	v_lshl_add_u64 v[104:105], s[4:5], 0, v[108:109]
	v_lshlrev_b32_e32 v110, 2, v199
	v_mov_b32_e32 v111, v145
	v_lshl_add_u64 v[108:109], s[6:7], 0, v[108:109]
	v_lshl_add_u64 v[114:115], v[104:105], 0, v[110:111]
	v_lshl_add_u64 v[116:117], v[108:109], 0, v[110:111]
	global_load_dwordx4 v[104:107], v[114:115], off
	global_load_dwordx4 v[108:111], v[116:117], off
	global_load_dwordx4 v[156:159], v[116:117], off offset:16
	global_load_dwordx4 v[160:163], v[114:115], off offset:16
	ds_bpermute_b32 v116, v198, v100
	ds_bpermute_b32 v126, v198, v96
	ds_bpermute_b32 v117, v198, v101
	ds_bpermute_b32 v127, v198, v97
	ds_bpermute_b32 v130, v198, v102
	ds_bpermute_b32 v134, v198, v98
	ds_bpermute_b32 v131, v198, v103
	ds_bpermute_b32 v135, v198, v99
	s_waitcnt vmcnt(0) lgkmcnt(0)
	v_mul_f32_e32 v128, v108, v116
	v_mul_f32_e32 v129, v109, v117
	v_mul_f32_e32 v114, v102, v106
	v_mul_f32_e32 v115, v103, v107
	v_mul_f32_e32 v118, v100, v104
	v_mul_f32_e32 v119, v101, v105
	v_mul_f32_e32 v132, v110, v130
	v_mul_f32_e32 v133, v111, v131
	v_mul_f32_e32 v116, v156, v126
	v_mul_f32_e32 v117, v157, v127
	v_mul_f32_e32 v126, v158, v134
	v_mul_f32_e32 v127, v159, v135
	v_mul_f32_e32 v130, v98, v162
	v_mul_f32_e32 v131, v99, v163
	v_mul_f32_e32 v134, v96, v160
	v_mul_f32_e32 v135, v97, v161
	s_and_saveexec_b64 s[28:29], s[92:93]
	s_xor_b64 s[28:29], exec, s[28:29]
	v_add_f32_e32 v106, v114, v132
	v_add_f32_e32 v107, v115, v133
	v_add_f32_e32 v104, v118, v128
	v_add_f32_e32 v105, v119, v129
	v_add_f32_e32 v110, v130, v126
	v_add_f32_e32 v111, v131, v127
	v_add_f32_e32 v108, v134, v116
	v_add_f32_e32 v109, v135, v117
	s_andn2_saveexec_b64 s[28:29], s[28:29]
	v_sub_f32_e32 v107, v115, v133
	v_sub_f32_e32 v106, v114, v132
	v_sub_f32_e32 v105, v119, v129
	v_sub_f32_e32 v104, v118, v128
	v_sub_f32_e32 v111, v131, v127
	v_sub_f32_e32 v110, v130, v126
	v_sub_f32_e32 v109, v135, v117
	v_sub_f32_e32 v108, v134, v116
	s_or_b64 exec, exec, s[28:29]
	v_mul_f32_e32 v104, v120, v104
	v_mul_f32_e32 v105, v120, v105
	v_mul_f32_e32 v106, v120, v106
	v_mul_f32_e32 v107, v120, v107
	v_lshl_add_u64 v[114:115], s[10:11], 0, v[124:125]
	v_lshlrev_b32_e32 v116, 1, v144
	v_mov_b32_e32 v117, v145
	v_cvt_pk_bf16_f32 v104, v104, v105
	v_cvt_pk_bf16_f32 v105, v106, v107
	v_mul_f32_e32 v106, v120, v108
	v_mul_f32_e32 v107, v120, v109
	v_mul_f32_e32 v108, v120, v110
	v_mul_f32_e32 v109, v120, v111
	v_lshl_add_u64 v[114:115], v[114:115], 0, v[116:117]
	v_cvt_pk_bf16_f32 v106, v106, v107
	v_cvt_pk_bf16_f32 v107, v108, v109
	global_store_dwordx4 v[114:115], v[104:107], off

; DI void st_bf8(u16* p, f32x4 a, f32x4 b, float sc) {
;   u32x4 u; u.x = pack2(a[0] * sc, a[1] * sc); u.y = pack2(a[2] * sc, a[3] * sc); u.z = pack2(b[0] * sc, b[1] * sc); u.w = pack2(b[2] * sc, b[3] * sc);
;   *(u32x4*)p = u;
;   DI void operator()(const f32x4 (&acc)[2][2][4][2], const pg8::Unit& u, int wr, int wc, int fr_, int fq_) const {
;     ...
;                 else if (gb < 640) st_bf8((u16*)(big + E_CKV) + (size_t)token * 256 + (f8 - 384), v, v1, rinv);
.LBB0_789:
	s_andn2_b64 vcc, exec, s[28:29]
	s_cbranch_vccnz .LBB0_791
	s_add_i32 s28, s13, s61
	v_lshl_add_u64 v[104:105], s[2:3], 0, v[122:123]
	v_add_u32_e32 v106, s28, v144
	v_mov_b32_e32 v107, v145
	v_lshl_add_u64 v[108:109], v[106:107], 1, v[104:105]
	v_mul_f32_e32 v104, v100, v120
	v_mul_f32_e32 v105, v101, v120
	v_mul_f32_e32 v106, v102, v120
	v_mul_f32_e32 v107, v103, v120
	v_cvt_pk_bf16_f32 v104, v104, v105
	v_cvt_pk_bf16_f32 v105, v106, v107
	v_mul_f32_e32 v106, v96, v120
	v_mul_f32_e32 v107, v97, v120
	v_mul_f32_e32 v110, v98, v120
	v_mul_f32_e32 v111, v99, v120
	v_add_co_u32_e32 v108, vcc, 0x17ff000, v108
	v_cvt_pk_bf16_f32 v106, v106, v107
	v_cvt_pk_bf16_f32 v107, v110, v111
	v_addc_co_u32_e32 v109, vcc, 0, v109, vcc
	global_store_dwordx4 v[108:109], v[104:107], off offset:3584

; DI void st_bf8(u16* p, f32x4 a, f32x4 b, float sc) {
;   u32x4 u; u.x = pack2(a[0] * sc, a[1] * sc); u.y = pack2(a[2] * sc, a[3] * sc); u.z = pack2(b[0] * sc, b[1] * sc); u.w = pack2(b[2] * sc, b[3] * sc);
;   *(u32x4*)p = u;
;   DI void operator()(const f32x4 (&acc)[2][2][4][2], const pg8::Unit& u, int wr, int wc, int fr_, int fq_) const {
;     ...
;         const int rl = ai * 128 + wr * 64 + m * 16 + fr;
;         const int token = u.pm * 256 + rl;
;         float rinv = 1.f;
;         if (EPI != EPI_RESID) rinv = rinv_tab[slot * 256 + rl];
;         float ssq = 0.f;
; #pragma unroll
;         for (int bj = 0; bj < 2; ++bj)
; #pragma unroll
;           for (int n = 0; n < 2; ++n) {
;             const int fb = u.pn * 256 + bj * 128 + wc * 32 + n * 16;
;             const int f = fb + 4 * fq;
;             const f32x4 v = acc[ai][bj][m][n];
;             if (EPI == EPI_ABIN) {
;               if (n == 0) {
;                 const int gb = u.pn * 256 + bj * 128 + wc * 32; const int f8 = gb + 8 * fq;
;                 const f32x4 v1 = acc[ai][bj][m][1];
;                 if (gb < 384) st_bf8((u16*)(big + E_CQ) + (size_t)token * 384 + f8, v, v1, rinv);
;                 else if (gb < 640) st_bf8((u16*)(big + E_CKV) + (size_t)token * 256 + (f8 - 384), v, v1, rinv);
;                 else if (gb < 672) {
;                   f32x4 a0 = v, a1 = v1;
;                   rope_perm(a0, a1, fq, t_ & 63, tcos, tsin, token & (S_ - 1));
;                   st_bf8((u16*)(big + E_KPE) + (size_t)token * 32 + 8 * fq, a0, a1, rinv);
;                 }
;                 else if (gb < 1184) st_bf8((u16*)(big + E_QNA) + (size_t)token * 512 + (f8 - 672), v, v1, rinv * (0.125f * LOG2E));
;                 else if (gb < 1696) st_bf8((u16*)(big + E_KNA) + (size_t)token * 512 + (f8 - 1184), v, v1, rinv);
;                 else if (gb < 2208) st_bf8((u16*)(big + E_VNAT) + (size_t)token * 512 + (f8 - 1696), v, v1, rinv);
.LBB0_792:
	s_andn2_b64 vcc, exec, s[28:29]
	s_cbranch_vccnz .LBB0_794
	s_ashr_i32 s29, s13, 31
	s_add_u32 s28, s13, s61
	s_addc_u32 s29, s29, 0
	v_mul_f32_e32 v100, v100, v120
	v_mul_f32_e32 v101, v101, v120
	v_mul_f32_e32 v102, v102, v120
	v_mul_f32_e32 v103, v103, v120
	v_mul_f32_e32 v96, v96, v120
	v_mul_f32_e32 v97, v97, v120
	v_lshl_add_u64 v[104:105], v[144:145], 0, s[28:29]
	v_cvt_pk_bf16_f32 v100, v100, v101
	v_cvt_pk_bf16_f32 v101, v102, v103
	v_cvt_pk_bf16_f32 v102, v96, v97
	v_mul_f32_e32 v96, v98, v120
	v_mul_f32_e32 v97, v99, v120
	v_lshl_add_u64 v[104:105], v[104:105], 1, v[112:113]
	v_cvt_pk_bf16_f32 v103, v96, v97
	global_store_dwordx4 v[104:105], v[100:103], off offset:256
.LBB0_794:
	ds_read_b32 v104, v200 offset:128
	v_add3_u32 v114, s15, v201, 32
	v_ashrrev_i32_e32 v115, 31, v114
	v_lshlrev_b32_e32 v96, 4, v114
	v_lshlrev_b64 v[112:113], 10, v[114:115]
	s_waitcnt lgkmcnt(0)
	v_mul_f32_e32 v110, 0x3e38aa3b, v104
	v_and_b32_e32 v105, 0xfef0, v96
	v_lshlrev_b64 v[108:109], 6, v[114:115]
	v_lshlrev_b64 v[106:107], 9, v[114:115]
	s_and_b64 vcc, exec, s[76:77]
	s_mov_b64 s[28:29], -1
	s_cbranch_vccnz .LBB0_818
	s_and_b64 vcc, exec, s[96:97]
	s_cbranch_vccnz .LBB0_815
	s_andn2_b64 vcc, exec, s[40:41]
	s_cbranch_vccnz .LBB0_808
	s_andn2_b64 vcc, exec, s[34:35]
	s_cbranch_vccnz .LBB0_805
	s_andn2_b64 vcc, exec, s[22:23]
	s_cbranch_vccnz .LBB0_802
	s_andn2_b64 vcc, exec, s[20:21]
	s_cbranch_vccnz .LBB0_801
	v_lshl_add_u64 v[96:97], s[2:3], 0, v[112:113]
	v_lshl_add_u64 v[100:101], v[152:153], 1, v[96:97]
	v_mul_f32_e32 v96, v92, v104
	v_mul_f32_e32 v97, v93, v104
	v_mul_f32_e32 v98, v94, v104
	v_mul_f32_e32 v99, v95, v104
	v_cvt_pk_bf16_f32 v96, v96, v97
	v_cvt_pk_bf16_f32 v97, v98, v99
	v_mul_f32_e32 v98, v88, v104
	v_mul_f32_e32 v99, v89, v104
	v_mul_f32_e32 v102, v90, v104
	v_mul_f32_e32 v103, v91, v104
	v_add_co_u32_e32 v100, vcc, 0x69ff000, v100
	v_cvt_pk_bf16_f32 v98, v98, v99
	v_cvt_pk_bf16_f32 v99, v102, v103
	v_addc_co_u32_e32 v101, vcc, 0, v101, vcc
	global_store_dwordx4 v[100:101], v[96:99], off offset:704

; DI void st_bf8(u16* p, f32x4 a, f32x4 b, float sc) {
;   u32x4 u; u.x = pack2(a[0] * sc, a[1] * sc); u.y = pack2(a[2] * sc, a[3] * sc); u.z = pack2(b[0] * sc, b[1] * sc); u.w = pack2(b[2] * sc, b[3] * sc);
;   *(u32x4*)p = u;
;   DI void operator()(const f32x4 (&acc)[2][2][4][2], const pg8::Unit& u, int wr, int wc, int fr_, int fq_) const {
;     ...
;                 else if (gb < 1696) st_bf8((u16*)(big + E_KNA) + (size_t)token * 512 + (f8 - 1184), v, v1, rinv);
.LBB0_802:
	s_andn2_b64 vcc, exec, s[28:29]
	s_cbranch_vccnz .LBB0_804
	v_lshl_add_u64 v[96:97], s[2:3], 0, v[112:113]
	v_lshl_add_u64 v[100:101], v[152:153], 1, v[96:97]
	v_mul_f32_e32 v96, v92, v104
	v_mul_f32_e32 v97, v93, v104
	v_mul_f32_e32 v98, v94, v104
	v_mul_f32_e32 v99, v95, v104
	v_cvt_pk_bf16_f32 v96, v96, v97
	v_cvt_pk_bf16_f32 v97, v98, v99
	v_mul_f32_e32 v98, v88, v104
	v_mul_f32_e32 v99, v89, v104
	v_mul_f32_e32 v102, v90, v104
	v_mul_f32_e32 v103, v91, v104
	v_add_co_u32_e32 v100, vcc, 0x49ff000, v100
	v_cvt_pk_bf16_f32 v98, v98, v99
	v_cvt_pk_bf16_f32 v99, v102, v103
	v_addc_co_u32_e32 v101, vcc, 0, v101, vcc
	global_store_dwordx4 v[100:101], v[96:99], off offset:1728

; DI void st_bf8(u16* p, f32x4 a, f32x4 b, float sc) {
;   u32x4 u; u.x = pack2(a[0] * sc, a[1] * sc); u.y = pack2(a[2] * sc, a[3] * sc); u.z = pack2(b[0] * sc, b[1] * sc); u.w = pack2(b[2] * sc, b[3] * sc);
;   *(u32x4*)p = u;
;   DI void operator()(const f32x4 (&acc)[2][2][4][2], const pg8::Unit& u, int wr, int wc, int fr_, int fq_) const {
;     ...
;                 else if (gb < 1184) st_bf8((u16*)(big + E_QNA) + (size_t)token * 512 + (f8 - 672), v, v1, rinv * (0.125f * LOG2E));
.LBB0_805:
	s_andn2_b64 vcc, exec, s[28:29]
	s_cbranch_vccnz .LBB0_807
	v_lshl_add_u64 v[96:97], s[2:3], 0, v[112:113]
	v_lshl_add_u64 v[100:101], v[152:153], 1, v[96:97]
	v_mul_f32_e32 v96, v92, v110
	v_mul_f32_e32 v97, v93, v110
	v_mul_f32_e32 v98, v94, v110
	v_mul_f32_e32 v99, v95, v110
	v_cvt_pk_bf16_f32 v96, v96, v97
	v_cvt_pk_bf16_f32 v97, v98, v99
	v_mul_f32_e32 v98, v88, v110
	v_mul_f32_e32 v99, v89, v110
	v_mul_f32_e32 v102, v90, v110
	v_mul_f32_e32 v103, v91, v110
	v_add_co_u32_e32 v100, vcc, 0x29ff000, v100
	v_cvt_pk_bf16_f32 v98, v98, v99
	v_cvt_pk_bf16_f32 v99, v102, v103
	v_addc_co_u32_e32 v101, vcc, 0, v101, vcc
	global_store_dwordx4 v[100:101], v[96:99], off offset:2752

; DI void rope_perm(f32x4& a0, f32x4& a1, int fq, int lane, const float* tcos, const float* tsin, int pos) {
;   f32x4 p0, p1;
; #pragma unroll
;   for (int e = 0; e < 4; ++e) { p0[e] = shx(a0[e], 32, lane); p1[e] = shx(a1[e], 32, lane); }
;   const int jb = 8 * (fq & 1);
;   const f32x4 c0 = *(const f32x4*)(tcos + pos * 16 + jb), c1 = *(const f32x4*)(tcos + pos * 16 + jb + 4);
;   const f32x4 s0 = *(const f32x4*)(tsin + pos * 16 + jb), s1 = *(const f32x4*)(tsin + pos * 16 + jb + 4);
;   if (fq < 2) { a0 = a0 * c0 - p0 * s0; a1 = a1 * c1 - p1 * s1; }
;   else        { a0 = a0 * c0 + p0 * s0; a1 = a1 * c1 + p1 * s1; }
; }
;   DI void operator()(const f32x4 (&acc)[2][2][4][2], const pg8::Unit& u, int wr, int wc, int fr_, int fq_) const {
;     ...
;                 else if (gb < 672) {
;                   f32x4 a0 = v, a1 = v1;
;                   rope_perm(a0, a1, fq, t_ & 63, tcos, tsin, token & (S_ - 1));
;                   st_bf8((u16*)(big + E_KPE) + (size_t)token * 32 + 8 * fq, a0, a1, rinv);
;                 }
.LBB0_808:
	s_andn2_b64 vcc, exec, s[28:29]
	s_cbranch_vccnz .LBB0_814
	v_lshlrev_b32_e32 v100, 2, v105
	v_mov_b32_e32 v101, v145
	v_lshl_add_u64 v[96:97], s[4:5], 0, v[100:101]
	v_lshlrev_b32_e32 v102, 2, v199
	v_mov_b32_e32 v103, v145
	v_lshl_add_u64 v[100:101], s[6:7], 0, v[100:101]
	v_lshl_add_u64 v[116:117], v[96:97], 0, v[102:103]
	v_lshl_add_u64 v[118:119], v[100:101], 0, v[102:103]
	global_load_dwordx4 v[96:99], v[116:117], off
	global_load_dwordx4 v[100:103], v[118:119], off
	global_load_dwordx4 v[130:133], v[118:119], off offset:16
	global_load_dwordx4 v[156:159], v[116:117], off offset:16
	ds_bpermute_b32 v118, v198, v92
	ds_bpermute_b32 v122, v198, v88
	ds_bpermute_b32 v119, v198, v93
	ds_bpermute_b32 v123, v198, v89
	ds_bpermute_b32 v126, v198, v94
	ds_bpermute_b32 v134, v198, v90
	ds_bpermute_b32 v127, v198, v95
	ds_bpermute_b32 v135, v198, v91
	s_waitcnt vmcnt(0) lgkmcnt(0)
	v_mul_f32_e32 v124, v100, v118
	v_mul_f32_e32 v125, v101, v119
	v_mul_f32_e32 v116, v94, v98
	v_mul_f32_e32 v117, v95, v99
	v_mul_f32_e32 v120, v92, v96
	v_mul_f32_e32 v121, v93, v97
	v_mul_f32_e32 v128, v102, v126
	v_mul_f32_e32 v129, v103, v127
	v_mul_f32_e32 v118, v130, v122
	v_mul_f32_e32 v119, v131, v123
	v_mul_f32_e32 v122, v132, v134
	v_mul_f32_e32 v123, v133, v135
	v_mul_f32_e32 v126, v90, v158
	v_mul_f32_e32 v127, v91, v159
	v_mul_f32_e32 v130, v88, v156
	v_mul_f32_e32 v131, v89, v157
	s_and_saveexec_b64 s[28:29], s[92:93]
	s_xor_b64 s[28:29], exec, s[28:29]
	v_add_f32_e32 v98, v116, v128
	v_add_f32_e32 v99, v117, v129
	v_add_f32_e32 v96, v120, v124
	v_add_f32_e32 v97, v121, v125
	v_add_f32_e32 v102, v126, v122
	v_add_f32_e32 v103, v127, v123
	v_add_f32_e32 v100, v130, v118
	v_add_f32_e32 v101, v131, v119
	s_andn2_saveexec_b64 s[28:29], s[28:29]
	v_sub_f32_e32 v99, v117, v129
	v_sub_f32_e32 v98, v116, v128
	v_sub_f32_e32 v97, v121, v125
	v_sub_f32_e32 v96, v120, v124
	v_sub_f32_e32 v103, v127, v123
	v_sub_f32_e32 v102, v126, v122
	v_sub_f32_e32 v101, v131, v119
	v_sub_f32_e32 v100, v130, v118
	s_or_b64 exec, exec, s[28:29]
	v_mul_f32_e32 v96, v104, v96
	v_mul_f32_e32 v97, v104, v97
	v_mul_f32_e32 v98, v104, v98
	v_mul_f32_e32 v99, v104, v99
	v_lshl_add_u64 v[116:117], s[10:11], 0, v[108:109]
	v_lshlrev_b32_e32 v118, 1, v144
	v_mov_b32_e32 v119, v145
	v_cvt_pk_bf16_f32 v96, v96, v97
	v_cvt_pk_bf16_f32 v97, v98, v99
	v_mul_f32_e32 v98, v104, v100
	v_mul_f32_e32 v99, v104, v101
	v_mul_f32_e32 v100, v104, v102
	v_mul_f32_e32 v101, v104, v103
	v_lshl_add_u64 v[116:117], v[116:117], 0, v[118:119]
	v_cvt_pk_bf16_f32 v98, v98, v99
	v_cvt_pk_bf16_f32 v99, v100, v101
	global_store_dwordx4 v[116:117], v[96:99], off

; DI void st_bf8(u16* p, f32x4 a, f32x4 b, float sc) {
;   u32x4 u; u.x = pack2(a[0] * sc, a[1] * sc); u.y = pack2(a[2] * sc, a[3] * sc); u.z = pack2(b[0] * sc, b[1] * sc); u.w = pack2(b[2] * sc, b[3] * sc);
;   *(u32x4*)p = u;
;   DI void operator()(const f32x4 (&acc)[2][2][4][2], const pg8::Unit& u, int wr, int wc, int fr_, int fq_) const {
;     ...
;                 else if (gb < 640) st_bf8((u16*)(big + E_CKV) + (size_t)token * 256 + (f8 - 384), v, v1, rinv);
.LBB0_815:
	s_andn2_b64 vcc, exec, s[28:29]
	s_cbranch_vccnz .LBB0_817
	v_lshl_add_u64 v[96:97], s[2:3], 0, v[106:107]
	v_lshl_add_u64 v[100:101], v[152:153], 1, v[96:97]
	v_mul_f32_e32 v96, v92, v104
	v_mul_f32_e32 v97, v93, v104
	v_mul_f32_e32 v98, v94, v104
	v_mul_f32_e32 v99, v95, v104
	v_cvt_pk_bf16_f32 v96, v96, v97
	v_cvt_pk_bf16_f32 v97, v98, v99
	v_mul_f32_e32 v98, v88, v104
	v_mul_f32_e32 v99, v89, v104
	v_mul_f32_e32 v102, v90, v104
	v_mul_f32_e32 v103, v91, v104
	v_add_co_u32_e32 v100, vcc, 0x17ff000, v100
	v_cvt_pk_bf16_f32 v98, v98, v99
	v_cvt_pk_bf16_f32 v99, v102, v103
	v_addc_co_u32_e32 v101, vcc, 0, v101, vcc
	global_store_dwordx4 v[100:101], v[96:99], off offset:3328

; DI void st_bf8(u16* p, f32x4 a, f32x4 b, float sc) {
;   u32x4 u; u.x = pack2(a[0] * sc, a[1] * sc); u.y = pack2(a[2] * sc, a[3] * sc); u.z = pack2(b[0] * sc, b[1] * sc); u.w = pack2(b[2] * sc, b[3] * sc);
;   *(u32x4*)p = u;
;   DI void operator()(const f32x4 (&acc)[2][2][4][2], const pg8::Unit& u, int wr, int wc, int fr_, int fq_) const {
;     ...
;         const int rl = ai * 128 + wr * 64 + m * 16 + fr;
;         const int token = u.pm * 256 + rl;
;         float rinv = 1.f;
;         if (EPI != EPI_RESID) rinv = rinv_tab[slot * 256 + rl];
;         float ssq = 0.f;
; #pragma unroll
;         for (int bj = 0; bj < 2; ++bj)
; #pragma unroll
;           for (int n = 0; n < 2; ++n) {
;             const int fb = u.pn * 256 + bj * 128 + wc * 32 + n * 16;
;             const int f = fb + 4 * fq;
;             const f32x4 v = acc[ai][bj][m][n];
;             if (EPI == EPI_ABIN) {
;               if (n == 0) {
;                 const int gb = u.pn * 256 + bj * 128 + wc * 32; const int f8 = gb + 8 * fq;
;                 const f32x4 v1 = acc[ai][bj][m][1];
;                 if (gb < 384) st_bf8((u16*)(big + E_CQ) + (size_t)token * 384 + f8, v, v1, rinv);
;                 else if (gb < 640) st_bf8((u16*)(big + E_CKV) + (size_t)token * 256 + (f8 - 384), v, v1, rinv);
;                 else if (gb < 672) {
;                   f32x4 a0 = v, a1 = v1;
;                   rope_perm(a0, a1, fq, t_ & 63, tcos, tsin, token & (S_ - 1));
;                   st_bf8((u16*)(big + E_KPE) + (size_t)token * 32 + 8 * fq, a0, a1, rinv);
;                 }
;                 else if (gb < 1184) st_bf8((u16*)(big + E_QNA) + (size_t)token * 512 + (f8 - 672), v, v1, rinv * (0.125f * LOG2E));
;                 else if (gb < 1696) st_bf8((u16*)(big + E_KNA) + (size_t)token * 512 + (f8 - 1184), v, v1, rinv);
;                 else if (gb < 2208) st_bf8((u16*)(big + E_VNAT) + (size_t)token * 512 + (f8 - 1696), v, v1, rinv);
.LBB0_821:
	s_ashr_i32 s29, s13, 31
	s_add_u32 s28, s13, s61
	s_addc_u32 s29, s29, 0
	v_mul_f32_e32 v84, v84, v104
	v_mul_f32_e32 v85, v85, v104
	v_mul_f32_e32 v86, v86, v104
	v_mul_f32_e32 v87, v87, v104
	v_mul_f32_e32 v80, v80, v104
	v_mul_f32_e32 v81, v81, v104
	v_lshl_add_u64 v[88:89], v[144:145], 0, s[28:29]
	v_cvt_pk_bf16_f32 v84, v84, v85
	v_cvt_pk_bf16_f32 v85, v86, v87
	v_cvt_pk_bf16_f32 v86, v80, v81
	v_mul_f32_e32 v80, v82, v104
	v_mul_f32_e32 v81, v83, v104
	v_lshl_add_u64 v[88:89], v[88:89], 1, v[96:97]
	v_cvt_pk_bf16_f32 v87, v80, v81
	global_store_dwordx4 v[88:89], v[84:87], off offset:256
.LBB0_822:
	ds_read_b32 v88, v200 offset:192
	v_add3_u32 v98, s15, v201, 48
	v_ashrrev_i32_e32 v99, 31, v98
	v_lshlrev_b32_e32 v80, 4, v98
	v_lshlrev_b64 v[96:97], 10, v[98:99]
	s_waitcnt lgkmcnt(0)
	v_mul_f32_e32 v94, 0x3e38aa3b, v88
	v_and_b32_e32 v89, 0xfff0, v80
	v_lshlrev_b64 v[92:93], 6, v[98:99]
	v_lshlrev_b64 v[90:91], 9, v[98:99]
	s_and_b64 vcc, exec, s[76:77]
	s_mov_b64 s[28:29], -1
	s_cbranch_vccnz .LBB0_846
	s_and_b64 vcc, exec, s[96:97]
	s_cbranch_vccnz .LBB0_843
	s_andn2_b64 vcc, exec, s[40:41]
	s_cbranch_vccnz .LBB0_836
	s_andn2_b64 vcc, exec, s[34:35]
	s_cbranch_vccnz .LBB0_833
	s_andn2_b64 vcc, exec, s[22:23]
	s_cbranch_vccnz .LBB0_830
	s_andn2_b64 vcc, exec, s[20:21]
	s_cbranch_vccnz .LBB0_829
	v_lshl_add_u64 v[80:81], s[2:3], 0, v[96:97]
	v_lshl_add_u64 v[84:85], v[152:153], 1, v[80:81]
	v_mul_f32_e32 v80, v76, v88
	v_mul_f32_e32 v81, v77, v88
	v_mul_f32_e32 v82, v78, v88
	v_mul_f32_e32 v83, v79, v88
	v_cvt_pk_bf16_f32 v80, v80, v81
	v_cvt_pk_bf16_f32 v81, v82, v83
	v_mul_f32_e32 v82, v72, v88
	v_mul_f32_e32 v83, v73, v88
	v_mul_f32_e32 v86, v74, v88
	v_mul_f32_e32 v87, v75, v88
	v_add_co_u32_e32 v84, vcc, 0x69ff000, v84
	v_cvt_pk_bf16_f32 v82, v82, v83
	v_cvt_pk_bf16_f32 v83, v86, v87
	v_addc_co_u32_e32 v85, vcc, 0, v85, vcc
	global_store_dwordx4 v[84:85], v[80:83], off offset:704

; DI void st_bf8(u16* p, f32x4 a, f32x4 b, float sc) {
;   u32x4 u; u.x = pack2(a[0] * sc, a[1] * sc); u.y = pack2(a[2] * sc, a[3] * sc); u.z = pack2(b[0] * sc, b[1] * sc); u.w = pack2(b[2] * sc, b[3] * sc);
;   *(u32x4*)p = u;
;   DI void operator()(const f32x4 (&acc)[2][2][4][2], const pg8::Unit& u, int wr, int wc, int fr_, int fq_) const {
;     ...
;                 else if (gb < 1696) st_bf8((u16*)(big + E_KNA) + (size_t)token * 512 + (f8 - 1184), v, v1, rinv);
.LBB0_830:
	s_andn2_b64 vcc, exec, s[28:29]
	s_cbranch_vccnz .LBB0_832
	v_lshl_add_u64 v[80:81], s[2:3], 0, v[96:97]
	v_lshl_add_u64 v[84:85], v[152:153], 1, v[80:81]
	v_mul_f32_e32 v80, v76, v88
	v_mul_f32_e32 v81, v77, v88
	v_mul_f32_e32 v82, v78, v88
	v_mul_f32_e32 v83, v79, v88
	v_cvt_pk_bf16_f32 v80, v80, v81
	v_cvt_pk_bf16_f32 v81, v82, v83
	v_mul_f32_e32 v82, v72, v88
	v_mul_f32_e32 v83, v73, v88
	v_mul_f32_e32 v86, v74, v88
	v_mul_f32_e32 v87, v75, v88
	v_add_co_u32_e32 v84, vcc, 0x49ff000, v84
	v_cvt_pk_bf16_f32 v82, v82, v83
	v_cvt_pk_bf16_f32 v83, v86, v87
	v_addc_co_u32_e32 v85, vcc, 0, v85, vcc
	global_store_dwordx4 v[84:85], v[80:83], off offset:1728

; DI void st_bf8(u16* p, f32x4 a, f32x4 b, float sc) {
;   u32x4 u; u.x = pack2(a[0] * sc, a[1] * sc); u.y = pack2(a[2] * sc, a[3] * sc); u.z = pack2(b[0] * sc, b[1] * sc); u.w = pack2(b[2] * sc, b[3] * sc);
;   *(u32x4*)p = u;
;   DI void operator()(const f32x4 (&acc)[2][2][4][2], const pg8::Unit& u, int wr, int wc, int fr_, int fq_) const {
;     ...
;                 else if (gb < 1184) st_bf8((u16*)(big + E_QNA) + (size_t)token * 512 + (f8 - 672), v, v1, rinv * (0.125f * LOG2E));
.LBB0_833:
	s_andn2_b64 vcc, exec, s[28:29]
	s_cbranch_vccnz .LBB0_835
	v_lshl_add_u64 v[80:81], s[2:3], 0, v[96:97]
	v_lshl_add_u64 v[84:85], v[152:153], 1, v[80:81]
	v_mul_f32_e32 v80, v76, v94
	v_mul_f32_e32 v81, v77, v94
	v_mul_f32_e32 v82, v78, v94
	v_mul_f32_e32 v83, v79, v94
	v_cvt_pk_bf16_f32 v80, v80, v81
	v_cvt_pk_bf16_f32 v81, v82, v83
	v_mul_f32_e32 v82, v72, v94
	v_mul_f32_e32 v83, v73, v94
	v_mul_f32_e32 v86, v74, v94
	v_mul_f32_e32 v87, v75, v94
	v_add_co_u32_e32 v84, vcc, 0x29ff000, v84
	v_cvt_pk_bf16_f32 v82, v82, v83
	v_cvt_pk_bf16_f32 v83, v86, v87
	v_addc_co_u32_e32 v85, vcc, 0, v85, vcc
	global_store_dwordx4 v[84:85], v[80:83], off offset:2752

; DI void rope_perm(f32x4& a0, f32x4& a1, int fq, int lane, const float* tcos, const float* tsin, int pos) {
;   f32x4 p0, p1;
; #pragma unroll
;   for (int e = 0; e < 4; ++e) { p0[e] = shx(a0[e], 32, lane); p1[e] = shx(a1[e], 32, lane); }
;   const int jb = 8 * (fq & 1);
;   const f32x4 c0 = *(const f32x4*)(tcos + pos * 16 + jb), c1 = *(const f32x4*)(tcos + pos * 16 + jb + 4);
;   const f32x4 s0 = *(const f32x4*)(tsin + pos * 16 + jb), s1 = *(const f32x4*)(tsin + pos * 16 + jb + 4);
;   if (fq < 2) { a0 = a0 * c0 - p0 * s0; a1 = a1 * c1 - p1 * s1; }
;   else        { a0 = a0 * c0 + p0 * s0; a1 = a1 * c1 + p1 * s1; }
; }
;   DI void operator()(const f32x4 (&acc)[2][2][4][2], const pg8::Unit& u, int wr, int wc, int fr_, int fq_) const {
;     ...
;                 else if (gb < 672) {
;                   f32x4 a0 = v, a1 = v1;
;                   rope_perm(a0, a1, fq, t_ & 63, tcos, tsin, token & (S_ - 1));
;                   st_bf8((u16*)(big + E_KPE) + (size_t)token * 32 + 8 * fq, a0, a1, rinv);
;                 }
.LBB0_836:
	s_andn2_b64 vcc, exec, s[28:29]
	s_cbranch_vccnz .LBB0_842
	v_lshlrev_b32_e32 v84, 2, v89
	v_mov_b32_e32 v85, v145
	v_lshl_add_u64 v[80:81], s[4:5], 0, v[84:85]
	v_lshlrev_b32_e32 v86, 2, v199
	v_mov_b32_e32 v87, v145
	v_lshl_add_u64 v[84:85], s[6:7], 0, v[84:85]
	v_lshl_add_u64 v[100:101], v[80:81], 0, v[86:87]
	v_lshl_add_u64 v[102:103], v[84:85], 0, v[86:87]
	global_load_dwordx4 v[80:83], v[100:101], off
	global_load_dwordx4 v[84:87], v[102:103], off
	global_load_dwordx4 v[114:117], v[102:103], off offset:16
	global_load_dwordx4 v[118:121], v[100:101], off offset:16
	ds_bpermute_b32 v102, v198, v76
	ds_bpermute_b32 v106, v198, v72
	ds_bpermute_b32 v103, v198, v77
	ds_bpermute_b32 v107, v198, v73
	ds_bpermute_b32 v110, v198, v78
	ds_bpermute_b32 v122, v198, v74
	ds_bpermute_b32 v111, v198, v79
	ds_bpermute_b32 v123, v198, v75
	s_waitcnt vmcnt(0) lgkmcnt(0)
	v_mul_f32_e32 v108, v84, v102
	v_mul_f32_e32 v109, v85, v103
	v_mul_f32_e32 v100, v78, v82
	v_mul_f32_e32 v101, v79, v83
	v_mul_f32_e32 v104, v76, v80
	v_mul_f32_e32 v105, v77, v81
	v_mul_f32_e32 v112, v86, v110
	v_mul_f32_e32 v113, v87, v111
	v_mul_f32_e32 v102, v114, v106
	v_mul_f32_e32 v103, v115, v107
	v_mul_f32_e32 v106, v116, v122
	v_mul_f32_e32 v107, v117, v123
	v_mul_f32_e32 v110, v74, v120
	v_mul_f32_e32 v111, v75, v121
	v_mul_f32_e32 v114, v72, v118
	v_mul_f32_e32 v115, v73, v119
	s_and_saveexec_b64 s[28:29], s[92:93]
	s_xor_b64 s[28:29], exec, s[28:29]
	v_add_f32_e32 v82, v100, v112
	v_add_f32_e32 v83, v101, v113
	v_add_f32_e32 v80, v104, v108
	v_add_f32_e32 v81, v105, v109
	v_add_f32_e32 v86, v110, v106
	v_add_f32_e32 v87, v111, v107
	v_add_f32_e32 v84, v114, v102
	v_add_f32_e32 v85, v115, v103
	s_andn2_saveexec_b64 s[28:29], s[28:29]
	v_sub_f32_e32 v83, v101, v113
	v_sub_f32_e32 v82, v100, v112
	v_sub_f32_e32 v81, v105, v109
	v_sub_f32_e32 v80, v104, v108
	v_sub_f32_e32 v87, v111, v107
	v_sub_f32_e32 v86, v110, v106
	v_sub_f32_e32 v85, v115, v103
	v_sub_f32_e32 v84, v114, v102
	s_or_b64 exec, exec, s[28:29]
	v_mul_f32_e32 v80, v88, v80
	v_mul_f32_e32 v81, v88, v81
	v_mul_f32_e32 v82, v88, v82
	v_mul_f32_e32 v83, v88, v83
	v_lshl_add_u64 v[100:101], s[10:11], 0, v[92:93]
	v_lshlrev_b32_e32 v102, 1, v144
	v_mov_b32_e32 v103, v145
	v_cvt_pk_bf16_f32 v80, v80, v81
	v_cvt_pk_bf16_f32 v81, v82, v83
	v_mul_f32_e32 v82, v88, v84
	v_mul_f32_e32 v83, v88, v85
	v_mul_f32_e32 v84, v88, v86
	v_mul_f32_e32 v85, v88, v87
	v_lshl_add_u64 v[100:101], v[100:101], 0, v[102:103]
	v_cvt_pk_bf16_f32 v82, v82, v83
	v_cvt_pk_bf16_f32 v83, v84, v85
	global_store_dwordx4 v[100:101], v[80:83], off

; DI void st_bf8(u16* p, f32x4 a, f32x4 b, float sc) {
;   u32x4 u; u.x = pack2(a[0] * sc, a[1] * sc); u.y = pack2(a[2] * sc, a[3] * sc); u.z = pack2(b[0] * sc, b[1] * sc); u.w = pack2(b[2] * sc, b[3] * sc);
;   *(u32x4*)p = u;
;   DI void operator()(const f32x4 (&acc)[2][2][4][2], const pg8::Unit& u, int wr, int wc, int fr_, int fq_) const {
;     ...
;                 else if (gb < 640) st_bf8((u16*)(big + E_CKV) + (size_t)token * 256 + (f8 - 384), v, v1, rinv);
.LBB0_843:
	s_andn2_b64 vcc, exec, s[28:29]
	s_cbranch_vccnz .LBB0_845
	v_lshl_add_u64 v[80:81], s[2:3], 0, v[90:91]
	v_lshl_add_u64 v[84:85], v[152:153], 1, v[80:81]
	v_mul_f32_e32 v80, v76, v88
	v_mul_f32_e32 v81, v77, v88
	v_mul_f32_e32 v82, v78, v88
	v_mul_f32_e32 v83, v79, v88
	v_cvt_pk_bf16_f32 v80, v80, v81
	v_cvt_pk_bf16_f32 v81, v82, v83
	v_mul_f32_e32 v82, v72, v88
	v_mul_f32_e32 v83, v73, v88
	v_mul_f32_e32 v86, v74, v88
	v_mul_f32_e32 v87, v75, v88
	v_add_co_u32_e32 v84, vcc, 0x17ff000, v84
	v_cvt_pk_bf16_f32 v82, v82, v83
	v_cvt_pk_bf16_f32 v83, v86, v87
	v_addc_co_u32_e32 v85, vcc, 0, v85, vcc
	global_store_dwordx4 v[84:85], v[80:83], off offset:3328

; DI void st_bf8(u16* p, f32x4 a, f32x4 b, float sc) {
;   u32x4 u; u.x = pack2(a[0] * sc, a[1] * sc); u.y = pack2(a[2] * sc, a[3] * sc); u.z = pack2(b[0] * sc, b[1] * sc); u.w = pack2(b[2] * sc, b[3] * sc);
;   *(u32x4*)p = u;
;   DI void operator()(const f32x4 (&acc)[2][2][4][2], const pg8::Unit& u, int wr, int wc, int fr_, int fq_) const {
;     ...
;         const int rl = ai * 128 + wr * 64 + m * 16 + fr;
;         const int token = u.pm * 256 + rl;
;         float rinv = 1.f;
;         if (EPI != EPI_RESID) rinv = rinv_tab[slot * 256 + rl];
;         float ssq = 0.f;
; #pragma unroll
;         for (int bj = 0; bj < 2; ++bj)
; #pragma unroll
;           for (int n = 0; n < 2; ++n) {
;             const int fb = u.pn * 256 + bj * 128 + wc * 32 + n * 16;
;             const int f = fb + 4 * fq;
;             const f32x4 v = acc[ai][bj][m][n];
;             if (EPI == EPI_ABIN) {
;               if (n == 0) {
;                 const int gb = u.pn * 256 + bj * 128 + wc * 32; const int f8 = gb + 8 * fq;
;                 const f32x4 v1 = acc[ai][bj][m][1];
;                 if (gb < 384) st_bf8((u16*)(big + E_CQ) + (size_t)token * 384 + f8, v, v1, rinv);
;                 else if (gb < 640) st_bf8((u16*)(big + E_CKV) + (size_t)token * 256 + (f8 - 384), v, v1, rinv);
;                 else if (gb < 672) {
;                   f32x4 a0 = v, a1 = v1;
;                   rope_perm(a0, a1, fq, t_ & 63, tcos, tsin, token & (S_ - 1));
;                   st_bf8((u16*)(big + E_KPE) + (size_t)token * 32 + 8 * fq, a0, a1, rinv);
;                 }
;                 else if (gb < 1184) st_bf8((u16*)(big + E_QNA) + (size_t)token * 512 + (f8 - 672), v, v1, rinv * (0.125f * LOG2E));
;                 else if (gb < 1696) st_bf8((u16*)(big + E_KNA) + (size_t)token * 512 + (f8 - 1184), v, v1, rinv);
;                 else if (gb < 2208) st_bf8((u16*)(big + E_VNAT) + (size_t)token * 512 + (f8 - 1696), v, v1, rinv);
.LBB0_849:
	s_ashr_i32 s15, s13, 31
	s_add_u32 s28, s13, s61
	s_addc_u32 s29, s15, 0
	v_mul_f32_e32 v68, v68, v88
	v_mul_f32_e32 v69, v69, v88
	v_mul_f32_e32 v70, v70, v88
	v_mul_f32_e32 v71, v71, v88
	v_mul_f32_e32 v64, v64, v88
	v_mul_f32_e32 v65, v65, v88
	v_lshl_add_u64 v[72:73], v[144:145], 0, s[28:29]
	v_cvt_pk_bf16_f32 v68, v68, v69
	v_cvt_pk_bf16_f32 v69, v70, v71
	v_cvt_pk_bf16_f32 v70, v64, v65
	v_mul_f32_e32 v64, v66, v88
	v_mul_f32_e32 v65, v67, v88
	v_lshl_add_u64 v[72:73], v[72:73], 1, v[80:81]
	v_cvt_pk_bf16_f32 v71, v64, v65
	global_store_dwordx4 v[72:73], v[68:71], off offset:256
.LBB0_850:
	ds_read_b32 v72, v200 offset:512
	v_add_u32_e32 v82, 0x80, v154
	v_ashrrev_i32_e32 v83, 31, v82
	v_lshlrev_b32_e32 v64, 4, v82
	v_lshlrev_b64 v[80:81], 10, v[82:83]
	s_waitcnt lgkmcnt(0)
	v_mul_f32_e32 v78, 0x3e38aa3b, v72
	v_and_b32_e32 v73, 0xfcf0, v64
	v_lshlrev_b64 v[76:77], 6, v[82:83]
	v_lshlrev_b64 v[74:75], 9, v[82:83]
	s_and_b64 vcc, exec, s[76:77]
	s_mov_b64 s[28:29], -1
	s_cbranch_vccnz .LBB0_874
	s_and_b64 vcc, exec, s[96:97]
	s_cbranch_vccnz .LBB0_871
	s_andn2_b64 vcc, exec, s[40:41]
	s_cbranch_vccnz .LBB0_864
	s_andn2_b64 vcc, exec, s[34:35]
	s_cbranch_vccnz .LBB0_861
	s_andn2_b64 vcc, exec, s[22:23]
	s_cbranch_vccnz .LBB0_858
	s_andn2_b64 vcc, exec, s[20:21]
	s_cbranch_vccnz .LBB0_857
	v_lshl_add_u64 v[64:65], s[2:3], 0, v[80:81]
	v_lshl_add_u64 v[68:69], v[152:153], 1, v[64:65]
	v_mul_f32_e32 v64, v60, v72
	v_mul_f32_e32 v65, v61, v72
	v_mul_f32_e32 v66, v62, v72
	v_mul_f32_e32 v67, v63, v72
	v_cvt_pk_bf16_f32 v64, v64, v65
	v_cvt_pk_bf16_f32 v65, v66, v67
	v_mul_f32_e32 v66, v56, v72
	v_mul_f32_e32 v67, v57, v72
	v_mul_f32_e32 v70, v58, v72
	v_mul_f32_e32 v71, v59, v72
	v_add_co_u32_e32 v68, vcc, 0x69ff000, v68
	v_cvt_pk_bf16_f32 v66, v66, v67
	v_cvt_pk_bf16_f32 v67, v70, v71
	v_addc_co_u32_e32 v69, vcc, 0, v69, vcc
	global_store_dwordx4 v[68:69], v[64:67], off offset:704

; DI void st_bf8(u16* p, f32x4 a, f32x4 b, float sc) {
;   u32x4 u; u.x = pack2(a[0] * sc, a[1] * sc); u.y = pack2(a[2] * sc, a[3] * sc); u.z = pack2(b[0] * sc, b[1] * sc); u.w = pack2(b[2] * sc, b[3] * sc);
;   *(u32x4*)p = u;
;   DI void operator()(const f32x4 (&acc)[2][2][4][2], const pg8::Unit& u, int wr, int wc, int fr_, int fq_) const {
;     ...
;                 else if (gb < 1696) st_bf8((u16*)(big + E_KNA) + (size_t)token * 512 + (f8 - 1184), v, v1, rinv);
.LBB0_858:
	s_andn2_b64 vcc, exec, s[28:29]
	s_cbranch_vccnz .LBB0_860
	v_lshl_add_u64 v[64:65], s[2:3], 0, v[80:81]
	v_lshl_add_u64 v[68:69], v[152:153], 1, v[64:65]
	v_mul_f32_e32 v64, v60, v72
	v_mul_f32_e32 v65, v61, v72
	v_mul_f32_e32 v66, v62, v72
	v_mul_f32_e32 v67, v63, v72
	v_cvt_pk_bf16_f32 v64, v64, v65
	v_cvt_pk_bf16_f32 v65, v66, v67
	v_mul_f32_e32 v66, v56, v72
	v_mul_f32_e32 v67, v57, v72
	v_mul_f32_e32 v70, v58, v72
	v_mul_f32_e32 v71, v59, v72
	v_add_co_u32_e32 v68, vcc, 0x49ff000, v68
	v_cvt_pk_bf16_f32 v66, v66, v67
	v_cvt_pk_bf16_f32 v67, v70, v71
	v_addc_co_u32_e32 v69, vcc, 0, v69, vcc
	global_store_dwordx4 v[68:69], v[64:67], off offset:1728

; DI void st_bf8(u16* p, f32x4 a, f32x4 b, float sc) {
;   u32x4 u; u.x = pack2(a[0] * sc, a[1] * sc); u.y = pack2(a[2] * sc, a[3] * sc); u.z = pack2(b[0] * sc, b[1] * sc); u.w = pack2(b[2] * sc, b[3] * sc);
;   *(u32x4*)p = u;
;   DI void operator()(const f32x4 (&acc)[2][2][4][2], const pg8::Unit& u, int wr, int wc, int fr_, int fq_) const {
;     ...
;                 else if (gb < 1184) st_bf8((u16*)(big + E_QNA) + (size_t)token * 512 + (f8 - 672), v, v1, rinv * (0.125f * LOG2E));
.LBB0_861:
	s_andn2_b64 vcc, exec, s[28:29]
	s_cbranch_vccnz .LBB0_863
	v_lshl_add_u64 v[64:65], s[2:3], 0, v[80:81]
	v_lshl_add_u64 v[68:69], v[152:153], 1, v[64:65]
	v_mul_f32_e32 v64, v60, v78
	v_mul_f32_e32 v65, v61, v78
	v_mul_f32_e32 v66, v62, v78
	v_mul_f32_e32 v67, v63, v78
	v_cvt_pk_bf16_f32 v64, v64, v65
	v_cvt_pk_bf16_f32 v65, v66, v67
	v_mul_f32_e32 v66, v56, v78
	v_mul_f32_e32 v67, v57, v78
	v_mul_f32_e32 v70, v58, v78
	v_mul_f32_e32 v71, v59, v78
	v_add_co_u32_e32 v68, vcc, 0x29ff000, v68
	v_cvt_pk_bf16_f32 v66, v66, v67
	v_cvt_pk_bf16_f32 v67, v70, v71
	v_addc_co_u32_e32 v69, vcc, 0, v69, vcc
	global_store_dwordx4 v[68:69], v[64:67], off offset:2752

; DI void rope_perm(f32x4& a0, f32x4& a1, int fq, int lane, const float* tcos, const float* tsin, int pos) {
;   f32x4 p0, p1;
; #pragma unroll
;   for (int e = 0; e < 4; ++e) { p0[e] = shx(a0[e], 32, lane); p1[e] = shx(a1[e], 32, lane); }
;   const int jb = 8 * (fq & 1);
;   const f32x4 c0 = *(const f32x4*)(tcos + pos * 16 + jb), c1 = *(const f32x4*)(tcos + pos * 16 + jb + 4);
;   const f32x4 s0 = *(const f32x4*)(tsin + pos * 16 + jb), s1 = *(const f32x4*)(tsin + pos * 16 + jb + 4);
;   if (fq < 2) { a0 = a0 * c0 - p0 * s0; a1 = a1 * c1 - p1 * s1; }
;   else        { a0 = a0 * c0 + p0 * s0; a1 = a1 * c1 + p1 * s1; }
; }
;   DI void operator()(const f32x4 (&acc)[2][2][4][2], const pg8::Unit& u, int wr, int wc, int fr_, int fq_) const {
;     ...
;                 else if (gb < 672) {
;                   f32x4 a0 = v, a1 = v1;
;                   rope_perm(a0, a1, fq, t_ & 63, tcos, tsin, token & (S_ - 1));
;                   st_bf8((u16*)(big + E_KPE) + (size_t)token * 32 + 8 * fq, a0, a1, rinv);
;                 }
.LBB0_864:
	s_andn2_b64 vcc, exec, s[28:29]
	s_cbranch_vccnz .LBB0_870
	v_lshlrev_b32_e32 v68, 2, v73
	v_mov_b32_e32 v69, v145
	v_lshl_add_u64 v[64:65], s[4:5], 0, v[68:69]
	v_lshlrev_b32_e32 v70, 2, v199
	v_mov_b32_e32 v71, v145
	v_lshl_add_u64 v[68:69], s[6:7], 0, v[68:69]
	v_lshl_add_u64 v[84:85], v[64:65], 0, v[70:71]
	v_lshl_add_u64 v[86:87], v[68:69], 0, v[70:71]
	global_load_dwordx4 v[64:67], v[84:85], off
	global_load_dwordx4 v[68:71], v[86:87], off
	global_load_dwordx4 v[98:101], v[86:87], off offset:16
	global_load_dwordx4 v[102:105], v[84:85], off offset:16
	ds_bpermute_b32 v86, v198, v60
	ds_bpermute_b32 v90, v198, v56
	ds_bpermute_b32 v87, v198, v61
	ds_bpermute_b32 v91, v198, v57
	ds_bpermute_b32 v94, v198, v62
	ds_bpermute_b32 v106, v198, v58
	ds_bpermute_b32 v95, v198, v63
	ds_bpermute_b32 v107, v198, v59
	s_waitcnt vmcnt(0) lgkmcnt(0)
	v_mul_f32_e32 v92, v68, v86
	v_mul_f32_e32 v93, v69, v87
	v_mul_f32_e32 v84, v62, v66
	v_mul_f32_e32 v85, v63, v67
	v_mul_f32_e32 v88, v60, v64
	v_mul_f32_e32 v89, v61, v65
	v_mul_f32_e32 v96, v70, v94
	v_mul_f32_e32 v97, v71, v95
	v_mul_f32_e32 v86, v98, v90
	v_mul_f32_e32 v87, v99, v91
	v_mul_f32_e32 v90, v100, v106
	v_mul_f32_e32 v91, v101, v107
	v_mul_f32_e32 v94, v58, v104
	v_mul_f32_e32 v95, v59, v105
	v_mul_f32_e32 v98, v56, v102
	v_mul_f32_e32 v99, v57, v103
	s_and_saveexec_b64 s[28:29], s[92:93]
	s_xor_b64 s[28:29], exec, s[28:29]
	v_add_f32_e32 v66, v84, v96
	v_add_f32_e32 v67, v85, v97
	v_add_f32_e32 v64, v88, v92
	v_add_f32_e32 v65, v89, v93
	v_add_f32_e32 v70, v94, v90
	v_add_f32_e32 v71, v95, v91
	v_add_f32_e32 v68, v98, v86
	v_add_f32_e32 v69, v99, v87
	s_andn2_saveexec_b64 s[28:29], s[28:29]
	v_sub_f32_e32 v67, v85, v97
	v_sub_f32_e32 v66, v84, v96
	v_sub_f32_e32 v65, v89, v93
	v_sub_f32_e32 v64, v88, v92
	v_sub_f32_e32 v71, v95, v91
	v_sub_f32_e32 v70, v94, v90
	v_sub_f32_e32 v69, v99, v87
	v_sub_f32_e32 v68, v98, v86
	s_or_b64 exec, exec, s[28:29]
	v_mul_f32_e32 v64, v72, v64
	v_mul_f32_e32 v65, v72, v65
	v_mul_f32_e32 v66, v72, v66
	v_mul_f32_e32 v67, v72, v67
	v_lshl_add_u64 v[84:85], s[10:11], 0, v[76:77]
	v_lshlrev_b32_e32 v86, 1, v144
	v_mov_b32_e32 v87, v145
	v_cvt_pk_bf16_f32 v64, v64, v65
	v_cvt_pk_bf16_f32 v65, v66, v67
	v_mul_f32_e32 v66, v72, v68
	v_mul_f32_e32 v67, v72, v69
	v_mul_f32_e32 v68, v72, v70
	v_mul_f32_e32 v69, v72, v71
	v_lshl_add_u64 v[84:85], v[84:85], 0, v[86:87]
	v_cvt_pk_bf16_f32 v66, v66, v67
	v_cvt_pk_bf16_f32 v67, v68, v69
	global_store_dwordx4 v[84:85], v[64:67], off

; DI void st_bf8(u16* p, f32x4 a, f32x4 b, float sc) {
;   u32x4 u; u.x = pack2(a[0] * sc, a[1] * sc); u.y = pack2(a[2] * sc, a[3] * sc); u.z = pack2(b[0] * sc, b[1] * sc); u.w = pack2(b[2] * sc, b[3] * sc);
;   *(u32x4*)p = u;
;   DI void operator()(const f32x4 (&acc)[2][2][4][2], const pg8::Unit& u, int wr, int wc, int fr_, int fq_) const {
;     ...
;                 else if (gb < 640) st_bf8((u16*)(big + E_CKV) + (size_t)token * 256 + (f8 - 384), v, v1, rinv);
.LBB0_871:
	s_andn2_b64 vcc, exec, s[28:29]
	s_cbranch_vccnz .LBB0_873
	v_lshl_add_u64 v[64:65], s[2:3], 0, v[74:75]
	v_lshl_add_u64 v[68:69], v[152:153], 1, v[64:65]
	v_mul_f32_e32 v64, v60, v72
	v_mul_f32_e32 v65, v61, v72
	v_mul_f32_e32 v66, v62, v72
	v_mul_f32_e32 v67, v63, v72
	v_cvt_pk_bf16_f32 v64, v64, v65
	v_cvt_pk_bf16_f32 v65, v66, v67
	v_mul_f32_e32 v66, v56, v72
	v_mul_f32_e32 v67, v57, v72
	v_mul_f32_e32 v70, v58, v72
	v_mul_f32_e32 v71, v59, v72
	v_add_co_u32_e32 v68, vcc, 0x17ff000, v68
	v_cvt_pk_bf16_f32 v66, v66, v67
	v_cvt_pk_bf16_f32 v67, v70, v71
	v_addc_co_u32_e32 v69, vcc, 0, v69, vcc
	global_store_dwordx4 v[68:69], v[64:67], off offset:3328

; DI void st_bf8(u16* p, f32x4 a, f32x4 b, float sc) {
;   u32x4 u; u.x = pack2(a[0] * sc, a[1] * sc); u.y = pack2(a[2] * sc, a[3] * sc); u.z = pack2(b[0] * sc, b[1] * sc); u.w = pack2(b[2] * sc, b[3] * sc);
;   *(u32x4*)p = u;
;   DI void operator()(const f32x4 (&acc)[2][2][4][2], const pg8::Unit& u, int wr, int wc, int fr_, int fq_) const {
;     ...
;         const int rl = ai * 128 + wr * 64 + m * 16 + fr;
;         const int token = u.pm * 256 + rl;
;         float rinv = 1.f;
;         if (EPI != EPI_RESID) rinv = rinv_tab[slot * 256 + rl];
;         float ssq = 0.f;
; #pragma unroll
;         for (int bj = 0; bj < 2; ++bj)
; #pragma unroll
;           for (int n = 0; n < 2; ++n) {
;             const int fb = u.pn * 256 + bj * 128 + wc * 32 + n * 16;
;             const int f = fb + 4 * fq;
;             const f32x4 v = acc[ai][bj][m][n];
;             if (EPI == EPI_ABIN) {
;               if (n == 0) {
;                 const int gb = u.pn * 256 + bj * 128 + wc * 32; const int f8 = gb + 8 * fq;
;                 const f32x4 v1 = acc[ai][bj][m][1];
;                 if (gb < 384) st_bf8((u16*)(big + E_CQ) + (size_t)token * 384 + f8, v, v1, rinv);
;                 else if (gb < 640) st_bf8((u16*)(big + E_CKV) + (size_t)token * 256 + (f8 - 384), v, v1, rinv);
;                 else if (gb < 672) {
;                   f32x4 a0 = v, a1 = v1;
;                   rope_perm(a0, a1, fq, t_ & 63, tcos, tsin, token & (S_ - 1));
;                   st_bf8((u16*)(big + E_KPE) + (size_t)token * 32 + 8 * fq, a0, a1, rinv);
;                 }
;                 else if (gb < 1184) st_bf8((u16*)(big + E_QNA) + (size_t)token * 512 + (f8 - 672), v, v1, rinv * (0.125f * LOG2E));
;                 else if (gb < 1696) st_bf8((u16*)(big + E_KNA) + (size_t)token * 512 + (f8 - 1184), v, v1, rinv);
;                 else if (gb < 2208) st_bf8((u16*)(big + E_VNAT) + (size_t)token * 512 + (f8 - 1696), v, v1, rinv);
.LBB0_877:
	s_ashr_i32 s15, s13, 31
	s_add_u32 s28, s13, s61
	s_addc_u32 s29, s15, 0
	v_mul_f32_e32 v52, v52, v72
	v_mul_f32_e32 v53, v53, v72
	v_mul_f32_e32 v54, v54, v72
	v_mul_f32_e32 v55, v55, v72
	v_mul_f32_e32 v48, v48, v72
	v_mul_f32_e32 v49, v49, v72
	v_lshl_add_u64 v[56:57], v[144:145], 0, s[28:29]
	v_cvt_pk_bf16_f32 v52, v52, v53
	v_cvt_pk_bf16_f32 v53, v54, v55
	v_cvt_pk_bf16_f32 v54, v48, v49
	v_mul_f32_e32 v48, v50, v72
	v_mul_f32_e32 v49, v51, v72
	v_lshl_add_u64 v[56:57], v[56:57], 1, v[64:65]
	v_cvt_pk_bf16_f32 v55, v48, v49
	global_store_dwordx4 v[56:57], v[52:55], off offset:256
.LBB0_878:
	ds_read_b32 v56, v200 offset:576
	v_add_u32_e32 v66, 0x90, v154
	v_ashrrev_i32_e32 v67, 31, v66
	v_lshlrev_b32_e32 v48, 4, v66
	v_lshlrev_b64 v[64:65], 10, v[66:67]
	s_waitcnt lgkmcnt(0)
	v_mul_f32_e32 v62, 0x3e38aa3b, v56
	v_and_b32_e32 v57, 0xfdf0, v48
	v_lshlrev_b64 v[60:61], 6, v[66:67]
	v_lshlrev_b64 v[58:59], 9, v[66:67]
	s_and_b64 vcc, exec, s[76:77]
	s_mov_b64 s[28:29], -1
	s_cbranch_vccnz .LBB0_902
	s_and_b64 vcc, exec, s[96:97]
	s_cbranch_vccnz .LBB0_899
	s_andn2_b64 vcc, exec, s[40:41]
	s_cbranch_vccnz .LBB0_892
	s_andn2_b64 vcc, exec, s[34:35]
	s_cbranch_vccnz .LBB0_889
	s_andn2_b64 vcc, exec, s[22:23]
	s_cbranch_vccnz .LBB0_886
	s_andn2_b64 vcc, exec, s[20:21]
	s_cbranch_vccnz .LBB0_885
	v_lshl_add_u64 v[48:49], s[2:3], 0, v[64:65]
	v_lshl_add_u64 v[52:53], v[152:153], 1, v[48:49]
	v_mul_f32_e32 v48, v44, v56
	v_mul_f32_e32 v49, v45, v56
	v_mul_f32_e32 v50, v46, v56
	v_mul_f32_e32 v51, v47, v56
	v_cvt_pk_bf16_f32 v48, v48, v49
	v_cvt_pk_bf16_f32 v49, v50, v51
	v_mul_f32_e32 v50, v40, v56
	v_mul_f32_e32 v51, v41, v56
	v_mul_f32_e32 v54, v42, v56
	v_mul_f32_e32 v55, v43, v56
	v_add_co_u32_e32 v52, vcc, 0x69ff000, v52
	v_cvt_pk_bf16_f32 v50, v50, v51
	v_cvt_pk_bf16_f32 v51, v54, v55
	v_addc_co_u32_e32 v53, vcc, 0, v53, vcc
	global_store_dwordx4 v[52:53], v[48:51], off offset:704

; DI void st_bf8(u16* p, f32x4 a, f32x4 b, float sc) {
;   u32x4 u; u.x = pack2(a[0] * sc, a[1] * sc); u.y = pack2(a[2] * sc, a[3] * sc); u.z = pack2(b[0] * sc, b[1] * sc); u.w = pack2(b[2] * sc, b[3] * sc);
;   *(u32x4*)p = u;
;   DI void operator()(const f32x4 (&acc)[2][2][4][2], const pg8::Unit& u, int wr, int wc, int fr_, int fq_) const {
;     ...
;                 else if (gb < 1696) st_bf8((u16*)(big + E_KNA) + (size_t)token * 512 + (f8 - 1184), v, v1, rinv);
.LBB0_886:
	s_andn2_b64 vcc, exec, s[28:29]
	s_cbranch_vccnz .LBB0_888
	v_lshl_add_u64 v[48:49], s[2:3], 0, v[64:65]
	v_lshl_add_u64 v[52:53], v[152:153], 1, v[48:49]
	v_mul_f32_e32 v48, v44, v56
	v_mul_f32_e32 v49, v45, v56
	v_mul_f32_e32 v50, v46, v56
	v_mul_f32_e32 v51, v47, v56
	v_cvt_pk_bf16_f32 v48, v48, v49
	v_cvt_pk_bf16_f32 v49, v50, v51
	v_mul_f32_e32 v50, v40, v56
	v_mul_f32_e32 v51, v41, v56
	v_mul_f32_e32 v54, v42, v56
	v_mul_f32_e32 v55, v43, v56
	v_add_co_u32_e32 v52, vcc, 0x49ff000, v52
	v_cvt_pk_bf16_f32 v50, v50, v51
	v_cvt_pk_bf16_f32 v51, v54, v55
	v_addc_co_u32_e32 v53, vcc, 0, v53, vcc
	global_store_dwordx4 v[52:53], v[48:51], off offset:1728

; DI void st_bf8(u16* p, f32x4 a, f32x4 b, float sc) {
;   u32x4 u; u.x = pack2(a[0] * sc, a[1] * sc); u.y = pack2(a[2] * sc, a[3] * sc); u.z = pack2(b[0] * sc, b[1] * sc); u.w = pack2(b[2] * sc, b[3] * sc);
;   *(u32x4*)p = u;
;   DI void operator()(const f32x4 (&acc)[2][2][4][2], const pg8::Unit& u, int wr, int wc, int fr_, int fq_) const {
;     ...
;                 else if (gb < 1184) st_bf8((u16*)(big + E_QNA) + (size_t)token * 512 + (f8 - 672), v, v1, rinv * (0.125f * LOG2E));
.LBB0_889:
	s_andn2_b64 vcc, exec, s[28:29]
	s_cbranch_vccnz .LBB0_891
	v_lshl_add_u64 v[48:49], s[2:3], 0, v[64:65]
	v_lshl_add_u64 v[52:53], v[152:153], 1, v[48:49]
	v_mul_f32_e32 v48, v44, v62
	v_mul_f32_e32 v49, v45, v62
	v_mul_f32_e32 v50, v46, v62
	v_mul_f32_e32 v51, v47, v62
	v_cvt_pk_bf16_f32 v48, v48, v49
	v_cvt_pk_bf16_f32 v49, v50, v51
	v_mul_f32_e32 v50, v40, v62
	v_mul_f32_e32 v51, v41, v62
	v_mul_f32_e32 v54, v42, v62
	v_mul_f32_e32 v55, v43, v62
	v_add_co_u32_e32 v52, vcc, 0x29ff000, v52
	v_cvt_pk_bf16_f32 v50, v50, v51
	v_cvt_pk_bf16_f32 v51, v54, v55
	v_addc_co_u32_e32 v53, vcc, 0, v53, vcc
	global_store_dwordx4 v[52:53], v[48:51], off offset:2752

; DI void rope_perm(f32x4& a0, f32x4& a1, int fq, int lane, const float* tcos, const float* tsin, int pos) {
;   f32x4 p0, p1;
; #pragma unroll
;   for (int e = 0; e < 4; ++e) { p0[e] = shx(a0[e], 32, lane); p1[e] = shx(a1[e], 32, lane); }
;   const int jb = 8 * (fq & 1);
;   const f32x4 c0 = *(const f32x4*)(tcos + pos * 16 + jb), c1 = *(const f32x4*)(tcos + pos * 16 + jb + 4);
;   const f32x4 s0 = *(const f32x4*)(tsin + pos * 16 + jb), s1 = *(const f32x4*)(tsin + pos * 16 + jb + 4);
;   if (fq < 2) { a0 = a0 * c0 - p0 * s0; a1 = a1 * c1 - p1 * s1; }
;   else        { a0 = a0 * c0 + p0 * s0; a1 = a1 * c1 + p1 * s1; }
; }
;   DI void operator()(const f32x4 (&acc)[2][2][4][2], const pg8::Unit& u, int wr, int wc, int fr_, int fq_) const {
;     ...
;                 else if (gb < 672) {
;                   f32x4 a0 = v, a1 = v1;
;                   rope_perm(a0, a1, fq, t_ & 63, tcos, tsin, token & (S_ - 1));
;                   st_bf8((u16*)(big + E_KPE) + (size_t)token * 32 + 8 * fq, a0, a1, rinv);
;                 }
.LBB0_892:
	s_andn2_b64 vcc, exec, s[28:29]
	s_cbranch_vccnz .LBB0_898
	v_lshlrev_b32_e32 v52, 2, v57
	v_mov_b32_e32 v53, v145
	v_lshl_add_u64 v[48:49], s[4:5], 0, v[52:53]
	v_lshlrev_b32_e32 v54, 2, v199
	v_mov_b32_e32 v55, v145
	v_lshl_add_u64 v[52:53], s[6:7], 0, v[52:53]
	v_lshl_add_u64 v[68:69], v[48:49], 0, v[54:55]
	v_lshl_add_u64 v[70:71], v[52:53], 0, v[54:55]
	global_load_dwordx4 v[48:51], v[68:69], off
	global_load_dwordx4 v[52:55], v[70:71], off
	global_load_dwordx4 v[82:85], v[70:71], off offset:16
	global_load_dwordx4 v[86:89], v[68:69], off offset:16
	ds_bpermute_b32 v70, v198, v44
	ds_bpermute_b32 v74, v198, v40
	ds_bpermute_b32 v71, v198, v45
	ds_bpermute_b32 v75, v198, v41
	ds_bpermute_b32 v78, v198, v46
	ds_bpermute_b32 v90, v198, v42
	ds_bpermute_b32 v79, v198, v47
	ds_bpermute_b32 v91, v198, v43
	s_waitcnt vmcnt(0) lgkmcnt(0)
	v_mul_f32_e32 v76, v52, v70
	v_mul_f32_e32 v77, v53, v71
	v_mul_f32_e32 v68, v46, v50
	v_mul_f32_e32 v69, v47, v51
	v_mul_f32_e32 v72, v44, v48
	v_mul_f32_e32 v73, v45, v49
	v_mul_f32_e32 v80, v54, v78
	v_mul_f32_e32 v81, v55, v79
	v_mul_f32_e32 v70, v82, v74
	v_mul_f32_e32 v71, v83, v75
	v_mul_f32_e32 v74, v84, v90
	v_mul_f32_e32 v75, v85, v91
	v_mul_f32_e32 v78, v42, v88
	v_mul_f32_e32 v79, v43, v89
	v_mul_f32_e32 v82, v40, v86
	v_mul_f32_e32 v83, v41, v87
	s_and_saveexec_b64 s[28:29], s[92:93]
	s_xor_b64 s[28:29], exec, s[28:29]
	v_add_f32_e32 v50, v68, v80
	v_add_f32_e32 v51, v69, v81
	v_add_f32_e32 v48, v72, v76
	v_add_f32_e32 v49, v73, v77
	v_add_f32_e32 v54, v78, v74
	v_add_f32_e32 v55, v79, v75
	v_add_f32_e32 v52, v82, v70
	v_add_f32_e32 v53, v83, v71
	s_andn2_saveexec_b64 s[28:29], s[28:29]
	v_sub_f32_e32 v51, v69, v81
	v_sub_f32_e32 v50, v68, v80
	v_sub_f32_e32 v49, v73, v77
	v_sub_f32_e32 v48, v72, v76
	v_sub_f32_e32 v55, v79, v75
	v_sub_f32_e32 v54, v78, v74
	v_sub_f32_e32 v53, v83, v71
	v_sub_f32_e32 v52, v82, v70
	s_or_b64 exec, exec, s[28:29]
	v_mul_f32_e32 v48, v56, v48
	v_mul_f32_e32 v49, v56, v49
	v_mul_f32_e32 v50, v56, v50
	v_mul_f32_e32 v51, v56, v51
	v_lshl_add_u64 v[68:69], s[10:11], 0, v[60:61]
	v_lshlrev_b32_e32 v70, 1, v144
	v_mov_b32_e32 v71, v145
	v_cvt_pk_bf16_f32 v48, v48, v49
	v_cvt_pk_bf16_f32 v49, v50, v51
	v_mul_f32_e32 v50, v56, v52
	v_mul_f32_e32 v51, v56, v53
	v_mul_f32_e32 v52, v56, v54
	v_mul_f32_e32 v53, v56, v55
	v_lshl_add_u64 v[68:69], v[68:69], 0, v[70:71]
	v_cvt_pk_bf16_f32 v50, v50, v51
	v_cvt_pk_bf16_f32 v51, v52, v53
	global_store_dwordx4 v[68:69], v[48:51], off

; DI void st_bf8(u16* p, f32x4 a, f32x4 b, float sc) {
;   u32x4 u; u.x = pack2(a[0] * sc, a[1] * sc); u.y = pack2(a[2] * sc, a[3] * sc); u.z = pack2(b[0] * sc, b[1] * sc); u.w = pack2(b[2] * sc, b[3] * sc);
;   *(u32x4*)p = u;
;   DI void operator()(const f32x4 (&acc)[2][2][4][2], const pg8::Unit& u, int wr, int wc, int fr_, int fq_) const {
;     ...
;                 else if (gb < 640) st_bf8((u16*)(big + E_CKV) + (size_t)token * 256 + (f8 - 384), v, v1, rinv);
.LBB0_899:
	s_andn2_b64 vcc, exec, s[28:29]
	s_cbranch_vccnz .LBB0_901
	v_lshl_add_u64 v[48:49], s[2:3], 0, v[58:59]
	v_lshl_add_u64 v[52:53], v[152:153], 1, v[48:49]
	v_mul_f32_e32 v48, v44, v56
	v_mul_f32_e32 v49, v45, v56
	v_mul_f32_e32 v50, v46, v56
	v_mul_f32_e32 v51, v47, v56
	v_cvt_pk_bf16_f32 v48, v48, v49
	v_cvt_pk_bf16_f32 v49, v50, v51
	v_mul_f32_e32 v50, v40, v56
	v_mul_f32_e32 v51, v41, v56
	v_mul_f32_e32 v54, v42, v56
	v_mul_f32_e32 v55, v43, v56
	v_add_co_u32_e32 v52, vcc, 0x17ff000, v52
	v_cvt_pk_bf16_f32 v50, v50, v51
	v_cvt_pk_bf16_f32 v51, v54, v55
	v_addc_co_u32_e32 v53, vcc, 0, v53, vcc
	global_store_dwordx4 v[52:53], v[48:51], off offset:3328

; DI void st_bf8(u16* p, f32x4 a, f32x4 b, float sc) {
;   u32x4 u; u.x = pack2(a[0] * sc, a[1] * sc); u.y = pack2(a[2] * sc, a[3] * sc); u.z = pack2(b[0] * sc, b[1] * sc); u.w = pack2(b[2] * sc, b[3] * sc);
;   *(u32x4*)p = u;
;   DI void operator()(const f32x4 (&acc)[2][2][4][2], const pg8::Unit& u, int wr, int wc, int fr_, int fq_) const {
;     ...
;         const int rl = ai * 128 + wr * 64 + m * 16 + fr;
;         const int token = u.pm * 256 + rl;
;         float rinv = 1.f;
;         if (EPI != EPI_RESID) rinv = rinv_tab[slot * 256 + rl];
;         float ssq = 0.f;
; #pragma unroll
;         for (int bj = 0; bj < 2; ++bj)
; #pragma unroll
;           for (int n = 0; n < 2; ++n) {
;             const int fb = u.pn * 256 + bj * 128 + wc * 32 + n * 16;
;             const int f = fb + 4 * fq;
;             const f32x4 v = acc[ai][bj][m][n];
;             if (EPI == EPI_ABIN) {
;               if (n == 0) {
;                 const int gb = u.pn * 256 + bj * 128 + wc * 32; const int f8 = gb + 8 * fq;
;                 const f32x4 v1 = acc[ai][bj][m][1];
;                 if (gb < 384) st_bf8((u16*)(big + E_CQ) + (size_t)token * 384 + f8, v, v1, rinv);
;                 else if (gb < 640) st_bf8((u16*)(big + E_CKV) + (size_t)token * 256 + (f8 - 384), v, v1, rinv);
;                 else if (gb < 672) {
;                   f32x4 a0 = v, a1 = v1;
;                   rope_perm(a0, a1, fq, t_ & 63, tcos, tsin, token & (S_ - 1));
;                   st_bf8((u16*)(big + E_KPE) + (size_t)token * 32 + 8 * fq, a0, a1, rinv);
;                 }
;                 else if (gb < 1184) st_bf8((u16*)(big + E_QNA) + (size_t)token * 512 + (f8 - 672), v, v1, rinv * (0.125f * LOG2E));
;                 else if (gb < 1696) st_bf8((u16*)(big + E_KNA) + (size_t)token * 512 + (f8 - 1184), v, v1, rinv);
;                 else if (gb < 2208) st_bf8((u16*)(big + E_VNAT) + (size_t)token * 512 + (f8 - 1696), v, v1, rinv);
.LBB0_905:
	s_ashr_i32 s15, s13, 31
	s_add_u32 s28, s13, s61
	s_addc_u32 s29, s15, 0
	v_mul_f32_e32 v36, v36, v56
	v_mul_f32_e32 v37, v37, v56
	v_mul_f32_e32 v38, v38, v56
	v_mul_f32_e32 v39, v39, v56
	v_mul_f32_e32 v32, v32, v56
	v_mul_f32_e32 v33, v33, v56
	v_lshl_add_u64 v[40:41], v[144:145], 0, s[28:29]
	v_cvt_pk_bf16_f32 v36, v36, v37
	v_cvt_pk_bf16_f32 v37, v38, v39
	v_cvt_pk_bf16_f32 v38, v32, v33
	v_mul_f32_e32 v32, v34, v56
	v_mul_f32_e32 v33, v35, v56
	v_lshl_add_u64 v[40:41], v[40:41], 1, v[48:49]
	v_cvt_pk_bf16_f32 v39, v32, v33
	global_store_dwordx4 v[40:41], v[36:39], off offset:256
.LBB0_906:
	ds_read_b32 v40, v200 offset:640
	v_add_u32_e32 v50, 0xa0, v154
	v_ashrrev_i32_e32 v51, 31, v50
	v_lshlrev_b32_e32 v32, 4, v50
	v_lshlrev_b64 v[48:49], 10, v[50:51]
	s_waitcnt lgkmcnt(0)
	v_mul_f32_e32 v46, 0x3e38aa3b, v40
	v_and_b32_e32 v41, 0xfef0, v32
	v_lshlrev_b64 v[44:45], 6, v[50:51]
	v_lshlrev_b64 v[42:43], 9, v[50:51]
	s_and_b64 vcc, exec, s[76:77]
	s_mov_b64 s[28:29], -1
	s_cbranch_vccnz .LBB0_930
	s_and_b64 vcc, exec, s[96:97]
	s_cbranch_vccnz .LBB0_927
	s_andn2_b64 vcc, exec, s[40:41]
	s_cbranch_vccnz .LBB0_920
	s_andn2_b64 vcc, exec, s[34:35]
	s_cbranch_vccnz .LBB0_917
	s_andn2_b64 vcc, exec, s[22:23]
	s_cbranch_vccnz .LBB0_914
	s_andn2_b64 vcc, exec, s[20:21]
	s_cbranch_vccnz .LBB0_913
	v_lshl_add_u64 v[32:33], s[2:3], 0, v[48:49]
	v_lshl_add_u64 v[36:37], v[152:153], 1, v[32:33]
	v_mul_f32_e32 v32, v28, v40
	v_mul_f32_e32 v33, v29, v40
	v_mul_f32_e32 v34, v30, v40
	v_mul_f32_e32 v35, v31, v40
	v_cvt_pk_bf16_f32 v32, v32, v33
	v_cvt_pk_bf16_f32 v33, v34, v35
	v_mul_f32_e32 v34, v24, v40
	v_mul_f32_e32 v35, v25, v40
	v_mul_f32_e32 v38, v26, v40
	v_mul_f32_e32 v39, v27, v40
	v_add_co_u32_e32 v36, vcc, 0x69ff000, v36
	v_cvt_pk_bf16_f32 v34, v34, v35
	v_cvt_pk_bf16_f32 v35, v38, v39
	v_addc_co_u32_e32 v37, vcc, 0, v37, vcc
	global_store_dwordx4 v[36:37], v[32:35], off offset:704

; DI void st_bf8(u16* p, f32x4 a, f32x4 b, float sc) {
;   u32x4 u; u.x = pack2(a[0] * sc, a[1] * sc); u.y = pack2(a[2] * sc, a[3] * sc); u.z = pack2(b[0] * sc, b[1] * sc); u.w = pack2(b[2] * sc, b[3] * sc);
;   *(u32x4*)p = u;
;   DI void operator()(const f32x4 (&acc)[2][2][4][2], const pg8::Unit& u, int wr, int wc, int fr_, int fq_) const {
;     ...
;                 else if (gb < 1696) st_bf8((u16*)(big + E_KNA) + (size_t)token * 512 + (f8 - 1184), v, v1, rinv);
.LBB0_914:
	s_andn2_b64 vcc, exec, s[28:29]
	s_cbranch_vccnz .LBB0_916
	v_lshl_add_u64 v[32:33], s[2:3], 0, v[48:49]
	v_lshl_add_u64 v[36:37], v[152:153], 1, v[32:33]
	v_mul_f32_e32 v32, v28, v40
	v_mul_f32_e32 v33, v29, v40
	v_mul_f32_e32 v34, v30, v40
	v_mul_f32_e32 v35, v31, v40
	v_cvt_pk_bf16_f32 v32, v32, v33
	v_cvt_pk_bf16_f32 v33, v34, v35
	v_mul_f32_e32 v34, v24, v40
	v_mul_f32_e32 v35, v25, v40
	v_mul_f32_e32 v38, v26, v40
	v_mul_f32_e32 v39, v27, v40
	v_add_co_u32_e32 v36, vcc, 0x49ff000, v36
	v_cvt_pk_bf16_f32 v34, v34, v35
	v_cvt_pk_bf16_f32 v35, v38, v39
	v_addc_co_u32_e32 v37, vcc, 0, v37, vcc
	global_store_dwordx4 v[36:37], v[32:35], off offset:1728

; DI void st_bf8(u16* p, f32x4 a, f32x4 b, float sc) {
;   u32x4 u; u.x = pack2(a[0] * sc, a[1] * sc); u.y = pack2(a[2] * sc, a[3] * sc); u.z = pack2(b[0] * sc, b[1] * sc); u.w = pack2(b[2] * sc, b[3] * sc);
;   *(u32x4*)p = u;
;   DI void operator()(const f32x4 (&acc)[2][2][4][2], const pg8::Unit& u, int wr, int wc, int fr_, int fq_) const {
;     ...
;                 else if (gb < 1184) st_bf8((u16*)(big + E_QNA) + (size_t)token * 512 + (f8 - 672), v, v1, rinv * (0.125f * LOG2E));
.LBB0_917:
	s_andn2_b64 vcc, exec, s[28:29]
	s_cbranch_vccnz .LBB0_919
	v_lshl_add_u64 v[32:33], s[2:3], 0, v[48:49]
	v_lshl_add_u64 v[36:37], v[152:153], 1, v[32:33]
	v_mul_f32_e32 v32, v28, v46
	v_mul_f32_e32 v33, v29, v46
	v_mul_f32_e32 v34, v30, v46
	v_mul_f32_e32 v35, v31, v46
	v_cvt_pk_bf16_f32 v32, v32, v33
	v_cvt_pk_bf16_f32 v33, v34, v35
	v_mul_f32_e32 v34, v24, v46
	v_mul_f32_e32 v35, v25, v46
	v_mul_f32_e32 v38, v26, v46
	v_mul_f32_e32 v39, v27, v46
	v_add_co_u32_e32 v36, vcc, 0x29ff000, v36
	v_cvt_pk_bf16_f32 v34, v34, v35
	v_cvt_pk_bf16_f32 v35, v38, v39
	v_addc_co_u32_e32 v37, vcc, 0, v37, vcc
	global_store_dwordx4 v[36:37], v[32:35], off offset:2752

; DI void rope_perm(f32x4& a0, f32x4& a1, int fq, int lane, const float* tcos, const float* tsin, int pos) {
;   f32x4 p0, p1;
; #pragma unroll
;   for (int e = 0; e < 4; ++e) { p0[e] = shx(a0[e], 32, lane); p1[e] = shx(a1[e], 32, lane); }
;   const int jb = 8 * (fq & 1);
;   const f32x4 c0 = *(const f32x4*)(tcos + pos * 16 + jb), c1 = *(const f32x4*)(tcos + pos * 16 + jb + 4);
;   const f32x4 s0 = *(const f32x4*)(tsin + pos * 16 + jb), s1 = *(const f32x4*)(tsin + pos * 16 + jb + 4);
;   if (fq < 2) { a0 = a0 * c0 - p0 * s0; a1 = a1 * c1 - p1 * s1; }
;   else        { a0 = a0 * c0 + p0 * s0; a1 = a1 * c1 + p1 * s1; }
; }
;   DI void operator()(const f32x4 (&acc)[2][2][4][2], const pg8::Unit& u, int wr, int wc, int fr_, int fq_) const {
;     ...
;                 else if (gb < 672) {
;                   f32x4 a0 = v, a1 = v1;
;                   rope_perm(a0, a1, fq, t_ & 63, tcos, tsin, token & (S_ - 1));
;                   st_bf8((u16*)(big + E_KPE) + (size_t)token * 32 + 8 * fq, a0, a1, rinv);
;                 }
.LBB0_920:
	s_andn2_b64 vcc, exec, s[28:29]
	s_cbranch_vccnz .LBB0_926
	v_lshlrev_b32_e32 v36, 2, v41
	v_mov_b32_e32 v37, v145
	v_lshl_add_u64 v[32:33], s[4:5], 0, v[36:37]
	v_lshlrev_b32_e32 v38, 2, v199
	v_mov_b32_e32 v39, v145
	v_lshl_add_u64 v[36:37], s[6:7], 0, v[36:37]
	v_lshl_add_u64 v[52:53], v[32:33], 0, v[38:39]
	v_lshl_add_u64 v[54:55], v[36:37], 0, v[38:39]
	global_load_dwordx4 v[32:35], v[52:53], off
	global_load_dwordx4 v[36:39], v[54:55], off
	global_load_dwordx4 v[66:69], v[54:55], off offset:16
	global_load_dwordx4 v[70:73], v[52:53], off offset:16
	ds_bpermute_b32 v54, v198, v28
	ds_bpermute_b32 v58, v198, v24
	ds_bpermute_b32 v55, v198, v29
	ds_bpermute_b32 v59, v198, v25
	ds_bpermute_b32 v62, v198, v30
	ds_bpermute_b32 v74, v198, v26
	ds_bpermute_b32 v63, v198, v31
	ds_bpermute_b32 v75, v198, v27
	s_waitcnt vmcnt(0) lgkmcnt(0)
	v_mul_f32_e32 v60, v36, v54
	v_mul_f32_e32 v61, v37, v55
	v_mul_f32_e32 v52, v30, v34
	v_mul_f32_e32 v53, v31, v35
	v_mul_f32_e32 v56, v28, v32
	v_mul_f32_e32 v57, v29, v33
	v_mul_f32_e32 v64, v38, v62
	v_mul_f32_e32 v65, v39, v63
	v_mul_f32_e32 v54, v66, v58
	v_mul_f32_e32 v55, v67, v59
	v_mul_f32_e32 v58, v68, v74
	v_mul_f32_e32 v59, v69, v75
	v_mul_f32_e32 v62, v26, v72
	v_mul_f32_e32 v63, v27, v73
	v_mul_f32_e32 v66, v24, v70
	v_mul_f32_e32 v67, v25, v71
	s_and_saveexec_b64 s[28:29], s[92:93]
	s_xor_b64 s[28:29], exec, s[28:29]
	v_add_f32_e32 v34, v52, v64
	v_add_f32_e32 v35, v53, v65
	v_add_f32_e32 v32, v56, v60
	v_add_f32_e32 v33, v57, v61
	v_add_f32_e32 v38, v62, v58
	v_add_f32_e32 v39, v63, v59
	v_add_f32_e32 v36, v66, v54
	v_add_f32_e32 v37, v67, v55
	s_andn2_saveexec_b64 s[28:29], s[28:29]
	v_sub_f32_e32 v35, v53, v65
	v_sub_f32_e32 v34, v52, v64
	v_sub_f32_e32 v33, v57, v61
	v_sub_f32_e32 v32, v56, v60
	v_sub_f32_e32 v39, v63, v59
	v_sub_f32_e32 v38, v62, v58
	v_sub_f32_e32 v37, v67, v55
	v_sub_f32_e32 v36, v66, v54
	s_or_b64 exec, exec, s[28:29]
	v_mul_f32_e32 v32, v40, v32
	v_mul_f32_e32 v33, v40, v33
	v_mul_f32_e32 v34, v40, v34
	v_mul_f32_e32 v35, v40, v35
	v_lshl_add_u64 v[52:53], s[10:11], 0, v[44:45]
	v_lshlrev_b32_e32 v54, 1, v144
	v_mov_b32_e32 v55, v145
	v_cvt_pk_bf16_f32 v32, v32, v33
	v_cvt_pk_bf16_f32 v33, v34, v35
	v_mul_f32_e32 v34, v40, v36
	v_mul_f32_e32 v35, v40, v37
	v_mul_f32_e32 v36, v40, v38
	v_mul_f32_e32 v37, v40, v39
	v_lshl_add_u64 v[52:53], v[52:53], 0, v[54:55]
	v_cvt_pk_bf16_f32 v34, v34, v35
	v_cvt_pk_bf16_f32 v35, v36, v37
	global_store_dwordx4 v[52:53], v[32:35], off

; DI void st_bf8(u16* p, f32x4 a, f32x4 b, float sc) {
;   u32x4 u; u.x = pack2(a[0] * sc, a[1] * sc); u.y = pack2(a[2] * sc, a[3] * sc); u.z = pack2(b[0] * sc, b[1] * sc); u.w = pack2(b[2] * sc, b[3] * sc);
;   *(u32x4*)p = u;
;   DI void operator()(const f32x4 (&acc)[2][2][4][2], const pg8::Unit& u, int wr, int wc, int fr_, int fq_) const {
;     ...
;                 else if (gb < 640) st_bf8((u16*)(big + E_CKV) + (size_t)token * 256 + (f8 - 384), v, v1, rinv);
.LBB0_927:
	s_andn2_b64 vcc, exec, s[28:29]
	s_cbranch_vccnz .LBB0_929
	v_lshl_add_u64 v[32:33], s[2:3], 0, v[42:43]
	v_lshl_add_u64 v[36:37], v[152:153], 1, v[32:33]
	v_mul_f32_e32 v32, v28, v40
	v_mul_f32_e32 v33, v29, v40
	v_mul_f32_e32 v34, v30, v40
	v_mul_f32_e32 v35, v31, v40
	v_cvt_pk_bf16_f32 v32, v32, v33
	v_cvt_pk_bf16_f32 v33, v34, v35
	v_mul_f32_e32 v34, v24, v40
	v_mul_f32_e32 v35, v25, v40
	v_mul_f32_e32 v38, v26, v40
	v_mul_f32_e32 v39, v27, v40
	v_add_co_u32_e32 v36, vcc, 0x17ff000, v36
	v_cvt_pk_bf16_f32 v34, v34, v35
	v_cvt_pk_bf16_f32 v35, v38, v39
	v_addc_co_u32_e32 v37, vcc, 0, v37, vcc
	global_store_dwordx4 v[36:37], v[32:35], off offset:3328

; DI void st_bf8(u16* p, f32x4 a, f32x4 b, float sc) {
;   u32x4 u; u.x = pack2(a[0] * sc, a[1] * sc); u.y = pack2(a[2] * sc, a[3] * sc); u.z = pack2(b[0] * sc, b[1] * sc); u.w = pack2(b[2] * sc, b[3] * sc);
;   *(u32x4*)p = u;
;   DI void operator()(const f32x4 (&acc)[2][2][4][2], const pg8::Unit& u, int wr, int wc, int fr_, int fq_) const {
;     ...
;         const int rl = ai * 128 + wr * 64 + m * 16 + fr;
;         const int token = u.pm * 256 + rl;
;         float rinv = 1.f;
;         if (EPI != EPI_RESID) rinv = rinv_tab[slot * 256 + rl];
;         float ssq = 0.f;
; #pragma unroll
;         for (int bj = 0; bj < 2; ++bj)
; #pragma unroll
;           for (int n = 0; n < 2; ++n) {
;             const int fb = u.pn * 256 + bj * 128 + wc * 32 + n * 16;
;             const int f = fb + 4 * fq;
;             const f32x4 v = acc[ai][bj][m][n];
;             if (EPI == EPI_ABIN) {
;               if (n == 0) {
;                 const int gb = u.pn * 256 + bj * 128 + wc * 32; const int f8 = gb + 8 * fq;
;                 const f32x4 v1 = acc[ai][bj][m][1];
;                 if (gb < 384) st_bf8((u16*)(big + E_CQ) + (size_t)token * 384 + f8, v, v1, rinv);
;                 else if (gb < 640) st_bf8((u16*)(big + E_CKV) + (size_t)token * 256 + (f8 - 384), v, v1, rinv);
;                 else if (gb < 672) {
;                   f32x4 a0 = v, a1 = v1;
;                   rope_perm(a0, a1, fq, t_ & 63, tcos, tsin, token & (S_ - 1));
;                   st_bf8((u16*)(big + E_KPE) + (size_t)token * 32 + 8 * fq, a0, a1, rinv);
;                 }
;                 else if (gb < 1184) st_bf8((u16*)(big + E_QNA) + (size_t)token * 512 + (f8 - 672), v, v1, rinv * (0.125f * LOG2E));
;                 else if (gb < 1696) st_bf8((u16*)(big + E_KNA) + (size_t)token * 512 + (f8 - 1184), v, v1, rinv);
;                 else if (gb < 2208) st_bf8((u16*)(big + E_VNAT) + (size_t)token * 512 + (f8 - 1696), v, v1, rinv);
.LBB0_933:
	s_ashr_i32 s15, s13, 31
	s_add_u32 s28, s13, s61
	s_addc_u32 s29, s15, 0
	v_mul_f32_e32 v20, v20, v40
	v_mul_f32_e32 v21, v21, v40
	v_mul_f32_e32 v22, v22, v40
	v_mul_f32_e32 v23, v23, v40
	v_mul_f32_e32 v16, v16, v40
	v_mul_f32_e32 v17, v17, v40
	v_lshl_add_u64 v[24:25], v[144:145], 0, s[28:29]
	v_cvt_pk_bf16_f32 v20, v20, v21
	v_cvt_pk_bf16_f32 v21, v22, v23
	v_cvt_pk_bf16_f32 v22, v16, v17
	v_mul_f32_e32 v16, v18, v40
	v_mul_f32_e32 v17, v19, v40
	v_lshl_add_u64 v[24:25], v[24:25], 1, v[32:33]
	v_cvt_pk_bf16_f32 v23, v16, v17
	global_store_dwordx4 v[24:25], v[20:23], off offset:256
.LBB0_934:
	ds_read_b32 v24, v200 offset:704
	v_add_u32_e32 v34, 0xb0, v154
	v_ashrrev_i32_e32 v35, 31, v34
	v_lshlrev_b32_e32 v16, 4, v34
	v_lshlrev_b64 v[32:33], 10, v[34:35]
	s_waitcnt lgkmcnt(0)
	v_mul_f32_e32 v30, 0x3e38aa3b, v24
	v_and_b32_e32 v25, 0xfff0, v16
	v_lshlrev_b64 v[28:29], 6, v[34:35]
	v_lshlrev_b64 v[26:27], 9, v[34:35]
	s_and_b64 vcc, exec, s[76:77]
	s_mov_b64 s[28:29], -1
	s_cbranch_vccnz .LBB0_958
	s_and_b64 vcc, exec, s[96:97]
	s_cbranch_vccnz .LBB0_955
	s_andn2_b64 vcc, exec, s[40:41]
	s_cbranch_vccnz .LBB0_948
	s_andn2_b64 vcc, exec, s[34:35]
	s_cbranch_vccnz .LBB0_945
	s_andn2_b64 vcc, exec, s[22:23]
	s_mov_b64 s[22:23], -1
	s_cbranch_vccnz .LBB0_942
	s_andn2_b64 vcc, exec, s[20:21]
	s_cbranch_vccnz .LBB0_941
	v_lshl_add_u64 v[16:17], s[2:3], 0, v[32:33]
	v_lshl_add_u64 v[20:21], v[152:153], 1, v[16:17]
	v_mul_f32_e32 v16, v12, v24
	v_mul_f32_e32 v17, v13, v24
	v_mul_f32_e32 v18, v14, v24
	v_mul_f32_e32 v19, v15, v24
	v_cvt_pk_bf16_f32 v16, v16, v17
	v_cvt_pk_bf16_f32 v17, v18, v19
	v_mul_f32_e32 v18, v8, v24
	v_mul_f32_e32 v19, v9, v24
	v_mul_f32_e32 v22, v10, v24
	v_mul_f32_e32 v23, v11, v24
	v_add_co_u32_e32 v20, vcc, 0x69ff000, v20
	v_cvt_pk_bf16_f32 v18, v18, v19
	v_cvt_pk_bf16_f32 v19, v22, v23
	v_addc_co_u32_e32 v21, vcc, 0, v21, vcc
	global_store_dwordx4 v[20:21], v[16:19], off offset:704

; DI void st_bf8(u16* p, f32x4 a, f32x4 b, float sc) {
;   u32x4 u; u.x = pack2(a[0] * sc, a[1] * sc); u.y = pack2(a[2] * sc, a[3] * sc); u.z = pack2(b[0] * sc, b[1] * sc); u.w = pack2(b[2] * sc, b[3] * sc);
;   *(u32x4*)p = u;
;   DI void operator()(const f32x4 (&acc)[2][2][4][2], const pg8::Unit& u, int wr, int wc, int fr_, int fq_) const {
;     ...
;                 else if (gb < 1696) st_bf8((u16*)(big + E_KNA) + (size_t)token * 512 + (f8 - 1184), v, v1, rinv);
.LBB0_942:
	s_andn2_b64 vcc, exec, s[22:23]
	s_cbranch_vccnz .LBB0_944
	v_lshl_add_u64 v[16:17], s[2:3], 0, v[32:33]
	v_lshl_add_u64 v[20:21], v[152:153], 1, v[16:17]
	v_mul_f32_e32 v16, v12, v24
	v_mul_f32_e32 v17, v13, v24
	v_mul_f32_e32 v18, v14, v24
	v_mul_f32_e32 v19, v15, v24
	v_cvt_pk_bf16_f32 v16, v16, v17
	v_cvt_pk_bf16_f32 v17, v18, v19
	v_mul_f32_e32 v18, v8, v24
	v_mul_f32_e32 v19, v9, v24
	v_mul_f32_e32 v22, v10, v24
	v_mul_f32_e32 v23, v11, v24
	v_add_co_u32_e32 v20, vcc, 0x49ff000, v20
	v_cvt_pk_bf16_f32 v18, v18, v19
	v_cvt_pk_bf16_f32 v19, v22, v23
	v_addc_co_u32_e32 v21, vcc, 0, v21, vcc
	global_store_dwordx4 v[20:21], v[16:19], off offset:1728

; DI void st_bf8(u16* p, f32x4 a, f32x4 b, float sc) {
;   u32x4 u; u.x = pack2(a[0] * sc, a[1] * sc); u.y = pack2(a[2] * sc, a[3] * sc); u.z = pack2(b[0] * sc, b[1] * sc); u.w = pack2(b[2] * sc, b[3] * sc);
;   *(u32x4*)p = u;
;   DI void operator()(const f32x4 (&acc)[2][2][4][2], const pg8::Unit& u, int wr, int wc, int fr_, int fq_) const {
;     ...
;                 else if (gb < 1184) st_bf8((u16*)(big + E_QNA) + (size_t)token * 512 + (f8 - 672), v, v1, rinv * (0.125f * LOG2E));
.LBB0_945:
	s_andn2_b64 vcc, exec, s[28:29]
	s_cbranch_vccnz .LBB0_947
	v_lshl_add_u64 v[16:17], s[2:3], 0, v[32:33]
	v_lshl_add_u64 v[20:21], v[152:153], 1, v[16:17]
	v_mul_f32_e32 v16, v12, v30
	v_mul_f32_e32 v17, v13, v30
	v_mul_f32_e32 v18, v14, v30
	v_mul_f32_e32 v19, v15, v30
	v_cvt_pk_bf16_f32 v16, v16, v17
	v_cvt_pk_bf16_f32 v17, v18, v19
	v_mul_f32_e32 v18, v8, v30
	v_mul_f32_e32 v19, v9, v30
	v_mul_f32_e32 v22, v10, v30
	v_mul_f32_e32 v23, v11, v30
	v_add_co_u32_e32 v20, vcc, 0x29ff000, v20
	v_cvt_pk_bf16_f32 v18, v18, v19
	v_cvt_pk_bf16_f32 v19, v22, v23
	v_addc_co_u32_e32 v21, vcc, 0, v21, vcc
	global_store_dwordx4 v[20:21], v[16:19], off offset:2752

; DI void rope_perm(f32x4& a0, f32x4& a1, int fq, int lane, const float* tcos, const float* tsin, int pos) {
;   f32x4 p0, p1;
; #pragma unroll
;   for (int e = 0; e < 4; ++e) { p0[e] = shx(a0[e], 32, lane); p1[e] = shx(a1[e], 32, lane); }
;   const int jb = 8 * (fq & 1);
;   const f32x4 c0 = *(const f32x4*)(tcos + pos * 16 + jb), c1 = *(const f32x4*)(tcos + pos * 16 + jb + 4);
;   const f32x4 s0 = *(const f32x4*)(tsin + pos * 16 + jb), s1 = *(const f32x4*)(tsin + pos * 16 + jb + 4);
;   if (fq < 2) { a0 = a0 * c0 - p0 * s0; a1 = a1 * c1 - p1 * s1; }
;   else        { a0 = a0 * c0 + p0 * s0; a1 = a1 * c1 + p1 * s1; }
; }
;   DI void operator()(const f32x4 (&acc)[2][2][4][2], const pg8::Unit& u, int wr, int wc, int fr_, int fq_) const {
;     ...
;                 else if (gb < 672) {
;                   f32x4 a0 = v, a1 = v1;
;                   rope_perm(a0, a1, fq, t_ & 63, tcos, tsin, token & (S_ - 1));
;                   st_bf8((u16*)(big + E_KPE) + (size_t)token * 32 + 8 * fq, a0, a1, rinv);
;                 }
.LBB0_948:
	s_andn2_b64 vcc, exec, s[28:29]
	s_cbranch_vccnz .LBB0_954
	v_lshlrev_b32_e32 v20, 2, v25
	v_mov_b32_e32 v21, v145
	v_lshl_add_u64 v[16:17], s[4:5], 0, v[20:21]
	v_lshlrev_b32_e32 v22, 2, v199
	v_mov_b32_e32 v23, v145
	v_lshl_add_u64 v[20:21], s[6:7], 0, v[20:21]
	v_lshl_add_u64 v[36:37], v[16:17], 0, v[22:23]
	v_lshl_add_u64 v[38:39], v[20:21], 0, v[22:23]
	global_load_dwordx4 v[16:19], v[36:37], off
	global_load_dwordx4 v[20:23], v[38:39], off
	global_load_dwordx4 v[50:53], v[38:39], off offset:16
	global_load_dwordx4 v[54:57], v[36:37], off offset:16
	ds_bpermute_b32 v38, v198, v12
	ds_bpermute_b32 v42, v198, v8
	ds_bpermute_b32 v39, v198, v13
	ds_bpermute_b32 v43, v198, v9
	ds_bpermute_b32 v46, v198, v14
	ds_bpermute_b32 v58, v198, v10
	ds_bpermute_b32 v47, v198, v15
	ds_bpermute_b32 v59, v198, v11
	s_waitcnt vmcnt(0) lgkmcnt(0)
	v_mul_f32_e32 v44, v20, v38
	v_mul_f32_e32 v45, v21, v39
	v_mul_f32_e32 v36, v14, v18
	v_mul_f32_e32 v37, v15, v19
	v_mul_f32_e32 v40, v12, v16
	v_mul_f32_e32 v41, v13, v17
	v_mul_f32_e32 v48, v22, v46
	v_mul_f32_e32 v49, v23, v47
	v_mul_f32_e32 v38, v50, v42
	v_mul_f32_e32 v39, v51, v43
	v_mul_f32_e32 v42, v52, v58
	v_mul_f32_e32 v43, v53, v59
	v_mul_f32_e32 v46, v10, v56
	v_mul_f32_e32 v47, v11, v57
	v_mul_f32_e32 v50, v8, v54
	v_mul_f32_e32 v51, v9, v55
	s_and_saveexec_b64 s[20:21], s[92:93]
	s_xor_b64 s[20:21], exec, s[20:21]
	v_add_f32_e32 v18, v36, v48
	v_add_f32_e32 v19, v37, v49
	v_add_f32_e32 v16, v40, v44
	v_add_f32_e32 v17, v41, v45
	v_add_f32_e32 v22, v46, v42
	v_add_f32_e32 v23, v47, v43
	v_add_f32_e32 v20, v50, v38
	v_add_f32_e32 v21, v51, v39
	s_andn2_saveexec_b64 s[20:21], s[20:21]
	v_sub_f32_e32 v19, v37, v49
	v_sub_f32_e32 v18, v36, v48
	v_sub_f32_e32 v17, v41, v45
	v_sub_f32_e32 v16, v40, v44
	v_sub_f32_e32 v23, v47, v43
	v_sub_f32_e32 v22, v46, v42
	v_sub_f32_e32 v21, v51, v39
	v_sub_f32_e32 v20, v50, v38
	s_or_b64 exec, exec, s[20:21]
	v_mul_f32_e32 v16, v24, v16
	v_mul_f32_e32 v17, v24, v17
	v_mul_f32_e32 v18, v24, v18
	v_mul_f32_e32 v19, v24, v19
	v_lshl_add_u64 v[36:37], s[10:11], 0, v[28:29]
	v_lshlrev_b32_e32 v38, 1, v144
	v_mov_b32_e32 v39, v145
	v_cvt_pk_bf16_f32 v16, v16, v17
	v_cvt_pk_bf16_f32 v17, v18, v19
	v_mul_f32_e32 v18, v24, v20
	v_mul_f32_e32 v19, v24, v21
	v_mul_f32_e32 v20, v24, v22
	v_mul_f32_e32 v21, v24, v23
	v_lshl_add_u64 v[36:37], v[36:37], 0, v[38:39]
	v_cvt_pk_bf16_f32 v18, v18, v19
	v_cvt_pk_bf16_f32 v19, v20, v21
	global_store_dwordx4 v[36:37], v[16:19], off

; DI void st_bf8(u16* p, f32x4 a, f32x4 b, float sc) {
;   u32x4 u; u.x = pack2(a[0] * sc, a[1] * sc); u.y = pack2(a[2] * sc, a[3] * sc); u.z = pack2(b[0] * sc, b[1] * sc); u.w = pack2(b[2] * sc, b[3] * sc);
;   *(u32x4*)p = u;
;   DI void operator()(const f32x4 (&acc)[2][2][4][2], const pg8::Unit& u, int wr, int wc, int fr_, int fq_) const {
;     ...
;                 else if (gb < 640) st_bf8((u16*)(big + E_CKV) + (size_t)token * 256 + (f8 - 384), v, v1, rinv);
.LBB0_955:
	s_andn2_b64 vcc, exec, s[28:29]
	s_cbranch_vccnz .LBB0_957
	v_lshl_add_u64 v[16:17], s[2:3], 0, v[26:27]
	v_lshl_add_u64 v[20:21], v[152:153], 1, v[16:17]
	v_mul_f32_e32 v16, v12, v24
	v_mul_f32_e32 v17, v13, v24
	v_mul_f32_e32 v18, v14, v24
	v_mul_f32_e32 v19, v15, v24
	v_cvt_pk_bf16_f32 v16, v16, v17
	v_cvt_pk_bf16_f32 v17, v18, v19
	v_mul_f32_e32 v18, v8, v24
	v_mul_f32_e32 v19, v9, v24
	v_mul_f32_e32 v22, v10, v24
	v_mul_f32_e32 v23, v11, v24
	v_add_co_u32_e32 v20, vcc, 0x17ff000, v20
	v_cvt_pk_bf16_f32 v18, v18, v19
	v_cvt_pk_bf16_f32 v19, v22, v23
	v_addc_co_u32_e32 v21, vcc, 0, v21, vcc
	global_store_dwordx4 v[20:21], v[16:19], off offset:3328

; DI void st_bf8(u16* p, f32x4 a, f32x4 b, float sc) {
;   u32x4 u; u.x = pack2(a[0] * sc, a[1] * sc); u.y = pack2(a[2] * sc, a[3] * sc); u.z = pack2(b[0] * sc, b[1] * sc); u.w = pack2(b[2] * sc, b[3] * sc);
;   *(u32x4*)p = u;
;   DI void operator()(const f32x4 (&acc)[2][2][4][2], const pg8::Unit& u, int wr, int wc, int fr_, int fq_) const {
;     ...
;         const int rl = ai * 128 + wr * 64 + m * 16 + fr;
;         const int token = u.pm * 256 + rl;
;         float rinv = 1.f;
;         if (EPI != EPI_RESID) rinv = rinv_tab[slot * 256 + rl];
;         float ssq = 0.f;
; #pragma unroll
;         for (int bj = 0; bj < 2; ++bj)
; #pragma unroll
;           for (int n = 0; n < 2; ++n) {
;             const int fb = u.pn * 256 + bj * 128 + wc * 32 + n * 16;
;             const int f = fb + 4 * fq;
;             const f32x4 v = acc[ai][bj][m][n];
;             if (EPI == EPI_ABIN) {
;               if (n == 0) {
;                 const int gb = u.pn * 256 + bj * 128 + wc * 32; const int f8 = gb + 8 * fq;
;                 const f32x4 v1 = acc[ai][bj][m][1];
;                 if (gb < 384) st_bf8((u16*)(big + E_CQ) + (size_t)token * 384 + f8, v, v1, rinv);
;                 else if (gb < 640) st_bf8((u16*)(big + E_CKV) + (size_t)token * 256 + (f8 - 384), v, v1, rinv);
;                 else if (gb < 672) {
;                   f32x4 a0 = v, a1 = v1;
;                   rope_perm(a0, a1, fq, t_ & 63, tcos, tsin, token & (S_ - 1));
;                   st_bf8((u16*)(big + E_KPE) + (size_t)token * 32 + 8 * fq, a0, a1, rinv);
;                 }
;                 else if (gb < 1184) st_bf8((u16*)(big + E_QNA) + (size_t)token * 512 + (f8 - 672), v, v1, rinv * (0.125f * LOG2E));
;                 else if (gb < 1696) st_bf8((u16*)(big + E_KNA) + (size_t)token * 512 + (f8 - 1184), v, v1, rinv);
;                 else if (gb < 2208) st_bf8((u16*)(big + E_VNAT) + (size_t)token * 512 + (f8 - 1696), v, v1, rinv);
.LBB0_961:
	v_mul_f32_e32 v92, v92, v104
	v_mul_f32_e32 v93, v93, v104
	v_mul_f32_e32 v94, v94, v104
	v_mul_f32_e32 v95, v95, v104
	v_mul_f32_e32 v88, v88, v104
	v_mul_f32_e32 v89, v89, v104
	v_cvt_pk_bf16_f32 v92, v92, v93
	v_cvt_pk_bf16_f32 v93, v94, v95
	v_cvt_pk_bf16_f32 v94, v88, v89
	v_mul_f32_e32 v88, v90, v104
	v_mul_f32_e32 v89, v91, v104
	v_lshl_add_u64 v[98:99], v[150:151], 1, v[96:97]
	v_cvt_pk_bf16_f32 v95, v88, v89
	global_store_dwordx4 v[98:99], v[92:95], off
	s_and_b64 vcc, exec, s[78:79]
	s_mov_b64 s[28:29], -1
	s_cbranch_vccnz .LBB0_820
.LBB0_962:
	s_and_b64 vcc, exec, s[94:95]
	s_cbranch_vccnz .LBB0_982
	s_andn2_b64 vcc, exec, s[44:45]
	s_cbranch_vccnz .LBB0_975
	s_andn2_b64 vcc, exec, s[42:43]
	s_cbranch_vccnz .LBB0_972
	s_andn2_b64 vcc, exec, s[38:39]
	s_cbranch_vccnz .LBB0_969
	s_andn2_b64 vcc, exec, s[36:37]
	s_cbranch_vccnz .LBB0_968
	s_add_i32 s28, s13, s61
	v_lshl_add_u64 v[88:89], s[2:3], 0, v[112:113]
	v_add_u32_e32 v90, s28, v144
	v_mov_b32_e32 v91, v145
	v_lshl_add_u64 v[92:93], v[90:91], 1, v[88:89]
	v_mul_f32_e32 v88, v84, v104
	v_mul_f32_e32 v89, v85, v104
	v_mul_f32_e32 v90, v86, v104
	v_mul_f32_e32 v91, v87, v104
	v_cvt_pk_bf16_f32 v88, v88, v89
	v_cvt_pk_bf16_f32 v89, v90, v91
	v_mul_f32_e32 v90, v80, v104
	v_mul_f32_e32 v91, v81, v104
	v_mul_f32_e32 v94, v82, v104
	v_mul_f32_e32 v95, v83, v104
	v_add_co_u32_e32 v92, vcc, 0x69ff000, v92
	v_cvt_pk_bf16_f32 v90, v90, v91
	v_cvt_pk_bf16_f32 v91, v94, v95
	v_addc_co_u32_e32 v93, vcc, 0, v93, vcc
	global_store_dwordx4 v[92:93], v[88:91], off offset:960

; DI void st_bf8(u16* p, f32x4 a, f32x4 b, float sc) {
;   u32x4 u; u.x = pack2(a[0] * sc, a[1] * sc); u.y = pack2(a[2] * sc, a[3] * sc); u.z = pack2(b[0] * sc, b[1] * sc); u.w = pack2(b[2] * sc, b[3] * sc);
;   *(u32x4*)p = u;
;   DI void operator()(const f32x4 (&acc)[2][2][4][2], const pg8::Unit& u, int wr, int wc, int fr_, int fq_) const {
;     ...
;                 else if (gb < 1696) st_bf8((u16*)(big + E_KNA) + (size_t)token * 512 + (f8 - 1184), v, v1, rinv);
.LBB0_969:
	s_andn2_b64 vcc, exec, s[28:29]
	s_cbranch_vccnz .LBB0_971
	s_add_i32 s28, s13, s61
	v_lshl_add_u64 v[88:89], s[2:3], 0, v[112:113]
	v_add_u32_e32 v90, s28, v144
	v_mov_b32_e32 v91, v145
	v_lshl_add_u64 v[92:93], v[90:91], 1, v[88:89]
	v_mul_f32_e32 v88, v84, v104
	v_mul_f32_e32 v89, v85, v104
	v_mul_f32_e32 v90, v86, v104
	v_mul_f32_e32 v91, v87, v104
	v_cvt_pk_bf16_f32 v88, v88, v89
	v_cvt_pk_bf16_f32 v89, v90, v91
	v_mul_f32_e32 v90, v80, v104
	v_mul_f32_e32 v91, v81, v104
	v_mul_f32_e32 v94, v82, v104
	v_mul_f32_e32 v95, v83, v104
	v_add_co_u32_e32 v92, vcc, 0x49ff000, v92
	v_cvt_pk_bf16_f32 v90, v90, v91
	v_cvt_pk_bf16_f32 v91, v94, v95
	v_addc_co_u32_e32 v93, vcc, 0, v93, vcc
	global_store_dwordx4 v[92:93], v[88:91], off offset:1984

; DI void st_bf8(u16* p, f32x4 a, f32x4 b, float sc) {
;   u32x4 u; u.x = pack2(a[0] * sc, a[1] * sc); u.y = pack2(a[2] * sc, a[3] * sc); u.z = pack2(b[0] * sc, b[1] * sc); u.w = pack2(b[2] * sc, b[3] * sc);
;   *(u32x4*)p = u;
;   DI void operator()(const f32x4 (&acc)[2][2][4][2], const pg8::Unit& u, int wr, int wc, int fr_, int fq_) const {
;     ...
;                 else if (gb < 1184) st_bf8((u16*)(big + E_QNA) + (size_t)token * 512 + (f8 - 672), v, v1, rinv * (0.125f * LOG2E));
.LBB0_972:
	s_andn2_b64 vcc, exec, s[28:29]
	s_cbranch_vccnz .LBB0_974
	s_add_i32 s28, s13, s61
	v_lshl_add_u64 v[88:89], s[2:3], 0, v[112:113]
	v_add_u32_e32 v90, s28, v144
	v_mov_b32_e32 v91, v145
	v_lshl_add_u64 v[92:93], v[90:91], 1, v[88:89]
	v_mul_f32_e32 v88, v84, v110
	v_mul_f32_e32 v89, v85, v110
	v_mul_f32_e32 v90, v86, v110
	v_mul_f32_e32 v91, v87, v110
	v_cvt_pk_bf16_f32 v88, v88, v89
	v_cvt_pk_bf16_f32 v89, v90, v91
	v_mul_f32_e32 v90, v80, v110
	v_mul_f32_e32 v91, v81, v110
	v_mul_f32_e32 v94, v82, v110
	v_mul_f32_e32 v95, v83, v110
	v_add_co_u32_e32 v92, vcc, 0x29ff000, v92
	v_cvt_pk_bf16_f32 v90, v90, v91
	v_cvt_pk_bf16_f32 v91, v94, v95
	v_addc_co_u32_e32 v93, vcc, 0, v93, vcc
	global_store_dwordx4 v[92:93], v[88:91], off offset:3008

; DI void rope_perm(f32x4& a0, f32x4& a1, int fq, int lane, const float* tcos, const float* tsin, int pos) {
;   f32x4 p0, p1;
; #pragma unroll
;   for (int e = 0; e < 4; ++e) { p0[e] = shx(a0[e], 32, lane); p1[e] = shx(a1[e], 32, lane); }
;   const int jb = 8 * (fq & 1);
;   const f32x4 c0 = *(const f32x4*)(tcos + pos * 16 + jb), c1 = *(const f32x4*)(tcos + pos * 16 + jb + 4);
;   const f32x4 s0 = *(const f32x4*)(tsin + pos * 16 + jb), s1 = *(const f32x4*)(tsin + pos * 16 + jb + 4);
;   if (fq < 2) { a0 = a0 * c0 - p0 * s0; a1 = a1 * c1 - p1 * s1; }
;   else        { a0 = a0 * c0 + p0 * s0; a1 = a1 * c1 + p1 * s1; }
; }
;   DI void operator()(const f32x4 (&acc)[2][2][4][2], const pg8::Unit& u, int wr, int wc, int fr_, int fq_) const {
;     ...
;                 else if (gb < 672) {
;                   f32x4 a0 = v, a1 = v1;
;                   rope_perm(a0, a1, fq, t_ & 63, tcos, tsin, token & (S_ - 1));
;                   st_bf8((u16*)(big + E_KPE) + (size_t)token * 32 + 8 * fq, a0, a1, rinv);
;                 }
.LBB0_975:
	s_andn2_b64 vcc, exec, s[28:29]
	s_cbranch_vccnz .LBB0_981
	v_lshlrev_b32_e32 v92, 2, v105
	v_mov_b32_e32 v93, v145
	v_lshl_add_u64 v[88:89], s[4:5], 0, v[92:93]
	v_lshlrev_b32_e32 v94, 2, v199
	v_mov_b32_e32 v95, v145
	v_lshl_add_u64 v[92:93], s[6:7], 0, v[92:93]
	v_lshl_add_u64 v[98:99], v[88:89], 0, v[94:95]
	v_lshl_add_u64 v[100:101], v[92:93], 0, v[94:95]
	global_load_dwordx4 v[88:91], v[98:99], off
	global_load_dwordx4 v[92:95], v[100:101], off
	global_load_dwordx4 v[118:121], v[100:101], off offset:16
	global_load_dwordx4 v[122:125], v[98:99], off offset:16
	ds_bpermute_b32 v100, v198, v84
	ds_bpermute_b32 v110, v198, v80
	ds_bpermute_b32 v101, v198, v85
	ds_bpermute_b32 v111, v198, v81
	ds_bpermute_b32 v114, v198, v86
	ds_bpermute_b32 v126, v198, v82
	ds_bpermute_b32 v115, v198, v87
	ds_bpermute_b32 v127, v198, v83
	s_waitcnt vmcnt(0) lgkmcnt(0)
	v_mul_f32_e32 v112, v92, v100
	v_mul_f32_e32 v113, v93, v101
	v_mul_f32_e32 v98, v86, v90
	v_mul_f32_e32 v99, v87, v91
	v_mul_f32_e32 v102, v84, v88
	v_mul_f32_e32 v103, v85, v89
	v_mul_f32_e32 v116, v94, v114
	v_mul_f32_e32 v117, v95, v115
	v_mul_f32_e32 v100, v118, v110
	v_mul_f32_e32 v101, v119, v111
	v_mul_f32_e32 v110, v120, v126
	v_mul_f32_e32 v111, v121, v127
	v_mul_f32_e32 v114, v82, v124
	v_mul_f32_e32 v115, v83, v125
	v_mul_f32_e32 v118, v80, v122
	v_mul_f32_e32 v119, v81, v123
	s_and_saveexec_b64 s[28:29], s[92:93]
	s_xor_b64 s[28:29], exec, s[28:29]
	v_add_f32_e32 v90, v98, v116
	v_add_f32_e32 v91, v99, v117
	v_add_f32_e32 v88, v102, v112
	v_add_f32_e32 v89, v103, v113
	v_add_f32_e32 v94, v114, v110
	v_add_f32_e32 v95, v115, v111
	v_add_f32_e32 v92, v118, v100
	v_add_f32_e32 v93, v119, v101
	s_andn2_saveexec_b64 s[28:29], s[28:29]
	v_sub_f32_e32 v91, v99, v117
	v_sub_f32_e32 v90, v98, v116
	v_sub_f32_e32 v89, v103, v113
	v_sub_f32_e32 v88, v102, v112
	v_sub_f32_e32 v95, v115, v111
	v_sub_f32_e32 v94, v114, v110
	v_sub_f32_e32 v93, v119, v101
	v_sub_f32_e32 v92, v118, v100
	s_or_b64 exec, exec, s[28:29]
	v_mul_f32_e32 v88, v104, v88
	v_mul_f32_e32 v89, v104, v89
	v_mul_f32_e32 v90, v104, v90
	v_mul_f32_e32 v91, v104, v91
	v_lshl_add_u64 v[98:99], s[10:11], 0, v[108:109]
	v_lshlrev_b32_e32 v100, 1, v144
	v_mov_b32_e32 v101, v145
	v_cvt_pk_bf16_f32 v88, v88, v89
	v_cvt_pk_bf16_f32 v89, v90, v91
	v_mul_f32_e32 v90, v104, v92
	v_mul_f32_e32 v91, v104, v93
	v_mul_f32_e32 v92, v104, v94
	v_mul_f32_e32 v93, v104, v95
	v_lshl_add_u64 v[98:99], v[98:99], 0, v[100:101]
	v_cvt_pk_bf16_f32 v90, v90, v91
	v_cvt_pk_bf16_f32 v91, v92, v93
	global_store_dwordx4 v[98:99], v[88:91], off

; DI void st_bf8(u16* p, f32x4 a, f32x4 b, float sc) {
;   u32x4 u; u.x = pack2(a[0] * sc, a[1] * sc); u.y = pack2(a[2] * sc, a[3] * sc); u.z = pack2(b[0] * sc, b[1] * sc); u.w = pack2(b[2] * sc, b[3] * sc);
;   *(u32x4*)p = u;
;   DI void operator()(const f32x4 (&acc)[2][2][4][2], const pg8::Unit& u, int wr, int wc, int fr_, int fq_) const {
;     ...
;                 else if (gb < 640) st_bf8((u16*)(big + E_CKV) + (size_t)token * 256 + (f8 - 384), v, v1, rinv);
.LBB0_982:
	s_andn2_b64 vcc, exec, s[28:29]
	s_cbranch_vccnz .LBB0_984
	s_add_i32 s28, s13, s61
	v_lshl_add_u64 v[88:89], s[2:3], 0, v[106:107]
	v_add_u32_e32 v90, s28, v144
	v_mov_b32_e32 v91, v145
	v_lshl_add_u64 v[92:93], v[90:91], 1, v[88:89]
	v_mul_f32_e32 v88, v84, v104
	v_mul_f32_e32 v89, v85, v104
	v_mul_f32_e32 v90, v86, v104
	v_mul_f32_e32 v91, v87, v104
	v_cvt_pk_bf16_f32 v88, v88, v89
	v_cvt_pk_bf16_f32 v89, v90, v91
	v_mul_f32_e32 v90, v80, v104
	v_mul_f32_e32 v91, v81, v104
	v_mul_f32_e32 v94, v82, v104
	v_mul_f32_e32 v95, v83, v104
	v_add_co_u32_e32 v92, vcc, 0x17ff000, v92
	v_cvt_pk_bf16_f32 v90, v90, v91
	v_cvt_pk_bf16_f32 v91, v94, v95
	v_addc_co_u32_e32 v93, vcc, 0, v93, vcc
	global_store_dwordx4 v[92:93], v[88:91], off offset:3584

; DI void st_bf8(u16* p, f32x4 a, f32x4 b, float sc) {
;   u32x4 u; u.x = pack2(a[0] * sc, a[1] * sc); u.y = pack2(a[2] * sc, a[3] * sc); u.z = pack2(b[0] * sc, b[1] * sc); u.w = pack2(b[2] * sc, b[3] * sc);
;   *(u32x4*)p = u;
;   DI void operator()(const f32x4 (&acc)[2][2][4][2], const pg8::Unit& u, int wr, int wc, int fr_, int fq_) const {
;     ...
;         const int rl = ai * 128 + wr * 64 + m * 16 + fr;
;         const int token = u.pm * 256 + rl;
;         float rinv = 1.f;
;         if (EPI != EPI_RESID) rinv = rinv_tab[slot * 256 + rl];
;         float ssq = 0.f;
; #pragma unroll
;         for (int bj = 0; bj < 2; ++bj)
; #pragma unroll
;           for (int n = 0; n < 2; ++n) {
;             const int fb = u.pn * 256 + bj * 128 + wc * 32 + n * 16;
;             const int f = fb + 4 * fq;
;             const f32x4 v = acc[ai][bj][m][n];
;             if (EPI == EPI_ABIN) {
;               if (n == 0) {
;                 const int gb = u.pn * 256 + bj * 128 + wc * 32; const int f8 = gb + 8 * fq;
;                 const f32x4 v1 = acc[ai][bj][m][1];
;                 if (gb < 384) st_bf8((u16*)(big + E_CQ) + (size_t)token * 384 + f8, v, v1, rinv);
;                 else if (gb < 640) st_bf8((u16*)(big + E_CKV) + (size_t)token * 256 + (f8 - 384), v, v1, rinv);
;                 else if (gb < 672) {
;                   f32x4 a0 = v, a1 = v1;
;                   rope_perm(a0, a1, fq, t_ & 63, tcos, tsin, token & (S_ - 1));
;                   st_bf8((u16*)(big + E_KPE) + (size_t)token * 32 + 8 * fq, a0, a1, rinv);
;                 }
;                 else if (gb < 1184) st_bf8((u16*)(big + E_QNA) + (size_t)token * 512 + (f8 - 672), v, v1, rinv * (0.125f * LOG2E));
;                 else if (gb < 1696) st_bf8((u16*)(big + E_KNA) + (size_t)token * 512 + (f8 - 1184), v, v1, rinv);
;                 else if (gb < 2208) st_bf8((u16*)(big + E_VNAT) + (size_t)token * 512 + (f8 - 1696), v, v1, rinv);
.LBB0_985:
	v_mul_f32_e32 v76, v76, v88
	v_mul_f32_e32 v77, v77, v88
	v_mul_f32_e32 v78, v78, v88
	v_mul_f32_e32 v79, v79, v88
	v_mul_f32_e32 v72, v72, v88
	v_mul_f32_e32 v73, v73, v88
	v_cvt_pk_bf16_f32 v76, v76, v77
	v_cvt_pk_bf16_f32 v77, v78, v79
	v_cvt_pk_bf16_f32 v78, v72, v73
	v_mul_f32_e32 v72, v74, v88
	v_mul_f32_e32 v73, v75, v88
	v_lshl_add_u64 v[82:83], v[150:151], 1, v[80:81]
	v_cvt_pk_bf16_f32 v79, v72, v73
	global_store_dwordx4 v[82:83], v[76:79], off
	s_and_b64 vcc, exec, s[78:79]
	s_mov_b64 s[28:29], -1
	s_cbranch_vccnz .LBB0_848
.LBB0_986:
	s_and_b64 vcc, exec, s[94:95]
	s_cbranch_vccnz .LBB0_1006
	s_andn2_b64 vcc, exec, s[44:45]
	s_cbranch_vccnz .LBB0_999
	s_andn2_b64 vcc, exec, s[42:43]
	s_cbranch_vccnz .LBB0_996
	s_andn2_b64 vcc, exec, s[38:39]
	s_cbranch_vccnz .LBB0_993
	s_andn2_b64 vcc, exec, s[36:37]
	s_cbranch_vccnz .LBB0_992
	s_add_i32 s15, s13, s61
	v_lshl_add_u64 v[72:73], s[2:3], 0, v[96:97]
	v_add_u32_e32 v74, s15, v144
	v_mov_b32_e32 v75, v145
	v_lshl_add_u64 v[76:77], v[74:75], 1, v[72:73]
	v_mul_f32_e32 v72, v68, v88
	v_mul_f32_e32 v73, v69, v88
	v_mul_f32_e32 v74, v70, v88
	v_mul_f32_e32 v75, v71, v88
	v_cvt_pk_bf16_f32 v72, v72, v73
	v_cvt_pk_bf16_f32 v73, v74, v75
	v_mul_f32_e32 v74, v64, v88
	v_mul_f32_e32 v75, v65, v88
	v_mul_f32_e32 v78, v66, v88
	v_mul_f32_e32 v79, v67, v88
	v_add_co_u32_e32 v76, vcc, 0x69ff000, v76
	v_cvt_pk_bf16_f32 v74, v74, v75
	v_cvt_pk_bf16_f32 v75, v78, v79
	v_addc_co_u32_e32 v77, vcc, 0, v77, vcc
	global_store_dwordx4 v[76:77], v[72:75], off offset:960

; DI void st_bf8(u16* p, f32x4 a, f32x4 b, float sc) {
;   u32x4 u; u.x = pack2(a[0] * sc, a[1] * sc); u.y = pack2(a[2] * sc, a[3] * sc); u.z = pack2(b[0] * sc, b[1] * sc); u.w = pack2(b[2] * sc, b[3] * sc);
;   *(u32x4*)p = u;
;   DI void operator()(const f32x4 (&acc)[2][2][4][2], const pg8::Unit& u, int wr, int wc, int fr_, int fq_) const {
;     ...
;                 else if (gb < 1696) st_bf8((u16*)(big + E_KNA) + (size_t)token * 512 + (f8 - 1184), v, v1, rinv);
.LBB0_993:
	s_andn2_b64 vcc, exec, s[28:29]
	s_cbranch_vccnz .LBB0_995
	s_add_i32 s15, s13, s61
	v_lshl_add_u64 v[72:73], s[2:3], 0, v[96:97]
	v_add_u32_e32 v74, s15, v144
	v_mov_b32_e32 v75, v145
	v_lshl_add_u64 v[76:77], v[74:75], 1, v[72:73]
	v_mul_f32_e32 v72, v68, v88
	v_mul_f32_e32 v73, v69, v88
	v_mul_f32_e32 v74, v70, v88
	v_mul_f32_e32 v75, v71, v88
	v_cvt_pk_bf16_f32 v72, v72, v73
	v_cvt_pk_bf16_f32 v73, v74, v75
	v_mul_f32_e32 v74, v64, v88
	v_mul_f32_e32 v75, v65, v88
	v_mul_f32_e32 v78, v66, v88
	v_mul_f32_e32 v79, v67, v88
	v_add_co_u32_e32 v76, vcc, 0x49ff000, v76
	v_cvt_pk_bf16_f32 v74, v74, v75
	v_cvt_pk_bf16_f32 v75, v78, v79
	v_addc_co_u32_e32 v77, vcc, 0, v77, vcc
	global_store_dwordx4 v[76:77], v[72:75], off offset:1984

; DI void st_bf8(u16* p, f32x4 a, f32x4 b, float sc) {
;   u32x4 u; u.x = pack2(a[0] * sc, a[1] * sc); u.y = pack2(a[2] * sc, a[3] * sc); u.z = pack2(b[0] * sc, b[1] * sc); u.w = pack2(b[2] * sc, b[3] * sc);
;   *(u32x4*)p = u;
;   DI void operator()(const f32x4 (&acc)[2][2][4][2], const pg8::Unit& u, int wr, int wc, int fr_, int fq_) const {
;     ...
;                 else if (gb < 1184) st_bf8((u16*)(big + E_QNA) + (size_t)token * 512 + (f8 - 672), v, v1, rinv * (0.125f * LOG2E));
.LBB0_996:
	s_andn2_b64 vcc, exec, s[28:29]
	s_cbranch_vccnz .LBB0_998
	s_add_i32 s15, s13, s61
	v_lshl_add_u64 v[72:73], s[2:3], 0, v[96:97]
	v_add_u32_e32 v74, s15, v144
	v_mov_b32_e32 v75, v145
	v_lshl_add_u64 v[76:77], v[74:75], 1, v[72:73]
	v_mul_f32_e32 v72, v68, v94
	v_mul_f32_e32 v73, v69, v94
	v_mul_f32_e32 v74, v70, v94
	v_mul_f32_e32 v75, v71, v94
	v_cvt_pk_bf16_f32 v72, v72, v73
	v_cvt_pk_bf16_f32 v73, v74, v75
	v_mul_f32_e32 v74, v64, v94
	v_mul_f32_e32 v75, v65, v94
	v_mul_f32_e32 v78, v66, v94
	v_mul_f32_e32 v79, v67, v94
	v_add_co_u32_e32 v76, vcc, 0x29ff000, v76
	v_cvt_pk_bf16_f32 v74, v74, v75
	v_cvt_pk_bf16_f32 v75, v78, v79
	v_addc_co_u32_e32 v77, vcc, 0, v77, vcc
	global_store_dwordx4 v[76:77], v[72:75], off offset:3008

; DI void rope_perm(f32x4& a0, f32x4& a1, int fq, int lane, const float* tcos, const float* tsin, int pos) {
;   f32x4 p0, p1;
; #pragma unroll
;   for (int e = 0; e < 4; ++e) { p0[e] = shx(a0[e], 32, lane); p1[e] = shx(a1[e], 32, lane); }
;   const int jb = 8 * (fq & 1);
;   const f32x4 c0 = *(const f32x4*)(tcos + pos * 16 + jb), c1 = *(const f32x4*)(tcos + pos * 16 + jb + 4);
;   const f32x4 s0 = *(const f32x4*)(tsin + pos * 16 + jb), s1 = *(const f32x4*)(tsin + pos * 16 + jb + 4);
;   if (fq < 2) { a0 = a0 * c0 - p0 * s0; a1 = a1 * c1 - p1 * s1; }
;   else        { a0 = a0 * c0 + p0 * s0; a1 = a1 * c1 + p1 * s1; }
; }
;   DI void operator()(const f32x4 (&acc)[2][2][4][2], const pg8::Unit& u, int wr, int wc, int fr_, int fq_) const {
;     ...
;                 else if (gb < 672) {
;                   f32x4 a0 = v, a1 = v1;
;                   rope_perm(a0, a1, fq, t_ & 63, tcos, tsin, token & (S_ - 1));
;                   st_bf8((u16*)(big + E_KPE) + (size_t)token * 32 + 8 * fq, a0, a1, rinv);
;                 }
.LBB0_999:
	s_andn2_b64 vcc, exec, s[28:29]
	s_cbranch_vccnz .LBB0_1005
	v_lshlrev_b32_e32 v76, 2, v89
	v_mov_b32_e32 v77, v145
	v_lshl_add_u64 v[72:73], s[4:5], 0, v[76:77]
	v_lshlrev_b32_e32 v78, 2, v199
	v_mov_b32_e32 v79, v145
	v_lshl_add_u64 v[76:77], s[6:7], 0, v[76:77]
	v_lshl_add_u64 v[82:83], v[72:73], 0, v[78:79]
	v_lshl_add_u64 v[84:85], v[76:77], 0, v[78:79]
	global_load_dwordx4 v[72:75], v[82:83], off
	global_load_dwordx4 v[76:79], v[84:85], off
	global_load_dwordx4 v[102:105], v[84:85], off offset:16
	global_load_dwordx4 v[106:109], v[82:83], off offset:16
	ds_bpermute_b32 v84, v198, v68
	ds_bpermute_b32 v94, v198, v64
	ds_bpermute_b32 v85, v198, v69
	ds_bpermute_b32 v95, v198, v65
	ds_bpermute_b32 v98, v198, v70
	ds_bpermute_b32 v110, v198, v66
	ds_bpermute_b32 v99, v198, v71
	ds_bpermute_b32 v111, v198, v67
	s_waitcnt vmcnt(0) lgkmcnt(0)
	v_mul_f32_e32 v96, v76, v84
	v_mul_f32_e32 v97, v77, v85
	v_mul_f32_e32 v82, v70, v74
	v_mul_f32_e32 v83, v71, v75
	v_mul_f32_e32 v86, v68, v72
	v_mul_f32_e32 v87, v69, v73
	v_mul_f32_e32 v100, v78, v98
	v_mul_f32_e32 v101, v79, v99
	v_mul_f32_e32 v84, v102, v94
	v_mul_f32_e32 v85, v103, v95
	v_mul_f32_e32 v94, v104, v110
	v_mul_f32_e32 v95, v105, v111
	v_mul_f32_e32 v98, v66, v108
	v_mul_f32_e32 v99, v67, v109
	v_mul_f32_e32 v102, v64, v106
	v_mul_f32_e32 v103, v65, v107
	s_and_saveexec_b64 s[28:29], s[92:93]
	s_xor_b64 s[28:29], exec, s[28:29]
	v_add_f32_e32 v74, v82, v100
	v_add_f32_e32 v75, v83, v101
	v_add_f32_e32 v72, v86, v96
	v_add_f32_e32 v73, v87, v97
	v_add_f32_e32 v78, v98, v94
	v_add_f32_e32 v79, v99, v95
	v_add_f32_e32 v76, v102, v84
	v_add_f32_e32 v77, v103, v85
	s_andn2_saveexec_b64 s[28:29], s[28:29]
	v_sub_f32_e32 v75, v83, v101
	v_sub_f32_e32 v74, v82, v100
	v_sub_f32_e32 v73, v87, v97
	v_sub_f32_e32 v72, v86, v96
	v_sub_f32_e32 v79, v99, v95
	v_sub_f32_e32 v78, v98, v94
	v_sub_f32_e32 v77, v103, v85
	v_sub_f32_e32 v76, v102, v84
	s_or_b64 exec, exec, s[28:29]
	v_mul_f32_e32 v72, v88, v72
	v_mul_f32_e32 v73, v88, v73
	v_mul_f32_e32 v74, v88, v74
	v_mul_f32_e32 v75, v88, v75
	v_lshl_add_u64 v[82:83], s[10:11], 0, v[92:93]
	v_lshlrev_b32_e32 v84, 1, v144
	v_mov_b32_e32 v85, v145
	v_cvt_pk_bf16_f32 v72, v72, v73
	v_cvt_pk_bf16_f32 v73, v74, v75
	v_mul_f32_e32 v74, v88, v76
	v_mul_f32_e32 v75, v88, v77
	v_mul_f32_e32 v76, v88, v78
	v_mul_f32_e32 v77, v88, v79
	v_lshl_add_u64 v[82:83], v[82:83], 0, v[84:85]
	v_cvt_pk_bf16_f32 v74, v74, v75
	v_cvt_pk_bf16_f32 v75, v76, v77
	global_store_dwordx4 v[82:83], v[72:75], off

; DI void st_bf8(u16* p, f32x4 a, f32x4 b, float sc) {
;   u32x4 u; u.x = pack2(a[0] * sc, a[1] * sc); u.y = pack2(a[2] * sc, a[3] * sc); u.z = pack2(b[0] * sc, b[1] * sc); u.w = pack2(b[2] * sc, b[3] * sc);
;   *(u32x4*)p = u;
;   DI void operator()(const f32x4 (&acc)[2][2][4][2], const pg8::Unit& u, int wr, int wc, int fr_, int fq_) const {
;     ...
;                 else if (gb < 640) st_bf8((u16*)(big + E_CKV) + (size_t)token * 256 + (f8 - 384), v, v1, rinv);
.LBB0_1006:
	s_andn2_b64 vcc, exec, s[28:29]
	s_cbranch_vccnz .LBB0_1008
	s_add_i32 s15, s13, s61
	v_lshl_add_u64 v[72:73], s[2:3], 0, v[90:91]
	v_add_u32_e32 v74, s15, v144
	v_mov_b32_e32 v75, v145
	v_lshl_add_u64 v[76:77], v[74:75], 1, v[72:73]
	v_mul_f32_e32 v72, v68, v88
	v_mul_f32_e32 v73, v69, v88
	v_mul_f32_e32 v74, v70, v88
	v_mul_f32_e32 v75, v71, v88
	v_cvt_pk_bf16_f32 v72, v72, v73
	v_cvt_pk_bf16_f32 v73, v74, v75
	v_mul_f32_e32 v74, v64, v88
	v_mul_f32_e32 v75, v65, v88
	v_mul_f32_e32 v78, v66, v88
	v_mul_f32_e32 v79, v67, v88
	v_add_co_u32_e32 v76, vcc, 0x17ff000, v76
	v_cvt_pk_bf16_f32 v74, v74, v75
	v_cvt_pk_bf16_f32 v75, v78, v79
	v_addc_co_u32_e32 v77, vcc, 0, v77, vcc
	global_store_dwordx4 v[76:77], v[72:75], off offset:3584

; DI void st_bf8(u16* p, f32x4 a, f32x4 b, float sc) {
;   u32x4 u; u.x = pack2(a[0] * sc, a[1] * sc); u.y = pack2(a[2] * sc, a[3] * sc); u.z = pack2(b[0] * sc, b[1] * sc); u.w = pack2(b[2] * sc, b[3] * sc);
;   *(u32x4*)p = u;
;   DI void operator()(const f32x4 (&acc)[2][2][4][2], const pg8::Unit& u, int wr, int wc, int fr_, int fq_) const {
;     ...
;         const int rl = ai * 128 + wr * 64 + m * 16 + fr;
;         const int token = u.pm * 256 + rl;
;         float rinv = 1.f;
;         if (EPI != EPI_RESID) rinv = rinv_tab[slot * 256 + rl];
;         float ssq = 0.f;
; #pragma unroll
;         for (int bj = 0; bj < 2; ++bj)
; #pragma unroll
;           for (int n = 0; n < 2; ++n) {
;             const int fb = u.pn * 256 + bj * 128 + wc * 32 + n * 16;
;             const int f = fb + 4 * fq;
;             const f32x4 v = acc[ai][bj][m][n];
;             if (EPI == EPI_ABIN) {
;               if (n == 0) {
;                 const int gb = u.pn * 256 + bj * 128 + wc * 32; const int f8 = gb + 8 * fq;
;                 const f32x4 v1 = acc[ai][bj][m][1];
;                 if (gb < 384) st_bf8((u16*)(big + E_CQ) + (size_t)token * 384 + f8, v, v1, rinv);
;                 else if (gb < 640) st_bf8((u16*)(big + E_CKV) + (size_t)token * 256 + (f8 - 384), v, v1, rinv);
;                 else if (gb < 672) {
;                   f32x4 a0 = v, a1 = v1;
;                   rope_perm(a0, a1, fq, t_ & 63, tcos, tsin, token & (S_ - 1));
;                   st_bf8((u16*)(big + E_KPE) + (size_t)token * 32 + 8 * fq, a0, a1, rinv);
;                 }
;                 else if (gb < 1184) st_bf8((u16*)(big + E_QNA) + (size_t)token * 512 + (f8 - 672), v, v1, rinv * (0.125f * LOG2E));
;                 else if (gb < 1696) st_bf8((u16*)(big + E_KNA) + (size_t)token * 512 + (f8 - 1184), v, v1, rinv);
;                 else if (gb < 2208) st_bf8((u16*)(big + E_VNAT) + (size_t)token * 512 + (f8 - 1696), v, v1, rinv);
.LBB0_1009:
	v_mul_f32_e32 v60, v60, v72
	v_mul_f32_e32 v61, v61, v72
	v_mul_f32_e32 v62, v62, v72
	v_mul_f32_e32 v63, v63, v72
	v_mul_f32_e32 v56, v56, v72
	v_mul_f32_e32 v57, v57, v72
	v_cvt_pk_bf16_f32 v60, v60, v61
	v_cvt_pk_bf16_f32 v61, v62, v63
	v_cvt_pk_bf16_f32 v62, v56, v57
	v_mul_f32_e32 v56, v58, v72
	v_mul_f32_e32 v57, v59, v72
	v_lshl_add_u64 v[66:67], v[150:151], 1, v[64:65]
	v_cvt_pk_bf16_f32 v63, v56, v57
	global_store_dwordx4 v[66:67], v[60:63], off
	s_and_b64 vcc, exec, s[78:79]
	s_mov_b64 s[28:29], -1
	s_cbranch_vccnz .LBB0_876
.LBB0_1010:
	s_and_b64 vcc, exec, s[94:95]
	s_cbranch_vccnz .LBB0_1030
	s_andn2_b64 vcc, exec, s[44:45]
	s_cbranch_vccnz .LBB0_1023
	s_andn2_b64 vcc, exec, s[42:43]
	s_cbranch_vccnz .LBB0_1020
	s_andn2_b64 vcc, exec, s[38:39]
	s_cbranch_vccnz .LBB0_1017
	s_andn2_b64 vcc, exec, s[36:37]
	s_cbranch_vccnz .LBB0_1016
	s_add_i32 s15, s13, s61
	v_lshl_add_u64 v[56:57], s[2:3], 0, v[80:81]
	v_add_u32_e32 v58, s15, v144
	v_mov_b32_e32 v59, v145
	v_lshl_add_u64 v[60:61], v[58:59], 1, v[56:57]
	v_mul_f32_e32 v56, v52, v72
	v_mul_f32_e32 v57, v53, v72
	v_mul_f32_e32 v58, v54, v72
	v_mul_f32_e32 v59, v55, v72
	v_cvt_pk_bf16_f32 v56, v56, v57
	v_cvt_pk_bf16_f32 v57, v58, v59
	v_mul_f32_e32 v58, v48, v72
	v_mul_f32_e32 v59, v49, v72
	v_mul_f32_e32 v62, v50, v72
	v_mul_f32_e32 v63, v51, v72
	v_add_co_u32_e32 v60, vcc, 0x69ff000, v60
	v_cvt_pk_bf16_f32 v58, v58, v59
	v_cvt_pk_bf16_f32 v59, v62, v63
	v_addc_co_u32_e32 v61, vcc, 0, v61, vcc
	global_store_dwordx4 v[60:61], v[56:59], off offset:960

; DI void st_bf8(u16* p, f32x4 a, f32x4 b, float sc) {
;   u32x4 u; u.x = pack2(a[0] * sc, a[1] * sc); u.y = pack2(a[2] * sc, a[3] * sc); u.z = pack2(b[0] * sc, b[1] * sc); u.w = pack2(b[2] * sc, b[3] * sc);
;   *(u32x4*)p = u;
;   DI void operator()(const f32x4 (&acc)[2][2][4][2], const pg8::Unit& u, int wr, int wc, int fr_, int fq_) const {
;     ...
;                 else if (gb < 1696) st_bf8((u16*)(big + E_KNA) + (size_t)token * 512 + (f8 - 1184), v, v1, rinv);
.LBB0_1017:
	s_andn2_b64 vcc, exec, s[28:29]
	s_cbranch_vccnz .LBB0_1019
	s_add_i32 s15, s13, s61
	v_lshl_add_u64 v[56:57], s[2:3], 0, v[80:81]
	v_add_u32_e32 v58, s15, v144
	v_mov_b32_e32 v59, v145
	v_lshl_add_u64 v[60:61], v[58:59], 1, v[56:57]
	v_mul_f32_e32 v56, v52, v72
	v_mul_f32_e32 v57, v53, v72
	v_mul_f32_e32 v58, v54, v72
	v_mul_f32_e32 v59, v55, v72
	v_cvt_pk_bf16_f32 v56, v56, v57
	v_cvt_pk_bf16_f32 v57, v58, v59
	v_mul_f32_e32 v58, v48, v72
	v_mul_f32_e32 v59, v49, v72
	v_mul_f32_e32 v62, v50, v72
	v_mul_f32_e32 v63, v51, v72
	v_add_co_u32_e32 v60, vcc, 0x49ff000, v60
	v_cvt_pk_bf16_f32 v58, v58, v59
	v_cvt_pk_bf16_f32 v59, v62, v63
	v_addc_co_u32_e32 v61, vcc, 0, v61, vcc
	global_store_dwordx4 v[60:61], v[56:59], off offset:1984

; DI void st_bf8(u16* p, f32x4 a, f32x4 b, float sc) {
;   u32x4 u; u.x = pack2(a[0] * sc, a[1] * sc); u.y = pack2(a[2] * sc, a[3] * sc); u.z = pack2(b[0] * sc, b[1] * sc); u.w = pack2(b[2] * sc, b[3] * sc);
;   *(u32x4*)p = u;
;   DI void operator()(const f32x4 (&acc)[2][2][4][2], const pg8::Unit& u, int wr, int wc, int fr_, int fq_) const {
;     ...
;                 else if (gb < 1184) st_bf8((u16*)(big + E_QNA) + (size_t)token * 512 + (f8 - 672), v, v1, rinv * (0.125f * LOG2E));
.LBB0_1020:
	s_andn2_b64 vcc, exec, s[28:29]
	s_cbranch_vccnz .LBB0_1022
	s_add_i32 s15, s13, s61
	v_lshl_add_u64 v[56:57], s[2:3], 0, v[80:81]
	v_add_u32_e32 v58, s15, v144
	v_mov_b32_e32 v59, v145
	v_lshl_add_u64 v[60:61], v[58:59], 1, v[56:57]
	v_mul_f32_e32 v56, v52, v78
	v_mul_f32_e32 v57, v53, v78
	v_mul_f32_e32 v58, v54, v78
	v_mul_f32_e32 v59, v55, v78
	v_cvt_pk_bf16_f32 v56, v56, v57
	v_cvt_pk_bf16_f32 v57, v58, v59
	v_mul_f32_e32 v58, v48, v78
	v_mul_f32_e32 v59, v49, v78
	v_mul_f32_e32 v62, v50, v78
	v_mul_f32_e32 v63, v51, v78
	v_add_co_u32_e32 v60, vcc, 0x29ff000, v60
	v_cvt_pk_bf16_f32 v58, v58, v59
	v_cvt_pk_bf16_f32 v59, v62, v63
	v_addc_co_u32_e32 v61, vcc, 0, v61, vcc
	global_store_dwordx4 v[60:61], v[56:59], off offset:3008

; DI void rope_perm(f32x4& a0, f32x4& a1, int fq, int lane, const float* tcos, const float* tsin, int pos) {
;   f32x4 p0, p1;
; #pragma unroll
;   for (int e = 0; e < 4; ++e) { p0[e] = shx(a0[e], 32, lane); p1[e] = shx(a1[e], 32, lane); }
;   const int jb = 8 * (fq & 1);
;   const f32x4 c0 = *(const f32x4*)(tcos + pos * 16 + jb), c1 = *(const f32x4*)(tcos + pos * 16 + jb + 4);
;   const f32x4 s0 = *(const f32x4*)(tsin + pos * 16 + jb), s1 = *(const f32x4*)(tsin + pos * 16 + jb + 4);
;   if (fq < 2) { a0 = a0 * c0 - p0 * s0; a1 = a1 * c1 - p1 * s1; }
;   else        { a0 = a0 * c0 + p0 * s0; a1 = a1 * c1 + p1 * s1; }
; }
;   DI void operator()(const f32x4 (&acc)[2][2][4][2], const pg8::Unit& u, int wr, int wc, int fr_, int fq_) const {
;     ...
;                 else if (gb < 672) {
;                   f32x4 a0 = v, a1 = v1;
;                   rope_perm(a0, a1, fq, t_ & 63, tcos, tsin, token & (S_ - 1));
;                   st_bf8((u16*)(big + E_KPE) + (size_t)token * 32 + 8 * fq, a0, a1, rinv);
;                 }
.LBB0_1023:
	s_andn2_b64 vcc, exec, s[28:29]
	s_cbranch_vccnz .LBB0_1029
	v_lshlrev_b32_e32 v60, 2, v73
	v_mov_b32_e32 v61, v145
	v_lshl_add_u64 v[56:57], s[4:5], 0, v[60:61]
	v_lshlrev_b32_e32 v62, 2, v199
	v_mov_b32_e32 v63, v145
	v_lshl_add_u64 v[60:61], s[6:7], 0, v[60:61]
	v_lshl_add_u64 v[66:67], v[56:57], 0, v[62:63]
	v_lshl_add_u64 v[68:69], v[60:61], 0, v[62:63]
	global_load_dwordx4 v[56:59], v[66:67], off
	global_load_dwordx4 v[60:63], v[68:69], off
	global_load_dwordx4 v[86:89], v[68:69], off offset:16
	global_load_dwordx4 v[90:93], v[66:67], off offset:16
	ds_bpermute_b32 v68, v198, v52
	ds_bpermute_b32 v78, v198, v48
	ds_bpermute_b32 v69, v198, v53
	ds_bpermute_b32 v79, v198, v49
	ds_bpermute_b32 v82, v198, v54
	ds_bpermute_b32 v94, v198, v50
	ds_bpermute_b32 v83, v198, v55
	ds_bpermute_b32 v95, v198, v51
	s_waitcnt vmcnt(0) lgkmcnt(0)
	v_mul_f32_e32 v80, v60, v68
	v_mul_f32_e32 v81, v61, v69
	v_mul_f32_e32 v66, v54, v58
	v_mul_f32_e32 v67, v55, v59
	v_mul_f32_e32 v70, v52, v56
	v_mul_f32_e32 v71, v53, v57
	v_mul_f32_e32 v84, v62, v82
	v_mul_f32_e32 v85, v63, v83
	v_mul_f32_e32 v68, v86, v78
	v_mul_f32_e32 v69, v87, v79
	v_mul_f32_e32 v78, v88, v94
	v_mul_f32_e32 v79, v89, v95
	v_mul_f32_e32 v82, v50, v92
	v_mul_f32_e32 v83, v51, v93
	v_mul_f32_e32 v86, v48, v90
	v_mul_f32_e32 v87, v49, v91
	s_and_saveexec_b64 s[28:29], s[92:93]
	s_xor_b64 s[28:29], exec, s[28:29]
	v_add_f32_e32 v58, v66, v84
	v_add_f32_e32 v59, v67, v85
	v_add_f32_e32 v56, v70, v80
	v_add_f32_e32 v57, v71, v81
	v_add_f32_e32 v62, v82, v78
	v_add_f32_e32 v63, v83, v79
	v_add_f32_e32 v60, v86, v68
	v_add_f32_e32 v61, v87, v69
	s_andn2_saveexec_b64 s[28:29], s[28:29]
	v_sub_f32_e32 v59, v67, v85
	v_sub_f32_e32 v58, v66, v84
	v_sub_f32_e32 v57, v71, v81
	v_sub_f32_e32 v56, v70, v80
	v_sub_f32_e32 v63, v83, v79
	v_sub_f32_e32 v62, v82, v78
	v_sub_f32_e32 v61, v87, v69
	v_sub_f32_e32 v60, v86, v68
	s_or_b64 exec, exec, s[28:29]
	v_mul_f32_e32 v56, v72, v56
	v_mul_f32_e32 v57, v72, v57
	v_mul_f32_e32 v58, v72, v58
	v_mul_f32_e32 v59, v72, v59
	v_lshl_add_u64 v[66:67], s[10:11], 0, v[76:77]
	v_lshlrev_b32_e32 v68, 1, v144
	v_mov_b32_e32 v69, v145
	v_cvt_pk_bf16_f32 v56, v56, v57
	v_cvt_pk_bf16_f32 v57, v58, v59
	v_mul_f32_e32 v58, v72, v60
	v_mul_f32_e32 v59, v72, v61
	v_mul_f32_e32 v60, v72, v62
	v_mul_f32_e32 v61, v72, v63
	v_lshl_add_u64 v[66:67], v[66:67], 0, v[68:69]
	v_cvt_pk_bf16_f32 v58, v58, v59
	v_cvt_pk_bf16_f32 v59, v60, v61
	global_store_dwordx4 v[66:67], v[56:59], off

; DI void st_bf8(u16* p, f32x4 a, f32x4 b, float sc) {
;   u32x4 u; u.x = pack2(a[0] * sc, a[1] * sc); u.y = pack2(a[2] * sc, a[3] * sc); u.z = pack2(b[0] * sc, b[1] * sc); u.w = pack2(b[2] * sc, b[3] * sc);
;   *(u32x4*)p = u;
;   DI void operator()(const f32x4 (&acc)[2][2][4][2], const pg8::Unit& u, int wr, int wc, int fr_, int fq_) const {
;     ...
;                 else if (gb < 640) st_bf8((u16*)(big + E_CKV) + (size_t)token * 256 + (f8 - 384), v, v1, rinv);
.LBB0_1030:
	s_andn2_b64 vcc, exec, s[28:29]
	s_cbranch_vccnz .LBB0_1032
	s_add_i32 s15, s13, s61
	v_lshl_add_u64 v[56:57], s[2:3], 0, v[74:75]
	v_add_u32_e32 v58, s15, v144
	v_mov_b32_e32 v59, v145
	v_lshl_add_u64 v[60:61], v[58:59], 1, v[56:57]
	v_mul_f32_e32 v56, v52, v72
	v_mul_f32_e32 v57, v53, v72
	v_mul_f32_e32 v58, v54, v72
	v_mul_f32_e32 v59, v55, v72
	v_cvt_pk_bf16_f32 v56, v56, v57
	v_cvt_pk_bf16_f32 v57, v58, v59
	v_mul_f32_e32 v58, v48, v72
	v_mul_f32_e32 v59, v49, v72
	v_mul_f32_e32 v62, v50, v72
	v_mul_f32_e32 v63, v51, v72
	v_add_co_u32_e32 v60, vcc, 0x17ff000, v60
	v_cvt_pk_bf16_f32 v58, v58, v59
	v_cvt_pk_bf16_f32 v59, v62, v63
	v_addc_co_u32_e32 v61, vcc, 0, v61, vcc
	global_store_dwordx4 v[60:61], v[56:59], off offset:3584

; DI void st_bf8(u16* p, f32x4 a, f32x4 b, float sc) {
;   u32x4 u; u.x = pack2(a[0] * sc, a[1] * sc); u.y = pack2(a[2] * sc, a[3] * sc); u.z = pack2(b[0] * sc, b[1] * sc); u.w = pack2(b[2] * sc, b[3] * sc);
;   *(u32x4*)p = u;
;   DI void operator()(const f32x4 (&acc)[2][2][4][2], const pg8::Unit& u, int wr, int wc, int fr_, int fq_) const {
;     ...
;         const int rl = ai * 128 + wr * 64 + m * 16 + fr;
;         const int token = u.pm * 256 + rl;
;         float rinv = 1.f;
;         if (EPI != EPI_RESID) rinv = rinv_tab[slot * 256 + rl];
;         float ssq = 0.f;
; #pragma unroll
;         for (int bj = 0; bj < 2; ++bj)
; #pragma unroll
;           for (int n = 0; n < 2; ++n) {
;             const int fb = u.pn * 256 + bj * 128 + wc * 32 + n * 16;
;             const int f = fb + 4 * fq;
;             const f32x4 v = acc[ai][bj][m][n];
;             if (EPI == EPI_ABIN) {
;               if (n == 0) {
;                 const int gb = u.pn * 256 + bj * 128 + wc * 32; const int f8 = gb + 8 * fq;
;                 const f32x4 v1 = acc[ai][bj][m][1];
;                 if (gb < 384) st_bf8((u16*)(big + E_CQ) + (size_t)token * 384 + f8, v, v1, rinv);
;                 else if (gb < 640) st_bf8((u16*)(big + E_CKV) + (size_t)token * 256 + (f8 - 384), v, v1, rinv);
;                 else if (gb < 672) {
;                   f32x4 a0 = v, a1 = v1;
;                   rope_perm(a0, a1, fq, t_ & 63, tcos, tsin, token & (S_ - 1));
;                   st_bf8((u16*)(big + E_KPE) + (size_t)token * 32 + 8 * fq, a0, a1, rinv);
;                 }
;                 else if (gb < 1184) st_bf8((u16*)(big + E_QNA) + (size_t)token * 512 + (f8 - 672), v, v1, rinv * (0.125f * LOG2E));
;                 else if (gb < 1696) st_bf8((u16*)(big + E_KNA) + (size_t)token * 512 + (f8 - 1184), v, v1, rinv);
;                 else if (gb < 2208) st_bf8((u16*)(big + E_VNAT) + (size_t)token * 512 + (f8 - 1696), v, v1, rinv);
.LBB0_1033:
	v_mul_f32_e32 v44, v44, v56
	v_mul_f32_e32 v45, v45, v56
	v_mul_f32_e32 v46, v46, v56
	v_mul_f32_e32 v47, v47, v56
	v_mul_f32_e32 v40, v40, v56
	v_mul_f32_e32 v41, v41, v56
	v_cvt_pk_bf16_f32 v44, v44, v45
	v_cvt_pk_bf16_f32 v45, v46, v47
	v_cvt_pk_bf16_f32 v46, v40, v41
	v_mul_f32_e32 v40, v42, v56
	v_mul_f32_e32 v41, v43, v56
	v_lshl_add_u64 v[50:51], v[150:151], 1, v[48:49]
	v_cvt_pk_bf16_f32 v47, v40, v41
	global_store_dwordx4 v[50:51], v[44:47], off
	s_and_b64 vcc, exec, s[78:79]
	s_mov_b64 s[28:29], -1
	s_cbranch_vccnz .LBB0_904
.LBB0_1034:
	s_and_b64 vcc, exec, s[94:95]
	s_cbranch_vccnz .LBB0_1054
	s_andn2_b64 vcc, exec, s[44:45]
	s_cbranch_vccnz .LBB0_1047
	s_andn2_b64 vcc, exec, s[42:43]
	s_cbranch_vccnz .LBB0_1044
	s_andn2_b64 vcc, exec, s[38:39]
	s_cbranch_vccnz .LBB0_1041
	s_andn2_b64 vcc, exec, s[36:37]
	s_cbranch_vccnz .LBB0_1040
	s_add_i32 s15, s13, s61
	v_lshl_add_u64 v[40:41], s[2:3], 0, v[64:65]
	v_add_u32_e32 v42, s15, v144
	v_mov_b32_e32 v43, v145
	v_lshl_add_u64 v[44:45], v[42:43], 1, v[40:41]
	v_mul_f32_e32 v40, v36, v56
	v_mul_f32_e32 v41, v37, v56
	v_mul_f32_e32 v42, v38, v56
	v_mul_f32_e32 v43, v39, v56
	v_cvt_pk_bf16_f32 v40, v40, v41
	v_cvt_pk_bf16_f32 v41, v42, v43
	v_mul_f32_e32 v42, v32, v56
	v_mul_f32_e32 v43, v33, v56
	v_mul_f32_e32 v46, v34, v56
	v_mul_f32_e32 v47, v35, v56
	v_add_co_u32_e32 v44, vcc, 0x69ff000, v44
	v_cvt_pk_bf16_f32 v42, v42, v43
	v_cvt_pk_bf16_f32 v43, v46, v47
	v_addc_co_u32_e32 v45, vcc, 0, v45, vcc
	global_store_dwordx4 v[44:45], v[40:43], off offset:960

; DI void st_bf8(u16* p, f32x4 a, f32x4 b, float sc) {
;   u32x4 u; u.x = pack2(a[0] * sc, a[1] * sc); u.y = pack2(a[2] * sc, a[3] * sc); u.z = pack2(b[0] * sc, b[1] * sc); u.w = pack2(b[2] * sc, b[3] * sc);
;   *(u32x4*)p = u;
;   DI void operator()(const f32x4 (&acc)[2][2][4][2], const pg8::Unit& u, int wr, int wc, int fr_, int fq_) const {
;     ...
;                 else if (gb < 1696) st_bf8((u16*)(big + E_KNA) + (size_t)token * 512 + (f8 - 1184), v, v1, rinv);
.LBB0_1041:
	s_andn2_b64 vcc, exec, s[28:29]
	s_cbranch_vccnz .LBB0_1043
	s_add_i32 s15, s13, s61
	v_lshl_add_u64 v[40:41], s[2:3], 0, v[64:65]
	v_add_u32_e32 v42, s15, v144
	v_mov_b32_e32 v43, v145
	v_lshl_add_u64 v[44:45], v[42:43], 1, v[40:41]
	v_mul_f32_e32 v40, v36, v56
	v_mul_f32_e32 v41, v37, v56
	v_mul_f32_e32 v42, v38, v56
	v_mul_f32_e32 v43, v39, v56
	v_cvt_pk_bf16_f32 v40, v40, v41
	v_cvt_pk_bf16_f32 v41, v42, v43
	v_mul_f32_e32 v42, v32, v56
	v_mul_f32_e32 v43, v33, v56
	v_mul_f32_e32 v46, v34, v56
	v_mul_f32_e32 v47, v35, v56
	v_add_co_u32_e32 v44, vcc, 0x49ff000, v44
	v_cvt_pk_bf16_f32 v42, v42, v43
	v_cvt_pk_bf16_f32 v43, v46, v47
	v_addc_co_u32_e32 v45, vcc, 0, v45, vcc
	global_store_dwordx4 v[44:45], v[40:43], off offset:1984

; DI void st_bf8(u16* p, f32x4 a, f32x4 b, float sc) {
;   u32x4 u; u.x = pack2(a[0] * sc, a[1] * sc); u.y = pack2(a[2] * sc, a[3] * sc); u.z = pack2(b[0] * sc, b[1] * sc); u.w = pack2(b[2] * sc, b[3] * sc);
;   *(u32x4*)p = u;
;   DI void operator()(const f32x4 (&acc)[2][2][4][2], const pg8::Unit& u, int wr, int wc, int fr_, int fq_) const {
;     ...
;                 else if (gb < 1184) st_bf8((u16*)(big + E_QNA) + (size_t)token * 512 + (f8 - 672), v, v1, rinv * (0.125f * LOG2E));
.LBB0_1044:
	s_andn2_b64 vcc, exec, s[28:29]
	s_cbranch_vccnz .LBB0_1046
	s_add_i32 s15, s13, s61
	v_lshl_add_u64 v[40:41], s[2:3], 0, v[64:65]
	v_add_u32_e32 v42, s15, v144
	v_mov_b32_e32 v43, v145
	v_lshl_add_u64 v[44:45], v[42:43], 1, v[40:41]
	v_mul_f32_e32 v40, v36, v62
	v_mul_f32_e32 v41, v37, v62
	v_mul_f32_e32 v42, v38, v62
	v_mul_f32_e32 v43, v39, v62
	v_cvt_pk_bf16_f32 v40, v40, v41
	v_cvt_pk_bf16_f32 v41, v42, v43
	v_mul_f32_e32 v42, v32, v62
	v_mul_f32_e32 v43, v33, v62
	v_mul_f32_e32 v46, v34, v62
	v_mul_f32_e32 v47, v35, v62
	v_add_co_u32_e32 v44, vcc, 0x29ff000, v44
	v_cvt_pk_bf16_f32 v42, v42, v43
	v_cvt_pk_bf16_f32 v43, v46, v47
	v_addc_co_u32_e32 v45, vcc, 0, v45, vcc
	global_store_dwordx4 v[44:45], v[40:43], off offset:3008

; DI void rope_perm(f32x4& a0, f32x4& a1, int fq, int lane, const float* tcos, const float* tsin, int pos) {
;   f32x4 p0, p1;
; #pragma unroll
;   for (int e = 0; e < 4; ++e) { p0[e] = shx(a0[e], 32, lane); p1[e] = shx(a1[e], 32, lane); }
;   const int jb = 8 * (fq & 1);
;   const f32x4 c0 = *(const f32x4*)(tcos + pos * 16 + jb), c1 = *(const f32x4*)(tcos + pos * 16 + jb + 4);
;   const f32x4 s0 = *(const f32x4*)(tsin + pos * 16 + jb), s1 = *(const f32x4*)(tsin + pos * 16 + jb + 4);
;   if (fq < 2) { a0 = a0 * c0 - p0 * s0; a1 = a1 * c1 - p1 * s1; }
;   else        { a0 = a0 * c0 + p0 * s0; a1 = a1 * c1 + p1 * s1; }
; }
;   DI void operator()(const f32x4 (&acc)[2][2][4][2], const pg8::Unit& u, int wr, int wc, int fr_, int fq_) const {
;     ...
;                 else if (gb < 672) {
;                   f32x4 a0 = v, a1 = v1;
;                   rope_perm(a0, a1, fq, t_ & 63, tcos, tsin, token & (S_ - 1));
;                   st_bf8((u16*)(big + E_KPE) + (size_t)token * 32 + 8 * fq, a0, a1, rinv);
;                 }
.LBB0_1047:
	s_andn2_b64 vcc, exec, s[28:29]
	s_cbranch_vccnz .LBB0_1053
	v_lshlrev_b32_e32 v44, 2, v57
	v_mov_b32_e32 v45, v145
	v_lshl_add_u64 v[40:41], s[4:5], 0, v[44:45]
	v_lshlrev_b32_e32 v46, 2, v199
	v_mov_b32_e32 v47, v145
	v_lshl_add_u64 v[44:45], s[6:7], 0, v[44:45]
	v_lshl_add_u64 v[50:51], v[40:41], 0, v[46:47]
	v_lshl_add_u64 v[52:53], v[44:45], 0, v[46:47]
	global_load_dwordx4 v[40:43], v[50:51], off
	global_load_dwordx4 v[44:47], v[52:53], off
	global_load_dwordx4 v[70:73], v[52:53], off offset:16
	global_load_dwordx4 v[74:77], v[50:51], off offset:16
	ds_bpermute_b32 v52, v198, v36
	ds_bpermute_b32 v62, v198, v32
	ds_bpermute_b32 v53, v198, v37
	ds_bpermute_b32 v63, v198, v33
	ds_bpermute_b32 v66, v198, v38
	ds_bpermute_b32 v78, v198, v34
	ds_bpermute_b32 v67, v198, v39
	ds_bpermute_b32 v79, v198, v35
	s_waitcnt vmcnt(0) lgkmcnt(0)
	v_mul_f32_e32 v64, v44, v52
	v_mul_f32_e32 v65, v45, v53
	v_mul_f32_e32 v50, v38, v42
	v_mul_f32_e32 v51, v39, v43
	v_mul_f32_e32 v54, v36, v40
	v_mul_f32_e32 v55, v37, v41
	v_mul_f32_e32 v68, v46, v66
	v_mul_f32_e32 v69, v47, v67
	v_mul_f32_e32 v52, v70, v62
	v_mul_f32_e32 v53, v71, v63
	v_mul_f32_e32 v62, v72, v78
	v_mul_f32_e32 v63, v73, v79
	v_mul_f32_e32 v66, v34, v76
	v_mul_f32_e32 v67, v35, v77
	v_mul_f32_e32 v70, v32, v74
	v_mul_f32_e32 v71, v33, v75
	s_and_saveexec_b64 s[28:29], s[92:93]
	s_xor_b64 s[28:29], exec, s[28:29]
	v_add_f32_e32 v42, v50, v68
	v_add_f32_e32 v43, v51, v69
	v_add_f32_e32 v40, v54, v64
	v_add_f32_e32 v41, v55, v65
	v_add_f32_e32 v46, v66, v62
	v_add_f32_e32 v47, v67, v63
	v_add_f32_e32 v44, v70, v52
	v_add_f32_e32 v45, v71, v53
	s_andn2_saveexec_b64 s[28:29], s[28:29]
	v_sub_f32_e32 v43, v51, v69
	v_sub_f32_e32 v42, v50, v68
	v_sub_f32_e32 v41, v55, v65
	v_sub_f32_e32 v40, v54, v64
	v_sub_f32_e32 v47, v67, v63
	v_sub_f32_e32 v46, v66, v62
	v_sub_f32_e32 v45, v71, v53
	v_sub_f32_e32 v44, v70, v52
	s_or_b64 exec, exec, s[28:29]
	v_mul_f32_e32 v40, v56, v40
	v_mul_f32_e32 v41, v56, v41
	v_mul_f32_e32 v42, v56, v42
	v_mul_f32_e32 v43, v56, v43
	v_lshl_add_u64 v[50:51], s[10:11], 0, v[60:61]
	v_lshlrev_b32_e32 v52, 1, v144
	v_mov_b32_e32 v53, v145
	v_cvt_pk_bf16_f32 v40, v40, v41
	v_cvt_pk_bf16_f32 v41, v42, v43
	v_mul_f32_e32 v42, v56, v44
	v_mul_f32_e32 v43, v56, v45
	v_mul_f32_e32 v44, v56, v46
	v_mul_f32_e32 v45, v56, v47
	v_lshl_add_u64 v[50:51], v[50:51], 0, v[52:53]
	v_cvt_pk_bf16_f32 v42, v42, v43
	v_cvt_pk_bf16_f32 v43, v44, v45
	global_store_dwordx4 v[50:51], v[40:43], off

; DI void st_bf8(u16* p, f32x4 a, f32x4 b, float sc) {
;   u32x4 u; u.x = pack2(a[0] * sc, a[1] * sc); u.y = pack2(a[2] * sc, a[3] * sc); u.z = pack2(b[0] * sc, b[1] * sc); u.w = pack2(b[2] * sc, b[3] * sc);
;   *(u32x4*)p = u;
;   DI void operator()(const f32x4 (&acc)[2][2][4][2], const pg8::Unit& u, int wr, int wc, int fr_, int fq_) const {
;     ...
;                 else if (gb < 640) st_bf8((u16*)(big + E_CKV) + (size_t)token * 256 + (f8 - 384), v, v1, rinv);
.LBB0_1054:
	s_andn2_b64 vcc, exec, s[28:29]
	s_cbranch_vccnz .LBB0_1056
	s_add_i32 s15, s13, s61
	v_lshl_add_u64 v[40:41], s[2:3], 0, v[58:59]
	v_add_u32_e32 v42, s15, v144
	v_mov_b32_e32 v43, v145
	v_lshl_add_u64 v[44:45], v[42:43], 1, v[40:41]
	v_mul_f32_e32 v40, v36, v56
	v_mul_f32_e32 v41, v37, v56
	v_mul_f32_e32 v42, v38, v56
	v_mul_f32_e32 v43, v39, v56
	v_cvt_pk_bf16_f32 v40, v40, v41
	v_cvt_pk_bf16_f32 v41, v42, v43
	v_mul_f32_e32 v42, v32, v56
	v_mul_f32_e32 v43, v33, v56
	v_mul_f32_e32 v46, v34, v56
	v_mul_f32_e32 v47, v35, v56
	v_add_co_u32_e32 v44, vcc, 0x17ff000, v44
	v_cvt_pk_bf16_f32 v42, v42, v43
	v_cvt_pk_bf16_f32 v43, v46, v47
	v_addc_co_u32_e32 v45, vcc, 0, v45, vcc
	global_store_dwordx4 v[44:45], v[40:43], off offset:3584

; DI void st_bf8(u16* p, f32x4 a, f32x4 b, float sc) {
;   u32x4 u; u.x = pack2(a[0] * sc, a[1] * sc); u.y = pack2(a[2] * sc, a[3] * sc); u.z = pack2(b[0] * sc, b[1] * sc); u.w = pack2(b[2] * sc, b[3] * sc);
;   *(u32x4*)p = u;
;   DI void operator()(const f32x4 (&acc)[2][2][4][2], const pg8::Unit& u, int wr, int wc, int fr_, int fq_) const {
;     ...
;         const int rl = ai * 128 + wr * 64 + m * 16 + fr;
;         const int token = u.pm * 256 + rl;
;         float rinv = 1.f;
;         if (EPI != EPI_RESID) rinv = rinv_tab[slot * 256 + rl];
;         float ssq = 0.f;
; #pragma unroll
;         for (int bj = 0; bj < 2; ++bj)
; #pragma unroll
;           for (int n = 0; n < 2; ++n) {
;             const int fb = u.pn * 256 + bj * 128 + wc * 32 + n * 16;
;             const int f = fb + 4 * fq;
;             const f32x4 v = acc[ai][bj][m][n];
;             if (EPI == EPI_ABIN) {
;               if (n == 0) {
;                 const int gb = u.pn * 256 + bj * 128 + wc * 32; const int f8 = gb + 8 * fq;
;                 const f32x4 v1 = acc[ai][bj][m][1];
;                 if (gb < 384) st_bf8((u16*)(big + E_CQ) + (size_t)token * 384 + f8, v, v1, rinv);
;                 else if (gb < 640) st_bf8((u16*)(big + E_CKV) + (size_t)token * 256 + (f8 - 384), v, v1, rinv);
;                 else if (gb < 672) {
;                   f32x4 a0 = v, a1 = v1;
;                   rope_perm(a0, a1, fq, t_ & 63, tcos, tsin, token & (S_ - 1));
;                   st_bf8((u16*)(big + E_KPE) + (size_t)token * 32 + 8 * fq, a0, a1, rinv);
;                 }
;                 else if (gb < 1184) st_bf8((u16*)(big + E_QNA) + (size_t)token * 512 + (f8 - 672), v, v1, rinv * (0.125f * LOG2E));
;                 else if (gb < 1696) st_bf8((u16*)(big + E_KNA) + (size_t)token * 512 + (f8 - 1184), v, v1, rinv);
;                 else if (gb < 2208) st_bf8((u16*)(big + E_VNAT) + (size_t)token * 512 + (f8 - 1696), v, v1, rinv);
.LBB0_1057:
	v_mul_f32_e32 v28, v28, v40
	v_mul_f32_e32 v29, v29, v40
	v_mul_f32_e32 v30, v30, v40
	v_mul_f32_e32 v31, v31, v40
	v_mul_f32_e32 v24, v24, v40
	v_mul_f32_e32 v25, v25, v40
	v_cvt_pk_bf16_f32 v28, v28, v29
	v_cvt_pk_bf16_f32 v29, v30, v31
	v_cvt_pk_bf16_f32 v30, v24, v25
	v_mul_f32_e32 v24, v26, v40
	v_mul_f32_e32 v25, v27, v40
	v_lshl_add_u64 v[34:35], v[150:151], 1, v[32:33]
	v_cvt_pk_bf16_f32 v31, v24, v25
	global_store_dwordx4 v[34:35], v[28:31], off
	s_and_b64 vcc, exec, s[78:79]
	s_mov_b64 s[28:29], -1
	s_cbranch_vccnz .LBB0_932
.LBB0_1058:
	s_and_b64 vcc, exec, s[94:95]
	s_cbranch_vccnz .LBB0_1078
	s_andn2_b64 vcc, exec, s[44:45]
	s_cbranch_vccnz .LBB0_1071
	s_andn2_b64 vcc, exec, s[42:43]
	s_cbranch_vccnz .LBB0_1068
	s_andn2_b64 vcc, exec, s[38:39]
	s_cbranch_vccnz .LBB0_1065
	s_andn2_b64 vcc, exec, s[36:37]
	s_cbranch_vccnz .LBB0_1064
	s_add_i32 s15, s13, s61
	v_lshl_add_u64 v[24:25], s[2:3], 0, v[48:49]
	v_add_u32_e32 v26, s15, v144
	v_mov_b32_e32 v27, v145
	v_lshl_add_u64 v[28:29], v[26:27], 1, v[24:25]
	v_mul_f32_e32 v24, v20, v40
	v_mul_f32_e32 v25, v21, v40
	v_mul_f32_e32 v26, v22, v40
	v_mul_f32_e32 v27, v23, v40
	v_cvt_pk_bf16_f32 v24, v24, v25
	v_cvt_pk_bf16_f32 v25, v26, v27
	v_mul_f32_e32 v26, v16, v40
	v_mul_f32_e32 v27, v17, v40
	v_mul_f32_e32 v30, v18, v40
	v_mul_f32_e32 v31, v19, v40
	v_add_co_u32_e32 v28, vcc, 0x69ff000, v28
	v_cvt_pk_bf16_f32 v26, v26, v27
	v_cvt_pk_bf16_f32 v27, v30, v31
	v_addc_co_u32_e32 v29, vcc, 0, v29, vcc
	global_store_dwordx4 v[28:29], v[24:27], off offset:960

; DI void st_bf8(u16* p, f32x4 a, f32x4 b, float sc) {
;   u32x4 u; u.x = pack2(a[0] * sc, a[1] * sc); u.y = pack2(a[2] * sc, a[3] * sc); u.z = pack2(b[0] * sc, b[1] * sc); u.w = pack2(b[2] * sc, b[3] * sc);
;   *(u32x4*)p = u;
;   DI void operator()(const f32x4 (&acc)[2][2][4][2], const pg8::Unit& u, int wr, int wc, int fr_, int fq_) const {
;     ...
;                 else if (gb < 1696) st_bf8((u16*)(big + E_KNA) + (size_t)token * 512 + (f8 - 1184), v, v1, rinv);
.LBB0_1065:
	s_andn2_b64 vcc, exec, s[28:29]
	s_cbranch_vccnz .LBB0_1067
	s_add_i32 s15, s13, s61
	v_lshl_add_u64 v[24:25], s[2:3], 0, v[48:49]
	v_add_u32_e32 v26, s15, v144
	v_mov_b32_e32 v27, v145
	v_lshl_add_u64 v[28:29], v[26:27], 1, v[24:25]
	v_mul_f32_e32 v24, v20, v40
	v_mul_f32_e32 v25, v21, v40
	v_mul_f32_e32 v26, v22, v40
	v_mul_f32_e32 v27, v23, v40
	v_cvt_pk_bf16_f32 v24, v24, v25
	v_cvt_pk_bf16_f32 v25, v26, v27
	v_mul_f32_e32 v26, v16, v40
	v_mul_f32_e32 v27, v17, v40
	v_mul_f32_e32 v30, v18, v40
	v_mul_f32_e32 v31, v19, v40
	v_add_co_u32_e32 v28, vcc, 0x49ff000, v28
	v_cvt_pk_bf16_f32 v26, v26, v27
	v_cvt_pk_bf16_f32 v27, v30, v31
	v_addc_co_u32_e32 v29, vcc, 0, v29, vcc
	global_store_dwordx4 v[28:29], v[24:27], off offset:1984

; DI void st_bf8(u16* p, f32x4 a, f32x4 b, float sc) {
;   u32x4 u; u.x = pack2(a[0] * sc, a[1] * sc); u.y = pack2(a[2] * sc, a[3] * sc); u.z = pack2(b[0] * sc, b[1] * sc); u.w = pack2(b[2] * sc, b[3] * sc);
;   *(u32x4*)p = u;
;   DI void operator()(const f32x4 (&acc)[2][2][4][2], const pg8::Unit& u, int wr, int wc, int fr_, int fq_) const {
;     ...
;                 else if (gb < 1184) st_bf8((u16*)(big + E_QNA) + (size_t)token * 512 + (f8 - 672), v, v1, rinv * (0.125f * LOG2E));
.LBB0_1068:
	s_andn2_b64 vcc, exec, s[28:29]
	s_cbranch_vccnz .LBB0_1070
	s_add_i32 s15, s13, s61
	v_lshl_add_u64 v[24:25], s[2:3], 0, v[48:49]
	v_add_u32_e32 v26, s15, v144
	v_mov_b32_e32 v27, v145
	v_lshl_add_u64 v[28:29], v[26:27], 1, v[24:25]
	v_mul_f32_e32 v24, v20, v46
	v_mul_f32_e32 v25, v21, v46
	v_mul_f32_e32 v26, v22, v46
	v_mul_f32_e32 v27, v23, v46
	v_cvt_pk_bf16_f32 v24, v24, v25
	v_cvt_pk_bf16_f32 v25, v26, v27
	v_mul_f32_e32 v26, v16, v46
	v_mul_f32_e32 v27, v17, v46
	v_mul_f32_e32 v30, v18, v46
	v_mul_f32_e32 v31, v19, v46
	v_add_co_u32_e32 v28, vcc, 0x29ff000, v28
	v_cvt_pk_bf16_f32 v26, v26, v27
	v_cvt_pk_bf16_f32 v27, v30, v31
	v_addc_co_u32_e32 v29, vcc, 0, v29, vcc
	global_store_dwordx4 v[28:29], v[24:27], off offset:3008

; DI void rope_perm(f32x4& a0, f32x4& a1, int fq, int lane, const float* tcos, const float* tsin, int pos) {
;   f32x4 p0, p1;
; #pragma unroll
;   for (int e = 0; e < 4; ++e) { p0[e] = shx(a0[e], 32, lane); p1[e] = shx(a1[e], 32, lane); }
;   const int jb = 8 * (fq & 1);
;   const f32x4 c0 = *(const f32x4*)(tcos + pos * 16 + jb), c1 = *(const f32x4*)(tcos + pos * 16 + jb + 4);
;   const f32x4 s0 = *(const f32x4*)(tsin + pos * 16 + jb), s1 = *(const f32x4*)(tsin + pos * 16 + jb + 4);
;   if (fq < 2) { a0 = a0 * c0 - p0 * s0; a1 = a1 * c1 - p1 * s1; }
;   else        { a0 = a0 * c0 + p0 * s0; a1 = a1 * c1 + p1 * s1; }
; }
;   DI void operator()(const f32x4 (&acc)[2][2][4][2], const pg8::Unit& u, int wr, int wc, int fr_, int fq_) const {
;     ...
;                 else if (gb < 672) {
;                   f32x4 a0 = v, a1 = v1;
;                   rope_perm(a0, a1, fq, t_ & 63, tcos, tsin, token & (S_ - 1));
;                   st_bf8((u16*)(big + E_KPE) + (size_t)token * 32 + 8 * fq, a0, a1, rinv);
.LBB0_1071:
	s_andn2_b64 vcc, exec, s[28:29]
	s_cbranch_vccnz .LBB0_1077
	v_lshlrev_b32_e32 v28, 2, v41
	v_mov_b32_e32 v29, v145
	v_lshl_add_u64 v[24:25], s[4:5], 0, v[28:29]
	v_lshlrev_b32_e32 v30, 2, v199
	v_mov_b32_e32 v31, v145
	v_lshl_add_u64 v[28:29], s[6:7], 0, v[28:29]
	v_lshl_add_u64 v[34:35], v[24:25], 0, v[30:31]
	v_lshl_add_u64 v[36:37], v[28:29], 0, v[30:31]
	global_load_dwordx4 v[24:27], v[34:35], off
	global_load_dwordx4 v[28:31], v[36:37], off
	global_load_dwordx4 v[54:57], v[36:37], off offset:16
	global_load_dwordx4 v[58:61], v[34:35], off offset:16
	ds_bpermute_b32 v36, v198, v20
	ds_bpermute_b32 v46, v198, v16
	ds_bpermute_b32 v37, v198, v21
	ds_bpermute_b32 v47, v198, v17
	ds_bpermute_b32 v50, v198, v22
	ds_bpermute_b32 v62, v198, v18
	ds_bpermute_b32 v51, v198, v23
	ds_bpermute_b32 v63, v198, v19
	s_waitcnt vmcnt(0) lgkmcnt(0)
	v_mul_f32_e32 v48, v28, v36
	v_mul_f32_e32 v49, v29, v37
	v_mul_f32_e32 v34, v22, v26
	v_mul_f32_e32 v35, v23, v27
	v_mul_f32_e32 v38, v20, v24
	v_mul_f32_e32 v39, v21, v25
	v_mul_f32_e32 v52, v30, v50
	v_mul_f32_e32 v53, v31, v51
	v_mul_f32_e32 v36, v54, v46
	v_mul_f32_e32 v37, v55, v47
	v_mul_f32_e32 v46, v56, v62
	v_mul_f32_e32 v47, v57, v63
	v_mul_f32_e32 v50, v18, v60
	v_mul_f32_e32 v51, v19, v61
	v_mul_f32_e32 v54, v16, v58
	v_mul_f32_e32 v55, v17, v59
	s_and_saveexec_b64 s[28:29], s[92:93]
	s_xor_b64 s[28:29], exec, s[28:29]
	v_add_f32_e32 v26, v34, v52
	v_add_f32_e32 v27, v35, v53
	v_add_f32_e32 v24, v38, v48
	v_add_f32_e32 v25, v39, v49
	v_add_f32_e32 v30, v50, v46
	v_add_f32_e32 v31, v51, v47
	v_add_f32_e32 v28, v54, v36
	v_add_f32_e32 v29, v55, v37
	s_andn2_saveexec_b64 s[28:29], s[28:29]
	v_sub_f32_e32 v27, v35, v53
	v_sub_f32_e32 v26, v34, v52
	v_sub_f32_e32 v25, v39, v49
	v_sub_f32_e32 v24, v38, v48
	v_sub_f32_e32 v31, v51, v47
	v_sub_f32_e32 v30, v50, v46
	v_sub_f32_e32 v29, v55, v37
	v_sub_f32_e32 v28, v54, v36
	s_or_b64 exec, exec, s[28:29]
	v_mul_f32_e32 v24, v40, v24
	v_mul_f32_e32 v25, v40, v25
	v_mul_f32_e32 v26, v40, v26
	v_mul_f32_e32 v27, v40, v27
	v_lshl_add_u64 v[34:35], s[10:11], 0, v[44:45]
	v_lshlrev_b32_e32 v36, 1, v144
	v_mov_b32_e32 v37, v145
	v_cvt_pk_bf16_f32 v24, v24, v25
	v_cvt_pk_bf16_f32 v25, v26, v27
	v_mul_f32_e32 v26, v40, v28
	v_mul_f32_e32 v27, v40, v29
	v_mul_f32_e32 v28, v40, v30
	v_mul_f32_e32 v29, v40, v31
	v_lshl_add_u64 v[34:35], v[34:35], 0, v[36:37]
	v_cvt_pk_bf16_f32 v26, v26, v27
	v_cvt_pk_bf16_f32 v27, v28, v29
	global_store_dwordx4 v[34:35], v[24:27], off

; DI void st_bf8(u16* p, f32x4 a, f32x4 b, float sc) {
;   u32x4 u; u.x = pack2(a[0] * sc, a[1] * sc); u.y = pack2(a[2] * sc, a[3] * sc); u.z = pack2(b[0] * sc, b[1] * sc); u.w = pack2(b[2] * sc, b[3] * sc);
;   *(u32x4*)p = u;
;   DI void operator()(const f32x4 (&acc)[2][2][4][2], const pg8::Unit& u, int wr, int wc, int fr_, int fq_) const {
;     ...
;                 if (gb < 384) st_bf8((u16*)(big + E_CQ) + (size_t)token * 384 + f8, v, v1, rinv);
;                 else if (gb < 640) st_bf8((u16*)(big + E_CKV) + (size_t)token * 256 + (f8 - 384), v, v1, rinv);
.LBB0_1078:
	s_andn2_b64 vcc, exec, s[28:29]
	s_cbranch_vccnz .LBB0_1080
	s_add_i32 s15, s13, s61
	v_lshl_add_u64 v[24:25], s[2:3], 0, v[42:43]
	v_add_u32_e32 v26, s15, v144
	v_mov_b32_e32 v27, v145
	v_lshl_add_u64 v[28:29], v[26:27], 1, v[24:25]
	v_mul_f32_e32 v24, v20, v40
	v_mul_f32_e32 v25, v21, v40
	v_mul_f32_e32 v26, v22, v40
	v_mul_f32_e32 v27, v23, v40
	v_cvt_pk_bf16_f32 v24, v24, v25
	v_cvt_pk_bf16_f32 v25, v26, v27
	v_mul_f32_e32 v26, v16, v40
	v_mul_f32_e32 v27, v17, v40
	v_mul_f32_e32 v30, v18, v40
	v_mul_f32_e32 v31, v19, v40
	v_add_co_u32_e32 v28, vcc, 0x17ff000, v28
	v_cvt_pk_bf16_f32 v26, v26, v27
	v_cvt_pk_bf16_f32 v27, v30, v31
	v_addc_co_u32_e32 v29, vcc, 0, v29, vcc
	global_store_dwordx4 v[28:29], v[24:27], off offset:3584

;   DI void operator()(const f32x4 (&acc)[2][2][4][2], const pg8::Unit& u, int wr, int wc, int fr_, int fq_) const {
;     ...
;             if (EPI == EPI_ABIN) {
;               if (n == 0) {
;                 const int gb = u.pn * 256 + bj * 128 + wc * 32; const int f8 = gb + 8 * fq;
;                 const f32x4 v1 = acc[ai][bj][m][1];
;                 if (gb < 384) st_bf8((u16*)(big + E_CQ) + (size_t)token * 384 + f8, v, v1, rinv);
;                 else if (gb < 640) st_bf8((u16*)(big + E_CKV) + (size_t)token * 256 + (f8 - 384), v, v1, rinv);
;                 else if (gb < 672) {
;                   f32x4 a0 = v, a1 = v1;
;                   rope_perm(a0, a1, fq, t_ & 63, tcos, tsin, token & (S_ - 1));
;                   st_bf8((u16*)(big + E_KPE) + (size_t)token * 32 + 8 * fq, a0, a1, rinv);
;                 }
;                 else if (gb < 1184) st_bf8((u16*)(big + E_QNA) + (size_t)token * 512 + (f8 - 672), v, v1, rinv * (0.125f * LOG2E));
;                 else if (gb < 1696) st_bf8((u16*)(big + E_KNA) + (size_t)token * 512 + (f8 - 1184), v, v1, rinv);
;                 else if (gb < 2208) st_bf8((u16*)(big + E_VNAT) + (size_t)token * 512 + (f8 - 1696), v, v1, rinv);
.LBB0_1081:
	v_mul_f32_e32 v12, v12, v24
	v_mul_f32_e32 v13, v13, v24
	v_mul_f32_e32 v14, v14, v24
	v_mul_f32_e32 v15, v15, v24
	v_mul_f32_e32 v8, v8, v24
	v_mul_f32_e32 v9, v9, v24
	v_cvt_pk_bf16_f32 v12, v12, v13
	v_cvt_pk_bf16_f32 v13, v14, v15
	v_cvt_pk_bf16_f32 v14, v8, v9
	v_mul_f32_e32 v8, v10, v24
	v_mul_f32_e32 v9, v11, v24
	v_lshl_add_u64 v[18:19], v[150:151], 1, v[16:17]
	v_cvt_pk_bf16_f32 v15, v8, v9
	global_store_dwordx4 v[18:19], v[12:15], off
	s_and_b64 vcc, exec, s[78:79]
	s_mov_b64 s[20:21], -1
	s_cbranch_vccnz .LBB0_960
.LBB0_1082:
	s_and_b64 vcc, exec, s[94:95]
	s_cbranch_vccnz .LBB0_1102
	s_andn2_b64 vcc, exec, s[44:45]
	s_cbranch_vccnz .LBB0_1095
	s_andn2_b64 vcc, exec, s[42:43]
	s_cbranch_vccnz .LBB0_1092
	s_andn2_b64 vcc, exec, s[38:39]
	s_cbranch_vccnz .LBB0_1089
	s_andn2_b64 vcc, exec, s[36:37]
	s_cbranch_vccnz .LBB0_1088
	s_add_i32 s15, s13, s61
	v_lshl_add_u64 v[8:9], s[2:3], 0, v[32:33]
	v_add_u32_e32 v10, s15, v144
	v_mov_b32_e32 v11, v145
	v_lshl_add_u64 v[12:13], v[10:11], 1, v[8:9]
	v_mul_f32_e32 v8, v4, v24
	v_mul_f32_e32 v9, v5, v24
	v_mul_f32_e32 v10, v6, v24
	v_mul_f32_e32 v11, v7, v24
	v_cvt_pk_bf16_f32 v8, v8, v9
	v_cvt_pk_bf16_f32 v9, v10, v11
	v_mul_f32_e32 v10, v0, v24
	v_mul_f32_e32 v11, v1, v24
	v_mul_f32_e32 v14, v2, v24
	v_mul_f32_e32 v15, v3, v24
	v_add_co_u32_e32 v12, vcc, 0x69ff000, v12
	v_cvt_pk_bf16_f32 v10, v10, v11
	v_cvt_pk_bf16_f32 v11, v14, v15
	v_addc_co_u32_e32 v13, vcc, 0, v13, vcc
	global_store_dwordx4 v[12:13], v[8:11], off offset:960

; DI void st_bf8(u16* p, f32x4 a, f32x4 b, float sc) {
;   u32x4 u; u.x = pack2(a[0] * sc, a[1] * sc); u.y = pack2(a[2] * sc, a[3] * sc); u.z = pack2(b[0] * sc, b[1] * sc); u.w = pack2(b[2] * sc, b[3] * sc);
;   *(u32x4*)p = u;
;   DI void operator()(const f32x4 (&acc)[2][2][4][2], const pg8::Unit& u, int wr, int wc, int fr_, int fq_) const {
;     ...
;                 else if (gb < 1184) st_bf8((u16*)(big + E_QNA) + (size_t)token * 512 + (f8 - 672), v, v1, rinv * (0.125f * LOG2E));
;                 else if (gb < 1696) st_bf8((u16*)(big + E_KNA) + (size_t)token * 512 + (f8 - 1184), v, v1, rinv);
.LBB0_1089:
	s_andn2_b64 vcc, exec, s[20:21]
	s_cbranch_vccnz .LBB0_1091
	s_add_i32 s15, s13, s61
	v_lshl_add_u64 v[8:9], s[2:3], 0, v[32:33]
	v_add_u32_e32 v10, s15, v144
	v_mov_b32_e32 v11, v145
	v_lshl_add_u64 v[12:13], v[10:11], 1, v[8:9]
	v_mul_f32_e32 v8, v4, v24
	v_mul_f32_e32 v9, v5, v24
	v_mul_f32_e32 v10, v6, v24
	v_mul_f32_e32 v11, v7, v24
	v_cvt_pk_bf16_f32 v8, v8, v9
	v_cvt_pk_bf16_f32 v9, v10, v11
	v_mul_f32_e32 v10, v0, v24
	v_mul_f32_e32 v11, v1, v24
	v_mul_f32_e32 v14, v2, v24
	v_mul_f32_e32 v15, v3, v24
	v_add_co_u32_e32 v12, vcc, 0x49ff000, v12
	v_cvt_pk_bf16_f32 v10, v10, v11
	v_cvt_pk_bf16_f32 v11, v14, v15
	v_addc_co_u32_e32 v13, vcc, 0, v13, vcc
	global_store_dwordx4 v[12:13], v[8:11], off offset:1984

; DI void st_bf8(u16* p, f32x4 a, f32x4 b, float sc) {
;   u32x4 u; u.x = pack2(a[0] * sc, a[1] * sc); u.y = pack2(a[2] * sc, a[3] * sc); u.z = pack2(b[0] * sc, b[1] * sc); u.w = pack2(b[2] * sc, b[3] * sc);
;   *(u32x4*)p = u;
;   DI void operator()(const f32x4 (&acc)[2][2][4][2], const pg8::Unit& u, int wr, int wc, int fr_, int fq_) const {
;     ...
;                 else if (gb < 1184) st_bf8((u16*)(big + E_QNA) + (size_t)token * 512 + (f8 - 672), v, v1, rinv * (0.125f * LOG2E));
.LBB0_1092:
	s_andn2_b64 vcc, exec, s[20:21]
	s_cbranch_vccnz .LBB0_1094
	s_add_i32 s15, s13, s61
	v_lshl_add_u64 v[8:9], s[2:3], 0, v[32:33]
	v_add_u32_e32 v10, s15, v144
	v_mov_b32_e32 v11, v145
	v_lshl_add_u64 v[12:13], v[10:11], 1, v[8:9]
	v_mul_f32_e32 v8, v4, v30
	v_mul_f32_e32 v9, v5, v30
	v_mul_f32_e32 v10, v6, v30
	v_mul_f32_e32 v11, v7, v30
	v_cvt_pk_bf16_f32 v8, v8, v9
	v_cvt_pk_bf16_f32 v9, v10, v11
	v_mul_f32_e32 v10, v0, v30
	v_mul_f32_e32 v11, v1, v30
	v_mul_f32_e32 v14, v2, v30
	v_mul_f32_e32 v15, v3, v30
	v_add_co_u32_e32 v12, vcc, 0x29ff000, v12
	v_cvt_pk_bf16_f32 v10, v10, v11
	v_cvt_pk_bf16_f32 v11, v14, v15
	v_addc_co_u32_e32 v13, vcc, 0, v13, vcc
	global_store_dwordx4 v[12:13], v[8:11], off offset:3008

; DI void rope_perm(f32x4& a0, f32x4& a1, int fq, int lane, const float* tcos, const float* tsin, int pos) {
;   f32x4 p0, p1;
; #pragma unroll
;   for (int e = 0; e < 4; ++e) { p0[e] = shx(a0[e], 32, lane); p1[e] = shx(a1[e], 32, lane); }
;   const int jb = 8 * (fq & 1);
;   const f32x4 c0 = *(const f32x4*)(tcos + pos * 16 + jb), c1 = *(const f32x4*)(tcos + pos * 16 + jb + 4);
;   const f32x4 s0 = *(const f32x4*)(tsin + pos * 16 + jb), s1 = *(const f32x4*)(tsin + pos * 16 + jb + 4);
;   if (fq < 2) { a0 = a0 * c0 - p0 * s0; a1 = a1 * c1 - p1 * s1; }
;   else        { a0 = a0 * c0 + p0 * s0; a1 = a1 * c1 + p1 * s1; }
; }
;   DI void operator()(const f32x4 (&acc)[2][2][4][2], const pg8::Unit& u, int wr, int wc, int fr_, int fq_) const {
;     ...
;                 else if (gb < 672) {
;                   f32x4 a0 = v, a1 = v1;
;                   rope_perm(a0, a1, fq, t_ & 63, tcos, tsin, token & (S_ - 1));
;                   st_bf8((u16*)(big + E_KPE) + (size_t)token * 32 + 8 * fq, a0, a1, rinv);
.LBB0_1095:
	s_andn2_b64 vcc, exec, s[20:21]
	s_cbranch_vccnz .LBB0_1101
	v_lshlrev_b32_e32 v12, 2, v25
	v_mov_b32_e32 v13, v145
	v_lshl_add_u64 v[8:9], s[4:5], 0, v[12:13]
	v_lshlrev_b32_e32 v14, 2, v199
	v_mov_b32_e32 v15, v145
	v_lshl_add_u64 v[12:13], s[6:7], 0, v[12:13]
	v_lshl_add_u64 v[18:19], v[8:9], 0, v[14:15]
	v_lshl_add_u64 v[20:21], v[12:13], 0, v[14:15]
	global_load_dwordx4 v[8:11], v[18:19], off
	global_load_dwordx4 v[12:15], v[20:21], off
	global_load_dwordx4 v[38:41], v[20:21], off offset:16
	global_load_dwordx4 v[42:45], v[18:19], off offset:16
	ds_bpermute_b32 v20, v198, v4
	ds_bpermute_b32 v30, v198, v0
	ds_bpermute_b32 v21, v198, v5
	ds_bpermute_b32 v31, v198, v1
	ds_bpermute_b32 v34, v198, v6
	ds_bpermute_b32 v46, v198, v2
	ds_bpermute_b32 v35, v198, v7
	ds_bpermute_b32 v47, v198, v3
	s_waitcnt vmcnt(0) lgkmcnt(0)
	v_mul_f32_e32 v32, v12, v20
	v_mul_f32_e32 v33, v13, v21
	v_mul_f32_e32 v18, v6, v10
	v_mul_f32_e32 v19, v7, v11
	v_mul_f32_e32 v22, v4, v8
	v_mul_f32_e32 v23, v5, v9
	v_mul_f32_e32 v36, v14, v34
	v_mul_f32_e32 v37, v15, v35
	v_mul_f32_e32 v20, v38, v30
	v_mul_f32_e32 v21, v39, v31
	v_mul_f32_e32 v30, v40, v46
	v_mul_f32_e32 v31, v41, v47
	v_mul_f32_e32 v34, v2, v44
	v_mul_f32_e32 v35, v3, v45
	v_mul_f32_e32 v38, v0, v42
	v_mul_f32_e32 v39, v1, v43
	s_and_saveexec_b64 s[20:21], s[92:93]
	s_xor_b64 s[20:21], exec, s[20:21]
	v_add_f32_e32 v10, v18, v36
	v_add_f32_e32 v11, v19, v37
	v_add_f32_e32 v8, v22, v32
	v_add_f32_e32 v9, v23, v33
	v_add_f32_e32 v14, v34, v30
	v_add_f32_e32 v15, v35, v31
	v_add_f32_e32 v12, v38, v20
	v_add_f32_e32 v13, v39, v21
	s_andn2_saveexec_b64 s[20:21], s[20:21]
	v_sub_f32_e32 v11, v19, v37
	v_sub_f32_e32 v10, v18, v36
	v_sub_f32_e32 v9, v23, v33
	v_sub_f32_e32 v8, v22, v32
	v_sub_f32_e32 v15, v35, v31
	v_sub_f32_e32 v14, v34, v30
	v_sub_f32_e32 v13, v39, v21
	v_sub_f32_e32 v12, v38, v20
	s_or_b64 exec, exec, s[20:21]
	v_mul_f32_e32 v8, v24, v8
	v_mul_f32_e32 v9, v24, v9
	v_mul_f32_e32 v10, v24, v10
	v_mul_f32_e32 v11, v24, v11
	v_lshl_add_u64 v[18:19], s[10:11], 0, v[28:29]
	v_lshlrev_b32_e32 v20, 1, v144
	v_mov_b32_e32 v21, v145
	v_cvt_pk_bf16_f32 v8, v8, v9
	v_cvt_pk_bf16_f32 v9, v10, v11
	v_mul_f32_e32 v10, v24, v12
	v_mul_f32_e32 v11, v24, v13
	v_mul_f32_e32 v12, v24, v14
	v_mul_f32_e32 v13, v24, v15
	v_lshl_add_u64 v[18:19], v[18:19], 0, v[20:21]
	v_cvt_pk_bf16_f32 v10, v10, v11
	v_cvt_pk_bf16_f32 v11, v12, v13
	global_store_dwordx4 v[18:19], v[8:11], off

; DI void st_bf8(u16* p, f32x4 a, f32x4 b, float sc) {
;   u32x4 u; u.x = pack2(a[0] * sc, a[1] * sc); u.y = pack2(a[2] * sc, a[3] * sc); u.z = pack2(b[0] * sc, b[1] * sc); u.w = pack2(b[2] * sc, b[3] * sc);
;   *(u32x4*)p = u;
;   DI void operator()(const f32x4 (&acc)[2][2][4][2], const pg8::Unit& u, int wr, int wc, int fr_, int fq_) const {
;     ...
;                 else if (gb < 640) st_bf8((u16*)(big + E_CKV) + (size_t)token * 256 + (f8 - 384), v, v1, rinv);
.LBB0_1102:
	s_andn2_b64 vcc, exec, s[20:21]
	s_cbranch_vccnz .LBB0_1104
	s_add_i32 s15, s13, s61
	v_lshl_add_u64 v[8:9], s[2:3], 0, v[26:27]
	v_add_u32_e32 v10, s15, v144
	v_mov_b32_e32 v11, v145
	v_lshl_add_u64 v[12:13], v[10:11], 1, v[8:9]
	v_mul_f32_e32 v8, v4, v24
	v_mul_f32_e32 v9, v5, v24
	v_mul_f32_e32 v10, v6, v24
	v_mul_f32_e32 v11, v7, v24
	v_cvt_pk_bf16_f32 v8, v8, v9
	v_cvt_pk_bf16_f32 v9, v10, v11
	v_mul_f32_e32 v10, v0, v24
	v_mul_f32_e32 v11, v1, v24
	v_mul_f32_e32 v14, v2, v24
	v_mul_f32_e32 v15, v3, v24
	v_add_co_u32_e32 v12, vcc, 0x17ff000, v12
	v_cvt_pk_bf16_f32 v10, v10, v11
	v_cvt_pk_bf16_f32 v11, v14, v15
	v_addc_co_u32_e32 v13, vcc, 0, v13, vcc
	global_store_dwordx4 v[12:13], v[8:11], off offset:3584

; DI void st_bf8(u16* p, f32x4 a, f32x4 b, float sc) {
;   u32x4 u; u.x = pack2(a[0] * sc, a[1] * sc); u.y = pack2(a[2] * sc, a[3] * sc); u.z = pack2(b[0] * sc, b[1] * sc); u.w = pack2(b[2] * sc, b[3] * sc);
;   *(u32x4*)p = u;
;   DI void operator()(const f32x4 (&acc)[2][2][4][2], const pg8::Unit& u, int wr, int wc, int fr_, int fq_) const {
;     ...
;                 if (gb < 384) st_bf8((u16*)(big + E_CQ) + (size_t)token * 384 + f8, v, v1, rinv);
.LBB0_1105:
	s_ashr_i32 s15, s13, 31
	s_add_u32 s20, s13, s61
	s_addc_u32 s21, s15, 0
	v_mul_f32_e32 v4, v4, v24
	v_mul_f32_e32 v5, v5, v24
	v_mul_f32_e32 v6, v6, v24
	v_mul_f32_e32 v7, v7, v24
	v_mul_f32_e32 v0, v0, v24
	v_mul_f32_e32 v1, v1, v24
	v_lshl_add_u64 v[8:9], v[144:145], 0, s[20:21]
	v_cvt_pk_bf16_f32 v4, v4, v5
	v_cvt_pk_bf16_f32 v5, v6, v7
	v_cvt_pk_bf16_f32 v6, v0, v1
	v_mul_f32_e32 v0, v2, v24
	v_mul_f32_e32 v1, v3, v24
	v_lshl_add_u64 v[8:9], v[8:9], 1, v[16:17]
	v_cvt_pk_bf16_f32 v7, v0, v1
	global_store_dwordx4 v[8:9], v[4:7], off offset:256
	s_branch .LBB0_685

; DI float bf2f(unsigned v) { return __uint_as_float(v << 16); }
; DI void rinv_prepass(const u16* __restrict__ A, int K, const pg8::StaticOrder& S, LAS float* tab) {
;     ...
;   for (int i = 0; i < 4 && S.next(i, u); ++i) {
;     const u16* pr = A + (size_t)(u.pm * 256 + row) * K + half * (K >> 1);
;     float ss = 0.f;
;     for (int c = 0; c < (K >> 1); c += 8) {
;       u32x4 w = *(const u32x4*)(pr + c);
;       float a;
;       a = bf2f(w.x & 0xffffu); ss += a * a; a = bf2f(w.x >> 16); ss += a * a;
;       a = bf2f(w.y & 0xffffu); ss += a * a; a = bf2f(w.y >> 16); ss += a * a;
;       a = bf2f(w.z & 0xffffu); ss += a * a; a = bf2f(w.z >> 16); ss += a * a;
;       a = bf2f(w.w & 0xffffu); ss += a * a; a = bf2f(w.w >> 16); ss += a * a;
;     }
;     ss += shx(ss, 1, tid & 63);
;     if (!half) tab[i * 256 + row] = rsqrtf(ss / (float)K + EPS);
;   }
.LBB0_1168:
	global_load_dwordx4 v[8:11], v[0:1], off offset:16
	global_load_dwordx4 v[12:15], v[0:1], off
	global_load_dwordx4 v[16:19], v[0:1], off offset:-16
	global_load_dwordx4 v[20:23], v[0:1], off offset:-32
	s_add_i32 s2, s2, 32
	v_lshl_add_u64 v[0:1], v[0:1], 0, 64
	s_cmpk_gt_u32 s2, 0xb7
	s_waitcnt vmcnt(0)
	v_lshlrev_b32_e32 v4, 16, v20
	v_lshlrev_b32_e32 v25, 16, v21
	v_and_b32_e32 v24, 0xffff0000, v20
	v_fmac_f32_e32 v6, v4, v4
	v_mul_f32_e32 v24, v24, v24
	v_mul_f32_e32 v25, v25, v25
	v_lshlrev_b32_e32 v7, 16, v22
	v_add_f32_e32 v4, v24, v6
	v_and_b32_e32 v6, 0xffff0000, v21
	v_add_f32_e32 v4, v25, v4
	v_mul_f32_e32 v6, v6, v6
	v_mul_f32_e32 v7, v7, v7
	s_nop 0
	v_add_f32_e32 v4, v6, v4
	v_add_f32_e32 v4, v7, v4
	v_lshlrev_b32_e32 v7, 16, v23
	v_and_b32_e32 v6, 0xffff0000, v22
	v_mul_f32_e32 v6, v6, v6
	v_mul_f32_e32 v7, v7, v7
	s_nop 0
	v_add_f32_e32 v4, v6, v4
	v_add_f32_e32 v4, v7, v4
	v_and_b32_e32 v6, 0xffff0000, v23
	v_fmac_f32_e32 v4, v6, v6
	v_lshlrev_b32_e32 v6, 16, v16
	v_fmac_f32_e32 v4, v6, v6
	v_lshlrev_b32_e32 v7, 16, v17
	v_and_b32_e32 v6, 0xffff0000, v16
	v_mul_f32_e32 v6, v6, v6
	v_mul_f32_e32 v7, v7, v7
	s_nop 0
	v_add_f32_e32 v4, v6, v4
	v_add_f32_e32 v4, v7, v4
	v_lshlrev_b32_e32 v7, 16, v18
	v_and_b32_e32 v6, 0xffff0000, v17
	v_mul_f32_e32 v6, v6, v6
	v_mul_f32_e32 v7, v7, v7
	s_nop 0
	v_add_f32_e32 v4, v6, v4
	v_add_f32_e32 v4, v7, v4
	v_lshlrev_b32_e32 v7, 16, v19
	v_and_b32_e32 v6, 0xffff0000, v18
	v_mul_f32_e32 v6, v6, v6
	v_mul_f32_e32 v7, v7, v7
	s_nop 0
	v_add_f32_e32 v4, v6, v4
	v_add_f32_e32 v4, v7, v4
	v_and_b32_e32 v6, 0xffff0000, v19
	v_fmac_f32_e32 v4, v6, v6
	v_lshlrev_b32_e32 v6, 16, v12
	v_fmac_f32_e32 v4, v6, v6
	v_lshlrev_b32_e32 v7, 16, v13
	v_and_b32_e32 v6, 0xffff0000, v12
	v_mul_f32_e32 v6, v6, v6
	v_mul_f32_e32 v7, v7, v7
	s_nop 0
	v_add_f32_e32 v4, v6, v4
	v_add_f32_e32 v4, v7, v4
	v_lshlrev_b32_e32 v7, 16, v14
	v_and_b32_e32 v6, 0xffff0000, v13
	v_mul_f32_e32 v6, v6, v6
	v_mul_f32_e32 v7, v7, v7
	s_nop 0
	v_add_f32_e32 v4, v6, v4
	v_add_f32_e32 v4, v7, v4
	v_lshlrev_b32_e32 v7, 16, v15
	v_and_b32_e32 v6, 0xffff0000, v14
	v_mul_f32_e32 v6, v6, v6
	v_mul_f32_e32 v7, v7, v7
	s_nop 0
	v_add_f32_e32 v4, v6, v4
	v_add_f32_e32 v4, v7, v4
	v_and_b32_e32 v6, 0xffff0000, v15
	v_fmac_f32_e32 v4, v6, v6
	v_lshlrev_b32_e32 v6, 16, v8
	v_fmac_f32_e32 v4, v6, v6
	v_lshlrev_b32_e32 v7, 16, v9
	v_and_b32_e32 v6, 0xffff0000, v8
	v_mul_f32_e32 v6, v6, v6
	v_mul_f32_e32 v7, v7, v7
	s_nop 0
	v_add_f32_e32 v4, v6, v4
	v_add_f32_e32 v4, v7, v4
	v_lshlrev_b32_e32 v7, 16, v10
	v_and_b32_e32 v6, 0xffff0000, v9
	v_mul_f32_e32 v6, v6, v6
	v_mul_f32_e32 v7, v7, v7
	s_nop 0
	v_add_f32_e32 v4, v6, v4
	v_add_f32_e32 v4, v7, v4
	v_lshlrev_b32_e32 v7, 16, v11
	v_and_b32_e32 v6, 0xffff0000, v10
	v_mul_f32_e32 v6, v6, v6
	v_mul_f32_e32 v7, v7, v7
	s_nop 0
	v_add_f32_e32 v4, v6, v4
	v_add_f32_e32 v6, v7, v4
	v_and_b32_e32 v4, 0xffff0000, v11
	v_fmac_f32_e32 v6, v4, v4
	s_cbranch_scc0 .LBB0_1168
	v_lshlrev_b32_e32 v0, 2, v2
	v_bitop3_b32 v4, v0, 4, v190 bitop3:0x6c
	ds_bpermute_b32 v0, v4, v6
	v_readlane_b32 s2, v238, 44
	v_cmp_eq_u32_e64 s[78:79], 0, v5
	s_nop 0
	v_lshl_add_u32 v2, v3, 2, s2
	s_and_saveexec_b64 s[2:3], s[78:79]
	s_cbranch_execz .LBB0_1171
	s_waitcnt lgkmcnt(0)
	v_add_f32_e32 v0, v6, v0
	s_mov_b32 s6, 0x43c00000
	v_div_scale_f32 v1, s[4:5], s6, s6, v0
	v_rcp_f32_e32 v5, v1
	v_div_scale_f32 v6, vcc, v0, s6, v0
	s_mov_b32 s4, 0x800000
	v_fma_f32 v7, -v1, v5, 1.0
	v_fmac_f32_e32 v5, v7, v5
	v_mul_f32_e32 v7, v6, v5
	v_fma_f32 v8, -v1, v7, v6
	v_fmac_f32_e32 v7, v8, v5
	v_fma_f32 v1, -v1, v7, v6
	v_div_fmas_f32 v1, v1, v5, v7
	v_div_fixup_f32 v0, v1, s6, v0
	v_add_f32_e32 v0, 0x358637bd, v0
	v_mul_f32_e32 v1, 0x4b800000, v0
	v_cmp_gt_f32_e32 vcc, s4, v0
	s_nop 1
	v_cndmask_b32_e32 v0, v0, v1, vcc
	v_rsq_f32_e32 v0, v0
	s_nop 0
	v_mul_f32_e32 v1, 0x45800000, v0
	v_cndmask_b32_e32 v0, v0, v1, vcc
	ds_write_b32 v2, v0

; DI float bf2f(unsigned v) { return __uint_as_float(v << 16); }
; DI void rinv_prepass(const u16* __restrict__ A, int K, const pg8::StaticOrder& S, LAS float* tab) {
;     ...
;   for (int i = 0; i < 4 && S.next(i, u); ++i) {
;     const u16* pr = A + (size_t)(u.pm * 256 + row) * K + half * (K >> 1);
;     float ss = 0.f;
;     for (int c = 0; c < (K >> 1); c += 8) {
;       u32x4 w = *(const u32x4*)(pr + c);
;       float a;
;       a = bf2f(w.x & 0xffffu); ss += a * a; a = bf2f(w.x >> 16); ss += a * a;
;       a = bf2f(w.y & 0xffffu); ss += a * a; a = bf2f(w.y >> 16); ss += a * a;
;       a = bf2f(w.z & 0xffffu); ss += a * a; a = bf2f(w.z >> 16); ss += a * a;
;       a = bf2f(w.w & 0xffffu); ss += a * a; a = bf2f(w.w >> 16); ss += a * a;
;     }
;     ss += shx(ss, 1, tid & 63);
;     if (!half) tab[i * 256 + row] = rsqrtf(ss / (float)K + EPS);
;   }
.LBB0_1173:
	global_load_dwordx4 v[6:9], v[0:1], off offset:16
	global_load_dwordx4 v[10:13], v[0:1], off
	global_load_dwordx4 v[14:17], v[0:1], off offset:-16
	global_load_dwordx4 v[18:21], v[0:1], off offset:-32
	s_add_i32 s2, s2, 32
	v_lshl_add_u64 v[0:1], v[0:1], 0, 64
	s_cmpk_lt_u32 s2, 0xb8
	s_waitcnt vmcnt(0)
	v_lshlrev_b32_e32 v22, 16, v18
	v_fmac_f32_e32 v5, v22, v22
	v_lshlrev_b32_e32 v23, 16, v19
	v_and_b32_e32 v22, 0xffff0000, v18
	v_mul_f32_e32 v22, v22, v22
	v_mul_f32_e32 v23, v23, v23
	s_nop 0
	v_add_f32_e32 v5, v22, v5
	v_add_f32_e32 v5, v23, v5
	v_lshlrev_b32_e32 v23, 16, v20
	v_and_b32_e32 v22, 0xffff0000, v19
	v_mul_f32_e32 v18, v22, v22
	v_mul_f32_e32 v19, v23, v23
	s_nop 0
	v_add_f32_e32 v5, v18, v5
	v_add_f32_e32 v5, v19, v5
	v_lshlrev_b32_e32 v19, 16, v21
	v_and_b32_e32 v18, 0xffff0000, v20
	v_mul_f32_e32 v18, v18, v18
	v_mul_f32_e32 v19, v19, v19
	s_nop 0
	v_add_f32_e32 v5, v18, v5
	v_add_f32_e32 v5, v19, v5
	v_and_b32_e32 v18, 0xffff0000, v21
	v_fmac_f32_e32 v5, v18, v18
	v_lshlrev_b32_e32 v18, 16, v14
	v_fmac_f32_e32 v5, v18, v18
	v_lshlrev_b32_e32 v19, 16, v15
	v_and_b32_e32 v18, 0xffff0000, v14
	v_mul_f32_e32 v18, v18, v18
	v_mul_f32_e32 v19, v19, v19
	s_nop 0
	v_add_f32_e32 v5, v18, v5
	v_add_f32_e32 v5, v19, v5
	v_lshlrev_b32_e32 v19, 16, v16
	v_and_b32_e32 v18, 0xffff0000, v15
	v_mul_f32_e32 v14, v18, v18
	v_mul_f32_e32 v15, v19, v19
	s_nop 0
	v_add_f32_e32 v5, v14, v5
	v_add_f32_e32 v5, v15, v5
	v_lshlrev_b32_e32 v15, 16, v17
	v_and_b32_e32 v14, 0xffff0000, v16
	v_mul_f32_e32 v14, v14, v14
	v_mul_f32_e32 v15, v15, v15
	s_nop 0
	v_add_f32_e32 v5, v14, v5
	v_add_f32_e32 v5, v15, v5
	v_and_b32_e32 v14, 0xffff0000, v17
	v_fmac_f32_e32 v5, v14, v14
	v_lshlrev_b32_e32 v14, 16, v10
	v_fmac_f32_e32 v5, v14, v14
	v_lshlrev_b32_e32 v15, 16, v11
	v_and_b32_e32 v14, 0xffff0000, v10
	v_mul_f32_e32 v14, v14, v14
	v_mul_f32_e32 v15, v15, v15
	s_nop 0
	v_add_f32_e32 v5, v14, v5
	v_add_f32_e32 v5, v15, v5
	v_lshlrev_b32_e32 v15, 16, v12
	v_and_b32_e32 v14, 0xffff0000, v11
	v_mul_f32_e32 v10, v14, v14
	v_mul_f32_e32 v11, v15, v15
	s_nop 0
	v_add_f32_e32 v5, v10, v5
	v_add_f32_e32 v5, v11, v5
	v_lshlrev_b32_e32 v11, 16, v13
	v_and_b32_e32 v10, 0xffff0000, v12
	v_mul_f32_e32 v10, v10, v10
	v_mul_f32_e32 v11, v11, v11
	s_nop 0
	v_add_f32_e32 v5, v10, v5
	v_add_f32_e32 v5, v11, v5
	v_and_b32_e32 v10, 0xffff0000, v13
	v_fmac_f32_e32 v5, v10, v10
	v_lshlrev_b32_e32 v10, 16, v6
	v_fmac_f32_e32 v5, v10, v10
	v_lshlrev_b32_e32 v11, 16, v7
	v_and_b32_e32 v10, 0xffff0000, v6
	v_mul_f32_e32 v10, v10, v10
	v_mul_f32_e32 v11, v11, v11
	s_nop 0
	v_add_f32_e32 v5, v10, v5
	v_add_f32_e32 v5, v11, v5
	v_lshlrev_b32_e32 v11, 16, v8
	v_and_b32_e32 v10, 0xffff0000, v7
	v_mul_f32_e32 v6, v10, v10
	v_mul_f32_e32 v7, v11, v11
	s_nop 0
	v_add_f32_e32 v5, v6, v5
	v_add_f32_e32 v5, v7, v5
	v_lshlrev_b32_e32 v7, 16, v9
	v_and_b32_e32 v6, 0xffff0000, v8
	v_mul_f32_e32 v6, v6, v6
	v_mul_f32_e32 v7, v7, v7
	s_nop 0
	v_add_f32_e32 v5, v6, v5
	v_add_f32_e32 v5, v7, v5
	v_and_b32_e32 v6, 0xffff0000, v9
	v_fmac_f32_e32 v5, v6, v6
	s_cbranch_scc1 .LBB0_1173
	ds_bpermute_b32 v0, v4, v5
	s_and_saveexec_b64 s[2:3], s[78:79]
	s_cbranch_execz .LBB0_1176
	s_waitcnt lgkmcnt(0)
	v_add_f32_e32 v0, v5, v0
	s_mov_b32 s6, 0x43c00000
	v_div_scale_f32 v1, s[4:5], s6, s6, v0
	v_rcp_f32_e32 v5, v1
	v_div_scale_f32 v6, vcc, v0, s6, v0
	s_mov_b32 s4, 0x800000
	v_fma_f32 v7, -v1, v5, 1.0
	v_fmac_f32_e32 v5, v7, v5
	v_mul_f32_e32 v7, v6, v5
	v_fma_f32 v8, -v1, v7, v6
	v_fmac_f32_e32 v7, v8, v5
	v_fma_f32 v1, -v1, v7, v6
	v_div_fmas_f32 v1, v1, v5, v7
	v_div_fixup_f32 v0, v1, s6, v0
	v_add_f32_e32 v0, 0x358637bd, v0
	v_mul_f32_e32 v1, 0x4b800000, v0
	v_cmp_gt_f32_e32 vcc, s4, v0
	s_nop 1
	v_cndmask_b32_e32 v0, v0, v1, vcc
	v_rsq_f32_e32 v0, v0
	s_nop 0
	v_mul_f32_e32 v1, 0x45800000, v0
	v_cndmask_b32_e32 v0, v0, v1, vcc
	ds_write_b32 v2, v0 offset:1024

; DI float bf2f(unsigned v) { return __uint_as_float(v << 16); }
; DI void rinv_prepass(const u16* __restrict__ A, int K, const pg8::StaticOrder& S, LAS float* tab) {
;     ...
;   for (int i = 0; i < 4 && S.next(i, u); ++i) {
;     const u16* pr = A + (size_t)(u.pm * 256 + row) * K + half * (K >> 1);
;     float ss = 0.f;
;     for (int c = 0; c < (K >> 1); c += 8) {
;       u32x4 w = *(const u32x4*)(pr + c);
;       float a;
;       a = bf2f(w.x & 0xffffu); ss += a * a; a = bf2f(w.x >> 16); ss += a * a;
;       a = bf2f(w.y & 0xffffu); ss += a * a; a = bf2f(w.y >> 16); ss += a * a;
;       a = bf2f(w.z & 0xffffu); ss += a * a; a = bf2f(w.z >> 16); ss += a * a;
;       a = bf2f(w.w & 0xffffu); ss += a * a; a = bf2f(w.w >> 16); ss += a * a;
;     }
;     ss += shx(ss, 1, tid & 63);
;     if (!half) tab[i * 256 + row] = rsqrtf(ss / (float)K + EPS);
;   }
.LBB0_1178:
	global_load_dwordx4 v[6:9], v[0:1], off offset:16
	global_load_dwordx4 v[10:13], v[0:1], off
	global_load_dwordx4 v[14:17], v[0:1], off offset:-16
	global_load_dwordx4 v[18:21], v[0:1], off offset:-32
	s_add_i32 s2, s2, 32
	v_lshl_add_u64 v[0:1], v[0:1], 0, 64
	s_cmpk_lt_u32 s2, 0xb8
	s_waitcnt vmcnt(0)
	v_lshlrev_b32_e32 v22, 16, v18
	v_fmac_f32_e32 v5, v22, v22
	v_lshlrev_b32_e32 v23, 16, v19
	v_and_b32_e32 v22, 0xffff0000, v18
	v_mul_f32_e32 v22, v22, v22
	v_mul_f32_e32 v23, v23, v23
	s_nop 0
	v_add_f32_e32 v5, v22, v5
	v_add_f32_e32 v5, v23, v5
	v_lshlrev_b32_e32 v23, 16, v20
	v_and_b32_e32 v22, 0xffff0000, v19
	v_mul_f32_e32 v18, v22, v22
	v_mul_f32_e32 v19, v23, v23
	s_nop 0
	v_add_f32_e32 v5, v18, v5
	v_add_f32_e32 v5, v19, v5
	v_lshlrev_b32_e32 v19, 16, v21
	v_and_b32_e32 v18, 0xffff0000, v20
	v_mul_f32_e32 v18, v18, v18
	v_mul_f32_e32 v19, v19, v19
	s_nop 0
	v_add_f32_e32 v5, v18, v5
	v_add_f32_e32 v5, v19, v5
	v_and_b32_e32 v18, 0xffff0000, v21
	v_fmac_f32_e32 v5, v18, v18
	v_lshlrev_b32_e32 v18, 16, v14
	v_fmac_f32_e32 v5, v18, v18
	v_lshlrev_b32_e32 v19, 16, v15
	v_and_b32_e32 v18, 0xffff0000, v14
	v_mul_f32_e32 v18, v18, v18
	v_mul_f32_e32 v19, v19, v19
	s_nop 0
	v_add_f32_e32 v5, v18, v5
	v_add_f32_e32 v5, v19, v5
	v_lshlrev_b32_e32 v19, 16, v16
	v_and_b32_e32 v18, 0xffff0000, v15
	v_mul_f32_e32 v14, v18, v18
	v_mul_f32_e32 v15, v19, v19
	s_nop 0
	v_add_f32_e32 v5, v14, v5
	v_add_f32_e32 v5, v15, v5
	v_lshlrev_b32_e32 v15, 16, v17
	v_and_b32_e32 v14, 0xffff0000, v16
	v_mul_f32_e32 v14, v14, v14
	v_mul_f32_e32 v15, v15, v15
	s_nop 0
	v_add_f32_e32 v5, v14, v5
	v_add_f32_e32 v5, v15, v5
	v_and_b32_e32 v14, 0xffff0000, v17
	v_fmac_f32_e32 v5, v14, v14
	v_lshlrev_b32_e32 v14, 16, v10
	v_fmac_f32_e32 v5, v14, v14
	v_lshlrev_b32_e32 v15, 16, v11
	v_and_b32_e32 v14, 0xffff0000, v10
	v_mul_f32_e32 v14, v14, v14
	v_mul_f32_e32 v15, v15, v15
	s_nop 0
	v_add_f32_e32 v5, v14, v5
	v_add_f32_e32 v5, v15, v5
	v_lshlrev_b32_e32 v15, 16, v12
	v_and_b32_e32 v14, 0xffff0000, v11
	v_mul_f32_e32 v10, v14, v14
	v_mul_f32_e32 v11, v15, v15
	s_nop 0
	v_add_f32_e32 v5, v10, v5
	v_add_f32_e32 v5, v11, v5
	v_lshlrev_b32_e32 v11, 16, v13
	v_and_b32_e32 v10, 0xffff0000, v12
	v_mul_f32_e32 v10, v10, v10
	v_mul_f32_e32 v11, v11, v11
	s_nop 0
	v_add_f32_e32 v5, v10, v5
	v_add_f32_e32 v5, v11, v5
	v_and_b32_e32 v10, 0xffff0000, v13
	v_fmac_f32_e32 v5, v10, v10
	v_lshlrev_b32_e32 v10, 16, v6
	v_fmac_f32_e32 v5, v10, v10
	v_lshlrev_b32_e32 v11, 16, v7
	v_and_b32_e32 v10, 0xffff0000, v6
	v_mul_f32_e32 v10, v10, v10
	v_mul_f32_e32 v11, v11, v11
	s_nop 0
	v_add_f32_e32 v5, v10, v5
	v_add_f32_e32 v5, v11, v5
	v_lshlrev_b32_e32 v11, 16, v8
	v_and_b32_e32 v10, 0xffff0000, v7
	v_mul_f32_e32 v6, v10, v10
	v_mul_f32_e32 v7, v11, v11
	s_nop 0
	v_add_f32_e32 v5, v6, v5
	v_add_f32_e32 v5, v7, v5
	v_lshlrev_b32_e32 v7, 16, v9
	v_and_b32_e32 v6, 0xffff0000, v8
	v_mul_f32_e32 v6, v6, v6
	v_mul_f32_e32 v7, v7, v7
	s_nop 0
	v_add_f32_e32 v5, v6, v5
	v_add_f32_e32 v5, v7, v5
	v_and_b32_e32 v6, 0xffff0000, v9
	v_fmac_f32_e32 v5, v6, v6
	s_cbranch_scc1 .LBB0_1178
	ds_bpermute_b32 v0, v4, v5
	s_and_saveexec_b64 s[2:3], s[78:79]
	s_cbranch_execz .LBB0_1181
	s_waitcnt lgkmcnt(0)
	v_add_f32_e32 v0, v5, v0
	s_mov_b32 s6, 0x43c00000
	v_div_scale_f32 v1, s[4:5], s6, s6, v0
	v_rcp_f32_e32 v5, v1
	v_div_scale_f32 v6, vcc, v0, s6, v0
	s_mov_b32 s4, 0x800000
	v_fma_f32 v7, -v1, v5, 1.0
	v_fmac_f32_e32 v5, v7, v5
	v_mul_f32_e32 v7, v6, v5
	v_fma_f32 v8, -v1, v7, v6
	v_fmac_f32_e32 v7, v8, v5
	v_fma_f32 v1, -v1, v7, v6
	v_div_fmas_f32 v1, v1, v5, v7
	v_div_fixup_f32 v0, v1, s6, v0
	v_add_f32_e32 v0, 0x358637bd, v0
	v_mul_f32_e32 v1, 0x4b800000, v0
	v_cmp_gt_f32_e32 vcc, s4, v0
	s_nop 1
	v_cndmask_b32_e32 v0, v0, v1, vcc
	v_rsq_f32_e32 v0, v0
	s_nop 0
	v_mul_f32_e32 v1, 0x45800000, v0
	v_cndmask_b32_e32 v0, v0, v1, vcc
	ds_write_b32 v2, v0 offset:2048

; DI float bf2f(unsigned v) { return __uint_as_float(v << 16); }
; DI void rinv_prepass(const u16* __restrict__ A, int K, const pg8::StaticOrder& S, LAS float* tab) {
;     ...
;   for (int i = 0; i < 4 && S.next(i, u); ++i) {
;     const u16* pr = A + (size_t)(u.pm * 256 + row) * K + half * (K >> 1);
;     float ss = 0.f;
;     for (int c = 0; c < (K >> 1); c += 8) {
;       u32x4 w = *(const u32x4*)(pr + c);
;       float a;
;       a = bf2f(w.x & 0xffffu); ss += a * a; a = bf2f(w.x >> 16); ss += a * a;
;       a = bf2f(w.y & 0xffffu); ss += a * a; a = bf2f(w.y >> 16); ss += a * a;
;       a = bf2f(w.z & 0xffffu); ss += a * a; a = bf2f(w.z >> 16); ss += a * a;
;       a = bf2f(w.w & 0xffffu); ss += a * a; a = bf2f(w.w >> 16); ss += a * a;
;     }
;     ss += shx(ss, 1, tid & 63);
;     if (!half) tab[i * 256 + row] = rsqrtf(ss / (float)K + EPS);
;   }
.LBB0_1183:
	global_load_dwordx4 v[6:9], v[0:1], off offset:16
	global_load_dwordx4 v[10:13], v[0:1], off
	global_load_dwordx4 v[14:17], v[0:1], off offset:-16
	global_load_dwordx4 v[18:21], v[0:1], off offset:-32
	s_add_i32 s2, s2, 32
	v_lshl_add_u64 v[0:1], v[0:1], 0, 64
	s_cmpk_lt_u32 s2, 0xb8
	s_waitcnt vmcnt(0)
	v_lshlrev_b32_e32 v5, 16, v18
	v_lshlrev_b32_e32 v23, 16, v19
	v_and_b32_e32 v22, 0xffff0000, v18
	v_fmac_f32_e32 v3, v5, v5
	v_mul_f32_e32 v22, v22, v22
	v_mul_f32_e32 v23, v23, v23
	v_and_b32_e32 v5, 0xffff0000, v21
	v_add_f32_e32 v3, v22, v3
	v_add_f32_e32 v3, v23, v3
	v_lshlrev_b32_e32 v23, 16, v20
	v_and_b32_e32 v22, 0xffff0000, v19
	v_mul_f32_e32 v18, v22, v22
	v_mul_f32_e32 v19, v23, v23
	s_nop 0
	v_add_f32_e32 v3, v18, v3
	v_add_f32_e32 v3, v19, v3
	v_lshlrev_b32_e32 v19, 16, v21
	v_and_b32_e32 v18, 0xffff0000, v20
	v_mul_f32_e32 v18, v18, v18
	v_mul_f32_e32 v19, v19, v19
	s_nop 0
	v_add_f32_e32 v3, v18, v3
	v_add_f32_e32 v3, v19, v3
	v_fmac_f32_e32 v3, v5, v5
	v_lshlrev_b32_e32 v5, 16, v14
	v_lshlrev_b32_e32 v19, 16, v15
	v_and_b32_e32 v18, 0xffff0000, v14
	v_fmac_f32_e32 v3, v5, v5
	v_mul_f32_e32 v18, v18, v18
	v_mul_f32_e32 v19, v19, v19
	v_and_b32_e32 v5, 0xffff0000, v17
	v_add_f32_e32 v3, v18, v3
	v_add_f32_e32 v3, v19, v3
	v_lshlrev_b32_e32 v19, 16, v16
	v_and_b32_e32 v18, 0xffff0000, v15
	v_mul_f32_e32 v14, v18, v18
	v_mul_f32_e32 v15, v19, v19
	s_nop 0
	v_add_f32_e32 v3, v14, v3
	v_add_f32_e32 v3, v15, v3
	v_lshlrev_b32_e32 v15, 16, v17
	v_and_b32_e32 v14, 0xffff0000, v16
	v_mul_f32_e32 v14, v14, v14
	v_mul_f32_e32 v15, v15, v15
	s_nop 0
	v_add_f32_e32 v3, v14, v3
	v_add_f32_e32 v3, v15, v3
	v_fmac_f32_e32 v3, v5, v5
	v_lshlrev_b32_e32 v5, 16, v10
	v_lshlrev_b32_e32 v15, 16, v11
	v_and_b32_e32 v14, 0xffff0000, v10
	v_fmac_f32_e32 v3, v5, v5
	v_mul_f32_e32 v14, v14, v14
	v_mul_f32_e32 v15, v15, v15
	v_and_b32_e32 v5, 0xffff0000, v13
	v_add_f32_e32 v3, v14, v3
	v_add_f32_e32 v3, v15, v3
	v_lshlrev_b32_e32 v15, 16, v12
	v_and_b32_e32 v14, 0xffff0000, v11
	v_mul_f32_e32 v10, v14, v14
	v_mul_f32_e32 v11, v15, v15
	s_nop 0
	v_add_f32_e32 v3, v10, v3
	v_add_f32_e32 v3, v11, v3
	v_lshlrev_b32_e32 v11, 16, v13
	v_and_b32_e32 v10, 0xffff0000, v12
	v_mul_f32_e32 v10, v10, v10
	v_mul_f32_e32 v11, v11, v11
	s_nop 0
	v_add_f32_e32 v3, v10, v3
	v_add_f32_e32 v3, v11, v3
	v_fmac_f32_e32 v3, v5, v5
	v_lshlrev_b32_e32 v5, 16, v6
	v_lshlrev_b32_e32 v11, 16, v7
	v_and_b32_e32 v10, 0xffff0000, v6
	v_fmac_f32_e32 v3, v5, v5
	v_mul_f32_e32 v10, v10, v10
	v_mul_f32_e32 v11, v11, v11
	v_and_b32_e32 v5, 0xffff0000, v9
	v_add_f32_e32 v3, v10, v3
	v_add_f32_e32 v3, v11, v3
	v_lshlrev_b32_e32 v11, 16, v8
	v_and_b32_e32 v10, 0xffff0000, v7
	v_mul_f32_e32 v6, v10, v10
	v_mul_f32_e32 v7, v11, v11
	s_nop 0
	v_add_f32_e32 v3, v6, v3
	v_add_f32_e32 v3, v7, v3
	v_lshlrev_b32_e32 v7, 16, v9
	v_and_b32_e32 v6, 0xffff0000, v8
	v_mul_f32_e32 v6, v6, v6
	v_mul_f32_e32 v7, v7, v7
	s_nop 0
	v_add_f32_e32 v3, v6, v3
	v_add_f32_e32 v3, v7, v3
	v_fmac_f32_e32 v3, v5, v5
	s_cbranch_scc1 .LBB0_1183
	ds_bpermute_b32 v0, v4, v3
	s_and_saveexec_b64 s[2:3], s[78:79]
	s_cbranch_execz .LBB0_1186
	s_waitcnt lgkmcnt(0)
	v_add_f32_e32 v0, v3, v0
	s_mov_b32 s6, 0x43c00000
	v_div_scale_f32 v1, s[4:5], s6, s6, v0
	v_rcp_f32_e32 v3, v1
	v_div_scale_f32 v4, vcc, v0, s6, v0
	s_mov_b32 s4, 0x800000
	v_fma_f32 v5, -v1, v3, 1.0
	v_fmac_f32_e32 v3, v5, v3
	v_mul_f32_e32 v5, v4, v3
	v_fma_f32 v6, -v1, v5, v4
	v_fmac_f32_e32 v5, v6, v3
	v_fma_f32 v1, -v1, v5, v4
	v_div_fmas_f32 v1, v1, v3, v5
	v_div_fixup_f32 v0, v1, s6, v0
	v_add_f32_e32 v0, 0x358637bd, v0
	v_mul_f32_e32 v1, 0x4b800000, v0
	v_cmp_gt_f32_e32 vcc, s4, v0
	s_nop 1
	v_cndmask_b32_e32 v0, v0, v1, vcc
	v_rsq_f32_e32 v0, v0
	s_nop 0
	v_mul_f32_e32 v1, 0x45800000, v0
	v_cndmask_b32_e32 v0, v0, v1, vcc
	ds_write_b32 v2, v0 offset:3072

;   DI void operator()(const f32x4 (&acc)[2][2][4][2], const pg8::Unit& u, int wr, int wc, int fr_, int fq_) const {
;     ...
;             } else if (EPI == EPI_UQ) {
;               if (n == 0) {
;                 const float sc = rinv * (0.10206207261596575f * LOG2E);
;                 const int gb = u.pn * 256 + bj * 128 + wc * 32;
;                 const int hd = gb / 96; const int within = gb - hd * 96;
;                 f32x4 a0 = v, a1 = acc[ai][bj][m][1];
;                 if (within == 64) rope_perm(a0, a1, fq, t_ & 63, tcos, tsin, token & (S_ - 1));
;                 st_bf8((u16*)(big + E_QMLA) + (size_t)token * 768 + gb + 8 * fq, a0, a1, sc);
;               }
.LBB0_1194:
	v_mov_b32_e32 v19, v18
	v_mul_f32_e32 v4, v18, v4
	v_mul_f32_e32 v5, v19, v5
	v_mul_f32_e32 v6, v18, v6
	v_mul_f32_e32 v7, v19, v7
	v_mul_f32_e32 v0, v18, v0
	v_mul_f32_e32 v1, v19, v1
	v_cvt_pk_bf16_f32 v4, v4, v5
	v_cvt_pk_bf16_f32 v5, v6, v7
	v_cvt_pk_bf16_f32 v6, v0, v1
	v_mul_f32_e32 v0, v18, v2
	v_mul_f32_e32 v1, v19, v3
	s_and_b64 vcc, exec, s[76:77]
	v_cvt_pk_bf16_f32 v7, v0, v1
	s_mov_b32 s51, s46
	s_mov_b32 s49, s47
	s_mov_b32 s50, s48
	s_mov_b64 s[20:21], s[4:5]
	s_mov_b64 s[18:19], s[2:3]
	global_store_dwordx4 v[20:21], v[4:7], off offset:256
	s_cbranch_vccnz .LBB0_1298

; #define PG8_STAGE(bufoff, gbase, voff) do { _Pragma("unroll") for (int _i = 0; _i < 2; ++_i) \
;     __builtin_amdgcn_global_load_lds((const unsigned*)((const char*)(gbase) + (voff)[_i]), (LAS unsigned*)(lds + (bufoff) + ldsw + _i * 8192), 16, 0, 0); } while (0)
; #define PG8_LDA(dst, b, h) do { _Pragma("unroll") for (int m = 0; m < 4; ++m) _Pragma("unroll") for (int k = 0; k < 2; ++k) dst[m][k] = *(const LAS bf16x8*)(lds + PG8_SA(b, h) + aoff + m * 2048 + k * 1024); } while (0)
; #define PG8_LDB(dst, b, h) do { _Pragma("unroll") for (int n = 0; n < 2; ++n) _Pragma("unroll") for (int k = 0; k < 2; ++k) dst[n][k] = *(const LAS bf16x8*)(lds + PG8_SB(b, h) + boff + n * 2048 + k * 1024); } while (0)
; #define PG8_MMA(ai, bj, At, Bt) do { __builtin_amdgcn_s_setprio(1); _Pragma("unroll") for (int m = 0; m < 4; ++m) _Pragma("unroll") for (int n = 0; n < 2; ++n) _Pragma("unroll") for (int k = 0; k < 2; ++k) \
;     acc[ai][bj][m][n] = __builtin_amdgcn_mfma_f32_16x16x32_bf16(Bt[n][k], At[m][k], acc[ai][bj][m][n], 0, 0, 0); __builtin_amdgcn_s_setprio(0); } while (0)
; #define PG8_WAIT_V(n) asm volatile("s_waitcnt vmcnt(" #n ")" ::: "memory")
; template <class Epi, class Sched>
; DI void gemm_phase(LAS unsigned char* lds, const Gemm g, const Sched& S, const Epi& E) {
;     ...
;     for (int t = 0; t < nt; t += 2) {
;       const bool last = (t == nt - 2);
;       const char* a1 = cA + (size_t)(t + 1) * kstep;
;       const char* a2 = last ? nA : cA + (size_t)(t + 2) * kstep; const char* b2 = last ? nB : cB + (size_t)(t + 2) * kstep;
;       const char* a3 = a2 + kstep; const char* b3 = b2 + kstep;
;       PG8_LDB(B0, 0, 0); PG8_SCHED; PG8_LDA(At, 0, 0); PG8_STAGE(PG8_SA(1, 1), a1 + hstep, voffA);
;       PG8_WAIT_L(8); PG8_BAR; PG8_WAIT_L(0); PG8_MMA(0, 0, At, B0); PG8_BAR; PG8_SCHED;
;       PG8_LDB(B1, 0, 1); PG8_STAGE(PG8_SB(0, 0), b2, voffB);
;       PG8_BAR; PG8_WAIT_L(0); PG8_MMA(0, 1, At, B1); PG8_BAR;
;       PG8_LDA(At, 0, 1); PG8_STAGE(PG8_SA(0, 0), a2, voffA);
;       PG8_BAR; PG8_WAIT_L(0); PG8_MMA(1, 0, At, B0); PG8_BAR; PG8_SCHED;
;       PG8_STAGE(PG8_SB(0, 1), b2 + hstep, voffB);
;       PG8_WAIT_V(6); PG8_BAR; PG8_MMA(1, 1, At, B1); PG8_BAR;
;       PG8_LDB(B0, 1, 0); PG8_SCHED; PG8_LDA(At, 1, 0); PG8_STAGE(PG8_SA(0, 1), a2 + hstep, voffA);
;       PG8_WAIT_L(8); PG8_BAR; PG8_WAIT_L(0); PG8_MMA(0, 0, At, B0); PG8_BAR; PG8_SCHED;
.LBB0_1202:
	s_add_u32 s20, s18, 0x100
	s_addc_u32 s21, s19, 0
	s_add_i32 s55, 0, 0x10000
	ds_read_b128 v[140:143], v224
	ds_read_b128 v[146:149], v224 offset:1024
	ds_read_b128 v[150:153], v224 offset:2048
	ds_read_b128 v[154:157], v224 offset:3072
	s_cmp_eq_u32 s54, 2
	s_cselect_b32 s29, s3, s21
	s_cselect_b32 s28, s2, s20
	s_cselect_b32 s23, s5, s53
	s_cselect_b32 s22, s4, s52
	s_add_i32 m0, s38, 0xc000
	ds_read_b128 v[158:161], v163
	ds_read_b128 v[164:167], v163 offset:1024
	ds_read_b128 v[168:171], v163 offset:2048
	ds_read_b128 v[172:175], v163 offset:3072
	ds_read_b128 v[176:179], v163 offset:4096
	ds_read_b128 v[196:199], v163 offset:5120
	ds_read_b128 v[200:203], v163 offset:6144
	ds_read_b128 v[204:207], v163 offset:7168
	global_load_lds_dwordx4 v136, s[18:19]
	s_add_i32 m0, s38, 0xe000
	s_nop 0
	global_load_lds_dwordx4 v138, s[18:19]
	s_waitcnt lgkmcnt(8)
	s_barrier
	s_waitcnt lgkmcnt(0)
	v_mfma_f32_16x16x32_bf16 v[124:127], v[140:143], v[158:161], v[124:127]
	v_mfma_f32_16x16x32_bf16 v[120:123], v[150:153], v[158:161], v[120:123]
	v_mfma_f32_16x16x32_bf16 v[108:111], v[140:143], v[168:171], v[108:111]
	v_mfma_f32_16x16x32_bf16 v[104:107], v[150:153], v[168:171], v[104:107]
	v_mfma_f32_16x16x32_bf16 v[92:95], v[140:143], v[176:179], v[92:95]
	v_mfma_f32_16x16x32_bf16 v[88:91], v[150:153], v[176:179], v[88:91]
	v_mfma_f32_16x16x32_bf16 v[76:79], v[140:143], v[200:203], v[76:79]
	v_mfma_f32_16x16x32_bf16 v[72:75], v[150:153], v[200:203], v[72:75]
	v_mfma_f32_16x16x32_bf16 v[124:127], v[146:149], v[164:167], v[124:127]
	v_mfma_f32_16x16x32_bf16 v[120:123], v[154:157], v[164:167], v[120:123]
	v_mfma_f32_16x16x32_bf16 v[108:111], v[146:149], v[172:175], v[108:111]
	v_mfma_f32_16x16x32_bf16 v[104:107], v[154:157], v[172:175], v[104:107]
	v_mfma_f32_16x16x32_bf16 v[92:95], v[146:149], v[196:199], v[92:95]
	v_mfma_f32_16x16x32_bf16 v[88:91], v[154:157], v[196:199], v[88:91]
	v_mfma_f32_16x16x32_bf16 v[76:79], v[146:149], v[204:207], v[76:79]
	v_mfma_f32_16x16x32_bf16 v[72:75], v[154:157], v[204:207], v[72:75]
	s_barrier
	s_add_i32 s56, 0, 0x14000
	s_add_i32 s18, s55, s35
	s_add_u32 vcc_lo, s22, s0
	s_addc_u32 vcc_hi, s23, s1
	s_mov_b32 m0, s18
	ds_read_b128 v[208:211], v225
	ds_read_b128 v[212:215], v225 offset:1024
	ds_read_b128 v[216:219], v225 offset:2048
	ds_read_b128 v[220:223], v225 offset:3072
	global_load_lds_dwordx4 v130, s[22:23]
	s_add_i32 m0, s18, 0x2000
	s_nop 0
	global_load_lds_dwordx4 v134, s[22:23]
	s_barrier
	s_waitcnt lgkmcnt(0)
	v_mfma_f32_16x16x32_bf16 v[116:119], v[208:211], v[158:161], v[116:119]
	v_mfma_f32_16x16x32_bf16 v[112:115], v[216:219], v[158:161], v[112:115]
	v_mfma_f32_16x16x32_bf16 v[100:103], v[208:211], v[168:171], v[100:103]
	v_mfma_f32_16x16x32_bf16 v[96:99], v[216:219], v[168:171], v[96:99]
	v_mfma_f32_16x16x32_bf16 v[84:87], v[208:211], v[176:179], v[84:87]
	v_mfma_f32_16x16x32_bf16 v[80:83], v[216:219], v[176:179], v[80:83]
	v_mfma_f32_16x16x32_bf16 v[68:71], v[208:211], v[200:203], v[68:71]
	v_mfma_f32_16x16x32_bf16 v[64:67], v[216:219], v[200:203], v[64:67]
	v_mfma_f32_16x16x32_bf16 v[116:119], v[212:215], v[164:167], v[116:119]
	v_mfma_f32_16x16x32_bf16 v[112:115], v[220:223], v[164:167], v[112:115]
	v_mfma_f32_16x16x32_bf16 v[100:103], v[212:215], v[172:175], v[100:103]
	v_mfma_f32_16x16x32_bf16 v[96:99], v[220:223], v[172:175], v[96:99]
	v_mfma_f32_16x16x32_bf16 v[84:87], v[212:215], v[196:199], v[84:87]
	v_mfma_f32_16x16x32_bf16 v[80:83], v[220:223], v[196:199], v[80:83]
	v_mfma_f32_16x16x32_bf16 v[68:71], v[212:215], v[204:207], v[68:71]
	v_mfma_f32_16x16x32_bf16 v[64:67], v[220:223], v[204:207], v[64:67]
	s_mov_b32 m0, s38
	s_add_u32 s100, s28, s0
	s_addc_u32 s101, s29, s1
	s_barrier
	ds_read_b128 v[158:161], v163 offset:16384
	ds_read_b128 v[164:167], v163 offset:17408
	ds_read_b128 v[168:171], v163 offset:18432
	ds_read_b128 v[172:175], v163 offset:19456
	ds_read_b128 v[176:179], v163 offset:20480
	ds_read_b128 v[196:199], v163 offset:21504
	ds_read_b128 v[200:203], v163 offset:22528
	ds_read_b128 v[204:207], v163 offset:23552
	global_load_lds_dwordx4 v128, s[28:29]
	s_mov_b32 m0, s39
	s_nop 0
	global_load_lds_dwordx4 v132, s[28:29]
	s_barrier
	s_waitcnt lgkmcnt(0)
	v_mfma_f32_16x16x32_bf16 v[60:63], v[140:143], v[158:161], v[60:63]
	v_mfma_f32_16x16x32_bf16 v[56:59], v[150:153], v[158:161], v[56:59]
	v_mfma_f32_16x16x32_bf16 v[44:47], v[140:143], v[168:171], v[44:47]
	v_mfma_f32_16x16x32_bf16 v[40:43], v[150:153], v[168:171], v[40:43]
	v_mfma_f32_16x16x32_bf16 v[28:31], v[140:143], v[176:179], v[28:31]
	v_mfma_f32_16x16x32_bf16 v[24:27], v[150:153], v[176:179], v[24:27]
	v_mfma_f32_16x16x32_bf16 v[12:15], v[140:143], v[200:203], v[12:15]
	v_mfma_f32_16x16x32_bf16 v[8:11], v[150:153], v[200:203], v[8:11]
	v_mfma_f32_16x16x32_bf16 v[60:63], v[146:149], v[164:167], v[60:63]
	v_mfma_f32_16x16x32_bf16 v[56:59], v[154:157], v[164:167], v[56:59]
	v_mfma_f32_16x16x32_bf16 v[44:47], v[146:149], v[172:175], v[44:47]
	v_mfma_f32_16x16x32_bf16 v[40:43], v[154:157], v[172:175], v[40:43]
	v_mfma_f32_16x16x32_bf16 v[28:31], v[146:149], v[196:199], v[28:31]
	v_mfma_f32_16x16x32_bf16 v[24:27], v[154:157], v[196:199], v[24:27]
	v_mfma_f32_16x16x32_bf16 v[12:15], v[146:149], v[204:207], v[12:15]
	v_mfma_f32_16x16x32_bf16 v[8:11], v[154:157], v[204:207], v[8:11]
	s_barrier
	s_add_u32 s18, s22, 0x18000
	s_addc_u32 s19, s23, 0
	s_add_i32 s55, s56, s35
	s_mov_b32 m0, s55
	s_nop 0
	global_load_lds_dwordx4 v130, s[18:19]
	s_add_i32 m0, s55, 0x2000
	s_nop 0
	global_load_lds_dwordx4 v134, s[18:19]
	s_waitcnt vmcnt(6)
	s_barrier
; #define PG8_STAGE(bufoff, gbase, voff) do { _Pragma("unroll") for (int _i = 0; _i < 2; ++_i) \
;     __builtin_amdgcn_global_load_lds((const unsigned*)((const char*)(gbase) + (voff)[_i]), (LAS unsigned*)(lds + (bufoff) + ldsw + _i * 8192), 16, 0, 0); } while (0)
; #define PG8_LDA(dst, b, h) do { _Pragma("unroll") for (int m = 0; m < 4; ++m) _Pragma("unroll") for (int k = 0; k < 2; ++k) dst[m][k] = *(const LAS bf16x8*)(lds + PG8_SA(b, h) + aoff + m * 2048 + k * 1024); } while (0)
; #define PG8_LDB(dst, b, h) do { _Pragma("unroll") for (int n = 0; n < 2; ++n) _Pragma("unroll") for (int k = 0; k < 2; ++k) dst[n][k] = *(const LAS bf16x8*)(lds + PG8_SB(b, h) + boff + n * 2048 + k * 1024); } while (0)
; #define PG8_MMA(ai, bj, At, Bt) do { __builtin_amdgcn_s_setprio(1); _Pragma("unroll") for (int m = 0; m < 4; ++m) _Pragma("unroll") for (int n = 0; n < 2; ++n) _Pragma("unroll") for (int k = 0; k < 2; ++k) \
;     acc[ai][bj][m][n] = __builtin_amdgcn_mfma_f32_16x16x32_bf16(Bt[n][k], At[m][k], acc[ai][bj][m][n], 0, 0, 0); __builtin_amdgcn_s_setprio(0); } while (0)
; #define PG8_WAIT_V(n) asm volatile("s_waitcnt vmcnt(" #n ")" ::: "memory")
; #define PG8_WAIT_L(n) asm volatile("s_waitcnt lgkmcnt(" #n ")" ::: "memory")
; #define PG8_BAR __builtin_amdgcn_s_barrier()
; #define PG8_SCHED __builtin_amdgcn_sched_barrier(0)
; template <class Epi, class Sched>
; DI void gemm_phase(LAS unsigned char* lds, const Gemm g, const Sched& S, const Epi& E) {
;     ...
;       PG8_WAIT_L(8); PG8_BAR; PG8_WAIT_L(0); PG8_MMA(0, 0, At, B0); PG8_BAR; PG8_SCHED;
;       PG8_LDB(B1, 1, 1); PG8_STAGE(PG8_SB(1, 0), b3, voffB);
;       PG8_BAR; PG8_WAIT_L(0); PG8_MMA(0, 1, At, B1); PG8_BAR;
;       PG8_LDA(At, 1, 1); PG8_STAGE(PG8_SA(1, 0), a3, voffA);
;       PG8_BAR; PG8_WAIT_L(0); PG8_MMA(1, 0, At, B0); PG8_BAR; PG8_SCHED;
;       PG8_STAGE(PG8_SB(1, 1), b3 + hstep, voffB);
;       PG8_WAIT_V(6); PG8_BAR; PG8_MMA(1, 1, At, B1); PG8_BAR;
	v_mfma_f32_16x16x32_bf16 v[52:55], v[208:211], v[158:161], v[52:55]
	v_mfma_f32_16x16x32_bf16 v[48:51], v[216:219], v[158:161], v[48:51]
	v_mfma_f32_16x16x32_bf16 v[36:39], v[208:211], v[168:171], v[36:39]
	v_mfma_f32_16x16x32_bf16 v[32:35], v[216:219], v[168:171], v[32:35]
	v_mfma_f32_16x16x32_bf16 v[20:23], v[208:211], v[176:179], v[20:23]
	v_mfma_f32_16x16x32_bf16 v[16:19], v[216:219], v[176:179], v[16:19]
	v_mfma_f32_16x16x32_bf16 v[4:7], v[208:211], v[200:203], v[4:7]
	v_mfma_f32_16x16x32_bf16 v[0:3], v[216:219], v[200:203], v[0:3]
	v_mfma_f32_16x16x32_bf16 v[52:55], v[212:215], v[164:167], v[52:55]
	v_mfma_f32_16x16x32_bf16 v[48:51], v[220:223], v[164:167], v[48:51]
	v_mfma_f32_16x16x32_bf16 v[36:39], v[212:215], v[172:175], v[36:39]
	v_mfma_f32_16x16x32_bf16 v[32:35], v[220:223], v[172:175], v[32:35]
	v_mfma_f32_16x16x32_bf16 v[20:23], v[212:215], v[196:199], v[20:23]
	v_mfma_f32_16x16x32_bf16 v[16:19], v[220:223], v[196:199], v[16:19]
	v_mfma_f32_16x16x32_bf16 v[4:7], v[212:215], v[204:207], v[4:7]
	v_mfma_f32_16x16x32_bf16 v[0:3], v[220:223], v[204:207], v[0:3]
	s_add_i32 s55, 0, 0x18000
	s_barrier
	ds_read_b128 v[140:143], v226
	ds_read_b128 v[146:149], v226 offset:1024
	ds_read_b128 v[150:153], v226 offset:2048
	ds_read_b128 v[154:157], v226 offset:3072
	s_add_u32 s18, s28, 0x18000
	s_addc_u32 s19, s29, 0
	s_mov_b32 m0, s40
	ds_read_b128 v[158:161], v163 offset:32768
	ds_read_b128 v[164:167], v163 offset:33792
	ds_read_b128 v[168:171], v163 offset:34816
	ds_read_b128 v[172:175], v163 offset:35840
	ds_read_b128 v[176:179], v163 offset:36864
	ds_read_b128 v[196:199], v163 offset:37888
	ds_read_b128 v[200:203], v163 offset:38912
	ds_read_b128 v[204:207], v163 offset:39936
	global_load_lds_dwordx4 v128, s[18:19]
	s_mov_b32 m0, s41
	s_nop 0
	global_load_lds_dwordx4 v132, s[18:19]
	s_waitcnt lgkmcnt(8)
	s_barrier
	s_waitcnt lgkmcnt(0)
	v_mfma_f32_16x16x32_bf16 v[124:127], v[140:143], v[158:161], v[124:127]
	v_mfma_f32_16x16x32_bf16 v[120:123], v[150:153], v[158:161], v[120:123]
	v_mfma_f32_16x16x32_bf16 v[108:111], v[140:143], v[168:171], v[108:111]
	v_mfma_f32_16x16x32_bf16 v[104:107], v[150:153], v[168:171], v[104:107]
	v_mfma_f32_16x16x32_bf16 v[92:95], v[140:143], v[176:179], v[92:95]
	v_mfma_f32_16x16x32_bf16 v[88:91], v[150:153], v[176:179], v[88:91]
	v_mfma_f32_16x16x32_bf16 v[76:79], v[140:143], v[200:203], v[76:79]
	v_mfma_f32_16x16x32_bf16 v[72:75], v[150:153], v[200:203], v[72:75]
	v_mfma_f32_16x16x32_bf16 v[124:127], v[146:149], v[164:167], v[124:127]
	v_mfma_f32_16x16x32_bf16 v[120:123], v[154:157], v[164:167], v[120:123]
	v_mfma_f32_16x16x32_bf16 v[108:111], v[146:149], v[172:175], v[108:111]
	v_mfma_f32_16x16x32_bf16 v[104:107], v[154:157], v[172:175], v[104:107]
	v_mfma_f32_16x16x32_bf16 v[92:95], v[146:149], v[196:199], v[92:95]
	v_mfma_f32_16x16x32_bf16 v[88:91], v[154:157], v[196:199], v[88:91]
	v_mfma_f32_16x16x32_bf16 v[76:79], v[146:149], v[204:207], v[76:79]
	v_mfma_f32_16x16x32_bf16 v[72:75], v[154:157], v[204:207], v[72:75]
	s_barrier
	s_add_i32 s28, 0, 0x1c000
	s_add_i32 s18, s55, s35
	s_mov_b32 m0, s18
	ds_read_b128 v[208:211], v227
	ds_read_b128 v[212:215], v227 offset:1024
	ds_read_b128 v[216:219], v227 offset:2048
	ds_read_b128 v[220:223], v227 offset:3072
	global_load_lds_dwordx4 v130, vcc
	s_add_i32 m0, s18, 0x2000
	s_nop 0
	global_load_lds_dwordx4 v134, vcc
	s_barrier
	s_waitcnt lgkmcnt(0)
	v_mfma_f32_16x16x32_bf16 v[116:119], v[208:211], v[158:161], v[116:119]
	v_mfma_f32_16x16x32_bf16 v[112:115], v[216:219], v[158:161], v[112:115]
	v_mfma_f32_16x16x32_bf16 v[100:103], v[208:211], v[168:171], v[100:103]
	v_mfma_f32_16x16x32_bf16 v[96:99], v[216:219], v[168:171], v[96:99]
	v_mfma_f32_16x16x32_bf16 v[84:87], v[208:211], v[176:179], v[84:87]
	v_mfma_f32_16x16x32_bf16 v[80:83], v[216:219], v[176:179], v[80:83]
	v_mfma_f32_16x16x32_bf16 v[68:71], v[208:211], v[200:203], v[68:71]
	v_mfma_f32_16x16x32_bf16 v[64:67], v[216:219], v[200:203], v[64:67]
	v_mfma_f32_16x16x32_bf16 v[116:119], v[212:215], v[164:167], v[116:119]
	v_mfma_f32_16x16x32_bf16 v[112:115], v[220:223], v[164:167], v[112:115]
	v_mfma_f32_16x16x32_bf16 v[100:103], v[212:215], v[172:175], v[100:103]
	v_mfma_f32_16x16x32_bf16 v[96:99], v[220:223], v[172:175], v[96:99]
	v_mfma_f32_16x16x32_bf16 v[84:87], v[212:215], v[196:199], v[84:87]
	v_mfma_f32_16x16x32_bf16 v[80:83], v[220:223], v[196:199], v[80:83]
	v_mfma_f32_16x16x32_bf16 v[68:71], v[212:215], v[204:207], v[68:71]
	v_mfma_f32_16x16x32_bf16 v[64:67], v[220:223], v[204:207], v[64:67]
	s_mov_b32 m0, s44
	s_barrier
	ds_read_b128 v[158:161], v163 offset:49152
	ds_read_b128 v[164:167], v163 offset:50176
	ds_read_b128 v[168:171], v163 offset:51200
	ds_read_b128 v[172:175], v163 offset:52224
	ds_read_b128 v[176:179], v163 offset:53248
	ds_read_b128 v[196:199], v163 offset:54272
	ds_read_b128 v[200:203], v163 offset:55296
	ds_read_b128 v[204:207], v163 offset:56320
	global_load_lds_dwordx4 v128, s[100:101]
	s_mov_b32 m0, s45
	s_nop 0
	global_load_lds_dwordx4 v132, s[100:101]
	s_barrier
	s_waitcnt lgkmcnt(0)
	v_mfma_f32_16x16x32_bf16 v[60:63], v[140:143], v[158:161], v[60:63]
	v_mfma_f32_16x16x32_bf16 v[56:59], v[150:153], v[158:161], v[56:59]
	v_mfma_f32_16x16x32_bf16 v[44:47], v[140:143], v[168:171], v[44:47]
	v_mfma_f32_16x16x32_bf16 v[40:43], v[150:153], v[168:171], v[40:43]
	v_mfma_f32_16x16x32_bf16 v[28:31], v[140:143], v[176:179], v[28:31]
	v_mfma_f32_16x16x32_bf16 v[24:27], v[150:153], v[176:179], v[24:27]
	v_mfma_f32_16x16x32_bf16 v[12:15], v[140:143], v[200:203], v[12:15]
	v_mfma_f32_16x16x32_bf16 v[8:11], v[150:153], v[200:203], v[8:11]
	v_mfma_f32_16x16x32_bf16 v[60:63], v[146:149], v[164:167], v[60:63]
	v_mfma_f32_16x16x32_bf16 v[56:59], v[154:157], v[164:167], v[56:59]
	v_mfma_f32_16x16x32_bf16 v[44:47], v[146:149], v[172:175], v[44:47]
	v_mfma_f32_16x16x32_bf16 v[40:43], v[154:157], v[172:175], v[40:43]
	v_mfma_f32_16x16x32_bf16 v[28:31], v[146:149], v[196:199], v[28:31]
	v_mfma_f32_16x16x32_bf16 v[24:27], v[154:157], v[196:199], v[24:27]
	v_mfma_f32_16x16x32_bf16 v[12:15], v[146:149], v[204:207], v[12:15]
	v_mfma_f32_16x16x32_bf16 v[8:11], v[154:157], v[204:207], v[8:11]
	s_barrier
; DI void rope_perm(f32x4& a0, f32x4& a1, int fq, int lane, const float* tcos, const float* tsin, int pos) {
;   f32x4 p0, p1;
; #pragma unroll
;   for (int e = 0; e < 4; ++e) { p0[e] = shx(a0[e], 32, lane); p1[e] = shx(a1[e], 32, lane); }
;   const int jb = 8 * (fq & 1);
;   const f32x4 c0 = *(const f32x4*)(tcos + pos * 16 + jb), c1 = *(const f32x4*)(tcos + pos * 16 + jb + 4);
;   const f32x4 s0 = *(const f32x4*)(tsin + pos * 16 + jb), s1 = *(const f32x4*)(tsin + pos * 16 + jb + 4);
;   if (fq < 2) { a0 = a0 * c0 - p0 * s0; a1 = a1 * c1 - p1 * s1; }
;   else        { a0 = a0 * c0 + p0 * s0; a1 = a1 * c1 + p1 * s1; }
; }
;   DI void operator()(const f32x4 (&acc)[2][2][4][2], const pg8::Unit& u, int wr, int wc, int fr_, int fq_) const {
;     ...
;             } else if (EPI == EPI_UQ) {
;               if (n == 0) {
;                 const float sc = rinv * (0.10206207261596575f * LOG2E);
;                 const int gb = u.pn * 256 + bj * 128 + wc * 32;
;                 const int hd = gb / 96; const int within = gb - hd * 96;
;                 f32x4 a0 = v, a1 = acc[ai][bj][m][1];
;                 if (within == 64) rope_perm(a0, a1, fq, t_ & 63, tcos, tsin, token & (S_ - 1));
;                 st_bf8((u16*)(big + E_QMLA) + (size_t)token * 768 + gb + 8 * fq, a0, a1, sc);
;               }
	s_add_u32 s18, s22, 0x18080
	s_addc_u32 s19, s23, 0
	s_add_i32 s22, s28, s35
	s_mov_b32 m0, s22
	s_nop 0
	global_load_lds_dwordx4 v130, s[18:19]
	s_add_i32 m0, s22, 0x2000
	s_nop 0
	global_load_lds_dwordx4 v134, s[18:19]
	s_waitcnt vmcnt(6)
	s_barrier
	v_mfma_f32_16x16x32_bf16 v[52:55], v[208:211], v[158:161], v[52:55]
	v_mfma_f32_16x16x32_bf16 v[48:51], v[216:219], v[158:161], v[48:51]
	v_mfma_f32_16x16x32_bf16 v[36:39], v[208:211], v[168:171], v[36:39]
	v_mfma_f32_16x16x32_bf16 v[32:35], v[216:219], v[168:171], v[32:35]
	v_mfma_f32_16x16x32_bf16 v[20:23], v[208:211], v[176:179], v[20:23]
	v_mfma_f32_16x16x32_bf16 v[16:19], v[216:219], v[176:179], v[16:19]
	v_mfma_f32_16x16x32_bf16 v[4:7], v[208:211], v[200:203], v[4:7]
	v_mfma_f32_16x16x32_bf16 v[0:3], v[216:219], v[200:203], v[0:3]
	v_mfma_f32_16x16x32_bf16 v[52:55], v[212:215], v[164:167], v[52:55]
	v_mfma_f32_16x16x32_bf16 v[48:51], v[220:223], v[164:167], v[48:51]
	v_mfma_f32_16x16x32_bf16 v[36:39], v[212:215], v[172:175], v[36:39]
	v_mfma_f32_16x16x32_bf16 v[32:35], v[220:223], v[172:175], v[32:35]
	v_mfma_f32_16x16x32_bf16 v[20:23], v[212:215], v[196:199], v[20:23]
	v_mfma_f32_16x16x32_bf16 v[16:19], v[220:223], v[196:199], v[16:19]
	v_mfma_f32_16x16x32_bf16 v[4:7], v[212:215], v[204:207], v[4:7]
	v_mfma_f32_16x16x32_bf16 v[0:3], v[220:223], v[204:207], v[0:3]
	s_add_i32 s54, s54, 2
	s_add_u32 s52, s52, 0x100
	s_addc_u32 s53, s53, 0
	s_cmp_gt_u32 s54, 3
	s_mov_b64 s[18:19], s[20:21]
	s_barrier
	s_cbranch_scc0 .LBB0_1202
	v_mov_b32_e32 v140, v182
	s_lshl_b32 s19, s51, 10
	s_lshl_b32 s18, s49, 8
	s_or_b32 s18, s18, s43
	v_and_or_b32 v167, v140, 15, s42
	v_lshlrev_b32_e32 v141, 2, v140
	s_movk_i32 s20, 0x80
	s_add_i32 s19, s19, 0
	v_bitop3_b32 v164, v141, s20, v190 bitop3:0x6c
	v_lshl_add_u32 v141, v167, 2, s19
	s_mul_hi_i32 s19, s18, 0x2aaaaaab
	v_add_u32_e32 v166, 0x20000, v141
	s_lshr_b32 s20, s19, 31
	s_lshr_b32 s19, s19, 4
	s_lshl_b32 s50, s50, 8
	ds_read_b32 v144, v166
	s_add_i32 s19, s19, s20
	v_add_u32_e32 v165, s50, v167
	s_mulk_i32 s19, 0x60
	v_bfe_u32 v168, v140, 4, 2
	v_lshrrev_b32_e32 v140, 1, v140
	v_lshlrev_b32_e32 v141, 4, v165
	s_sub_i32 s19, s18, s19
	v_and_b32_e32 v140, 8, v140
	v_and_b32_e32 v141, 0xfcf0, v141
	s_cmp_eq_u32 s19, 64
	v_cmp_lt_u32_e64 s[78:79], 1, v168
	s_cselect_b64 s[20:21], -1, 0
	s_cmp_lg_u32 s19, 64
	v_lshlrev_b32_e32 v142, 2, v141
	v_lshlrev_b32_e32 v140, 2, v140
	s_cbranch_scc1 .LBB0_1209
	v_mov_b32_e32 v143, v145
	v_lshl_add_u64 v[146:147], s[12:13], 0, v[142:143]
	v_mov_b32_e32 v141, v145
	v_lshl_add_u64 v[152:153], s[14:15], 0, v[142:143]
	v_lshl_add_u64 v[146:147], v[146:147], 0, v[140:141]
	v_lshl_add_u64 v[152:153], v[152:153], 0, v[140:141]
	global_load_dwordx4 v[148:151], v[146:147], off
	global_load_dwordx4 v[154:157], v[152:153], off
	global_load_dwordx4 v[170:173], v[152:153], off offset:16
	global_load_dwordx4 v[174:177], v[146:147], off offset:16
	ds_bpermute_b32 v152, v164, v124
	ds_bpermute_b32 v160, v164, v120
	ds_bpermute_b32 v153, v164, v125
	ds_bpermute_b32 v161, v164, v121
	ds_bpermute_b32 v158, v164, v126
	ds_bpermute_b32 v178, v164, v122
	ds_bpermute_b32 v159, v164, v127
	ds_bpermute_b32 v179, v164, v123
	s_waitcnt vmcnt(0) lgkmcnt(0)
	v_mul_f32_e32 v154, v154, v152
	v_mul_f32_e32 v155, v155, v153
	v_mul_f32_e32 v146, v126, v150
	v_mul_f32_e32 v147, v127, v151
	v_mul_f32_e32 v150, v124, v148
	v_mul_f32_e32 v151, v125, v149
	v_mul_f32_e32 v158, v156, v158
	v_mul_f32_e32 v159, v157, v159
	v_mul_f32_e32 v148, v170, v160
	v_mul_f32_e32 v149, v171, v161
	v_mul_f32_e32 v152, v172, v178
	v_mul_f32_e32 v153, v173, v179
	v_mul_f32_e32 v156, v122, v176
	v_mul_f32_e32 v157, v123, v177
	v_mul_f32_e32 v160, v120, v174
	v_mul_f32_e32 v161, v121, v175
	s_and_saveexec_b64 s[22:23], s[78:79]
	s_xor_b64 s[22:23], exec, s[22:23]
	v_add_f32_e32 v126, v146, v158
	v_add_f32_e32 v127, v147, v159
	v_add_f32_e32 v124, v150, v154
	v_add_f32_e32 v125, v151, v155
	v_add_f32_e32 v122, v156, v152
	v_add_f32_e32 v123, v157, v153
	v_add_f32_e32 v120, v160, v148
	v_add_f32_e32 v121, v161, v149
	s_andn2_saveexec_b64 s[22:23], s[22:23]
	v_sub_f32_e32 v127, v147, v159
	v_sub_f32_e32 v126, v146, v158
	v_sub_f32_e32 v125, v151, v155
	v_sub_f32_e32 v124, v150, v154
	v_sub_f32_e32 v123, v157, v153
	v_sub_f32_e32 v122, v156, v152
	v_sub_f32_e32 v121, v161, v149
	v_sub_f32_e32 v120, v160, v148
	s_or_b64 exec, exec, s[22:23]
; DI void rope_perm(f32x4& a0, f32x4& a1, int fq, int lane, const float* tcos, const float* tsin, int pos) {
;   f32x4 p0, p1;
; #pragma unroll
;   for (int e = 0; e < 4; ++e) { p0[e] = shx(a0[e], 32, lane); p1[e] = shx(a1[e], 32, lane); }
;   const int jb = 8 * (fq & 1);
;   const f32x4 c0 = *(const f32x4*)(tcos + pos * 16 + jb), c1 = *(const f32x4*)(tcos + pos * 16 + jb + 4);
;   const f32x4 s0 = *(const f32x4*)(tsin + pos * 16 + jb), s1 = *(const f32x4*)(tsin + pos * 16 + jb + 4);
;   if (fq < 2) { a0 = a0 * c0 - p0 * s0; a1 = a1 * c1 - p1 * s1; }
;   else        { a0 = a0 * c0 + p0 * s0; a1 = a1 * c1 + p1 * s1; }
; }
;   DI void operator()(const f32x4 (&acc)[2][2][4][2], const pg8::Unit& u, int wr, int wc, int fr_, int fq_) const {
;     ...
;             } else if (EPI == EPI_UQ) {
;               if (n == 0) {
;                 const float sc = rinv * (0.10206207261596575f * LOG2E);
;                 const int gb = u.pn * 256 + bj * 128 + wc * 32;
;                 const int hd = gb / 96; const int within = gb - hd * 96;
;                 f32x4 a0 = v, a1 = acc[ai][bj][m][1];
;                 if (within == 64) rope_perm(a0, a1, fq, t_ & 63, tcos, tsin, token & (S_ - 1));
;                 st_bf8((u16*)(big + E_QMLA) + (size_t)token * 768 + gb + 8 * fq, a0, a1, sc);
;               }
.LBB0_1209:
	v_mov_b64_e32 v[148:149], s[16:17]
	s_movk_i32 s22, 0x600
	v_mad_i64_i32 v[148:149], s[22:23], v165, s22, v[148:149]
	s_or_b32 s22, s18, 0x80
	s_mul_hi_i32 s23, s22, 0x2aaaaaab
	s_lshr_b32 s28, s23, 31
	s_lshr_b32 s23, s23, 4
	s_add_i32 s23, s23, s28
	s_waitcnt lgkmcnt(0)
	v_mul_f32_e32 v146, 0x3e16c740, v144
	s_mulk_i32 s23, 0x60
	s_ashr_i32 s19, s18, 31
	v_mul_f32_e32 v124, v146, v124
	v_mul_f32_e32 v125, v146, v125
	v_mul_f32_e32 v126, v146, v126
	v_mul_f32_e32 v127, v146, v127
	v_mul_f32_e32 v120, v146, v120
	v_mul_f32_e32 v121, v146, v121
	s_sub_i32 s28, s22, s23
	v_lshl_add_u64 v[148:149], s[18:19], 1, v[148:149]
	v_lshlrev_b32_e32 v144, 4, v168
	v_cvt_pk_bf16_f32 v124, v124, v125
	v_cvt_pk_bf16_f32 v125, v126, v127
	v_cvt_pk_bf16_f32 v126, v120, v121
	v_mul_f32_e32 v120, v146, v122
	v_mul_f32_e32 v121, v146, v123
	s_cmp_eq_u32 s28, 64
	v_lshl_add_u64 v[148:149], v[148:149], 0, v[144:145]
	v_cvt_pk_bf16_f32 v127, v120, v121
	s_cselect_b64 s[22:23], -1, 0
	s_cmp_lg_u32 s28, 64
	global_store_dwordx4 v[148:149], v[124:127], off
	s_cbranch_scc1 .LBB0_1215
	v_mov_b32_e32 v143, v145
	v_lshl_add_u64 v[120:121], s[12:13], 0, v[142:143]
	v_mov_b32_e32 v141, v145
	v_lshl_add_u64 v[126:127], s[14:15], 0, v[142:143]
	v_lshl_add_u64 v[120:121], v[120:121], 0, v[140:141]
	v_lshl_add_u64 v[126:127], v[126:127], 0, v[140:141]
	global_load_dwordx4 v[122:125], v[120:121], off
	global_load_dwordx4 v[150:153], v[126:127], off
	global_load_dwordx4 v[154:157], v[126:127], off offset:16
	global_load_dwordx4 v[158:161], v[120:121], off offset:16
	ds_bpermute_b32 v126, v164, v116
	ds_bpermute_b32 v170, v164, v112
	ds_bpermute_b32 v127, v164, v117
	ds_bpermute_b32 v171, v164, v113
	ds_bpermute_b32 v172, v164, v118
	ds_bpermute_b32 v174, v164, v114
	ds_bpermute_b32 v173, v164, v119
	ds_bpermute_b32 v175, v164, v115
	s_waitcnt vmcnt(0) lgkmcnt(0)
	v_mul_f32_e32 v142, v150, v126
	v_mul_f32_e32 v143, v151, v127
	v_mul_f32_e32 v120, v118, v124
	v_mul_f32_e32 v121, v119, v125
	v_mul_f32_e32 v124, v116, v122
	v_mul_f32_e32 v125, v117, v123
	v_mul_f32_e32 v152, v152, v172
	v_mul_f32_e32 v153, v153, v173
	v_mul_f32_e32 v122, v154, v170
	v_mul_f32_e32 v123, v155, v171
	v_mul_f32_e32 v126, v156, v174
	v_mul_f32_e32 v127, v157, v175
	v_mul_f32_e32 v150, v114, v160
	v_mul_f32_e32 v151, v115, v161
	v_mul_f32_e32 v154, v112, v158
	v_mul_f32_e32 v155, v113, v159
	s_and_saveexec_b64 s[28:29], s[78:79]
	s_xor_b64 s[28:29], exec, s[28:29]
	v_add_f32_e32 v118, v120, v152
	v_add_f32_e32 v119, v121, v153
	v_add_f32_e32 v116, v124, v142
	v_add_f32_e32 v117, v125, v143
	v_add_f32_e32 v114, v150, v126
	v_add_f32_e32 v115, v151, v127
	v_add_f32_e32 v112, v154, v122
	v_add_f32_e32 v113, v155, v123
	s_andn2_saveexec_b64 s[28:29], s[28:29]
	v_sub_f32_e32 v119, v121, v153
	v_sub_f32_e32 v118, v120, v152
	v_sub_f32_e32 v117, v125, v143
	v_sub_f32_e32 v116, v124, v142
	v_sub_f32_e32 v115, v151, v127
	v_sub_f32_e32 v114, v150, v126
	v_sub_f32_e32 v113, v155, v123
	v_sub_f32_e32 v112, v154, v122
	s_or_b64 exec, exec, s[28:29]
.LBB0_1215:
	v_mov_b32_e32 v147, v146
	v_mul_f32_e32 v116, v146, v116
	v_mul_f32_e32 v117, v147, v117
	v_mul_f32_e32 v118, v146, v118
	v_mul_f32_e32 v119, v147, v119
	v_mul_f32_e32 v112, v146, v112
	v_mul_f32_e32 v113, v147, v113
	v_cvt_pk_bf16_f32 v116, v116, v117
	v_cvt_pk_bf16_f32 v117, v118, v119
	v_cvt_pk_bf16_f32 v118, v112, v113
	v_mul_f32_e32 v112, v146, v114
	v_mul_f32_e32 v113, v147, v115
	ds_read_b32 v146, v166 offset:64
	v_add3_u32 v144, s50, v167, 16
	v_cvt_pk_bf16_f32 v119, v112, v113
	v_lshlrev_b32_e32 v112, 4, v144
	v_and_b32_e32 v112, 0xfdf0, v112
	v_cndmask_b32_e64 v113, 0, 1, s[20:21]
	v_cmp_ne_u32_e64 s[70:71], 1, v113
	s_andn2_b64 vcc, exec, s[20:21]
	v_lshlrev_b32_e32 v112, 2, v112
	global_store_dwordx4 v[148:149], v[116:119], off offset:256
	s_cbranch_vccnz .LBB0_1221
	v_mov_b32_e32 v113, v145
	v_lshl_add_u64 v[114:115], s[12:13], 0, v[112:113]
	v_mov_b32_e32 v141, v145
	v_lshl_add_u64 v[120:121], s[14:15], 0, v[112:113]
	v_lshl_add_u64 v[114:115], v[114:115], 0, v[140:141]
	v_lshl_add_u64 v[120:121], v[120:121], 0, v[140:141]
	global_load_dwordx4 v[116:119], v[114:115], off
	global_load_dwordx4 v[122:125], v[120:121], off
	global_load_dwordx4 v[148:151], v[120:121], off offset:16
	global_load_dwordx4 v[152:155], v[114:115], off offset:16
	ds_bpermute_b32 v120, v164, v108
	ds_bpermute_b32 v142, v164, v104
	ds_bpermute_b32 v121, v164, v109
	ds_bpermute_b32 v143, v164, v105
	ds_bpermute_b32 v126, v164, v110
	ds_bpermute_b32 v156, v164, v106
	ds_bpermute_b32 v127, v164, v111
	ds_bpermute_b32 v157, v164, v107
	s_waitcnt vmcnt(0) lgkmcnt(0)
	v_mul_f32_e32 v122, v122, v120
	v_mul_f32_e32 v123, v123, v121
	v_mul_f32_e32 v114, v110, v118
	v_mul_f32_e32 v115, v111, v119
	v_mul_f32_e32 v118, v108, v116
	v_mul_f32_e32 v119, v109, v117
	v_mul_f32_e32 v126, v124, v126
	v_mul_f32_e32 v127, v125, v127
	v_mul_f32_e32 v116, v148, v142
	v_mul_f32_e32 v117, v149, v143
	v_mul_f32_e32 v120, v150, v156
	v_mul_f32_e32 v121, v151, v157
	v_mul_f32_e32 v124, v106, v154
	v_mul_f32_e32 v125, v107, v155
	v_mul_f32_e32 v142, v104, v152
	v_mul_f32_e32 v143, v105, v153
	s_and_saveexec_b64 s[20:21], s[78:79]
	s_xor_b64 s[20:21], exec, s[20:21]
	v_add_f32_e32 v110, v114, v126
	v_add_f32_e32 v111, v115, v127
	v_add_f32_e32 v108, v118, v122
	v_add_f32_e32 v109, v119, v123
	v_add_f32_e32 v106, v124, v120
	v_add_f32_e32 v107, v125, v121
	v_add_f32_e32 v104, v142, v116
	v_add_f32_e32 v105, v143, v117
	s_andn2_saveexec_b64 s[20:21], s[20:21]
	v_sub_f32_e32 v111, v115, v127
	v_sub_f32_e32 v110, v114, v126
	v_sub_f32_e32 v109, v119, v123
	v_sub_f32_e32 v108, v118, v122
	v_sub_f32_e32 v107, v125, v121
	v_sub_f32_e32 v106, v124, v120
	v_sub_f32_e32 v105, v143, v117
	v_sub_f32_e32 v104, v142, v116
	s_or_b64 exec, exec, s[20:21]
; DI void rope_perm(f32x4& a0, f32x4& a1, int fq, int lane, const float* tcos, const float* tsin, int pos) {
;   f32x4 p0, p1;
; #pragma unroll
;   for (int e = 0; e < 4; ++e) { p0[e] = shx(a0[e], 32, lane); p1[e] = shx(a1[e], 32, lane); }
;   const int jb = 8 * (fq & 1);
;   const f32x4 c0 = *(const f32x4*)(tcos + pos * 16 + jb), c1 = *(const f32x4*)(tcos + pos * 16 + jb + 4);
;   const f32x4 s0 = *(const f32x4*)(tsin + pos * 16 + jb), s1 = *(const f32x4*)(tsin + pos * 16 + jb + 4);
;   if (fq < 2) { a0 = a0 * c0 - p0 * s0; a1 = a1 * c1 - p1 * s1; }
;   else        { a0 = a0 * c0 + p0 * s0; a1 = a1 * c1 + p1 * s1; }
; }
;   DI void operator()(const f32x4 (&acc)[2][2][4][2], const pg8::Unit& u, int wr, int wc, int fr_, int fq_) const {
;     ...
;             } else if (EPI == EPI_UQ) {
;               if (n == 0) {
;                 const float sc = rinv * (0.10206207261596575f * LOG2E);
;                 const int gb = u.pn * 256 + bj * 128 + wc * 32;
;                 const int hd = gb / 96; const int within = gb - hd * 96;
;                 f32x4 a0 = v, a1 = acc[ai][bj][m][1];
;                 if (within == 64) rope_perm(a0, a1, fq, t_ & 63, tcos, tsin, token & (S_ - 1));
;                 st_bf8((u16*)(big + E_QMLA) + (size_t)token * 768 + gb + 8 * fq, a0, a1, sc);
;               }
.LBB0_1221:
	s_waitcnt lgkmcnt(0)
	v_mul_f32_e32 v114, 0x3e16c740, v146
	v_mov_b64_e32 v[116:117], s[16:17]
	s_movk_i32 s20, 0x600
	v_mul_f32_e32 v108, v114, v108
	v_mul_f32_e32 v109, v114, v109
	v_mul_f32_e32 v110, v114, v110
	v_mul_f32_e32 v111, v114, v111
	v_mul_f32_e32 v104, v114, v104
	v_mul_f32_e32 v105, v114, v105
	v_lshlrev_b32_e32 v113, 3, v168
	v_mad_i64_i32 v[116:117], s[20:21], v144, s20, v[116:117]
	v_cvt_pk_bf16_f32 v108, v108, v109
	v_cvt_pk_bf16_f32 v109, v110, v111
	v_cvt_pk_bf16_f32 v110, v104, v105
	v_mul_f32_e32 v104, v114, v106
	v_mul_f32_e32 v105, v114, v107
	v_lshl_add_u64 v[116:117], s[18:19], 1, v[116:117]
	v_lshlrev_b32_e32 v144, 1, v113
	v_cvt_pk_bf16_f32 v111, v104, v105
	v_cndmask_b32_e64 v104, 0, 1, s[22:23]
	v_lshl_add_u64 v[116:117], v[116:117], 0, v[144:145]
	v_cmp_ne_u32_e64 s[72:73], 1, v104
	s_andn2_b64 vcc, exec, s[22:23]
	global_store_dwordx4 v[116:117], v[108:111], off
	s_cbranch_vccnz .LBB0_1227
	v_mov_b32_e32 v113, v145
	v_lshl_add_u64 v[104:105], s[12:13], 0, v[112:113]
	v_mov_b32_e32 v141, v145
	v_lshl_add_u64 v[110:111], s[14:15], 0, v[112:113]
	v_lshl_add_u64 v[104:105], v[104:105], 0, v[140:141]
	v_lshl_add_u64 v[110:111], v[110:111], 0, v[140:141]
	global_load_dwordx4 v[106:109], v[104:105], off
	global_load_dwordx4 v[118:121], v[110:111], off
	global_load_dwordx4 v[122:125], v[110:111], off offset:16
	global_load_dwordx4 v[146:149], v[104:105], off offset:16
	ds_bpermute_b32 v110, v164, v100
	ds_bpermute_b32 v126, v164, v96
	ds_bpermute_b32 v111, v164, v101
	ds_bpermute_b32 v127, v164, v97
	ds_bpermute_b32 v142, v164, v102
	ds_bpermute_b32 v150, v164, v98
	ds_bpermute_b32 v143, v164, v103
	ds_bpermute_b32 v151, v164, v99
	s_waitcnt vmcnt(0) lgkmcnt(0)
	v_mul_f32_e32 v112, v118, v110
	v_mul_f32_e32 v113, v119, v111
	v_mul_f32_e32 v104, v102, v108
	v_mul_f32_e32 v105, v103, v109
	v_mul_f32_e32 v108, v100, v106
	v_mul_f32_e32 v109, v101, v107
	v_mul_f32_e32 v120, v120, v142
	v_mul_f32_e32 v121, v121, v143
	v_mul_f32_e32 v106, v122, v126
	v_mul_f32_e32 v107, v123, v127
	v_mul_f32_e32 v110, v124, v150
	v_mul_f32_e32 v111, v125, v151
	v_mul_f32_e32 v118, v98, v148
	v_mul_f32_e32 v119, v99, v149
	v_mul_f32_e32 v122, v96, v146
	v_mul_f32_e32 v123, v97, v147
	s_and_saveexec_b64 s[20:21], s[78:79]
	s_xor_b64 s[20:21], exec, s[20:21]
	v_add_f32_e32 v102, v104, v120
	v_add_f32_e32 v103, v105, v121
	v_add_f32_e32 v100, v108, v112
	v_add_f32_e32 v101, v109, v113
	v_add_f32_e32 v98, v118, v110
	v_add_f32_e32 v99, v119, v111
	v_add_f32_e32 v96, v122, v106
	v_add_f32_e32 v97, v123, v107
	s_andn2_saveexec_b64 s[20:21], s[20:21]
	v_sub_f32_e32 v103, v105, v121
	v_sub_f32_e32 v102, v104, v120
	v_sub_f32_e32 v101, v109, v113
	v_sub_f32_e32 v100, v108, v112
	v_sub_f32_e32 v99, v119, v111
	v_sub_f32_e32 v98, v118, v110
	v_sub_f32_e32 v97, v123, v107
	v_sub_f32_e32 v96, v122, v106
	s_or_b64 exec, exec, s[20:21]
.LBB0_1227:
	v_mov_b32_e32 v115, v114
	v_mul_f32_e32 v100, v114, v100
	v_mul_f32_e32 v101, v115, v101
	v_mul_f32_e32 v102, v114, v102
	v_mul_f32_e32 v103, v115, v103
	v_mul_f32_e32 v96, v114, v96
	v_mul_f32_e32 v97, v115, v97
	v_cvt_pk_bf16_f32 v100, v100, v101
	v_cvt_pk_bf16_f32 v101, v102, v103
	v_cvt_pk_bf16_f32 v102, v96, v97
	v_mul_f32_e32 v96, v114, v98
	v_mul_f32_e32 v97, v115, v99
	ds_read_b32 v115, v166 offset:128
	v_add3_u32 v114, s50, v167, 32
	v_cvt_pk_bf16_f32 v103, v96, v97
	v_lshlrev_b32_e32 v96, 4, v114
	v_and_b32_e32 v96, 0xfef0, v96
	s_and_b64 vcc, exec, s[70:71]
	v_lshlrev_b32_e32 v96, 2, v96
	global_store_dwordx4 v[116:117], v[100:103], off offset:256
	s_cbranch_vccnz .LBB0_1233
	v_mov_b32_e32 v97, v145
	v_lshl_add_u64 v[98:99], s[12:13], 0, v[96:97]
	v_mov_b32_e32 v141, v145
	v_lshl_add_u64 v[104:105], s[14:15], 0, v[96:97]
	v_lshl_add_u64 v[98:99], v[98:99], 0, v[140:141]
	v_lshl_add_u64 v[104:105], v[104:105], 0, v[140:141]
	global_load_dwordx4 v[100:103], v[98:99], off
	global_load_dwordx4 v[106:109], v[104:105], off
	global_load_dwordx4 v[116:119], v[104:105], off offset:16
	global_load_dwordx4 v[120:123], v[98:99], off offset:16
	ds_bpermute_b32 v104, v164, v92
	ds_bpermute_b32 v112, v164, v88
	ds_bpermute_b32 v105, v164, v93
	ds_bpermute_b32 v113, v164, v89
	ds_bpermute_b32 v110, v164, v94
	ds_bpermute_b32 v124, v164, v90
	ds_bpermute_b32 v111, v164, v95
	ds_bpermute_b32 v125, v164, v91
	s_waitcnt vmcnt(0) lgkmcnt(0)
	v_mul_f32_e32 v106, v106, v104
	v_mul_f32_e32 v107, v107, v105
	v_mul_f32_e32 v98, v94, v102
	v_mul_f32_e32 v99, v95, v103
	v_mul_f32_e32 v102, v92, v100
	v_mul_f32_e32 v103, v93, v101
	v_mul_f32_e32 v110, v108, v110
	v_mul_f32_e32 v111, v109, v111
	v_mul_f32_e32 v100, v116, v112
	v_mul_f32_e32 v101, v117, v113
	v_mul_f32_e32 v104, v118, v124
	v_mul_f32_e32 v105, v119, v125
	v_mul_f32_e32 v108, v90, v122
	v_mul_f32_e32 v109, v91, v123
	v_mul_f32_e32 v112, v88, v120
	v_mul_f32_e32 v113, v89, v121
	s_and_saveexec_b64 s[20:21], s[78:79]
	s_xor_b64 s[20:21], exec, s[20:21]
	v_add_f32_e32 v94, v98, v110
	v_add_f32_e32 v95, v99, v111
	v_add_f32_e32 v92, v102, v106
	v_add_f32_e32 v93, v103, v107
	v_add_f32_e32 v90, v108, v104
	v_add_f32_e32 v91, v109, v105
	v_add_f32_e32 v88, v112, v100
	v_add_f32_e32 v89, v113, v101
	s_andn2_saveexec_b64 s[20:21], s[20:21]
	v_sub_f32_e32 v95, v99, v111
	v_sub_f32_e32 v94, v98, v110
	v_sub_f32_e32 v93, v103, v107
	v_sub_f32_e32 v92, v102, v106
	v_sub_f32_e32 v91, v109, v105
	v_sub_f32_e32 v90, v108, v104
	v_sub_f32_e32 v89, v113, v101
	v_sub_f32_e32 v88, v112, v100
	s_or_b64 exec, exec, s[20:21]
; DI void rope_perm(f32x4& a0, f32x4& a1, int fq, int lane, const float* tcos, const float* tsin, int pos) {
;   f32x4 p0, p1;
; #pragma unroll
;   for (int e = 0; e < 4; ++e) { p0[e] = shx(a0[e], 32, lane); p1[e] = shx(a1[e], 32, lane); }
;   const int jb = 8 * (fq & 1);
;   const f32x4 c0 = *(const f32x4*)(tcos + pos * 16 + jb), c1 = *(const f32x4*)(tcos + pos * 16 + jb + 4);
;   const f32x4 s0 = *(const f32x4*)(tsin + pos * 16 + jb), s1 = *(const f32x4*)(tsin + pos * 16 + jb + 4);
;   if (fq < 2) { a0 = a0 * c0 - p0 * s0; a1 = a1 * c1 - p1 * s1; }
;   else        { a0 = a0 * c0 + p0 * s0; a1 = a1 * c1 + p1 * s1; }
; }
;   DI void operator()(const f32x4 (&acc)[2][2][4][2], const pg8::Unit& u, int wr, int wc, int fr_, int fq_) const {
;     ...
;             } else if (EPI == EPI_UQ) {
;               if (n == 0) {
;                 const float sc = rinv * (0.10206207261596575f * LOG2E);
;                 const int gb = u.pn * 256 + bj * 128 + wc * 32;
;                 const int hd = gb / 96; const int within = gb - hd * 96;
;                 f32x4 a0 = v, a1 = acc[ai][bj][m][1];
;                 if (within == 64) rope_perm(a0, a1, fq, t_ & 63, tcos, tsin, token & (S_ - 1));
;                 st_bf8((u16*)(big + E_QMLA) + (size_t)token * 768 + gb + 8 * fq, a0, a1, sc);
;               }
.LBB0_1233:
	s_waitcnt lgkmcnt(0)
	v_mul_f32_e32 v98, 0x3e16c740, v115
	v_mov_b64_e32 v[100:101], s[16:17]
	s_movk_i32 s20, 0x600
	v_mad_i64_i32 v[100:101], s[20:21], v114, s20, v[100:101]
	v_mul_f32_e32 v92, v98, v92
	v_mul_f32_e32 v93, v98, v93
	v_mul_f32_e32 v94, v98, v94
	v_mul_f32_e32 v95, v98, v95
	v_mul_f32_e32 v88, v98, v88
	v_mul_f32_e32 v89, v98, v89
	v_lshl_add_u64 v[100:101], s[18:19], 1, v[100:101]
	v_cvt_pk_bf16_f32 v92, v92, v93
	v_cvt_pk_bf16_f32 v93, v94, v95
	v_cvt_pk_bf16_f32 v94, v88, v89
	v_mul_f32_e32 v88, v98, v90
	v_mul_f32_e32 v89, v98, v91
	v_lshl_add_u64 v[100:101], v[100:101], 0, v[144:145]
	v_cvt_pk_bf16_f32 v95, v88, v89
	s_and_b64 vcc, exec, s[72:73]
	global_store_dwordx4 v[100:101], v[92:95], off
	s_cbranch_vccnz .LBB0_1239
	v_mov_b32_e32 v97, v145
	v_lshl_add_u64 v[88:89], s[12:13], 0, v[96:97]
	v_mov_b32_e32 v141, v145
	v_lshl_add_u64 v[94:95], s[14:15], 0, v[96:97]
	v_lshl_add_u64 v[88:89], v[88:89], 0, v[140:141]
	v_lshl_add_u64 v[94:95], v[94:95], 0, v[140:141]
	global_load_dwordx4 v[90:93], v[88:89], off
	global_load_dwordx4 v[102:105], v[94:95], off
	global_load_dwordx4 v[106:109], v[94:95], off offset:16
	global_load_dwordx4 v[110:113], v[88:89], off offset:16
	ds_bpermute_b32 v94, v164, v84
	ds_bpermute_b32 v114, v164, v80
	ds_bpermute_b32 v95, v164, v85
	ds_bpermute_b32 v115, v164, v81
	ds_bpermute_b32 v116, v164, v86
	ds_bpermute_b32 v118, v164, v82
	ds_bpermute_b32 v117, v164, v87
	ds_bpermute_b32 v119, v164, v83
	s_waitcnt vmcnt(0) lgkmcnt(0)
	v_mul_f32_e32 v96, v102, v94
	v_mul_f32_e32 v97, v103, v95
	v_mul_f32_e32 v88, v86, v92
	v_mul_f32_e32 v89, v87, v93
	v_mul_f32_e32 v92, v84, v90
	v_mul_f32_e32 v93, v85, v91
	v_mul_f32_e32 v104, v104, v116
	v_mul_f32_e32 v105, v105, v117
	v_mul_f32_e32 v90, v106, v114
	v_mul_f32_e32 v91, v107, v115
	v_mul_f32_e32 v94, v108, v118
	v_mul_f32_e32 v95, v109, v119
	v_mul_f32_e32 v102, v82, v112
	v_mul_f32_e32 v103, v83, v113
	v_mul_f32_e32 v106, v80, v110
	v_mul_f32_e32 v107, v81, v111
	s_and_saveexec_b64 s[20:21], s[78:79]
	s_xor_b64 s[20:21], exec, s[20:21]
	v_add_f32_e32 v86, v88, v104
	v_add_f32_e32 v87, v89, v105
	v_add_f32_e32 v84, v92, v96
	v_add_f32_e32 v85, v93, v97
	v_add_f32_e32 v82, v102, v94
	v_add_f32_e32 v83, v103, v95
	v_add_f32_e32 v80, v106, v90
	v_add_f32_e32 v81, v107, v91
	s_andn2_saveexec_b64 s[20:21], s[20:21]
	v_sub_f32_e32 v87, v89, v105
	v_sub_f32_e32 v86, v88, v104
	v_sub_f32_e32 v85, v93, v97
	v_sub_f32_e32 v84, v92, v96
	v_sub_f32_e32 v83, v103, v95
	v_sub_f32_e32 v82, v102, v94
	v_sub_f32_e32 v81, v107, v91
	v_sub_f32_e32 v80, v106, v90
	s_or_b64 exec, exec, s[20:21]
.LBB0_1239:
	v_mov_b32_e32 v99, v98
	v_mul_f32_e32 v84, v98, v84
	v_mul_f32_e32 v85, v99, v85
	v_mul_f32_e32 v86, v98, v86
	v_mul_f32_e32 v87, v99, v87
	v_mul_f32_e32 v80, v98, v80
	v_mul_f32_e32 v81, v99, v81
	v_cvt_pk_bf16_f32 v84, v84, v85
	v_cvt_pk_bf16_f32 v85, v86, v87
	v_cvt_pk_bf16_f32 v86, v80, v81
	v_mul_f32_e32 v80, v98, v82
	v_mul_f32_e32 v81, v99, v83
	ds_read_b32 v99, v166 offset:192
	v_add3_u32 v98, s50, v167, 48
	v_cvt_pk_bf16_f32 v87, v80, v81
	v_lshlrev_b32_e32 v80, 4, v98
	v_and_b32_e32 v80, 0xfff0, v80
	s_and_b64 vcc, exec, s[70:71]
	v_lshlrev_b32_e32 v80, 2, v80
	global_store_dwordx4 v[100:101], v[84:87], off offset:256
	s_cbranch_vccnz .LBB0_1245
	v_mov_b32_e32 v81, v145
	v_lshl_add_u64 v[82:83], s[12:13], 0, v[80:81]
	v_mov_b32_e32 v141, v145
	v_lshl_add_u64 v[88:89], s[14:15], 0, v[80:81]
	v_lshl_add_u64 v[82:83], v[82:83], 0, v[140:141]
	v_lshl_add_u64 v[88:89], v[88:89], 0, v[140:141]
	global_load_dwordx4 v[84:87], v[82:83], off
	global_load_dwordx4 v[90:93], v[88:89], off
	global_load_dwordx4 v[100:103], v[88:89], off offset:16
	global_load_dwordx4 v[104:107], v[82:83], off offset:16
	ds_bpermute_b32 v88, v164, v76
	ds_bpermute_b32 v96, v164, v72
	ds_bpermute_b32 v89, v164, v77
	ds_bpermute_b32 v97, v164, v73
	ds_bpermute_b32 v94, v164, v78
	ds_bpermute_b32 v108, v164, v74
	ds_bpermute_b32 v95, v164, v79
	ds_bpermute_b32 v109, v164, v75
	s_waitcnt vmcnt(0) lgkmcnt(0)
	v_mul_f32_e32 v90, v90, v88
	v_mul_f32_e32 v91, v91, v89
	v_mul_f32_e32 v82, v78, v86
	v_mul_f32_e32 v83, v79, v87
	v_mul_f32_e32 v86, v76, v84
	v_mul_f32_e32 v87, v77, v85
	v_mul_f32_e32 v94, v92, v94
	v_mul_f32_e32 v95, v93, v95
	v_mul_f32_e32 v84, v100, v96
	v_mul_f32_e32 v85, v101, v97
	v_mul_f32_e32 v88, v102, v108
	v_mul_f32_e32 v89, v103, v109
	v_mul_f32_e32 v92, v74, v106
	v_mul_f32_e32 v93, v75, v107
	v_mul_f32_e32 v96, v72, v104
	v_mul_f32_e32 v97, v73, v105
	s_and_saveexec_b64 s[20:21], s[78:79]
	s_xor_b64 s[20:21], exec, s[20:21]
	v_add_f32_e32 v78, v82, v94
	v_add_f32_e32 v79, v83, v95
	v_add_f32_e32 v76, v86, v90
	v_add_f32_e32 v77, v87, v91
	v_add_f32_e32 v74, v92, v88
	v_add_f32_e32 v75, v93, v89
	v_add_f32_e32 v72, v96, v84
	v_add_f32_e32 v73, v97, v85
	s_andn2_saveexec_b64 s[20:21], s[20:21]
	v_sub_f32_e32 v79, v83, v95
	v_sub_f32_e32 v78, v82, v94
	v_sub_f32_e32 v77, v87, v91
	v_sub_f32_e32 v76, v86, v90
	v_sub_f32_e32 v75, v93, v89
	v_sub_f32_e32 v74, v92, v88
	v_sub_f32_e32 v73, v97, v85
	v_sub_f32_e32 v72, v96, v84
	s_or_b64 exec, exec, s[20:21]
; DI void rope_perm(f32x4& a0, f32x4& a1, int fq, int lane, const float* tcos, const float* tsin, int pos) {
;   f32x4 p0, p1;
; #pragma unroll
;   for (int e = 0; e < 4; ++e) { p0[e] = shx(a0[e], 32, lane); p1[e] = shx(a1[e], 32, lane); }
;   const int jb = 8 * (fq & 1);
;   const f32x4 c0 = *(const f32x4*)(tcos + pos * 16 + jb), c1 = *(const f32x4*)(tcos + pos * 16 + jb + 4);
;   const f32x4 s0 = *(const f32x4*)(tsin + pos * 16 + jb), s1 = *(const f32x4*)(tsin + pos * 16 + jb + 4);
;   if (fq < 2) { a0 = a0 * c0 - p0 * s0; a1 = a1 * c1 - p1 * s1; }
;   else        { a0 = a0 * c0 + p0 * s0; a1 = a1 * c1 + p1 * s1; }
; }
;   DI void operator()(const f32x4 (&acc)[2][2][4][2], const pg8::Unit& u, int wr, int wc, int fr_, int fq_) const {
;     ...
;             } else if (EPI == EPI_UQ) {
;               if (n == 0) {
;                 const float sc = rinv * (0.10206207261596575f * LOG2E);
;                 const int gb = u.pn * 256 + bj * 128 + wc * 32;
;                 const int hd = gb / 96; const int within = gb - hd * 96;
;                 f32x4 a0 = v, a1 = acc[ai][bj][m][1];
;                 if (within == 64) rope_perm(a0, a1, fq, t_ & 63, tcos, tsin, token & (S_ - 1));
;                 st_bf8((u16*)(big + E_QMLA) + (size_t)token * 768 + gb + 8 * fq, a0, a1, sc);
;               }
.LBB0_1245:
	s_waitcnt lgkmcnt(0)
	v_mul_f32_e32 v82, 0x3e16c740, v99
	v_mov_b64_e32 v[84:85], s[16:17]
	s_movk_i32 s20, 0x600
	v_mad_i64_i32 v[84:85], s[20:21], v98, s20, v[84:85]
	v_mul_f32_e32 v76, v82, v76
	v_mul_f32_e32 v77, v82, v77
	v_mul_f32_e32 v78, v82, v78
	v_mul_f32_e32 v79, v82, v79
	v_mul_f32_e32 v72, v82, v72
	v_mul_f32_e32 v73, v82, v73
	v_lshl_add_u64 v[84:85], s[18:19], 1, v[84:85]
	v_cvt_pk_bf16_f32 v76, v76, v77
	v_cvt_pk_bf16_f32 v77, v78, v79
	v_cvt_pk_bf16_f32 v78, v72, v73
	v_mul_f32_e32 v72, v82, v74
	v_mul_f32_e32 v73, v82, v75
	v_lshl_add_u64 v[84:85], v[84:85], 0, v[144:145]
	v_cvt_pk_bf16_f32 v79, v72, v73
	s_and_b64 vcc, exec, s[72:73]
	global_store_dwordx4 v[84:85], v[76:79], off
	s_cbranch_vccnz .LBB0_1251
	v_mov_b32_e32 v81, v145
	v_lshl_add_u64 v[72:73], s[12:13], 0, v[80:81]
	v_mov_b32_e32 v141, v145
	v_lshl_add_u64 v[78:79], s[14:15], 0, v[80:81]
	v_lshl_add_u64 v[72:73], v[72:73], 0, v[140:141]
	v_lshl_add_u64 v[78:79], v[78:79], 0, v[140:141]
	global_load_dwordx4 v[74:77], v[72:73], off
	global_load_dwordx4 v[86:89], v[78:79], off
	global_load_dwordx4 v[90:93], v[78:79], off offset:16
	global_load_dwordx4 v[94:97], v[72:73], off offset:16
	ds_bpermute_b32 v78, v164, v68
	ds_bpermute_b32 v98, v164, v64
	ds_bpermute_b32 v79, v164, v69
	ds_bpermute_b32 v99, v164, v65
	ds_bpermute_b32 v100, v164, v70
	ds_bpermute_b32 v102, v164, v66
	ds_bpermute_b32 v101, v164, v71
	ds_bpermute_b32 v103, v164, v67
	s_waitcnt vmcnt(0) lgkmcnt(0)
	v_mul_f32_e32 v80, v86, v78
	v_mul_f32_e32 v81, v87, v79
	v_mul_f32_e32 v72, v70, v76
	v_mul_f32_e32 v73, v71, v77
	v_mul_f32_e32 v76, v68, v74
	v_mul_f32_e32 v77, v69, v75
	v_mul_f32_e32 v88, v88, v100
	v_mul_f32_e32 v89, v89, v101
	v_mul_f32_e32 v74, v90, v98
	v_mul_f32_e32 v75, v91, v99
	v_mul_f32_e32 v78, v92, v102
	v_mul_f32_e32 v79, v93, v103
	v_mul_f32_e32 v86, v66, v96
	v_mul_f32_e32 v87, v67, v97
	v_mul_f32_e32 v90, v64, v94
	v_mul_f32_e32 v91, v65, v95
	s_and_saveexec_b64 s[20:21], s[78:79]
	s_xor_b64 s[20:21], exec, s[20:21]
	v_add_f32_e32 v70, v72, v88
	v_add_f32_e32 v71, v73, v89
	v_add_f32_e32 v68, v76, v80
	v_add_f32_e32 v69, v77, v81
	v_add_f32_e32 v66, v86, v78
	v_add_f32_e32 v67, v87, v79
	v_add_f32_e32 v64, v90, v74
	v_add_f32_e32 v65, v91, v75
	s_andn2_saveexec_b64 s[20:21], s[20:21]
	v_sub_f32_e32 v71, v73, v89
	v_sub_f32_e32 v70, v72, v88
	v_sub_f32_e32 v69, v77, v81
	v_sub_f32_e32 v68, v76, v80
	v_sub_f32_e32 v67, v87, v79
	v_sub_f32_e32 v66, v86, v78
	v_sub_f32_e32 v65, v91, v75
	v_sub_f32_e32 v64, v90, v74
	s_or_b64 exec, exec, s[20:21]
.LBB0_1251:
	v_mov_b32_e32 v83, v82
	v_mul_f32_e32 v68, v82, v68
	v_mul_f32_e32 v69, v83, v69
	v_mul_f32_e32 v70, v82, v70
	v_mul_f32_e32 v71, v83, v71
	v_mul_f32_e32 v64, v82, v64
	v_mul_f32_e32 v65, v83, v65
	v_cvt_pk_bf16_f32 v68, v68, v69
	v_cvt_pk_bf16_f32 v69, v70, v71
	v_cvt_pk_bf16_f32 v70, v64, v65
	v_mul_f32_e32 v64, v82, v66
	v_mul_f32_e32 v65, v83, v67
	ds_read_b32 v83, v166 offset:512
	v_add_u32_e32 v82, 0x80, v165
	v_cvt_pk_bf16_f32 v71, v64, v65
	v_lshlrev_b32_e32 v64, 4, v82
	v_and_b32_e32 v64, 0xfcf0, v64
	s_and_b64 vcc, exec, s[70:71]
	v_lshlrev_b32_e32 v64, 2, v64
	global_store_dwordx4 v[84:85], v[68:71], off offset:256
	s_cbranch_vccnz .LBB0_1257
	v_mov_b32_e32 v65, v145
	v_lshl_add_u64 v[66:67], s[12:13], 0, v[64:65]
	v_mov_b32_e32 v141, v145
	v_lshl_add_u64 v[72:73], s[14:15], 0, v[64:65]
	v_lshl_add_u64 v[66:67], v[66:67], 0, v[140:141]
	v_lshl_add_u64 v[72:73], v[72:73], 0, v[140:141]
	global_load_dwordx4 v[68:71], v[66:67], off
	global_load_dwordx4 v[74:77], v[72:73], off
	global_load_dwordx4 v[84:87], v[72:73], off offset:16
	global_load_dwordx4 v[88:91], v[66:67], off offset:16
	ds_bpermute_b32 v72, v164, v60
	ds_bpermute_b32 v80, v164, v56
	ds_bpermute_b32 v73, v164, v61
	ds_bpermute_b32 v81, v164, v57
	ds_bpermute_b32 v78, v164, v62
	ds_bpermute_b32 v92, v164, v58
	ds_bpermute_b32 v79, v164, v63
	ds_bpermute_b32 v93, v164, v59
	s_waitcnt vmcnt(0) lgkmcnt(0)
	v_mul_f32_e32 v74, v74, v72
	v_mul_f32_e32 v75, v75, v73
	v_mul_f32_e32 v66, v62, v70
	v_mul_f32_e32 v67, v63, v71
	v_mul_f32_e32 v70, v60, v68
	v_mul_f32_e32 v71, v61, v69
	v_mul_f32_e32 v78, v76, v78
	v_mul_f32_e32 v79, v77, v79
	v_mul_f32_e32 v68, v84, v80
	v_mul_f32_e32 v69, v85, v81
	v_mul_f32_e32 v72, v86, v92
	v_mul_f32_e32 v73, v87, v93
	v_mul_f32_e32 v76, v58, v90
	v_mul_f32_e32 v77, v59, v91
	v_mul_f32_e32 v80, v56, v88
	v_mul_f32_e32 v81, v57, v89
	s_and_saveexec_b64 s[20:21], s[78:79]
	s_xor_b64 s[20:21], exec, s[20:21]
	v_add_f32_e32 v62, v66, v78
	v_add_f32_e32 v63, v67, v79
	v_add_f32_e32 v60, v70, v74
	v_add_f32_e32 v61, v71, v75
	v_add_f32_e32 v58, v76, v72
	v_add_f32_e32 v59, v77, v73
	v_add_f32_e32 v56, v80, v68
	v_add_f32_e32 v57, v81, v69
	s_andn2_saveexec_b64 s[20:21], s[20:21]
	v_sub_f32_e32 v63, v67, v79
	v_sub_f32_e32 v62, v66, v78
	v_sub_f32_e32 v61, v71, v75
	v_sub_f32_e32 v60, v70, v74
	v_sub_f32_e32 v59, v77, v73
	v_sub_f32_e32 v58, v76, v72
	v_sub_f32_e32 v57, v81, v69
	v_sub_f32_e32 v56, v80, v68
	s_or_b64 exec, exec, s[20:21]
; DI void rope_perm(f32x4& a0, f32x4& a1, int fq, int lane, const float* tcos, const float* tsin, int pos) {
;   f32x4 p0, p1;
; #pragma unroll
;   for (int e = 0; e < 4; ++e) { p0[e] = shx(a0[e], 32, lane); p1[e] = shx(a1[e], 32, lane); }
;   const int jb = 8 * (fq & 1);
;   const f32x4 c0 = *(const f32x4*)(tcos + pos * 16 + jb), c1 = *(const f32x4*)(tcos + pos * 16 + jb + 4);
;   const f32x4 s0 = *(const f32x4*)(tsin + pos * 16 + jb), s1 = *(const f32x4*)(tsin + pos * 16 + jb + 4);
;   if (fq < 2) { a0 = a0 * c0 - p0 * s0; a1 = a1 * c1 - p1 * s1; }
;   else        { a0 = a0 * c0 + p0 * s0; a1 = a1 * c1 + p1 * s1; }
; }
;   DI void operator()(const f32x4 (&acc)[2][2][4][2], const pg8::Unit& u, int wr, int wc, int fr_, int fq_) const {
;     ...
;             } else if (EPI == EPI_UQ) {
;               if (n == 0) {
;                 const float sc = rinv * (0.10206207261596575f * LOG2E);
;                 const int gb = u.pn * 256 + bj * 128 + wc * 32;
;                 const int hd = gb / 96; const int within = gb - hd * 96;
;                 f32x4 a0 = v, a1 = acc[ai][bj][m][1];
;                 if (within == 64) rope_perm(a0, a1, fq, t_ & 63, tcos, tsin, token & (S_ - 1));
;                 st_bf8((u16*)(big + E_QMLA) + (size_t)token * 768 + gb + 8 * fq, a0, a1, sc);
;               }
.LBB0_1257:
	s_waitcnt lgkmcnt(0)
	v_mul_f32_e32 v66, 0x3e16c740, v83
	v_mov_b64_e32 v[68:69], s[16:17]
	s_movk_i32 s20, 0x600
	v_mad_i64_i32 v[68:69], s[20:21], v82, s20, v[68:69]
	v_mul_f32_e32 v60, v66, v60
	v_mul_f32_e32 v61, v66, v61
	v_mul_f32_e32 v62, v66, v62
	v_mul_f32_e32 v63, v66, v63
	v_mul_f32_e32 v56, v66, v56
	v_mul_f32_e32 v57, v66, v57
	v_lshl_add_u64 v[68:69], s[18:19], 1, v[68:69]
	v_cvt_pk_bf16_f32 v60, v60, v61
	v_cvt_pk_bf16_f32 v61, v62, v63
	v_cvt_pk_bf16_f32 v62, v56, v57
	v_mul_f32_e32 v56, v66, v58
	v_mul_f32_e32 v57, v66, v59
	v_lshl_add_u64 v[68:69], v[68:69], 0, v[144:145]
	v_cvt_pk_bf16_f32 v63, v56, v57
	s_and_b64 vcc, exec, s[72:73]
	global_store_dwordx4 v[68:69], v[60:63], off
	s_cbranch_vccnz .LBB0_1263
	v_mov_b32_e32 v65, v145
	v_lshl_add_u64 v[56:57], s[12:13], 0, v[64:65]
	v_mov_b32_e32 v141, v145
	v_lshl_add_u64 v[62:63], s[14:15], 0, v[64:65]
	v_lshl_add_u64 v[56:57], v[56:57], 0, v[140:141]
	v_lshl_add_u64 v[62:63], v[62:63], 0, v[140:141]
	global_load_dwordx4 v[58:61], v[56:57], off
	global_load_dwordx4 v[70:73], v[62:63], off
	global_load_dwordx4 v[74:77], v[62:63], off offset:16
	global_load_dwordx4 v[78:81], v[56:57], off offset:16
	ds_bpermute_b32 v62, v164, v52
	ds_bpermute_b32 v82, v164, v48
	ds_bpermute_b32 v63, v164, v53
	ds_bpermute_b32 v83, v164, v49
	ds_bpermute_b32 v84, v164, v54
	ds_bpermute_b32 v86, v164, v50
	ds_bpermute_b32 v85, v164, v55
	ds_bpermute_b32 v87, v164, v51
	s_waitcnt vmcnt(0) lgkmcnt(0)
	v_mul_f32_e32 v64, v70, v62
	v_mul_f32_e32 v65, v71, v63
	v_mul_f32_e32 v56, v54, v60
	v_mul_f32_e32 v57, v55, v61
	v_mul_f32_e32 v60, v52, v58
	v_mul_f32_e32 v61, v53, v59
	v_mul_f32_e32 v72, v72, v84
	v_mul_f32_e32 v73, v73, v85
	v_mul_f32_e32 v58, v74, v82
	v_mul_f32_e32 v59, v75, v83
	v_mul_f32_e32 v62, v76, v86
	v_mul_f32_e32 v63, v77, v87
	v_mul_f32_e32 v70, v50, v80
	v_mul_f32_e32 v71, v51, v81
	v_mul_f32_e32 v74, v48, v78
	v_mul_f32_e32 v75, v49, v79
	s_and_saveexec_b64 s[20:21], s[78:79]
	s_xor_b64 s[20:21], exec, s[20:21]
	v_add_f32_e32 v54, v56, v72
	v_add_f32_e32 v55, v57, v73
	v_add_f32_e32 v52, v60, v64
	v_add_f32_e32 v53, v61, v65
	v_add_f32_e32 v50, v70, v62
	v_add_f32_e32 v51, v71, v63
	v_add_f32_e32 v48, v74, v58
	v_add_f32_e32 v49, v75, v59
	s_andn2_saveexec_b64 s[20:21], s[20:21]
	v_sub_f32_e32 v55, v57, v73
	v_sub_f32_e32 v54, v56, v72
	v_sub_f32_e32 v53, v61, v65
	v_sub_f32_e32 v52, v60, v64
	v_sub_f32_e32 v51, v71, v63
	v_sub_f32_e32 v50, v70, v62
	v_sub_f32_e32 v49, v75, v59
	v_sub_f32_e32 v48, v74, v58
	s_or_b64 exec, exec, s[20:21]
.LBB0_1263:
	v_mov_b32_e32 v67, v66
	v_mul_f32_e32 v52, v66, v52
	v_mul_f32_e32 v53, v67, v53
	v_mul_f32_e32 v54, v66, v54
	v_mul_f32_e32 v55, v67, v55
	v_mul_f32_e32 v48, v66, v48
	v_mul_f32_e32 v49, v67, v49
	v_cvt_pk_bf16_f32 v52, v52, v53
	v_cvt_pk_bf16_f32 v53, v54, v55
	v_cvt_pk_bf16_f32 v54, v48, v49
	v_mul_f32_e32 v48, v66, v50
	v_mul_f32_e32 v49, v67, v51
	ds_read_b32 v67, v166 offset:576
	v_add_u32_e32 v66, 0x90, v165
	v_cvt_pk_bf16_f32 v55, v48, v49
	v_lshlrev_b32_e32 v48, 4, v66
	v_and_b32_e32 v48, 0xfdf0, v48
	s_and_b64 vcc, exec, s[70:71]
	v_lshlrev_b32_e32 v48, 2, v48
	global_store_dwordx4 v[68:69], v[52:55], off offset:256
	s_cbranch_vccnz .LBB0_1269
	v_mov_b32_e32 v49, v145
	v_lshl_add_u64 v[50:51], s[12:13], 0, v[48:49]
	v_mov_b32_e32 v141, v145
	v_lshl_add_u64 v[56:57], s[14:15], 0, v[48:49]
	v_lshl_add_u64 v[50:51], v[50:51], 0, v[140:141]
	v_lshl_add_u64 v[56:57], v[56:57], 0, v[140:141]
	global_load_dwordx4 v[52:55], v[50:51], off
	global_load_dwordx4 v[58:61], v[56:57], off
	global_load_dwordx4 v[68:71], v[56:57], off offset:16
	global_load_dwordx4 v[72:75], v[50:51], off offset:16
	ds_bpermute_b32 v56, v164, v44
	ds_bpermute_b32 v64, v164, v40
	ds_bpermute_b32 v57, v164, v45
	ds_bpermute_b32 v65, v164, v41
	ds_bpermute_b32 v62, v164, v46
	ds_bpermute_b32 v76, v164, v42
	ds_bpermute_b32 v63, v164, v47
	ds_bpermute_b32 v77, v164, v43
	s_waitcnt vmcnt(0) lgkmcnt(0)
	v_mul_f32_e32 v58, v58, v56
	v_mul_f32_e32 v59, v59, v57
	v_mul_f32_e32 v50, v46, v54
	v_mul_f32_e32 v51, v47, v55
	v_mul_f32_e32 v54, v44, v52
	v_mul_f32_e32 v55, v45, v53
	v_mul_f32_e32 v62, v60, v62
	v_mul_f32_e32 v63, v61, v63
	v_mul_f32_e32 v52, v68, v64
	v_mul_f32_e32 v53, v69, v65
	v_mul_f32_e32 v56, v70, v76
	v_mul_f32_e32 v57, v71, v77
	v_mul_f32_e32 v60, v42, v74
	v_mul_f32_e32 v61, v43, v75
	v_mul_f32_e32 v64, v40, v72
	v_mul_f32_e32 v65, v41, v73
	s_and_saveexec_b64 s[20:21], s[78:79]
	s_xor_b64 s[20:21], exec, s[20:21]
	v_add_f32_e32 v46, v50, v62
	v_add_f32_e32 v47, v51, v63
	v_add_f32_e32 v44, v54, v58
	v_add_f32_e32 v45, v55, v59
	v_add_f32_e32 v42, v60, v56
	v_add_f32_e32 v43, v61, v57
	v_add_f32_e32 v40, v64, v52
	v_add_f32_e32 v41, v65, v53
	s_andn2_saveexec_b64 s[20:21], s[20:21]
	v_sub_f32_e32 v47, v51, v63
	v_sub_f32_e32 v46, v50, v62
	v_sub_f32_e32 v45, v55, v59
	v_sub_f32_e32 v44, v54, v58
	v_sub_f32_e32 v43, v61, v57
	v_sub_f32_e32 v42, v60, v56
	v_sub_f32_e32 v41, v65, v53
	v_sub_f32_e32 v40, v64, v52
	s_or_b64 exec, exec, s[20:21]
; DI void rope_perm(f32x4& a0, f32x4& a1, int fq, int lane, const float* tcos, const float* tsin, int pos) {
;   f32x4 p0, p1;
; #pragma unroll
;   for (int e = 0; e < 4; ++e) { p0[e] = shx(a0[e], 32, lane); p1[e] = shx(a1[e], 32, lane); }
;   const int jb = 8 * (fq & 1);
;   const f32x4 c0 = *(const f32x4*)(tcos + pos * 16 + jb), c1 = *(const f32x4*)(tcos + pos * 16 + jb + 4);
;   const f32x4 s0 = *(const f32x4*)(tsin + pos * 16 + jb), s1 = *(const f32x4*)(tsin + pos * 16 + jb + 4);
;   if (fq < 2) { a0 = a0 * c0 - p0 * s0; a1 = a1 * c1 - p1 * s1; }
;   else        { a0 = a0 * c0 + p0 * s0; a1 = a1 * c1 + p1 * s1; }
; }
;   DI void operator()(const f32x4 (&acc)[2][2][4][2], const pg8::Unit& u, int wr, int wc, int fr_, int fq_) const {
;     ...
;             } else if (EPI == EPI_UQ) {
;               if (n == 0) {
;                 const float sc = rinv * (0.10206207261596575f * LOG2E);
;                 const int gb = u.pn * 256 + bj * 128 + wc * 32;
;                 const int hd = gb / 96; const int within = gb - hd * 96;
;                 f32x4 a0 = v, a1 = acc[ai][bj][m][1];
;                 if (within == 64) rope_perm(a0, a1, fq, t_ & 63, tcos, tsin, token & (S_ - 1));
;                 st_bf8((u16*)(big + E_QMLA) + (size_t)token * 768 + gb + 8 * fq, a0, a1, sc);
;               }
.LBB0_1269:
	s_waitcnt lgkmcnt(0)
	v_mul_f32_e32 v50, 0x3e16c740, v67
	v_mov_b64_e32 v[52:53], s[16:17]
	s_movk_i32 s20, 0x600
	v_mad_i64_i32 v[52:53], s[20:21], v66, s20, v[52:53]
	v_mul_f32_e32 v44, v50, v44
	v_mul_f32_e32 v45, v50, v45
	v_mul_f32_e32 v46, v50, v46
	v_mul_f32_e32 v47, v50, v47
	v_mul_f32_e32 v40, v50, v40
	v_mul_f32_e32 v41, v50, v41
	v_lshl_add_u64 v[52:53], s[18:19], 1, v[52:53]
	v_cvt_pk_bf16_f32 v44, v44, v45
	v_cvt_pk_bf16_f32 v45, v46, v47
	v_cvt_pk_bf16_f32 v46, v40, v41
	v_mul_f32_e32 v40, v50, v42
	v_mul_f32_e32 v41, v50, v43
	v_lshl_add_u64 v[52:53], v[52:53], 0, v[144:145]
	v_cvt_pk_bf16_f32 v47, v40, v41
	s_and_b64 vcc, exec, s[72:73]
	global_store_dwordx4 v[52:53], v[44:47], off
	s_cbranch_vccnz .LBB0_1275
	v_mov_b32_e32 v49, v145
	v_lshl_add_u64 v[40:41], s[12:13], 0, v[48:49]
	v_mov_b32_e32 v141, v145
	v_lshl_add_u64 v[46:47], s[14:15], 0, v[48:49]
	v_lshl_add_u64 v[40:41], v[40:41], 0, v[140:141]
	v_lshl_add_u64 v[46:47], v[46:47], 0, v[140:141]
	global_load_dwordx4 v[42:45], v[40:41], off
	global_load_dwordx4 v[54:57], v[46:47], off
	global_load_dwordx4 v[58:61], v[46:47], off offset:16
	global_load_dwordx4 v[62:65], v[40:41], off offset:16
	ds_bpermute_b32 v46, v164, v36
	ds_bpermute_b32 v66, v164, v32
	ds_bpermute_b32 v47, v164, v37
	ds_bpermute_b32 v67, v164, v33
	ds_bpermute_b32 v68, v164, v38
	ds_bpermute_b32 v70, v164, v34
	ds_bpermute_b32 v69, v164, v39
	ds_bpermute_b32 v71, v164, v35
	s_waitcnt vmcnt(0) lgkmcnt(0)
	v_mul_f32_e32 v48, v54, v46
	v_mul_f32_e32 v49, v55, v47
	v_mul_f32_e32 v40, v38, v44
	v_mul_f32_e32 v41, v39, v45
	v_mul_f32_e32 v44, v36, v42
	v_mul_f32_e32 v45, v37, v43
	v_mul_f32_e32 v56, v56, v68
	v_mul_f32_e32 v57, v57, v69
	v_mul_f32_e32 v42, v58, v66
	v_mul_f32_e32 v43, v59, v67
	v_mul_f32_e32 v46, v60, v70
	v_mul_f32_e32 v47, v61, v71
	v_mul_f32_e32 v54, v34, v64
	v_mul_f32_e32 v55, v35, v65
	v_mul_f32_e32 v58, v32, v62
	v_mul_f32_e32 v59, v33, v63
	s_and_saveexec_b64 s[20:21], s[78:79]
	s_xor_b64 s[20:21], exec, s[20:21]
	v_add_f32_e32 v38, v40, v56
	v_add_f32_e32 v39, v41, v57
	v_add_f32_e32 v36, v44, v48
	v_add_f32_e32 v37, v45, v49
	v_add_f32_e32 v34, v54, v46
	v_add_f32_e32 v35, v55, v47
	v_add_f32_e32 v32, v58, v42
	v_add_f32_e32 v33, v59, v43
	s_andn2_saveexec_b64 s[20:21], s[20:21]
	v_sub_f32_e32 v39, v41, v57
	v_sub_f32_e32 v38, v40, v56
	v_sub_f32_e32 v37, v45, v49
	v_sub_f32_e32 v36, v44, v48
	v_sub_f32_e32 v35, v55, v47
	v_sub_f32_e32 v34, v54, v46
	v_sub_f32_e32 v33, v59, v43
	v_sub_f32_e32 v32, v58, v42
	s_or_b64 exec, exec, s[20:21]
.LBB0_1275:
	v_mov_b32_e32 v51, v50
	v_mul_f32_e32 v36, v50, v36
	v_mul_f32_e32 v37, v51, v37
	v_mul_f32_e32 v38, v50, v38
	v_mul_f32_e32 v39, v51, v39
	v_mul_f32_e32 v32, v50, v32
	v_mul_f32_e32 v33, v51, v33
	v_cvt_pk_bf16_f32 v36, v36, v37
	v_cvt_pk_bf16_f32 v37, v38, v39
	v_cvt_pk_bf16_f32 v38, v32, v33
	v_mul_f32_e32 v32, v50, v34
	v_mul_f32_e32 v33, v51, v35
	ds_read_b32 v51, v166 offset:640
	v_add_u32_e32 v50, 0xa0, v165
	v_cvt_pk_bf16_f32 v39, v32, v33
	v_lshlrev_b32_e32 v32, 4, v50
	v_and_b32_e32 v32, 0xfef0, v32
	s_and_b64 vcc, exec, s[70:71]
	v_lshlrev_b32_e32 v32, 2, v32
	global_store_dwordx4 v[52:53], v[36:39], off offset:256
	s_cbranch_vccnz .LBB0_1281
	v_mov_b32_e32 v33, v145
	v_lshl_add_u64 v[34:35], s[12:13], 0, v[32:33]
	v_mov_b32_e32 v141, v145
	v_lshl_add_u64 v[40:41], s[14:15], 0, v[32:33]
	v_lshl_add_u64 v[34:35], v[34:35], 0, v[140:141]
	v_lshl_add_u64 v[40:41], v[40:41], 0, v[140:141]
	global_load_dwordx4 v[36:39], v[34:35], off
	global_load_dwordx4 v[42:45], v[40:41], off
	global_load_dwordx4 v[52:55], v[40:41], off offset:16
	global_load_dwordx4 v[56:59], v[34:35], off offset:16
	ds_bpermute_b32 v40, v164, v28
	ds_bpermute_b32 v48, v164, v24
	ds_bpermute_b32 v41, v164, v29
	ds_bpermute_b32 v49, v164, v25
	ds_bpermute_b32 v46, v164, v30
	ds_bpermute_b32 v60, v164, v26
	ds_bpermute_b32 v47, v164, v31
	ds_bpermute_b32 v61, v164, v27
	s_waitcnt vmcnt(0) lgkmcnt(0)
	v_mul_f32_e32 v42, v42, v40
	v_mul_f32_e32 v43, v43, v41
	v_mul_f32_e32 v34, v30, v38
	v_mul_f32_e32 v35, v31, v39
	v_mul_f32_e32 v38, v28, v36
	v_mul_f32_e32 v39, v29, v37
	v_mul_f32_e32 v46, v44, v46
	v_mul_f32_e32 v47, v45, v47
	v_mul_f32_e32 v36, v52, v48
	v_mul_f32_e32 v37, v53, v49
	v_mul_f32_e32 v40, v54, v60
	v_mul_f32_e32 v41, v55, v61
	v_mul_f32_e32 v44, v26, v58
	v_mul_f32_e32 v45, v27, v59
	v_mul_f32_e32 v48, v24, v56
	v_mul_f32_e32 v49, v25, v57
	s_and_saveexec_b64 s[20:21], s[78:79]
	s_xor_b64 s[20:21], exec, s[20:21]
	v_add_f32_e32 v30, v34, v46
	v_add_f32_e32 v31, v35, v47
	v_add_f32_e32 v28, v38, v42
	v_add_f32_e32 v29, v39, v43
	v_add_f32_e32 v26, v44, v40
	v_add_f32_e32 v27, v45, v41
	v_add_f32_e32 v24, v48, v36
	v_add_f32_e32 v25, v49, v37
	s_andn2_saveexec_b64 s[20:21], s[20:21]
	v_sub_f32_e32 v31, v35, v47
	v_sub_f32_e32 v30, v34, v46
	v_sub_f32_e32 v29, v39, v43
	v_sub_f32_e32 v28, v38, v42
	v_sub_f32_e32 v27, v45, v41
	v_sub_f32_e32 v26, v44, v40
	v_sub_f32_e32 v25, v49, v37
	v_sub_f32_e32 v24, v48, v36
	s_or_b64 exec, exec, s[20:21]
; DI void rope_perm(f32x4& a0, f32x4& a1, int fq, int lane, const float* tcos, const float* tsin, int pos) {
;   f32x4 p0, p1;
; #pragma unroll
;   for (int e = 0; e < 4; ++e) { p0[e] = shx(a0[e], 32, lane); p1[e] = shx(a1[e], 32, lane); }
;   const int jb = 8 * (fq & 1);
;   const f32x4 c0 = *(const f32x4*)(tcos + pos * 16 + jb), c1 = *(const f32x4*)(tcos + pos * 16 + jb + 4);
;   const f32x4 s0 = *(const f32x4*)(tsin + pos * 16 + jb), s1 = *(const f32x4*)(tsin + pos * 16 + jb + 4);
;   if (fq < 2) { a0 = a0 * c0 - p0 * s0; a1 = a1 * c1 - p1 * s1; }
;   else        { a0 = a0 * c0 + p0 * s0; a1 = a1 * c1 + p1 * s1; }
; }
;   DI void operator()(const f32x4 (&acc)[2][2][4][2], const pg8::Unit& u, int wr, int wc, int fr_, int fq_) const {
;     ...
;             } else if (EPI == EPI_UQ) {
;               if (n == 0) {
;                 const float sc = rinv * (0.10206207261596575f * LOG2E);
;                 const int gb = u.pn * 256 + bj * 128 + wc * 32;
;                 const int hd = gb / 96; const int within = gb - hd * 96;
;                 f32x4 a0 = v, a1 = acc[ai][bj][m][1];
;                 if (within == 64) rope_perm(a0, a1, fq, t_ & 63, tcos, tsin, token & (S_ - 1));
;                 st_bf8((u16*)(big + E_QMLA) + (size_t)token * 768 + gb + 8 * fq, a0, a1, sc);
;               }
.LBB0_1281:
	s_waitcnt lgkmcnt(0)
	v_mul_f32_e32 v34, 0x3e16c740, v51
	v_mov_b64_e32 v[36:37], s[16:17]
	s_movk_i32 s20, 0x600
	v_mad_i64_i32 v[36:37], s[20:21], v50, s20, v[36:37]
	v_mul_f32_e32 v28, v34, v28
	v_mul_f32_e32 v29, v34, v29
	v_mul_f32_e32 v30, v34, v30
	v_mul_f32_e32 v31, v34, v31
	v_mul_f32_e32 v24, v34, v24
	v_mul_f32_e32 v25, v34, v25
	v_lshl_add_u64 v[36:37], s[18:19], 1, v[36:37]
	v_cvt_pk_bf16_f32 v28, v28, v29
	v_cvt_pk_bf16_f32 v29, v30, v31
	v_cvt_pk_bf16_f32 v30, v24, v25
	v_mul_f32_e32 v24, v34, v26
	v_mul_f32_e32 v25, v34, v27
	v_lshl_add_u64 v[36:37], v[36:37], 0, v[144:145]
	v_cvt_pk_bf16_f32 v31, v24, v25
	s_and_b64 vcc, exec, s[72:73]
	global_store_dwordx4 v[36:37], v[28:31], off
	s_cbranch_vccnz .LBB0_1287
	v_mov_b32_e32 v33, v145
	v_lshl_add_u64 v[24:25], s[12:13], 0, v[32:33]
	v_mov_b32_e32 v141, v145
	v_lshl_add_u64 v[30:31], s[14:15], 0, v[32:33]
	v_lshl_add_u64 v[24:25], v[24:25], 0, v[140:141]
	v_lshl_add_u64 v[30:31], v[30:31], 0, v[140:141]
	global_load_dwordx4 v[26:29], v[24:25], off
	global_load_dwordx4 v[38:41], v[30:31], off
	global_load_dwordx4 v[42:45], v[30:31], off offset:16
	global_load_dwordx4 v[46:49], v[24:25], off offset:16
	ds_bpermute_b32 v30, v164, v20
	ds_bpermute_b32 v50, v164, v16
	ds_bpermute_b32 v31, v164, v21
	ds_bpermute_b32 v51, v164, v17
	ds_bpermute_b32 v52, v164, v22
	ds_bpermute_b32 v54, v164, v18
	ds_bpermute_b32 v53, v164, v23
	ds_bpermute_b32 v55, v164, v19
	s_waitcnt vmcnt(0) lgkmcnt(0)
	v_mul_f32_e32 v32, v38, v30
	v_mul_f32_e32 v33, v39, v31
	v_mul_f32_e32 v24, v22, v28
	v_mul_f32_e32 v25, v23, v29
	v_mul_f32_e32 v28, v20, v26
	v_mul_f32_e32 v29, v21, v27
	v_mul_f32_e32 v40, v40, v52
	v_mul_f32_e32 v41, v41, v53
	v_mul_f32_e32 v26, v42, v50
	v_mul_f32_e32 v27, v43, v51
	v_mul_f32_e32 v30, v44, v54
	v_mul_f32_e32 v31, v45, v55
	v_mul_f32_e32 v38, v18, v48
	v_mul_f32_e32 v39, v19, v49
	v_mul_f32_e32 v42, v16, v46
	v_mul_f32_e32 v43, v17, v47
	s_and_saveexec_b64 s[20:21], s[78:79]
	s_xor_b64 s[20:21], exec, s[20:21]
	v_add_f32_e32 v22, v24, v40
	v_add_f32_e32 v23, v25, v41
	v_add_f32_e32 v20, v28, v32
	v_add_f32_e32 v21, v29, v33
	v_add_f32_e32 v18, v38, v30
	v_add_f32_e32 v19, v39, v31
	v_add_f32_e32 v16, v42, v26
	v_add_f32_e32 v17, v43, v27
	s_andn2_saveexec_b64 s[20:21], s[20:21]
	v_sub_f32_e32 v23, v25, v41
	v_sub_f32_e32 v22, v24, v40
	v_sub_f32_e32 v21, v29, v33
	v_sub_f32_e32 v20, v28, v32
	v_sub_f32_e32 v19, v39, v31
	v_sub_f32_e32 v18, v38, v30
	v_sub_f32_e32 v17, v43, v27
	v_sub_f32_e32 v16, v42, v26
	s_or_b64 exec, exec, s[20:21]
; DI void rope_perm(f32x4& a0, f32x4& a1, int fq, int lane, const float* tcos, const float* tsin, int pos) {
;   f32x4 p0, p1;
; #pragma unroll
;   for (int e = 0; e < 4; ++e) { p0[e] = shx(a0[e], 32, lane); p1[e] = shx(a1[e], 32, lane); }
;   const int jb = 8 * (fq & 1);
;   const f32x4 c0 = *(const f32x4*)(tcos + pos * 16 + jb), c1 = *(const f32x4*)(tcos + pos * 16 + jb + 4);
;   const f32x4 s0 = *(const f32x4*)(tsin + pos * 16 + jb), s1 = *(const f32x4*)(tsin + pos * 16 + jb + 4);
;   if (fq < 2) { a0 = a0 * c0 - p0 * s0; a1 = a1 * c1 - p1 * s1; }
;   else        { a0 = a0 * c0 + p0 * s0; a1 = a1 * c1 + p1 * s1; }
; }
;   DI void operator()(const f32x4 (&acc)[2][2][4][2], const pg8::Unit& u, int wr, int wc, int fr_, int fq_) const {
;     ...
;             } else if (EPI == EPI_UQ) {
;               if (n == 0) {
;                 const float sc = rinv * (0.10206207261596575f * LOG2E);
;                 const int gb = u.pn * 256 + bj * 128 + wc * 32;
;                 const int hd = gb / 96; const int within = gb - hd * 96;
;                 f32x4 a0 = v, a1 = acc[ai][bj][m][1];
;                 if (within == 64) rope_perm(a0, a1, fq, t_ & 63, tcos, tsin, token & (S_ - 1));
;                 st_bf8((u16*)(big + E_QMLA) + (size_t)token * 768 + gb + 8 * fq, a0, a1, sc);
;               }
.LBB0_1287:
	v_mov_b32_e32 v35, v34
	v_mul_f32_e32 v20, v34, v20
	v_mul_f32_e32 v21, v35, v21
	v_mul_f32_e32 v22, v34, v22
	v_mul_f32_e32 v23, v35, v23
	v_mul_f32_e32 v16, v34, v16
	v_mul_f32_e32 v17, v35, v17
	v_cvt_pk_bf16_f32 v20, v20, v21
	v_cvt_pk_bf16_f32 v21, v22, v23
	v_cvt_pk_bf16_f32 v22, v16, v17
	v_mul_f32_e32 v16, v34, v18
	v_mul_f32_e32 v17, v35, v19
	ds_read_b32 v35, v166 offset:704
	v_add_u32_e32 v34, 0xb0, v165
	v_cvt_pk_bf16_f32 v23, v16, v17
	v_lshlrev_b32_e32 v16, 4, v34
	v_and_b32_e32 v16, 0xfff0, v16
	s_and_b64 vcc, exec, s[70:71]
	v_lshlrev_b32_e32 v16, 2, v16
	global_store_dwordx4 v[36:37], v[20:23], off offset:256
	s_cbranch_vccnz .LBB0_1293
	v_mov_b32_e32 v17, v145
	v_lshl_add_u64 v[18:19], s[12:13], 0, v[16:17]
	v_mov_b32_e32 v141, v145
	v_lshl_add_u64 v[24:25], s[14:15], 0, v[16:17]
	v_lshl_add_u64 v[18:19], v[18:19], 0, v[140:141]
	v_lshl_add_u64 v[24:25], v[24:25], 0, v[140:141]
	global_load_dwordx4 v[20:23], v[18:19], off
	global_load_dwordx4 v[26:29], v[24:25], off
	global_load_dwordx4 v[36:39], v[24:25], off offset:16
	global_load_dwordx4 v[40:43], v[18:19], off offset:16
	ds_bpermute_b32 v24, v164, v12
	ds_bpermute_b32 v32, v164, v8
	ds_bpermute_b32 v25, v164, v13
	ds_bpermute_b32 v33, v164, v9
	ds_bpermute_b32 v30, v164, v14
	ds_bpermute_b32 v44, v164, v10
	ds_bpermute_b32 v31, v164, v15
	ds_bpermute_b32 v45, v164, v11
	s_waitcnt vmcnt(0) lgkmcnt(0)
	v_mul_f32_e32 v26, v26, v24
	v_mul_f32_e32 v27, v27, v25
	v_mul_f32_e32 v18, v14, v22
	v_mul_f32_e32 v19, v15, v23
	v_mul_f32_e32 v22, v12, v20
	v_mul_f32_e32 v23, v13, v21
	v_mul_f32_e32 v30, v28, v30
	v_mul_f32_e32 v31, v29, v31
	v_mul_f32_e32 v20, v36, v32
	v_mul_f32_e32 v21, v37, v33
	v_mul_f32_e32 v24, v38, v44
	v_mul_f32_e32 v25, v39, v45
	v_mul_f32_e32 v28, v10, v42
	v_mul_f32_e32 v29, v11, v43
	v_mul_f32_e32 v32, v8, v40
	v_mul_f32_e32 v33, v9, v41
	s_and_saveexec_b64 s[20:21], s[78:79]
	s_xor_b64 s[20:21], exec, s[20:21]
	v_add_f32_e32 v14, v18, v30
	v_add_f32_e32 v15, v19, v31
	v_add_f32_e32 v12, v22, v26
	v_add_f32_e32 v13, v23, v27
	v_add_f32_e32 v10, v28, v24
	v_add_f32_e32 v11, v29, v25
	v_add_f32_e32 v8, v32, v20
	v_add_f32_e32 v9, v33, v21
	s_andn2_saveexec_b64 s[20:21], s[20:21]
	v_sub_f32_e32 v15, v19, v31
	v_sub_f32_e32 v14, v18, v30
	v_sub_f32_e32 v13, v23, v27
	v_sub_f32_e32 v12, v22, v26
	v_sub_f32_e32 v11, v29, v25
	v_sub_f32_e32 v10, v28, v24
	v_sub_f32_e32 v9, v33, v21
	v_sub_f32_e32 v8, v32, v20
	s_or_b64 exec, exec, s[20:21]
.LBB0_1293:
	s_waitcnt lgkmcnt(0)
	v_mul_f32_e32 v18, 0x3e16c740, v35
	v_mov_b64_e32 v[20:21], s[16:17]
	s_movk_i32 s20, 0x600
	v_mad_i64_i32 v[20:21], s[20:21], v34, s20, v[20:21]
	v_mul_f32_e32 v12, v18, v12
	v_mul_f32_e32 v13, v18, v13
	v_mul_f32_e32 v14, v18, v14
	v_mul_f32_e32 v15, v18, v15
	v_mul_f32_e32 v8, v18, v8
	v_mul_f32_e32 v9, v18, v9
	v_lshl_add_u64 v[20:21], s[18:19], 1, v[20:21]
	v_cvt_pk_bf16_f32 v12, v12, v13
	v_cvt_pk_bf16_f32 v13, v14, v15
	v_cvt_pk_bf16_f32 v14, v8, v9
	v_mul_f32_e32 v8, v18, v10
	v_mul_f32_e32 v9, v18, v11
	v_lshl_add_u64 v[20:21], v[20:21], 0, v[144:145]
	v_cvt_pk_bf16_f32 v15, v8, v9
	s_and_b64 vcc, exec, s[72:73]
	global_store_dwordx4 v[20:21], v[12:15], off
	s_cbranch_vccnz .LBB0_1194
	v_mov_b32_e32 v17, v145
	v_lshl_add_u64 v[8:9], s[12:13], 0, v[16:17]
	v_mov_b32_e32 v141, v145
	v_lshl_add_u64 v[14:15], s[14:15], 0, v[16:17]
	v_lshl_add_u64 v[8:9], v[8:9], 0, v[140:141]
	v_lshl_add_u64 v[14:15], v[14:15], 0, v[140:141]
	global_load_dwordx4 v[10:13], v[8:9], off
	global_load_dwordx4 v[22:25], v[14:15], off
	global_load_dwordx4 v[26:29], v[14:15], off offset:16
	global_load_dwordx4 v[30:33], v[8:9], off offset:16
	ds_bpermute_b32 v14, v164, v4
	ds_bpermute_b32 v34, v164, v0
	ds_bpermute_b32 v15, v164, v5
	ds_bpermute_b32 v35, v164, v1
	ds_bpermute_b32 v36, v164, v6
	ds_bpermute_b32 v38, v164, v2
	ds_bpermute_b32 v37, v164, v7
	ds_bpermute_b32 v39, v164, v3
	s_waitcnt vmcnt(0) lgkmcnt(0)
	v_mul_f32_e32 v16, v22, v14
	v_mul_f32_e32 v17, v23, v15
	v_mul_f32_e32 v8, v6, v12
	v_mul_f32_e32 v9, v7, v13
	v_mul_f32_e32 v12, v4, v10
	v_mul_f32_e32 v13, v5, v11
	v_mul_f32_e32 v24, v24, v36
	v_mul_f32_e32 v25, v25, v37
	v_mul_f32_e32 v10, v26, v34
	v_mul_f32_e32 v11, v27, v35
	v_mul_f32_e32 v14, v28, v38
	v_mul_f32_e32 v15, v29, v39
	v_mul_f32_e32 v22, v2, v32
	v_mul_f32_e32 v23, v3, v33
	v_mul_f32_e32 v26, v0, v30
	v_mul_f32_e32 v27, v1, v31
	s_and_saveexec_b64 s[18:19], s[78:79]
	s_xor_b64 s[18:19], exec, s[18:19]
	v_add_f32_e32 v6, v8, v24
	v_add_f32_e32 v7, v9, v25
	v_add_f32_e32 v4, v12, v16
	v_add_f32_e32 v5, v13, v17
	v_add_f32_e32 v2, v22, v14
	v_add_f32_e32 v3, v23, v15
	v_add_f32_e32 v0, v26, v10
	v_add_f32_e32 v1, v27, v11
	s_andn2_saveexec_b64 s[18:19], s[18:19]
	s_cbranch_execz .LBB0_1193
	v_sub_f32_e32 v7, v9, v25
	v_sub_f32_e32 v6, v8, v24
	v_sub_f32_e32 v5, v13, v17
	v_sub_f32_e32 v4, v12, v16
	v_sub_f32_e32 v3, v23, v15
	v_sub_f32_e32 v2, v22, v14
	v_sub_f32_e32 v1, v27, v11
	v_sub_f32_e32 v0, v26, v10
	s_branch .LBB0_1193

; DI float bf2f(unsigned v) { return __uint_as_float(v << 16); }
; DI void rinv_prepass(const u16* __restrict__ A, int K, const pg8::StaticOrder& S, LAS float* tab) {
;     ...
;   for (int i = 0; i < 4 && S.next(i, u); ++i) {
;     const u16* pr = A + (size_t)(u.pm * 256 + row) * K + half * (K >> 1);
;     float ss = 0.f;
;     for (int c = 0; c < (K >> 1); c += 8) {
;       u32x4 w = *(const u32x4*)(pr + c);
;       float a;
;       a = bf2f(w.x & 0xffffu); ss += a * a; a = bf2f(w.x >> 16); ss += a * a;
;       a = bf2f(w.y & 0xffffu); ss += a * a; a = bf2f(w.y >> 16); ss += a * a;
;       a = bf2f(w.z & 0xffffu); ss += a * a; a = bf2f(w.z >> 16); ss += a * a;
;       a = bf2f(w.w & 0xffffu); ss += a * a; a = bf2f(w.w >> 16); ss += a * a;
;     }
;     ss += shx(ss, 1, tid & 63);
;     if (!half) tab[i * 256 + row] = rsqrtf(ss / (float)K + EPS);
;   }
.LBB0_1305:
	global_load_dwordx4 v[8:11], v[0:1], off offset:16
	global_load_dwordx4 v[12:15], v[0:1], off
	global_load_dwordx4 v[16:19], v[0:1], off offset:-16
	global_load_dwordx4 v[20:23], v[0:1], off offset:-32
	s_add_i32 s2, s2, 32
	v_lshl_add_u64 v[0:1], v[0:1], 0, 64
	s_cmpk_gt_u32 s2, 0x77
	s_waitcnt vmcnt(0)
	v_lshlrev_b32_e32 v4, 16, v20
	v_lshlrev_b32_e32 v25, 16, v21
	v_and_b32_e32 v24, 0xffff0000, v20
	v_fmac_f32_e32 v6, v4, v4
	v_mul_f32_e32 v24, v24, v24
	v_mul_f32_e32 v25, v25, v25
	v_lshlrev_b32_e32 v7, 16, v22
	v_add_f32_e32 v4, v24, v6
	v_and_b32_e32 v6, 0xffff0000, v21
	v_add_f32_e32 v4, v25, v4
	v_mul_f32_e32 v6, v6, v6
	v_mul_f32_e32 v7, v7, v7
	s_nop 0
	v_add_f32_e32 v4, v6, v4
	v_add_f32_e32 v4, v7, v4
	v_lshlrev_b32_e32 v7, 16, v23
	v_and_b32_e32 v6, 0xffff0000, v22
	v_mul_f32_e32 v6, v6, v6
	v_mul_f32_e32 v7, v7, v7
	s_nop 0
	v_add_f32_e32 v4, v6, v4
	v_add_f32_e32 v4, v7, v4
	v_and_b32_e32 v6, 0xffff0000, v23
	v_fmac_f32_e32 v4, v6, v6
	v_lshlrev_b32_e32 v6, 16, v16
	v_fmac_f32_e32 v4, v6, v6
	v_lshlrev_b32_e32 v7, 16, v17
	v_and_b32_e32 v6, 0xffff0000, v16
	v_mul_f32_e32 v6, v6, v6
	v_mul_f32_e32 v7, v7, v7
	s_nop 0
	v_add_f32_e32 v4, v6, v4
	v_add_f32_e32 v4, v7, v4
	v_lshlrev_b32_e32 v7, 16, v18
	v_and_b32_e32 v6, 0xffff0000, v17
	v_mul_f32_e32 v6, v6, v6
	v_mul_f32_e32 v7, v7, v7
	s_nop 0
	v_add_f32_e32 v4, v6, v4
	v_add_f32_e32 v4, v7, v4
	v_lshlrev_b32_e32 v7, 16, v19
	v_and_b32_e32 v6, 0xffff0000, v18
	v_mul_f32_e32 v6, v6, v6
	v_mul_f32_e32 v7, v7, v7
	s_nop 0
	v_add_f32_e32 v4, v6, v4
	v_add_f32_e32 v4, v7, v4
	v_and_b32_e32 v6, 0xffff0000, v19
	v_fmac_f32_e32 v4, v6, v6
	v_lshlrev_b32_e32 v6, 16, v12
	v_fmac_f32_e32 v4, v6, v6
	v_lshlrev_b32_e32 v7, 16, v13
	v_and_b32_e32 v6, 0xffff0000, v12
	v_mul_f32_e32 v6, v6, v6
	v_mul_f32_e32 v7, v7, v7
	s_nop 0
	v_add_f32_e32 v4, v6, v4
	v_add_f32_e32 v4, v7, v4
	v_lshlrev_b32_e32 v7, 16, v14
	v_and_b32_e32 v6, 0xffff0000, v13
	v_mul_f32_e32 v6, v6, v6
	v_mul_f32_e32 v7, v7, v7
	s_nop 0
	v_add_f32_e32 v4, v6, v4
	v_add_f32_e32 v4, v7, v4
	v_lshlrev_b32_e32 v7, 16, v15
	v_and_b32_e32 v6, 0xffff0000, v14
	v_mul_f32_e32 v6, v6, v6
	v_mul_f32_e32 v7, v7, v7
	s_nop 0
	v_add_f32_e32 v4, v6, v4
	v_add_f32_e32 v4, v7, v4
	v_and_b32_e32 v6, 0xffff0000, v15
	v_fmac_f32_e32 v4, v6, v6
	v_lshlrev_b32_e32 v6, 16, v8
	v_fmac_f32_e32 v4, v6, v6
	v_lshlrev_b32_e32 v7, 16, v9
	v_and_b32_e32 v6, 0xffff0000, v8
	v_mul_f32_e32 v6, v6, v6
	v_mul_f32_e32 v7, v7, v7
	s_nop 0
	v_add_f32_e32 v4, v6, v4
	v_add_f32_e32 v4, v7, v4
	v_lshlrev_b32_e32 v7, 16, v10
	v_and_b32_e32 v6, 0xffff0000, v9
	v_mul_f32_e32 v6, v6, v6
	v_mul_f32_e32 v7, v7, v7
	s_nop 0
	v_add_f32_e32 v4, v6, v4
	v_add_f32_e32 v4, v7, v4
	v_lshlrev_b32_e32 v7, 16, v11
	v_and_b32_e32 v6, 0xffff0000, v10
	v_mul_f32_e32 v6, v6, v6
	v_mul_f32_e32 v7, v7, v7
	s_nop 0
	v_add_f32_e32 v4, v6, v4
	v_add_f32_e32 v6, v7, v4
	v_and_b32_e32 v4, 0xffff0000, v11
	v_fmac_f32_e32 v6, v4, v4
	s_cbranch_scc0 .LBB0_1305
	v_lshlrev_b32_e32 v0, 2, v3
	v_bitop3_b32 v4, v0, 4, v190 bitop3:0x6c
	ds_bpermute_b32 v0, v4, v6
	v_readlane_b32 s2, v238, 44
	v_cmp_eq_u32_e64 s[90:91], 0, v5
	s_nop 0
	v_lshl_add_u32 v3, v2, 2, s2
	s_and_saveexec_b64 s[2:3], s[90:91]
	s_cbranch_execz .LBB0_1308
	s_waitcnt lgkmcnt(0)
	v_add_f32_e32 v0, v6, v0
	v_fmamk_f32 v0, v0, 0x3b800000, v184
	s_mov_b32 s4, 0x800000
	v_mul_f32_e32 v1, 0x4b800000, v0
	v_cmp_gt_f32_e32 vcc, s4, v0
	s_nop 1
	v_cndmask_b32_e32 v0, v0, v1, vcc
	v_rsq_f32_e32 v0, v0
	s_nop 0
	v_mul_f32_e32 v1, 0x45800000, v0
	v_cndmask_b32_e32 v0, v0, v1, vcc
	ds_write_b32 v3, v0

; DI float bf2f(unsigned v) { return __uint_as_float(v << 16); }
; DI void rinv_prepass(const u16* __restrict__ A, int K, const pg8::StaticOrder& S, LAS float* tab) {
;     ...
;   for (int i = 0; i < 4 && S.next(i, u); ++i) {
;     const u16* pr = A + (size_t)(u.pm * 256 + row) * K + half * (K >> 1);
;     float ss = 0.f;
;     for (int c = 0; c < (K >> 1); c += 8) {
;       u32x4 w = *(const u32x4*)(pr + c);
;       float a;
;       a = bf2f(w.x & 0xffffu); ss += a * a; a = bf2f(w.x >> 16); ss += a * a;
;       a = bf2f(w.y & 0xffffu); ss += a * a; a = bf2f(w.y >> 16); ss += a * a;
;       a = bf2f(w.z & 0xffffu); ss += a * a; a = bf2f(w.z >> 16); ss += a * a;
;       a = bf2f(w.w & 0xffffu); ss += a * a; a = bf2f(w.w >> 16); ss += a * a;
;     }
;     ss += shx(ss, 1, tid & 63);
;     if (!half) tab[i * 256 + row] = rsqrtf(ss / (float)K + EPS);
;   }
.LBB0_1312:
	global_load_dwordx4 v[6:9], v[0:1], off offset:16
	global_load_dwordx4 v[10:13], v[0:1], off
	global_load_dwordx4 v[14:17], v[0:1], off offset:-16
	global_load_dwordx4 v[18:21], v[0:1], off offset:-32
	s_add_i32 s2, s2, 32
	v_lshl_add_u64 v[0:1], v[0:1], 0, 64
	s_cmpk_lt_u32 s2, 0x78
	s_waitcnt vmcnt(0)
	v_lshlrev_b32_e32 v22, 16, v18
	v_fmac_f32_e32 v5, v22, v22
	v_lshlrev_b32_e32 v23, 16, v19
	v_and_b32_e32 v22, 0xffff0000, v18
	v_mul_f32_e32 v22, v22, v22
	v_mul_f32_e32 v23, v23, v23
	s_nop 0
	v_add_f32_e32 v5, v22, v5
	v_add_f32_e32 v5, v23, v5
	v_lshlrev_b32_e32 v23, 16, v20
	v_and_b32_e32 v22, 0xffff0000, v19
	v_mul_f32_e32 v18, v22, v22
	v_mul_f32_e32 v19, v23, v23
	s_nop 0
	v_add_f32_e32 v5, v18, v5
	v_add_f32_e32 v5, v19, v5
	v_lshlrev_b32_e32 v19, 16, v21
	v_and_b32_e32 v18, 0xffff0000, v20
	v_mul_f32_e32 v18, v18, v18
	v_mul_f32_e32 v19, v19, v19
	s_nop 0
	v_add_f32_e32 v5, v18, v5
	v_add_f32_e32 v5, v19, v5
	v_and_b32_e32 v18, 0xffff0000, v21
	v_fmac_f32_e32 v5, v18, v18
	v_lshlrev_b32_e32 v18, 16, v14
	v_fmac_f32_e32 v5, v18, v18
	v_lshlrev_b32_e32 v19, 16, v15
	v_and_b32_e32 v18, 0xffff0000, v14
	v_mul_f32_e32 v18, v18, v18
	v_mul_f32_e32 v19, v19, v19
	s_nop 0
	v_add_f32_e32 v5, v18, v5
	v_add_f32_e32 v5, v19, v5
	v_lshlrev_b32_e32 v19, 16, v16
	v_and_b32_e32 v18, 0xffff0000, v15
	v_mul_f32_e32 v14, v18, v18
	v_mul_f32_e32 v15, v19, v19
	s_nop 0
	v_add_f32_e32 v5, v14, v5
	v_add_f32_e32 v5, v15, v5
	v_lshlrev_b32_e32 v15, 16, v17
	v_and_b32_e32 v14, 0xffff0000, v16
	v_mul_f32_e32 v14, v14, v14
	v_mul_f32_e32 v15, v15, v15
	s_nop 0
	v_add_f32_e32 v5, v14, v5
	v_add_f32_e32 v5, v15, v5
	v_and_b32_e32 v14, 0xffff0000, v17
	v_fmac_f32_e32 v5, v14, v14
	v_lshlrev_b32_e32 v14, 16, v10
	v_fmac_f32_e32 v5, v14, v14
	v_lshlrev_b32_e32 v15, 16, v11
	v_and_b32_e32 v14, 0xffff0000, v10
	v_mul_f32_e32 v14, v14, v14
	v_mul_f32_e32 v15, v15, v15
	s_nop 0
	v_add_f32_e32 v5, v14, v5
	v_add_f32_e32 v5, v15, v5
	v_lshlrev_b32_e32 v15, 16, v12
	v_and_b32_e32 v14, 0xffff0000, v11
	v_mul_f32_e32 v10, v14, v14
	v_mul_f32_e32 v11, v15, v15
	s_nop 0
	v_add_f32_e32 v5, v10, v5
	v_add_f32_e32 v5, v11, v5
	v_lshlrev_b32_e32 v11, 16, v13
	v_and_b32_e32 v10, 0xffff0000, v12
	v_mul_f32_e32 v10, v10, v10
	v_mul_f32_e32 v11, v11, v11
	s_nop 0
	v_add_f32_e32 v5, v10, v5
	v_add_f32_e32 v5, v11, v5
	v_and_b32_e32 v10, 0xffff0000, v13
	v_fmac_f32_e32 v5, v10, v10
	v_lshlrev_b32_e32 v10, 16, v6
	v_fmac_f32_e32 v5, v10, v10
	v_lshlrev_b32_e32 v11, 16, v7
	v_and_b32_e32 v10, 0xffff0000, v6
	v_mul_f32_e32 v10, v10, v10
	v_mul_f32_e32 v11, v11, v11
	s_nop 0
	v_add_f32_e32 v5, v10, v5
	v_add_f32_e32 v5, v11, v5
	v_lshlrev_b32_e32 v11, 16, v8
	v_and_b32_e32 v10, 0xffff0000, v7
	v_mul_f32_e32 v6, v10, v10
	v_mul_f32_e32 v7, v11, v11
	s_nop 0
	v_add_f32_e32 v5, v6, v5
	v_add_f32_e32 v5, v7, v5
	v_lshlrev_b32_e32 v7, 16, v9
	v_and_b32_e32 v6, 0xffff0000, v8
	v_mul_f32_e32 v6, v6, v6
	v_mul_f32_e32 v7, v7, v7
	s_nop 0
	v_add_f32_e32 v5, v6, v5
	v_add_f32_e32 v5, v7, v5
	v_and_b32_e32 v6, 0xffff0000, v9
	v_fmac_f32_e32 v5, v6, v6
	s_cbranch_scc1 .LBB0_1312
	ds_bpermute_b32 v0, v4, v5
	s_and_saveexec_b64 s[2:3], s[90:91]
	s_cbranch_execz .LBB0_1315
	s_waitcnt lgkmcnt(0)
	v_add_f32_e32 v0, v5, v0
	v_fmamk_f32 v0, v0, 0x3b800000, v184
	s_mov_b32 s4, 0x800000
	v_mul_f32_e32 v1, 0x4b800000, v0
	v_cmp_gt_f32_e32 vcc, s4, v0
	s_nop 1
	v_cndmask_b32_e32 v0, v0, v1, vcc
	v_rsq_f32_e32 v0, v0
	s_nop 0
	v_mul_f32_e32 v1, 0x45800000, v0
	v_cndmask_b32_e32 v0, v0, v1, vcc
	ds_write_b32 v3, v0 offset:1024

; DI float bf2f(unsigned v) { return __uint_as_float(v << 16); }
; DI void rinv_prepass(const u16* __restrict__ A, int K, const pg8::StaticOrder& S, LAS float* tab) {
;     ...
;   for (int i = 0; i < 4 && S.next(i, u); ++i) {
;     const u16* pr = A + (size_t)(u.pm * 256 + row) * K + half * (K >> 1);
;     float ss = 0.f;
;     for (int c = 0; c < (K >> 1); c += 8) {
;       u32x4 w = *(const u32x4*)(pr + c);
;       float a;
;       a = bf2f(w.x & 0xffffu); ss += a * a; a = bf2f(w.x >> 16); ss += a * a;
;       a = bf2f(w.y & 0xffffu); ss += a * a; a = bf2f(w.y >> 16); ss += a * a;
;       a = bf2f(w.z & 0xffffu); ss += a * a; a = bf2f(w.z >> 16); ss += a * a;
;       a = bf2f(w.w & 0xffffu); ss += a * a; a = bf2f(w.w >> 16); ss += a * a;
;     }
;     ss += shx(ss, 1, tid & 63);
;     if (!half) tab[i * 256 + row] = rsqrtf(ss / (float)K + EPS);
;   }
.LBB0_1319:
	global_load_dwordx4 v[6:9], v[0:1], off offset:16
	global_load_dwordx4 v[10:13], v[0:1], off
	global_load_dwordx4 v[14:17], v[0:1], off offset:-16
	global_load_dwordx4 v[18:21], v[0:1], off offset:-32
	s_add_i32 s2, s2, 32
	v_lshl_add_u64 v[0:1], v[0:1], 0, 64
	s_cmpk_lt_u32 s2, 0x78
	s_waitcnt vmcnt(0)
	v_lshlrev_b32_e32 v22, 16, v18
	v_fmac_f32_e32 v5, v22, v22
	v_lshlrev_b32_e32 v23, 16, v19
	v_and_b32_e32 v22, 0xffff0000, v18
	v_mul_f32_e32 v22, v22, v22
	v_mul_f32_e32 v23, v23, v23
	s_nop 0
	v_add_f32_e32 v5, v22, v5
	v_add_f32_e32 v5, v23, v5
	v_lshlrev_b32_e32 v23, 16, v20
	v_and_b32_e32 v22, 0xffff0000, v19
	v_mul_f32_e32 v18, v22, v22
	v_mul_f32_e32 v19, v23, v23
	s_nop 0
	v_add_f32_e32 v5, v18, v5
	v_add_f32_e32 v5, v19, v5
	v_lshlrev_b32_e32 v19, 16, v21
	v_and_b32_e32 v18, 0xffff0000, v20
	v_mul_f32_e32 v18, v18, v18
	v_mul_f32_e32 v19, v19, v19
	s_nop 0
	v_add_f32_e32 v5, v18, v5
	v_add_f32_e32 v5, v19, v5
	v_and_b32_e32 v18, 0xffff0000, v21
	v_fmac_f32_e32 v5, v18, v18
	v_lshlrev_b32_e32 v18, 16, v14
	v_fmac_f32_e32 v5, v18, v18
	v_lshlrev_b32_e32 v19, 16, v15
	v_and_b32_e32 v18, 0xffff0000, v14
	v_mul_f32_e32 v18, v18, v18
	v_mul_f32_e32 v19, v19, v19
	s_nop 0
	v_add_f32_e32 v5, v18, v5
	v_add_f32_e32 v5, v19, v5
	v_lshlrev_b32_e32 v19, 16, v16
	v_and_b32_e32 v18, 0xffff0000, v15
	v_mul_f32_e32 v14, v18, v18
	v_mul_f32_e32 v15, v19, v19
	s_nop 0
	v_add_f32_e32 v5, v14, v5
	v_add_f32_e32 v5, v15, v5
	v_lshlrev_b32_e32 v15, 16, v17
	v_and_b32_e32 v14, 0xffff0000, v16
	v_mul_f32_e32 v14, v14, v14
	v_mul_f32_e32 v15, v15, v15
	s_nop 0
	v_add_f32_e32 v5, v14, v5
	v_add_f32_e32 v5, v15, v5
	v_and_b32_e32 v14, 0xffff0000, v17
	v_fmac_f32_e32 v5, v14, v14
	v_lshlrev_b32_e32 v14, 16, v10
	v_fmac_f32_e32 v5, v14, v14
	v_lshlrev_b32_e32 v15, 16, v11
	v_and_b32_e32 v14, 0xffff0000, v10
	v_mul_f32_e32 v14, v14, v14
	v_mul_f32_e32 v15, v15, v15
	s_nop 0
	v_add_f32_e32 v5, v14, v5
	v_add_f32_e32 v5, v15, v5
	v_lshlrev_b32_e32 v15, 16, v12
	v_and_b32_e32 v14, 0xffff0000, v11
	v_mul_f32_e32 v10, v14, v14
	v_mul_f32_e32 v11, v15, v15
	s_nop 0
	v_add_f32_e32 v5, v10, v5
	v_add_f32_e32 v5, v11, v5
	v_lshlrev_b32_e32 v11, 16, v13
	v_and_b32_e32 v10, 0xffff0000, v12
	v_mul_f32_e32 v10, v10, v10
	v_mul_f32_e32 v11, v11, v11
	s_nop 0
	v_add_f32_e32 v5, v10, v5
	v_add_f32_e32 v5, v11, v5
	v_and_b32_e32 v10, 0xffff0000, v13
	v_fmac_f32_e32 v5, v10, v10
	v_lshlrev_b32_e32 v10, 16, v6
	v_fmac_f32_e32 v5, v10, v10
	v_lshlrev_b32_e32 v11, 16, v7
	v_and_b32_e32 v10, 0xffff0000, v6
	v_mul_f32_e32 v10, v10, v10
	v_mul_f32_e32 v11, v11, v11
	s_nop 0
	v_add_f32_e32 v5, v10, v5
	v_add_f32_e32 v5, v11, v5
	v_lshlrev_b32_e32 v11, 16, v8
	v_and_b32_e32 v10, 0xffff0000, v7
	v_mul_f32_e32 v6, v10, v10
	v_mul_f32_e32 v7, v11, v11
	s_nop 0
	v_add_f32_e32 v5, v6, v5
	v_add_f32_e32 v5, v7, v5
	v_lshlrev_b32_e32 v7, 16, v9
	v_and_b32_e32 v6, 0xffff0000, v8
	v_mul_f32_e32 v6, v6, v6
	v_mul_f32_e32 v7, v7, v7
	s_nop 0
	v_add_f32_e32 v5, v6, v5
	v_add_f32_e32 v5, v7, v5
	v_and_b32_e32 v6, 0xffff0000, v9
	v_fmac_f32_e32 v5, v6, v6
	s_cbranch_scc1 .LBB0_1319
	ds_bpermute_b32 v0, v4, v5
	s_and_saveexec_b64 s[2:3], s[90:91]
	s_cbranch_execz .LBB0_1322
	s_waitcnt lgkmcnt(0)
	v_add_f32_e32 v0, v5, v0
	v_fmamk_f32 v0, v0, 0x3b800000, v184
	s_mov_b32 s4, 0x800000
	v_mul_f32_e32 v1, 0x4b800000, v0
	v_cmp_gt_f32_e32 vcc, s4, v0
	s_nop 1
	v_cndmask_b32_e32 v0, v0, v1, vcc
	v_rsq_f32_e32 v0, v0
	s_nop 0
	v_mul_f32_e32 v1, 0x45800000, v0
	v_cndmask_b32_e32 v0, v0, v1, vcc
	ds_write_b32 v3, v0 offset:2048

; DI float bf2f(unsigned v) { return __uint_as_float(v << 16); }
; DI void rinv_prepass(const u16* __restrict__ A, int K, const pg8::StaticOrder& S, LAS float* tab) {
;     ...
;   for (int i = 0; i < 4 && S.next(i, u); ++i) {
;     const u16* pr = A + (size_t)(u.pm * 256 + row) * K + half * (K >> 1);
;     float ss = 0.f;
;     for (int c = 0; c < (K >> 1); c += 8) {
;       u32x4 w = *(const u32x4*)(pr + c);
;       float a;
;       a = bf2f(w.x & 0xffffu); ss += a * a; a = bf2f(w.x >> 16); ss += a * a;
;       a = bf2f(w.y & 0xffffu); ss += a * a; a = bf2f(w.y >> 16); ss += a * a;
;       a = bf2f(w.z & 0xffffu); ss += a * a; a = bf2f(w.z >> 16); ss += a * a;
;       a = bf2f(w.w & 0xffffu); ss += a * a; a = bf2f(w.w >> 16); ss += a * a;
;     }
;     ss += shx(ss, 1, tid & 63);
;     if (!half) tab[i * 256 + row] = rsqrtf(ss / (float)K + EPS);
;   }
.LBB0_1326:
	global_load_dwordx4 v[6:9], v[0:1], off offset:16
	global_load_dwordx4 v[10:13], v[0:1], off
	global_load_dwordx4 v[14:17], v[0:1], off offset:-16
	global_load_dwordx4 v[18:21], v[0:1], off offset:-32
	s_add_i32 s2, s2, 32
	v_lshl_add_u64 v[0:1], v[0:1], 0, 64
	s_cmpk_lt_u32 s2, 0x78
	s_waitcnt vmcnt(0)
	v_lshlrev_b32_e32 v5, 16, v18
	v_lshlrev_b32_e32 v23, 16, v19
	v_and_b32_e32 v22, 0xffff0000, v18
	v_fmac_f32_e32 v2, v5, v5
	v_mul_f32_e32 v22, v22, v22
	v_mul_f32_e32 v23, v23, v23
	v_and_b32_e32 v5, 0xffff0000, v21
	v_add_f32_e32 v2, v22, v2
	v_add_f32_e32 v2, v23, v2
	v_lshlrev_b32_e32 v23, 16, v20
	v_and_b32_e32 v22, 0xffff0000, v19
	v_mul_f32_e32 v18, v22, v22
	v_mul_f32_e32 v19, v23, v23
	s_nop 0
	v_add_f32_e32 v2, v18, v2
	v_add_f32_e32 v2, v19, v2
	v_lshlrev_b32_e32 v19, 16, v21
	v_and_b32_e32 v18, 0xffff0000, v20
	v_mul_f32_e32 v18, v18, v18
	v_mul_f32_e32 v19, v19, v19
	s_nop 0
	v_add_f32_e32 v2, v18, v2
	v_add_f32_e32 v2, v19, v2
	v_fmac_f32_e32 v2, v5, v5
	v_lshlrev_b32_e32 v5, 16, v14
	v_lshlrev_b32_e32 v19, 16, v15
	v_and_b32_e32 v18, 0xffff0000, v14
	v_fmac_f32_e32 v2, v5, v5
	v_mul_f32_e32 v18, v18, v18
	v_mul_f32_e32 v19, v19, v19
	v_and_b32_e32 v5, 0xffff0000, v17
	v_add_f32_e32 v2, v18, v2
	v_add_f32_e32 v2, v19, v2
	v_lshlrev_b32_e32 v19, 16, v16
	v_and_b32_e32 v18, 0xffff0000, v15
	v_mul_f32_e32 v14, v18, v18
	v_mul_f32_e32 v15, v19, v19
	s_nop 0
	v_add_f32_e32 v2, v14, v2
	v_add_f32_e32 v2, v15, v2
	v_lshlrev_b32_e32 v15, 16, v17
	v_and_b32_e32 v14, 0xffff0000, v16
	v_mul_f32_e32 v14, v14, v14
	v_mul_f32_e32 v15, v15, v15
	s_nop 0
	v_add_f32_e32 v2, v14, v2
	v_add_f32_e32 v2, v15, v2
	v_fmac_f32_e32 v2, v5, v5
	v_lshlrev_b32_e32 v5, 16, v10
	v_lshlrev_b32_e32 v15, 16, v11
	v_and_b32_e32 v14, 0xffff0000, v10
	v_fmac_f32_e32 v2, v5, v5
	v_mul_f32_e32 v14, v14, v14
	v_mul_f32_e32 v15, v15, v15
	v_and_b32_e32 v5, 0xffff0000, v13
	v_add_f32_e32 v2, v14, v2
	v_add_f32_e32 v2, v15, v2
	v_lshlrev_b32_e32 v15, 16, v12
	v_and_b32_e32 v14, 0xffff0000, v11
	v_mul_f32_e32 v10, v14, v14
	v_mul_f32_e32 v11, v15, v15
	s_nop 0
	v_add_f32_e32 v2, v10, v2
	v_add_f32_e32 v2, v11, v2
	v_lshlrev_b32_e32 v11, 16, v13
	v_and_b32_e32 v10, 0xffff0000, v12
	v_mul_f32_e32 v10, v10, v10
	v_mul_f32_e32 v11, v11, v11
	s_nop 0
	v_add_f32_e32 v2, v10, v2
	v_add_f32_e32 v2, v11, v2
	v_fmac_f32_e32 v2, v5, v5
	v_lshlrev_b32_e32 v5, 16, v6
	v_lshlrev_b32_e32 v11, 16, v7
	v_and_b32_e32 v10, 0xffff0000, v6
	v_fmac_f32_e32 v2, v5, v5
	v_mul_f32_e32 v10, v10, v10
	v_mul_f32_e32 v11, v11, v11
	v_and_b32_e32 v5, 0xffff0000, v9
	v_add_f32_e32 v2, v10, v2
	v_add_f32_e32 v2, v11, v2
	v_lshlrev_b32_e32 v11, 16, v8
	v_and_b32_e32 v10, 0xffff0000, v7
	v_mul_f32_e32 v6, v10, v10
	v_mul_f32_e32 v7, v11, v11
	s_nop 0
	v_add_f32_e32 v2, v6, v2
	v_add_f32_e32 v2, v7, v2
	v_lshlrev_b32_e32 v7, 16, v9
	v_and_b32_e32 v6, 0xffff0000, v8
	v_mul_f32_e32 v6, v6, v6
	v_mul_f32_e32 v7, v7, v7
	s_nop 0
	v_add_f32_e32 v2, v6, v2
	v_add_f32_e32 v2, v7, v2
	v_fmac_f32_e32 v2, v5, v5
	s_cbranch_scc1 .LBB0_1326
	ds_bpermute_b32 v0, v4, v2
	s_and_saveexec_b64 s[2:3], s[90:91]
	s_cbranch_execz .LBB0_1329
	s_waitcnt lgkmcnt(0)
	v_add_f32_e32 v0, v2, v0
	v_fmamk_f32 v0, v0, 0x3b800000, v184
	s_mov_b32 s4, 0x800000
	v_mul_f32_e32 v1, 0x4b800000, v0
	v_cmp_gt_f32_e32 vcc, s4, v0
	s_nop 1
	v_cndmask_b32_e32 v0, v0, v1, vcc
	v_rsq_f32_e32 v0, v0
	s_nop 0
	v_mul_f32_e32 v1, 0x45800000, v0
	v_cndmask_b32_e32 v0, v0, v1, vcc
	ds_write_b32 v3, v0 offset:3072

; #define PG8_STAGE(bufoff, gbase, voff) do { _Pragma("unroll") for (int _i = 0; _i < 2; ++_i) \
;     __builtin_amdgcn_global_load_lds((const unsigned*)((const char*)(gbase) + (voff)[_i]), (LAS unsigned*)(lds + (bufoff) + ldsw + _i * 8192), 16, 0, 0); } while (0)
; #define PG8_LDA(dst, b, h) do { _Pragma("unroll") for (int m = 0; m < 4; ++m) _Pragma("unroll") for (int k = 0; k < 2; ++k) dst[m][k] = *(const LAS bf16x8*)(lds + PG8_SA(b, h) + aoff + m * 2048 + k * 1024); } while (0)
; #define PG8_LDB(dst, b, h) do { _Pragma("unroll") for (int n = 0; n < 2; ++n) _Pragma("unroll") for (int k = 0; k < 2; ++k) dst[n][k] = *(const LAS bf16x8*)(lds + PG8_SB(b, h) + boff + n * 2048 + k * 1024); } while (0)
; #define PG8_MMA(ai, bj, At, Bt) do { __builtin_amdgcn_s_setprio(1); _Pragma("unroll") for (int m = 0; m < 4; ++m) _Pragma("unroll") for (int n = 0; n < 2; ++n) _Pragma("unroll") for (int k = 0; k < 2; ++k) \
;     acc[ai][bj][m][n] = __builtin_amdgcn_mfma_f32_16x16x32_bf16(Bt[n][k], At[m][k], acc[ai][bj][m][n], 0, 0, 0); __builtin_amdgcn_s_setprio(0); } while (0)
; #define PG8_WAIT_V(n) asm volatile("s_waitcnt vmcnt(" #n ")" ::: "memory")
; template <class Epi, class Sched>
; DI void gemm_phase(LAS unsigned char* lds, const Gemm g, const Sched& S, const Epi& E) {
;     ...
;     for (int t = 0; t < nt; t += 2) {
;       const bool last = (t == nt - 2);
;       const char* a1 = cA + (size_t)(t + 1) * kstep;
;       const char* a2 = last ? nA : cA + (size_t)(t + 2) * kstep; const char* b2 = last ? nB : cB + (size_t)(t + 2) * kstep;
;       const char* a3 = a2 + kstep; const char* b3 = b2 + kstep;
;       PG8_LDB(B0, 0, 0); PG8_SCHED; PG8_LDA(At, 0, 0); PG8_STAGE(PG8_SA(1, 1), a1 + hstep, voffA);
;       PG8_WAIT_L(8); PG8_BAR; PG8_WAIT_L(0); PG8_MMA(0, 0, At, B0); PG8_BAR; PG8_SCHED;
;       PG8_LDB(B1, 0, 1); PG8_STAGE(PG8_SB(0, 0), b2, voffB);
;       PG8_BAR; PG8_WAIT_L(0); PG8_MMA(0, 1, At, B1); PG8_BAR;
;       PG8_LDA(At, 0, 1); PG8_STAGE(PG8_SA(0, 0), a2, voffA);
;       PG8_BAR; PG8_WAIT_L(0); PG8_MMA(1, 0, At, B0); PG8_BAR; PG8_SCHED;
;       PG8_STAGE(PG8_SB(0, 1), b2 + hstep, voffB);
;       PG8_WAIT_V(6); PG8_BAR; PG8_MMA(1, 1, At, B1); PG8_BAR;
;       PG8_LDB(B0, 1, 0); PG8_SCHED; PG8_LDA(At, 1, 0); PG8_STAGE(PG8_SA(0, 1), a2 + hstep, voffA);
;       PG8_WAIT_L(8); PG8_BAR; PG8_WAIT_L(0); PG8_MMA(0, 0, At, B0); PG8_BAR; PG8_SCHED;
.LBB0_1346:
	s_add_u32 s48, s28, s40
	s_addc_u32 s49, s29, s41
	s_add_u32 s44, s48, 0x100
	s_addc_u32 s45, s49, 0
	s_and_b64 s[42:43], s[36:37], exec
	s_cselect_b32 s45, s15, s45
	s_cselect_b32 s44, s21, s44
	s_add_u32 s40, s22, s40
	s_addc_u32 s41, s23, s41
	s_add_u32 s40, s40, 0x100
	s_addc_u32 s41, s41, 0
	s_add_i32 s70, 0, 0x10000
	s_and_b64 s[36:37], s[36:37], exec
	s_cselect_b32 s47, s13, s41
	s_cselect_b32 s46, s24, s40
	s_add_u32 s48, s48, 0x10080
	s_addc_u32 s49, s49, 0
	s_add_i32 s74, s70, s51
	s_add_i32 m0, s56, 0xc000
	s_add_i32 s75, s56, 0xe000
	s_add_i32 s73, 0, 0x14000
	s_add_i32 s72, s74, 0x2000
	s_add_u32 s42, s46, 0x10000
	s_addc_u32 s43, s47, 0
	s_add_i32 s69, s73, s51
	ds_read_b128 v[136:139], v220
	ds_read_b128 v[146:149], v220 offset:1024
	ds_read_b128 v[150:153], v220 offset:2048
	ds_read_b128 v[154:157], v220 offset:3072
	s_add_i32 s68, s69, 0x2000
	s_add_i32 s67, 0, 0x18000
	s_add_u32 s40, s44, 0x10000
	s_addc_u32 s41, s45, 0
	s_add_i32 s66, s67, s51
	s_add_i32 s65, 0, 0x1c000
	s_add_i32 s64, s66, 0x2000
	s_add_u32 s36, s46, 0x10080
	s_addc_u32 s37, s47, 0
	s_add_i32 s71, s65, s51
	s_add_i32 s70, s71, 0x2000
	ds_read_b128 v[158:161], v143
	ds_read_b128 v[162:165], v143 offset:1024
	ds_read_b128 v[166:169], v143 offset:2048
	ds_read_b128 v[170:173], v143 offset:3072
	ds_read_b128 v[174:177], v143 offset:4096
	ds_read_b128 v[178:181], v143 offset:5120
	ds_read_b128 v[196:199], v143 offset:6144
	ds_read_b128 v[200:203], v143 offset:7168
	global_load_lds_dwordx4 v128, s[48:49]
	s_mov_b32 m0, s75
	s_nop 0
	global_load_lds_dwordx4 v132, s[48:49]
	s_waitcnt lgkmcnt(8)
	s_barrier
	s_waitcnt lgkmcnt(0)
	v_mfma_f32_16x16x32_bf16 v[124:127], v[136:139], v[158:161], v[124:127]
	v_mfma_f32_16x16x32_bf16 v[120:123], v[150:153], v[158:161], v[120:123]
	v_mfma_f32_16x16x32_bf16 v[108:111], v[136:139], v[166:169], v[108:111]
	v_mfma_f32_16x16x32_bf16 v[104:107], v[150:153], v[166:169], v[104:107]
	v_mfma_f32_16x16x32_bf16 v[92:95], v[136:139], v[174:177], v[92:95]
	v_mfma_f32_16x16x32_bf16 v[88:91], v[150:153], v[174:177], v[88:91]
	v_mfma_f32_16x16x32_bf16 v[76:79], v[136:139], v[196:199], v[76:79]
	v_mfma_f32_16x16x32_bf16 v[72:75], v[150:153], v[196:199], v[72:75]
	v_mfma_f32_16x16x32_bf16 v[124:127], v[146:149], v[162:165], v[124:127]
	v_mfma_f32_16x16x32_bf16 v[120:123], v[154:157], v[162:165], v[120:123]
	v_mfma_f32_16x16x32_bf16 v[108:111], v[146:149], v[170:173], v[108:111]
	v_mfma_f32_16x16x32_bf16 v[104:107], v[154:157], v[170:173], v[104:107]
	v_mfma_f32_16x16x32_bf16 v[92:95], v[146:149], v[178:181], v[92:95]
	v_mfma_f32_16x16x32_bf16 v[88:91], v[154:157], v[178:181], v[88:91]
	v_mfma_f32_16x16x32_bf16 v[76:79], v[146:149], v[200:203], v[76:79]
	v_mfma_f32_16x16x32_bf16 v[72:75], v[154:157], v[200:203], v[72:75]
	s_barrier
	s_mov_b32 m0, s74
	ds_read_b128 v[204:207], v221
	ds_read_b128 v[208:211], v221 offset:1024
	ds_read_b128 v[212:215], v221 offset:2048
	ds_read_b128 v[216:219], v221 offset:3072
	s_add_u32 vcc_lo, s46, s0
	s_addc_u32 vcc_hi, s47, s1
	global_load_lds_dwordx4 v130, s[46:47]
	s_mov_b32 m0, s72
	s_nop 0
	global_load_lds_dwordx4 v134, s[46:47]
	s_barrier
	s_waitcnt lgkmcnt(0)
	v_mfma_f32_16x16x32_bf16 v[116:119], v[204:207], v[158:161], v[116:119]
	v_mfma_f32_16x16x32_bf16 v[112:115], v[212:215], v[158:161], v[112:115]
	v_mfma_f32_16x16x32_bf16 v[100:103], v[204:207], v[166:169], v[100:103]
	v_mfma_f32_16x16x32_bf16 v[96:99], v[212:215], v[166:169], v[96:99]
	v_mfma_f32_16x16x32_bf16 v[84:87], v[204:207], v[174:177], v[84:87]
	v_mfma_f32_16x16x32_bf16 v[80:83], v[212:215], v[174:177], v[80:83]
	v_mfma_f32_16x16x32_bf16 v[68:71], v[204:207], v[196:199], v[68:71]
	v_mfma_f32_16x16x32_bf16 v[64:67], v[212:215], v[196:199], v[64:67]
	v_mfma_f32_16x16x32_bf16 v[116:119], v[208:211], v[162:165], v[116:119]
	v_mfma_f32_16x16x32_bf16 v[112:115], v[216:219], v[162:165], v[112:115]
	v_mfma_f32_16x16x32_bf16 v[100:103], v[208:211], v[170:173], v[100:103]
	v_mfma_f32_16x16x32_bf16 v[96:99], v[216:219], v[170:173], v[96:99]
	v_mfma_f32_16x16x32_bf16 v[84:87], v[208:211], v[178:181], v[84:87]
	v_mfma_f32_16x16x32_bf16 v[80:83], v[216:219], v[178:181], v[80:83]
	v_mfma_f32_16x16x32_bf16 v[68:71], v[208:211], v[200:203], v[68:71]
	v_mfma_f32_16x16x32_bf16 v[64:67], v[216:219], v[200:203], v[64:67]
	s_mov_b32 m0, s56
	s_add_u32 s100, s44, s0
	s_addc_u32 s101, s45, s1
	s_barrier
	ds_read_b128 v[158:161], v143 offset:16384
	ds_read_b128 v[162:165], v143 offset:17408
	ds_read_b128 v[166:169], v143 offset:18432
	ds_read_b128 v[170:173], v143 offset:19456
	ds_read_b128 v[174:177], v143 offset:20480
	ds_read_b128 v[178:181], v143 offset:21504
	ds_read_b128 v[196:199], v143 offset:22528
	ds_read_b128 v[200:203], v143 offset:23552
	global_load_lds_dwordx4 v128, s[44:45]
	s_mov_b32 m0, s57
	s_nop 0
	global_load_lds_dwordx4 v132, s[44:45]
	s_barrier
	s_waitcnt lgkmcnt(0)
	v_mfma_f32_16x16x32_bf16 v[60:63], v[136:139], v[158:161], v[60:63]
	v_mfma_f32_16x16x32_bf16 v[56:59], v[150:153], v[158:161], v[56:59]
	v_mfma_f32_16x16x32_bf16 v[44:47], v[136:139], v[166:169], v[44:47]
	v_mfma_f32_16x16x32_bf16 v[40:43], v[150:153], v[166:169], v[40:43]
	v_mfma_f32_16x16x32_bf16 v[28:31], v[136:139], v[174:177], v[28:31]
	v_mfma_f32_16x16x32_bf16 v[24:27], v[150:153], v[174:177], v[24:27]
	v_mfma_f32_16x16x32_bf16 v[12:15], v[136:139], v[196:199], v[12:15]
	v_mfma_f32_16x16x32_bf16 v[8:11], v[150:153], v[196:199], v[8:11]
	v_mfma_f32_16x16x32_bf16 v[60:63], v[146:149], v[162:165], v[60:63]
	v_mfma_f32_16x16x32_bf16 v[56:59], v[154:157], v[162:165], v[56:59]
	v_mfma_f32_16x16x32_bf16 v[44:47], v[146:149], v[170:173], v[44:47]
	v_mfma_f32_16x16x32_bf16 v[40:43], v[154:157], v[170:173], v[40:43]
	v_mfma_f32_16x16x32_bf16 v[28:31], v[146:149], v[178:181], v[28:31]
	v_mfma_f32_16x16x32_bf16 v[24:27], v[154:157], v[178:181], v[24:27]
	v_mfma_f32_16x16x32_bf16 v[12:15], v[146:149], v[200:203], v[12:15]
	v_mfma_f32_16x16x32_bf16 v[8:11], v[154:157], v[200:203], v[8:11]
	s_barrier
; #define PG8_STAGE(bufoff, gbase, voff) do { _Pragma("unroll") for (int _i = 0; _i < 2; ++_i) \
;     __builtin_amdgcn_global_load_lds((const unsigned*)((const char*)(gbase) + (voff)[_i]), (LAS unsigned*)(lds + (bufoff) + ldsw + _i * 8192), 16, 0, 0); } while (0)
; #define PG8_LDA(dst, b, h) do { _Pragma("unroll") for (int m = 0; m < 4; ++m) _Pragma("unroll") for (int k = 0; k < 2; ++k) dst[m][k] = *(const LAS bf16x8*)(lds + PG8_SA(b, h) + aoff + m * 2048 + k * 1024); } while (0)
; #define PG8_LDB(dst, b, h) do { _Pragma("unroll") for (int n = 0; n < 2; ++n) _Pragma("unroll") for (int k = 0; k < 2; ++k) dst[n][k] = *(const LAS bf16x8*)(lds + PG8_SB(b, h) + boff + n * 2048 + k * 1024); } while (0)
; #define PG8_MMA(ai, bj, At, Bt) do { __builtin_amdgcn_s_setprio(1); _Pragma("unroll") for (int m = 0; m < 4; ++m) _Pragma("unroll") for (int n = 0; n < 2; ++n) _Pragma("unroll") for (int k = 0; k < 2; ++k) \
;     acc[ai][bj][m][n] = __builtin_amdgcn_mfma_f32_16x16x32_bf16(Bt[n][k], At[m][k], acc[ai][bj][m][n], 0, 0, 0); __builtin_amdgcn_s_setprio(0); } while (0)
; #define PG8_WAIT_V(n) asm volatile("s_waitcnt vmcnt(" #n ")" ::: "memory")
; #define PG8_WAIT_L(n) asm volatile("s_waitcnt lgkmcnt(" #n ")" ::: "memory")
; #define PG8_BAR __builtin_amdgcn_s_barrier()
; #define PG8_SCHED __builtin_amdgcn_sched_barrier(0)
; template <class Epi, class Sched>
; DI void gemm_phase(LAS unsigned char* lds, const Gemm g, const Sched& S, const Epi& E) {
;     ...
;       PG8_WAIT_V(6); PG8_BAR; PG8_MMA(1, 1, At, B1); PG8_BAR;
;       PG8_LDB(B0, 1, 0); PG8_SCHED; PG8_LDA(At, 1, 0); PG8_STAGE(PG8_SA(0, 1), a2 + hstep, voffA);
;       PG8_WAIT_L(8); PG8_BAR; PG8_WAIT_L(0); PG8_MMA(0, 0, At, B0); PG8_BAR; PG8_SCHED;
;       PG8_LDB(B1, 1, 1); PG8_STAGE(PG8_SB(1, 0), b3, voffB);
;       PG8_BAR; PG8_WAIT_L(0); PG8_MMA(0, 1, At, B1); PG8_BAR;
	s_mov_b32 m0, s69
	s_nop 0
	global_load_lds_dwordx4 v130, s[42:43]
	s_mov_b32 m0, s68
	s_nop 0
	global_load_lds_dwordx4 v134, s[42:43]
	s_waitcnt vmcnt(6)
	s_barrier
	v_mfma_f32_16x16x32_bf16 v[52:55], v[204:207], v[158:161], v[52:55]
	v_mfma_f32_16x16x32_bf16 v[48:51], v[212:215], v[158:161], v[48:51]
	v_mfma_f32_16x16x32_bf16 v[36:39], v[204:207], v[166:169], v[36:39]
	v_mfma_f32_16x16x32_bf16 v[32:35], v[212:215], v[166:169], v[32:35]
	v_mfma_f32_16x16x32_bf16 v[20:23], v[204:207], v[174:177], v[20:23]
	v_mfma_f32_16x16x32_bf16 v[16:19], v[212:215], v[174:177], v[16:19]
	v_mfma_f32_16x16x32_bf16 v[4:7], v[204:207], v[196:199], v[4:7]
	v_mfma_f32_16x16x32_bf16 v[0:3], v[212:215], v[196:199], v[0:3]
	v_mfma_f32_16x16x32_bf16 v[52:55], v[208:211], v[162:165], v[52:55]
	v_mfma_f32_16x16x32_bf16 v[48:51], v[216:219], v[162:165], v[48:51]
	v_mfma_f32_16x16x32_bf16 v[36:39], v[208:211], v[170:173], v[36:39]
	v_mfma_f32_16x16x32_bf16 v[32:35], v[216:219], v[170:173], v[32:35]
	v_mfma_f32_16x16x32_bf16 v[20:23], v[208:211], v[178:181], v[20:23]
	v_mfma_f32_16x16x32_bf16 v[16:19], v[216:219], v[178:181], v[16:19]
	v_mfma_f32_16x16x32_bf16 v[4:7], v[208:211], v[200:203], v[4:7]
	v_mfma_f32_16x16x32_bf16 v[0:3], v[216:219], v[200:203], v[0:3]
	s_barrier
	ds_read_b128 v[136:139], v222
	ds_read_b128 v[146:149], v222 offset:1024
	ds_read_b128 v[150:153], v222 offset:2048
	ds_read_b128 v[154:157], v222 offset:3072
	s_mov_b32 m0, s58
	ds_read_b128 v[158:161], v143 offset:32768
	ds_read_b128 v[162:165], v143 offset:33792
	ds_read_b128 v[166:169], v143 offset:34816
	ds_read_b128 v[170:173], v143 offset:35840
	ds_read_b128 v[174:177], v143 offset:36864
	ds_read_b128 v[178:181], v143 offset:37888
	ds_read_b128 v[196:199], v143 offset:38912
	ds_read_b128 v[200:203], v143 offset:39936
	global_load_lds_dwordx4 v128, s[40:41]
	s_mov_b32 m0, s59
	s_nop 0
	global_load_lds_dwordx4 v132, s[40:41]
	s_waitcnt lgkmcnt(8)
	s_barrier
	s_waitcnt lgkmcnt(0)
	v_mfma_f32_16x16x32_bf16 v[124:127], v[136:139], v[158:161], v[124:127]
	v_mfma_f32_16x16x32_bf16 v[120:123], v[150:153], v[158:161], v[120:123]
	v_mfma_f32_16x16x32_bf16 v[108:111], v[136:139], v[166:169], v[108:111]
	v_mfma_f32_16x16x32_bf16 v[104:107], v[150:153], v[166:169], v[104:107]
	v_mfma_f32_16x16x32_bf16 v[92:95], v[136:139], v[174:177], v[92:95]
	v_mfma_f32_16x16x32_bf16 v[88:91], v[150:153], v[174:177], v[88:91]
	v_mfma_f32_16x16x32_bf16 v[76:79], v[136:139], v[196:199], v[76:79]
	v_mfma_f32_16x16x32_bf16 v[72:75], v[150:153], v[196:199], v[72:75]
	v_mfma_f32_16x16x32_bf16 v[124:127], v[146:149], v[162:165], v[124:127]
	v_mfma_f32_16x16x32_bf16 v[120:123], v[154:157], v[162:165], v[120:123]
	v_mfma_f32_16x16x32_bf16 v[108:111], v[146:149], v[170:173], v[108:111]
	v_mfma_f32_16x16x32_bf16 v[104:107], v[154:157], v[170:173], v[104:107]
	v_mfma_f32_16x16x32_bf16 v[92:95], v[146:149], v[178:181], v[92:95]
	v_mfma_f32_16x16x32_bf16 v[88:91], v[154:157], v[178:181], v[88:91]
	v_mfma_f32_16x16x32_bf16 v[76:79], v[146:149], v[200:203], v[76:79]
	v_mfma_f32_16x16x32_bf16 v[72:75], v[154:157], v[200:203], v[72:75]
	s_barrier
	s_mov_b32 m0, s66
	ds_read_b128 v[204:207], v223
	ds_read_b128 v[208:211], v223 offset:1024
	ds_read_b128 v[212:215], v223 offset:2048
	ds_read_b128 v[216:219], v223 offset:3072
	global_load_lds_dwordx4 v130, vcc
	s_mov_b32 m0, s64
	s_nop 0
	global_load_lds_dwordx4 v134, vcc
	s_barrier
	s_waitcnt lgkmcnt(0)
	v_mfma_f32_16x16x32_bf16 v[116:119], v[204:207], v[158:161], v[116:119]
	v_mfma_f32_16x16x32_bf16 v[112:115], v[212:215], v[158:161], v[112:115]
	v_mfma_f32_16x16x32_bf16 v[100:103], v[204:207], v[166:169], v[100:103]
	v_mfma_f32_16x16x32_bf16 v[96:99], v[212:215], v[166:169], v[96:99]
	v_mfma_f32_16x16x32_bf16 v[84:87], v[204:207], v[174:177], v[84:87]
	v_mfma_f32_16x16x32_bf16 v[80:83], v[212:215], v[174:177], v[80:83]
	v_mfma_f32_16x16x32_bf16 v[68:71], v[204:207], v[196:199], v[68:71]
	v_mfma_f32_16x16x32_bf16 v[64:67], v[212:215], v[196:199], v[64:67]
	v_mfma_f32_16x16x32_bf16 v[116:119], v[208:211], v[162:165], v[116:119]
	v_mfma_f32_16x16x32_bf16 v[112:115], v[216:219], v[162:165], v[112:115]
	v_mfma_f32_16x16x32_bf16 v[100:103], v[208:211], v[170:173], v[100:103]
	v_mfma_f32_16x16x32_bf16 v[96:99], v[216:219], v[170:173], v[96:99]
	v_mfma_f32_16x16x32_bf16 v[84:87], v[208:211], v[178:181], v[84:87]
	v_mfma_f32_16x16x32_bf16 v[80:83], v[216:219], v[178:181], v[80:83]
	v_mfma_f32_16x16x32_bf16 v[68:71], v[208:211], v[200:203], v[68:71]
	v_mfma_f32_16x16x32_bf16 v[64:67], v[216:219], v[200:203], v[64:67]
	s_mov_b32 m0, s62
	s_barrier
; #define PG8_STAGE(bufoff, gbase, voff) do { _Pragma("unroll") for (int _i = 0; _i < 2; ++_i) \
;     __builtin_amdgcn_global_load_lds((const unsigned*)((const char*)(gbase) + (voff)[_i]), (LAS unsigned*)(lds + (bufoff) + ldsw + _i * 8192), 16, 0, 0); } while (0)
; #define PG8_LDA(dst, b, h) do { _Pragma("unroll") for (int m = 0; m < 4; ++m) _Pragma("unroll") for (int k = 0; k < 2; ++k) dst[m][k] = *(const LAS bf16x8*)(lds + PG8_SA(b, h) + aoff + m * 2048 + k * 1024); } while (0)
; #define PG8_MMA(ai, bj, At, Bt) do { __builtin_amdgcn_s_setprio(1); _Pragma("unroll") for (int m = 0; m < 4; ++m) _Pragma("unroll") for (int n = 0; n < 2; ++n) _Pragma("unroll") for (int k = 0; k < 2; ++k) \
;     acc[ai][bj][m][n] = __builtin_amdgcn_mfma_f32_16x16x32_bf16(Bt[n][k], At[m][k], acc[ai][bj][m][n], 0, 0, 0); __builtin_amdgcn_s_setprio(0); } while (0)
; #define PG8_WAIT_V(n) asm volatile("s_waitcnt vmcnt(" #n ")" ::: "memory")
; #define PG8_WAIT_L(n) asm volatile("s_waitcnt lgkmcnt(" #n ")" ::: "memory")
; #define PG8_BAR __builtin_amdgcn_s_barrier()
; #define PG8_SCHED __builtin_amdgcn_sched_barrier(0)
; template <class Epi, class Sched>
; DI void gemm_phase(LAS unsigned char* lds, const Gemm g, const Sched& S, const Epi& E) {
;     ...
;       PG8_LDA(At, 1, 1); PG8_STAGE(PG8_SA(1, 0), a3, voffA);
;       PG8_BAR; PG8_WAIT_L(0); PG8_MMA(1, 0, At, B0); PG8_BAR; PG8_SCHED;
;       PG8_STAGE(PG8_SB(1, 1), b3 + hstep, voffB);
;       PG8_WAIT_V(6); PG8_BAR; PG8_MMA(1, 1, At, B1); PG8_BAR;
;     }
;     E(acc, cur, wr, wc, fr, fq);
;   DI void operator()(const f32x4 (&acc)[2][2][4][2], const pg8::Unit& u, int wr, int wc, int fr_, int fq_) const {
;     ...
;             } else if (EPI == EPI_UKV) {
;               if (n == 0) {
;                 const int gb = u.pn * 256 + bj * 128 + wc * 32;
;                 const int hd = gb >> 7, within = (gb & 127) + 8 * fq;
;                 const f32x4 v1 = acc[ai][bj][m][1];
;                 if (within < 64) st_bf8((u16*)(big + E_KNOPE) + (size_t)token * 512 + hd * 64 + within, v, v1, rinv);
;                 else st_bf8((u16*)(big + E_VMLAT) + (size_t)token * 512 + hd * 64 + (within - 64), v, v1, rinv);
;               }
	ds_read_b128 v[158:161], v143 offset:49152
	ds_read_b128 v[162:165], v143 offset:50176
	ds_read_b128 v[166:169], v143 offset:51200
	ds_read_b128 v[170:173], v143 offset:52224
	ds_read_b128 v[174:177], v143 offset:53248
	ds_read_b128 v[178:181], v143 offset:54272
	ds_read_b128 v[196:199], v143 offset:55296
	ds_read_b128 v[200:203], v143 offset:56320
	global_load_lds_dwordx4 v128, s[100:101]
	s_mov_b32 m0, s63
	s_nop 0
	global_load_lds_dwordx4 v132, s[100:101]
	s_barrier
	s_waitcnt lgkmcnt(0)
	v_mfma_f32_16x16x32_bf16 v[60:63], v[136:139], v[158:161], v[60:63]
	v_mfma_f32_16x16x32_bf16 v[56:59], v[150:153], v[158:161], v[56:59]
	v_mfma_f32_16x16x32_bf16 v[44:47], v[136:139], v[166:169], v[44:47]
	v_mfma_f32_16x16x32_bf16 v[40:43], v[150:153], v[166:169], v[40:43]
	v_mfma_f32_16x16x32_bf16 v[28:31], v[136:139], v[174:177], v[28:31]
	v_mfma_f32_16x16x32_bf16 v[24:27], v[150:153], v[174:177], v[24:27]
	v_mfma_f32_16x16x32_bf16 v[12:15], v[136:139], v[196:199], v[12:15]
	v_mfma_f32_16x16x32_bf16 v[8:11], v[150:153], v[196:199], v[8:11]
	v_mfma_f32_16x16x32_bf16 v[60:63], v[146:149], v[162:165], v[60:63]
	v_mfma_f32_16x16x32_bf16 v[56:59], v[154:157], v[162:165], v[56:59]
	v_mfma_f32_16x16x32_bf16 v[44:47], v[146:149], v[170:173], v[44:47]
	v_mfma_f32_16x16x32_bf16 v[40:43], v[154:157], v[170:173], v[40:43]
	v_mfma_f32_16x16x32_bf16 v[28:31], v[146:149], v[178:181], v[28:31]
	v_mfma_f32_16x16x32_bf16 v[24:27], v[154:157], v[178:181], v[24:27]
	v_mfma_f32_16x16x32_bf16 v[12:15], v[146:149], v[200:203], v[12:15]
	v_mfma_f32_16x16x32_bf16 v[8:11], v[154:157], v[200:203], v[8:11]
	s_barrier
	s_mov_b32 m0, s71
	s_nop 0
	global_load_lds_dwordx4 v130, s[36:37]
	s_mov_b32 m0, s70
	s_nop 0
	global_load_lds_dwordx4 v134, s[36:37]
	s_waitcnt vmcnt(6)
	s_barrier
	v_mfma_f32_16x16x32_bf16 v[52:55], v[204:207], v[158:161], v[52:55]
	v_mfma_f32_16x16x32_bf16 v[48:51], v[212:215], v[158:161], v[48:51]
	v_mfma_f32_16x16x32_bf16 v[36:39], v[204:207], v[166:169], v[36:39]
	v_mfma_f32_16x16x32_bf16 v[32:35], v[212:215], v[166:169], v[32:35]
	v_mfma_f32_16x16x32_bf16 v[20:23], v[204:207], v[174:177], v[20:23]
	v_mfma_f32_16x16x32_bf16 v[16:19], v[212:215], v[174:177], v[16:19]
	v_mfma_f32_16x16x32_bf16 v[4:7], v[204:207], v[196:199], v[4:7]
	v_mfma_f32_16x16x32_bf16 v[0:3], v[212:215], v[196:199], v[0:3]
	v_mfma_f32_16x16x32_bf16 v[52:55], v[208:211], v[162:165], v[52:55]
	v_mfma_f32_16x16x32_bf16 v[48:51], v[216:219], v[162:165], v[48:51]
	v_mfma_f32_16x16x32_bf16 v[36:39], v[208:211], v[170:173], v[36:39]
	v_mfma_f32_16x16x32_bf16 v[32:35], v[216:219], v[170:173], v[32:35]
	v_mfma_f32_16x16x32_bf16 v[20:23], v[208:211], v[178:181], v[20:23]
	v_mfma_f32_16x16x32_bf16 v[16:19], v[216:219], v[178:181], v[16:19]
	v_mfma_f32_16x16x32_bf16 v[4:7], v[208:211], v[200:203], v[4:7]
	v_mfma_f32_16x16x32_bf16 v[0:3], v[216:219], v[200:203], v[0:3]
	s_andn2_b64 vcc, exec, s[34:35]
	s_mov_b64 s[36:37], -1
	s_mov_b64 s[34:35], 0
	s_mov_b64 s[40:41], 0x100
	s_barrier
	s_cbranch_vccz .LBB0_1346
	v_mov_b32_e32 v136, v182
	s_lshl_b32 s3, s3, 10
	s_add_i32 s3, s3, 0
	v_and_or_b32 v147, v136, 15, s60
	v_lshl_add_u32 v137, v147, 2, s3
	v_add_u32_e32 v146, 0x20000, v137
	ds_read_b32 v138, v146
	s_lshl_b32 s13, s20, 8
	v_lshrrev_b32_e32 v136, 1, v136
	v_and_or_b32 v139, v136, 24, s61
	v_add_u32_e32 v136, s13, v147
	v_ashrrev_i32_e32 v137, 31, v136
	s_waitcnt lgkmcnt(0)
	v_mul_f32_e32 v124, v124, v138
	v_mul_f32_e32 v125, v125, v138
	v_mul_f32_e32 v126, v126, v138
	v_mul_f32_e32 v127, v127, v138
	v_mul_f32_e32 v120, v120, v138
	v_mul_f32_e32 v121, v121, v138
	v_lshlrev_b64 v[140:141], 10, v[136:137]
	s_lshl_b32 s20, s2, 7
	v_cvt_pk_bf16_f32 v124, v124, v125
	v_cvt_pk_bf16_f32 v125, v126, v127
	v_cvt_pk_bf16_f32 v126, v120, v121
	v_mul_f32_e32 v120, v122, v138
	v_mul_f32_e32 v121, v123, v138
	s_ashr_i32 s21, s20, 31
	v_cvt_pk_bf16_f32 v127, v120, v121
	v_lshl_add_u64 v[120:121], s[6:7], 0, v[140:141]
	s_mov_b64 s[2:3], -1
	s_and_b64 vcc, exec, s[4:5]
	v_lshl_add_u64 v[120:121], s[20:21], 1, v[120:121]
	v_lshlrev_b32_e32 v144, 1, v139
	s_cbranch_vccz .LBB0_1349
	v_lshl_add_u64 v[122:123], v[120:121], 0, v[144:145]
	v_add_co_u32_e32 v122, vcc, 0xd9ff000, v122
	s_mov_b64 s[2:3], 0
	s_nop 0
	v_addc_co_u32_e32 v123, vcc, 0, v123, vcc
	global_store_dwordx4 v[122:123], v[124:127], off offset:3968

; DI void st_bf8(u16* p, f32x4 a, f32x4 b, float sc) {
;   u32x4 u; u.x = pack2(a[0] * sc, a[1] * sc); u.y = pack2(a[2] * sc, a[3] * sc); u.z = pack2(b[0] * sc, b[1] * sc); u.w = pack2(b[2] * sc, b[3] * sc);
;   *(u32x4*)p = u;
;   DI void operator()(const f32x4 (&acc)[2][2][4][2], const pg8::Unit& u, int wr, int wc, int fr_, int fq_) const {
;     ...
;             } else if (EPI == EPI_UKV) {
;               if (n == 0) {
;                 const int gb = u.pn * 256 + bj * 128 + wc * 32;
;                 const int hd = gb >> 7, within = (gb & 127) + 8 * fq;
;                 const f32x4 v1 = acc[ai][bj][m][1];
;                 if (within < 64) st_bf8((u16*)(big + E_KNOPE) + (size_t)token * 512 + hd * 64 + within, v, v1, rinv);
;                 else st_bf8((u16*)(big + E_VMLAT) + (size_t)token * 512 + hd * 64 + (within - 64), v, v1, rinv);
;               }
.LBB0_1351:
	v_mov_b32_e32 v139, v138
	v_mul_f32_e32 v116, v116, v138
	v_mul_f32_e32 v117, v117, v139
	v_mul_f32_e32 v118, v118, v138
	v_mul_f32_e32 v119, v119, v139
	v_mul_f32_e32 v112, v112, v138
	v_mul_f32_e32 v113, v113, v139
	v_cvt_pk_bf16_f32 v116, v116, v117
	v_cvt_pk_bf16_f32 v117, v118, v119
	v_cvt_pk_bf16_f32 v118, v112, v113
	v_mul_f32_e32 v112, v114, v138
	v_mul_f32_e32 v113, v115, v139
	s_andn2_b64 vcc, exec, s[4:5]
	v_cvt_pk_bf16_f32 v119, v112, v113
	v_cndmask_b32_e64 v112, 0, 1, s[4:5]
	v_cmp_ne_u32_e64 s[2:3], 1, v112
	s_mov_b64 s[22:23], -1
	s_cbranch_vccnz .LBB0_1353
	v_lshl_add_u64 v[112:113], v[120:121], 0, v[144:145]
	v_add_co_u32_e32 v112, vcc, 0xda00000, v112
	s_mov_b64 s[22:23], 0
	s_nop 0
	v_addc_co_u32_e32 v113, vcc, 0, v113, vcc
	global_store_dwordx4 v[112:113], v[116:119], off

; DI void st_bf8(u16* p, f32x4 a, f32x4 b, float sc) {
;   u32x4 u; u.x = pack2(a[0] * sc, a[1] * sc); u.y = pack2(a[2] * sc, a[3] * sc); u.z = pack2(b[0] * sc, b[1] * sc); u.w = pack2(b[2] * sc, b[3] * sc);
;   *(u32x4*)p = u;
;   DI void operator()(const f32x4 (&acc)[2][2][4][2], const pg8::Unit& u, int wr, int wc, int fr_, int fq_) const {
;     ...
;             } else if (EPI == EPI_UKV) {
;               if (n == 0) {
;                 const int gb = u.pn * 256 + bj * 128 + wc * 32;
;                 const int hd = gb >> 7, within = (gb & 127) + 8 * fq;
;                 const f32x4 v1 = acc[ai][bj][m][1];
;                 if (within < 64) st_bf8((u16*)(big + E_KNOPE) + (size_t)token * 512 + hd * 64 + within, v, v1, rinv);
;                 else st_bf8((u16*)(big + E_VMLAT) + (size_t)token * 512 + hd * 64 + (within - 64), v, v1, rinv);
;               }
.LBB0_1355:
	ds_read_b32 v112, v146 offset:64
	v_add3_u32 v114, s13, v147, 16
	v_ashrrev_i32_e32 v115, 31, v114
	v_lshlrev_b64 v[114:115], 10, v[114:115]
	s_mov_b64 s[22:23], -1
	s_waitcnt lgkmcnt(0)
	v_mul_f32_e32 v108, v108, v112
	v_mul_f32_e32 v109, v109, v112
	v_mul_f32_e32 v110, v110, v112
	v_mul_f32_e32 v111, v111, v112
	v_mul_f32_e32 v104, v104, v112
	v_mul_f32_e32 v105, v105, v112
	v_cvt_pk_bf16_f32 v108, v108, v109
	v_cvt_pk_bf16_f32 v109, v110, v111
	v_cvt_pk_bf16_f32 v110, v104, v105
	v_mul_f32_e32 v104, v106, v112
	v_mul_f32_e32 v105, v107, v112
	s_and_b64 vcc, exec, s[2:3]
	v_cvt_pk_bf16_f32 v111, v104, v105
	v_lshl_add_u64 v[104:105], s[6:7], 0, v[114:115]
	v_lshl_add_u64 v[104:105], s[20:21], 1, v[104:105]
	s_cbranch_vccnz .LBB0_1357
	v_lshl_add_u64 v[106:107], v[104:105], 0, v[144:145]
	v_add_co_u32_e32 v106, vcc, 0xd9ff000, v106
	s_mov_b64 s[22:23], 0
	s_nop 0
	v_addc_co_u32_e32 v107, vcc, 0, v107, vcc
	global_store_dwordx4 v[106:107], v[108:111], off offset:3968

; DI void st_bf8(u16* p, f32x4 a, f32x4 b, float sc) {
;   u32x4 u; u.x = pack2(a[0] * sc, a[1] * sc); u.y = pack2(a[2] * sc, a[3] * sc); u.z = pack2(b[0] * sc, b[1] * sc); u.w = pack2(b[2] * sc, b[3] * sc);
;   *(u32x4*)p = u;
;   DI void operator()(const f32x4 (&acc)[2][2][4][2], const pg8::Unit& u, int wr, int wc, int fr_, int fq_) const {
;     ...
;             } else if (EPI == EPI_UKV) {
;               if (n == 0) {
;                 const int gb = u.pn * 256 + bj * 128 + wc * 32;
;                 const int hd = gb >> 7, within = (gb & 127) + 8 * fq;
;                 const f32x4 v1 = acc[ai][bj][m][1];
;                 if (within < 64) st_bf8((u16*)(big + E_KNOPE) + (size_t)token * 512 + hd * 64 + within, v, v1, rinv);
;                 else st_bf8((u16*)(big + E_VMLAT) + (size_t)token * 512 + hd * 64 + (within - 64), v, v1, rinv);
;               }
.LBB0_1359:
	v_mov_b32_e32 v113, v112
	v_mul_f32_e32 v100, v100, v112
	v_mul_f32_e32 v101, v101, v113
	v_mul_f32_e32 v102, v102, v112
	v_mul_f32_e32 v103, v103, v113
	v_mul_f32_e32 v96, v96, v112
	v_mul_f32_e32 v97, v97, v113
	v_cvt_pk_bf16_f32 v100, v100, v101
	v_cvt_pk_bf16_f32 v101, v102, v103
	v_cvt_pk_bf16_f32 v102, v96, v97
	v_mul_f32_e32 v96, v98, v112
	v_mul_f32_e32 v97, v99, v113
	s_and_b64 vcc, exec, s[2:3]
	v_cvt_pk_bf16_f32 v103, v96, v97
	s_mov_b64 s[22:23], -1
	s_cbranch_vccnz .LBB0_1361
	v_lshl_add_u64 v[96:97], v[104:105], 0, v[144:145]
	v_add_co_u32_e32 v96, vcc, 0xda00000, v96
	s_mov_b64 s[22:23], 0
	s_nop 0
	v_addc_co_u32_e32 v97, vcc, 0, v97, vcc
	global_store_dwordx4 v[96:97], v[100:103], off

; DI void st_bf8(u16* p, f32x4 a, f32x4 b, float sc) {
;   u32x4 u; u.x = pack2(a[0] * sc, a[1] * sc); u.y = pack2(a[2] * sc, a[3] * sc); u.z = pack2(b[0] * sc, b[1] * sc); u.w = pack2(b[2] * sc, b[3] * sc);
;   *(u32x4*)p = u;
;   DI void operator()(const f32x4 (&acc)[2][2][4][2], const pg8::Unit& u, int wr, int wc, int fr_, int fq_) const {
;     ...
;             } else if (EPI == EPI_UKV) {
;               if (n == 0) {
;                 const int gb = u.pn * 256 + bj * 128 + wc * 32;
;                 const int hd = gb >> 7, within = (gb & 127) + 8 * fq;
;                 const f32x4 v1 = acc[ai][bj][m][1];
;                 if (within < 64) st_bf8((u16*)(big + E_KNOPE) + (size_t)token * 512 + hd * 64 + within, v, v1, rinv);
;                 else st_bf8((u16*)(big + E_VMLAT) + (size_t)token * 512 + hd * 64 + (within - 64), v, v1, rinv);
;               }
.LBB0_1363:
	ds_read_b32 v96, v146 offset:128
	v_add3_u32 v98, s13, v147, 32
	v_ashrrev_i32_e32 v99, 31, v98
	v_lshlrev_b64 v[98:99], 10, v[98:99]
	s_mov_b64 s[22:23], -1
	s_waitcnt lgkmcnt(0)
	v_mul_f32_e32 v92, v92, v96
	v_mul_f32_e32 v93, v93, v96
	v_mul_f32_e32 v94, v94, v96
	v_mul_f32_e32 v95, v95, v96
	v_mul_f32_e32 v88, v88, v96
	v_mul_f32_e32 v89, v89, v96
	v_cvt_pk_bf16_f32 v92, v92, v93
	v_cvt_pk_bf16_f32 v93, v94, v95
	v_cvt_pk_bf16_f32 v94, v88, v89
	v_mul_f32_e32 v88, v90, v96
	v_mul_f32_e32 v89, v91, v96
	s_and_b64 vcc, exec, s[2:3]
	v_cvt_pk_bf16_f32 v95, v88, v89
	v_lshl_add_u64 v[88:89], s[6:7], 0, v[98:99]
	v_lshl_add_u64 v[88:89], s[20:21], 1, v[88:89]
	s_cbranch_vccnz .LBB0_1365
	v_lshl_add_u64 v[90:91], v[88:89], 0, v[144:145]
	v_add_co_u32_e32 v90, vcc, 0xd9ff000, v90
	s_mov_b64 s[22:23], 0
	s_nop 0
	v_addc_co_u32_e32 v91, vcc, 0, v91, vcc
	global_store_dwordx4 v[90:91], v[92:95], off offset:3968

; DI void st_bf8(u16* p, f32x4 a, f32x4 b, float sc) {
;   u32x4 u; u.x = pack2(a[0] * sc, a[1] * sc); u.y = pack2(a[2] * sc, a[3] * sc); u.z = pack2(b[0] * sc, b[1] * sc); u.w = pack2(b[2] * sc, b[3] * sc);
;   *(u32x4*)p = u;
;   DI void operator()(const f32x4 (&acc)[2][2][4][2], const pg8::Unit& u, int wr, int wc, int fr_, int fq_) const {
;     ...
;             } else if (EPI == EPI_UKV) {
;               if (n == 0) {
;                 const int gb = u.pn * 256 + bj * 128 + wc * 32;
;                 const int hd = gb >> 7, within = (gb & 127) + 8 * fq;
;                 const f32x4 v1 = acc[ai][bj][m][1];
;                 if (within < 64) st_bf8((u16*)(big + E_KNOPE) + (size_t)token * 512 + hd * 64 + within, v, v1, rinv);
;                 else st_bf8((u16*)(big + E_VMLAT) + (size_t)token * 512 + hd * 64 + (within - 64), v, v1, rinv);
;               }
.LBB0_1367:
	v_mov_b32_e32 v97, v96
	v_mul_f32_e32 v84, v84, v96
	v_mul_f32_e32 v85, v85, v97
	v_mul_f32_e32 v86, v86, v96
	v_mul_f32_e32 v87, v87, v97
	v_mul_f32_e32 v80, v80, v96
	v_mul_f32_e32 v81, v81, v97
	v_cvt_pk_bf16_f32 v84, v84, v85
	v_cvt_pk_bf16_f32 v85, v86, v87
	v_cvt_pk_bf16_f32 v86, v80, v81
	v_mul_f32_e32 v80, v82, v96
	v_mul_f32_e32 v81, v83, v97
	s_and_b64 vcc, exec, s[2:3]
	v_cvt_pk_bf16_f32 v87, v80, v81
	s_mov_b64 s[22:23], -1
	s_cbranch_vccnz .LBB0_1369
	v_lshl_add_u64 v[80:81], v[88:89], 0, v[144:145]
	v_add_co_u32_e32 v80, vcc, 0xda00000, v80
	s_mov_b64 s[22:23], 0
	s_nop 0
	v_addc_co_u32_e32 v81, vcc, 0, v81, vcc
	global_store_dwordx4 v[80:81], v[84:87], off

; DI void st_bf8(u16* p, f32x4 a, f32x4 b, float sc) {
;   u32x4 u; u.x = pack2(a[0] * sc, a[1] * sc); u.y = pack2(a[2] * sc, a[3] * sc); u.z = pack2(b[0] * sc, b[1] * sc); u.w = pack2(b[2] * sc, b[3] * sc);
;   *(u32x4*)p = u;
;   DI void operator()(const f32x4 (&acc)[2][2][4][2], const pg8::Unit& u, int wr, int wc, int fr_, int fq_) const {
;     ...
;             } else if (EPI == EPI_UKV) {
;               if (n == 0) {
;                 const int gb = u.pn * 256 + bj * 128 + wc * 32;
;                 const int hd = gb >> 7, within = (gb & 127) + 8 * fq;
;                 const f32x4 v1 = acc[ai][bj][m][1];
;                 if (within < 64) st_bf8((u16*)(big + E_KNOPE) + (size_t)token * 512 + hd * 64 + within, v, v1, rinv);
;                 else st_bf8((u16*)(big + E_VMLAT) + (size_t)token * 512 + hd * 64 + (within - 64), v, v1, rinv);
;               }
.LBB0_1371:
	ds_read_b32 v80, v146 offset:192
	v_add3_u32 v82, s13, v147, 48
	v_ashrrev_i32_e32 v83, 31, v82
	v_lshlrev_b64 v[82:83], 10, v[82:83]
	s_mov_b64 s[22:23], -1
	s_waitcnt lgkmcnt(0)
	v_mul_f32_e32 v76, v76, v80
	v_mul_f32_e32 v77, v77, v80
	v_mul_f32_e32 v78, v78, v80
	v_mul_f32_e32 v79, v79, v80
	v_mul_f32_e32 v72, v72, v80
	v_mul_f32_e32 v73, v73, v80
	v_cvt_pk_bf16_f32 v76, v76, v77
	v_cvt_pk_bf16_f32 v77, v78, v79
	v_cvt_pk_bf16_f32 v78, v72, v73
	v_mul_f32_e32 v72, v74, v80
	v_mul_f32_e32 v73, v75, v80
	s_and_b64 vcc, exec, s[2:3]
	v_cvt_pk_bf16_f32 v79, v72, v73
	v_lshl_add_u64 v[72:73], s[6:7], 0, v[82:83]
	v_lshl_add_u64 v[72:73], s[20:21], 1, v[72:73]
	s_cbranch_vccnz .LBB0_1373
	v_lshl_add_u64 v[74:75], v[72:73], 0, v[144:145]
	v_add_co_u32_e32 v74, vcc, 0xd9ff000, v74
	s_mov_b64 s[22:23], 0
	s_nop 0
	v_addc_co_u32_e32 v75, vcc, 0, v75, vcc
	global_store_dwordx4 v[74:75], v[76:79], off offset:3968

; DI void st_bf8(u16* p, f32x4 a, f32x4 b, float sc) {
;   u32x4 u; u.x = pack2(a[0] * sc, a[1] * sc); u.y = pack2(a[2] * sc, a[3] * sc); u.z = pack2(b[0] * sc, b[1] * sc); u.w = pack2(b[2] * sc, b[3] * sc);
;   *(u32x4*)p = u;
;   DI void operator()(const f32x4 (&acc)[2][2][4][2], const pg8::Unit& u, int wr, int wc, int fr_, int fq_) const {
;     ...
;             } else if (EPI == EPI_UKV) {
;               if (n == 0) {
;                 const int gb = u.pn * 256 + bj * 128 + wc * 32;
;                 const int hd = gb >> 7, within = (gb & 127) + 8 * fq;
;                 const f32x4 v1 = acc[ai][bj][m][1];
;                 if (within < 64) st_bf8((u16*)(big + E_KNOPE) + (size_t)token * 512 + hd * 64 + within, v, v1, rinv);
;                 else st_bf8((u16*)(big + E_VMLAT) + (size_t)token * 512 + hd * 64 + (within - 64), v, v1, rinv);
;               }
.LBB0_1375:
	v_mov_b32_e32 v81, v80
	v_mul_f32_e32 v68, v68, v80
	v_mul_f32_e32 v69, v69, v81
	v_mul_f32_e32 v70, v70, v80
	v_mul_f32_e32 v71, v71, v81
	v_mul_f32_e32 v64, v64, v80
	v_mul_f32_e32 v65, v65, v81
	v_cvt_pk_bf16_f32 v68, v68, v69
	v_cvt_pk_bf16_f32 v69, v70, v71
	v_cvt_pk_bf16_f32 v70, v64, v65
	v_mul_f32_e32 v64, v66, v80
	v_mul_f32_e32 v65, v67, v81
	s_and_b64 vcc, exec, s[2:3]
	v_cvt_pk_bf16_f32 v71, v64, v65
	s_mov_b64 s[22:23], -1
	s_cbranch_vccnz .LBB0_1377
	v_lshl_add_u64 v[64:65], v[72:73], 0, v[144:145]
	v_add_co_u32_e32 v64, vcc, 0xda00000, v64
	s_mov_b64 s[22:23], 0
	s_nop 0
	v_addc_co_u32_e32 v65, vcc, 0, v65, vcc
	global_store_dwordx4 v[64:65], v[68:71], off

; DI void st_bf8(u16* p, f32x4 a, f32x4 b, float sc) {
;   u32x4 u; u.x = pack2(a[0] * sc, a[1] * sc); u.y = pack2(a[2] * sc, a[3] * sc); u.z = pack2(b[0] * sc, b[1] * sc); u.w = pack2(b[2] * sc, b[3] * sc);
;   *(u32x4*)p = u;
;   DI void operator()(const f32x4 (&acc)[2][2][4][2], const pg8::Unit& u, int wr, int wc, int fr_, int fq_) const {
;     ...
;             } else if (EPI == EPI_UKV) {
;               if (n == 0) {
;                 const int gb = u.pn * 256 + bj * 128 + wc * 32;
;                 const int hd = gb >> 7, within = (gb & 127) + 8 * fq;
;                 const f32x4 v1 = acc[ai][bj][m][1];
;                 if (within < 64) st_bf8((u16*)(big + E_KNOPE) + (size_t)token * 512 + hd * 64 + within, v, v1, rinv);
;                 else st_bf8((u16*)(big + E_VMLAT) + (size_t)token * 512 + hd * 64 + (within - 64), v, v1, rinv);
;               }
.LBB0_1379:
	ds_read_b32 v64, v146 offset:512
	v_add_u32_e32 v66, 0x80, v136
	v_ashrrev_i32_e32 v67, 31, v66
	v_lshlrev_b64 v[66:67], 10, v[66:67]
	s_mov_b64 s[22:23], -1
	s_waitcnt lgkmcnt(0)
	v_mul_f32_e32 v60, v60, v64
	v_mul_f32_e32 v61, v61, v64
	v_mul_f32_e32 v62, v62, v64
	v_mul_f32_e32 v63, v63, v64
	v_mul_f32_e32 v56, v56, v64
	v_mul_f32_e32 v57, v57, v64
	v_cvt_pk_bf16_f32 v60, v60, v61
	v_cvt_pk_bf16_f32 v61, v62, v63
	v_cvt_pk_bf16_f32 v62, v56, v57
	v_mul_f32_e32 v56, v58, v64
	v_mul_f32_e32 v57, v59, v64
	s_and_b64 vcc, exec, s[2:3]
	v_cvt_pk_bf16_f32 v63, v56, v57
	v_lshl_add_u64 v[56:57], s[6:7], 0, v[66:67]
	v_lshl_add_u64 v[56:57], s[20:21], 1, v[56:57]
	s_cbranch_vccnz .LBB0_1381
	v_lshl_add_u64 v[58:59], v[56:57], 0, v[144:145]
	v_add_co_u32_e32 v58, vcc, 0xd9ff000, v58
	s_mov_b64 s[22:23], 0
	s_nop 0
	v_addc_co_u32_e32 v59, vcc, 0, v59, vcc
	global_store_dwordx4 v[58:59], v[60:63], off offset:3968

; DI void st_bf8(u16* p, f32x4 a, f32x4 b, float sc) {
;   u32x4 u; u.x = pack2(a[0] * sc, a[1] * sc); u.y = pack2(a[2] * sc, a[3] * sc); u.z = pack2(b[0] * sc, b[1] * sc); u.w = pack2(b[2] * sc, b[3] * sc);
;   *(u32x4*)p = u;
;   DI void operator()(const f32x4 (&acc)[2][2][4][2], const pg8::Unit& u, int wr, int wc, int fr_, int fq_) const {
;     ...
;             } else if (EPI == EPI_UKV) {
;               if (n == 0) {
;                 const int gb = u.pn * 256 + bj * 128 + wc * 32;
;                 const int hd = gb >> 7, within = (gb & 127) + 8 * fq;
;                 const f32x4 v1 = acc[ai][bj][m][1];
;                 if (within < 64) st_bf8((u16*)(big + E_KNOPE) + (size_t)token * 512 + hd * 64 + within, v, v1, rinv);
;                 else st_bf8((u16*)(big + E_VMLAT) + (size_t)token * 512 + hd * 64 + (within - 64), v, v1, rinv);
;               }
.LBB0_1383:
	v_mov_b32_e32 v65, v64
	v_mul_f32_e32 v52, v52, v64
	v_mul_f32_e32 v53, v53, v65
	v_mul_f32_e32 v54, v54, v64
	v_mul_f32_e32 v55, v55, v65
	v_mul_f32_e32 v48, v48, v64
	v_mul_f32_e32 v49, v49, v65
	v_cvt_pk_bf16_f32 v52, v52, v53
	v_cvt_pk_bf16_f32 v53, v54, v55
	v_cvt_pk_bf16_f32 v54, v48, v49
	v_mul_f32_e32 v48, v50, v64
	v_mul_f32_e32 v49, v51, v65
	s_and_b64 vcc, exec, s[2:3]
	v_cvt_pk_bf16_f32 v55, v48, v49
	s_mov_b64 s[22:23], -1
	s_cbranch_vccnz .LBB0_1385
	v_lshl_add_u64 v[48:49], v[56:57], 0, v[144:145]
	v_add_co_u32_e32 v48, vcc, 0xda00000, v48
	s_mov_b64 s[22:23], 0
	s_nop 0
	v_addc_co_u32_e32 v49, vcc, 0, v49, vcc
	global_store_dwordx4 v[48:49], v[52:55], off

; DI void st_bf8(u16* p, f32x4 a, f32x4 b, float sc) {
;   u32x4 u; u.x = pack2(a[0] * sc, a[1] * sc); u.y = pack2(a[2] * sc, a[3] * sc); u.z = pack2(b[0] * sc, b[1] * sc); u.w = pack2(b[2] * sc, b[3] * sc);
;   *(u32x4*)p = u;
;   DI void operator()(const f32x4 (&acc)[2][2][4][2], const pg8::Unit& u, int wr, int wc, int fr_, int fq_) const {
;     ...
;             } else if (EPI == EPI_UKV) {
;               if (n == 0) {
;                 const int gb = u.pn * 256 + bj * 128 + wc * 32;
;                 const int hd = gb >> 7, within = (gb & 127) + 8 * fq;
;                 const f32x4 v1 = acc[ai][bj][m][1];
;                 if (within < 64) st_bf8((u16*)(big + E_KNOPE) + (size_t)token * 512 + hd * 64 + within, v, v1, rinv);
;                 else st_bf8((u16*)(big + E_VMLAT) + (size_t)token * 512 + hd * 64 + (within - 64), v, v1, rinv);
;               }
.LBB0_1387:
	ds_read_b32 v48, v146 offset:576
	v_add_u32_e32 v50, 0x90, v136
	v_ashrrev_i32_e32 v51, 31, v50
	v_lshlrev_b64 v[50:51], 10, v[50:51]
	s_mov_b64 s[22:23], -1
	s_waitcnt lgkmcnt(0)
	v_mul_f32_e32 v44, v44, v48
	v_mul_f32_e32 v45, v45, v48
	v_mul_f32_e32 v46, v46, v48
	v_mul_f32_e32 v47, v47, v48
	v_mul_f32_e32 v40, v40, v48
	v_mul_f32_e32 v41, v41, v48
	v_cvt_pk_bf16_f32 v44, v44, v45
	v_cvt_pk_bf16_f32 v45, v46, v47
	v_cvt_pk_bf16_f32 v46, v40, v41
	v_mul_f32_e32 v40, v42, v48
	v_mul_f32_e32 v41, v43, v48
	s_and_b64 vcc, exec, s[2:3]
	v_cvt_pk_bf16_f32 v47, v40, v41
	v_lshl_add_u64 v[40:41], s[6:7], 0, v[50:51]
	v_lshl_add_u64 v[40:41], s[20:21], 1, v[40:41]
	s_cbranch_vccnz .LBB0_1389
	v_lshl_add_u64 v[42:43], v[40:41], 0, v[144:145]
	v_add_co_u32_e32 v42, vcc, 0xd9ff000, v42
	s_mov_b64 s[22:23], 0
	s_nop 0
	v_addc_co_u32_e32 v43, vcc, 0, v43, vcc
	global_store_dwordx4 v[42:43], v[44:47], off offset:3968

; DI void st_bf8(u16* p, f32x4 a, f32x4 b, float sc) {
;   u32x4 u; u.x = pack2(a[0] * sc, a[1] * sc); u.y = pack2(a[2] * sc, a[3] * sc); u.z = pack2(b[0] * sc, b[1] * sc); u.w = pack2(b[2] * sc, b[3] * sc);
;   *(u32x4*)p = u;
;   DI void operator()(const f32x4 (&acc)[2][2][4][2], const pg8::Unit& u, int wr, int wc, int fr_, int fq_) const {
;     ...
;             } else if (EPI == EPI_UKV) {
;               if (n == 0) {
;                 const int gb = u.pn * 256 + bj * 128 + wc * 32;
;                 const int hd = gb >> 7, within = (gb & 127) + 8 * fq;
;                 const f32x4 v1 = acc[ai][bj][m][1];
;                 if (within < 64) st_bf8((u16*)(big + E_KNOPE) + (size_t)token * 512 + hd * 64 + within, v, v1, rinv);
;                 else st_bf8((u16*)(big + E_VMLAT) + (size_t)token * 512 + hd * 64 + (within - 64), v, v1, rinv);
;               }
.LBB0_1391:
	v_mov_b32_e32 v49, v48
	v_mul_f32_e32 v36, v36, v48
	v_mul_f32_e32 v37, v37, v49
	v_mul_f32_e32 v38, v38, v48
	v_mul_f32_e32 v39, v39, v49
	v_mul_f32_e32 v32, v32, v48
	v_mul_f32_e32 v33, v33, v49
	v_cvt_pk_bf16_f32 v36, v36, v37
	v_cvt_pk_bf16_f32 v37, v38, v39
	v_cvt_pk_bf16_f32 v38, v32, v33
	v_mul_f32_e32 v32, v34, v48
	v_mul_f32_e32 v33, v35, v49
	s_and_b64 vcc, exec, s[2:3]
	v_cvt_pk_bf16_f32 v39, v32, v33
	s_mov_b64 s[22:23], -1
	s_cbranch_vccnz .LBB0_1393
	v_lshl_add_u64 v[32:33], v[40:41], 0, v[144:145]
	v_add_co_u32_e32 v32, vcc, 0xda00000, v32
	s_mov_b64 s[22:23], 0
	s_nop 0
	v_addc_co_u32_e32 v33, vcc, 0, v33, vcc
	global_store_dwordx4 v[32:33], v[36:39], off

; DI void st_bf8(u16* p, f32x4 a, f32x4 b, float sc) {
;   u32x4 u; u.x = pack2(a[0] * sc, a[1] * sc); u.y = pack2(a[2] * sc, a[3] * sc); u.z = pack2(b[0] * sc, b[1] * sc); u.w = pack2(b[2] * sc, b[3] * sc);
;   *(u32x4*)p = u;
;   DI void operator()(const f32x4 (&acc)[2][2][4][2], const pg8::Unit& u, int wr, int wc, int fr_, int fq_) const {
;     ...
;             } else if (EPI == EPI_UKV) {
;               if (n == 0) {
;                 const int gb = u.pn * 256 + bj * 128 + wc * 32;
;                 const int hd = gb >> 7, within = (gb & 127) + 8 * fq;
;                 const f32x4 v1 = acc[ai][bj][m][1];
;                 if (within < 64) st_bf8((u16*)(big + E_KNOPE) + (size_t)token * 512 + hd * 64 + within, v, v1, rinv);
;                 else st_bf8((u16*)(big + E_VMLAT) + (size_t)token * 512 + hd * 64 + (within - 64), v, v1, rinv);
;               }
.LBB0_1395:
	ds_read_b32 v32, v146 offset:640
	v_add_u32_e32 v34, 0xa0, v136
	v_ashrrev_i32_e32 v35, 31, v34
	v_lshlrev_b64 v[34:35], 10, v[34:35]
	s_mov_b64 s[22:23], -1
	s_waitcnt lgkmcnt(0)
	v_mul_f32_e32 v28, v28, v32
	v_mul_f32_e32 v29, v29, v32
	v_mul_f32_e32 v30, v30, v32
	v_mul_f32_e32 v31, v31, v32
	v_mul_f32_e32 v24, v24, v32
	v_mul_f32_e32 v25, v25, v32
	v_cvt_pk_bf16_f32 v28, v28, v29
	v_cvt_pk_bf16_f32 v29, v30, v31
	v_cvt_pk_bf16_f32 v30, v24, v25
	v_mul_f32_e32 v24, v26, v32
	v_mul_f32_e32 v25, v27, v32
	s_and_b64 vcc, exec, s[2:3]
	v_cvt_pk_bf16_f32 v31, v24, v25
	v_lshl_add_u64 v[24:25], s[6:7], 0, v[34:35]
	v_lshl_add_u64 v[24:25], s[20:21], 1, v[24:25]
	s_cbranch_vccnz .LBB0_1397
	v_lshl_add_u64 v[26:27], v[24:25], 0, v[144:145]
	v_add_co_u32_e32 v26, vcc, 0xd9ff000, v26
	s_mov_b64 s[22:23], 0
	s_nop 0
	v_addc_co_u32_e32 v27, vcc, 0, v27, vcc
	global_store_dwordx4 v[26:27], v[28:31], off offset:3968

; DI void st_bf8(u16* p, f32x4 a, f32x4 b, float sc) {
;   u32x4 u; u.x = pack2(a[0] * sc, a[1] * sc); u.y = pack2(a[2] * sc, a[3] * sc); u.z = pack2(b[0] * sc, b[1] * sc); u.w = pack2(b[2] * sc, b[3] * sc);
;   *(u32x4*)p = u;
;   DI void operator()(const f32x4 (&acc)[2][2][4][2], const pg8::Unit& u, int wr, int wc, int fr_, int fq_) const {
;     ...
;             } else if (EPI == EPI_UKV) {
;               if (n == 0) {
;                 const int gb = u.pn * 256 + bj * 128 + wc * 32;
;                 const int hd = gb >> 7, within = (gb & 127) + 8 * fq;
;                 const f32x4 v1 = acc[ai][bj][m][1];
;                 if (within < 64) st_bf8((u16*)(big + E_KNOPE) + (size_t)token * 512 + hd * 64 + within, v, v1, rinv);
;                 else st_bf8((u16*)(big + E_VMLAT) + (size_t)token * 512 + hd * 64 + (within - 64), v, v1, rinv);
;               }
.LBB0_1399:
	v_mov_b32_e32 v33, v32
	v_mul_f32_e32 v20, v20, v32
	v_mul_f32_e32 v21, v21, v33
	v_mul_f32_e32 v22, v22, v32
	v_mul_f32_e32 v23, v23, v33
	v_mul_f32_e32 v16, v16, v32
	v_mul_f32_e32 v17, v17, v33
	v_cvt_pk_bf16_f32 v20, v20, v21
	v_cvt_pk_bf16_f32 v21, v22, v23
	v_cvt_pk_bf16_f32 v22, v16, v17
	v_mul_f32_e32 v16, v18, v32
	v_mul_f32_e32 v17, v19, v33
	s_and_b64 vcc, exec, s[2:3]
	v_cvt_pk_bf16_f32 v23, v16, v17
	s_mov_b64 s[22:23], -1
	s_cbranch_vccnz .LBB0_1401
	v_lshl_add_u64 v[16:17], v[24:25], 0, v[144:145]
	v_add_co_u32_e32 v16, vcc, 0xda00000, v16
	s_mov_b64 s[22:23], 0
	s_nop 0
	v_addc_co_u32_e32 v17, vcc, 0, v17, vcc
	global_store_dwordx4 v[16:17], v[20:23], off

; DI void st_bf8(u16* p, f32x4 a, f32x4 b, float sc) {
;   u32x4 u; u.x = pack2(a[0] * sc, a[1] * sc); u.y = pack2(a[2] * sc, a[3] * sc); u.z = pack2(b[0] * sc, b[1] * sc); u.w = pack2(b[2] * sc, b[3] * sc);
;   *(u32x4*)p = u;
;   DI void operator()(const f32x4 (&acc)[2][2][4][2], const pg8::Unit& u, int wr, int wc, int fr_, int fq_) const {
;     ...
;             } else if (EPI == EPI_UKV) {
;               if (n == 0) {
;                 const int gb = u.pn * 256 + bj * 128 + wc * 32;
;                 const int hd = gb >> 7, within = (gb & 127) + 8 * fq;
;                 const f32x4 v1 = acc[ai][bj][m][1];
;                 if (within < 64) st_bf8((u16*)(big + E_KNOPE) + (size_t)token * 512 + hd * 64 + within, v, v1, rinv);
;                 else st_bf8((u16*)(big + E_VMLAT) + (size_t)token * 512 + hd * 64 + (within - 64), v, v1, rinv);
;               }
.LBB0_1403:
	ds_read_b32 v16, v146 offset:704
	v_add_u32_e32 v18, 0xb0, v136
	v_ashrrev_i32_e32 v19, 31, v18
	v_lshlrev_b64 v[18:19], 10, v[18:19]
	s_mov_b64 s[22:23], -1
	s_waitcnt lgkmcnt(0)
	v_mul_f32_e32 v12, v12, v16
	v_mul_f32_e32 v13, v13, v16
	v_mul_f32_e32 v14, v14, v16
	v_mul_f32_e32 v15, v15, v16
	v_mul_f32_e32 v8, v8, v16
	v_mul_f32_e32 v9, v9, v16
	v_cvt_pk_bf16_f32 v12, v12, v13
	v_cvt_pk_bf16_f32 v13, v14, v15
	v_cvt_pk_bf16_f32 v14, v8, v9
	v_mul_f32_e32 v8, v10, v16
	v_mul_f32_e32 v9, v11, v16
	s_and_b64 vcc, exec, s[2:3]
	v_cvt_pk_bf16_f32 v15, v8, v9
	v_lshl_add_u64 v[8:9], s[6:7], 0, v[18:19]
	v_lshl_add_u64 v[8:9], s[20:21], 1, v[8:9]
	s_cbranch_vccnz .LBB0_1405
	v_lshl_add_u64 v[10:11], v[8:9], 0, v[144:145]
	v_add_co_u32_e32 v10, vcc, 0xd9ff000, v10
	s_mov_b64 s[22:23], 0
	s_nop 0
	v_addc_co_u32_e32 v11, vcc, 0, v11, vcc
	global_store_dwordx4 v[10:11], v[12:15], off offset:3968

; DI void st_bf8(u16* p, f32x4 a, f32x4 b, float sc) {
;   u32x4 u; u.x = pack2(a[0] * sc, a[1] * sc); u.y = pack2(a[2] * sc, a[3] * sc); u.z = pack2(b[0] * sc, b[1] * sc); u.w = pack2(b[2] * sc, b[3] * sc);
;   *(u32x4*)p = u;
;   DI void operator()(const f32x4 (&acc)[2][2][4][2], const pg8::Unit& u, int wr, int wc, int fr_, int fq_) const {
;     ...
;             } else if (EPI == EPI_UKV) {
;               if (n == 0) {
;                 const int gb = u.pn * 256 + bj * 128 + wc * 32;
;                 const int hd = gb >> 7, within = (gb & 127) + 8 * fq;
;                 const f32x4 v1 = acc[ai][bj][m][1];
;                 if (within < 64) st_bf8((u16*)(big + E_KNOPE) + (size_t)token * 512 + hd * 64 + within, v, v1, rinv);
;                 else st_bf8((u16*)(big + E_VMLAT) + (size_t)token * 512 + hd * 64 + (within - 64), v, v1, rinv);
;               }
.LBB0_1407:
	v_mov_b32_e32 v17, v16
	v_mul_f32_e32 v4, v4, v16
	v_mul_f32_e32 v5, v5, v17
	v_mul_f32_e32 v6, v6, v16
	v_mul_f32_e32 v7, v7, v17
	v_mul_f32_e32 v0, v0, v16
	v_mul_f32_e32 v1, v1, v17
	v_cvt_pk_bf16_f32 v4, v4, v5
	v_cvt_pk_bf16_f32 v5, v6, v7
	v_cvt_pk_bf16_f32 v6, v0, v1
	v_mul_f32_e32 v0, v2, v16
	v_mul_f32_e32 v1, v3, v17
	s_and_b64 vcc, exec, s[2:3]
	v_cvt_pk_bf16_f32 v7, v0, v1
	s_mov_b64 s[2:3], -1
	s_cbranch_vccnz .LBB0_1409
	v_lshl_add_u64 v[0:1], v[8:9], 0, v[144:145]
	v_add_co_u32_e32 v0, vcc, 0xda00000, v0
	s_mov_b64 s[2:3], 0
	s_nop 0
	v_addc_co_u32_e32 v1, vcc, 0, v1, vcc
	global_store_dwordx4 v[0:1], v[4:7], off

; DI bool softmax_tile(f32x16& s0, f32x16& s1, float& m, float& l, float& alpha, bf16x8* pf, int lane, bool first, bool check) {
;     ...
;   for (int i = 0; i < 16; ++i) { s0[i] = __builtin_amdgcn_exp2f(s0[i]); sum += s0[i]; }
; #pragma unroll
;   for (int i = 0; i < 16; ++i) { s1[i] = __builtin_amdgcn_exp2f(s1[i]); sum += s1[i]; }
;   l += sum;
; DI void attn_mla_unit(const Params& p, int b, int h, int qb, char* smem, bool pre, int nh, bool has_next) {
;     ...
;   const float lt = l + shx(l, 32, lane);
;   const float inv = 1.f / lt;
;   u16* op = o + (size_t)qrow * 1024 + h * 64 + 4 * hh;
; #pragma unroll
;   for (int i4 = 0; i4 < 4; ++i4) {
;     st_bf4(op + 8 * i4, (f32x4){O0[4 * i4], O0[4 * i4 + 1], O0[4 * i4 + 2], O0[4 * i4 + 3]}, inv);
;     st_bf4(op + 32 + 8 * i4, (f32x4){O1[4 * i4], O1[4 * i4 + 1], O1[4 * i4 + 2], O1[4 * i4 + 3]}, inv);
;   }
.LBB0_1472:
	v_add_f32_e32 v64, 0, v64
	v_add_f32_e32 v64, v65, v64
	v_add_f32_e32 v48, 0, v48
	v_add_f32_e32 v64, v66, v64
	v_add_f32_e32 v48, v49, v48
	v_add_f32_e32 v64, v67, v64
	v_add_f32_e32 v48, v50, v48
	v_add_f32_e32 v64, v68, v64
	v_add_f32_e32 v48, v51, v48
	v_add_f32_e32 v64, v69, v64
	v_add_f32_e32 v48, v52, v48
	v_add_f32_e32 v64, v70, v64
	v_add_f32_e32 v48, v53, v48
	v_add_f32_e32 v64, v71, v64
	v_add_f32_e32 v48, v54, v48
	v_add_f32_e32 v64, v72, v64
	v_add_f32_e32 v48, v55, v48
	v_add_f32_e32 v64, v73, v64
	v_add_f32_e32 v48, v56, v48
	v_add_f32_e32 v64, v74, v64
	v_add_f32_e32 v48, v57, v48
	v_add_f32_e32 v64, v75, v64
	v_add_f32_e32 v48, v58, v48
	v_add_f32_e32 v64, v76, v64
	v_add_f32_e32 v48, v59, v48
	v_add_f32_e32 v64, v77, v64
	v_add_f32_e32 v48, v60, v48
	v_add_f32_e32 v64, v78, v64
	v_add_f32_e32 v48, v61, v48
	v_add_f32_e32 v64, v79, v64
	v_add_f32_e32 v48, v62, v48
	v_add_f32_e32 v64, v126, v64
	v_add_f32_e32 v48, v63, v48
	v_add_f32_e32 v64, v127, v64
	v_add_f32_e32 v32, v32, v48
	v_add_f32_e32 v64, v128, v64
	v_add_f32_e32 v32, v33, v32
	v_add_f32_e32 v64, v129, v64
	v_add_f32_e32 v32, v34, v32
	v_add_f32_e32 v64, v130, v64
	v_add_f32_e32 v32, v35, v32
	v_add_f32_e32 v64, v131, v64
	v_add_f32_e32 v32, v36, v32
	v_add_f32_e32 v64, v132, v64
	v_add_f32_e32 v32, v37, v32
	v_add_f32_e32 v64, v133, v64
	v_add_f32_e32 v32, v38, v32
	v_add_f32_e32 v64, v134, v64
	v_add_f32_e32 v32, v39, v32
	v_add_f32_e32 v64, v135, v64
	v_add_f32_e32 v32, v40, v32
	v_add_f32_e32 v64, v142, v64
	v_add_f32_e32 v32, v41, v32
	v_add_f32_e32 v64, v143, v64
	v_add_f32_e32 v32, v42, v32
	v_add_f32_e32 v64, v144, v64
	v_add_f32_e32 v32, v43, v32
	v_add_f32_e32 v64, v146, v64
	v_add_f32_e32 v32, v44, v32
	v_add_f32_e32 v64, v147, v64
	v_add_f32_e32 v32, v45, v32
	v_add_f32_e32 v64, v148, v64
	v_add_f32_e32 v32, v46, v32
	v_add_f32_e32 v64, v153, v64
	v_add_f32_e32 v32, v47, v32
	v_add_f32_e32 v32, v64, v32
	ds_bpermute_b32 v33, v140, v32
	s_lshl_b32 s24, s9, 1
	v_lshlrev_b32_e32 v144, 3, v137
	s_waitcnt lgkmcnt(0)
	s_barrier
	v_add_f32_e32 v32, v32, v33
	v_div_scale_f32 v33, s[10:11], v32, v32, 1.0
	v_rcp_f32_e32 v34, v33
	s_nop 0
	v_fma_f32 v35, -v33, v34, 1.0
	v_fmac_f32_e32 v34, v35, v34
	v_div_scale_f32 v35, vcc, 1.0, v32, 1.0
	v_mul_f32_e32 v36, v35, v34
	v_fma_f32 v37, -v33, v36, v35
	v_fmac_f32_e32 v36, v37, v34
	v_fma_f32 v33, -v33, v36, v35
	v_div_fmas_f32 v33, v33, v34, v36
	v_lshlrev_b64 v[34:35], 11, v[124:125]
	v_div_fixup_f32 v32, v33, v32, 1.0
	v_lshl_add_u64 v[34:35], s[42:43], 0, v[34:35]
	v_lshl_add_u64 v[34:35], v[34:35], 0, s[24:25]
	v_mul_f32_e32 v0, v0, v32
	v_mul_f32_e32 v1, v1, v32
	v_mul_f32_e32 v2, v2, v32
	v_mul_f32_e32 v3, v3, v32
	v_lshl_add_u64 v[34:35], v[34:35], 0, v[144:145]
	v_cvt_pk_bf16_f32 v0, v0, v1
	v_cvt_pk_bf16_f32 v1, v2, v3
	global_store_dwordx2 v[34:35], v[0:1], off offset:64
	v_mul_f32_e32 v0, v20, v32
	v_mul_f32_e32 v1, v21, v32
	v_mul_f32_e32 v2, v22, v32
	v_mul_f32_e32 v3, v23, v32
	v_cvt_pk_bf16_f32 v0, v0, v1
	v_cvt_pk_bf16_f32 v1, v2, v3
	global_store_dwordx2 v[34:35], v[0:1], off offset:16
	v_mul_f32_e32 v0, v4, v32
	v_mul_f32_e32 v1, v5, v32
	v_mul_f32_e32 v2, v6, v32
	v_mul_f32_e32 v3, v7, v32
	v_cvt_pk_bf16_f32 v0, v0, v1
	v_cvt_pk_bf16_f32 v1, v2, v3
	global_store_dwordx2 v[34:35], v[0:1], off offset:80
	v_mul_f32_e32 v0, v24, v32
	v_mul_f32_e32 v1, v25, v32
	v_mul_f32_e32 v2, v26, v32
	v_mul_f32_e32 v3, v27, v32
	v_cvt_pk_bf16_f32 v0, v0, v1
	v_cvt_pk_bf16_f32 v1, v2, v3
	global_store_dwordx2 v[34:35], v[0:1], off offset:32
	v_mul_f32_e32 v0, v8, v32
	v_mul_f32_e32 v1, v9, v32
	v_mul_f32_e32 v2, v10, v32
	v_mul_f32_e32 v3, v11, v32
	v_cvt_pk_bf16_f32 v0, v0, v1
	v_cvt_pk_bf16_f32 v1, v2, v3
	global_store_dwordx2 v[34:35], v[0:1], off offset:96
	v_mul_f32_e32 v0, v28, v32
	v_mul_f32_e32 v1, v29, v32
	v_mul_f32_e32 v2, v30, v32
	v_mul_f32_e32 v3, v31, v32
	v_cvt_pk_bf16_f32 v0, v0, v1
	v_cvt_pk_bf16_f32 v1, v2, v3
	v_mul_f32_e32 v16, v16, v32
	v_mul_f32_e32 v17, v17, v32
	v_mul_f32_e32 v18, v18, v32
	v_mul_f32_e32 v19, v19, v32
	global_store_dwordx2 v[34:35], v[0:1], off offset:48
	v_mul_f32_e32 v0, v12, v32
	v_mul_f32_e32 v1, v13, v32
	v_mul_f32_e32 v2, v14, v32
	v_mul_f32_e32 v3, v15, v32
	v_cvt_pk_bf16_f32 v16, v16, v17
	v_cvt_pk_bf16_f32 v17, v18, v19
	v_cvt_pk_bf16_f32 v0, v0, v1
	v_cvt_pk_bf16_f32 v1, v2, v3
	s_and_b64 vcc, exec, s[2:3]
	global_store_dwordx2 v[34:35], v[16:17], off
	global_store_dwordx2 v[34:35], v[0:1], off offset:112
	s_cbranch_vccnz .LBB0_1499

; DI f32x16 mfma32(bf16x8 a, bf16x8 b, f32x16 c) { return __builtin_amdgcn_mfma_f32_32x32x16_bf16(a, b, c, 0, 0, 0); }
; DI bool softmax_tile(f32x16& s0, f32x16& s1, float& m, float& l, float& alpha, bf16x8* pf, int lane, bool first, bool check) {
;   if (first) {
;     float mx = fmaxf(s0[0], s1[0]);
; #pragma unroll
;     for (int i = 1; i < 16; ++i) mx = fmaxf(mx, fmaxf(s0[i], s1[i]));
;     mx = fmaxf(mx, shx(mx, 32, lane));
; DI void attn_mla_unit(const Params& p, int b, int h, int qb, char* smem, bool pre, int nh, bool has_next) {
;     ...
;     for (int i = 0; i < 2; ++i) { rk[i] = *(const u32x4*)(gk + (size_t)(k0 + i * 64) * 512); rv[i] = *(const u32x4*)(gv + (size_t)(k0 + i * 64) * 512); }
;     rp = *(const u32x4*)(gp + (size_t)k0 * 32);
;   };
;   __syncthreads();
;   if (!pre) put_stage(smem);
;   __syncthreads();
;   get_stage(1);
;   for (int kt = 0; kt < 32; ++kt) {
;     const char* ks = smem + (kt & 1) * STG; const char* vs = ks + 128 * KR;
; #pragma unroll
;     for (int sub = 0; sub < 2; ++sub) {
;       f32x16 s0, s1;
; #pragma unroll
;       for (int i = 0; i < 16; ++i) { s0[i] = -m; s1[i] = -m; }
;       {
;         bf16x8 kf[12];
; #pragma unroll
;         for (int s = 0; s < 6; ++s) {
;           kf[2 * s] = *(const bf16x8*)(ks + (sub * 64 + r32) * KR + (s * 16 + hh * 8) * 2);
;           kf[2 * s + 1] = *(const bf16x8*)(ks + (sub * 64 + 32 + r32) * KR + (s * 16 + hh * 8) * 2);
;         }
;         __builtin_amdgcn_sched_barrier(0); __builtin_amdgcn_s_setprio(1);
; #pragma unroll
;         for (int s = 0; s < 6; ++s) { s0 = mfma32(kf[2 * s], qf[s], s0); s1 = mfma32(kf[2 * s + 1], qf[s], s1); }
.LBB0_1479:
	s_waitcnt vmcnt(4)
	v_and_b32_e32 v0, 63, v22
	v_bfe_u32 v2, v22, 2, 2
	v_lshrrev_b32_e32 v3, 3, v22
	v_and_b32_e32 v1, 16, v22
	v_and_or_b32 v34, v3, 4, v2
	v_lshlrev_b32_e32 v2, 2, v0
	v_and_or_b32 v0, v2, 12, v1
	v_lshlrev_b32_e32 v147, 1, v0
	v_add_co_u32_e32 v0, vcc, 0x20000, v128
	s_waitcnt lgkmcnt(0)
	s_nop 0
	v_addc_co_u32_e32 v1, vcc, 0, v129, vcc
	s_barrier
	global_load_dwordx4 v[64:67], v[0:1], off
	v_add_co_u32_e32 v0, vcc, 0x20000, v130
	v_xor_b32_e32 v140, 0x80, v2
	s_nop 0
	v_addc_co_u32_e32 v1, vcc, 0, v131, vcc
	global_load_dwordx4 v[68:71], v[0:1], off
	v_add_co_u32_e32 v0, vcc, 0x30000, v128
	s_nop 1
	v_addc_co_u32_e32 v1, vcc, 0, v129, vcc
	global_load_dwordx4 v[72:75], v[0:1], off
	v_add_co_u32_e32 v0, vcc, 0x30000, v130
	s_nop 1
	v_addc_co_u32_e32 v1, vcc, 0, v131, vcc
	global_load_dwordx4 v[76:79], v[0:1], off
	v_add_co_u32_e32 v0, vcc, 0x2000, v126
	s_nop 1
	v_addc_co_u32_e32 v1, vcc, 0, v127, vcc
	global_load_dwordx4 v[104:107], v[0:1], off
	v_mad_u32_u24 v0, v34, s46, 0
	v_add_u32_e32 v108, v0, v147
	v_mad_u32_u24 v0, v33, s47, 0
	v_add_u32_e32 v141, v0, v144
	ds_read_b128 v[36:39], v141 offset:6656
	ds_read_b128 v[40:43], v141
	ds_read_b128 v[44:47], v141 offset:32
	ds_read_b128 v[48:51], v141 offset:6688
	ds_read_b128 v[52:55], v141 offset:64
	ds_read_b128 v[56:59], v141 offset:6720
	ds_read_b128 v[60:63], v141 offset:96
	ds_read_b128 v[110:113], v141 offset:6752
	ds_read_b128 v[114:117], v141 offset:128
	ds_read_b128 v[118:121], v141 offset:6784
	ds_read_b128 v[148:151], v141 offset:160
	ds_read_b128 v[152:155], v141 offset:6816
	s_setprio 1
	s_mov_b32 s22, s8
	s_mov_b32 s23, s8
	s_mov_b32 s9, s8
	s_mov_b32 s10, s8
	s_mov_b32 s11, s8
	s_mov_b32 s12, s8
	s_mov_b32 s13, s8
	s_mov_b32 s14, s8
	s_mov_b32 s15, s8
	s_mov_b32 s16, s8
	s_mov_b32 s17, s8
	s_mov_b32 s18, s8
	s_mov_b32 s19, s8
	s_mov_b32 s20, s8
	s_mov_b32 s21, s8
	s_waitcnt vmcnt(5)
	v_mov_b64_e32 v[30:31], s[22:23]
	v_mov_b64_e32 v[28:29], s[20:21]
	v_mov_b64_e32 v[26:27], s[18:19]
	v_mov_b64_e32 v[24:25], s[16:17]
	v_mov_b64_e32 v[22:23], s[14:15]
	v_mov_b64_e32 v[20:21], s[12:13]
	v_mov_b64_e32 v[18:19], s[10:11]
	v_mov_b64_e32 v[16:17], s[8:9]
	s_waitcnt lgkmcnt(10)
	s_nop 0
	v_mfma_f32_32x32x16_bf16 v[0:15], v[40:43], v[100:103], v[16:31]
	v_mfma_f32_32x32x16_bf16 v[16:31], v[36:39], v[100:103], v[16:31]
	s_waitcnt lgkmcnt(9)
	v_mfma_f32_32x32x16_bf16 v[0:15], v[44:47], v[96:99], v[0:15]
	s_waitcnt lgkmcnt(8)
	v_mfma_f32_32x32x16_bf16 v[16:31], v[48:51], v[96:99], v[16:31]
	s_waitcnt lgkmcnt(7)
	v_mfma_f32_32x32x16_bf16 v[0:15], v[52:55], v[92:95], v[0:15]
	s_waitcnt lgkmcnt(6)
	v_mfma_f32_32x32x16_bf16 v[16:31], v[56:59], v[92:95], v[16:31]
	s_waitcnt lgkmcnt(5)
	v_mfma_f32_32x32x16_bf16 v[0:15], v[60:63], v[88:91], v[0:15]
	s_waitcnt lgkmcnt(4)
	v_mfma_f32_32x32x16_bf16 v[16:31], v[110:113], v[88:91], v[16:31]
	s_waitcnt lgkmcnt(3)
	v_mfma_f32_32x32x16_bf16 v[0:15], v[114:117], v[84:87], v[0:15]
	s_waitcnt lgkmcnt(2)
	v_mfma_f32_32x32x16_bf16 v[16:31], v[118:121], v[84:87], v[16:31]
	s_waitcnt lgkmcnt(1)
	v_mfma_f32_32x32x16_bf16 v[0:15], v[148:151], v[80:83], v[0:15]
	s_waitcnt lgkmcnt(0)
	v_mfma_f32_32x32x16_bf16 v[16:31], v[152:155], v[80:83], v[16:31]
	s_setprio 0
	s_nop 10
	v_max_f32_e32 v32, v17, v17
	v_max_f32_e32 v35, v1, v1
	v_max_f32_e32 v32, v35, v32
	v_max_f32_e32 v35, v18, v18
	v_max_f32_e32 v36, v2, v2
	v_max_f32_e32 v35, v36, v35
	v_max_f32_e32 v36, v19, v19
	v_max_f32_e32 v37, v3, v3
	v_max3_f32 v32, v0, v16, v32
	v_max_f32_e32 v36, v37, v36
	v_max3_f32 v32, v32, v35, v36
	v_max_f32_e32 v35, v20, v20
	v_max_f32_e32 v36, v4, v4
	v_max_f32_e32 v35, v36, v35
	v_max_f32_e32 v36, v21, v21
	v_max_f32_e32 v37, v5, v5
	v_max_f32_e32 v36, v37, v36
	v_max3_f32 v32, v32, v35, v36
	v_max_f32_e32 v35, v22, v22
	v_max_f32_e32 v36, v6, v6
	v_max_f32_e32 v35, v36, v35
	v_max_f32_e32 v36, v23, v23
	v_max_f32_e32 v37, v7, v7
	v_max_f32_e32 v36, v37, v36
	v_max3_f32 v32, v32, v35, v36
	v_max_f32_e32 v35, v24, v24
	v_max_f32_e32 v36, v8, v8
	v_max_f32_e32 v35, v36, v35
	v_max_f32_e32 v36, v25, v25
	v_max_f32_e32 v37, v9, v9
	v_max_f32_e32 v36, v37, v36
	v_max3_f32 v32, v32, v35, v36
	v_max_f32_e32 v35, v26, v26
	v_max_f32_e32 v36, v10, v10
	v_max_f32_e32 v35, v36, v35
	v_max_f32_e32 v36, v27, v27
	v_max_f32_e32 v37, v11, v11
	v_max_f32_e32 v36, v37, v36
	v_max3_f32 v32, v32, v35, v36
	v_max_f32_e32 v35, v28, v28
	v_max_f32_e32 v36, v12, v12
	v_max_f32_e32 v35, v36, v35
	v_max_f32_e32 v36, v29, v29
	v_max_f32_e32 v37, v13, v13
	v_max_f32_e32 v36, v37, v36
	v_max3_f32 v32, v32, v35, v36
	v_max_f32_e32 v35, v30, v30
	v_max_f32_e32 v36, v14, v14
	v_max_f32_e32 v35, v36, v35
	v_max_f32_e32 v36, v31, v31
	v_max_f32_e32 v37, v15, v15
	v_max_f32_e32 v36, v37, v36
	v_max3_f32 v32, v32, v35, v36
	ds_bpermute_b32 v35, v140, v32
	s_waitcnt lgkmcnt(0)
; DI f32x16 mfma32(bf16x8 a, bf16x8 b, f32x16 c) { return __builtin_amdgcn_mfma_f32_32x32x16_bf16(a, b, c, 0, 0, 0); }
; DI bool softmax_tile(f32x16& s0, f32x16& s1, float& m, float& l, float& alpha, bf16x8* pf, int lane, bool first, bool check) {
;     ...
;     m += mx;
; #pragma unroll
;     for (int i = 0; i < 16; ++i) { s0[i] -= mx; s1[i] -= mx; }
;   }
;   float sum = 0.f;
; #pragma unroll
;   for (int i = 0; i < 16; ++i) { s0[i] = __builtin_amdgcn_exp2f(s0[i]); sum += s0[i]; }
; #pragma unroll
;   for (int i = 0; i < 16; ++i) { s1[i] = __builtin_amdgcn_exp2f(s1[i]); sum += s1[i]; }
;   l += sum;
;   pf[0] = pack8(s0, 0); pf[1] = pack8(s0, 8); pf[2] = pack8(s1, 0); pf[3] = pack8(s1, 8);
;   alpha = 1.f;
;   if (!check) return false;
;   const float rsum = sum + shx(sum, 32, lane);
;   const bool trig = rsum > 65536.f;
;   const bool resc = (__builtin_amdgcn_ballot_w64(trig) != 0ull);
;   alpha = 1.f;
;   if (resc) {
;     const float d = trig ? (float)(__builtin_amdgcn_frexp_expf(rsum) - 7) : 0.f;
;     alpha = __builtin_amdgcn_exp2f(-d);
;     m += d; l *= alpha;
;   }
;   return resc;
; }
; DI void attn_mla_unit(const Params& p, int b, int h, int qb, char* smem, bool pre, int nh, bool has_next) {
;     ...
;       float alpha; bf16x8 pf[4];
;       const bool resc = softmax_tile(s0, s1, m, l, alpha, pf, lane, (kt == 0) && (sub == 0), (sub == 0) && ((kt & 3) == 0));
;       {
;         bf16x8 vf[8];
; #pragma unroll
;         for (int s = 0; s < 4; ++s) { vf[2 * s] = ld_vfrag_tr(vs, vbase, VR, sub * 64 + 16 * s, 0); vf[2 * s + 1] = ld_vfrag_tr(vs, vbase, VR, sub * 64 + 16 * s, 32); }
;         __builtin_amdgcn_sched_barrier(0); __builtin_amdgcn_s_setprio(1);
; #pragma unroll
;         for (int s = 0; s < 4; ++s) { O0 = mfma32(vf[2 * s], pf[s], O0); O1 = mfma32(vf[2 * s + 1], pf[s], O1); }
;       __builtin_amdgcn_s_setprio(0);
; }
;       if (resc) { scale16(O0, alpha); scale16(O1, alpha); }
	v_max_f32_e32 v35, v35, v35
	v_max_f32_e32 v35, v32, v35
	v_sub_f32_e32 v0, v0, v35
	v_sub_f32_e32 v1, v1, v35
	v_exp_f32_e32 v0, v0
	v_sub_f32_e32 v2, v2, v35
	v_exp_f32_e32 v1, v1
	v_sub_f32_e32 v3, v3, v35
	v_exp_f32_e32 v2, v2
	v_sub_f32_e32 v4, v4, v35
	v_exp_f32_e32 v3, v3
	v_sub_f32_e32 v5, v5, v35
	v_add_f32_e32 v32, 0, v0
	v_exp_f32_e32 v4, v4
	v_sub_f32_e32 v6, v6, v35
	v_add_f32_e32 v32, v1, v32
	v_exp_f32_e32 v5, v5
	v_sub_f32_e32 v7, v7, v35
	v_add_f32_e32 v32, v2, v32
	v_exp_f32_e32 v6, v6
	v_sub_f32_e32 v8, v8, v35
	v_add_f32_e32 v32, v3, v32
	v_exp_f32_e32 v7, v7
	v_sub_f32_e32 v9, v9, v35
	v_add_f32_e32 v32, v4, v32
	v_exp_f32_e32 v8, v8
	v_sub_f32_e32 v10, v10, v35
	v_add_f32_e32 v32, v5, v32
	v_exp_f32_e32 v9, v9
	v_sub_f32_e32 v11, v11, v35
	v_add_f32_e32 v32, v6, v32
	v_exp_f32_e32 v10, v10
	v_sub_f32_e32 v12, v12, v35
	v_add_f32_e32 v32, v7, v32
	v_exp_f32_e32 v11, v11
	v_sub_f32_e32 v13, v13, v35
	v_add_f32_e32 v32, v8, v32
	v_exp_f32_e32 v12, v12
	v_sub_f32_e32 v14, v14, v35
	v_add_f32_e32 v32, v9, v32
	v_exp_f32_e32 v13, v13
	v_sub_f32_e32 v15, v15, v35
	v_add_f32_e32 v32, v10, v32
	v_exp_f32_e32 v14, v14
	v_sub_f32_e32 v16, v16, v35
	v_add_f32_e32 v32, v11, v32
	v_exp_f32_e32 v15, v15
	v_sub_f32_e32 v17, v17, v35
	v_add_f32_e32 v32, v12, v32
	v_exp_f32_e32 v16, v16
	v_sub_f32_e32 v18, v18, v35
	v_add_f32_e32 v32, v13, v32
	v_exp_f32_e32 v17, v17
	v_sub_f32_e32 v19, v19, v35
	v_add_f32_e32 v32, v14, v32
	v_exp_f32_e32 v18, v18
	v_sub_f32_e32 v20, v20, v35
	v_add_f32_e32 v32, v15, v32
	v_exp_f32_e32 v19, v19
	v_sub_f32_e32 v21, v21, v35
	v_add_f32_e32 v32, v16, v32
	v_exp_f32_e32 v20, v20
	v_sub_f32_e32 v22, v22, v35
	v_add_f32_e32 v32, v17, v32
	v_exp_f32_e32 v21, v21
	v_sub_f32_e32 v23, v23, v35
	v_add_f32_e32 v32, v18, v32
	v_exp_f32_e32 v22, v22
	v_sub_f32_e32 v24, v24, v35
	v_add_f32_e32 v32, v19, v32
	v_exp_f32_e32 v23, v23
	v_sub_f32_e32 v25, v25, v35
	v_add_f32_e32 v32, v20, v32
	v_exp_f32_e32 v24, v24
	v_sub_f32_e32 v26, v26, v35
	v_add_f32_e32 v32, v21, v32
	v_exp_f32_e32 v25, v25
	v_sub_f32_e32 v27, v27, v35
	v_add_f32_e32 v32, v22, v32
	v_exp_f32_e32 v26, v26
	v_sub_f32_e32 v28, v28, v35
	v_add_f32_e32 v32, v23, v32
	v_exp_f32_e32 v27, v27
	v_sub_f32_e32 v29, v29, v35
	v_add_f32_e32 v32, v24, v32
	v_exp_f32_e32 v28, v28
	v_sub_f32_e32 v30, v30, v35
	v_add_f32_e32 v32, v25, v32
	v_exp_f32_e32 v29, v29
	v_sub_f32_e32 v31, v31, v35
	v_add_f32_e32 v32, v26, v32
	v_exp_f32_e32 v30, v30
	v_add_f32_e32 v32, v27, v32
	v_exp_f32_e32 v31, v31
	v_add_f32_e32 v32, v28, v32
	v_add_f32_e32 v32, v29, v32
	v_add_f32_e32 v32, v30, v32
	v_add_f32_e32 v36, v31, v32
	v_cvt_pk_bf16_f32 v0, v0, v1
	v_cvt_pk_bf16_f32 v1, v2, v3
	v_cvt_pk_bf16_f32 v2, v4, v5
	ds_bpermute_b32 v4, v140, v36
	v_cvt_pk_bf16_f32 v3, v6, v7
	v_cvt_pk_bf16_f32 v38, v8, v9
	v_cvt_pk_bf16_f32 v39, v10, v11
	v_cvt_pk_bf16_f32 v40, v12, v13
	s_waitcnt lgkmcnt(0)
	v_add_f32_e32 v4, v36, v4
	v_cmp_lt_f32_e32 vcc, s88, v4
	v_frexp_exp_i32_f32_e32 v4, v4
	v_add_u32_e32 v4, -7, v4
	v_cvt_f32_i32_e32 v4, v4
	s_cmp_eq_u64 vcc, 0
	s_cselect_b64 s[2:3], -1, 0
	v_cvt_pk_bf16_f32 v41, v14, v15
	v_cndmask_b32_e32 v37, 0, v4, vcc
	ds_read_b64_tr_b16 v[4:5], v108 offset:26624
	ds_read_b64_tr_b16 v[6:7], v108 offset:28160
	ds_read_b64_tr_b16 v[8:9], v108 offset:26688
	ds_read_b64_tr_b16 v[10:11], v108 offset:28224
	ds_read_b64_tr_b16 v[50:51], v108 offset:29696
	ds_read_b64_tr_b16 v[52:53], v108 offset:31232
	ds_read_b64_tr_b16 v[54:55], v108 offset:29760
	ds_read_b64_tr_b16 v[56:57], v108 offset:31296
	ds_read_b64_tr_b16 v[58:59], v108 offset:32768
	ds_read_b64_tr_b16 v[60:61], v108 offset:34304
	ds_read_b64_tr_b16 v[110:111], v108 offset:32832
	ds_read_b64_tr_b16 v[112:113], v108 offset:34368
	ds_read_b64_tr_b16 v[114:115], v108 offset:35840
	ds_read_b64_tr_b16 v[116:117], v108 offset:37376
	ds_read_b64_tr_b16 v[118:119], v108 offset:35904
	ds_read_b64_tr_b16 v[120:121], v108 offset:37440
	v_exp_f32_e64 v32, -v37
	v_cvt_pk_bf16_f32 v42, v16, v17
	v_cvt_pk_bf16_f32 v43, v18, v19
	v_cvt_pk_bf16_f32 v44, v20, v21
	v_cvt_pk_bf16_f32 v45, v22, v23
	v_cvt_pk_bf16_f32 v46, v24, v25
	v_cvt_pk_bf16_f32 v47, v26, v27
	v_cvt_pk_bf16_f32 v48, v28, v29
	v_cvt_pk_bf16_f32 v49, v30, v31
	s_setprio 1
	s_waitcnt lgkmcnt(14)
	v_mfma_f32_32x32x16_bf16 v[16:31], v[4:7], v[0:3], 0
	s_waitcnt lgkmcnt(12)
	v_mfma_f32_32x32x16_bf16 v[0:15], v[8:11], v[0:3], 0
	s_waitcnt lgkmcnt(10)
	v_mfma_f32_32x32x16_bf16 v[16:31], v[50:53], v[38:41], v[16:31]
	s_waitcnt lgkmcnt(8)
	v_mfma_f32_32x32x16_bf16 v[0:15], v[54:57], v[38:41], v[0:15]
	s_waitcnt lgkmcnt(6)
	v_mfma_f32_32x32x16_bf16 v[16:31], v[58:61], v[42:45], v[16:31]
	s_waitcnt lgkmcnt(4)
	v_mfma_f32_32x32x16_bf16 v[0:15], v[110:113], v[42:45], v[0:15]
	s_waitcnt lgkmcnt(2)
	v_mfma_f32_32x32x16_bf16 v[16:31], v[114:117], v[46:49], v[16:31]
	s_waitcnt lgkmcnt(0)
	v_mfma_f32_32x32x16_bf16 v[0:15], v[118:121], v[46:49], v[0:15]
	s_setprio 0
	s_cbranch_vccz .LBB0_1481
	s_nop 7
	v_mul_f32_e32 v30, v30, v32
	v_mul_f32_e32 v31, v31, v32
	v_mul_f32_e32 v28, v28, v32
	v_mul_f32_e32 v29, v29, v32
	v_mul_f32_e32 v26, v26, v32
	v_mul_f32_e32 v27, v27, v32
	v_mul_f32_e32 v24, v24, v32
	v_mul_f32_e32 v25, v25, v32
	v_mul_f32_e32 v22, v22, v32
	v_mul_f32_e32 v23, v23, v32
	v_mul_f32_e32 v20, v20, v32
	v_mul_f32_e32 v21, v21, v32
	v_mul_f32_e32 v18, v18, v32
	v_mul_f32_e32 v19, v19, v32
	v_mul_f32_e32 v16, v16, v32
	v_mul_f32_e32 v17, v17, v32
	v_mul_f32_e32 v14, v14, v32
	v_mul_f32_e32 v15, v15, v32
	v_mul_f32_e32 v12, v12, v32
	v_mul_f32_e32 v13, v13, v32
	v_mul_f32_e32 v10, v10, v32
	v_mul_f32_e32 v11, v11, v32
	v_mul_f32_e32 v8, v8, v32
	v_mul_f32_e32 v9, v9, v32
	v_mul_f32_e32 v6, v6, v32
	v_mul_f32_e32 v7, v7, v32
	v_mul_f32_e32 v4, v4, v32
	v_mul_f32_e32 v5, v5, v32
	v_mul_f32_e32 v2, v2, v32
	v_mul_f32_e32 v3, v3, v32
	v_mul_f32_e32 v0, v0, v32
	v_mul_f32_e32 v1, v1, v32

; DI void attn_na_unit(const Params& p, int li, int b, int r, int hp, char* smem) {
;     ...
;   const float lt = l + shx(l, 32, lane);
;   const float inv = 1.f / lt;
;   u16* op = o + (size_t)qrow * 1024 + 512 + head * 64 + 4 * hh;
; #pragma unroll
;   for (int i4 = 0; i4 < 4; ++i4) {
;     st_bf4(op + 8 * i4, (f32x4){O0[4 * i4], O0[4 * i4 + 1], O0[4 * i4 + 2], O0[4 * i4 + 3]}, inv);
;     st_bf4(op + 32 + 8 * i4, (f32x4){O1[4 * i4], O1[4 * i4 + 1], O1[4 * i4 + 2], O1[4 * i4 + 3]}, inv);
;   }
; __global__ void __launch_bounds__(512) mega(Params p, int ph_lo, int ph_hi) {
;     ...
;           for (int up = jx; up < 128; up += nx) { const int u = 2 * up + half; attn_na_unit(q, li, xcd, u >> 2, u & 3, sm); }
.LBB0_1500:
	ds_bpermute_b32 v34, v124, v127
	v_lshlrev_b64 v[32:33], 11, v[112:113]
	v_lshlrev_b32_e32 v144, 1, v126
	s_waitcnt lgkmcnt(0)
	v_add_f32_e32 v34, v127, v34
	v_div_scale_f32 v35, s[2:3], v34, v34, 1.0
	v_rcp_f32_e32 v36, v35
	v_div_scale_f32 v37, vcc, 1.0, v34, 1.0
	v_readlane_b32 s2, v237, 12
	v_fma_f32 v38, -v35, v36, 1.0
	v_fmac_f32_e32 v36, v38, v36
	v_mul_f32_e32 v38, v37, v36
	v_fma_f32 v39, -v35, v38, v37
	v_fmac_f32_e32 v38, v39, v36
	v_readlane_b32 s3, v237, 13
	v_fma_f32 v35, -v35, v38, v37
	v_div_fmas_f32 v35, v35, v36, v38
	v_lshl_add_u64 v[32:33], s[2:3], 0, v[32:33]
	v_div_fixup_f32 v34, v35, v34, 1.0
	v_lshl_add_u64 v[32:33], v[32:33], 0, v[144:145]
	v_lshlrev_b32_e32 v144, 1, v122
	v_lshl_add_u64 v[32:33], v[32:33], 0, v[144:145]
	s_mov_b64 s[2:3], 0x63a8500
	v_mul_f32_e32 v0, v0, v34
	v_mul_f32_e32 v1, v1, v34
	v_mul_f32_e32 v2, v2, v34
	v_mul_f32_e32 v3, v3, v34
	v_lshl_add_u64 v[36:37], v[32:33], 0, s[2:3]
	v_cvt_pk_bf16_f32 v0, v0, v1
	v_cvt_pk_bf16_f32 v1, v2, v3
	global_store_dwordx2 v[36:37], v[0:1], off offset:64
	v_mul_f32_e32 v0, v20, v34
	v_mul_f32_e32 v1, v21, v34
	v_mul_f32_e32 v2, v22, v34
	v_mul_f32_e32 v3, v23, v34
	v_cvt_pk_bf16_f32 v0, v0, v1
	v_cvt_pk_bf16_f32 v1, v2, v3
	global_store_dwordx2 v[36:37], v[0:1], off offset:16
	v_mul_f32_e32 v0, v4, v34
	v_mul_f32_e32 v1, v5, v34
	v_mul_f32_e32 v2, v6, v34
	v_mul_f32_e32 v3, v7, v34
	v_cvt_pk_bf16_f32 v0, v0, v1
	v_cvt_pk_bf16_f32 v1, v2, v3
	global_store_dwordx2 v[36:37], v[0:1], off offset:80
	v_mul_f32_e32 v0, v24, v34
	v_mul_f32_e32 v1, v25, v34
	v_mul_f32_e32 v2, v26, v34
	v_mul_f32_e32 v3, v27, v34
	v_cvt_pk_bf16_f32 v0, v0, v1
	v_cvt_pk_bf16_f32 v1, v2, v3
	global_store_dwordx2 v[36:37], v[0:1], off offset:32
	v_mul_f32_e32 v0, v8, v34
	v_mul_f32_e32 v1, v9, v34
	v_mul_f32_e32 v2, v10, v34
	v_mul_f32_e32 v3, v11, v34
	v_cvt_pk_bf16_f32 v0, v0, v1
	v_cvt_pk_bf16_f32 v1, v2, v3
	v_mul_f32_e32 v16, v16, v34
	v_mul_f32_e32 v17, v17, v34
	v_mul_f32_e32 v18, v18, v34
	v_mul_f32_e32 v19, v19, v34
	s_mov_b32 s2, 0x63a8000
	global_store_dwordx2 v[36:37], v[0:1], off offset:96
	v_mul_f32_e32 v0, v28, v34
	v_mul_f32_e32 v1, v29, v34
	v_mul_f32_e32 v2, v30, v34
	v_mul_f32_e32 v3, v31, v34
	v_cvt_pk_bf16_f32 v16, v16, v17
	v_cvt_pk_bf16_f32 v17, v18, v19
	v_add_co_u32_e32 v18, vcc, s2, v32
	v_cvt_pk_bf16_f32 v0, v0, v1
	v_cvt_pk_bf16_f32 v1, v2, v3
	v_readlane_b32 s2, v237, 2
	global_store_dwordx2 v[36:37], v[0:1], off offset:48
	v_mul_f32_e32 v0, v12, v34
	v_mul_f32_e32 v1, v13, v34
	v_mul_f32_e32 v2, v14, v34
	v_mul_f32_e32 v3, v15, v34
	s_add_i32 s89, s89, s2
	v_readlane_b32 s2, v238, 43
	v_addc_co_u32_e32 v19, vcc, 0, v33, vcc
	v_cvt_pk_bf16_f32 v0, v0, v1
	v_cvt_pk_bf16_f32 v1, v2, v3
	s_cmpk_lt_u32 s89, 0x80
	v_subrev_u16_e32 v121, s2, v121
	global_store_dwordx2 v[18:19], v[16:17], off offset:1280
	global_store_dwordx2 v[36:37], v[0:1], off offset:112
	s_cbranch_scc0 .LBB0_1575

; DI bool softmax_tile(f32x16& s0, f32x16& s1, float& m, float& l, float& alpha, bf16x8* pf, int lane, bool first, bool check) {
;   if (first) {
;     float mx = fmaxf(s0[0], s1[0]);
; #pragma unroll
;     for (int i = 1; i < 16; ++i) mx = fmaxf(mx, fmaxf(s0[i], s1[i]));
;     mx = fmaxf(mx, shx(mx, 32, lane));
;     m += mx;
; #pragma unroll
;     for (int i = 0; i < 16; ++i) { s0[i] -= mx; s1[i] -= mx; }
;   }
;   float sum = 0.f;
; #pragma unroll
;   for (int i = 0; i < 16; ++i) { s0[i] = __builtin_amdgcn_exp2f(s0[i]); sum += s0[i]; }
; #pragma unroll
;   for (int i = 0; i < 16; ++i) { s1[i] = __builtin_amdgcn_exp2f(s1[i]); sum += s1[i]; }
; DI void attn_na_unit(const Params& p, int li, int b, int r, int hp, char* smem) {
;     ...
;     const int drow = rs + kt - r + 7;
;     const float* trow = tab + hs * 465 + drow * 31;
; #pragma unroll
;     for (int i = 0; i < 16; ++i) {
;       const int kc0 = (i & 3) + 8 * (i >> 2) + 4 * hh;
;       const int kc1 = kc0 + 32;
;       const bool v0 = (unsigned)(kc0 - cs) < 16u;
;       const bool v1 = (unsigned)(kc1 - cs) < 16u;
;       const int d0 = v0 ? (kc0 - wq + 15) : 0;
;       const int d1 = v1 ? (kc1 - wq + 15) : 0;
;       const float b0 = trow[d0], b1 = trow[d1];
;       s0[i] = v0 ? s0[i] + b0 : -1e30f;
;       s1[i] = v1 ? s1[i] + b1 : -1e30f;
;     }
;     float alpha; bf16x8 pf[4];
;     const bool resc = softmax_tile(s0, s1, m, l, alpha, pf, lane, kt == 0, true);
.LBB0_1535:
	s_or_b64 exec, exec, s[6:7]
	v_and_b32_e32 v31, 63, v35
	v_bfe_u32 v34, v35, 2, 2
	v_lshrrev_b32_e32 v50, 3, v35
	v_and_or_b32 v34, v50, 4, v34
	v_and_b32_e32 v50, 16, v35
	v_lshlrev_b32_e32 v31, 2, v31
	s_waitcnt lgkmcnt(14)
	v_add_f32_e32 v1, v1, v115
	v_and_or_b32 v50, v31, 12, v50
	v_mul_u32_u24_e32 v34, 0x140, v34
	s_waitcnt lgkmcnt(12)
	v_add_f32_e32 v3, v3, v125
	v_add_f32_e32 v2, v2, v124
	v_cndmask_b32_e64 v1, v195, v1, s[92:93]
	v_add_f32_e32 v0, v0, v62
	v_lshlrev_b32_e32 v50, 1, v50
	s_waitcnt lgkmcnt(0)
	v_add_f32_e32 v15, v15, v30
	v_max_f32_e32 v30, v60, v60
	v_cndmask_b32_e64 v3, v195, v3, s[72:73]
	v_cndmask_b32_e64 v2, v195, v2, s[94:95]
	v_cndmask_b32_e64 v0, v195, v0, s[78:79]
	v_xor_b32_e32 v124, 0x80, v31
	v_add3_u32 v31, v117, v50, v34
	v_max_f32_e32 v30, v30, v1
	v_max_f32_e32 v34, v17, v17
	v_max_f32_e32 v50, v16, v16
	v_add_f32_e32 v5, v5, v127
	v_add_f32_e32 v4, v4, v126
	v_max3_f32 v30, v61, v0, v30
	v_max_f32_e32 v34, v34, v2
	v_max_f32_e32 v50, v50, v3
	v_cndmask_b32_e64 v5, v195, v5, s[74:75]
	v_cndmask_b32_e64 v4, v195, v4, s[80:81]
	v_max3_f32 v30, v30, v34, v50
	v_max_f32_e32 v34, v19, v19
	v_max_f32_e32 v50, v18, v18
	v_add_f32_e32 v7, v7, v129
	v_add_f32_e32 v6, v6, v128
	v_max_f32_e32 v34, v34, v4
	v_max_f32_e32 v50, v50, v5
	v_cndmask_b32_e64 v7, v195, v7, s[48:49]
	v_cndmask_b32_e64 v6, v195, v6, s[58:59]
	v_max3_f32 v30, v30, v34, v50
	v_max_f32_e32 v34, v21, v21
	v_max_f32_e32 v50, v20, v20
	v_add_f32_e32 v9, v9, v131
	v_add_f32_e32 v8, v8, v130
	v_max_f32_e32 v34, v34, v6
	v_max_f32_e32 v50, v50, v7
	v_cndmask_b32_e64 v9, v195, v9, s[62:63]
	v_cndmask_b32_e64 v8, v195, v8, s[50:51]
	v_max3_f32 v30, v30, v34, v50
	v_max_f32_e32 v34, v23, v23
	v_max_f32_e32 v50, v22, v22
	v_add_f32_e32 v11, v11, v133
	v_add_f32_e32 v10, v10, v132
	v_max_f32_e32 v34, v34, v8
	v_max_f32_e32 v50, v50, v9
	v_cndmask_b32_e64 v11, v195, v11, s[44:45]
	v_cndmask_b32_e64 v10, v195, v10, s[38:39]
	v_max3_f32 v30, v30, v34, v50
	v_max_f32_e32 v34, v25, v25
	v_max_f32_e32 v50, v24, v24
	v_add_f32_e32 v13, v13, v135
	v_add_f32_e32 v12, v12, v134
	v_max_f32_e32 v34, v34, v10
	v_max_f32_e32 v50, v50, v11
	v_cndmask_b32_e64 v13, v195, v13, s[82:83]
	v_cndmask_b32_e64 v12, v195, v12, s[56:57]
	v_max3_f32 v30, v30, v34, v50
	v_max_f32_e32 v34, v27, v27
	v_max_f32_e32 v50, v26, v26
	v_add_f32_e32 v14, v14, v136
	v_max_f32_e32 v34, v34, v12
	v_max_f32_e32 v50, v50, v13
	v_cndmask_b32_e64 v14, v195, v14, s[84:85]
	v_cndmask_b32_e64 v15, v195, v15, s[2:3]
	v_max3_f32 v30, v30, v34, v50
	v_max_f32_e32 v34, v28, v28
	v_max_f32_e32 v50, v29, v29
	v_max_f32_e32 v34, v34, v14
	v_max_f32_e32 v50, v50, v15
	v_max3_f32 v30, v30, v34, v50
	ds_bpermute_b32 v34, v124, v30
	v_add_u32_e32 v125, v31, v42
	s_waitcnt lgkmcnt(0)
	v_max_f32_e32 v34, v34, v34
	v_max_f32_e32 v50, v30, v34
	v_sub_f32_e32 v30, v61, v50
	v_sub_f32_e32 v34, v60, v50
	v_exp_f32_e32 v30, v30
	v_sub_f32_e32 v17, v17, v50
	v_exp_f32_e32 v34, v34
	v_sub_f32_e32 v16, v16, v50
	v_exp_f32_e32 v17, v17
	v_sub_f32_e32 v19, v19, v50
	v_exp_f32_e32 v16, v16
	v_sub_f32_e32 v18, v18, v50
	v_add_f32_e32 v60, 0, v30
	v_exp_f32_e32 v19, v19
	v_sub_f32_e32 v21, v21, v50
	v_add_f32_e32 v60, v34, v60
	v_exp_f32_e32 v18, v18
	v_sub_f32_e32 v20, v20, v50
	v_add_f32_e32 v60, v17, v60
	v_exp_f32_e32 v21, v21
	v_sub_f32_e32 v23, v23, v50
	v_add_f32_e32 v60, v16, v60
	v_exp_f32_e32 v20, v20
	v_sub_f32_e32 v22, v22, v50
	v_add_f32_e32 v60, v19, v60
	v_exp_f32_e32 v23, v23
	v_sub_f32_e32 v25, v25, v50
	v_add_f32_e32 v60, v18, v60
	v_exp_f32_e32 v22, v22
	v_sub_f32_e32 v24, v24, v50
	v_add_f32_e32 v60, v21, v60
	v_exp_f32_e32 v25, v25
	v_sub_f32_e32 v27, v27, v50
	v_add_f32_e32 v60, v20, v60
	v_exp_f32_e32 v24, v24
	v_sub_f32_e32 v26, v26, v50
	v_add_f32_e32 v60, v23, v60
	v_exp_f32_e32 v27, v27
	v_sub_f32_e32 v28, v28, v50
	v_add_f32_e32 v60, v22, v60
	v_exp_f32_e32 v26, v26
	v_sub_f32_e32 v29, v29, v50
	v_add_f32_e32 v60, v25, v60
	v_exp_f32_e32 v28, v28
	v_sub_f32_e32 v0, v0, v50
	v_add_f32_e32 v60, v24, v60
	v_exp_f32_e32 v29, v29
	v_sub_f32_e32 v1, v1, v50
	v_add_f32_e32 v60, v27, v60
	v_exp_f32_e32 v61, v0
	v_sub_f32_e32 v2, v2, v50
	v_add_f32_e32 v60, v26, v60
	v_exp_f32_e32 v62, v1
	v_sub_f32_e32 v3, v3, v50
	v_add_f32_e32 v60, v28, v60
	v_exp_f32_e32 v63, v2
	v_sub_f32_e32 v4, v4, v50
	v_add_f32_e32 v60, v29, v60
	v_exp_f32_e32 v114, v3
	v_sub_f32_e32 v5, v5, v50
	v_add_f32_e32 v0, v61, v60
	v_exp_f32_e32 v4, v4
	v_sub_f32_e32 v6, v6, v50
	v_add_f32_e32 v0, v62, v0
	v_exp_f32_e32 v5, v5
	v_sub_f32_e32 v7, v7, v50
	v_add_f32_e32 v0, v63, v0
	v_exp_f32_e32 v6, v6
	v_sub_f32_e32 v8, v8, v50
	v_add_f32_e32 v0, v114, v0
	v_exp_f32_e32 v7, v7
	v_sub_f32_e32 v9, v9, v50
	v_add_f32_e32 v0, v4, v0
	v_exp_f32_e32 v8, v8
	v_sub_f32_e32 v10, v10, v50
	v_add_f32_e32 v0, v5, v0
	v_exp_f32_e32 v9, v9
	v_sub_f32_e32 v11, v11, v50
	v_add_f32_e32 v0, v6, v0
	v_exp_f32_e32 v10, v10
	v_sub_f32_e32 v12, v12, v50
	v_add_f32_e32 v0, v7, v0
	v_exp_f32_e32 v11, v11
	v_sub_f32_e32 v13, v13, v50
	v_add_f32_e32 v0, v8, v0
	v_exp_f32_e32 v12, v12
	v_sub_f32_e32 v14, v14, v50
	v_add_f32_e32 v0, v9, v0
	v_exp_f32_e32 v13, v13
	v_sub_f32_e32 v15, v15, v50
	v_add_f32_e32 v0, v10, v0
	v_exp_f32_e32 v14, v14
	v_add_f32_e32 v0, v11, v0
	v_exp_f32_e32 v15, v15
	v_add_f32_e32 v0, v12, v0
	v_add_f32_e32 v0, v13, v0
	v_add_f32_e32 v0, v14, v0
	v_add_f32_e32 v60, v15, v0
	v_cvt_pk_bf16_f32 v132, v4, v5
	ds_bpermute_b32 v4, v124, v60
	v_cvt_pk_bf16_f32 v130, v61, v62
	v_cvt_pk_bf16_f32 v133, v6, v7
	v_cvt_pk_bf16_f32 v134, v8, v9
	v_cvt_pk_bf16_f32 v135, v10, v11
	s_waitcnt lgkmcnt(0)
; DI f32x16 mfma32(bf16x8 a, bf16x8 b, f32x16 c) { return __builtin_amdgcn_mfma_f32_32x32x16_bf16(a, b, c, 0, 0, 0); }
; DI bool softmax_tile(f32x16& s0, f32x16& s1, float& m, float& l, float& alpha, bf16x8* pf, int lane, bool first, bool check) {
;     ...
;   l += sum;
;   pf[0] = pack8(s0, 0); pf[1] = pack8(s0, 8); pf[2] = pack8(s1, 0); pf[3] = pack8(s1, 8);
;   alpha = 1.f;
;   if (!check) return false;
;   const float rsum = sum + shx(sum, 32, lane);
;   const bool trig = rsum > 65536.f;
;   const bool resc = (__builtin_amdgcn_ballot_w64(trig) != 0ull);
;   alpha = 1.f;
;   if (resc) {
;     const float d = trig ? (float)(__builtin_amdgcn_frexp_expf(rsum) - 7) : 0.f;
;     alpha = __builtin_amdgcn_exp2f(-d);
;     m += d; l *= alpha;
;   }
;   return resc;
; }
; DI void attn_na_unit(const Params& p, int li, int b, int r, int hp, char* smem) {
;     ...
;     float alpha; bf16x8 pf[4];
;     const bool resc = softmax_tile(s0, s1, m, l, alpha, pf, lane, kt == 0, true);
;     {
;       bf16x8 vf[8];
; #pragma unroll
;       for (int s = 0; s < 4; ++s) { vf[2 * s] = ld_vfrag_tr(vs, vbase, VR, 16 * s, hs * 64); vf[2 * s + 1] = ld_vfrag_tr(vs, vbase, VR, 16 * s, hs * 64 + 32); }
;       __builtin_amdgcn_sched_barrier(0); __builtin_amdgcn_s_setprio(1);
; #pragma unroll
;       for (int s = 0; s < 4; ++s) { O0 = mfma32(vf[2 * s], pf[s], O0); O1 = mfma32(vf[2 * s + 1], pf[s], O1); }
;     __builtin_amdgcn_s_setprio(0);
; }
;     if (resc) { scale16(O0, alpha); scale16(O1, alpha); }
	v_add_f32_e32 v4, v60, v4
	v_cmp_lt_f32_e32 vcc, s88, v4
	v_frexp_exp_i32_f32_e32 v4, v4
	v_add_u32_e32 v4, -7, v4
	v_cvt_f32_i32_e32 v4, v4
	v_cvt_pk_bf16_f32 v0, v30, v34
	s_cmp_eq_u64 vcc, 0
	v_cvt_pk_bf16_f32 v1, v17, v16
	v_cndmask_b32_e32 v61, 0, v4, vcc
	ds_read_b64_tr_b16 v[4:5], v125 offset:17408
	ds_read_b64_tr_b16 v[6:7], v125 offset:19968
	ds_read_b64_tr_b16 v[8:9], v125 offset:17472
	ds_read_b64_tr_b16 v[10:11], v125 offset:20032
	ds_read_b64_tr_b16 v[138:139], v125 offset:22528
	ds_read_b64_tr_b16 v[140:141], v125 offset:25088
	ds_read_b64_tr_b16 v[146:147], v125 offset:22592
	ds_read_b64_tr_b16 v[148:149], v125 offset:25152
	ds_read_b64_tr_b16 v[150:151], v125 offset:27648
	ds_read_b64_tr_b16 v[152:153], v125 offset:30208
	ds_read_b64_tr_b16 v[154:155], v125 offset:27712
	ds_read_b64_tr_b16 v[156:157], v125 offset:30272
	ds_read_b64_tr_b16 v[158:159], v125 offset:32768
	ds_read_b64_tr_b16 v[160:161], v125 offset:35328
	ds_read_b64_tr_b16 v[162:163], v125 offset:32832
	ds_read_b64_tr_b16 v[164:165], v125 offset:35392
	v_exp_f32_e64 v34, -v61
	v_cvt_pk_bf16_f32 v2, v19, v18
	v_cvt_pk_bf16_f32 v3, v21, v20
	s_cselect_b64 s[6:7], -1, 0
	v_cvt_pk_bf16_f32 v126, v23, v22
	v_cvt_pk_bf16_f32 v127, v25, v24
	v_cvt_pk_bf16_f32 v128, v27, v26
	v_cvt_pk_bf16_f32 v129, v28, v29
	v_cvt_pk_bf16_f32 v131, v63, v114
	v_cvt_pk_bf16_f32 v136, v12, v13
	v_cvt_pk_bf16_f32 v137, v14, v15
	s_setprio 1
	s_waitcnt lgkmcnt(14)
	v_mfma_f32_32x32x16_bf16 v[16:31], v[4:7], v[0:3], 0
	s_waitcnt lgkmcnt(12)
	v_mfma_f32_32x32x16_bf16 v[0:15], v[8:11], v[0:3], 0
	s_waitcnt lgkmcnt(10)
	v_mfma_f32_32x32x16_bf16 v[16:31], v[138:141], v[126:129], v[16:31]
	s_waitcnt lgkmcnt(8)
	v_mfma_f32_32x32x16_bf16 v[0:15], v[146:149], v[126:129], v[0:15]
	s_waitcnt lgkmcnt(6)
	v_mfma_f32_32x32x16_bf16 v[16:31], v[150:153], v[130:133], v[16:31]
	s_waitcnt lgkmcnt(4)
	v_mfma_f32_32x32x16_bf16 v[0:15], v[154:157], v[130:133], v[0:15]
	s_waitcnt lgkmcnt(2)
	v_mfma_f32_32x32x16_bf16 v[16:31], v[158:161], v[134:137], v[16:31]
	s_waitcnt lgkmcnt(0)
	v_mfma_f32_32x32x16_bf16 v[0:15], v[162:165], v[134:137], v[0:15]
	s_setprio 0
	s_cbranch_vccz .LBB0_1537
	s_nop 7
	v_mul_f32_e32 v30, v30, v34
	v_mul_f32_e32 v31, v31, v34
	v_mul_f32_e32 v28, v28, v34
	v_mul_f32_e32 v29, v29, v34
	v_mul_f32_e32 v26, v26, v34
	v_mul_f32_e32 v27, v27, v34
	v_mul_f32_e32 v24, v24, v34
	v_mul_f32_e32 v25, v25, v34
	v_mul_f32_e32 v22, v22, v34
	v_mul_f32_e32 v23, v23, v34
	v_mul_f32_e32 v20, v20, v34
	v_mul_f32_e32 v21, v21, v34
	v_mul_f32_e32 v18, v18, v34
	v_mul_f32_e32 v19, v19, v34
	v_mul_f32_e32 v16, v16, v34
	v_mul_f32_e32 v17, v17, v34
	v_mul_f32_e32 v14, v14, v34
	v_mul_f32_e32 v15, v15, v34
	v_mul_f32_e32 v12, v12, v34
	v_mul_f32_e32 v13, v13, v34
	v_mul_f32_e32 v10, v10, v34
	v_mul_f32_e32 v11, v11, v34
	v_mul_f32_e32 v8, v8, v34
	v_mul_f32_e32 v9, v9, v34
	v_mul_f32_e32 v6, v6, v34
	v_mul_f32_e32 v7, v7, v34
	v_mul_f32_e32 v4, v4, v34
	v_mul_f32_e32 v5, v5, v34
	v_mul_f32_e32 v2, v2, v34
	v_mul_f32_e32 v3, v3, v34
	v_mul_f32_e32 v0, v0, v34
	v_mul_f32_e32 v1, v1, v34

; DI float bf2f(unsigned v) { return __uint_as_float(v << 16); }
;   DI void operator()(const f32x4 (&acc)[2][2][4][2], const pg8::Unit& u, int wr, int wc, int fr_, int fq_) const {
;     ...
;             } else if (EPI == EPI_RESID) {
;               if (n == 0) {
;                 const int f8 = u.pn * 256 + bj * 128 + wc * 32 + 8 * fq;
;                 const f32x4 v1 = acc[ai][bj][m][1];
;                 f32x4 r0, r1;
;                 if (rsrc) {
;                   r0 = *(const f32x4*)(rsrc + (size_t)token * 1024 + f8); r1 = *(const f32x4*)(rsrc + (size_t)token * 1024 + f8 + 4);
;                 } else {
;                   const u32x4 xu = *(const u32x4*)(xr + (size_t)token * 1024 + f8);
;                   r0 = (f32x4){bf2f(xu.x & 0xffffu), bf2f(xu.x >> 16), bf2f(xu.y & 0xffffu), bf2f(xu.y >> 16)};
;                   r1 = (f32x4){bf2f(xu.z & 0xffffu), bf2f(xu.z >> 16), bf2f(xu.w & 0xffffu), bf2f(xu.w >> 16)};
;                 }
;                 r0 += v; r1 += v1;
;                 st_bf8(xr + (size_t)token * 1024 + f8, r0, r1, 1.f);
.LBB0_1650:
	s_waitcnt vmcnt(0)
	v_add_f32_e32 v130, v126, v130
	v_add_f32_e32 v131, v127, v131
	v_add_f32_e32 v156, v124, v128
	v_add_f32_e32 v157, v125, v129
	v_add_f32_e32 v128, v122, v134
	v_add_f32_e32 v129, v123, v135
	v_add_f32_e32 v132, v120, v132
	v_add_f32_e32 v133, v121, v133
	v_cvt_pk_bf16_f32 v120, v156, v157
	v_cvt_pk_bf16_f32 v121, v130, v131
	v_cvt_pk_bf16_f32 v122, v132, v133
	v_cvt_pk_bf16_f32 v123, v128, v129
	s_and_b64 vcc, exec, s[2:3]
	global_store_dwordx4 v[152:153], v[120:123], off
	s_cbranch_vccnz .LBB0_1657
	global_load_dwordx4 v[124:127], v[154:155], off offset:528
	global_load_dwordx4 v[120:123], v[154:155], off offset:512
	s_cbranch_execnz .LBB0_1653

;   DI void operator()(const f32x4 (&acc)[2][2][4][2], const pg8::Unit& u, int wr, int wc, int fr_, int fq_) const {
;     ...
;                 r0 += v; r1 += v1;
;                 st_bf8(xr + (size_t)token * 1024 + f8, r0, r1, 1.f);
;                 ssq += r0[0] * r0[0] + r0[1] * r0[1] + r0[2] * r0[2] + r0[3] * r0[3] + r1[0] * r1[0] + r1[1] * r1[1] + r1[2] * r1[2] + r1[3] * r1[3];
;               }
;             } else {
;               if (n == 0) {
;                 const f32x4 v1 = acc[ai][bj][m][1];
;                 u32x4 o4;
;                 { const float t0 = fmaxf(v[0], 0.f) * rinv, t1 = fmaxf(v[1], 0.f) * rinv, t2 = fmaxf(v[2], 0.f) * rinv, t3 = fmaxf(v[3], 0.f) * rinv;
;                   o4.x = pack2(t0 * t0, t1 * t1); o4.y = pack2(t2 * t2, t3 * t3); }
;                 { const float t0 = fmaxf(v1[0], 0.f) * rinv, t1 = fmaxf(v1[1], 0.f) * rinv, t2 = fmaxf(v1[2], 0.f) * rinv, t3 = fmaxf(v1[3], 0.f) * rinv;
;                   o4.z = pack2(t0 * t0, t1 * t1); o4.w = pack2(t2 * t2, t3 * t3); }
;                 *(u32x4*)((u16*)big + (size_t)token * 4096 + u.pn * 256 + bj * 128 + wc * 32 + 8 * fq) = o4;
;               }
;             }
;           }
;         if (EPI == EPI_RESID) {
;           ssq += shx(ssq, 16, t_ & 63);
;           ssq += shx(ssq, 32, t_ & 63);
;           if (fq == 0) ss_out[(size_t)token * 16 + u.pn * 4 + wc] = ssq;
;         }
.LBB0_1653:
	s_waitcnt vmcnt(0)
	v_add_f32_e32 v116, v116, v120
	v_add_f32_e32 v117, v117, v121
	v_mul_f32_e32 v134, v157, v157
	v_add_f32_e32 v118, v118, v122
	v_add_f32_e32 v119, v119, v123
	v_add_f32_e32 v122, v112, v124
	v_add_f32_e32 v123, v113, v125
	v_mul_f32_e32 v112, v117, v117
	v_fmac_f32_e32 v134, v156, v156
	v_fmac_f32_e32 v112, v116, v116
	v_fmac_f32_e32 v134, v130, v130
	v_fmac_f32_e32 v112, v118, v118
	v_fmac_f32_e32 v134, v131, v131
	v_fmac_f32_e32 v112, v119, v119
	v_fmac_f32_e32 v134, v132, v132
	v_fmac_f32_e32 v112, v122, v122
	v_fmac_f32_e32 v134, v133, v133
	v_add_f32_e32 v120, v114, v126
	v_add_f32_e32 v121, v115, v127
	v_fmac_f32_e32 v112, v123, v123
	v_fmac_f32_e32 v134, v128, v128
	v_fmac_f32_e32 v112, v120, v120
	v_fmac_f32_e32 v134, v129, v129
	v_lshlrev_b32_e32 v128, 2, v161
	v_fmac_f32_e32 v112, v121, v121
	v_bitop3_b32 v129, v128, 64, v190 bitop3:0x6c
	v_add_f32_e32 v112, v134, v112
	ds_bpermute_b32 v113, v129, v112
	s_movk_i32 s4, 0x80
	v_bitop3_b32 v128, v128, s4, v190 bitop3:0x6c
	s_lshl_b32 s28, s24, 2
	v_cmp_eq_u32_e64 s[4:5], 0, v160
	s_waitcnt lgkmcnt(0)
	v_add_f32_e32 v112, v112, v113
	ds_bpermute_b32 v113, v128, v112
	s_ashr_i32 s29, s28, 31
	v_cvt_pk_bf16_f32 v114, v116, v117
	v_cvt_pk_bf16_f32 v115, v118, v119
	v_cvt_pk_bf16_f32 v116, v122, v123
	v_cvt_pk_bf16_f32 v117, v120, v121
	global_store_dwordx4 v[152:153], v[114:117], off offset:256
	s_and_saveexec_b64 s[34:35], s[4:5]
	s_cbranch_execz .LBB0_1655
	s_waitcnt lgkmcnt(0)
	v_add_f32_e32 v114, v112, v113
	v_lshlrev_b64 v[112:113], 6, v[150:151]
	v_lshl_add_u64 v[112:113], s[10:11], 0, v[112:113]
	v_lshl_add_u64 v[112:113], s[28:29], 2, v[112:113]
	s_lshl_b32 s24, s46, 2
	v_lshl_add_u64 v[112:113], v[112:113], 0, s[24:25]
	global_store_dword v[112:113], v114, off

; DI float bf2f(unsigned v) { return __uint_as_float(v << 16); }
;   DI void operator()(const f32x4 (&acc)[2][2][4][2], const pg8::Unit& u, int wr, int wc, int fr_, int fq_) const {
;     ...
;             } else if (EPI == EPI_RESID) {
;               if (n == 0) {
;                 const int f8 = u.pn * 256 + bj * 128 + wc * 32 + 8 * fq;
;                 const f32x4 v1 = acc[ai][bj][m][1];
;                 f32x4 r0, r1;
;                 if (rsrc) {
;                   r0 = *(const f32x4*)(rsrc + (size_t)token * 1024 + f8); r1 = *(const f32x4*)(rsrc + (size_t)token * 1024 + f8 + 4);
;                 } else {
;                   const u32x4 xu = *(const u32x4*)(xr + (size_t)token * 1024 + f8);
;                   r0 = (f32x4){bf2f(xu.x & 0xffffu), bf2f(xu.x >> 16), bf2f(xu.y & 0xffffu), bf2f(xu.y >> 16)};
;                   r1 = (f32x4){bf2f(xu.z & 0xffffu), bf2f(xu.z >> 16), bf2f(xu.w & 0xffffu), bf2f(xu.w >> 16)};
;                 }
;                 r0 += v; r1 += v1;
;                 st_bf8(xr + (size_t)token * 1024 + f8, r0, r1, 1.f);
.LBB0_1661:
	s_waitcnt vmcnt(0)
	v_add_f32_e32 v114, v110, v114
	v_add_f32_e32 v115, v111, v115
	v_add_f32_e32 v126, v108, v112
	v_add_f32_e32 v127, v109, v113
	v_add_f32_e32 v112, v106, v118
	v_add_f32_e32 v113, v107, v119
	v_add_f32_e32 v116, v104, v116
	v_add_f32_e32 v117, v105, v117
	v_cvt_pk_bf16_f32 v104, v126, v127
	v_cvt_pk_bf16_f32 v105, v114, v115
	v_cvt_pk_bf16_f32 v106, v116, v117
	v_cvt_pk_bf16_f32 v107, v112, v113
	s_and_b64 vcc, exec, s[2:3]
	global_store_dwordx4 v[122:123], v[104:107], off
	s_cbranch_vccnz .LBB0_1668
	global_load_dwordx4 v[108:111], v[124:125], off offset:528
	global_load_dwordx4 v[104:107], v[124:125], off offset:512
	s_cbranch_execnz .LBB0_1664

;   DI void operator()(const f32x4 (&acc)[2][2][4][2], const pg8::Unit& u, int wr, int wc, int fr_, int fq_) const {
;     ...
;                 r0 += v; r1 += v1;
;                 st_bf8(xr + (size_t)token * 1024 + f8, r0, r1, 1.f);
;                 ssq += r0[0] * r0[0] + r0[1] * r0[1] + r0[2] * r0[2] + r0[3] * r0[3] + r1[0] * r1[0] + r1[1] * r1[1] + r1[2] * r1[2] + r1[3] * r1[3];
;               }
;             } else {
;               if (n == 0) {
;                 const f32x4 v1 = acc[ai][bj][m][1];
;                 u32x4 o4;
;                 { const float t0 = fmaxf(v[0], 0.f) * rinv, t1 = fmaxf(v[1], 0.f) * rinv, t2 = fmaxf(v[2], 0.f) * rinv, t3 = fmaxf(v[3], 0.f) * rinv;
;                   o4.x = pack2(t0 * t0, t1 * t1); o4.y = pack2(t2 * t2, t3 * t3); }
;                 { const float t0 = fmaxf(v1[0], 0.f) * rinv, t1 = fmaxf(v1[1], 0.f) * rinv, t2 = fmaxf(v1[2], 0.f) * rinv, t3 = fmaxf(v1[3], 0.f) * rinv;
;                   o4.z = pack2(t0 * t0, t1 * t1); o4.w = pack2(t2 * t2, t3 * t3); }
;                 *(u32x4*)((u16*)big + (size_t)token * 4096 + u.pn * 256 + bj * 128 + wc * 32 + 8 * fq) = o4;
;               }
;             }
;           }
;         if (EPI == EPI_RESID) {
;           ssq += shx(ssq, 16, t_ & 63);
;           ssq += shx(ssq, 32, t_ & 63);
;           if (fq == 0) ss_out[(size_t)token * 16 + u.pn * 4 + wc] = ssq;
;         }
.LBB0_1664:
	s_waitcnt vmcnt(0)
	v_add_f32_e32 v100, v100, v104
	v_add_f32_e32 v101, v101, v105
	v_mul_f32_e32 v118, v127, v127
	v_add_f32_e32 v102, v102, v106
	v_add_f32_e32 v103, v103, v107
	v_add_f32_e32 v106, v96, v108
	v_add_f32_e32 v107, v97, v109
	v_mul_f32_e32 v96, v101, v101
	v_fmac_f32_e32 v118, v126, v126
	v_fmac_f32_e32 v96, v100, v100
	v_fmac_f32_e32 v118, v114, v114
	v_fmac_f32_e32 v96, v102, v102
	v_fmac_f32_e32 v118, v115, v115
	v_fmac_f32_e32 v96, v103, v103
	v_fmac_f32_e32 v118, v116, v116
	v_fmac_f32_e32 v96, v106, v106
	v_fmac_f32_e32 v118, v117, v117
	v_add_f32_e32 v104, v98, v110
	v_add_f32_e32 v105, v99, v111
	v_fmac_f32_e32 v96, v107, v107
	v_fmac_f32_e32 v118, v112, v112
	v_fmac_f32_e32 v96, v104, v104
	v_fmac_f32_e32 v118, v113, v113
	v_fmac_f32_e32 v96, v105, v105
	v_add_f32_e32 v96, v118, v96
	ds_bpermute_b32 v97, v129, v96
	v_cvt_pk_bf16_f32 v98, v100, v101
	v_cvt_pk_bf16_f32 v99, v102, v103
	v_cvt_pk_bf16_f32 v100, v106, v107
	v_cvt_pk_bf16_f32 v101, v104, v105
	s_waitcnt lgkmcnt(0)
	v_add_f32_e32 v96, v96, v97
	ds_bpermute_b32 v97, v128, v96
	global_store_dwordx4 v[122:123], v[98:101], off offset:256
	s_and_saveexec_b64 s[34:35], s[4:5]
	s_cbranch_execz .LBB0_1666
	s_waitcnt lgkmcnt(0)
	v_add_f32_e32 v98, v96, v97
	v_lshlrev_b64 v[96:97], 6, v[120:121]
	v_lshl_add_u64 v[96:97], s[10:11], 0, v[96:97]
	v_lshl_add_u64 v[96:97], s[28:29], 2, v[96:97]
	s_lshl_b32 s24, s46, 2
	v_lshl_add_u64 v[96:97], v[96:97], 0, s[24:25]
	global_store_dword v[96:97], v98, off

; DI float bf2f(unsigned v) { return __uint_as_float(v << 16); }
;   DI void operator()(const f32x4 (&acc)[2][2][4][2], const pg8::Unit& u, int wr, int wc, int fr_, int fq_) const {
;     ...
;             } else if (EPI == EPI_RESID) {
;               if (n == 0) {
;                 const int f8 = u.pn * 256 + bj * 128 + wc * 32 + 8 * fq;
;                 const f32x4 v1 = acc[ai][bj][m][1];
;                 f32x4 r0, r1;
;                 if (rsrc) {
;                   r0 = *(const f32x4*)(rsrc + (size_t)token * 1024 + f8); r1 = *(const f32x4*)(rsrc + (size_t)token * 1024 + f8 + 4);
;                 } else {
;                   const u32x4 xu = *(const u32x4*)(xr + (size_t)token * 1024 + f8);
;                   r0 = (f32x4){bf2f(xu.x & 0xffffu), bf2f(xu.x >> 16), bf2f(xu.y & 0xffffu), bf2f(xu.y >> 16)};
;                   r1 = (f32x4){bf2f(xu.z & 0xffffu), bf2f(xu.z >> 16), bf2f(xu.w & 0xffffu), bf2f(xu.w >> 16)};
;                 }
;                 r0 += v; r1 += v1;
;                 st_bf8(xr + (size_t)token * 1024 + f8, r0, r1, 1.f);
.LBB0_1672:
	s_waitcnt vmcnt(0)
	v_add_f32_e32 v98, v94, v98
	v_add_f32_e32 v99, v95, v99
	v_add_f32_e32 v110, v92, v96
	v_add_f32_e32 v111, v93, v97
	v_add_f32_e32 v96, v90, v102
	v_add_f32_e32 v97, v91, v103
	v_add_f32_e32 v100, v88, v100
	v_add_f32_e32 v101, v89, v101
	v_cvt_pk_bf16_f32 v88, v110, v111
	v_cvt_pk_bf16_f32 v89, v98, v99
	v_cvt_pk_bf16_f32 v90, v100, v101
	v_cvt_pk_bf16_f32 v91, v96, v97
	s_and_b64 vcc, exec, s[2:3]
	global_store_dwordx4 v[106:107], v[88:91], off
	s_cbranch_vccnz .LBB0_1679
	global_load_dwordx4 v[92:95], v[108:109], off offset:528
	global_load_dwordx4 v[88:91], v[108:109], off offset:512
	s_cbranch_execnz .LBB0_1675

;   DI void operator()(const f32x4 (&acc)[2][2][4][2], const pg8::Unit& u, int wr, int wc, int fr_, int fq_) const {
;     ...
;                 r0 += v; r1 += v1;
;                 st_bf8(xr + (size_t)token * 1024 + f8, r0, r1, 1.f);
;                 ssq += r0[0] * r0[0] + r0[1] * r0[1] + r0[2] * r0[2] + r0[3] * r0[3] + r1[0] * r1[0] + r1[1] * r1[1] + r1[2] * r1[2] + r1[3] * r1[3];
;               }
;             } else {
;               if (n == 0) {
;                 const f32x4 v1 = acc[ai][bj][m][1];
;                 u32x4 o4;
;                 { const float t0 = fmaxf(v[0], 0.f) * rinv, t1 = fmaxf(v[1], 0.f) * rinv, t2 = fmaxf(v[2], 0.f) * rinv, t3 = fmaxf(v[3], 0.f) * rinv;
;                   o4.x = pack2(t0 * t0, t1 * t1); o4.y = pack2(t2 * t2, t3 * t3); }
;                 { const float t0 = fmaxf(v1[0], 0.f) * rinv, t1 = fmaxf(v1[1], 0.f) * rinv, t2 = fmaxf(v1[2], 0.f) * rinv, t3 = fmaxf(v1[3], 0.f) * rinv;
;                   o4.z = pack2(t0 * t0, t1 * t1); o4.w = pack2(t2 * t2, t3 * t3); }
;                 *(u32x4*)((u16*)big + (size_t)token * 4096 + u.pn * 256 + bj * 128 + wc * 32 + 8 * fq) = o4;
;               }
;             }
;           }
;         if (EPI == EPI_RESID) {
;           ssq += shx(ssq, 16, t_ & 63);
;           ssq += shx(ssq, 32, t_ & 63);
;           if (fq == 0) ss_out[(size_t)token * 16 + u.pn * 4 + wc] = ssq;
;         }
.LBB0_1675:
	s_waitcnt vmcnt(0)
	v_add_f32_e32 v84, v84, v88
	v_add_f32_e32 v85, v85, v89
	v_mul_f32_e32 v102, v111, v111
	v_add_f32_e32 v86, v86, v90
	v_add_f32_e32 v87, v87, v91
	v_add_f32_e32 v90, v80, v92
	v_add_f32_e32 v91, v81, v93
	v_mul_f32_e32 v80, v85, v85
	v_fmac_f32_e32 v102, v110, v110
	v_fmac_f32_e32 v80, v84, v84
	v_fmac_f32_e32 v102, v98, v98
	v_fmac_f32_e32 v80, v86, v86
	v_fmac_f32_e32 v102, v99, v99
	v_fmac_f32_e32 v80, v87, v87
	v_fmac_f32_e32 v102, v100, v100
	v_fmac_f32_e32 v80, v90, v90
	v_fmac_f32_e32 v102, v101, v101
	v_add_f32_e32 v88, v82, v94
	v_add_f32_e32 v89, v83, v95
	v_fmac_f32_e32 v80, v91, v91
	v_fmac_f32_e32 v102, v96, v96
	v_fmac_f32_e32 v80, v88, v88
	v_fmac_f32_e32 v102, v97, v97
	v_fmac_f32_e32 v80, v89, v89
	v_add_f32_e32 v80, v102, v80
	ds_bpermute_b32 v81, v129, v80
	v_cvt_pk_bf16_f32 v82, v84, v85
	v_cvt_pk_bf16_f32 v83, v86, v87
	v_cvt_pk_bf16_f32 v84, v90, v91
	v_cvt_pk_bf16_f32 v85, v88, v89
	s_waitcnt lgkmcnt(0)
	v_add_f32_e32 v80, v80, v81
	ds_bpermute_b32 v81, v128, v80
	global_store_dwordx4 v[106:107], v[82:85], off offset:256
	s_and_saveexec_b64 s[34:35], s[4:5]
	s_cbranch_execz .LBB0_1677
	s_waitcnt lgkmcnt(0)
	v_add_f32_e32 v82, v80, v81
	v_lshlrev_b64 v[80:81], 6, v[104:105]
	v_lshl_add_u64 v[80:81], s[10:11], 0, v[80:81]
	v_lshl_add_u64 v[80:81], s[28:29], 2, v[80:81]
	s_lshl_b32 s24, s46, 2
	v_lshl_add_u64 v[80:81], v[80:81], 0, s[24:25]
	global_store_dword v[80:81], v82, off

; DI float bf2f(unsigned v) { return __uint_as_float(v << 16); }
;   DI void operator()(const f32x4 (&acc)[2][2][4][2], const pg8::Unit& u, int wr, int wc, int fr_, int fq_) const {
;     ...
;             } else if (EPI == EPI_RESID) {
;               if (n == 0) {
;                 const int f8 = u.pn * 256 + bj * 128 + wc * 32 + 8 * fq;
;                 const f32x4 v1 = acc[ai][bj][m][1];
;                 f32x4 r0, r1;
;                 if (rsrc) {
;                   r0 = *(const f32x4*)(rsrc + (size_t)token * 1024 + f8); r1 = *(const f32x4*)(rsrc + (size_t)token * 1024 + f8 + 4);
;                 } else {
;                   const u32x4 xu = *(const u32x4*)(xr + (size_t)token * 1024 + f8);
;                   r0 = (f32x4){bf2f(xu.x & 0xffffu), bf2f(xu.x >> 16), bf2f(xu.y & 0xffffu), bf2f(xu.y >> 16)};
;                   r1 = (f32x4){bf2f(xu.z & 0xffffu), bf2f(xu.z >> 16), bf2f(xu.w & 0xffffu), bf2f(xu.w >> 16)};
;                 }
;                 r0 += v; r1 += v1;
;                 st_bf8(xr + (size_t)token * 1024 + f8, r0, r1, 1.f);
.LBB0_1683:
	s_waitcnt vmcnt(0)
	v_add_f32_e32 v82, v78, v82
	v_add_f32_e32 v83, v79, v83
	v_add_f32_e32 v94, v76, v80
	v_add_f32_e32 v95, v77, v81
	v_add_f32_e32 v80, v74, v86
	v_add_f32_e32 v81, v75, v87
	v_add_f32_e32 v84, v72, v84
	v_add_f32_e32 v85, v73, v85
	v_cvt_pk_bf16_f32 v72, v94, v95
	v_cvt_pk_bf16_f32 v73, v82, v83
	v_cvt_pk_bf16_f32 v74, v84, v85
	v_cvt_pk_bf16_f32 v75, v80, v81
	s_and_b64 vcc, exec, s[2:3]
	global_store_dwordx4 v[90:91], v[72:75], off
	s_cbranch_vccnz .LBB0_1690
	global_load_dwordx4 v[76:79], v[92:93], off offset:528
	global_load_dwordx4 v[72:75], v[92:93], off offset:512
	s_cbranch_execnz .LBB0_1686

;   DI void operator()(const f32x4 (&acc)[2][2][4][2], const pg8::Unit& u, int wr, int wc, int fr_, int fq_) const {
;     ...
;                 r0 += v; r1 += v1;
;                 st_bf8(xr + (size_t)token * 1024 + f8, r0, r1, 1.f);
;                 ssq += r0[0] * r0[0] + r0[1] * r0[1] + r0[2] * r0[2] + r0[3] * r0[3] + r1[0] * r1[0] + r1[1] * r1[1] + r1[2] * r1[2] + r1[3] * r1[3];
;               }
;             } else {
;               if (n == 0) {
;                 const f32x4 v1 = acc[ai][bj][m][1];
;                 u32x4 o4;
;                 { const float t0 = fmaxf(v[0], 0.f) * rinv, t1 = fmaxf(v[1], 0.f) * rinv, t2 = fmaxf(v[2], 0.f) * rinv, t3 = fmaxf(v[3], 0.f) * rinv;
;                   o4.x = pack2(t0 * t0, t1 * t1); o4.y = pack2(t2 * t2, t3 * t3); }
;                 { const float t0 = fmaxf(v1[0], 0.f) * rinv, t1 = fmaxf(v1[1], 0.f) * rinv, t2 = fmaxf(v1[2], 0.f) * rinv, t3 = fmaxf(v1[3], 0.f) * rinv;
;                   o4.z = pack2(t0 * t0, t1 * t1); o4.w = pack2(t2 * t2, t3 * t3); }
;                 *(u32x4*)((u16*)big + (size_t)token * 4096 + u.pn * 256 + bj * 128 + wc * 32 + 8 * fq) = o4;
;               }
;             }
;           }
;         if (EPI == EPI_RESID) {
;           ssq += shx(ssq, 16, t_ & 63);
;           ssq += shx(ssq, 32, t_ & 63);
;           if (fq == 0) ss_out[(size_t)token * 16 + u.pn * 4 + wc] = ssq;
;         }
.LBB0_1686:
	s_waitcnt vmcnt(0)
	v_add_f32_e32 v68, v68, v72
	v_add_f32_e32 v69, v69, v73
	v_mul_f32_e32 v86, v95, v95
	v_add_f32_e32 v70, v70, v74
	v_add_f32_e32 v71, v71, v75
	v_add_f32_e32 v74, v64, v76
	v_add_f32_e32 v75, v65, v77
	v_mul_f32_e32 v64, v69, v69
	v_fmac_f32_e32 v86, v94, v94
	v_fmac_f32_e32 v64, v68, v68
	v_fmac_f32_e32 v86, v82, v82
	v_fmac_f32_e32 v64, v70, v70
	v_fmac_f32_e32 v86, v83, v83
	v_fmac_f32_e32 v64, v71, v71
	v_fmac_f32_e32 v86, v84, v84
	v_fmac_f32_e32 v64, v74, v74
	v_fmac_f32_e32 v86, v85, v85
	v_add_f32_e32 v72, v66, v78
	v_add_f32_e32 v73, v67, v79
	v_fmac_f32_e32 v64, v75, v75
	v_fmac_f32_e32 v86, v80, v80
	v_fmac_f32_e32 v64, v72, v72
	v_fmac_f32_e32 v86, v81, v81
	v_fmac_f32_e32 v64, v73, v73
	v_add_f32_e32 v64, v86, v64
	ds_bpermute_b32 v65, v129, v64
	v_cvt_pk_bf16_f32 v66, v68, v69
	v_cvt_pk_bf16_f32 v67, v70, v71
	v_cvt_pk_bf16_f32 v68, v74, v75
	v_cvt_pk_bf16_f32 v69, v72, v73
	s_waitcnt lgkmcnt(0)
	v_add_f32_e32 v64, v64, v65
	ds_bpermute_b32 v65, v128, v64
	global_store_dwordx4 v[90:91], v[66:69], off offset:256
	s_and_saveexec_b64 s[34:35], s[4:5]
	s_cbranch_execz .LBB0_1688
	s_waitcnt lgkmcnt(0)
	v_add_f32_e32 v66, v64, v65
	v_lshlrev_b64 v[64:65], 6, v[88:89]
	v_lshl_add_u64 v[64:65], s[10:11], 0, v[64:65]
	v_lshl_add_u64 v[64:65], s[28:29], 2, v[64:65]
	s_lshl_b32 s24, s46, 2
	v_lshl_add_u64 v[64:65], v[64:65], 0, s[24:25]
	global_store_dword v[64:65], v66, off

; DI float bf2f(unsigned v) { return __uint_as_float(v << 16); }
;   DI void operator()(const f32x4 (&acc)[2][2][4][2], const pg8::Unit& u, int wr, int wc, int fr_, int fq_) const {
;     ...
;             } else if (EPI == EPI_RESID) {
;               if (n == 0) {
;                 const int f8 = u.pn * 256 + bj * 128 + wc * 32 + 8 * fq;
;                 const f32x4 v1 = acc[ai][bj][m][1];
;                 f32x4 r0, r1;
;                 if (rsrc) {
;                   r0 = *(const f32x4*)(rsrc + (size_t)token * 1024 + f8); r1 = *(const f32x4*)(rsrc + (size_t)token * 1024 + f8 + 4);
;                 } else {
;                   const u32x4 xu = *(const u32x4*)(xr + (size_t)token * 1024 + f8);
;                   r0 = (f32x4){bf2f(xu.x & 0xffffu), bf2f(xu.x >> 16), bf2f(xu.y & 0xffffu), bf2f(xu.y >> 16)};
;                   r1 = (f32x4){bf2f(xu.z & 0xffffu), bf2f(xu.z >> 16), bf2f(xu.w & 0xffffu), bf2f(xu.w >> 16)};
;                 }
;                 r0 += v; r1 += v1;
;                 st_bf8(xr + (size_t)token * 1024 + f8, r0, r1, 1.f);
.LBB0_1694:
	s_waitcnt vmcnt(0)
	v_add_f32_e32 v66, v62, v66
	v_add_f32_e32 v67, v63, v67
	v_add_f32_e32 v78, v60, v64
	v_add_f32_e32 v79, v61, v65
	v_add_f32_e32 v64, v58, v70
	v_add_f32_e32 v65, v59, v71
	v_add_f32_e32 v68, v56, v68
	v_add_f32_e32 v69, v57, v69
	v_cvt_pk_bf16_f32 v56, v78, v79
	v_cvt_pk_bf16_f32 v57, v66, v67
	v_cvt_pk_bf16_f32 v58, v68, v69
	v_cvt_pk_bf16_f32 v59, v64, v65
	s_and_b64 vcc, exec, s[2:3]
	global_store_dwordx4 v[74:75], v[56:59], off
	s_cbranch_vccnz .LBB0_1701
	global_load_dwordx4 v[60:63], v[76:77], off offset:528
	global_load_dwordx4 v[56:59], v[76:77], off offset:512
	s_cbranch_execnz .LBB0_1697

;   DI void operator()(const f32x4 (&acc)[2][2][4][2], const pg8::Unit& u, int wr, int wc, int fr_, int fq_) const {
;     ...
;                 r0 += v; r1 += v1;
;                 st_bf8(xr + (size_t)token * 1024 + f8, r0, r1, 1.f);
;                 ssq += r0[0] * r0[0] + r0[1] * r0[1] + r0[2] * r0[2] + r0[3] * r0[3] + r1[0] * r1[0] + r1[1] * r1[1] + r1[2] * r1[2] + r1[3] * r1[3];
;               }
;             } else {
;               if (n == 0) {
;                 const f32x4 v1 = acc[ai][bj][m][1];
;                 u32x4 o4;
;                 { const float t0 = fmaxf(v[0], 0.f) * rinv, t1 = fmaxf(v[1], 0.f) * rinv, t2 = fmaxf(v[2], 0.f) * rinv, t3 = fmaxf(v[3], 0.f) * rinv;
;                   o4.x = pack2(t0 * t0, t1 * t1); o4.y = pack2(t2 * t2, t3 * t3); }
;                 { const float t0 = fmaxf(v1[0], 0.f) * rinv, t1 = fmaxf(v1[1], 0.f) * rinv, t2 = fmaxf(v1[2], 0.f) * rinv, t3 = fmaxf(v1[3], 0.f) * rinv;
;                   o4.z = pack2(t0 * t0, t1 * t1); o4.w = pack2(t2 * t2, t3 * t3); }
;                 *(u32x4*)((u16*)big + (size_t)token * 4096 + u.pn * 256 + bj * 128 + wc * 32 + 8 * fq) = o4;
;               }
;             }
;           }
;         if (EPI == EPI_RESID) {
;           ssq += shx(ssq, 16, t_ & 63);
;           ssq += shx(ssq, 32, t_ & 63);
;           if (fq == 0) ss_out[(size_t)token * 16 + u.pn * 4 + wc] = ssq;
;         }
.LBB0_1697:
	s_waitcnt vmcnt(0)
	v_add_f32_e32 v52, v52, v56
	v_add_f32_e32 v53, v53, v57
	v_mul_f32_e32 v70, v79, v79
	v_add_f32_e32 v54, v54, v58
	v_add_f32_e32 v55, v55, v59
	v_add_f32_e32 v58, v48, v60
	v_add_f32_e32 v59, v49, v61
	v_mul_f32_e32 v48, v53, v53
	v_fmac_f32_e32 v70, v78, v78
	v_fmac_f32_e32 v48, v52, v52
	v_fmac_f32_e32 v70, v66, v66
	v_fmac_f32_e32 v48, v54, v54
	v_fmac_f32_e32 v70, v67, v67
	v_fmac_f32_e32 v48, v55, v55
	v_fmac_f32_e32 v70, v68, v68
	v_fmac_f32_e32 v48, v58, v58
	v_fmac_f32_e32 v70, v69, v69
	v_add_f32_e32 v56, v50, v62
	v_add_f32_e32 v57, v51, v63
	v_fmac_f32_e32 v48, v59, v59
	v_fmac_f32_e32 v70, v64, v64
	v_fmac_f32_e32 v48, v56, v56
	v_fmac_f32_e32 v70, v65, v65
	v_fmac_f32_e32 v48, v57, v57
	v_add_f32_e32 v48, v70, v48
	ds_bpermute_b32 v49, v129, v48
	v_cvt_pk_bf16_f32 v50, v52, v53
	v_cvt_pk_bf16_f32 v51, v54, v55
	v_cvt_pk_bf16_f32 v52, v58, v59
	v_cvt_pk_bf16_f32 v53, v56, v57
	s_waitcnt lgkmcnt(0)
	v_add_f32_e32 v48, v48, v49
	ds_bpermute_b32 v49, v128, v48
	global_store_dwordx4 v[74:75], v[50:53], off offset:256
	s_and_saveexec_b64 s[34:35], s[4:5]
	s_cbranch_execz .LBB0_1699
	s_waitcnt lgkmcnt(0)
	v_add_f32_e32 v50, v48, v49
	v_lshlrev_b64 v[48:49], 6, v[72:73]
	v_lshl_add_u64 v[48:49], s[10:11], 0, v[48:49]
	v_lshl_add_u64 v[48:49], s[28:29], 2, v[48:49]
	s_lshl_b32 s24, s46, 2
	v_lshl_add_u64 v[48:49], v[48:49], 0, s[24:25]
	global_store_dword v[48:49], v50, off

; DI float bf2f(unsigned v) { return __uint_as_float(v << 16); }
;   DI void operator()(const f32x4 (&acc)[2][2][4][2], const pg8::Unit& u, int wr, int wc, int fr_, int fq_) const {
;     ...
;             } else if (EPI == EPI_RESID) {
;               if (n == 0) {
;                 const int f8 = u.pn * 256 + bj * 128 + wc * 32 + 8 * fq;
;                 const f32x4 v1 = acc[ai][bj][m][1];
;                 f32x4 r0, r1;
;                 if (rsrc) {
;                   r0 = *(const f32x4*)(rsrc + (size_t)token * 1024 + f8); r1 = *(const f32x4*)(rsrc + (size_t)token * 1024 + f8 + 4);
;                 } else {
;                   const u32x4 xu = *(const u32x4*)(xr + (size_t)token * 1024 + f8);
;                   r0 = (f32x4){bf2f(xu.x & 0xffffu), bf2f(xu.x >> 16), bf2f(xu.y & 0xffffu), bf2f(xu.y >> 16)};
;                   r1 = (f32x4){bf2f(xu.z & 0xffffu), bf2f(xu.z >> 16), bf2f(xu.w & 0xffffu), bf2f(xu.w >> 16)};
;                 }
;                 r0 += v; r1 += v1;
;                 st_bf8(xr + (size_t)token * 1024 + f8, r0, r1, 1.f);
.LBB0_1705:
	s_waitcnt vmcnt(0)
	v_add_f32_e32 v50, v46, v50
	v_add_f32_e32 v51, v47, v51
	v_add_f32_e32 v62, v44, v48
	v_add_f32_e32 v63, v45, v49
	v_add_f32_e32 v48, v42, v54
	v_add_f32_e32 v49, v43, v55
	v_add_f32_e32 v52, v40, v52
	v_add_f32_e32 v53, v41, v53
	v_cvt_pk_bf16_f32 v40, v62, v63
	v_cvt_pk_bf16_f32 v41, v50, v51
	v_cvt_pk_bf16_f32 v42, v52, v53
	v_cvt_pk_bf16_f32 v43, v48, v49
	s_and_b64 vcc, exec, s[2:3]
	global_store_dwordx4 v[58:59], v[40:43], off
	s_cbranch_vccnz .LBB0_1712
	global_load_dwordx4 v[44:47], v[60:61], off offset:528
	global_load_dwordx4 v[40:43], v[60:61], off offset:512
	s_cbranch_execnz .LBB0_1708

;   DI void operator()(const f32x4 (&acc)[2][2][4][2], const pg8::Unit& u, int wr, int wc, int fr_, int fq_) const {
;     ...
;                 r0 += v; r1 += v1;
;                 st_bf8(xr + (size_t)token * 1024 + f8, r0, r1, 1.f);
;                 ssq += r0[0] * r0[0] + r0[1] * r0[1] + r0[2] * r0[2] + r0[3] * r0[3] + r1[0] * r1[0] + r1[1] * r1[1] + r1[2] * r1[2] + r1[3] * r1[3];
;               }
;             } else {
;               if (n == 0) {
;                 const f32x4 v1 = acc[ai][bj][m][1];
;                 u32x4 o4;
;                 { const float t0 = fmaxf(v[0], 0.f) * rinv, t1 = fmaxf(v[1], 0.f) * rinv, t2 = fmaxf(v[2], 0.f) * rinv, t3 = fmaxf(v[3], 0.f) * rinv;
;                   o4.x = pack2(t0 * t0, t1 * t1); o4.y = pack2(t2 * t2, t3 * t3); }
;                 { const float t0 = fmaxf(v1[0], 0.f) * rinv, t1 = fmaxf(v1[1], 0.f) * rinv, t2 = fmaxf(v1[2], 0.f) * rinv, t3 = fmaxf(v1[3], 0.f) * rinv;
;                   o4.z = pack2(t0 * t0, t1 * t1); o4.w = pack2(t2 * t2, t3 * t3); }
;                 *(u32x4*)((u16*)big + (size_t)token * 4096 + u.pn * 256 + bj * 128 + wc * 32 + 8 * fq) = o4;
;               }
;             }
;           }
;         if (EPI == EPI_RESID) {
;           ssq += shx(ssq, 16, t_ & 63);
;           ssq += shx(ssq, 32, t_ & 63);
;           if (fq == 0) ss_out[(size_t)token * 16 + u.pn * 4 + wc] = ssq;
;         }
.LBB0_1708:
	s_waitcnt vmcnt(0)
	v_add_f32_e32 v36, v36, v40
	v_add_f32_e32 v37, v37, v41
	v_mul_f32_e32 v54, v63, v63
	v_add_f32_e32 v38, v38, v42
	v_add_f32_e32 v39, v39, v43
	v_add_f32_e32 v42, v32, v44
	v_add_f32_e32 v43, v33, v45
	v_mul_f32_e32 v32, v37, v37
	v_fmac_f32_e32 v54, v62, v62
	v_fmac_f32_e32 v32, v36, v36
	v_fmac_f32_e32 v54, v50, v50
	v_fmac_f32_e32 v32, v38, v38
	v_fmac_f32_e32 v54, v51, v51
	v_fmac_f32_e32 v32, v39, v39
	v_fmac_f32_e32 v54, v52, v52
	v_fmac_f32_e32 v32, v42, v42
	v_fmac_f32_e32 v54, v53, v53
	v_add_f32_e32 v40, v34, v46
	v_add_f32_e32 v41, v35, v47
	v_fmac_f32_e32 v32, v43, v43
	v_fmac_f32_e32 v54, v48, v48
	v_fmac_f32_e32 v32, v40, v40
	v_fmac_f32_e32 v54, v49, v49
	v_fmac_f32_e32 v32, v41, v41
	v_add_f32_e32 v32, v54, v32
	ds_bpermute_b32 v33, v129, v32
	v_cvt_pk_bf16_f32 v34, v36, v37
	v_cvt_pk_bf16_f32 v35, v38, v39
	v_cvt_pk_bf16_f32 v36, v42, v43
	v_cvt_pk_bf16_f32 v37, v40, v41
	s_waitcnt lgkmcnt(0)
	v_add_f32_e32 v32, v32, v33
	ds_bpermute_b32 v33, v128, v32
	global_store_dwordx4 v[58:59], v[34:37], off offset:256
	s_and_saveexec_b64 s[34:35], s[4:5]
	s_cbranch_execz .LBB0_1710
	s_waitcnt lgkmcnt(0)
	v_add_f32_e32 v34, v32, v33
	v_lshlrev_b64 v[32:33], 6, v[56:57]
	v_lshl_add_u64 v[32:33], s[10:11], 0, v[32:33]
	v_lshl_add_u64 v[32:33], s[28:29], 2, v[32:33]
	s_lshl_b32 s24, s46, 2
	v_lshl_add_u64 v[32:33], v[32:33], 0, s[24:25]
	global_store_dword v[32:33], v34, off

; DI float bf2f(unsigned v) { return __uint_as_float(v << 16); }
;   DI void operator()(const f32x4 (&acc)[2][2][4][2], const pg8::Unit& u, int wr, int wc, int fr_, int fq_) const {
;     ...
;             } else if (EPI == EPI_RESID) {
;               if (n == 0) {
;                 const int f8 = u.pn * 256 + bj * 128 + wc * 32 + 8 * fq;
;                 const f32x4 v1 = acc[ai][bj][m][1];
;                 f32x4 r0, r1;
;                 if (rsrc) {
;                   r0 = *(const f32x4*)(rsrc + (size_t)token * 1024 + f8); r1 = *(const f32x4*)(rsrc + (size_t)token * 1024 + f8 + 4);
;                 } else {
;                   const u32x4 xu = *(const u32x4*)(xr + (size_t)token * 1024 + f8);
;                   r0 = (f32x4){bf2f(xu.x & 0xffffu), bf2f(xu.x >> 16), bf2f(xu.y & 0xffffu), bf2f(xu.y >> 16)};
;                   r1 = (f32x4){bf2f(xu.z & 0xffffu), bf2f(xu.z >> 16), bf2f(xu.w & 0xffffu), bf2f(xu.w >> 16)};
;                 }
;                 r0 += v; r1 += v1;
;                 st_bf8(xr + (size_t)token * 1024 + f8, r0, r1, 1.f);
.LBB0_1716:
	s_waitcnt vmcnt(0)
	v_add_f32_e32 v34, v30, v34
	v_add_f32_e32 v35, v31, v35
	v_add_f32_e32 v46, v28, v32
	v_add_f32_e32 v47, v29, v33
	v_add_f32_e32 v32, v26, v38
	v_add_f32_e32 v33, v27, v39
	v_add_f32_e32 v36, v24, v36
	v_add_f32_e32 v37, v25, v37
	v_cvt_pk_bf16_f32 v24, v46, v47
	v_cvt_pk_bf16_f32 v25, v34, v35
	v_cvt_pk_bf16_f32 v26, v36, v37
	v_cvt_pk_bf16_f32 v27, v32, v33
	s_and_b64 vcc, exec, s[2:3]
	global_store_dwordx4 v[42:43], v[24:27], off
	s_cbranch_vccnz .LBB0_1723
	global_load_dwordx4 v[28:31], v[44:45], off offset:528
	global_load_dwordx4 v[24:27], v[44:45], off offset:512
	s_cbranch_execnz .LBB0_1719

;   DI void operator()(const f32x4 (&acc)[2][2][4][2], const pg8::Unit& u, int wr, int wc, int fr_, int fq_) const {
;     ...
;                 r0 += v; r1 += v1;
;                 st_bf8(xr + (size_t)token * 1024 + f8, r0, r1, 1.f);
;                 ssq += r0[0] * r0[0] + r0[1] * r0[1] + r0[2] * r0[2] + r0[3] * r0[3] + r1[0] * r1[0] + r1[1] * r1[1] + r1[2] * r1[2] + r1[3] * r1[3];
;               }
;             } else {
;               if (n == 0) {
;                 const f32x4 v1 = acc[ai][bj][m][1];
;                 u32x4 o4;
;                 { const float t0 = fmaxf(v[0], 0.f) * rinv, t1 = fmaxf(v[1], 0.f) * rinv, t2 = fmaxf(v[2], 0.f) * rinv, t3 = fmaxf(v[3], 0.f) * rinv;
;                   o4.x = pack2(t0 * t0, t1 * t1); o4.y = pack2(t2 * t2, t3 * t3); }
;                 { const float t0 = fmaxf(v1[0], 0.f) * rinv, t1 = fmaxf(v1[1], 0.f) * rinv, t2 = fmaxf(v1[2], 0.f) * rinv, t3 = fmaxf(v1[3], 0.f) * rinv;
;                   o4.z = pack2(t0 * t0, t1 * t1); o4.w = pack2(t2 * t2, t3 * t3); }
;                 *(u32x4*)((u16*)big + (size_t)token * 4096 + u.pn * 256 + bj * 128 + wc * 32 + 8 * fq) = o4;
;               }
;             }
;           }
;         if (EPI == EPI_RESID) {
;           ssq += shx(ssq, 16, t_ & 63);
;           ssq += shx(ssq, 32, t_ & 63);
;           if (fq == 0) ss_out[(size_t)token * 16 + u.pn * 4 + wc] = ssq;
;         }
.LBB0_1719:
	s_waitcnt vmcnt(0)
	v_add_f32_e32 v20, v20, v24
	v_add_f32_e32 v21, v21, v25
	v_mul_f32_e32 v38, v47, v47
	v_add_f32_e32 v22, v22, v26
	v_add_f32_e32 v23, v23, v27
	v_add_f32_e32 v26, v16, v28
	v_add_f32_e32 v27, v17, v29
	v_mul_f32_e32 v16, v21, v21
	v_fmac_f32_e32 v38, v46, v46
	v_fmac_f32_e32 v16, v20, v20
	v_fmac_f32_e32 v38, v34, v34
	v_fmac_f32_e32 v16, v22, v22
	v_fmac_f32_e32 v38, v35, v35
	v_fmac_f32_e32 v16, v23, v23
	v_fmac_f32_e32 v38, v36, v36
	v_fmac_f32_e32 v16, v26, v26
	v_fmac_f32_e32 v38, v37, v37
	v_add_f32_e32 v24, v18, v30
	v_add_f32_e32 v25, v19, v31
	v_fmac_f32_e32 v16, v27, v27
	v_fmac_f32_e32 v38, v32, v32
	v_fmac_f32_e32 v16, v24, v24
	v_fmac_f32_e32 v38, v33, v33
	v_fmac_f32_e32 v16, v25, v25
	v_add_f32_e32 v16, v38, v16
	ds_bpermute_b32 v17, v129, v16
	v_cvt_pk_bf16_f32 v18, v20, v21
	v_cvt_pk_bf16_f32 v19, v22, v23
	v_cvt_pk_bf16_f32 v20, v26, v27
	v_cvt_pk_bf16_f32 v21, v24, v25
	s_waitcnt lgkmcnt(0)
	v_add_f32_e32 v16, v16, v17
	ds_bpermute_b32 v17, v128, v16
	global_store_dwordx4 v[42:43], v[18:21], off offset:256
	s_and_saveexec_b64 s[34:35], s[4:5]
	s_cbranch_execz .LBB0_1721
	s_waitcnt lgkmcnt(0)
	v_add_f32_e32 v18, v16, v17
	v_lshlrev_b64 v[16:17], 6, v[40:41]
	v_lshl_add_u64 v[16:17], s[10:11], 0, v[16:17]
	v_lshl_add_u64 v[16:17], s[28:29], 2, v[16:17]
	s_lshl_b32 s24, s46, 2
	v_lshl_add_u64 v[16:17], v[16:17], 0, s[24:25]
	global_store_dword v[16:17], v18, off

; DI float bf2f(unsigned v) { return __uint_as_float(v << 16); }
;   DI void operator()(const f32x4 (&acc)[2][2][4][2], const pg8::Unit& u, int wr, int wc, int fr_, int fq_) const {
;     ...
;             } else if (EPI == EPI_RESID) {
;               if (n == 0) {
;                 const int f8 = u.pn * 256 + bj * 128 + wc * 32 + 8 * fq;
;                 const f32x4 v1 = acc[ai][bj][m][1];
;                 f32x4 r0, r1;
;                 if (rsrc) {
;                   r0 = *(const f32x4*)(rsrc + (size_t)token * 1024 + f8); r1 = *(const f32x4*)(rsrc + (size_t)token * 1024 + f8 + 4);
;                 } else {
;                   const u32x4 xu = *(const u32x4*)(xr + (size_t)token * 1024 + f8);
;                   r0 = (f32x4){bf2f(xu.x & 0xffffu), bf2f(xu.x >> 16), bf2f(xu.y & 0xffffu), bf2f(xu.y >> 16)};
;                   r1 = (f32x4){bf2f(xu.z & 0xffffu), bf2f(xu.z >> 16), bf2f(xu.w & 0xffffu), bf2f(xu.w >> 16)};
;                 }
;                 r0 += v; r1 += v1;
;                 st_bf8(xr + (size_t)token * 1024 + f8, r0, r1, 1.f);
.LBB0_1727:
	s_waitcnt vmcnt(0)
	v_add_f32_e32 v18, v14, v18
	v_add_f32_e32 v19, v15, v19
	v_add_f32_e32 v30, v12, v16
	v_add_f32_e32 v31, v13, v17
	v_add_f32_e32 v16, v10, v22
	v_add_f32_e32 v17, v11, v23
	v_add_f32_e32 v20, v8, v20
	v_add_f32_e32 v21, v9, v21
	v_cvt_pk_bf16_f32 v8, v30, v31
	v_cvt_pk_bf16_f32 v9, v18, v19
	v_cvt_pk_bf16_f32 v10, v20, v21
	v_cvt_pk_bf16_f32 v11, v16, v17
	s_and_b64 vcc, exec, s[2:3]
	global_store_dwordx4 v[26:27], v[8:11], off
	s_cbranch_vccnz .LBB0_1732
	global_load_dwordx4 v[12:15], v[28:29], off offset:528
	global_load_dwordx4 v[8:11], v[28:29], off offset:512
	s_cbranch_execnz .LBB0_1730

;   DI void operator()(const f32x4 (&acc)[2][2][4][2], const pg8::Unit& u, int wr, int wc, int fr_, int fq_) const {
;     ...
;                 r0 += v; r1 += v1;
;                 st_bf8(xr + (size_t)token * 1024 + f8, r0, r1, 1.f);
;                 ssq += r0[0] * r0[0] + r0[1] * r0[1] + r0[2] * r0[2] + r0[3] * r0[3] + r1[0] * r1[0] + r1[1] * r1[1] + r1[2] * r1[2] + r1[3] * r1[3];
;               }
;             } else {
;               if (n == 0) {
;                 const f32x4 v1 = acc[ai][bj][m][1];
;                 u32x4 o4;
;                 { const float t0 = fmaxf(v[0], 0.f) * rinv, t1 = fmaxf(v[1], 0.f) * rinv, t2 = fmaxf(v[2], 0.f) * rinv, t3 = fmaxf(v[3], 0.f) * rinv;
;                   o4.x = pack2(t0 * t0, t1 * t1); o4.y = pack2(t2 * t2, t3 * t3); }
;                 { const float t0 = fmaxf(v1[0], 0.f) * rinv, t1 = fmaxf(v1[1], 0.f) * rinv, t2 = fmaxf(v1[2], 0.f) * rinv, t3 = fmaxf(v1[3], 0.f) * rinv;
;                   o4.z = pack2(t0 * t0, t1 * t1); o4.w = pack2(t2 * t2, t3 * t3); }
;                 *(u32x4*)((u16*)big + (size_t)token * 4096 + u.pn * 256 + bj * 128 + wc * 32 + 8 * fq) = o4;
;               }
;             }
;           }
;         if (EPI == EPI_RESID) {
;           ssq += shx(ssq, 16, t_ & 63);
;           ssq += shx(ssq, 32, t_ & 63);
;           if (fq == 0) ss_out[(size_t)token * 16 + u.pn * 4 + wc] = ssq;
;         }
.LBB0_1730:
	s_waitcnt vmcnt(0)
	v_add_f32_e32 v4, v4, v8
	v_add_f32_e32 v5, v5, v9
	v_mul_f32_e32 v22, v31, v31
	v_add_f32_e32 v6, v6, v10
	v_add_f32_e32 v7, v7, v11
	v_add_f32_e32 v10, v0, v12
	v_add_f32_e32 v11, v1, v13
	v_mul_f32_e32 v0, v5, v5
	v_fmac_f32_e32 v22, v30, v30
	v_fmac_f32_e32 v0, v4, v4
	v_fmac_f32_e32 v22, v18, v18
	v_fmac_f32_e32 v0, v6, v6
	v_fmac_f32_e32 v22, v19, v19
	v_fmac_f32_e32 v0, v7, v7
	v_fmac_f32_e32 v22, v20, v20
	v_fmac_f32_e32 v0, v10, v10
	v_fmac_f32_e32 v22, v21, v21
	v_add_f32_e32 v8, v2, v14
	v_add_f32_e32 v9, v3, v15
	v_fmac_f32_e32 v0, v11, v11
	v_fmac_f32_e32 v22, v16, v16
	v_fmac_f32_e32 v0, v8, v8
	v_fmac_f32_e32 v22, v17, v17
	v_fmac_f32_e32 v0, v9, v9
	v_add_f32_e32 v0, v22, v0
	ds_bpermute_b32 v1, v129, v0
	v_cvt_pk_bf16_f32 v2, v4, v5
	v_cvt_pk_bf16_f32 v3, v6, v7
	v_cvt_pk_bf16_f32 v4, v10, v11
	v_cvt_pk_bf16_f32 v5, v8, v9
	s_waitcnt lgkmcnt(0)
	v_add_f32_e32 v0, v0, v1
	ds_bpermute_b32 v1, v128, v0
	global_store_dwordx4 v[26:27], v[2:5], off offset:256
	s_and_saveexec_b64 s[2:3], s[4:5]
	s_cbranch_execz .LBB0_1636
	s_waitcnt lgkmcnt(0)
	v_add_f32_e32 v2, v0, v1
	v_lshlrev_b64 v[0:1], 6, v[24:25]
	v_lshl_add_u64 v[0:1], s[10:11], 0, v[0:1]
	v_lshl_add_u64 v[0:1], s[28:29], 2, v[0:1]
	s_lshl_b32 s24, s46, 2
	v_lshl_add_u64 v[0:1], v[0:1], 0, s[24:25]
	global_store_dword v[0:1], v2, off
	s_branch .LBB0_1636

; #define PG8_STAGE(bufoff, gbase, voff) do { _Pragma("unroll") for (int _i = 0; _i < 2; ++_i) \
;     __builtin_amdgcn_global_load_lds((const unsigned*)((const char*)(gbase) + (voff)[_i]), (LAS unsigned*)(lds + (bufoff) + ldsw + _i * 8192), 16, 0, 0); } while (0)
; #define PG8_LDA(dst, b, h) do { _Pragma("unroll") for (int m = 0; m < 4; ++m) _Pragma("unroll") for (int k = 0; k < 2; ++k) dst[m][k] = *(const LAS bf16x8*)(lds + PG8_SA(b, h) + aoff + m * 2048 + k * 1024); } while (0)
; #define PG8_LDB(dst, b, h) do { _Pragma("unroll") for (int n = 0; n < 2; ++n) _Pragma("unroll") for (int k = 0; k < 2; ++k) dst[n][k] = *(const LAS bf16x8*)(lds + PG8_SB(b, h) + boff + n * 2048 + k * 1024); } while (0)
; #define PG8_MMA(ai, bj, At, Bt) do { __builtin_amdgcn_s_setprio(1); _Pragma("unroll") for (int m = 0; m < 4; ++m) _Pragma("unroll") for (int n = 0; n < 2; ++n) _Pragma("unroll") for (int k = 0; k < 2; ++k) \
;     acc[ai][bj][m][n] = __builtin_amdgcn_mfma_f32_16x16x32_bf16(Bt[n][k], At[m][k], acc[ai][bj][m][n], 0, 0, 0); __builtin_amdgcn_s_setprio(0); } while (0)
; #define PG8_WAIT_V(n) asm volatile("s_waitcnt vmcnt(" #n ")" ::: "memory")
; #define PG8_WAIT_L(n) asm volatile("s_waitcnt lgkmcnt(" #n ")" ::: "memory")
; #define PG8_BAR __builtin_amdgcn_s_barrier()
; #define PG8_SCHED __builtin_amdgcn_sched_barrier(0)
; template <class Epi, class Sched>
; DI void gemm_phase(LAS unsigned char* lds, const Gemm g, const Sched& S, const Epi& E) {
;     ...
;     for (int t = 0; t < nt; t += 2) {
;       const bool last = (t == nt - 2);
;       const char* a1 = cA + (size_t)(t + 1) * kstep;
;       const char* a2 = last ? nA : cA + (size_t)(t + 2) * kstep; const char* b2 = last ? nB : cB + (size_t)(t + 2) * kstep;
;       const char* a3 = a2 + kstep; const char* b3 = b2 + kstep;
;       PG8_LDB(B0, 0, 0); PG8_SCHED; PG8_LDA(At, 0, 0); PG8_STAGE(PG8_SA(1, 1), a1 + hstep, voffA);
;       PG8_WAIT_L(8); PG8_BAR; PG8_WAIT_L(0); PG8_MMA(0, 0, At, B0); PG8_BAR; PG8_SCHED;
;       PG8_LDB(B1, 0, 1); PG8_STAGE(PG8_SB(0, 0), b2, voffB);
;       PG8_BAR; PG8_WAIT_L(0); PG8_MMA(0, 1, At, B1); PG8_BAR;
;       PG8_LDA(At, 0, 1); PG8_STAGE(PG8_SA(0, 0), a2, voffA);
;       PG8_BAR; PG8_WAIT_L(0); PG8_MMA(1, 0, At, B0); PG8_BAR; PG8_SCHED;
;       PG8_STAGE(PG8_SB(0, 1), b2 + hstep, voffB);
;       PG8_WAIT_V(6); PG8_BAR; PG8_MMA(1, 1, At, B1); PG8_BAR;
.LBB0_1829:
	s_add_u32 s16, s14, 0xfffc0080
	s_addc_u32 s17, s15, -1
	s_add_i32 s51, 0, 0x10000
	ds_read_b128 v[146:149], v224
	ds_read_b128 v[150:153], v224 offset:1024
	ds_read_b128 v[154:157], v224 offset:2048
	ds_read_b128 v[158:161], v224 offset:3072
	s_cmp_eq_u32 s50, 12
	s_cselect_b32 s19, s7, s17
	s_cselect_b32 s18, s46, s16
	s_cselect_b32 s17, s5, s49
	s_cselect_b32 s16, s47, s48
	s_add_i32 m0, s29, 0xc000
	ds_read_b128 v[162:165], v143
	ds_read_b128 v[166:169], v143 offset:1024
	ds_read_b128 v[170:173], v143 offset:2048
	ds_read_b128 v[174:177], v143 offset:3072
	ds_read_b128 v[178:181], v143 offset:4096
	ds_read_b128 v[196:199], v143 offset:5120
	ds_read_b128 v[200:203], v143 offset:6144
	ds_read_b128 v[204:207], v143 offset:7168
	global_load_lds_dwordx4 v136, s[14:15]
	s_add_i32 m0, s29, 0xe000
	s_nop 0
	global_load_lds_dwordx4 v138, s[14:15]
	s_waitcnt lgkmcnt(8)
	s_barrier
	s_waitcnt lgkmcnt(0)
	v_mfma_f32_16x16x32_bf16 v[124:127], v[146:149], v[162:165], v[124:127]
	v_mfma_f32_16x16x32_bf16 v[120:123], v[154:157], v[162:165], v[120:123]
	v_mfma_f32_16x16x32_bf16 v[112:115], v[146:149], v[170:173], v[112:115]
	v_mfma_f32_16x16x32_bf16 v[104:107], v[154:157], v[170:173], v[104:107]
	v_mfma_f32_16x16x32_bf16 v[92:95], v[146:149], v[178:181], v[92:95]
	v_mfma_f32_16x16x32_bf16 v[88:91], v[154:157], v[178:181], v[88:91]
	v_mfma_f32_16x16x32_bf16 v[80:83], v[146:149], v[200:203], v[80:83]
	v_mfma_f32_16x16x32_bf16 v[72:75], v[154:157], v[200:203], v[72:75]
	v_mfma_f32_16x16x32_bf16 v[124:127], v[150:153], v[166:169], v[124:127]
	v_mfma_f32_16x16x32_bf16 v[120:123], v[158:161], v[166:169], v[120:123]
	v_mfma_f32_16x16x32_bf16 v[112:115], v[150:153], v[174:177], v[112:115]
	v_mfma_f32_16x16x32_bf16 v[104:107], v[158:161], v[174:177], v[104:107]
	v_mfma_f32_16x16x32_bf16 v[92:95], v[150:153], v[196:199], v[92:95]
	v_mfma_f32_16x16x32_bf16 v[88:91], v[158:161], v[196:199], v[88:91]
	v_mfma_f32_16x16x32_bf16 v[80:83], v[150:153], v[204:207], v[80:83]
	v_mfma_f32_16x16x32_bf16 v[72:75], v[158:161], v[204:207], v[72:75]
	s_barrier
	s_add_i32 s54, 0, 0x14000
	s_add_i32 s51, s51, s20
	ds_read_b128 v[208:211], v225
	ds_read_b128 v[212:215], v225 offset:1024
	ds_read_b128 v[216:219], v225 offset:2048
	ds_read_b128 v[220:223], v225 offset:3072
	s_add_u32 vcc_lo, s16, s0
	s_addc_u32 vcc_hi, s17, s1
	s_mov_b32 m0, s51
	s_nop 0
	global_load_lds_dwordx4 v132, s[16:17]
	s_add_i32 m0, s51, 0x2000
	s_nop 0
	global_load_lds_dwordx4 v128, s[16:17]
	s_barrier
	s_waitcnt lgkmcnt(0)
	v_mfma_f32_16x16x32_bf16 v[116:119], v[208:211], v[162:165], v[116:119]
	v_mfma_f32_16x16x32_bf16 v[108:111], v[216:219], v[162:165], v[108:111]
	v_mfma_f32_16x16x32_bf16 v[100:103], v[208:211], v[170:173], v[100:103]
	v_mfma_f32_16x16x32_bf16 v[96:99], v[216:219], v[170:173], v[96:99]
	v_mfma_f32_16x16x32_bf16 v[84:87], v[208:211], v[178:181], v[84:87]
	v_mfma_f32_16x16x32_bf16 v[76:79], v[216:219], v[178:181], v[76:79]
	v_mfma_f32_16x16x32_bf16 v[68:71], v[208:211], v[200:203], v[68:71]
	v_mfma_f32_16x16x32_bf16 v[64:67], v[216:219], v[200:203], v[64:67]
	v_mfma_f32_16x16x32_bf16 v[116:119], v[212:215], v[166:169], v[116:119]
	v_mfma_f32_16x16x32_bf16 v[108:111], v[220:223], v[166:169], v[108:111]
	v_mfma_f32_16x16x32_bf16 v[100:103], v[212:215], v[174:177], v[100:103]
	v_mfma_f32_16x16x32_bf16 v[96:99], v[220:223], v[174:177], v[96:99]
	v_mfma_f32_16x16x32_bf16 v[84:87], v[212:215], v[196:199], v[84:87]
	v_mfma_f32_16x16x32_bf16 v[76:79], v[220:223], v[196:199], v[76:79]
	v_mfma_f32_16x16x32_bf16 v[68:71], v[212:215], v[204:207], v[68:71]
	v_mfma_f32_16x16x32_bf16 v[64:67], v[220:223], v[204:207], v[64:67]
	s_mov_b32 m0, s29
	s_add_u32 s100, s18, s0
	s_addc_u32 s101, s19, s1
	s_barrier
	ds_read_b128 v[162:165], v143 offset:16384
	ds_read_b128 v[166:169], v143 offset:17408
	ds_read_b128 v[170:173], v143 offset:18432
	ds_read_b128 v[174:177], v143 offset:19456
	ds_read_b128 v[178:181], v143 offset:20480
	ds_read_b128 v[196:199], v143 offset:21504
	ds_read_b128 v[200:203], v143 offset:22528
	ds_read_b128 v[204:207], v143 offset:23552
	global_load_lds_dwordx4 v134, s[18:19]
	s_mov_b32 m0, s34
	s_nop 0
	global_load_lds_dwordx4 v130, s[18:19]
	s_barrier
	s_waitcnt lgkmcnt(0)
	v_mfma_f32_16x16x32_bf16 v[60:63], v[146:149], v[162:165], v[60:63]
	v_mfma_f32_16x16x32_bf16 v[56:59], v[154:157], v[162:165], v[56:59]
	v_mfma_f32_16x16x32_bf16 v[48:51], v[146:149], v[170:173], v[48:51]
	v_mfma_f32_16x16x32_bf16 v[40:43], v[154:157], v[170:173], v[40:43]
	v_mfma_f32_16x16x32_bf16 v[28:31], v[146:149], v[178:181], v[28:31]
	v_mfma_f32_16x16x32_bf16 v[24:27], v[154:157], v[178:181], v[24:27]
	v_mfma_f32_16x16x32_bf16 v[16:19], v[146:149], v[200:203], v[16:19]
	v_mfma_f32_16x16x32_bf16 v[8:11], v[154:157], v[200:203], v[8:11]
	v_mfma_f32_16x16x32_bf16 v[60:63], v[150:153], v[166:169], v[60:63]
	v_mfma_f32_16x16x32_bf16 v[56:59], v[158:161], v[166:169], v[56:59]
	v_mfma_f32_16x16x32_bf16 v[48:51], v[150:153], v[174:177], v[48:51]
	v_mfma_f32_16x16x32_bf16 v[40:43], v[158:161], v[174:177], v[40:43]
	v_mfma_f32_16x16x32_bf16 v[28:31], v[150:153], v[196:199], v[28:31]
	v_mfma_f32_16x16x32_bf16 v[24:27], v[158:161], v[196:199], v[24:27]
	v_mfma_f32_16x16x32_bf16 v[16:19], v[150:153], v[204:207], v[16:19]
	v_mfma_f32_16x16x32_bf16 v[8:11], v[158:161], v[204:207], v[8:11]
	s_barrier
	s_add_u32 s52, s16, 0x40000
	s_addc_u32 s53, s17, 0
	s_add_i32 s51, s54, s20
	s_mov_b32 m0, s51
	s_nop 0
	global_load_lds_dwordx4 v132, s[52:53]
	s_add_i32 m0, s51, 0x2000
	s_nop 0
	global_load_lds_dwordx4 v128, s[52:53]
	s_waitcnt vmcnt(6)
	s_barrier
; #define PG8_STAGE(bufoff, gbase, voff) do { _Pragma("unroll") for (int _i = 0; _i < 2; ++_i) \
;     __builtin_amdgcn_global_load_lds((const unsigned*)((const char*)(gbase) + (voff)[_i]), (LAS unsigned*)(lds + (bufoff) + ldsw + _i * 8192), 16, 0, 0); } while (0)
; #define PG8_LDA(dst, b, h) do { _Pragma("unroll") for (int m = 0; m < 4; ++m) _Pragma("unroll") for (int k = 0; k < 2; ++k) dst[m][k] = *(const LAS bf16x8*)(lds + PG8_SA(b, h) + aoff + m * 2048 + k * 1024); } while (0)
; #define PG8_LDB(dst, b, h) do { _Pragma("unroll") for (int n = 0; n < 2; ++n) _Pragma("unroll") for (int k = 0; k < 2; ++k) dst[n][k] = *(const LAS bf16x8*)(lds + PG8_SB(b, h) + boff + n * 2048 + k * 1024); } while (0)
; #define PG8_MMA(ai, bj, At, Bt) do { __builtin_amdgcn_s_setprio(1); _Pragma("unroll") for (int m = 0; m < 4; ++m) _Pragma("unroll") for (int n = 0; n < 2; ++n) _Pragma("unroll") for (int k = 0; k < 2; ++k) \
;     acc[ai][bj][m][n] = __builtin_amdgcn_mfma_f32_16x16x32_bf16(Bt[n][k], At[m][k], acc[ai][bj][m][n], 0, 0, 0); __builtin_amdgcn_s_setprio(0); } while (0)
; #define PG8_WAIT_V(n) asm volatile("s_waitcnt vmcnt(" #n ")" ::: "memory")
; #define PG8_WAIT_L(n) asm volatile("s_waitcnt lgkmcnt(" #n ")" ::: "memory")
; #define PG8_BAR __builtin_amdgcn_s_barrier()
; #define PG8_SCHED __builtin_amdgcn_sched_barrier(0)
; template <class Epi, class Sched>
; DI void gemm_phase(LAS unsigned char* lds, const Gemm g, const Sched& S, const Epi& E) {
;     ...
;       PG8_WAIT_V(6); PG8_BAR; PG8_MMA(1, 1, At, B1); PG8_BAR;
;       PG8_LDB(B0, 1, 0); PG8_SCHED; PG8_LDA(At, 1, 0); PG8_STAGE(PG8_SA(0, 1), a2 + hstep, voffA);
;       PG8_WAIT_L(8); PG8_BAR; PG8_WAIT_L(0); PG8_MMA(0, 0, At, B0); PG8_BAR; PG8_SCHED;
;       PG8_LDB(B1, 1, 1); PG8_STAGE(PG8_SB(1, 0), b3, voffB);
;       PG8_BAR; PG8_WAIT_L(0); PG8_MMA(0, 1, At, B1); PG8_BAR;
;       PG8_LDA(At, 1, 1); PG8_STAGE(PG8_SA(1, 0), a3, voffA);
;       PG8_BAR; PG8_WAIT_L(0); PG8_MMA(1, 0, At, B0); PG8_BAR; PG8_SCHED;
	v_mfma_f32_16x16x32_bf16 v[52:55], v[208:211], v[162:165], v[52:55]
	v_mfma_f32_16x16x32_bf16 v[44:47], v[216:219], v[162:165], v[44:47]
	v_mfma_f32_16x16x32_bf16 v[36:39], v[208:211], v[170:173], v[36:39]
	v_mfma_f32_16x16x32_bf16 v[32:35], v[216:219], v[170:173], v[32:35]
	v_mfma_f32_16x16x32_bf16 v[20:23], v[208:211], v[178:181], v[20:23]
	v_mfma_f32_16x16x32_bf16 v[12:15], v[216:219], v[178:181], v[12:15]
	v_mfma_f32_16x16x32_bf16 v[4:7], v[208:211], v[200:203], v[4:7]
	v_mfma_f32_16x16x32_bf16 v[0:3], v[216:219], v[200:203], v[0:3]
	v_mfma_f32_16x16x32_bf16 v[52:55], v[212:215], v[166:169], v[52:55]
	v_mfma_f32_16x16x32_bf16 v[44:47], v[220:223], v[166:169], v[44:47]
	v_mfma_f32_16x16x32_bf16 v[36:39], v[212:215], v[174:177], v[36:39]
	v_mfma_f32_16x16x32_bf16 v[32:35], v[220:223], v[174:177], v[32:35]
	v_mfma_f32_16x16x32_bf16 v[20:23], v[212:215], v[196:199], v[20:23]
	v_mfma_f32_16x16x32_bf16 v[12:15], v[220:223], v[196:199], v[12:15]
	v_mfma_f32_16x16x32_bf16 v[4:7], v[212:215], v[204:207], v[4:7]
	v_mfma_f32_16x16x32_bf16 v[0:3], v[220:223], v[204:207], v[0:3]
	s_add_i32 s51, 0, 0x18000
	s_barrier
	ds_read_b128 v[146:149], v226
	ds_read_b128 v[150:153], v226 offset:1024
	ds_read_b128 v[154:157], v226 offset:2048
	ds_read_b128 v[158:161], v226 offset:3072
	s_add_u32 s18, s18, 0x40000
	s_addc_u32 s19, s19, 0
	s_mov_b32 m0, s35
	ds_read_b128 v[162:165], v143 offset:32768
	ds_read_b128 v[166:169], v143 offset:33792
	ds_read_b128 v[170:173], v143 offset:34816
	ds_read_b128 v[174:177], v143 offset:35840
	ds_read_b128 v[178:181], v143 offset:36864
	ds_read_b128 v[196:199], v143 offset:37888
	ds_read_b128 v[200:203], v143 offset:38912
	ds_read_b128 v[204:207], v143 offset:39936
	global_load_lds_dwordx4 v134, s[18:19]
	s_mov_b32 m0, s38
	s_nop 0
	global_load_lds_dwordx4 v130, s[18:19]
	s_waitcnt lgkmcnt(8)
	s_barrier
	s_waitcnt lgkmcnt(0)
	v_mfma_f32_16x16x32_bf16 v[124:127], v[146:149], v[162:165], v[124:127]
	v_mfma_f32_16x16x32_bf16 v[120:123], v[154:157], v[162:165], v[120:123]
	v_mfma_f32_16x16x32_bf16 v[112:115], v[146:149], v[170:173], v[112:115]
	v_mfma_f32_16x16x32_bf16 v[104:107], v[154:157], v[170:173], v[104:107]
	v_mfma_f32_16x16x32_bf16 v[92:95], v[146:149], v[178:181], v[92:95]
	v_mfma_f32_16x16x32_bf16 v[88:91], v[154:157], v[178:181], v[88:91]
	v_mfma_f32_16x16x32_bf16 v[80:83], v[146:149], v[200:203], v[80:83]
	v_mfma_f32_16x16x32_bf16 v[72:75], v[154:157], v[200:203], v[72:75]
	v_mfma_f32_16x16x32_bf16 v[124:127], v[150:153], v[166:169], v[124:127]
	v_mfma_f32_16x16x32_bf16 v[120:123], v[158:161], v[166:169], v[120:123]
	v_mfma_f32_16x16x32_bf16 v[112:115], v[150:153], v[174:177], v[112:115]
	v_mfma_f32_16x16x32_bf16 v[104:107], v[158:161], v[174:177], v[104:107]
	v_mfma_f32_16x16x32_bf16 v[92:95], v[150:153], v[196:199], v[92:95]
	v_mfma_f32_16x16x32_bf16 v[88:91], v[158:161], v[196:199], v[88:91]
	v_mfma_f32_16x16x32_bf16 v[80:83], v[150:153], v[204:207], v[80:83]
	v_mfma_f32_16x16x32_bf16 v[72:75], v[158:161], v[204:207], v[72:75]
	s_barrier
	s_add_i32 s18, 0, 0x1c000
	s_add_i32 s19, s51, s20
	s_mov_b32 m0, s19
	ds_read_b128 v[208:211], v227
	ds_read_b128 v[212:215], v227 offset:1024
	ds_read_b128 v[216:219], v227 offset:2048
	ds_read_b128 v[220:223], v227 offset:3072
	global_load_lds_dwordx4 v132, vcc
	s_add_i32 m0, s19, 0x2000
	s_nop 0
	global_load_lds_dwordx4 v128, vcc
	s_barrier
	s_waitcnt lgkmcnt(0)
	v_mfma_f32_16x16x32_bf16 v[116:119], v[208:211], v[162:165], v[116:119]
	v_mfma_f32_16x16x32_bf16 v[108:111], v[216:219], v[162:165], v[108:111]
	v_mfma_f32_16x16x32_bf16 v[100:103], v[208:211], v[170:173], v[100:103]
	v_mfma_f32_16x16x32_bf16 v[96:99], v[216:219], v[170:173], v[96:99]
	v_mfma_f32_16x16x32_bf16 v[84:87], v[208:211], v[178:181], v[84:87]
	v_mfma_f32_16x16x32_bf16 v[76:79], v[216:219], v[178:181], v[76:79]
	v_mfma_f32_16x16x32_bf16 v[68:71], v[208:211], v[200:203], v[68:71]
	v_mfma_f32_16x16x32_bf16 v[64:67], v[216:219], v[200:203], v[64:67]
	v_mfma_f32_16x16x32_bf16 v[116:119], v[212:215], v[166:169], v[116:119]
	v_mfma_f32_16x16x32_bf16 v[108:111], v[220:223], v[166:169], v[108:111]
	v_mfma_f32_16x16x32_bf16 v[100:103], v[212:215], v[174:177], v[100:103]
	v_mfma_f32_16x16x32_bf16 v[96:99], v[220:223], v[174:177], v[96:99]
	v_mfma_f32_16x16x32_bf16 v[84:87], v[212:215], v[196:199], v[84:87]
	v_mfma_f32_16x16x32_bf16 v[76:79], v[220:223], v[196:199], v[76:79]
	v_mfma_f32_16x16x32_bf16 v[68:71], v[212:215], v[204:207], v[68:71]
	v_mfma_f32_16x16x32_bf16 v[64:67], v[220:223], v[204:207], v[64:67]
	s_mov_b32 m0, s40
	s_barrier
	ds_read_b128 v[162:165], v143 offset:49152
	ds_read_b128 v[166:169], v143 offset:50176
	ds_read_b128 v[170:173], v143 offset:51200
	ds_read_b128 v[174:177], v143 offset:52224
	ds_read_b128 v[178:181], v143 offset:53248
	ds_read_b128 v[196:199], v143 offset:54272
	ds_read_b128 v[200:203], v143 offset:55296
	ds_read_b128 v[204:207], v143 offset:56320
	global_load_lds_dwordx4 v134, s[100:101]
	s_mov_b32 m0, s41
	s_nop 0
	global_load_lds_dwordx4 v130, s[100:101]
	s_barrier
	s_waitcnt lgkmcnt(0)
	v_mfma_f32_16x16x32_bf16 v[60:63], v[146:149], v[162:165], v[60:63]
	v_mfma_f32_16x16x32_bf16 v[56:59], v[154:157], v[162:165], v[56:59]
	v_mfma_f32_16x16x32_bf16 v[48:51], v[146:149], v[170:173], v[48:51]
	v_mfma_f32_16x16x32_bf16 v[40:43], v[154:157], v[170:173], v[40:43]
	v_mfma_f32_16x16x32_bf16 v[28:31], v[146:149], v[178:181], v[28:31]
	v_mfma_f32_16x16x32_bf16 v[24:27], v[154:157], v[178:181], v[24:27]
	v_mfma_f32_16x16x32_bf16 v[16:19], v[146:149], v[200:203], v[16:19]
	v_mfma_f32_16x16x32_bf16 v[8:11], v[154:157], v[200:203], v[8:11]
	v_mfma_f32_16x16x32_bf16 v[60:63], v[150:153], v[166:169], v[60:63]
	v_mfma_f32_16x16x32_bf16 v[56:59], v[158:161], v[166:169], v[56:59]
	v_mfma_f32_16x16x32_bf16 v[48:51], v[150:153], v[174:177], v[48:51]
	v_mfma_f32_16x16x32_bf16 v[40:43], v[158:161], v[174:177], v[40:43]
	v_mfma_f32_16x16x32_bf16 v[28:31], v[150:153], v[196:199], v[28:31]
	v_mfma_f32_16x16x32_bf16 v[24:27], v[158:161], v[196:199], v[24:27]
	v_mfma_f32_16x16x32_bf16 v[16:19], v[150:153], v[204:207], v[16:19]
	v_mfma_f32_16x16x32_bf16 v[8:11], v[158:161], v[204:207], v[8:11]
	s_barrier
; #define PG8_STAGE(bufoff, gbase, voff) do { _Pragma("unroll") for (int _i = 0; _i < 2; ++_i) \
;     __builtin_amdgcn_global_load_lds((const unsigned*)((const char*)(gbase) + (voff)[_i]), (LAS unsigned*)(lds + (bufoff) + ldsw + _i * 8192), 16, 0, 0); } while (0)
; #define PG8_MMA(ai, bj, At, Bt) do { __builtin_amdgcn_s_setprio(1); _Pragma("unroll") for (int m = 0; m < 4; ++m) _Pragma("unroll") for (int n = 0; n < 2; ++n) _Pragma("unroll") for (int k = 0; k < 2; ++k) \
;     acc[ai][bj][m][n] = __builtin_amdgcn_mfma_f32_16x16x32_bf16(Bt[n][k], At[m][k], acc[ai][bj][m][n], 0, 0, 0); __builtin_amdgcn_s_setprio(0); } while (0)
; #define PG8_WAIT_V(n) asm volatile("s_waitcnt vmcnt(" #n ")" ::: "memory")
; #define PG8_BAR __builtin_amdgcn_s_barrier()
; template <class Epi, class Sched>
; DI void gemm_phase(LAS unsigned char* lds, const Gemm g, const Sched& S, const Epi& E) {
;     ...
;       PG8_STAGE(PG8_SB(1, 1), b3 + hstep, voffB);
;       PG8_WAIT_V(6); PG8_BAR; PG8_MMA(1, 1, At, B1); PG8_BAR;
;     }
;     E(acc, cur, wr, wc, fr, fq);
;   DI void operator()(const f32x4 (&acc)[2][2][4][2], const pg8::Unit& u, int wr, int wc, int fr_, int fq_) const {
;     ...
;             } else {
;               if (n == 0) {
;                 const f32x4 v1 = acc[ai][bj][m][1];
;                 u32x4 o4;
;                 { const float t0 = fmaxf(v[0], 0.f) * rinv, t1 = fmaxf(v[1], 0.f) * rinv, t2 = fmaxf(v[2], 0.f) * rinv, t3 = fmaxf(v[3], 0.f) * rinv;
;                   o4.x = pack2(t0 * t0, t1 * t1); o4.y = pack2(t2 * t2, t3 * t3); }
;                 { const float t0 = fmaxf(v1[0], 0.f) * rinv, t1 = fmaxf(v1[1], 0.f) * rinv, t2 = fmaxf(v1[2], 0.f) * rinv, t3 = fmaxf(v1[3], 0.f) * rinv;
;                   o4.z = pack2(t0 * t0, t1 * t1); o4.w = pack2(t2 * t2, t3 * t3); }
;                 *(u32x4*)((u16*)big + (size_t)token * 4096 + u.pn * 256 + bj * 128 + wc * 32 + 8 * fq) = o4;
	s_add_u32 s16, s16, 0x40080
	s_addc_u32 s17, s17, 0
	s_add_i32 s18, s18, s20
	s_mov_b32 m0, s18
	s_nop 0
	global_load_lds_dwordx4 v132, s[16:17]
	s_add_i32 m0, s18, 0x2000
	s_nop 0
	global_load_lds_dwordx4 v128, s[16:17]
	s_waitcnt vmcnt(6)
	s_barrier
	v_mfma_f32_16x16x32_bf16 v[52:55], v[208:211], v[162:165], v[52:55]
	v_mfma_f32_16x16x32_bf16 v[44:47], v[216:219], v[162:165], v[44:47]
	v_mfma_f32_16x16x32_bf16 v[36:39], v[208:211], v[170:173], v[36:39]
	v_mfma_f32_16x16x32_bf16 v[32:35], v[216:219], v[170:173], v[32:35]
	v_mfma_f32_16x16x32_bf16 v[20:23], v[208:211], v[178:181], v[20:23]
	v_mfma_f32_16x16x32_bf16 v[12:15], v[216:219], v[178:181], v[12:15]
	v_mfma_f32_16x16x32_bf16 v[4:7], v[208:211], v[200:203], v[4:7]
	v_mfma_f32_16x16x32_bf16 v[0:3], v[216:219], v[200:203], v[0:3]
	v_mfma_f32_16x16x32_bf16 v[52:55], v[212:215], v[166:169], v[52:55]
	v_mfma_f32_16x16x32_bf16 v[44:47], v[220:223], v[166:169], v[44:47]
	v_mfma_f32_16x16x32_bf16 v[36:39], v[212:215], v[174:177], v[36:39]
	v_mfma_f32_16x16x32_bf16 v[32:35], v[220:223], v[174:177], v[32:35]
	v_mfma_f32_16x16x32_bf16 v[20:23], v[212:215], v[196:199], v[20:23]
	v_mfma_f32_16x16x32_bf16 v[12:15], v[220:223], v[196:199], v[12:15]
	v_mfma_f32_16x16x32_bf16 v[4:7], v[212:215], v[204:207], v[4:7]
	v_mfma_f32_16x16x32_bf16 v[0:3], v[220:223], v[204:207], v[0:3]
	s_add_i32 s50, s50, 2
	s_add_u32 s14, s14, 0x100
	s_addc_u32 s15, s15, 0
	s_add_u32 s48, s48, 0x100
	s_addc_u32 s49, s49, 0
	s_cmp_gt_u32 s50, 13
	s_barrier
	s_cbranch_scc0 .LBB0_1829
	v_mov_b32_e32 v144, v182
	s_lshl_b32 s5, s43, 10
	s_add_i32 s5, s5, 0
	v_and_or_b32 v141, v144, 15, s39
	v_lshl_add_u32 v140, s44, 8, v141
	v_lshl_add_u32 v141, v141, 2, s5
	v_add_u32_e32 v146, 0x20000, v141
	ds_read2_b32 v[148:149], v146 offset1:16
	v_max_f32_e32 v124, 0, v124
	v_max_f32_e32 v125, 0, v125
	v_max_f32_e32 v126, 0, v126
	v_max_f32_e32 v127, 0, v127
	v_max_f32_e32 v120, 0, v120
	v_max_f32_e32 v121, 0, v121
	s_waitcnt lgkmcnt(0)
	v_mul_f32_e32 v124, v124, v148
	v_mul_f32_e32 v125, v125, v148
	v_mul_f32_e32 v126, v126, v148
	v_mul_f32_e32 v127, v127, v148
	v_mul_f32_e32 v120, v120, v148
	v_mul_f32_e32 v121, v121, v148
	v_mul_f32_e32 v124, v124, v124
	v_mul_f32_e32 v125, v125, v125
	v_mul_f32_e32 v126, v126, v126
	v_mul_f32_e32 v127, v127, v127
	v_max_f32_e32 v122, 0, v122
	v_max_f32_e32 v123, 0, v123
	v_mul_f32_e32 v120, v120, v120
	v_mul_f32_e32 v121, v121, v121
	v_max_f32_e32 v116, 0, v116
	v_max_f32_e32 v117, 0, v117
	v_max_f32_e32 v118, 0, v118
	v_max_f32_e32 v119, 0, v119
	v_max_f32_e32 v108, 0, v108
	v_max_f32_e32 v109, 0, v109
	s_lshl_b32 s14, s45, 8
	v_ashrrev_i32_e32 v141, 31, v140
	v_cvt_pk_bf16_f32 v124, v124, v125
	v_cvt_pk_bf16_f32 v125, v126, v127
	v_cvt_pk_bf16_f32 v126, v120, v121
	v_mul_f32_e32 v120, v122, v148
	v_mul_f32_e32 v121, v123, v148
	v_mul_f32_e32 v116, v116, v148
	v_mul_f32_e32 v117, v117, v148
	v_mul_f32_e32 v118, v118, v148
	v_mul_f32_e32 v119, v119, v148
	v_mul_f32_e32 v108, v108, v148
	v_mul_f32_e32 v109, v109, v148
	s_ashr_i32 s15, s14, 31
	v_lshlrev_b64 v[150:151], 13, v[140:141]
	v_mul_f32_e32 v120, v120, v120
	v_mul_f32_e32 v121, v121, v121
	v_mul_f32_e32 v116, v116, v116
	v_mul_f32_e32 v117, v117, v117
	v_mul_f32_e32 v118, v118, v118
	v_mul_f32_e32 v119, v119, v119
	v_max_f32_e32 v110, 0, v110
	v_max_f32_e32 v111, 0, v111
	v_mul_f32_e32 v108, v108, v108
	v_mul_f32_e32 v109, v109, v109
	v_cvt_pk_bf16_f32 v127, v120, v121
	v_lshl_add_u64 v[120:121], s[2:3], 0, v[150:151]
	s_lshl_b64 s[14:15], s[14:15], 1
	v_cvt_pk_bf16_f32 v116, v116, v117
	v_cvt_pk_bf16_f32 v117, v118, v119
	v_cvt_pk_bf16_f32 v118, v108, v109
	v_mul_f32_e32 v108, v110, v148
	v_mul_f32_e32 v109, v111, v148
	v_lshl_add_u64 v[120:121], v[120:121], 0, s[14:15]
	v_mul_f32_e32 v108, v108, v108
	v_mul_f32_e32 v109, v109, v109
	v_lshl_add_u64 v[120:121], v[120:121], 0, s[24:25]
	v_and_b32_e32 v144, 48, v144
	v_cvt_pk_bf16_f32 v119, v108, v109
	v_add_u32_e32 v108, 16, v140
	v_lshl_add_u64 v[120:121], v[120:121], 0, v[144:145]
	v_ashrrev_i32_e32 v109, 31, v108
	global_store_dwordx4 v[120:121], v[116:119], off offset:256
	v_max_f32_e32 v100, 0, v100
	v_max_f32_e32 v101, 0, v101
	v_lshlrev_b64 v[116:117], 13, v[108:109]
	v_max_f32_e32 v108, v112, v112
	v_mov_b32_e32 v112, v149
	v_max_f32_e32 v102, 0, v102
	v_max_f32_e32 v103, 0, v103
	v_max_f32_e32 v96, 0, v96
	v_max_f32_e32 v97, 0, v97
	v_mul_f32_e32 v100, v100, v112
	v_mul_f32_e32 v101, v101, v112
	v_mul_f32_e32 v102, v102, v112
	v_mul_f32_e32 v103, v103, v112
	v_mul_f32_e32 v96, v96, v112
	v_mul_f32_e32 v97, v97, v112
	v_mul_f32_e32 v100, v100, v100
	v_mul_f32_e32 v101, v101, v101
	v_mul_f32_e32 v102, v102, v102
	v_mul_f32_e32 v103, v103, v103
	v_max_f32_e32 v98, 0, v98
	v_max_f32_e32 v99, 0, v99
	v_mul_f32_e32 v96, v96, v96
	v_mul_f32_e32 v97, v97, v97
	v_cvt_pk_bf16_f32 v100, v100, v101
	v_cvt_pk_bf16_f32 v101, v102, v103
	v_cvt_pk_bf16_f32 v102, v96, v97
	v_mul_f32_e32 v96, v98, v112
	v_mul_f32_e32 v97, v99, v112
	ds_read2_b32 v[98:99], v146 offset0:32 offset1:48
	v_max_f32_e32 v92, 0, v92
	v_max_f32_e32 v93, 0, v93
	v_max_f32_e32 v94, 0, v94
	v_max_f32_e32 v95, 0, v95
	v_max_f32_e32 v88, 0, v88
	v_max_f32_e32 v89, 0, v89
	v_mul_f32_e32 v96, v96, v96
	v_mul_f32_e32 v97, v97, v97
	s_waitcnt lgkmcnt(0)
;   DI void operator()(const f32x4 (&acc)[2][2][4][2], const pg8::Unit& u, int wr, int wc, int fr_, int fq_) const {
;     ...
;             } else {
;               if (n == 0) {
;                 const f32x4 v1 = acc[ai][bj][m][1];
;                 u32x4 o4;
;                 { const float t0 = fmaxf(v[0], 0.f) * rinv, t1 = fmaxf(v[1], 0.f) * rinv, t2 = fmaxf(v[2], 0.f) * rinv, t3 = fmaxf(v[3], 0.f) * rinv;
;                   o4.x = pack2(t0 * t0, t1 * t1); o4.y = pack2(t2 * t2, t3 * t3); }
;                 { const float t0 = fmaxf(v1[0], 0.f) * rinv, t1 = fmaxf(v1[1], 0.f) * rinv, t2 = fmaxf(v1[2], 0.f) * rinv, t3 = fmaxf(v1[3], 0.f) * rinv;
;                   o4.z = pack2(t0 * t0, t1 * t1); o4.w = pack2(t2 * t2, t3 * t3); }
;                 *(u32x4*)((u16*)big + (size_t)token * 4096 + u.pn * 256 + bj * 128 + wc * 32 + 8 * fq) = o4;
	v_mul_f32_e32 v92, v92, v98
	v_mul_f32_e32 v93, v93, v98
	v_mul_f32_e32 v94, v94, v98
	v_mul_f32_e32 v95, v95, v98
	v_mul_f32_e32 v88, v88, v98
	v_mul_f32_e32 v89, v89, v98
	v_cvt_pk_bf16_f32 v103, v96, v97
	v_add_u32_e32 v96, 32, v140
	v_mul_f32_e32 v92, v92, v92
	v_mul_f32_e32 v93, v93, v93
	v_mul_f32_e32 v94, v94, v94
	v_mul_f32_e32 v95, v95, v95
	v_max_f32_e32 v90, 0, v90
	v_max_f32_e32 v91, 0, v91
	v_mul_f32_e32 v88, v88, v88
	v_mul_f32_e32 v89, v89, v89
	v_max_f32_e32 v84, 0, v84
	v_max_f32_e32 v85, 0, v85
	v_max_f32_e32 v86, 0, v86
	v_max_f32_e32 v87, 0, v87
	v_max_f32_e32 v76, 0, v76
	v_max_f32_e32 v77, 0, v77
	v_ashrrev_i32_e32 v97, 31, v96
	v_cvt_pk_bf16_f32 v92, v92, v93
	v_cvt_pk_bf16_f32 v93, v94, v95
	v_cvt_pk_bf16_f32 v94, v88, v89
	v_mul_f32_e32 v88, v90, v98
	v_mul_f32_e32 v89, v91, v98
	v_mul_f32_e32 v84, v84, v98
	v_mul_f32_e32 v85, v85, v98
	v_mul_f32_e32 v86, v86, v98
	v_mul_f32_e32 v87, v87, v98
	v_mul_f32_e32 v76, v76, v98
	v_mul_f32_e32 v77, v77, v98
	v_lshlrev_b64 v[96:97], 13, v[96:97]
	v_mul_f32_e32 v88, v88, v88
	v_mul_f32_e32 v89, v89, v89
	v_mul_f32_e32 v84, v84, v84
	v_mul_f32_e32 v85, v85, v85
	v_mul_f32_e32 v86, v86, v86
	v_mul_f32_e32 v87, v87, v87
	v_max_f32_e32 v78, 0, v78
	v_max_f32_e32 v79, 0, v79
	v_mul_f32_e32 v76, v76, v76
	v_mul_f32_e32 v77, v77, v77
	v_cvt_pk_bf16_f32 v95, v88, v89
	v_lshl_add_u64 v[88:89], s[2:3], 0, v[96:97]
	v_cvt_pk_bf16_f32 v84, v84, v85
	v_cvt_pk_bf16_f32 v85, v86, v87
	v_cvt_pk_bf16_f32 v86, v76, v77
	v_mul_f32_e32 v76, v78, v98
	v_mul_f32_e32 v77, v79, v98
	v_lshl_add_u64 v[88:89], v[88:89], 0, s[14:15]
	v_mul_f32_e32 v76, v76, v76
	v_mul_f32_e32 v77, v77, v77
	v_lshl_add_u64 v[88:89], v[88:89], 0, s[24:25]
	v_cvt_pk_bf16_f32 v87, v76, v77
	v_add_u32_e32 v76, 48, v140
	v_lshl_add_u64 v[88:89], v[88:89], 0, v[144:145]
	v_ashrrev_i32_e32 v77, 31, v76
	global_store_dwordx4 v[88:89], v[84:87], off offset:256
	v_max_f32_e32 v68, 0, v68
	v_max_f32_e32 v69, 0, v69
	v_lshlrev_b64 v[84:85], 13, v[76:77]
	v_max_f32_e32 v76, v80, v80
	v_mov_b32_e32 v80, v99
	v_max_f32_e32 v70, 0, v70
	v_max_f32_e32 v71, 0, v71
	v_max_f32_e32 v64, 0, v64
	v_max_f32_e32 v65, 0, v65
	v_mul_f32_e32 v68, v68, v80
	v_mul_f32_e32 v69, v69, v80
	v_mul_f32_e32 v70, v70, v80
	v_mul_f32_e32 v71, v71, v80
	v_mul_f32_e32 v64, v64, v80
	v_mul_f32_e32 v65, v65, v80
	v_mul_f32_e32 v68, v68, v68
	v_mul_f32_e32 v69, v69, v69
	v_mul_f32_e32 v70, v70, v70
	v_mul_f32_e32 v71, v71, v71
	v_max_f32_e32 v66, 0, v66
	v_max_f32_e32 v67, 0, v67
	v_mul_f32_e32 v64, v64, v64
	v_mul_f32_e32 v65, v65, v65
	v_cvt_pk_bf16_f32 v68, v68, v69
	v_cvt_pk_bf16_f32 v69, v70, v71
	v_cvt_pk_bf16_f32 v70, v64, v65
	v_mul_f32_e32 v64, v66, v80
	v_mul_f32_e32 v65, v67, v80
	ds_read2_b32 v[66:67], v146 offset0:128 offset1:144
	v_max_f32_e32 v60, 0, v60
	v_max_f32_e32 v61, 0, v61
	v_max_f32_e32 v62, 0, v62
	v_max_f32_e32 v63, 0, v63
	v_max_f32_e32 v56, 0, v56
	v_max_f32_e32 v57, 0, v57
	v_mul_f32_e32 v64, v64, v64
	v_mul_f32_e32 v65, v65, v65
	s_waitcnt lgkmcnt(0)
	v_mul_f32_e32 v60, v60, v66
	v_mul_f32_e32 v61, v61, v66
	v_mul_f32_e32 v62, v62, v66
	v_mul_f32_e32 v63, v63, v66
	v_mul_f32_e32 v56, v56, v66
	v_mul_f32_e32 v57, v57, v66
	v_cvt_pk_bf16_f32 v71, v64, v65
	v_add_u32_e32 v64, 0x80, v140
	v_mul_f32_e32 v60, v60, v60
	v_mul_f32_e32 v61, v61, v61
	v_mul_f32_e32 v62, v62, v62
	v_mul_f32_e32 v63, v63, v63
	v_max_f32_e32 v58, 0, v58
	v_max_f32_e32 v59, 0, v59
	v_mul_f32_e32 v56, v56, v56
	v_mul_f32_e32 v57, v57, v57
	v_max_f32_e32 v52, 0, v52
	v_max_f32_e32 v53, 0, v53
	v_max_f32_e32 v54, 0, v54
	v_max_f32_e32 v55, 0, v55
	v_max_f32_e32 v44, 0, v44
	v_max_f32_e32 v45, 0, v45
	v_ashrrev_i32_e32 v65, 31, v64
	v_cvt_pk_bf16_f32 v60, v60, v61
	v_cvt_pk_bf16_f32 v61, v62, v63
	v_cvt_pk_bf16_f32 v62, v56, v57
	v_mul_f32_e32 v56, v58, v66
	v_mul_f32_e32 v57, v59, v66
	v_mul_f32_e32 v52, v52, v66
	v_mul_f32_e32 v53, v53, v66
	v_mul_f32_e32 v54, v54, v66
	v_mul_f32_e32 v55, v55, v66
	v_mul_f32_e32 v44, v44, v66
	v_mul_f32_e32 v45, v45, v66
	v_lshlrev_b64 v[64:65], 13, v[64:65]
	v_mul_f32_e32 v56, v56, v56
	v_mul_f32_e32 v57, v57, v57
	v_mul_f32_e32 v52, v52, v52
	v_mul_f32_e32 v53, v53, v53
	v_mul_f32_e32 v54, v54, v54
	v_mul_f32_e32 v55, v55, v55
	v_max_f32_e32 v46, 0, v46
	v_max_f32_e32 v47, 0, v47
	v_mul_f32_e32 v44, v44, v44
	v_mul_f32_e32 v45, v45, v45
	v_cvt_pk_bf16_f32 v63, v56, v57
	v_lshl_add_u64 v[56:57], s[2:3], 0, v[64:65]
	v_cvt_pk_bf16_f32 v52, v52, v53
	v_cvt_pk_bf16_f32 v53, v54, v55
	v_cvt_pk_bf16_f32 v54, v44, v45
	v_mul_f32_e32 v44, v46, v66
	v_mul_f32_e32 v45, v47, v66
	v_lshl_add_u64 v[56:57], v[56:57], 0, s[14:15]
	v_mul_f32_e32 v44, v44, v44
	v_mul_f32_e32 v45, v45, v45
	v_lshl_add_u64 v[56:57], v[56:57], 0, s[24:25]
	v_cvt_pk_bf16_f32 v55, v44, v45
	v_add_u32_e32 v44, 0x90, v140
	v_lshl_add_u64 v[56:57], v[56:57], 0, v[144:145]
	v_ashrrev_i32_e32 v45, 31, v44
	global_store_dwordx4 v[56:57], v[52:55], off offset:256
	v_max_f32_e32 v36, 0, v36
	v_max_f32_e32 v37, 0, v37
	v_lshlrev_b64 v[52:53], 13, v[44:45]
	v_max_f32_e32 v44, v48, v48
	v_mov_b32_e32 v48, v67
	v_max_f32_e32 v38, 0, v38
	v_max_f32_e32 v39, 0, v39
	v_max_f32_e32 v32, 0, v32
	v_max_f32_e32 v33, 0, v33
	v_mul_f32_e32 v36, v36, v48
	v_mul_f32_e32 v37, v37, v48
	v_mul_f32_e32 v38, v38, v48
	v_mul_f32_e32 v39, v39, v48
	v_mul_f32_e32 v32, v32, v48
	v_mul_f32_e32 v33, v33, v48
	v_mul_f32_e32 v36, v36, v36
	v_mul_f32_e32 v37, v37, v37
	v_mul_f32_e32 v38, v38, v38
	v_mul_f32_e32 v39, v39, v39
	v_max_f32_e32 v34, 0, v34
	v_max_f32_e32 v35, 0, v35
	v_mul_f32_e32 v32, v32, v32
	v_mul_f32_e32 v33, v33, v33
	v_cvt_pk_bf16_f32 v36, v36, v37
	v_cvt_pk_bf16_f32 v37, v38, v39
	v_cvt_pk_bf16_f32 v38, v32, v33
	v_mul_f32_e32 v32, v34, v48
	v_mul_f32_e32 v33, v35, v48
	ds_read2_b32 v[34:35], v146 offset0:160 offset1:176
	v_max_f32_e32 v28, 0, v28
	v_max_f32_e32 v29, 0, v29
	v_max_f32_e32 v30, 0, v30
	v_max_f32_e32 v31, 0, v31
	v_max_f32_e32 v24, 0, v24
	v_max_f32_e32 v25, 0, v25
	v_mul_f32_e32 v32, v32, v32
	v_mul_f32_e32 v33, v33, v33
	s_waitcnt lgkmcnt(0)
;   DI void operator()(const f32x4 (&acc)[2][2][4][2], const pg8::Unit& u, int wr, int wc, int fr_, int fq_) const {
;     ...
;             } else {
;               if (n == 0) {
;                 const f32x4 v1 = acc[ai][bj][m][1];
;                 u32x4 o4;
;                 { const float t0 = fmaxf(v[0], 0.f) * rinv, t1 = fmaxf(v[1], 0.f) * rinv, t2 = fmaxf(v[2], 0.f) * rinv, t3 = fmaxf(v[3], 0.f) * rinv;
;                   o4.x = pack2(t0 * t0, t1 * t1); o4.y = pack2(t2 * t2, t3 * t3); }
;                 { const float t0 = fmaxf(v1[0], 0.f) * rinv, t1 = fmaxf(v1[1], 0.f) * rinv, t2 = fmaxf(v1[2], 0.f) * rinv, t3 = fmaxf(v1[3], 0.f) * rinv;
;                   o4.z = pack2(t0 * t0, t1 * t1); o4.w = pack2(t2 * t2, t3 * t3); }
;                 *(u32x4*)((u16*)big + (size_t)token * 4096 + u.pn * 256 + bj * 128 + wc * 32 + 8 * fq) = o4;
	v_mul_f32_e32 v28, v28, v34
	v_mul_f32_e32 v29, v29, v34
	v_mul_f32_e32 v30, v30, v34
	v_mul_f32_e32 v31, v31, v34
	v_mul_f32_e32 v24, v24, v34
	v_mul_f32_e32 v25, v25, v34
	v_cvt_pk_bf16_f32 v39, v32, v33
	v_add_u32_e32 v32, 0xa0, v140
	v_mul_f32_e32 v28, v28, v28
	v_mul_f32_e32 v29, v29, v29
	v_mul_f32_e32 v30, v30, v30
	v_mul_f32_e32 v31, v31, v31
	v_max_f32_e32 v26, 0, v26
	v_max_f32_e32 v27, 0, v27
	v_mul_f32_e32 v24, v24, v24
	v_mul_f32_e32 v25, v25, v25
	v_max_f32_e32 v20, 0, v20
	v_max_f32_e32 v21, 0, v21
	v_max_f32_e32 v22, 0, v22
	v_max_f32_e32 v23, 0, v23
	v_max_f32_e32 v12, 0, v12
	v_max_f32_e32 v13, 0, v13
	v_ashrrev_i32_e32 v33, 31, v32
	v_cvt_pk_bf16_f32 v28, v28, v29
	v_cvt_pk_bf16_f32 v29, v30, v31
	v_cvt_pk_bf16_f32 v30, v24, v25
	v_mul_f32_e32 v24, v26, v34
	v_mul_f32_e32 v25, v27, v34
	v_mul_f32_e32 v20, v20, v34
	v_mul_f32_e32 v21, v21, v34
	v_mul_f32_e32 v22, v22, v34
	v_mul_f32_e32 v23, v23, v34
	v_mul_f32_e32 v12, v12, v34
	v_mul_f32_e32 v13, v13, v34
	v_lshlrev_b64 v[32:33], 13, v[32:33]
	v_mul_f32_e32 v24, v24, v24
	v_mul_f32_e32 v25, v25, v25
	v_mul_f32_e32 v20, v20, v20
	v_mul_f32_e32 v21, v21, v21
	v_mul_f32_e32 v22, v22, v22
	v_mul_f32_e32 v23, v23, v23
	v_max_f32_e32 v14, 0, v14
	v_max_f32_e32 v15, 0, v15
	v_mul_f32_e32 v12, v12, v12
	v_mul_f32_e32 v13, v13, v13
	v_cvt_pk_bf16_f32 v31, v24, v25
	v_lshl_add_u64 v[24:25], s[2:3], 0, v[32:33]
	v_cvt_pk_bf16_f32 v20, v20, v21
	v_cvt_pk_bf16_f32 v21, v22, v23
	v_cvt_pk_bf16_f32 v22, v12, v13
	v_mul_f32_e32 v12, v14, v34
	v_mul_f32_e32 v13, v15, v34
	v_lshl_add_u64 v[24:25], v[24:25], 0, s[14:15]
	v_mul_f32_e32 v12, v12, v12
	v_mul_f32_e32 v13, v13, v13
	v_lshl_add_u64 v[24:25], v[24:25], 0, s[24:25]
	v_cvt_pk_bf16_f32 v23, v12, v13
	v_add_u32_e32 v12, 0xb0, v140
	v_lshl_add_u64 v[24:25], v[24:25], 0, v[144:145]
	v_ashrrev_i32_e32 v13, 31, v12
	v_max_f32_e32 v109, v113, v113
	v_max_f32_e32 v110, v114, v114
	v_max_f32_e32 v111, v115, v115
	v_max_f32_e32 v77, v81, v81
	v_max_f32_e32 v78, v82, v82
	v_max_f32_e32 v79, v83, v83
	v_max_f32_e32 v45, v49, v49
	v_max_f32_e32 v46, v50, v50
	v_max_f32_e32 v47, v51, v51
	global_store_dwordx4 v[24:25], v[20:23], off offset:256
	v_max_f32_e32 v14, v18, v18
	v_max_f32_e32 v15, v19, v19
	v_lshlrev_b64 v[20:21], 13, v[12:13]
	v_max_f32_e32 v12, v16, v16
	v_max_f32_e32 v13, v17, v17
	v_max_f32_e32 v108, 0, v108
	v_max_f32_e32 v109, 0, v109
	v_max_f32_e32 v110, 0, v110
	v_max_f32_e32 v111, 0, v111
	v_max_f32_e32 v104, 0, v104
	v_max_f32_e32 v105, 0, v105
	v_max_f32_e32 v76, 0, v76
	v_max_f32_e32 v77, 0, v77
	v_max_f32_e32 v78, 0, v78
	v_max_f32_e32 v79, 0, v79
	v_max_f32_e32 v72, 0, v72
	v_max_f32_e32 v73, 0, v73
	v_max_f32_e32 v44, 0, v44
	v_max_f32_e32 v45, 0, v45
	v_max_f32_e32 v46, 0, v46
	v_max_f32_e32 v47, 0, v47
	v_max_f32_e32 v40, 0, v40
	v_max_f32_e32 v41, 0, v41
	v_max_f32_e32 v12, 0, v12
	v_max_f32_e32 v13, 0, v13
	v_max_f32_e32 v14, 0, v14
	v_max_f32_e32 v15, 0, v15
	v_mov_b32_e32 v16, v35
	v_max_f32_e32 v8, 0, v8
	v_max_f32_e32 v9, 0, v9
	v_mul_f32_e32 v108, v108, v112
	v_mul_f32_e32 v109, v109, v112
	v_mul_f32_e32 v110, v110, v112
	v_mul_f32_e32 v111, v111, v112
	v_mul_f32_e32 v104, v104, v112
	v_mul_f32_e32 v105, v105, v112
	v_mul_f32_e32 v76, v76, v80
	v_mul_f32_e32 v77, v77, v80
	v_mul_f32_e32 v78, v78, v80
	v_mul_f32_e32 v79, v79, v80
	v_mul_f32_e32 v72, v72, v80
	v_mul_f32_e32 v73, v73, v80
	v_mul_f32_e32 v44, v44, v48
	v_mul_f32_e32 v45, v45, v48
	v_mul_f32_e32 v46, v46, v48
	v_mul_f32_e32 v47, v47, v48
	v_mul_f32_e32 v40, v40, v48
	v_mul_f32_e32 v41, v41, v48
	v_mul_f32_e32 v12, v12, v16
	v_mul_f32_e32 v13, v13, v16
	v_mul_f32_e32 v14, v14, v16
	v_mul_f32_e32 v15, v15, v16
	v_mul_f32_e32 v8, v8, v16
	v_mul_f32_e32 v9, v9, v16
	v_mul_f32_e32 v108, v108, v108
	v_mul_f32_e32 v109, v109, v109
	v_mul_f32_e32 v110, v110, v110
	v_mul_f32_e32 v111, v111, v111
	v_max_f32_e32 v106, 0, v106
	v_max_f32_e32 v107, 0, v107
	v_mul_f32_e32 v104, v104, v104
	v_mul_f32_e32 v105, v105, v105
	v_mul_f32_e32 v76, v76, v76
	v_mul_f32_e32 v77, v77, v77
; #define PG8_WAIT_V(n) asm volatile("s_waitcnt vmcnt(" #n ")" ::: "memory")
; #define PG8_BAR __builtin_amdgcn_s_barrier()
; template <class Epi, class Sched>
; DI void gemm_phase(LAS unsigned char* lds, const Gemm g, const Sched& S, const Epi& E) {
;     ...
;     E(acc, cur, wr, wc, fr, fq);
;     if (!has_next) break;
; #pragma unroll
;     for (int a = 0; a < 2; ++a)
; #pragma unroll
;       for (int b = 0; b < 2; ++b)
; #pragma unroll
;         for (int m = 0; m < 4; ++m)
; #pragma unroll
;           for (int n = 0; n < 2; ++n) acc[a][b][m][n] = (f32x4){0.f, 0.f, 0.f, 0.f};
;     cur = nxt; cA = nA; cB = nB; ++ui;
;   }
;   PG8_WAIT_V(0);
;   if (wr == 0) PG8_BAR;
;   PG8_BAR;
;   DI void operator()(const f32x4 (&acc)[2][2][4][2], const pg8::Unit& u, int wr, int wc, int fr_, int fq_) const {
;     ...
;             } else {
;               if (n == 0) {
;                 const f32x4 v1 = acc[ai][bj][m][1];
;                 u32x4 o4;
;                 { const float t0 = fmaxf(v[0], 0.f) * rinv, t1 = fmaxf(v[1], 0.f) * rinv, t2 = fmaxf(v[2], 0.f) * rinv, t3 = fmaxf(v[3], 0.f) * rinv;
;                   o4.x = pack2(t0 * t0, t1 * t1); o4.y = pack2(t2 * t2, t3 * t3); }
;                 { const float t0 = fmaxf(v1[0], 0.f) * rinv, t1 = fmaxf(v1[1], 0.f) * rinv, t2 = fmaxf(v1[2], 0.f) * rinv, t3 = fmaxf(v1[3], 0.f) * rinv;
;                   o4.z = pack2(t0 * t0, t1 * t1); o4.w = pack2(t2 * t2, t3 * t3); }
;                 *(u32x4*)((u16*)big + (size_t)token * 4096 + u.pn * 256 + bj * 128 + wc * 32 + 8 * fq) = o4;
	v_mul_f32_e32 v78, v78, v78
	v_mul_f32_e32 v79, v79, v79
	v_max_f32_e32 v74, 0, v74
	v_max_f32_e32 v75, 0, v75
	v_mul_f32_e32 v72, v72, v72
	v_mul_f32_e32 v73, v73, v73
	v_mul_f32_e32 v44, v44, v44
	v_mul_f32_e32 v45, v45, v45
	v_mul_f32_e32 v46, v46, v46
	v_mul_f32_e32 v47, v47, v47
	v_max_f32_e32 v42, 0, v42
	v_max_f32_e32 v43, 0, v43
	v_mul_f32_e32 v40, v40, v40
	v_mul_f32_e32 v41, v41, v41
	v_mul_f32_e32 v12, v12, v12
	v_mul_f32_e32 v13, v13, v13
	v_mul_f32_e32 v14, v14, v14
	v_mul_f32_e32 v15, v15, v15
	v_max_f32_e32 v10, 0, v10
	v_max_f32_e32 v11, 0, v11
	v_mul_f32_e32 v8, v8, v8
	v_mul_f32_e32 v9, v9, v9
	v_cvt_pk_bf16_f32 v108, v108, v109
	v_cvt_pk_bf16_f32 v109, v110, v111
	v_cvt_pk_bf16_f32 v110, v104, v105
	v_mul_f32_e32 v104, v106, v112
	v_mul_f32_e32 v105, v107, v112
	v_cvt_pk_bf16_f32 v76, v76, v77
	v_cvt_pk_bf16_f32 v77, v78, v79
	v_cvt_pk_bf16_f32 v78, v72, v73
	v_mul_f32_e32 v72, v74, v80
	v_mul_f32_e32 v73, v75, v80
	v_cvt_pk_bf16_f32 v44, v44, v45
	v_cvt_pk_bf16_f32 v45, v46, v47
	v_cvt_pk_bf16_f32 v46, v40, v41
	v_mul_f32_e32 v40, v42, v48
	v_mul_f32_e32 v41, v43, v48
	v_cvt_pk_bf16_f32 v12, v12, v13
	v_cvt_pk_bf16_f32 v13, v14, v15
	v_cvt_pk_bf16_f32 v14, v8, v9
	v_mul_f32_e32 v8, v10, v16
	v_mul_f32_e32 v9, v11, v16
	v_max_f32_e32 v4, 0, v4
	v_max_f32_e32 v5, 0, v5
	v_max_f32_e32 v6, 0, v6
	v_max_f32_e32 v7, 0, v7
	v_max_f32_e32 v0, 0, v0
	v_max_f32_e32 v1, 0, v1
	v_mul_f32_e32 v104, v104, v104
	v_mul_f32_e32 v105, v105, v105
	v_mul_f32_e32 v72, v72, v72
	v_mul_f32_e32 v73, v73, v73
	v_mul_f32_e32 v40, v40, v40
	v_mul_f32_e32 v41, v41, v41
	v_mul_f32_e32 v8, v8, v8
	v_mul_f32_e32 v9, v9, v9
	v_mul_f32_e32 v4, v4, v16
	v_mul_f32_e32 v5, v5, v16
	v_mul_f32_e32 v6, v6, v16
	v_mul_f32_e32 v7, v7, v16
	v_mul_f32_e32 v0, v0, v16
	v_mul_f32_e32 v1, v1, v16
	v_cvt_pk_bf16_f32 v111, v104, v105
	v_lshl_add_u64 v[104:105], s[2:3], 0, v[116:117]
	v_cvt_pk_bf16_f32 v79, v72, v73
	v_lshl_add_u64 v[72:73], s[2:3], 0, v[84:85]
	v_cvt_pk_bf16_f32 v47, v40, v41
	v_lshl_add_u64 v[40:41], s[2:3], 0, v[52:53]
	v_cvt_pk_bf16_f32 v15, v8, v9
	v_lshl_add_u64 v[8:9], s[2:3], 0, v[20:21]
	v_mul_f32_e32 v4, v4, v4
	v_mul_f32_e32 v5, v5, v5
	v_mul_f32_e32 v6, v6, v6
	v_mul_f32_e32 v7, v7, v7
	v_max_f32_e32 v2, 0, v2
	v_max_f32_e32 v3, 0, v3
	v_mul_f32_e32 v0, v0, v0
	v_mul_f32_e32 v1, v1, v1
	v_lshl_add_u64 v[104:105], v[104:105], 0, s[14:15]
	v_lshl_add_u64 v[72:73], v[72:73], 0, s[14:15]
	v_lshl_add_u64 v[40:41], v[40:41], 0, s[14:15]
	v_lshl_add_u64 v[8:9], v[8:9], 0, s[14:15]
	v_cvt_pk_bf16_f32 v4, v4, v5
	v_cvt_pk_bf16_f32 v5, v6, v7
	v_cvt_pk_bf16_f32 v6, v0, v1
	v_mul_f32_e32 v0, v2, v16
	v_mul_f32_e32 v1, v3, v16
	v_lshl_add_u64 v[104:105], v[104:105], 0, s[24:25]
	v_lshl_add_u64 v[72:73], v[72:73], 0, s[24:25]
	v_lshl_add_u64 v[40:41], v[40:41], 0, s[24:25]
	v_lshl_add_u64 v[8:9], v[8:9], 0, s[24:25]
	v_mul_f32_e32 v0, v0, v0
	v_mul_f32_e32 v1, v1, v1
	v_lshl_add_u64 v[104:105], v[104:105], 0, v[144:145]
	v_lshl_add_u64 v[72:73], v[72:73], 0, v[144:145]
	v_lshl_add_u64 v[40:41], v[40:41], 0, v[144:145]
	v_lshl_add_u64 v[8:9], v[8:9], 0, v[144:145]
	v_cvt_pk_bf16_f32 v7, v0, v1
	s_and_b64 vcc, exec, s[36:37]
	s_mov_b32 s43, s42
	s_mov_b32 s45, s4
	s_mov_b32 s44, s6
	s_mov_b64 s[16:17], s[12:13]
	s_mov_b64 s[14:15], s[10:11]
	v_readlane_b32 s51, v237, 11
	global_store_dwordx4 v[120:121], v[124:127], off
	global_store_dwordx4 v[104:105], v[108:111], off
	global_store_dwordx4 v[104:105], v[100:103], off offset:256
	global_store_dwordx4 v[88:89], v[92:95], off
	global_store_dwordx4 v[72:73], v[76:79], off
	global_store_dwordx4 v[72:73], v[68:71], off offset:256
	global_store_dwordx4 v[56:57], v[60:63], off
	global_store_dwordx4 v[40:41], v[44:47], off
	global_store_dwordx4 v[40:41], v[36:39], off offset:256
	global_store_dwordx4 v[24:25], v[28:31], off
	global_store_dwordx4 v[8:9], v[12:15], off
	global_store_dwordx4 v[8:9], v[4:7], off offset:256
	s_cbranch_vccz .LBB0_1822
	s_waitcnt vmcnt(0)
	s_cmpk_gt_u32 s9, 0xff
	s_cbranch_scc1 .LBB0_1833
	s_barrier

; #define PG8_STAGE(bufoff, gbase, voff) do { _Pragma("unroll") for (int _i = 0; _i < 2; ++_i) \
;     __builtin_amdgcn_global_load_lds((const unsigned*)((const char*)(gbase) + (voff)[_i]), (LAS unsigned*)(lds + (bufoff) + ldsw + _i * 8192), 16, 0, 0); } while (0)
; #define PG8_LDA(dst, b, h) do { _Pragma("unroll") for (int m = 0; m < 4; ++m) _Pragma("unroll") for (int k = 0; k < 2; ++k) dst[m][k] = *(const LAS bf16x8*)(lds + PG8_SA(b, h) + aoff + m * 2048 + k * 1024); } while (0)
; #define PG8_LDB(dst, b, h) do { _Pragma("unroll") for (int n = 0; n < 2; ++n) _Pragma("unroll") for (int k = 0; k < 2; ++k) dst[n][k] = *(const LAS bf16x8*)(lds + PG8_SB(b, h) + boff + n * 2048 + k * 1024); } while (0)
; #define PG8_MMA(ai, bj, At, Bt) do { __builtin_amdgcn_s_setprio(1); _Pragma("unroll") for (int m = 0; m < 4; ++m) _Pragma("unroll") for (int n = 0; n < 2; ++n) _Pragma("unroll") for (int k = 0; k < 2; ++k) \
;     acc[ai][bj][m][n] = __builtin_amdgcn_mfma_f32_16x16x32_bf16(Bt[n][k], At[m][k], acc[ai][bj][m][n], 0, 0, 0); __builtin_amdgcn_s_setprio(0); } while (0)
; #define PG8_WAIT_V(n) asm volatile("s_waitcnt vmcnt(" #n ")" ::: "memory")
; #define PG8_WAIT_L(n) asm volatile("s_waitcnt lgkmcnt(" #n ")" ::: "memory")
; #define PG8_BAR __builtin_amdgcn_s_barrier()
; #define PG8_SCHED __builtin_amdgcn_sched_barrier(0)
; template <class Epi, class Sched>
; DI void gemm_phase(LAS unsigned char* lds, const Gemm g, const Sched& S, const Epi& E) {
;     ...
;     for (int t = 0; t < nt; t += 2) {
;       const bool last = (t == nt - 2);
;       const char* a1 = cA + (size_t)(t + 1) * kstep;
;       const char* a2 = last ? nA : cA + (size_t)(t + 2) * kstep; const char* b2 = last ? nB : cB + (size_t)(t + 2) * kstep;
;       const char* a3 = a2 + kstep; const char* b3 = b2 + kstep;
;       PG8_LDB(B0, 0, 0); PG8_SCHED; PG8_LDA(At, 0, 0); PG8_STAGE(PG8_SA(1, 1), a1 + hstep, voffA);
;       PG8_WAIT_L(8); PG8_BAR; PG8_WAIT_L(0); PG8_MMA(0, 0, At, B0); PG8_BAR; PG8_SCHED;
;       PG8_LDB(B1, 0, 1); PG8_STAGE(PG8_SB(0, 0), b2, voffB);
;       PG8_BAR; PG8_WAIT_L(0); PG8_MMA(0, 1, At, B1); PG8_BAR;
;       PG8_LDA(At, 0, 1); PG8_STAGE(PG8_SA(0, 0), a2, voffA);
;       PG8_BAR; PG8_WAIT_L(0); PG8_MMA(1, 0, At, B0); PG8_BAR; PG8_SCHED;
;       PG8_STAGE(PG8_SB(0, 1), b2 + hstep, voffB);
;       PG8_WAIT_V(6); PG8_BAR; PG8_MMA(1, 1, At, B1); PG8_BAR;
.LBB0_1905:
	s_add_u32 s22, s20, 0xfff00080
	s_addc_u32 s23, s21, -1
	s_add_i32 s51, 0, 0x10000
	ds_read_b128 v[138:141], v224
	ds_read_b128 v[148:151], v224 offset:1024
	ds_read_b128 v[152:155], v224 offset:2048
	ds_read_b128 v[156:159], v224 offset:3072
	s_cmp_eq_u32 s50, 60
	s_cselect_b32 s29, s11, s23
	s_cselect_b32 s28, s17, s22
	s_cselect_b32 s23, s7, s49
	s_cselect_b32 s22, s19, s24
	s_add_i32 m0, s39, 0xc000
	ds_read_b128 v[160:163], v147
	ds_read_b128 v[164:167], v147 offset:1024
	ds_read_b128 v[168:171], v147 offset:2048
	ds_read_b128 v[172:175], v147 offset:3072
	ds_read_b128 v[176:179], v147 offset:4096
	ds_read_b128 v[196:199], v147 offset:5120
	ds_read_b128 v[200:203], v147 offset:6144
	ds_read_b128 v[204:207], v147 offset:7168
	global_load_lds_dwordx4 v134, s[20:21]
	s_add_i32 m0, s39, 0xe000
	s_nop 0
	global_load_lds_dwordx4 v136, s[20:21]
	s_waitcnt lgkmcnt(8)
	s_barrier
	s_waitcnt lgkmcnt(0)
	v_mfma_f32_16x16x32_bf16 v[124:127], v[138:141], v[160:163], v[124:127]
	v_mfma_f32_16x16x32_bf16 v[120:123], v[152:155], v[160:163], v[120:123]
	v_mfma_f32_16x16x32_bf16 v[108:111], v[138:141], v[168:171], v[108:111]
	v_mfma_f32_16x16x32_bf16 v[104:107], v[152:155], v[168:171], v[104:107]
	v_mfma_f32_16x16x32_bf16 v[92:95], v[138:141], v[176:179], v[92:95]
	v_mfma_f32_16x16x32_bf16 v[88:91], v[152:155], v[176:179], v[88:91]
	v_mfma_f32_16x16x32_bf16 v[76:79], v[138:141], v[200:203], v[76:79]
	v_mfma_f32_16x16x32_bf16 v[72:75], v[152:155], v[200:203], v[72:75]
	v_mfma_f32_16x16x32_bf16 v[124:127], v[148:151], v[164:167], v[124:127]
	v_mfma_f32_16x16x32_bf16 v[120:123], v[156:159], v[164:167], v[120:123]
	v_mfma_f32_16x16x32_bf16 v[108:111], v[148:151], v[172:175], v[108:111]
	v_mfma_f32_16x16x32_bf16 v[104:107], v[156:159], v[172:175], v[104:107]
	v_mfma_f32_16x16x32_bf16 v[92:95], v[148:151], v[196:199], v[92:95]
	v_mfma_f32_16x16x32_bf16 v[88:91], v[156:159], v[196:199], v[88:91]
	v_mfma_f32_16x16x32_bf16 v[76:79], v[148:151], v[204:207], v[76:79]
	v_mfma_f32_16x16x32_bf16 v[72:75], v[156:159], v[204:207], v[72:75]
	s_barrier
	s_add_i32 s54, 0, 0x14000
	s_add_i32 s51, s51, s38
	ds_read_b128 v[208:211], v225
	ds_read_b128 v[212:215], v225 offset:1024
	ds_read_b128 v[216:219], v225 offset:2048
	ds_read_b128 v[220:223], v225 offset:3072
	s_add_u32 vcc_lo, s22, s0
	s_addc_u32 vcc_hi, s23, s1
	s_mov_b32 m0, s51
	s_nop 0
	global_load_lds_dwordx4 v144, s[22:23]
	s_add_i32 m0, s51, 0x2000
	s_nop 0
	global_load_lds_dwordx4 v132, s[22:23]
	s_barrier
	s_waitcnt lgkmcnt(0)
	v_mfma_f32_16x16x32_bf16 v[116:119], v[208:211], v[160:163], v[116:119]
	v_mfma_f32_16x16x32_bf16 v[112:115], v[216:219], v[160:163], v[112:115]
	v_mfma_f32_16x16x32_bf16 v[100:103], v[208:211], v[168:171], v[100:103]
	v_mfma_f32_16x16x32_bf16 v[96:99], v[216:219], v[168:171], v[96:99]
	v_mfma_f32_16x16x32_bf16 v[84:87], v[208:211], v[176:179], v[84:87]
	v_mfma_f32_16x16x32_bf16 v[80:83], v[216:219], v[176:179], v[80:83]
	v_mfma_f32_16x16x32_bf16 v[68:71], v[208:211], v[200:203], v[68:71]
	v_mfma_f32_16x16x32_bf16 v[64:67], v[216:219], v[200:203], v[64:67]
	v_mfma_f32_16x16x32_bf16 v[116:119], v[212:215], v[164:167], v[116:119]
	v_mfma_f32_16x16x32_bf16 v[112:115], v[220:223], v[164:167], v[112:115]
	v_mfma_f32_16x16x32_bf16 v[100:103], v[212:215], v[172:175], v[100:103]
	v_mfma_f32_16x16x32_bf16 v[96:99], v[220:223], v[172:175], v[96:99]
	v_mfma_f32_16x16x32_bf16 v[84:87], v[212:215], v[196:199], v[84:87]
	v_mfma_f32_16x16x32_bf16 v[80:83], v[220:223], v[196:199], v[80:83]
	v_mfma_f32_16x16x32_bf16 v[68:71], v[212:215], v[204:207], v[68:71]
	v_mfma_f32_16x16x32_bf16 v[64:67], v[220:223], v[204:207], v[64:67]
	s_mov_b32 m0, s39
	s_add_u32 s100, s28, s0
	s_addc_u32 s101, s29, s1
	s_barrier
	ds_read_b128 v[160:163], v147 offset:16384
	ds_read_b128 v[164:167], v147 offset:17408
	ds_read_b128 v[168:171], v147 offset:18432
	ds_read_b128 v[172:175], v147 offset:19456
	ds_read_b128 v[176:179], v147 offset:20480
	ds_read_b128 v[196:199], v147 offset:21504
	ds_read_b128 v[200:203], v147 offset:22528
	ds_read_b128 v[204:207], v147 offset:23552
	global_load_lds_dwordx4 v128, s[28:29]
	s_mov_b32 m0, s40
	s_nop 0
	global_load_lds_dwordx4 v130, s[28:29]
	s_barrier
	s_waitcnt lgkmcnt(0)
	v_mfma_f32_16x16x32_bf16 v[60:63], v[138:141], v[160:163], v[60:63]
	v_mfma_f32_16x16x32_bf16 v[56:59], v[152:155], v[160:163], v[56:59]
	v_mfma_f32_16x16x32_bf16 v[44:47], v[138:141], v[168:171], v[44:47]
	v_mfma_f32_16x16x32_bf16 v[40:43], v[152:155], v[168:171], v[40:43]
	v_mfma_f32_16x16x32_bf16 v[28:31], v[138:141], v[176:179], v[28:31]
	v_mfma_f32_16x16x32_bf16 v[24:27], v[152:155], v[176:179], v[24:27]
	v_mfma_f32_16x16x32_bf16 v[12:15], v[138:141], v[200:203], v[12:15]
	v_mfma_f32_16x16x32_bf16 v[8:11], v[152:155], v[200:203], v[8:11]
	v_mfma_f32_16x16x32_bf16 v[60:63], v[148:151], v[164:167], v[60:63]
	v_mfma_f32_16x16x32_bf16 v[56:59], v[156:159], v[164:167], v[56:59]
	v_mfma_f32_16x16x32_bf16 v[44:47], v[148:151], v[172:175], v[44:47]
	v_mfma_f32_16x16x32_bf16 v[40:43], v[156:159], v[172:175], v[40:43]
	v_mfma_f32_16x16x32_bf16 v[28:31], v[148:151], v[196:199], v[28:31]
	v_mfma_f32_16x16x32_bf16 v[24:27], v[156:159], v[196:199], v[24:27]
	v_mfma_f32_16x16x32_bf16 v[12:15], v[148:151], v[204:207], v[12:15]
	v_mfma_f32_16x16x32_bf16 v[8:11], v[156:159], v[204:207], v[8:11]
	s_barrier
	s_add_u32 s52, s22, 0x100000
	s_addc_u32 s53, s23, 0
	s_add_i32 s51, s54, s38
	s_mov_b32 m0, s51
	s_nop 0
	global_load_lds_dwordx4 v144, s[52:53]
	s_add_i32 m0, s51, 0x2000
	s_nop 0
	global_load_lds_dwordx4 v132, s[52:53]
	s_waitcnt vmcnt(6)
	s_barrier
; #define PG8_STAGE(bufoff, gbase, voff) do { _Pragma("unroll") for (int _i = 0; _i < 2; ++_i) \
;     __builtin_amdgcn_global_load_lds((const unsigned*)((const char*)(gbase) + (voff)[_i]), (LAS unsigned*)(lds + (bufoff) + ldsw + _i * 8192), 16, 0, 0); } while (0)
; #define PG8_LDA(dst, b, h) do { _Pragma("unroll") for (int m = 0; m < 4; ++m) _Pragma("unroll") for (int k = 0; k < 2; ++k) dst[m][k] = *(const LAS bf16x8*)(lds + PG8_SA(b, h) + aoff + m * 2048 + k * 1024); } while (0)
; #define PG8_LDB(dst, b, h) do { _Pragma("unroll") for (int n = 0; n < 2; ++n) _Pragma("unroll") for (int k = 0; k < 2; ++k) dst[n][k] = *(const LAS bf16x8*)(lds + PG8_SB(b, h) + boff + n * 2048 + k * 1024); } while (0)
; #define PG8_MMA(ai, bj, At, Bt) do { __builtin_amdgcn_s_setprio(1); _Pragma("unroll") for (int m = 0; m < 4; ++m) _Pragma("unroll") for (int n = 0; n < 2; ++n) _Pragma("unroll") for (int k = 0; k < 2; ++k) \
;     acc[ai][bj][m][n] = __builtin_amdgcn_mfma_f32_16x16x32_bf16(Bt[n][k], At[m][k], acc[ai][bj][m][n], 0, 0, 0); __builtin_amdgcn_s_setprio(0); } while (0)
; #define PG8_WAIT_V(n) asm volatile("s_waitcnt vmcnt(" #n ")" ::: "memory")
; #define PG8_WAIT_L(n) asm volatile("s_waitcnt lgkmcnt(" #n ")" ::: "memory")
; #define PG8_BAR __builtin_amdgcn_s_barrier()
; #define PG8_SCHED __builtin_amdgcn_sched_barrier(0)
; template <class Epi, class Sched>
; DI void gemm_phase(LAS unsigned char* lds, const Gemm g, const Sched& S, const Epi& E) {
;     ...
;       PG8_WAIT_V(6); PG8_BAR; PG8_MMA(1, 1, At, B1); PG8_BAR;
;       PG8_LDB(B0, 1, 0); PG8_SCHED; PG8_LDA(At, 1, 0); PG8_STAGE(PG8_SA(0, 1), a2 + hstep, voffA);
;       PG8_WAIT_L(8); PG8_BAR; PG8_WAIT_L(0); PG8_MMA(0, 0, At, B0); PG8_BAR; PG8_SCHED;
;       PG8_LDB(B1, 1, 1); PG8_STAGE(PG8_SB(1, 0), b3, voffB);
;       PG8_BAR; PG8_WAIT_L(0); PG8_MMA(0, 1, At, B1); PG8_BAR;
;       PG8_LDA(At, 1, 1); PG8_STAGE(PG8_SA(1, 0), a3, voffA);
;       PG8_BAR; PG8_WAIT_L(0); PG8_MMA(1, 0, At, B0); PG8_BAR; PG8_SCHED;
	v_mfma_f32_16x16x32_bf16 v[52:55], v[208:211], v[160:163], v[52:55]
	v_mfma_f32_16x16x32_bf16 v[48:51], v[216:219], v[160:163], v[48:51]
	v_mfma_f32_16x16x32_bf16 v[36:39], v[208:211], v[168:171], v[36:39]
	v_mfma_f32_16x16x32_bf16 v[32:35], v[216:219], v[168:171], v[32:35]
	v_mfma_f32_16x16x32_bf16 v[20:23], v[208:211], v[176:179], v[20:23]
	v_mfma_f32_16x16x32_bf16 v[16:19], v[216:219], v[176:179], v[16:19]
	v_mfma_f32_16x16x32_bf16 v[4:7], v[208:211], v[200:203], v[4:7]
	v_mfma_f32_16x16x32_bf16 v[0:3], v[216:219], v[200:203], v[0:3]
	v_mfma_f32_16x16x32_bf16 v[52:55], v[212:215], v[164:167], v[52:55]
	v_mfma_f32_16x16x32_bf16 v[48:51], v[220:223], v[164:167], v[48:51]
	v_mfma_f32_16x16x32_bf16 v[36:39], v[212:215], v[172:175], v[36:39]
	v_mfma_f32_16x16x32_bf16 v[32:35], v[220:223], v[172:175], v[32:35]
	v_mfma_f32_16x16x32_bf16 v[20:23], v[212:215], v[196:199], v[20:23]
	v_mfma_f32_16x16x32_bf16 v[16:19], v[220:223], v[196:199], v[16:19]
	v_mfma_f32_16x16x32_bf16 v[4:7], v[212:215], v[204:207], v[4:7]
	v_mfma_f32_16x16x32_bf16 v[0:3], v[220:223], v[204:207], v[0:3]
	s_add_i32 s51, 0, 0x18000
	s_barrier
	ds_read_b128 v[138:141], v226
	ds_read_b128 v[148:151], v226 offset:1024
	ds_read_b128 v[152:155], v226 offset:2048
	ds_read_b128 v[156:159], v226 offset:3072
	s_add_u32 s28, s28, 0x100000
	s_addc_u32 s29, s29, 0
	s_mov_b32 m0, s41
	ds_read_b128 v[160:163], v147 offset:32768
	ds_read_b128 v[164:167], v147 offset:33792
	ds_read_b128 v[168:171], v147 offset:34816
	ds_read_b128 v[172:175], v147 offset:35840
	ds_read_b128 v[176:179], v147 offset:36864
	ds_read_b128 v[196:199], v147 offset:37888
	ds_read_b128 v[200:203], v147 offset:38912
	ds_read_b128 v[204:207], v147 offset:39936
	global_load_lds_dwordx4 v128, s[28:29]
	s_mov_b32 m0, s42
	s_nop 0
	global_load_lds_dwordx4 v130, s[28:29]
	s_waitcnt lgkmcnt(8)
	s_barrier
	s_waitcnt lgkmcnt(0)
	v_mfma_f32_16x16x32_bf16 v[124:127], v[138:141], v[160:163], v[124:127]
	v_mfma_f32_16x16x32_bf16 v[120:123], v[152:155], v[160:163], v[120:123]
	v_mfma_f32_16x16x32_bf16 v[108:111], v[138:141], v[168:171], v[108:111]
	v_mfma_f32_16x16x32_bf16 v[104:107], v[152:155], v[168:171], v[104:107]
	v_mfma_f32_16x16x32_bf16 v[92:95], v[138:141], v[176:179], v[92:95]
	v_mfma_f32_16x16x32_bf16 v[88:91], v[152:155], v[176:179], v[88:91]
	v_mfma_f32_16x16x32_bf16 v[76:79], v[138:141], v[200:203], v[76:79]
	v_mfma_f32_16x16x32_bf16 v[72:75], v[152:155], v[200:203], v[72:75]
	v_mfma_f32_16x16x32_bf16 v[124:127], v[148:151], v[164:167], v[124:127]
	v_mfma_f32_16x16x32_bf16 v[120:123], v[156:159], v[164:167], v[120:123]
	v_mfma_f32_16x16x32_bf16 v[108:111], v[148:151], v[172:175], v[108:111]
	v_mfma_f32_16x16x32_bf16 v[104:107], v[156:159], v[172:175], v[104:107]
	v_mfma_f32_16x16x32_bf16 v[92:95], v[148:151], v[196:199], v[92:95]
	v_mfma_f32_16x16x32_bf16 v[88:91], v[156:159], v[196:199], v[88:91]
	v_mfma_f32_16x16x32_bf16 v[76:79], v[148:151], v[204:207], v[76:79]
	v_mfma_f32_16x16x32_bf16 v[72:75], v[156:159], v[204:207], v[72:75]
	s_barrier
	s_add_i32 s28, 0, 0x1c000
	s_add_i32 s29, s51, s38
	s_mov_b32 m0, s29
	ds_read_b128 v[208:211], v227
	ds_read_b128 v[212:215], v227 offset:1024
	ds_read_b128 v[216:219], v227 offset:2048
	ds_read_b128 v[220:223], v227 offset:3072
	global_load_lds_dwordx4 v144, vcc
	s_add_i32 m0, s29, 0x2000
	s_nop 0
	global_load_lds_dwordx4 v132, vcc
	s_barrier
	s_waitcnt lgkmcnt(0)
	v_mfma_f32_16x16x32_bf16 v[116:119], v[208:211], v[160:163], v[116:119]
	v_mfma_f32_16x16x32_bf16 v[112:115], v[216:219], v[160:163], v[112:115]
	v_mfma_f32_16x16x32_bf16 v[100:103], v[208:211], v[168:171], v[100:103]
	v_mfma_f32_16x16x32_bf16 v[96:99], v[216:219], v[168:171], v[96:99]
	v_mfma_f32_16x16x32_bf16 v[84:87], v[208:211], v[176:179], v[84:87]
	v_mfma_f32_16x16x32_bf16 v[80:83], v[216:219], v[176:179], v[80:83]
	v_mfma_f32_16x16x32_bf16 v[68:71], v[208:211], v[200:203], v[68:71]
	v_mfma_f32_16x16x32_bf16 v[64:67], v[216:219], v[200:203], v[64:67]
	v_mfma_f32_16x16x32_bf16 v[116:119], v[212:215], v[164:167], v[116:119]
	v_mfma_f32_16x16x32_bf16 v[112:115], v[220:223], v[164:167], v[112:115]
	v_mfma_f32_16x16x32_bf16 v[100:103], v[212:215], v[172:175], v[100:103]
	v_mfma_f32_16x16x32_bf16 v[96:99], v[220:223], v[172:175], v[96:99]
	v_mfma_f32_16x16x32_bf16 v[84:87], v[212:215], v[196:199], v[84:87]
	v_mfma_f32_16x16x32_bf16 v[80:83], v[220:223], v[196:199], v[80:83]
	v_mfma_f32_16x16x32_bf16 v[68:71], v[212:215], v[204:207], v[68:71]
	v_mfma_f32_16x16x32_bf16 v[64:67], v[220:223], v[204:207], v[64:67]
	s_mov_b32 m0, s46
	s_barrier
	ds_read_b128 v[160:163], v147 offset:49152
	ds_read_b128 v[164:167], v147 offset:50176
	ds_read_b128 v[168:171], v147 offset:51200
	ds_read_b128 v[172:175], v147 offset:52224
	ds_read_b128 v[176:179], v147 offset:53248
	ds_read_b128 v[196:199], v147 offset:54272
	ds_read_b128 v[200:203], v147 offset:55296
	ds_read_b128 v[204:207], v147 offset:56320
	global_load_lds_dwordx4 v128, s[100:101]
	s_mov_b32 m0, s47
	s_nop 0
	global_load_lds_dwordx4 v130, s[100:101]
	s_barrier
	s_waitcnt lgkmcnt(0)
	v_mfma_f32_16x16x32_bf16 v[60:63], v[138:141], v[160:163], v[60:63]
	v_mfma_f32_16x16x32_bf16 v[56:59], v[152:155], v[160:163], v[56:59]
	v_mfma_f32_16x16x32_bf16 v[44:47], v[138:141], v[168:171], v[44:47]
	v_mfma_f32_16x16x32_bf16 v[40:43], v[152:155], v[168:171], v[40:43]
	v_mfma_f32_16x16x32_bf16 v[28:31], v[138:141], v[176:179], v[28:31]
	v_mfma_f32_16x16x32_bf16 v[24:27], v[152:155], v[176:179], v[24:27]
	v_mfma_f32_16x16x32_bf16 v[12:15], v[138:141], v[200:203], v[12:15]
	v_mfma_f32_16x16x32_bf16 v[8:11], v[152:155], v[200:203], v[8:11]
	v_mfma_f32_16x16x32_bf16 v[60:63], v[148:151], v[164:167], v[60:63]
	v_mfma_f32_16x16x32_bf16 v[56:59], v[156:159], v[164:167], v[56:59]
	v_mfma_f32_16x16x32_bf16 v[44:47], v[148:151], v[172:175], v[44:47]
	v_mfma_f32_16x16x32_bf16 v[40:43], v[156:159], v[172:175], v[40:43]
	v_mfma_f32_16x16x32_bf16 v[28:31], v[148:151], v[196:199], v[28:31]
	v_mfma_f32_16x16x32_bf16 v[24:27], v[156:159], v[196:199], v[24:27]
	v_mfma_f32_16x16x32_bf16 v[12:15], v[148:151], v[204:207], v[12:15]
	v_mfma_f32_16x16x32_bf16 v[8:11], v[156:159], v[204:207], v[8:11]
	s_barrier
; template <class Epi, class Sched>
; DI void gemm_phase(LAS unsigned char* lds, const Gemm g, const Sched& S, const Epi& E) {
;     ...
;       PG8_WAIT_V(6); PG8_BAR; PG8_MMA(1, 1, At, B1); PG8_BAR;
;     }
;     E(acc, cur, wr, wc, fr, fq);
;   DI void operator()(const f32x4 (&acc)[2][2][4][2], const pg8::Unit& u, int wr, int wc, int fr_, int fq_) const {
;     ...
;             } else if (EPI == EPI_RESID) {
;               if (n == 0) {
;                 const int f8 = u.pn * 256 + bj * 128 + wc * 32 + 8 * fq;
;                 const f32x4 v1 = acc[ai][bj][m][1];
;                 f32x4 r0, r1;
;                 if (rsrc) {
;                   r0 = *(const f32x4*)(rsrc + (size_t)token * 1024 + f8); r1 = *(const f32x4*)(rsrc + (size_t)token * 1024 + f8 + 4);
;                 } else {
;                   const u32x4 xu = *(const u32x4*)(xr + (size_t)token * 1024 + f8);
;                   r0 = (f32x4){bf2f(xu.x & 0xffffu), bf2f(xu.x >> 16), bf2f(xu.y & 0xffffu), bf2f(xu.y >> 16)};
;                   r1 = (f32x4){bf2f(xu.z & 0xffffu), bf2f(xu.z >> 16), bf2f(xu.w & 0xffffu), bf2f(xu.w >> 16)};
;                 }
;                 r0 += v; r1 += v1;
;                 st_bf8(xr + (size_t)token * 1024 + f8, r0, r1, 1.f);
;                 ssq += r0[0] * r0[0] + r0[1] * r0[1] + r0[2] * r0[2] + r0[3] * r0[3] + r1[0] * r1[0] + r1[1] * r1[1] + r1[2] * r1[2] + r1[3] * r1[3];
;               }
;             } else {
;               if (n == 0) {
;                 const f32x4 v1 = acc[ai][bj][m][1];
;                 u32x4 o4;
;                 { const float t0 = fmaxf(v[0], 0.f) * rinv, t1 = fmaxf(v[1], 0.f) * rinv, t2 = fmaxf(v[2], 0.f) * rinv, t3 = fmaxf(v[3], 0.f) * rinv;
;                   o4.x = pack2(t0 * t0, t1 * t1); o4.y = pack2(t2 * t2, t3 * t3); }
;                 { const float t0 = fmaxf(v1[0], 0.f) * rinv, t1 = fmaxf(v1[1], 0.f) * rinv, t2 = fmaxf(v1[2], 0.f) * rinv, t3 = fmaxf(v1[3], 0.f) * rinv;
;                   o4.z = pack2(t0 * t0, t1 * t1); o4.w = pack2(t2 * t2, t3 * t3); }
;                 *(u32x4*)((u16*)big + (size_t)token * 4096 + u.pn * 256 + bj * 128 + wc * 32 + 8 * fq) = o4;
;               }
;             }
;           }
;         if (EPI == EPI_RESID) {
;           ssq += shx(ssq, 16, t_ & 63);
;           ssq += shx(ssq, 32, t_ & 63);
;           if (fq == 0) ss_out[(size_t)token * 16 + u.pn * 4 + wc] = ssq;
	s_add_u32 s22, s22, 0x100080
	s_addc_u32 s23, s23, 0
	s_add_i32 s28, s28, s38
	s_mov_b32 m0, s28
	s_nop 0
	global_load_lds_dwordx4 v144, s[22:23]
	s_add_i32 m0, s28, 0x2000
	s_nop 0
	global_load_lds_dwordx4 v132, s[22:23]
	s_waitcnt vmcnt(6)
	s_barrier
	v_mfma_f32_16x16x32_bf16 v[52:55], v[208:211], v[160:163], v[52:55]
	v_mfma_f32_16x16x32_bf16 v[48:51], v[216:219], v[160:163], v[48:51]
	v_mfma_f32_16x16x32_bf16 v[36:39], v[208:211], v[168:171], v[36:39]
	v_mfma_f32_16x16x32_bf16 v[32:35], v[216:219], v[168:171], v[32:35]
	v_mfma_f32_16x16x32_bf16 v[20:23], v[208:211], v[176:179], v[20:23]
	v_mfma_f32_16x16x32_bf16 v[16:19], v[216:219], v[176:179], v[16:19]
	v_mfma_f32_16x16x32_bf16 v[4:7], v[208:211], v[200:203], v[4:7]
	v_mfma_f32_16x16x32_bf16 v[0:3], v[216:219], v[200:203], v[0:3]
	v_mfma_f32_16x16x32_bf16 v[52:55], v[212:215], v[164:167], v[52:55]
	v_mfma_f32_16x16x32_bf16 v[48:51], v[220:223], v[164:167], v[48:51]
	v_mfma_f32_16x16x32_bf16 v[36:39], v[212:215], v[172:175], v[36:39]
	v_mfma_f32_16x16x32_bf16 v[32:35], v[220:223], v[172:175], v[32:35]
	v_mfma_f32_16x16x32_bf16 v[20:23], v[212:215], v[196:199], v[20:23]
	v_mfma_f32_16x16x32_bf16 v[16:19], v[220:223], v[196:199], v[16:19]
	v_mfma_f32_16x16x32_bf16 v[4:7], v[212:215], v[204:207], v[4:7]
	v_mfma_f32_16x16x32_bf16 v[0:3], v[220:223], v[204:207], v[0:3]
	s_add_i32 s50, s50, 2
	s_add_u32 s20, s20, 0x100
	s_addc_u32 s21, s21, 0
	s_add_u32 s24, s24, 0x100
	s_addc_u32 s49, s49, 0
	s_cmp_gt_u32 s50, 61
	s_barrier
	s_cbranch_scc0 .LBB0_1905
	s_lshl_b32 s7, s18, 8
	v_mov_b32_e32 v139, v182
	s_add_i32 s7, s7, s44
	s_nop 0
	v_and_or_b32 v140, v139, 15, s7
	s_lshl_b32 s7, s16, 8
	v_bfe_u32 v141, v139, 4, 2
	s_or_b32 s7, s7, s45
	v_lshl_or_b32 v138, v141, 3, s7
	v_cmp_eq_u32_e32 vcc, 0, v141
	v_ashrrev_i32_e32 v141, 31, v140
	v_lshlrev_b32_e32 v139, 2, v139
	s_movk_i32 s7, 0x80
	v_lshlrev_b64 v[142:143], 11, v[140:141]
	v_bitop3_b32 v149, v139, 64, v190 bitop3:0x6c
	v_bitop3_b32 v148, v139, s7, v190 bitop3:0x6c
	v_ashrrev_i32_e32 v139, 31, v138
	v_lshl_add_u64 v[142:143], s[4:5], 0, v[142:143]
	v_lshl_add_u64 v[142:143], v[138:139], 1, v[142:143]
	global_load_dwordx4 v[150:153], v[142:143], off
	s_lshl_b32 s16, s16, 2
	s_ashr_i32 s17, s16, 31
	s_waitcnt vmcnt(0)
	v_lshlrev_b32_e32 v154, 16, v150
	v_and_b32_e32 v155, 0xffff0000, v150
	v_lshlrev_b32_e32 v150, 16, v151
	v_and_b32_e32 v151, 0xffff0000, v151
	v_lshlrev_b32_e32 v156, 16, v152
	v_and_b32_e32 v157, 0xffff0000, v152
	v_lshlrev_b32_e32 v152, 16, v153
	v_and_b32_e32 v153, 0xffff0000, v153
	v_add_f32_e32 v126, v126, v150
	v_add_f32_e32 v127, v127, v151
	v_add_f32_e32 v124, v124, v154
	v_add_f32_e32 v125, v125, v155
	v_add_f32_e32 v150, v122, v152
	v_add_f32_e32 v151, v123, v153
	v_add_f32_e32 v152, v120, v156
	v_add_f32_e32 v153, v121, v157
	v_cvt_pk_bf16_f32 v120, v124, v125
	v_cvt_pk_bf16_f32 v121, v126, v127
	v_cvt_pk_bf16_f32 v122, v152, v153
	v_cvt_pk_bf16_f32 v123, v150, v151
	global_store_dwordx4 v[142:143], v[120:123], off
	global_load_dwordx4 v[120:123], v[142:143], off offset:256
	v_mul_f32_e32 v154, v125, v125
	v_fmac_f32_e32 v154, v124, v124
	v_fmac_f32_e32 v154, v126, v126
	v_fmac_f32_e32 v154, v127, v127
	v_fmac_f32_e32 v154, v152, v152
	v_fmac_f32_e32 v154, v153, v153
	v_fmac_f32_e32 v154, v150, v150
	v_fmac_f32_e32 v154, v151, v151
	s_waitcnt vmcnt(0)
	v_lshlrev_b32_e32 v124, 16, v120
	v_and_b32_e32 v125, 0xffff0000, v120
	v_lshlrev_b32_e32 v120, 16, v121
	v_and_b32_e32 v121, 0xffff0000, v121
	v_lshlrev_b32_e32 v126, 16, v122
	v_and_b32_e32 v127, 0xffff0000, v122
	v_lshlrev_b32_e32 v122, 16, v123
	v_and_b32_e32 v123, 0xffff0000, v123
	v_add_f32_e32 v118, v118, v120
	v_add_f32_e32 v119, v119, v121
	v_add_f32_e32 v116, v116, v124
	v_add_f32_e32 v117, v117, v125
	v_add_f32_e32 v120, v114, v122
	v_add_f32_e32 v121, v115, v123
	v_add_f32_e32 v122, v112, v126
	v_add_f32_e32 v123, v113, v127
	v_cvt_pk_bf16_f32 v112, v116, v117
	v_cvt_pk_bf16_f32 v113, v118, v119
	v_cvt_pk_bf16_f32 v114, v122, v123
	v_cvt_pk_bf16_f32 v115, v120, v121
	global_store_dwordx4 v[142:143], v[112:115], off offset:256
	s_nop 1
	v_mul_f32_e32 v112, v117, v117
	v_fmac_f32_e32 v112, v116, v116
	v_fmac_f32_e32 v112, v118, v118
	v_fmac_f32_e32 v112, v119, v119
	v_fmac_f32_e32 v112, v122, v122
	v_fmac_f32_e32 v112, v123, v123
	v_fmac_f32_e32 v112, v120, v120
	v_fmac_f32_e32 v112, v121, v121
	v_add_f32_e32 v112, v154, v112
	ds_bpermute_b32 v113, v149, v112
	s_waitcnt lgkmcnt(0)
	v_add_f32_e32 v112, v112, v113
	ds_bpermute_b32 v113, v148, v112
	s_and_saveexec_b64 s[18:19], vcc
	s_cbranch_execz .LBB0_1908
	s_waitcnt lgkmcnt(0)
	v_add_f32_e32 v114, v112, v113
	v_lshlrev_b64 v[112:113], 6, v[140:141]
	v_lshl_add_u64 v[112:113], s[2:3], 0, v[112:113]
	v_lshl_add_u64 v[112:113], s[16:17], 2, v[112:113]
	s_lshl_b32 s24, s43, 2
	v_lshl_add_u64 v[112:113], v[112:113], 0, s[24:25]
	global_store_dword v[112:113], v114, off
; DI float bf2f(unsigned v) { return __uint_as_float(v << 16); }
;   DI void operator()(const f32x4 (&acc)[2][2][4][2], const pg8::Unit& u, int wr, int wc, int fr_, int fq_) const {
;     ...
;             } else if (EPI == EPI_RESID) {
;               if (n == 0) {
;                 const int f8 = u.pn * 256 + bj * 128 + wc * 32 + 8 * fq;
;                 const f32x4 v1 = acc[ai][bj][m][1];
;                 f32x4 r0, r1;
;                 if (rsrc) {
;                   r0 = *(const f32x4*)(rsrc + (size_t)token * 1024 + f8); r1 = *(const f32x4*)(rsrc + (size_t)token * 1024 + f8 + 4);
;                 } else {
;                   const u32x4 xu = *(const u32x4*)(xr + (size_t)token * 1024 + f8);
;                   r0 = (f32x4){bf2f(xu.x & 0xffffu), bf2f(xu.x >> 16), bf2f(xu.y & 0xffffu), bf2f(xu.y >> 16)};
;                   r1 = (f32x4){bf2f(xu.z & 0xffffu), bf2f(xu.z >> 16), bf2f(xu.w & 0xffffu), bf2f(xu.w >> 16)};
;                 }
;                 r0 += v; r1 += v1;
;                 st_bf8(xr + (size_t)token * 1024 + f8, r0, r1, 1.f);
;                 ssq += r0[0] * r0[0] + r0[1] * r0[1] + r0[2] * r0[2] + r0[3] * r0[3] + r1[0] * r1[0] + r1[1] * r1[1] + r1[2] * r1[2] + r1[3] * r1[3];
;               }
;             } else {
;               if (n == 0) {
;                 const f32x4 v1 = acc[ai][bj][m][1];
;                 u32x4 o4;
;                 { const float t0 = fmaxf(v[0], 0.f) * rinv, t1 = fmaxf(v[1], 0.f) * rinv, t2 = fmaxf(v[2], 0.f) * rinv, t3 = fmaxf(v[3], 0.f) * rinv;
;                   o4.x = pack2(t0 * t0, t1 * t1); o4.y = pack2(t2 * t2, t3 * t3); }
;                 { const float t0 = fmaxf(v1[0], 0.f) * rinv, t1 = fmaxf(v1[1], 0.f) * rinv, t2 = fmaxf(v1[2], 0.f) * rinv, t3 = fmaxf(v1[3], 0.f) * rinv;
;                   o4.z = pack2(t0 * t0, t1 * t1); o4.w = pack2(t2 * t2, t3 * t3); }
;                 *(u32x4*)((u16*)big + (size_t)token * 4096 + u.pn * 256 + bj * 128 + wc * 32 + 8 * fq) = o4;
;               }
;             }
;           }
;         if (EPI == EPI_RESID) {
;           ssq += shx(ssq, 16, t_ & 63);
;           ssq += shx(ssq, 32, t_ & 63);
;           if (fq == 0) ss_out[(size_t)token * 16 + u.pn * 4 + wc] = ssq;
.LBB0_1908:
	s_or_b64 exec, exec, s[18:19]
	v_or_b32_e32 v112, 16, v140
	s_waitcnt lgkmcnt(0)
	v_ashrrev_i32_e32 v113, 31, v112
	v_lshlrev_b64 v[114:115], 11, v[112:113]
	v_lshl_add_u64 v[114:115], s[4:5], 0, v[114:115]
	v_lshl_add_u64 v[118:119], v[138:139], 1, v[114:115]
	global_load_dwordx4 v[114:117], v[118:119], off
	s_waitcnt vmcnt(0)
	v_lshlrev_b32_e32 v120, 16, v114
	v_and_b32_e32 v121, 0xffff0000, v114
	v_lshlrev_b32_e32 v114, 16, v115
	v_and_b32_e32 v115, 0xffff0000, v115
	v_lshlrev_b32_e32 v122, 16, v116
	v_and_b32_e32 v123, 0xffff0000, v116
	v_lshlrev_b32_e32 v116, 16, v117
	v_and_b32_e32 v117, 0xffff0000, v117
	v_add_f32_e32 v110, v110, v114
	v_add_f32_e32 v111, v111, v115
	v_add_f32_e32 v108, v108, v120
	v_add_f32_e32 v109, v109, v121
	v_add_f32_e32 v114, v106, v116
	v_add_f32_e32 v115, v107, v117
	v_add_f32_e32 v116, v104, v122
	v_add_f32_e32 v117, v105, v123
	v_cvt_pk_bf16_f32 v104, v108, v109
	v_cvt_pk_bf16_f32 v105, v110, v111
	v_cvt_pk_bf16_f32 v106, v116, v117
	v_cvt_pk_bf16_f32 v107, v114, v115
	global_store_dwordx4 v[118:119], v[104:107], off
	global_load_dwordx4 v[104:107], v[118:119], off offset:256
	v_mul_f32_e32 v120, v109, v109
	v_fmac_f32_e32 v120, v108, v108
	v_fmac_f32_e32 v120, v110, v110
	v_fmac_f32_e32 v120, v111, v111
	v_fmac_f32_e32 v120, v116, v116
	v_fmac_f32_e32 v120, v117, v117
	v_fmac_f32_e32 v120, v114, v114
	v_fmac_f32_e32 v120, v115, v115
	s_waitcnt vmcnt(0)
	v_lshlrev_b32_e32 v108, 16, v104
	v_and_b32_e32 v109, 0xffff0000, v104
	v_lshlrev_b32_e32 v104, 16, v105
	v_and_b32_e32 v105, 0xffff0000, v105
	v_lshlrev_b32_e32 v110, 16, v106
	v_and_b32_e32 v111, 0xffff0000, v106
	v_lshlrev_b32_e32 v106, 16, v107
	v_and_b32_e32 v107, 0xffff0000, v107
	v_add_f32_e32 v102, v102, v104
	v_add_f32_e32 v103, v103, v105
	v_add_f32_e32 v100, v100, v108
	v_add_f32_e32 v101, v101, v109
	v_add_f32_e32 v104, v98, v106
	v_add_f32_e32 v105, v99, v107
	v_add_f32_e32 v106, v96, v110
	v_add_f32_e32 v107, v97, v111
	v_cvt_pk_bf16_f32 v96, v100, v101
	v_cvt_pk_bf16_f32 v97, v102, v103
	v_cvt_pk_bf16_f32 v98, v106, v107
	v_cvt_pk_bf16_f32 v99, v104, v105
	global_store_dwordx4 v[118:119], v[96:99], off offset:256
	s_nop 1
	v_mul_f32_e32 v96, v101, v101
	v_fmac_f32_e32 v96, v100, v100
	v_fmac_f32_e32 v96, v102, v102
	v_fmac_f32_e32 v96, v103, v103
	v_fmac_f32_e32 v96, v106, v106
	v_fmac_f32_e32 v96, v107, v107
	v_fmac_f32_e32 v96, v104, v104
	v_fmac_f32_e32 v96, v105, v105
	v_add_f32_e32 v96, v120, v96
	ds_bpermute_b32 v97, v149, v96
	s_waitcnt lgkmcnt(0)
	v_add_f32_e32 v96, v96, v97
	ds_bpermute_b32 v97, v148, v96
	s_and_saveexec_b64 s[18:19], vcc
	s_cbranch_execz .LBB0_1910
	s_waitcnt lgkmcnt(0)
	v_add_f32_e32 v98, v96, v97
	v_lshlrev_b64 v[96:97], 6, v[112:113]
	v_lshl_add_u64 v[96:97], s[2:3], 0, v[96:97]
	v_lshl_add_u64 v[96:97], s[16:17], 2, v[96:97]
	s_lshl_b32 s24, s43, 2
	v_lshl_add_u64 v[96:97], v[96:97], 0, s[24:25]
	global_store_dword v[96:97], v98, off
.LBB0_1910:
	s_or_b64 exec, exec, s[18:19]
	v_or_b32_e32 v96, 32, v140
	s_waitcnt lgkmcnt(0)
	v_ashrrev_i32_e32 v97, 31, v96
	v_lshlrev_b64 v[98:99], 11, v[96:97]
	v_lshl_add_u64 v[98:99], s[4:5], 0, v[98:99]
	v_lshl_add_u64 v[102:103], v[138:139], 1, v[98:99]
	global_load_dwordx4 v[98:101], v[102:103], off
	s_waitcnt vmcnt(0)
	v_lshlrev_b32_e32 v104, 16, v98
	v_and_b32_e32 v105, 0xffff0000, v98
	v_lshlrev_b32_e32 v98, 16, v99
	v_and_b32_e32 v99, 0xffff0000, v99
	v_lshlrev_b32_e32 v106, 16, v100
	v_and_b32_e32 v107, 0xffff0000, v100
	v_lshlrev_b32_e32 v100, 16, v101
	v_and_b32_e32 v101, 0xffff0000, v101
	v_add_f32_e32 v94, v94, v98
	v_add_f32_e32 v95, v95, v99
	v_add_f32_e32 v92, v92, v104
	v_add_f32_e32 v93, v93, v105
	v_add_f32_e32 v98, v90, v100
	v_add_f32_e32 v99, v91, v101
	v_add_f32_e32 v100, v88, v106
	v_add_f32_e32 v101, v89, v107
	v_cvt_pk_bf16_f32 v88, v92, v93
	v_cvt_pk_bf16_f32 v89, v94, v95
	v_cvt_pk_bf16_f32 v90, v100, v101
	v_cvt_pk_bf16_f32 v91, v98, v99
	global_store_dwordx4 v[102:103], v[88:91], off
	global_load_dwordx4 v[88:91], v[102:103], off offset:256
	v_mul_f32_e32 v104, v93, v93
	v_fmac_f32_e32 v104, v92, v92
	v_fmac_f32_e32 v104, v94, v94
	v_fmac_f32_e32 v104, v95, v95
	v_fmac_f32_e32 v104, v100, v100
	v_fmac_f32_e32 v104, v101, v101
	v_fmac_f32_e32 v104, v98, v98
	v_fmac_f32_e32 v104, v99, v99
	s_waitcnt vmcnt(0)
	v_lshlrev_b32_e32 v92, 16, v88
	v_and_b32_e32 v93, 0xffff0000, v88
	v_lshlrev_b32_e32 v88, 16, v89
	v_and_b32_e32 v89, 0xffff0000, v89
	v_lshlrev_b32_e32 v94, 16, v90
	v_and_b32_e32 v95, 0xffff0000, v90
	v_lshlrev_b32_e32 v90, 16, v91
	v_and_b32_e32 v91, 0xffff0000, v91
	v_add_f32_e32 v86, v86, v88
	v_add_f32_e32 v87, v87, v89
	v_add_f32_e32 v84, v84, v92
	v_add_f32_e32 v85, v85, v93
	v_add_f32_e32 v88, v82, v90
	v_add_f32_e32 v89, v83, v91
	v_add_f32_e32 v90, v80, v94
	v_add_f32_e32 v91, v81, v95
	v_cvt_pk_bf16_f32 v80, v84, v85
	v_cvt_pk_bf16_f32 v81, v86, v87
	v_cvt_pk_bf16_f32 v82, v90, v91
	v_cvt_pk_bf16_f32 v83, v88, v89
	global_store_dwordx4 v[102:103], v[80:83], off offset:256
	s_nop 1
	v_mul_f32_e32 v80, v85, v85
	v_fmac_f32_e32 v80, v84, v84
	v_fmac_f32_e32 v80, v86, v86
	v_fmac_f32_e32 v80, v87, v87
	v_fmac_f32_e32 v80, v90, v90
	v_fmac_f32_e32 v80, v91, v91
	v_fmac_f32_e32 v80, v88, v88
	v_fmac_f32_e32 v80, v89, v89
	v_add_f32_e32 v80, v104, v80
	ds_bpermute_b32 v81, v149, v80
	s_waitcnt lgkmcnt(0)
	v_add_f32_e32 v80, v80, v81
	ds_bpermute_b32 v81, v148, v80
	s_and_saveexec_b64 s[18:19], vcc
	s_cbranch_execz .LBB0_1912
	s_waitcnt lgkmcnt(0)
	v_add_f32_e32 v82, v80, v81
	v_lshlrev_b64 v[80:81], 6, v[96:97]
	v_lshl_add_u64 v[80:81], s[2:3], 0, v[80:81]
	v_lshl_add_u64 v[80:81], s[16:17], 2, v[80:81]
	s_lshl_b32 s24, s43, 2
	v_lshl_add_u64 v[80:81], v[80:81], 0, s[24:25]
	global_store_dword v[80:81], v82, off
; DI float bf2f(unsigned v) { return __uint_as_float(v << 16); }
;   DI void operator()(const f32x4 (&acc)[2][2][4][2], const pg8::Unit& u, int wr, int wc, int fr_, int fq_) const {
;     ...
;             } else if (EPI == EPI_RESID) {
;               if (n == 0) {
;                 const int f8 = u.pn * 256 + bj * 128 + wc * 32 + 8 * fq;
;                 const f32x4 v1 = acc[ai][bj][m][1];
;                 f32x4 r0, r1;
;                 if (rsrc) {
;                   r0 = *(const f32x4*)(rsrc + (size_t)token * 1024 + f8); r1 = *(const f32x4*)(rsrc + (size_t)token * 1024 + f8 + 4);
;                 } else {
;                   const u32x4 xu = *(const u32x4*)(xr + (size_t)token * 1024 + f8);
;                   r0 = (f32x4){bf2f(xu.x & 0xffffu), bf2f(xu.x >> 16), bf2f(xu.y & 0xffffu), bf2f(xu.y >> 16)};
;                   r1 = (f32x4){bf2f(xu.z & 0xffffu), bf2f(xu.z >> 16), bf2f(xu.w & 0xffffu), bf2f(xu.w >> 16)};
;                 }
;                 r0 += v; r1 += v1;
;                 st_bf8(xr + (size_t)token * 1024 + f8, r0, r1, 1.f);
;                 ssq += r0[0] * r0[0] + r0[1] * r0[1] + r0[2] * r0[2] + r0[3] * r0[3] + r1[0] * r1[0] + r1[1] * r1[1] + r1[2] * r1[2] + r1[3] * r1[3];
;               }
;             } else {
;               if (n == 0) {
;                 const f32x4 v1 = acc[ai][bj][m][1];
;                 u32x4 o4;
;                 { const float t0 = fmaxf(v[0], 0.f) * rinv, t1 = fmaxf(v[1], 0.f) * rinv, t2 = fmaxf(v[2], 0.f) * rinv, t3 = fmaxf(v[3], 0.f) * rinv;
;                   o4.x = pack2(t0 * t0, t1 * t1); o4.y = pack2(t2 * t2, t3 * t3); }
;                 { const float t0 = fmaxf(v1[0], 0.f) * rinv, t1 = fmaxf(v1[1], 0.f) * rinv, t2 = fmaxf(v1[2], 0.f) * rinv, t3 = fmaxf(v1[3], 0.f) * rinv;
;                   o4.z = pack2(t0 * t0, t1 * t1); o4.w = pack2(t2 * t2, t3 * t3); }
;                 *(u32x4*)((u16*)big + (size_t)token * 4096 + u.pn * 256 + bj * 128 + wc * 32 + 8 * fq) = o4;
;               }
;             }
;           }
;         if (EPI == EPI_RESID) {
;           ssq += shx(ssq, 16, t_ & 63);
;           ssq += shx(ssq, 32, t_ & 63);
;           if (fq == 0) ss_out[(size_t)token * 16 + u.pn * 4 + wc] = ssq;
.LBB0_1912:
	s_or_b64 exec, exec, s[18:19]
	v_or_b32_e32 v80, 48, v140
	s_waitcnt lgkmcnt(0)
	v_ashrrev_i32_e32 v81, 31, v80
	v_lshlrev_b64 v[82:83], 11, v[80:81]
	v_lshl_add_u64 v[82:83], s[4:5], 0, v[82:83]
	v_lshl_add_u64 v[86:87], v[138:139], 1, v[82:83]
	global_load_dwordx4 v[82:85], v[86:87], off
	s_waitcnt vmcnt(0)
	v_lshlrev_b32_e32 v88, 16, v82
	v_and_b32_e32 v89, 0xffff0000, v82
	v_lshlrev_b32_e32 v82, 16, v83
	v_and_b32_e32 v83, 0xffff0000, v83
	v_lshlrev_b32_e32 v90, 16, v84
	v_and_b32_e32 v91, 0xffff0000, v84
	v_lshlrev_b32_e32 v84, 16, v85
	v_and_b32_e32 v85, 0xffff0000, v85
	v_add_f32_e32 v78, v78, v82
	v_add_f32_e32 v79, v79, v83
	v_add_f32_e32 v76, v76, v88
	v_add_f32_e32 v77, v77, v89
	v_add_f32_e32 v82, v74, v84
	v_add_f32_e32 v83, v75, v85
	v_add_f32_e32 v84, v72, v90
	v_add_f32_e32 v85, v73, v91
	v_cvt_pk_bf16_f32 v72, v76, v77
	v_cvt_pk_bf16_f32 v73, v78, v79
	v_cvt_pk_bf16_f32 v74, v84, v85
	v_cvt_pk_bf16_f32 v75, v82, v83
	global_store_dwordx4 v[86:87], v[72:75], off
	global_load_dwordx4 v[72:75], v[86:87], off offset:256
	v_mul_f32_e32 v88, v77, v77
	v_fmac_f32_e32 v88, v76, v76
	v_fmac_f32_e32 v88, v78, v78
	v_fmac_f32_e32 v88, v79, v79
	v_fmac_f32_e32 v88, v84, v84
	v_fmac_f32_e32 v88, v85, v85
	v_fmac_f32_e32 v88, v82, v82
	v_fmac_f32_e32 v88, v83, v83
	s_waitcnt vmcnt(0)
	v_lshlrev_b32_e32 v76, 16, v72
	v_and_b32_e32 v77, 0xffff0000, v72
	v_lshlrev_b32_e32 v72, 16, v73
	v_and_b32_e32 v73, 0xffff0000, v73
	v_lshlrev_b32_e32 v78, 16, v74
	v_and_b32_e32 v79, 0xffff0000, v74
	v_lshlrev_b32_e32 v74, 16, v75
	v_and_b32_e32 v75, 0xffff0000, v75
	v_add_f32_e32 v70, v70, v72
	v_add_f32_e32 v71, v71, v73
	v_add_f32_e32 v68, v68, v76
	v_add_f32_e32 v69, v69, v77
	v_add_f32_e32 v72, v66, v74
	v_add_f32_e32 v73, v67, v75
	v_add_f32_e32 v74, v64, v78
	v_add_f32_e32 v75, v65, v79
	v_cvt_pk_bf16_f32 v64, v68, v69
	v_cvt_pk_bf16_f32 v65, v70, v71
	v_cvt_pk_bf16_f32 v66, v74, v75
	v_cvt_pk_bf16_f32 v67, v72, v73
	global_store_dwordx4 v[86:87], v[64:67], off offset:256
	s_nop 1
	v_mul_f32_e32 v64, v69, v69
	v_fmac_f32_e32 v64, v68, v68
	v_fmac_f32_e32 v64, v70, v70
	v_fmac_f32_e32 v64, v71, v71
	v_fmac_f32_e32 v64, v74, v74
	v_fmac_f32_e32 v64, v75, v75
	v_fmac_f32_e32 v64, v72, v72
	v_fmac_f32_e32 v64, v73, v73
	v_add_f32_e32 v64, v88, v64
	ds_bpermute_b32 v65, v149, v64
	s_waitcnt lgkmcnt(0)
	v_add_f32_e32 v64, v64, v65
	ds_bpermute_b32 v65, v148, v64
	s_and_saveexec_b64 s[18:19], vcc
	v_readlane_b32 s51, v237, 11
	s_cbranch_execz .LBB0_1914
	s_waitcnt lgkmcnt(0)
	v_add_f32_e32 v66, v64, v65
	v_lshlrev_b64 v[64:65], 6, v[80:81]
	v_lshl_add_u64 v[64:65], s[2:3], 0, v[64:65]
	v_lshl_add_u64 v[64:65], s[16:17], 2, v[64:65]
	s_lshl_b32 s24, s43, 2
	v_lshl_add_u64 v[64:65], v[64:65], 0, s[24:25]
	global_store_dword v[64:65], v66, off
.LBB0_1914:
	s_or_b64 exec, exec, s[18:19]
	v_add_u32_e32 v64, 0x80, v140
	s_waitcnt lgkmcnt(0)
	v_ashrrev_i32_e32 v65, 31, v64
	v_lshlrev_b64 v[66:67], 11, v[64:65]
	v_lshl_add_u64 v[66:67], s[4:5], 0, v[66:67]
	v_lshl_add_u64 v[70:71], v[138:139], 1, v[66:67]
	global_load_dwordx4 v[66:69], v[70:71], off
	s_waitcnt vmcnt(0)
	v_lshlrev_b32_e32 v72, 16, v66
	v_and_b32_e32 v73, 0xffff0000, v66
	v_lshlrev_b32_e32 v66, 16, v67
	v_and_b32_e32 v67, 0xffff0000, v67
	v_lshlrev_b32_e32 v74, 16, v68
	v_and_b32_e32 v75, 0xffff0000, v68
	v_lshlrev_b32_e32 v68, 16, v69
	v_and_b32_e32 v69, 0xffff0000, v69
	v_add_f32_e32 v62, v62, v66
	v_add_f32_e32 v63, v63, v67
	v_add_f32_e32 v60, v60, v72
	v_add_f32_e32 v61, v61, v73
	v_add_f32_e32 v66, v58, v68
	v_add_f32_e32 v67, v59, v69
	v_add_f32_e32 v68, v56, v74
	v_add_f32_e32 v69, v57, v75
	v_cvt_pk_bf16_f32 v56, v60, v61
	v_cvt_pk_bf16_f32 v57, v62, v63
	v_cvt_pk_bf16_f32 v58, v68, v69
	v_cvt_pk_bf16_f32 v59, v66, v67
	global_store_dwordx4 v[70:71], v[56:59], off
	global_load_dwordx4 v[56:59], v[70:71], off offset:256
	v_mul_f32_e32 v72, v61, v61
	v_fmac_f32_e32 v72, v60, v60
	v_fmac_f32_e32 v72, v62, v62
	v_fmac_f32_e32 v72, v63, v63
	v_fmac_f32_e32 v72, v68, v68
	v_fmac_f32_e32 v72, v69, v69
	v_fmac_f32_e32 v72, v66, v66
	v_fmac_f32_e32 v72, v67, v67
	s_waitcnt vmcnt(0)
	v_lshlrev_b32_e32 v60, 16, v56
	v_and_b32_e32 v61, 0xffff0000, v56
	v_lshlrev_b32_e32 v56, 16, v57
	v_and_b32_e32 v57, 0xffff0000, v57
	v_lshlrev_b32_e32 v62, 16, v58
	v_and_b32_e32 v63, 0xffff0000, v58
	v_lshlrev_b32_e32 v58, 16, v59
	v_and_b32_e32 v59, 0xffff0000, v59
	v_add_f32_e32 v54, v54, v56
	v_add_f32_e32 v55, v55, v57
	v_add_f32_e32 v52, v52, v60
	v_add_f32_e32 v53, v53, v61
	v_add_f32_e32 v56, v50, v58
	v_add_f32_e32 v57, v51, v59
	v_add_f32_e32 v58, v48, v62
	v_add_f32_e32 v59, v49, v63
	v_cvt_pk_bf16_f32 v48, v52, v53
	v_cvt_pk_bf16_f32 v49, v54, v55
	v_cvt_pk_bf16_f32 v50, v58, v59
	v_cvt_pk_bf16_f32 v51, v56, v57
	global_store_dwordx4 v[70:71], v[48:51], off offset:256
	s_nop 1
	v_mul_f32_e32 v48, v53, v53
	v_fmac_f32_e32 v48, v52, v52
	v_fmac_f32_e32 v48, v54, v54
	v_fmac_f32_e32 v48, v55, v55
	v_fmac_f32_e32 v48, v58, v58
	v_fmac_f32_e32 v48, v59, v59
	v_fmac_f32_e32 v48, v56, v56
	v_fmac_f32_e32 v48, v57, v57
	v_add_f32_e32 v48, v72, v48
	ds_bpermute_b32 v49, v149, v48
	s_waitcnt lgkmcnt(0)
	v_add_f32_e32 v48, v48, v49
	ds_bpermute_b32 v49, v148, v48
	s_and_saveexec_b64 s[18:19], vcc
	s_cbranch_execz .LBB0_1916
	s_waitcnt lgkmcnt(0)
	v_add_f32_e32 v50, v48, v49
	v_lshlrev_b64 v[48:49], 6, v[64:65]
	v_lshl_add_u64 v[48:49], s[2:3], 0, v[48:49]
	v_lshl_add_u64 v[48:49], s[16:17], 2, v[48:49]
	s_lshl_b32 s24, s43, 2
	v_lshl_add_u64 v[48:49], v[48:49], 0, s[24:25]
	global_store_dword v[48:49], v50, off
; DI float bf2f(unsigned v) { return __uint_as_float(v << 16); }
;   DI void operator()(const f32x4 (&acc)[2][2][4][2], const pg8::Unit& u, int wr, int wc, int fr_, int fq_) const {
;     ...
;             } else if (EPI == EPI_RESID) {
;               if (n == 0) {
;                 const int f8 = u.pn * 256 + bj * 128 + wc * 32 + 8 * fq;
;                 const f32x4 v1 = acc[ai][bj][m][1];
;                 f32x4 r0, r1;
;                 if (rsrc) {
;                   r0 = *(const f32x4*)(rsrc + (size_t)token * 1024 + f8); r1 = *(const f32x4*)(rsrc + (size_t)token * 1024 + f8 + 4);
;                 } else {
;                   const u32x4 xu = *(const u32x4*)(xr + (size_t)token * 1024 + f8);
;                   r0 = (f32x4){bf2f(xu.x & 0xffffu), bf2f(xu.x >> 16), bf2f(xu.y & 0xffffu), bf2f(xu.y >> 16)};
;                   r1 = (f32x4){bf2f(xu.z & 0xffffu), bf2f(xu.z >> 16), bf2f(xu.w & 0xffffu), bf2f(xu.w >> 16)};
;                 }
;                 r0 += v; r1 += v1;
;                 st_bf8(xr + (size_t)token * 1024 + f8, r0, r1, 1.f);
;                 ssq += r0[0] * r0[0] + r0[1] * r0[1] + r0[2] * r0[2] + r0[3] * r0[3] + r1[0] * r1[0] + r1[1] * r1[1] + r1[2] * r1[2] + r1[3] * r1[3];
;               }
;             } else {
;               if (n == 0) {
;                 const f32x4 v1 = acc[ai][bj][m][1];
;                 u32x4 o4;
;                 { const float t0 = fmaxf(v[0], 0.f) * rinv, t1 = fmaxf(v[1], 0.f) * rinv, t2 = fmaxf(v[2], 0.f) * rinv, t3 = fmaxf(v[3], 0.f) * rinv;
;                   o4.x = pack2(t0 * t0, t1 * t1); o4.y = pack2(t2 * t2, t3 * t3); }
;                 { const float t0 = fmaxf(v1[0], 0.f) * rinv, t1 = fmaxf(v1[1], 0.f) * rinv, t2 = fmaxf(v1[2], 0.f) * rinv, t3 = fmaxf(v1[3], 0.f) * rinv;
;                   o4.z = pack2(t0 * t0, t1 * t1); o4.w = pack2(t2 * t2, t3 * t3); }
;                 *(u32x4*)((u16*)big + (size_t)token * 4096 + u.pn * 256 + bj * 128 + wc * 32 + 8 * fq) = o4;
;               }
;             }
;           }
;         if (EPI == EPI_RESID) {
;           ssq += shx(ssq, 16, t_ & 63);
;           ssq += shx(ssq, 32, t_ & 63);
;           if (fq == 0) ss_out[(size_t)token * 16 + u.pn * 4 + wc] = ssq;
.LBB0_1916:
	s_or_b64 exec, exec, s[18:19]
	v_add_u32_e32 v48, 0x90, v140
	s_waitcnt lgkmcnt(0)
	v_ashrrev_i32_e32 v49, 31, v48
	v_lshlrev_b64 v[50:51], 11, v[48:49]
	v_lshl_add_u64 v[50:51], s[4:5], 0, v[50:51]
	v_lshl_add_u64 v[54:55], v[138:139], 1, v[50:51]
	global_load_dwordx4 v[50:53], v[54:55], off
	s_waitcnt vmcnt(0)
	v_lshlrev_b32_e32 v56, 16, v50
	v_and_b32_e32 v57, 0xffff0000, v50
	v_lshlrev_b32_e32 v50, 16, v51
	v_and_b32_e32 v51, 0xffff0000, v51
	v_lshlrev_b32_e32 v58, 16, v52
	v_and_b32_e32 v59, 0xffff0000, v52
	v_lshlrev_b32_e32 v52, 16, v53
	v_and_b32_e32 v53, 0xffff0000, v53
	v_add_f32_e32 v46, v46, v50
	v_add_f32_e32 v47, v47, v51
	v_add_f32_e32 v44, v44, v56
	v_add_f32_e32 v45, v45, v57
	v_add_f32_e32 v50, v42, v52
	v_add_f32_e32 v51, v43, v53
	v_add_f32_e32 v52, v40, v58
	v_add_f32_e32 v53, v41, v59
	v_cvt_pk_bf16_f32 v40, v44, v45
	v_cvt_pk_bf16_f32 v41, v46, v47
	v_cvt_pk_bf16_f32 v42, v52, v53
	v_cvt_pk_bf16_f32 v43, v50, v51
	global_store_dwordx4 v[54:55], v[40:43], off
	global_load_dwordx4 v[40:43], v[54:55], off offset:256
	v_mul_f32_e32 v56, v45, v45
	v_fmac_f32_e32 v56, v44, v44
	v_fmac_f32_e32 v56, v46, v46
	v_fmac_f32_e32 v56, v47, v47
	v_fmac_f32_e32 v56, v52, v52
	v_fmac_f32_e32 v56, v53, v53
	v_fmac_f32_e32 v56, v50, v50
	v_fmac_f32_e32 v56, v51, v51
	s_waitcnt vmcnt(0)
	v_lshlrev_b32_e32 v44, 16, v40
	v_and_b32_e32 v45, 0xffff0000, v40
	v_lshlrev_b32_e32 v40, 16, v41
	v_and_b32_e32 v41, 0xffff0000, v41
	v_lshlrev_b32_e32 v46, 16, v42
	v_and_b32_e32 v47, 0xffff0000, v42
	v_lshlrev_b32_e32 v42, 16, v43
	v_and_b32_e32 v43, 0xffff0000, v43
	v_add_f32_e32 v38, v38, v40
	v_add_f32_e32 v39, v39, v41
	v_add_f32_e32 v36, v36, v44
	v_add_f32_e32 v37, v37, v45
	v_add_f32_e32 v40, v34, v42
	v_add_f32_e32 v41, v35, v43
	v_add_f32_e32 v42, v32, v46
	v_add_f32_e32 v43, v33, v47
	v_cvt_pk_bf16_f32 v32, v36, v37
	v_cvt_pk_bf16_f32 v33, v38, v39
	v_cvt_pk_bf16_f32 v34, v42, v43
	v_cvt_pk_bf16_f32 v35, v40, v41
	global_store_dwordx4 v[54:55], v[32:35], off offset:256
	s_nop 1
	v_mul_f32_e32 v32, v37, v37
	v_fmac_f32_e32 v32, v36, v36
	v_fmac_f32_e32 v32, v38, v38
	v_fmac_f32_e32 v32, v39, v39
	v_fmac_f32_e32 v32, v42, v42
	v_fmac_f32_e32 v32, v43, v43
	v_fmac_f32_e32 v32, v40, v40
	v_fmac_f32_e32 v32, v41, v41
	v_add_f32_e32 v32, v56, v32
	ds_bpermute_b32 v33, v149, v32
	s_waitcnt lgkmcnt(0)
	v_add_f32_e32 v32, v32, v33
	ds_bpermute_b32 v33, v148, v32
	s_and_saveexec_b64 s[18:19], vcc
	s_cbranch_execz .LBB0_1918
	s_waitcnt lgkmcnt(0)
	v_add_f32_e32 v34, v32, v33
	v_lshlrev_b64 v[32:33], 6, v[48:49]
	v_lshl_add_u64 v[32:33], s[2:3], 0, v[32:33]
	v_lshl_add_u64 v[32:33], s[16:17], 2, v[32:33]
	s_lshl_b32 s24, s43, 2
	v_lshl_add_u64 v[32:33], v[32:33], 0, s[24:25]
	global_store_dword v[32:33], v34, off
; DI float bf2f(unsigned v) { return __uint_as_float(v << 16); }
;   DI void operator()(const f32x4 (&acc)[2][2][4][2], const pg8::Unit& u, int wr, int wc, int fr_, int fq_) const {
;     ...
;             } else if (EPI == EPI_RESID) {
;               if (n == 0) {
;                 const int f8 = u.pn * 256 + bj * 128 + wc * 32 + 8 * fq;
;                 const f32x4 v1 = acc[ai][bj][m][1];
;                 f32x4 r0, r1;
;                 if (rsrc) {
;                   r0 = *(const f32x4*)(rsrc + (size_t)token * 1024 + f8); r1 = *(const f32x4*)(rsrc + (size_t)token * 1024 + f8 + 4);
;                 } else {
;                   const u32x4 xu = *(const u32x4*)(xr + (size_t)token * 1024 + f8);
;                   r0 = (f32x4){bf2f(xu.x & 0xffffu), bf2f(xu.x >> 16), bf2f(xu.y & 0xffffu), bf2f(xu.y >> 16)};
;                   r1 = (f32x4){bf2f(xu.z & 0xffffu), bf2f(xu.z >> 16), bf2f(xu.w & 0xffffu), bf2f(xu.w >> 16)};
;                 }
;                 r0 += v; r1 += v1;
;                 st_bf8(xr + (size_t)token * 1024 + f8, r0, r1, 1.f);
;                 ssq += r0[0] * r0[0] + r0[1] * r0[1] + r0[2] * r0[2] + r0[3] * r0[3] + r1[0] * r1[0] + r1[1] * r1[1] + r1[2] * r1[2] + r1[3] * r1[3];
;               }
;             } else {
;               if (n == 0) {
;                 const f32x4 v1 = acc[ai][bj][m][1];
;                 u32x4 o4;
;                 { const float t0 = fmaxf(v[0], 0.f) * rinv, t1 = fmaxf(v[1], 0.f) * rinv, t2 = fmaxf(v[2], 0.f) * rinv, t3 = fmaxf(v[3], 0.f) * rinv;
;                   o4.x = pack2(t0 * t0, t1 * t1); o4.y = pack2(t2 * t2, t3 * t3); }
;                 { const float t0 = fmaxf(v1[0], 0.f) * rinv, t1 = fmaxf(v1[1], 0.f) * rinv, t2 = fmaxf(v1[2], 0.f) * rinv, t3 = fmaxf(v1[3], 0.f) * rinv;
;                   o4.z = pack2(t0 * t0, t1 * t1); o4.w = pack2(t2 * t2, t3 * t3); }
;                 *(u32x4*)((u16*)big + (size_t)token * 4096 + u.pn * 256 + bj * 128 + wc * 32 + 8 * fq) = o4;
;               }
;             }
;           }
;         if (EPI == EPI_RESID) {
;           ssq += shx(ssq, 16, t_ & 63);
;           ssq += shx(ssq, 32, t_ & 63);
;           if (fq == 0) ss_out[(size_t)token * 16 + u.pn * 4 + wc] = ssq;
.LBB0_1918:
	s_or_b64 exec, exec, s[18:19]
	v_add_u32_e32 v32, 0xa0, v140
	s_waitcnt lgkmcnt(0)
	v_ashrrev_i32_e32 v33, 31, v32
	v_lshlrev_b64 v[34:35], 11, v[32:33]
	v_lshl_add_u64 v[34:35], s[4:5], 0, v[34:35]
	v_lshl_add_u64 v[38:39], v[138:139], 1, v[34:35]
	global_load_dwordx4 v[34:37], v[38:39], off
	s_waitcnt vmcnt(0)
	v_lshlrev_b32_e32 v40, 16, v34
	v_and_b32_e32 v41, 0xffff0000, v34
	v_lshlrev_b32_e32 v34, 16, v35
	v_and_b32_e32 v35, 0xffff0000, v35
	v_lshlrev_b32_e32 v42, 16, v36
	v_and_b32_e32 v43, 0xffff0000, v36
	v_lshlrev_b32_e32 v36, 16, v37
	v_and_b32_e32 v37, 0xffff0000, v37
	v_add_f32_e32 v30, v30, v34
	v_add_f32_e32 v31, v31, v35
	v_add_f32_e32 v28, v28, v40
	v_add_f32_e32 v29, v29, v41
	v_add_f32_e32 v34, v26, v36
	v_add_f32_e32 v35, v27, v37
	v_add_f32_e32 v36, v24, v42
	v_add_f32_e32 v37, v25, v43
	v_cvt_pk_bf16_f32 v24, v28, v29
	v_cvt_pk_bf16_f32 v25, v30, v31
	v_cvt_pk_bf16_f32 v26, v36, v37
	v_cvt_pk_bf16_f32 v27, v34, v35
	global_store_dwordx4 v[38:39], v[24:27], off
	global_load_dwordx4 v[24:27], v[38:39], off offset:256
	v_mul_f32_e32 v40, v29, v29
	v_fmac_f32_e32 v40, v28, v28
	v_fmac_f32_e32 v40, v30, v30
	v_fmac_f32_e32 v40, v31, v31
	v_fmac_f32_e32 v40, v36, v36
	v_fmac_f32_e32 v40, v37, v37
	v_fmac_f32_e32 v40, v34, v34
	v_fmac_f32_e32 v40, v35, v35
	s_waitcnt vmcnt(0)
	v_lshlrev_b32_e32 v28, 16, v24
	v_and_b32_e32 v29, 0xffff0000, v24
	v_lshlrev_b32_e32 v24, 16, v25
	v_and_b32_e32 v25, 0xffff0000, v25
	v_lshlrev_b32_e32 v30, 16, v26
	v_and_b32_e32 v31, 0xffff0000, v26
	v_lshlrev_b32_e32 v26, 16, v27
	v_and_b32_e32 v27, 0xffff0000, v27
	v_add_f32_e32 v22, v22, v24
	v_add_f32_e32 v23, v23, v25
	v_add_f32_e32 v20, v20, v28
	v_add_f32_e32 v21, v21, v29
	v_add_f32_e32 v24, v18, v26
	v_add_f32_e32 v25, v19, v27
	v_add_f32_e32 v26, v16, v30
	v_add_f32_e32 v27, v17, v31
	v_cvt_pk_bf16_f32 v16, v20, v21
	v_cvt_pk_bf16_f32 v17, v22, v23
	v_cvt_pk_bf16_f32 v18, v26, v27
	v_cvt_pk_bf16_f32 v19, v24, v25
	global_store_dwordx4 v[38:39], v[16:19], off offset:256
	s_nop 1
	v_mul_f32_e32 v16, v21, v21
	v_fmac_f32_e32 v16, v20, v20
	v_fmac_f32_e32 v16, v22, v22
	v_fmac_f32_e32 v16, v23, v23
	v_fmac_f32_e32 v16, v26, v26
	v_fmac_f32_e32 v16, v27, v27
	v_fmac_f32_e32 v16, v24, v24
	v_fmac_f32_e32 v16, v25, v25
	v_add_f32_e32 v16, v40, v16
	ds_bpermute_b32 v17, v149, v16
	s_waitcnt lgkmcnt(0)
	v_add_f32_e32 v16, v16, v17
	ds_bpermute_b32 v17, v148, v16
	s_and_saveexec_b64 s[18:19], vcc
	s_cbranch_execz .LBB0_1920
	s_waitcnt lgkmcnt(0)
	v_add_f32_e32 v18, v16, v17
	v_lshlrev_b64 v[16:17], 6, v[32:33]
	v_lshl_add_u64 v[16:17], s[2:3], 0, v[16:17]
	v_lshl_add_u64 v[16:17], s[16:17], 2, v[16:17]
	s_lshl_b32 s24, s43, 2
	v_lshl_add_u64 v[16:17], v[16:17], 0, s[24:25]
	global_store_dword v[16:17], v18, off
.LBB0_1920:
	s_or_b64 exec, exec, s[18:19]
	v_add_u32_e32 v16, 0xb0, v140
	s_waitcnt lgkmcnt(0)
	v_ashrrev_i32_e32 v17, 31, v16
	v_lshlrev_b64 v[18:19], 11, v[16:17]
	v_lshl_add_u64 v[18:19], s[4:5], 0, v[18:19]
	v_lshl_add_u64 v[22:23], v[138:139], 1, v[18:19]
	global_load_dwordx4 v[18:21], v[22:23], off
	s_waitcnt vmcnt(0)
	v_lshlrev_b32_e32 v24, 16, v18
	v_and_b32_e32 v25, 0xffff0000, v18
	v_lshlrev_b32_e32 v18, 16, v19
	v_and_b32_e32 v19, 0xffff0000, v19
	v_lshlrev_b32_e32 v26, 16, v20
	v_and_b32_e32 v27, 0xffff0000, v20
	v_lshlrev_b32_e32 v20, 16, v21
	v_and_b32_e32 v21, 0xffff0000, v21
	v_add_f32_e32 v14, v14, v18
	v_add_f32_e32 v15, v15, v19
	v_add_f32_e32 v12, v12, v24
	v_add_f32_e32 v13, v13, v25
	v_add_f32_e32 v18, v10, v20
	v_add_f32_e32 v19, v11, v21
	v_add_f32_e32 v20, v8, v26
	v_add_f32_e32 v21, v9, v27
	v_cvt_pk_bf16_f32 v8, v12, v13
	v_cvt_pk_bf16_f32 v9, v14, v15
	v_cvt_pk_bf16_f32 v10, v20, v21
	v_cvt_pk_bf16_f32 v11, v18, v19
	global_store_dwordx4 v[22:23], v[8:11], off
	global_load_dwordx4 v[8:11], v[22:23], off offset:256
	v_mul_f32_e32 v24, v13, v13
	v_fmac_f32_e32 v24, v12, v12
	v_fmac_f32_e32 v24, v14, v14
	v_fmac_f32_e32 v24, v15, v15
	v_fmac_f32_e32 v24, v20, v20
	v_fmac_f32_e32 v24, v21, v21
	v_fmac_f32_e32 v24, v18, v18
	v_fmac_f32_e32 v24, v19, v19
	s_waitcnt vmcnt(0)
	v_lshlrev_b32_e32 v12, 16, v8
	v_and_b32_e32 v13, 0xffff0000, v8
	v_lshlrev_b32_e32 v8, 16, v9
	v_and_b32_e32 v9, 0xffff0000, v9
	v_lshlrev_b32_e32 v14, 16, v10
	v_and_b32_e32 v15, 0xffff0000, v10
	v_lshlrev_b32_e32 v10, 16, v11
	v_and_b32_e32 v11, 0xffff0000, v11
	v_add_f32_e32 v6, v6, v8
	v_add_f32_e32 v7, v7, v9
	v_add_f32_e32 v4, v4, v12
	v_add_f32_e32 v5, v5, v13
	v_add_f32_e32 v8, v2, v10
	v_add_f32_e32 v9, v3, v11
	v_add_f32_e32 v10, v0, v14
	v_add_f32_e32 v11, v1, v15
	v_cvt_pk_bf16_f32 v0, v4, v5
	v_cvt_pk_bf16_f32 v1, v6, v7
	v_cvt_pk_bf16_f32 v2, v10, v11
	v_cvt_pk_bf16_f32 v3, v8, v9
	global_store_dwordx4 v[22:23], v[0:3], off offset:256
	s_nop 1
	v_mul_f32_e32 v0, v5, v5
	v_fmac_f32_e32 v0, v4, v4
	v_fmac_f32_e32 v0, v6, v6
	v_fmac_f32_e32 v0, v7, v7
	v_fmac_f32_e32 v0, v10, v10
	v_fmac_f32_e32 v0, v11, v11
	v_fmac_f32_e32 v0, v8, v8
	v_fmac_f32_e32 v0, v9, v9
	v_add_f32_e32 v0, v24, v0
	ds_bpermute_b32 v1, v149, v0
	s_waitcnt lgkmcnt(0)
	v_add_f32_e32 v0, v0, v1
	ds_bpermute_b32 v1, v148, v0
	s_and_saveexec_b64 s[18:19], vcc
	s_cbranch_execz .LBB0_1897
	s_waitcnt lgkmcnt(0)
	v_add_f32_e32 v2, v0, v1
	v_lshlrev_b64 v[0:1], 6, v[16:17]
	v_lshl_add_u64 v[0:1], s[2:3], 0, v[0:1]
	v_lshl_add_u64 v[0:1], s[16:17], 2, v[0:1]
	s_lshl_b32 s24, s43, 2
	v_lshl_add_u64 v[0:1], v[0:1], 0, s[24:25]
	global_store_dword v[0:1], v2, off
	s_branch .LBB0_1897

; DI float bf2f(unsigned v) { return __uint_as_float(v << 16); }
; template <bool FINAL, bool IN_BF16>
; DI void phase_norm(const void* __restrict__ xin, const float* __restrict__ g, u16* __restrict__ h, float* __restrict__ outf) {
;     ...
;   for (int row = blockIdx.x * 8 + wave; row < T_; row += gridDim.x * 8) {
;     f32x4 v[4]; float ss = 0.f;
;     if (IN_BF16) {
;       const u32x4* xr = (const u32x4*)((const u16*)xin + (size_t)row * 1024);
; #pragma unroll
;       for (int i = 0; i < 2; ++i) {
;         const u32x4 u = xr[lane + 64 * i];
;         v[2 * i]     = (f32x4){bf2f(u.x & 0xffffu), bf2f(u.x >> 16), bf2f(u.y & 0xffffu), bf2f(u.y >> 16)};
;         v[2 * i + 1] = (f32x4){bf2f(u.z & 0xffffu), bf2f(u.z >> 16), bf2f(u.w & 0xffffu), bf2f(u.w >> 16)};
;       }
;     } else {
;       const f32x4* xr = (const f32x4*)((const float*)xin + (size_t)row * 1024);
; #pragma unroll
;       for (int i = 0; i < 2; ++i) { v[2 * i] = xr[2 * lane + 128 * i]; v[2 * i + 1] = xr[2 * lane + 128 * i + 1]; }
;     }
; #pragma unroll
;     for (int i = 0; i < 4; ++i) ss += v[i][0] * v[i][0] + v[i][1] * v[i][1] + v[i][2] * v[i][2] + v[i][3] * v[i][3];
;     ss = wave_sum(ss, lane);
;     const float rinv = rsqrtf(ss * (1.f / 1024.f) + EPS);
; #pragma unroll
;     for (int i = 0; i < 2; ++i) {
;       const f32x4 g0 = ((const f32x4*)g)[2 * lane + 128 * i], g1 = ((const f32x4*)g)[2 * lane + 128 * i + 1];
;       const f32x4 a = v[2 * i] * g0 * rinv, b = v[2 * i + 1] * g1 * rinv;
;       if (FINAL) {
;         f32x4* op = (f32x4*)(outf + (size_t)row * 1024);
;         op[2 * lane + 128 * i] = a; op[2 * lane + 128 * i + 1] = b;
;       } else {
;         st_bf8(h + (size_t)row * 1024 + 8 * lane + 512 * i, a, b, 1.f);
;       }
;     }
;   }
.LBB0_1980:
	v_ashrrev_i32_e32 v17, 31, v16
	v_lshlrev_b64 v[30:31], 11, v[16:17]
	v_lshl_add_u64 v[38:39], v[18:19], 0, v[30:31]
	global_load_dwordx4 v[30:33], v[38:39], off
	global_load_dwordx4 v[34:37], v[38:39], off offset:1024
	s_waitcnt vmcnt(0)
	v_and_b32_e32 v41, 0xffff0000, v32
	v_and_b32_e32 v40, 0xffff0000, v30
	v_lshlrev_b32_e32 v39, 16, v32
	v_lshlrev_b32_e32 v38, 16, v30
	v_lshlrev_b32_e32 v42, 16, v31
	v_and_b32_e32 v32, 0xffff0000, v31
	v_lshlrev_b32_e32 v31, 16, v34
	v_lshlrev_b32_e32 v30, 16, v36
	v_and_b32_e32 v45, 0xffff0000, v34
	v_and_b32_e32 v44, 0xffff0000, v36
	v_lshlrev_b32_e32 v46, 16, v37
	v_and_b32_e32 v34, 0xffff0000, v37
	v_mul_f32_e32 v36, v40, v40
	v_mul_f32_e32 v37, v41, v41
	v_lshlrev_b32_e32 v43, 16, v33
	v_mul_f32_e32 v48, v44, v44
	v_mul_f32_e32 v49, v45, v45
	v_pk_fma_f32 v[36:37], v[38:39], v[38:39], v[36:37]
	v_and_b32_e32 v33, 0xffff0000, v33
	v_lshlrev_b32_e32 v47, 16, v35
	v_pk_fma_f32 v[48:49], v[30:31], v[30:31], v[48:49]
	v_pk_fma_f32 v[36:37], v[42:43], v[42:43], v[36:37]
	v_and_b32_e32 v35, 0xffff0000, v35
	v_pk_fma_f32 v[48:49], v[46:47], v[46:47], v[48:49]
	v_pk_fma_f32 v[36:37], v[32:33], v[32:33], v[36:37]
	v_pk_fma_f32 v[48:49], v[34:35], v[34:35], v[48:49]
	v_add_f32_e32 v29, v36, v37
	v_add_f32_e32 v29, v29, v49
	v_add_f32_e32 v29, v48, v29
	ds_bpermute_b32 v48, v22, v29
	v_lshlrev_b64 v[36:37], 12, v[16:17]
	v_add_u32_e32 v16, s4, v16
	v_cmp_lt_i32_e32 vcc, s6, v16
	s_or_b64 s[0:1], vcc, s[0:1]
	s_waitcnt lgkmcnt(0)
	v_add_f32_e32 v17, v29, v48
	ds_bpermute_b32 v29, v23, v17
	v_lshl_add_u64 v[48:49], v[20:21], 0, v[36:37]
	v_mov_b32_e32 v36, v38
	v_mov_b32_e32 v37, v40
	v_mov_b32_e32 v50, v42
	s_waitcnt lgkmcnt(0)
	v_add_f32_e32 v17, v17, v29
	ds_bpermute_b32 v29, v24, v17
	v_mov_b32_e32 v51, v32
	v_mov_b32_e32 v52, v47
	v_mov_b32_e32 v47, v34
	v_mov_b32_e32 v40, v39
	s_waitcnt lgkmcnt(0)
	v_add_f32_e32 v17, v17, v29
	ds_bpermute_b32 v29, v25, v17
	v_mov_b32_e32 v38, v31
	v_mov_b32_e32 v39, v45
	v_mov_b32_e32 v53, v35
	v_mul_f32_e32 v36, v4, v36
	v_mul_f32_e32 v37, v5, v37
	s_waitcnt lgkmcnt(0)
	v_add_f32_e32 v17, v17, v29
	ds_bpermute_b32 v29, v26, v17
	v_mul_f32_e32 v50, v6, v50
	v_mul_f32_e32 v51, v7, v51
	v_mov_b32_e32 v31, v44
	v_mov_b32_e32 v32, v43
	v_mul_f32_e32 v42, v10, v46
	v_mul_f32_e32 v43, v11, v47
	s_waitcnt lgkmcnt(0)
	v_add_f32_e32 v17, v17, v29
	ds_bpermute_b32 v29, v27, v17
	v_mul_f32_e32 v40, v0, v40
	v_mul_f32_e32 v41, v1, v41
	v_mul_f32_e32 v38, v12, v38
	v_mul_f32_e32 v39, v13, v39
	v_mul_f32_e32 v52, v14, v52
	v_mul_f32_e32 v53, v15, v53
	v_mul_f32_e32 v54, v8, v30
	v_mul_f32_e32 v55, v9, v31
	s_waitcnt lgkmcnt(0)
	v_add_f32_e32 v17, v17, v29
	v_fmamk_f32 v17, v17, 0x3a800000, v28
	v_mul_f32_e32 v29, 0x4b800000, v17
	v_cmp_gt_f32_e32 vcc, s5, v17
	v_mul_f32_e32 v34, v2, v32
	v_mul_f32_e32 v35, v3, v33
	s_nop 0
	v_cndmask_b32_e32 v17, v17, v29, vcc
	v_rsq_f32_e32 v17, v17
	s_nop 0
	v_mul_f32_e32 v29, 0x45800000, v17
	v_cndmask_b32_e32 v46, v17, v29, vcc
	v_mul_f32_e32 v32, v50, v46
	v_mul_f32_e32 v33, v51, v46
	v_mul_f32_e32 v30, v36, v46
	v_mul_f32_e32 v31, v37, v46
	v_mul_f32_e32 v36, v34, v46
	v_mul_f32_e32 v37, v35, v46
	v_mul_f32_e32 v34, v40, v46
	v_mul_f32_e32 v35, v41, v46
	v_mul_f32_e32 v40, v52, v46
	v_mul_f32_e32 v41, v53, v46
	v_mul_f32_e32 v38, v38, v46
	v_mul_f32_e32 v39, v39, v46
	v_mul_f32_e32 v44, v42, v46
	v_mul_f32_e32 v45, v43, v46
	v_mul_f32_e32 v42, v54, v46
	v_mul_f32_e32 v43, v55, v46
	global_store_dwordx4 v[48:49], v[30:33], off
	global_store_dwordx4 v[48:49], v[34:37], off offset:16
	global_store_dwordx4 v[48:49], v[38:41], off offset:2048
	global_store_dwordx4 v[48:49], v[42:45], off offset:2064
	s_andn2_b64 exec, exec, s[0:1]
	s_cbranch_execnz .LBB0_1980
